# peephole: split v_pk f32 ops whose operand pairs were assembled by v_mov copies into scalar ops, deleting the dead copies (symbolically verified)
# speedup vs baseline: 1.1281x; 1.0037x over previous
.LBB0_116:
	s_or_b64 exec, exec, s[50:51]
	v_mov_b32_e32 v1, v6
	s_barrier
	s_waitcnt vmcnt(0)
	v_mul_f32_e32 v4, v15, v14
	v_ashrrev_i32_e32 v2, 31, v1
	v_lshrrev_b32_e32 v2, 24, v2
	v_and_b32_e32 v17, 0xff, v1
	v_add_lshl_u32 v1, v1, v2, 4
	v_and_or_b32 v1, v1, s87, v17
	v_ashrrev_i32_e32 v2, 4, v1
	v_lshlrev_b32_e32 v1, 3, v1
	v_lshl_add_u32 v82, v2, 3, v1
	v_pk_add_f32 v[2:3], v[4:5], 0 op_sel_hi:[1,0]
	v_cvt_f32_i32_e32 v1, v17
	v_sub_f32_e32 v16, 0, v5
	v_add_f32_e32 v22, v2, v3
	v_mov_b32_e32 v23, v0
	v_add_f32_e32 v1, v1, v1
	v_mul_f32_e32 v1, 0x39800000, v1
	v_mul_f32_e32 v1, 0.5, v1
	v_readlane_b32 s4, v245, 24
	v_sin_f32_e32 v28, v1
	ds_write_b64 v82, v[22:23]
	v_sub_f32_e64 v23, 0, -v5
	v_mul_f32_e64 v22, -v16, s21
	v_readlane_b32 s5, v245, 25
	v_cos_f32_e32 v34, v1
	s_nop 0
	v_pk_add_f32 v[36:37], v[22:23], s[4:5]
	v_pk_mul_f32 v[22:23], v[22:23], s[70:71]
	s_nop 0
	s_nop 0
	v_sub_f32_e32 v38, 0, v23
	v_add_f32_e32 v22, v36, v2
	v_add_f32_e32 v23, v23, v0
	v_xor_b32_e32 v35, 0x80000000, v28
	v_pk_mul_f32 v[44:45], v[22:23], v[28:29] op_sel_hi:[1,0]
	v_sub_f32_e32 v42, 0, v23
	v_pk_fma_f32 v[46:47], v[22:23], v[34:35], v[44:45] op_sel:[0,0,1] op_sel_hi:[1,1,0]
	v_pk_fma_f32 v[22:23], v[22:23], v[34:35], v[44:45] op_sel:[0,0,1] op_sel_hi:[1,0,0] neg_lo:[0,0,1] neg_hi:[0,0,1]
	v_mov_b32_e32 v29, v34
	v_mov_b32_e32 v47, v23
	v_mul_f32_e32 v22, v28, v28
	v_mul_f32_e32 v23, v29, v35
	v_sub_f32_e32 v18, 0, v3
	v_pk_fma_f32 v[44:45], v[34:35], v[34:35], v[22:23] op_sel_hi:[0,1,1] neg_lo:[0,0,1] neg_hi:[0,0,1]
	v_pk_fma_f32 v[22:23], v[34:35], v[34:35], v[22:23] op_sel_hi:[0,1,1]
	v_fma_f32 v20, v18, s3, 0
	v_pk_mov_b32 v[48:49], v[22:23], v[44:45] op_sel:[1,0]
	v_add_f32_e32 v26, v2, v20
	ds_write_b64 v82, v[46:47] offset:2176
	v_mov_b32_e32 v46, v44
	v_mov_b32_e32 v47, v23
	v_mul_f32_e32 v27, v34, v44
	v_pk_mul_f32 v[50:51], v[20:21], v[48:49] op_sel_hi:[0,1]
	v_pk_fma_f32 v[52:53], v[26:27], v[44:45], v[50:51] neg_lo:[0,0,1] neg_hi:[0,0,1]
	v_pk_fma_f32 v[50:51], v[26:27], v[46:47], v[50:51] op_sel_hi:[0,1,1]
	v_mov_b32_e32 v53, v51
	v_pk_mul_f32 v[48:49], v[48:49], v[22:23] op_sel:[0,1]
	ds_write_b64 v82, v[52:53] offset:4352
	v_mov_b32_e32 v179, v44
	v_pk_fma_f32 v[52:53], v[44:45], v[46:47], v[48:49] op_sel_hi:[0,1,1] neg_lo:[0,0,1] neg_hi:[0,0,1]
	v_pk_fma_f32 v[44:45], v[44:45], v[46:47], v[48:49] op_sel_hi:[0,1,1]
	v_mov_b32_e32 v48, v52
	v_mov_b32_e32 v49, v45
	v_pk_mul_f32 v[66:67], v[48:49], v[44:45] op_sel:[0,1]
	v_mul_f32_e32 v22, v34, v45
	v_pk_fma_f32 v[68:69], v[52:53], v[48:49], v[66:67] op_sel:[0,0,1] op_sel_hi:[0,1,0] neg_lo:[0,0,1] neg_hi:[0,0,1]
	v_pk_fma_f32 v[66:67], v[52:53], v[48:49], v[66:67] op_sel:[0,0,1] op_sel_hi:[0,1,0]
	v_pk_mov_b32 v[72:73], v[66:67], v[68:69] op_sel:[1,0]
	v_mov_b32_e32 v70, v68
	v_mov_b32_e32 v71, v67
	v_pk_add_f32 v[76:77], v[2:3], v[2:3] op_sel:[0,1] op_sel_hi:[0,1] neg_lo:[0,1] neg_hi:[0,1]
	v_pk_mul_f32 v[78:79], v[72:73], 0 op_sel_hi:[1,0]
	v_fma_f32 v17, v18, s20, 0
	v_pk_fma_f32 v[54:55], v[28:29], v[48:49], v[22:23] op_sel_hi:[1,1,0] neg_lo:[1,0,0] neg_hi:[1,0,0]
	v_mul_f32_e32 v22, v23, v68
	v_pk_fma_f32 v[68:69], v[76:77], v[68:69], v[78:79] neg_lo:[0,0,1] neg_hi:[0,0,1]
	v_pk_fma_f32 v[76:77], v[76:77], v[70:71], v[78:79]
	v_add_f32_e32 v30, v2, v17
	v_sub_f32_e32 v32, v2, v17
	v_mul_f32_e32 v19, v28, v23
	v_mov_b32_e32 v17, v28
	v_mul_f32_e32 v39, v28, v45
	v_mov_b32_e32 v69, v77
	v_pk_mul_f32 v[28:29], v[28:29], v[70:71] op_sel_hi:[0,1]
	ds_write_b64 v82, v[68:69] offset:17408
	v_pk_fma_f32 v[68:69], v[34:35], v[70:71], v[28:29] op_sel:[0,0,1] op_sel_hi:[0,1,0]
	v_pk_fma_f32 v[28:29], v[34:35], v[70:71], v[28:29] op_sel:[0,0,1] op_sel_hi:[0,1,0] neg_lo:[0,0,1] neg_hi:[0,0,1]
	v_sub_f32_e64 v24, 0, -v3
	v_mul_f32_e32 v25, v34, v52
	v_pk_mov_b32 v[56:57], v[44:45], v[52:53] op_sel:[1,0]
	v_mov_b32_e32 v35, v29
	v_pk_mov_b32 v[28:29], v[28:29], v[68:69] op_sel:[1,0]
	v_pk_add_f32 v[40:41], v[2:3], v[36:37] neg_lo:[0,1] neg_hi:[0,1]
	v_mul_f32_e32 v1, v34, v23
	v_pk_mul_f32 v[58:59], v[24:25], v[56:57] op_sel_hi:[0,1]
	v_mov_b32_e32 v34, v68
	v_pk_mul_f32 v[28:29], v[42:43], v[28:29] op_sel_hi:[0,1]
	v_pk_fma_f32 v[60:61], v[2:3], v[52:53], v[58:59] neg_lo:[0,0,1] neg_hi:[0,0,1]
	v_pk_fma_f32 v[58:59], v[2:3], v[48:49], v[58:59] op_sel_hi:[0,1,1]
	v_pk_mul_f32 v[74:75], v[46:47], v[70:71]
	v_pk_fma_f32 v[42:43], v[40:41], v[68:69], v[28:29] neg_lo:[0,0,1] neg_hi:[0,0,1]
	v_pk_fma_f32 v[28:29], v[40:41], v[34:35], v[28:29] op_sel_hi:[0,1,1]
	v_mov_b32_e32 v61, v59
	v_pk_mul_f32 v[58:59], v[46:47], v[44:45] op_sel:[0,1]
	v_mov_b32_e32 v43, v29
	v_mov_b32_e32 v29, v0
	v_mov_b32_e32 v35, v20
	ds_write_b64 v82, v[60:61] offset:8704
	v_pk_fma_f32 v[60:61], v[46:47], v[52:53], v[58:59] op_sel:[0,0,1] op_sel_hi:[1,0,0] neg_lo:[0,0,1] neg_hi:[0,0,1]
	v_pk_fma_f32 v[58:59], v[46:47], v[52:53], v[58:59] op_sel:[0,0,1] op_sel_hi:[1,0,0]
	v_sub_f32_e32 v20, v74, v75
	v_sub_f32_e32 v21, v29, v35
	v_pk_mov_b32 v[64:65], v[58:59], v[60:61] op_sel:[1,0]
	v_sub_f32_e32 v28, 0, v21
	v_pk_mul_f32 v[28:29], v[28:29], v[64:65] op_sel_hi:[0,1]
	v_pk_fma_f32 v[40:41], v[30:31], v[60:61], v[28:29] neg_lo:[0,0,1] neg_hi:[0,0,1]
	v_fma_f32 v28, v30, v60, v28
	v_fma_f32 v29, v30, v59, v29
	v_mov_b32_e32 v41, v29
	v_pk_fma_f32 v[22:23], v[46:47], v[72:73], v[22:23] op_sel_hi:[1,1,0]
	v_sub_f32_e32 v28, v2, v35
	v_sub_f32_e32 v29, v74, v75
	v_mov_b32_e32 v30, v22
	v_mov_b32_e32 v31, v28
	v_pk_mov_b32 v[22:23], v[20:21], v[22:23] op_sel:[1,0]
	v_mov_b32_e32 v24, v2
	v_pk_mul_f32 v[22:23], v[30:31], v[22:23]
	v_pk_add_f32 v[24:25], v[24:25], v[38:39]
	v_pk_fma_f32 v[30:31], v[20:21], v[28:29], v[22:23] neg_lo:[0,0,1] neg_hi:[0,0,1]
	v_pk_fma_f32 v[22:23], v[20:21], v[28:29], v[22:23]
	v_pk_mul_f32 v[28:29], v[44:45], v[70:71] op_sel:[1,0]
	v_mov_b32_e32 v31, v23
	ds_write_b64 v82, v[30:31] offset:21760
	v_pk_fma_f32 v[30:31], v[52:53], v[70:71], v[28:29] op_sel:[0,0,1] op_sel_hi:[0,1,0] neg_lo:[0,0,1] neg_hi:[0,0,1]
	v_pk_fma_f32 v[28:29], v[52:53], v[70:71], v[28:29] op_sel:[0,0,1] op_sel_hi:[0,1,0]
	v_mov_b32_e32 v35, v29
	v_pk_mov_b32 v[28:29], v[28:29], v[30:31] op_sel:[1,0]
	v_pk_mul_f32 v[46:47], v[66:67], v[54:55] op_sel:[1,0] op_sel_hi:[0,1]
	v_pk_mul_f32 v[78:79], v[70:71], v[24:25] op_sel:[0,1] op_sel_hi:[1,0]
	v_mov_b32_e32 v34, v30
	v_pk_mul_f32 v[28:29], v[18:19], v[28:29] op_sel_hi:[0,1]
	v_pk_fma_f32 v[30:31], v[2:3], v[30:31], v[28:29] neg_lo:[0,0,1] neg_hi:[0,0,1]
	v_pk_fma_f32 v[28:29], v[2:3], v[34:35], v[28:29] op_sel_hi:[0,1,1]
	v_mov_b32_e32 v31, v29
	v_sub_f32_e32 v28, v78, v46
	v_sub_f32_e32 v29, v0, v36
	ds_write_b64 v82, v[30:31] offset:26112
	v_sub_f32_e32 v30, 0, v29
	v_mov_b32_e32 v31, v24
	v_pk_mul_f32 v[34:35], v[30:31], v[54:55] op_sel_hi:[1,0]
	v_pk_mov_b32 v[30:31], v[24:25], v[30:31] op_sel:[1,0]
	v_mov_b32_e32 v80, v54
	v_mov_b32_e32 v81, v25
	v_mul_f32_e32 v66, v67, v25
	v_pk_fma_f32 v[36:37], v[24:25], v[30:31], v[34:35] neg_lo:[0,0,1] neg_hi:[0,0,1]
	v_pk_fma_f32 v[24:25], v[24:25], v[30:31], v[34:35]
	v_pk_fma_f32 v[80:81], v[70:71], v[80:81], v[66:67] op_sel_hi:[1,1,0]
	v_mov_b32_e32 v37, v25
	v_sub_f32_e32 v24, v2, v38
	v_sub_f32_e32 v25, v78, v46
	s_nop 0
	s_nop 0
	v_pk_mov_b32 v[34:35], v[28:29], v[80:81] op_sel:[1,0]
	v_readlane_b32 s4, v245, 26
	v_mul_f32_e32 v30, v80, v34
	v_mul_f32_e32 v31, v24, v35
	v_pk_fma_f32 v[50:51], v[16:17], v[178:179], v[0:1] neg_lo:[1,0,0] neg_hi:[1,0,0]
	v_pk_fma_f32 v[34:35], v[28:29], v[24:25], v[30:31] neg_lo:[0,0,1] neg_hi:[0,0,1]
	v_pk_fma_f32 v[24:25], v[28:29], v[24:25], v[30:31]
	v_mov_b32_e32 v26, v2
	v_mov_b32_e32 v35, v25
	v_pk_mul_f32 v[24:25], v[72:73], v[58:59] op_sel:[0,1]
	v_fma_f32 v18, v16, s4, 0
	v_pk_fma_f32 v[28:29], v[70:71], v[60:61], v[24:25] op_sel_hi:[1,0,1] neg_lo:[0,0,1] neg_hi:[0,0,1]
	v_pk_fma_f32 v[24:25], v[70:71], v[60:61], v[24:25] op_sel_hi:[1,0,1]
	v_mov_b32_e32 v30, v28
	v_mov_b32_e32 v31, v25
	v_pk_mov_b32 v[24:25], v[24:25], v[28:29] op_sel:[1,0]
	v_pk_mul_f32 v[56:57], v[56:57], v[50:51] op_sel:[0,1]
	v_pk_mul_f32 v[20:21], v[20:21], v[24:25] op_sel:[1,0]
	v_pk_mul_f32 v[76:77], v[50:51], v[70:71]
	v_pk_fma_f32 v[24:25], v[32:33], v[28:29], v[20:21] neg_lo:[0,0,1] neg_hi:[0,0,1]
	v_pk_fma_f32 v[20:21], v[32:33], v[30:31], v[20:21] op_sel_hi:[0,1,1]
	v_mov_b32_e32 v25, v21
	v_pk_add_f32 v[20:21], v[26:27], v[18:19]
	ds_write_b64 v82, v[24:25] offset:30464
	v_pk_fma_f32 v[24:25], v[48:49], v[20:21], v[56:57] op_sel:[0,1,0] neg_lo:[0,0,1] neg_hi:[0,0,1]
	v_pk_fma_f32 v[26:27], v[48:49], v[20:21], v[56:57] op_sel:[0,1,0]
	v_mov_b32_e32 v28, v24
	v_mov_b32_e32 v29, v27
	v_pk_mul_f32 v[32:33], v[70:71], v[28:29]
	ds_write_b64 v82, v[34:35] offset:28288
	v_mul_f32_e64 v17, -v5, s4
	v_pk_mul_f32 v[30:31], v[20:21], v[70:71] op_sel:[1,0] op_sel_hi:[0,1]
	v_pk_mov_b32 v[22:23], v[76:77], v[50:51] op_sel:[1,0]
	ds_write_b64 v82, v[36:37] offset:10880
	v_mov_b32_e32 v31, v0
	v_sub_f32_e32 v34, v32, v33
	v_sub_f32_e32 v35, v0, v17
	v_pk_mov_b32 v[36:37], v[50:51], v[20:21] op_sel:[1,0]
	v_pk_add_f32 v[22:23], v[30:31], v[22:23] neg_lo:[0,1] neg_hi:[0,1]
	v_sub_f32_e32 v16, 0, v35
	v_pk_mul_f32 v[36:37], v[50:51], v[36:37]
	v_pk_mov_b32 v[38:39], v[20:21], v[50:51] op_sel:[1,0]
	v_pk_mov_b32 v[26:27], v[26:27], v[24:25] op_sel:[1,0]
	ds_write_b64 v82, v[40:41] offset:13056
	v_mov_b32_e32 v1, v4
	v_mov_b32_e32 v4, v17
	v_pk_fma_f32 v[40:41], v[20:21], v[38:39], v[36:37] neg_lo:[0,0,1] neg_hi:[0,0,1]
	v_pk_fma_f32 v[36:37], v[20:21], v[38:39], v[36:37]
	v_pk_mul_f32 v[16:17], v[16:17], v[26:27] op_sel_hi:[0,1]
	v_mov_b32_e32 v20, v51
	v_mul_f32_e32 v26, v21, v67
	v_fma_f32 v14, v15, v14, v23
	v_pk_fma_f32 v[20:21], v[20:21], v[70:71], v[26:27] op_sel_hi:[1,1,0]
	v_pk_fma_f32 v[24:25], v[14:15], v[24:25], v[16:17] neg_lo:[0,0,1] neg_hi:[0,0,1]
	v_pk_fma_f32 v[14:15], v[14:15], v[28:29], v[16:17] op_sel_hi:[0,1,1]
	v_sub_f32_e32 v2, v2, v18
	v_sub_f32_e32 v3, v30, v77
	v_mov_b32_e32 v25, v15
	v_pk_mov_b32 v[16:17], v[22:23], v[20:21] op_sel:[1,0]
	v_mov_b32_e32 v5, v23
	v_mul_f32_e32 v14, v20, v16
	v_mul_f32_e32 v15, v2, v17
	v_pk_mul_f32 v[26:27], v[72:73], v[28:29]
	v_pk_fma_f32 v[16:17], v[22:23], v[2:3], v[14:15] neg_lo:[0,0,1] neg_hi:[0,0,1]
	v_pk_fma_f32 v[2:3], v[22:23], v[2:3], v[14:15]
	v_pk_add_f32 v[4:5], v[0:1], v[4:5] neg_lo:[0,1] neg_hi:[0,1]
	v_mov_b32_e32 v41, v37
	v_pk_mov_b32 v[36:37], v[0:1], v[32:33] op_sel:[1,0]
	v_mov_b32_e32 v32, v23
	v_mov_b32_e32 v17, v3
	v_pk_add_f32 v[2:3], v[26:27], v[26:27] op_sel:[0,1] op_sel_hi:[0,1]
	v_pk_add_f32 v[32:33], v[36:37], v[32:33] neg_lo:[0,1] neg_hi:[0,1]
	v_pk_mul_f32 v[2:3], v[4:5], v[2:3]
	v_mov_b32_e32 v1, v12
	v_pk_fma_f32 v[4:5], v[34:35], v[32:33], v[2:3] neg_lo:[0,0,1] neg_hi:[0,0,1]
	v_pk_fma_f32 v[2:3], v[34:35], v[32:33], v[2:3]
	ds_write_b64 v82, v[42:43] offset:19584
	ds_write_b64 v82, v[40:41] offset:6528
	ds_write_b64 v82, v[24:25] offset:15232
	v_mov_b32_e32 v5, v3
	ds_write_b64 v82, v[16:17] offset:23936
	ds_write_b64 v82, v[4:5] offset:32640
	s_waitcnt lgkmcnt(0)
	s_barrier
	s_mov_b32 s54, s71
	v_ashrrev_i32_e32 v2, 31, v1
	v_lshrrev_b32_e32 v2, 28, v2
	v_and_b32_e32 v70, 15, v1
	v_add_u32_e32 v1, v1, v2
	v_ashrrev_i32_e32 v1, 4, v1
	v_lshlrev_b32_e32 v2, 11, v1
	v_lshl_add_u32 v1, v1, 7, v2
	v_lshl_or_b32 v1, v70, 3, v1
	ds_read2_b64 v[20:23], v1 offset1:17
	ds_read2_b64 v[24:27], v1 offset0:68 offset1:85
	ds_read2_b64 v[28:31], v1 offset0:136 offset1:153
	ds_read2_b64 v[32:35], v1 offset0:170 offset1:187
	ds_read2_b64 v[36:39], v1 offset0:204 offset1:221
	ds_read2_b64 v[40:43], v1 offset0:238 offset1:255
	ds_read2_b64 v[44:47], v1 offset0:34 offset1:51
	ds_read2_b64 v[48:51], v1 offset0:102 offset1:119
	s_waitcnt lgkmcnt(5)
	v_pk_add_f32 v[18:19], v[28:29], v[20:21]
	s_waitcnt lgkmcnt(2)
	v_pk_mov_b32 v[68:69], v[34:35], v[42:43] op_sel:[1,0]
	s_waitcnt lgkmcnt(1)
	v_pk_add_f32 v[64:65], v[46:47], v[34:35]
	s_waitcnt lgkmcnt(0)
	v_pk_add_f32 v[66:67], v[50:51], v[42:43]
	v_pk_mov_b32 v[16:17], v[46:47], v[50:51] op_sel:[1,0]
	v_mov_b32_e32 v35, v43
	v_pk_add_f32 v[42:43], v[64:65], v[66:67] neg_lo:[0,1] neg_hi:[0,1]
	v_pk_add_f32 v[68:69], v[16:17], v[68:69] neg_lo:[0,1] neg_hi:[0,1]
	v_pk_add_f32 v[16:17], v[64:65], v[66:67]
	v_mul_f32_e32 v64, 0x3f3504f3, v43
	v_mul_f32_e32 v67, 0xbf3504f3, v43
	v_cvt_f32_i32_e32 v43, v70
	v_mov_b32_e32 v47, v51
	v_pk_add_f32 v[34:35], v[46:47], v[34:35] neg_lo:[0,1] neg_hi:[0,1]
	v_pk_add_f32 v[28:29], v[20:21], v[28:29] neg_lo:[0,1] neg_hi:[0,1]
	v_add_f32_e32 v43, v43, v43
	v_pk_add_f32 v[20:21], v[24:25], v[36:37] neg_lo:[0,1] neg_hi:[0,1]
	v_pk_add_f32 v[52:53], v[36:37], v[24:25]
	v_pk_add_f32 v[54:55], v[22:23], v[30:31]
	v_pk_add_f32 v[56:57], v[26:27], v[38:39]
	v_pk_add_f32 v[46:47], v[34:35], v[34:35] op_sel:[0,1] op_sel_hi:[1,0] neg_lo:[0,1] neg_hi:[0,1]
	v_mul_f32_e32 v43, 0x3b800000, v43
	v_pk_mov_b32 v[24:25], v[20:21], v[20:21] op_sel:[1,0]
	v_pk_add_f32 v[36:37], v[28:29], v[20:21] op_sel:[0,1] op_sel_hi:[1,0]
	v_pk_add_f32 v[20:21], v[28:29], v[20:21] op_sel:[0,1] op_sel_hi:[1,0] neg_lo:[0,1] neg_hi:[0,1]
	v_pk_add_f32 v[34:35], v[34:35], v[34:35] op_sel:[0,1] op_sel_hi:[0,1]
	s_mov_b32 s55, s21
	v_pk_add_f32 v[4:5], v[54:55], v[56:57]
	v_pk_add_f32 v[58:59], v[44:45], v[32:33]
	v_pk_add_f32 v[60:61], v[48:49], v[40:41]
	v_pk_add_f32 v[54:55], v[54:55], v[56:57] neg_lo:[0,1] neg_hi:[0,1]
	v_mul_f32_e32 v43, 0.5, v43
	v_mov_b32_e32 v37, v21
	v_pk_add_f32 v[20:21], v[68:69], v[68:69] op_sel:[0,1] op_sel_hi:[0,1] neg_lo:[0,1] neg_hi:[0,1]
	s_mov_b32 s70, s21
	v_pk_mul_f32 v[34:35], v[34:35], s[54:55]
	v_pk_add_f32 v[14:15], v[58:59], v[60:61]
	v_pk_add_f32 v[62:63], v[58:59], v[60:61] neg_lo:[0,1] neg_hi:[0,1]
	v_pk_add_f32 v[50:51], v[68:69], v[68:69] op_sel:[0,1] op_sel_hi:[1,0]
	v_pk_mul_f32 v[56:57], v[54:55], s[20:21] op_sel_hi:[1,0]
	v_mul_f32_e32 v42, 0x3f3504f3, v42
	v_sin_f32_e32 v58, v43
	v_cos_f32_e32 v76, v43
	v_pk_fma_f32 v[68:69], v[20:21], s[70:71], v[34:35]
	v_pk_fma_f32 v[20:21], v[20:21], s[70:71], v[34:35] neg_lo:[0,0,1] neg_hi:[0,0,1]
	s_nop 0
	s_nop 0
	v_pk_add_f32 v[2:3], v[18:19], v[52:53]
	v_mov_b32_e32 v69, v21
	v_mov_b32_e32 v20, v18
	v_sub_f32_e32 v18, v64, v42
	v_sub_f32_e32 v19, v19, v53
	v_sub_f32_e32 v20, v20, v52
	v_sub_f32_e32 v21, v57, v56
	v_mov_b32_e32 v35, v42
	v_pk_add_f32 v[42:43], v[18:19], v[62:63] op_sel:[1,0] op_sel_hi:[0,1]
	v_mov_b32_e32 v53, v62
	v_sub_f32_e32 v34, v59, v61
	v_sub_f32_e32 v35, v67, v35
	v_sub_f32_e32 v62, v44, v32
	v_sub_f32_e32 v63, v22, v30
	v_sub_f32_e32 v64, v49, v41
	v_sub_f32_e32 v65, v27, v39
	s_nop 0
	v_mul_f32_e32 v78, 0x3f6c835e, v50
	v_mul_f32_e32 v79, 0x3ec3ef15, v46
	v_sub_f32_e32 v22, v45, v33
	v_sub_f32_e32 v23, v23, v31
	v_sub_f32_e32 v27, v26, v38
	v_sub_f32_e32 v26, v48, v40
	v_pk_add_f32 v[32:33], v[62:63], v[64:65] neg_lo:[0,1] neg_hi:[0,1]
	v_readlane_b32 s5, v245, 27
	v_pk_fma_f32 v[54:55], v[54:55], s[20:21], v[56:57] op_sel:[0,0,1] op_sel_hi:[1,0,0]
	v_pk_add_f32 v[66:67], v[62:63], v[64:65]
	v_pk_add_f32 v[30:31], v[22:23], v[26:27] neg_lo:[0,1] neg_hi:[0,1]
	v_pk_add_f32 v[22:23], v[22:23], v[26:27]
	s_mov_b32 s56, s3
	s_mov_b32 s57, s76
	v_mov_b32_e32 v51, v32
	v_mov_b32_e32 v39, v29
	v_mov_b32_e32 v27, v25
	v_mov_b32_e32 v52, v54
	v_pk_add_f32 v[54:55], v[54:55], v[18:19] neg_lo:[0,1] neg_hi:[0,1]
	v_mul_f32_e32 v26, 0x3ec3ef15, v33
	v_pk_mul_f32 v[40:41], v[32:33], s[56:57]
	s_mov_b32 s56, s20
	s_mov_b32 s57, s71
	v_pk_mul_f32 v[32:33], v[50:51], s[4:5]
	v_mov_b32_e32 v47, v22
	v_sub_f32_e32 v24, v28, v24
	v_sub_f32_e32 v25, v79, v78
	v_pk_mul_f32 v[28:29], v[66:67], s[70:71] op_sel:[1,0]
	v_pk_add_f32 v[56:57], v[18:19], v[52:53]
	v_pk_add_f32 v[52:53], v[18:19], v[52:53] neg_lo:[0,1] neg_hi:[0,1]
	v_pk_add_f32 v[18:19], v[42:43], v[54:55]
	v_mul_f32_e32 v38, 0x3f6c835e, v23
	v_mul_f32_e32 v43, 0x3f3504f3, v66
	v_mul_f32_e32 v44, 0x3f3504f3, v30
	v_pk_fma_f32 v[40:41], v[22:23], s[56:57], v[40:41]
	v_pk_fma_f32 v[22:23], v[46:47], s[30:31], v[32:33]
	v_pk_fma_f32 v[32:33], v[30:31], s[54:55], v[28:29] op_sel:[1,0,0]
	v_pk_fma_f32 v[28:29], v[30:31], s[54:55], v[28:29] op_sel:[1,0,0] neg_lo:[0,0,1] neg_hi:[0,0,1]
	v_pk_add_f32 v[26:27], v[38:39], v[26:27]
	v_mov_b32_e32 v33, v29
	v_add_f32_e32 v28, v44, v43
	v_fma_f32 v29, v30, s20, -v43
	v_pk_add_f32 v[30:31], v[36:37], v[28:29]
	v_pk_add_f32 v[38:39], v[32:33], v[68:69]
	v_xor_b32_e32 v77, 0x80000000, v58
	v_pk_add_f32 v[44:45], v[38:39], v[30:31]
	v_pk_add_f32 v[70:71], v[2:3], v[14:15]
	v_pk_mul_f32 v[50:51], v[58:59], v[44:45] op_sel_hi:[0,1]
	v_pk_fma_f32 v[62:63], v[76:77], v[44:45], v[50:51] op_sel:[0,0,1] op_sel_hi:[1,1,0]
	v_pk_fma_f32 v[44:45], v[76:77], v[44:45], v[50:51] op_sel:[0,0,1] op_sel_hi:[0,1,0] neg_lo:[0,0,1] neg_hi:[0,0,1]
	v_mov_b32_e32 v63, v45
	v_mov_b32_e32 v59, v76
	v_pk_add_f32 v[72:73], v[4:5], v[16:17]
	v_mul_f32_e32 v44, v58, v58
	v_mul_f32_e32 v45, v59, v77
	v_pk_add_f32 v[74:75], v[72:73], v[70:71]
	v_pk_fma_f32 v[50:51], v[76:77], v[76:77], v[44:45] op_sel_hi:[0,1,1] neg_lo:[0,0,1] neg_hi:[0,0,1]
	v_pk_fma_f32 v[44:45], v[76:77], v[76:77], v[44:45] op_sel_hi:[0,1,1]
	v_mov_b32_e32 v57, v53
	v_pk_add_f32 v[60:61], v[20:21], v[34:35]
	ds_write2_b64 v1, v[74:75], v[62:63] offset1:17
	v_pk_mov_b32 v[74:75], v[44:45], v[50:51] op_sel:[1,0]
	v_pk_add_f32 v[20:21], v[20:21], v[34:35] neg_lo:[0,1] neg_hi:[0,1]
	v_pk_add_f32 v[34:35], v[60:61], v[56:57]
	v_mov_b32_e32 v62, v50
	v_mov_b32_e32 v63, v45
	v_pk_mul_f32 v[74:75], v[44:45], v[74:75] op_sel:[1,0]
	v_pk_mul_f32 v[44:45], v[34:35], v[44:45] op_sel:[1,1] op_sel_hi:[0,1]
	v_pk_fma_f32 v[78:79], v[50:51], v[62:63], v[74:75] op_sel_hi:[0,1,1] neg_lo:[0,0,1] neg_hi:[0,0,1]
	v_pk_fma_f32 v[74:75], v[50:51], v[62:63], v[74:75] op_sel_hi:[0,1,1]
	v_pk_fma_f32 v[88:89], v[34:35], v[50:51], v[44:45] neg_lo:[0,0,1] neg_hi:[0,0,1]
	v_pk_fma_f32 v[34:35], v[34:35], v[50:51], v[44:45] op_sel_hi:[1,0,1]
	v_pk_mul_f32 v[44:45], v[62:63], v[74:75] op_sel:[0,1]
	v_pk_add_f32 v[32:33], v[32:33], v[68:69] neg_lo:[0,1] neg_hi:[0,1]
	v_pk_fma_f32 v[50:51], v[62:63], v[78:79], v[44:45] op_sel:[0,0,1] op_sel_hi:[1,0,0] neg_lo:[0,0,1] neg_hi:[0,0,1]
	v_pk_fma_f32 v[44:45], v[62:63], v[78:79], v[44:45] op_sel:[0,0,1] op_sel_hi:[1,0,0]
	v_sub_f32_e32 v42, v42, v54
	v_mov_b32_e32 v69, v45
	v_pk_mov_b32 v[44:45], v[44:45], v[50:51] op_sel:[1,0]
	v_mov_b32_e32 v77, v58
	v_mov_b32_e32 v80, v78
	v_mov_b32_e32 v81, v75
	v_pk_add_f32 v[90:91], v[20:21], v[20:21] op_sel:[0,1] op_sel_hi:[0,1]
	v_pk_mul_f32 v[42:43], v[42:43], v[44:45] op_sel_hi:[0,1]
	v_pk_mul_f32 v[64:65], v[76:77], v[62:63]
	v_pk_mul_f32 v[66:67], v[58:59], v[62:63]
	v_mov_b32_e32 v68, v50
	v_pk_fma_f32 v[44:45], v[90:91], v[50:51], v[42:43] neg_lo:[0,0,1] neg_hi:[0,0,1]
	v_pk_mul_f32 v[50:51], v[80:81], v[74:75] op_sel:[0,1]
	v_pk_add_f32 v[30:31], v[30:31], v[38:39] neg_lo:[0,1] neg_hi:[0,1]
	v_pk_add_f32 v[38:39], v[40:41], v[24:25]
	v_pk_add_f32 v[46:47], v[26:27], v[22:23]
	v_pk_fma_f32 v[42:43], v[90:91], v[68:69], v[42:43]
	v_pk_fma_f32 v[54:55], v[78:79], v[80:81], v[50:51] op_sel:[0,0,1] op_sel_hi:[0,1,0] neg_lo:[0,0,1] neg_hi:[0,0,1]
	v_pk_fma_f32 v[50:51], v[78:79], v[80:81], v[50:51] op_sel:[0,0,1] op_sel_hi:[0,1,0]
	v_mov_b32_e32 v92, v64
	v_mov_b32_e32 v93, v67
	v_pk_mov_b32 v[64:65], v[64:65], v[66:67] op_sel:[1,0]
	v_pk_add_f32 v[48:49], v[38:39], v[46:47]
	v_mov_b32_e32 v45, v43
	v_pk_add_f32 v[42:43], v[70:71], v[72:73] neg_lo:[0,1] neg_hi:[0,1]
	v_pk_mov_b32 v[72:73], v[50:51], v[54:55] op_sel:[1,0]
	v_pk_add_f32 v[66:67], v[92:93], v[64:65]
	v_pk_add_f32 v[64:65], v[92:93], v[64:65] neg_lo:[0,1] neg_hi:[0,1]
	v_pk_mul_f32 v[82:83], v[76:77], v[80:81]
	v_pk_mul_f32 v[84:85], v[58:59], v[80:81]
	v_pk_add_f32 v[28:29], v[36:37], v[28:29] neg_lo:[0,1] neg_hi:[0,1]
	v_mov_b32_e32 v70, v54
	v_mov_b32_e32 v71, v51
	v_pk_mul_f32 v[58:59], v[58:59], v[72:73] op_sel_hi:[0,1]
	v_pk_mul_f32 v[94:95], v[48:49], v[64:65] op_sel:[0,1]
	v_pk_mov_b32 v[86:87], v[74:75], v[78:79] op_sel:[1,0]
	v_mov_b32_e32 v89, v35
	v_pk_add_f32 v[34:35], v[28:29], v[32:33] op_sel:[0,1] op_sel_hi:[1,0]
	v_pk_add_f32 v[28:29], v[28:29], v[32:33] op_sel:[0,1] op_sel_hi:[1,0] neg_lo:[0,1] neg_hi:[0,1]
	v_pk_fma_f32 v[74:75], v[76:77], v[70:71], v[58:59] op_sel_hi:[0,1,1]
	v_pk_fma_f32 v[58:59], v[76:77], v[70:71], v[58:59] op_sel_hi:[0,1,1] neg_lo:[0,0,1] neg_hi:[0,0,1]
	v_pk_fma_f32 v[96:97], v[48:49], v[66:67], v[94:95] op_sel:[0,0,1] op_sel_hi:[1,1,0] neg_lo:[0,0,1] neg_hi:[0,0,1]
	v_pk_fma_f32 v[48:49], v[48:49], v[66:67], v[94:95] op_sel:[0,0,1] op_sel_hi:[1,0,0]
	v_mov_b32_e32 v98, v82
	v_mov_b32_e32 v99, v85
	v_pk_mov_b32 v[82:83], v[82:83], v[84:85] op_sel:[1,0]
	v_pk_mov_b32 v[36:37], v[28:29], v[34:35] op_sel:[1,0]
	v_mov_b32_e32 v77, v59
	v_mov_b32_e32 v97, v49
	v_pk_mul_f32 v[48:49], v[80:81], v[64:65] op_sel:[0,1]
	v_pk_add_f32 v[84:85], v[98:99], v[82:83]
	v_pk_add_f32 v[82:83], v[98:99], v[82:83] neg_lo:[0,1] neg_hi:[0,1]
	v_pk_mov_b32 v[58:59], v[58:59], v[74:75] op_sel:[1,0]
	v_mov_b32_e32 v76, v74
	v_mov_b32_e32 v93, v65
	v_pk_fma_f32 v[64:65], v[80:81], v[66:67], v[48:49] op_sel:[0,0,1] op_sel_hi:[1,0,0] neg_lo:[0,0,1] neg_hi:[0,0,1]
	v_pk_fma_f32 v[48:49], v[80:81], v[66:67], v[48:49] op_sel:[0,0,1] op_sel_hi:[1,0,0]
	v_pk_mul_f32 v[36:37], v[36:37], v[82:83] op_sel:[0,1]
	v_pk_mul_f32 v[58:59], v[30:31], v[58:59] op_sel:[1,0]
	v_mov_b32_e32 v92, v66
	v_mov_b32_e32 v66, v64
	v_mov_b32_e32 v67, v49
	v_mov_b32_e32 v98, v84
	v_mov_b32_e32 v99, v83
	v_pk_fma_f32 v[82:83], v[34:35], v[84:85], v[36:37] neg_lo:[0,0,1] neg_hi:[0,0,1]
	v_fma_f32 v32, v34, v84, v36
	v_fma_f32 v33, v29, v84, v37
	v_pk_fma_f32 v[74:75], v[30:31], v[74:75], v[58:59] neg_lo:[0,0,1] neg_hi:[0,0,1]
	v_pk_fma_f32 v[30:31], v[30:31], v[76:77], v[58:59] op_sel_hi:[0,1,1]
	v_pk_mul_f32 v[50:51], v[42:43], v[50:51] op_sel:[1,1] op_sel_hi:[0,1]
	v_pk_mul_f32 v[90:91], v[62:63], v[70:71]
	v_pk_mul_f32 v[62:63], v[62:63], v[72:73]
	ds_write2_b64 v1, v[88:89], v[96:97] offset0:34 offset1:51
	v_pk_mul_f32 v[88:89], v[92:93], v[70:71]
	v_pk_mul_f32 v[92:93], v[92:93], v[72:73]
	v_pk_mul_f32 v[94:95], v[80:81], v[70:71]
	v_pk_mul_f32 v[96:97], v[80:81], v[72:73]
	v_mov_b32_e32 v83, v33
	v_pk_mul_f32 v[32:33], v[70:71], v[98:99]
	v_pk_mul_f32 v[36:37], v[72:73], v[98:99]
	v_mov_b32_e32 v75, v31
	v_pk_mul_f32 v[30:31], v[70:71], v[68:69]
	v_pk_mul_f32 v[58:59], v[72:73], v[68:69]
	v_pk_mul_f32 v[68:69], v[70:71], v[66:67]
	v_pk_mul_f32 v[70:71], v[72:73], v[66:67]
	v_pk_fma_f32 v[72:73], v[42:43], v[54:55], v[50:51] neg_lo:[0,0,1] neg_hi:[0,0,1]
	v_pk_fma_f32 v[42:43], v[42:43], v[54:55], v[50:51] op_sel_hi:[1,0,1]
	v_mov_b32_e32 v73, v43
	v_sub_f32_e32 v42, v60, v56
	v_sub_f32_e32 v43, v53, v61
	v_pk_add_f32 v[50:51], v[62:63], v[62:63] op_sel:[0,1] op_sel_hi:[0,1]
	v_pk_mul_f32 v[50:51], v[42:43], v[50:51] op_sel:[1,0] op_sel_hi:[0,1]
	v_pk_add_f32 v[52:53], v[90:91], v[90:91] op_sel:[0,1] op_sel_hi:[0,1] neg_lo:[0,1] neg_hi:[0,1]
	v_pk_fma_f32 v[54:55], v[42:43], v[52:53], v[50:51] neg_lo:[0,0,1] neg_hi:[0,0,1]
	v_pk_fma_f32 v[42:43], v[42:43], v[52:53], v[50:51]
	v_pk_add_f32 v[2:3], v[2:3], v[14:15] neg_lo:[0,1] neg_hi:[0,1]
	v_mov_b32_e32 v55, v43
	v_mov_b32_e32 v43, v47
	v_sub_f32_e32 v38, v38, v46
	v_sub_f32_e32 v39, v43, v39
	v_pk_add_f32 v[42:43], v[92:93], v[92:93] op_sel:[0,1] op_sel_hi:[0,1]
	v_pk_add_f32 v[4:5], v[4:5], v[16:17] neg_lo:[0,1] neg_hi:[0,1]
	v_pk_mul_f32 v[42:43], v[38:39], v[42:43] op_sel:[1,0] op_sel_hi:[0,1]
	v_pk_add_f32 v[46:47], v[88:89], v[88:89] op_sel:[0,1] op_sel_hi:[0,1] neg_lo:[0,1] neg_hi:[0,1]
	v_pk_add_f32 v[14:15], v[2:3], v[4:5] op_sel:[0,1] op_sel_hi:[1,0]
	v_pk_add_f32 v[2:3], v[2:3], v[4:5] op_sel:[0,1] op_sel_hi:[1,0] neg_lo:[0,1] neg_hi:[0,1]
	v_pk_fma_f32 v[50:51], v[38:39], v[46:47], v[42:43] neg_lo:[0,0,1] neg_hi:[0,0,1]
	v_pk_fma_f32 v[38:39], v[38:39], v[46:47], v[42:43]
	v_pk_mul_f32 v[16:17], v[2:3], v[86:87] op_sel:[1,0]
	v_mov_b32_e32 v51, v39
	v_pk_fma_f32 v[38:39], v[14:15], v[78:79], v[16:17] neg_lo:[0,0,1] neg_hi:[0,0,1]
	v_pk_fma_f32 v[16:17], v[14:15], v[80:81], v[16:17] op_sel_hi:[0,1,1]
	v_mov_b32_e32 v5, v15
	v_mov_b32_e32 v39, v17
	v_pk_mov_b32 v[14:15], v[14:15], v[2:3] op_sel:[1,0]
	v_pk_add_f32 v[16:17], v[96:97], v[96:97] op_sel:[0,1] op_sel_hi:[0,1]
	v_mov_b32_e32 v4, v2
	v_pk_mul_f32 v[14:15], v[14:15], v[16:17]
	v_pk_add_f32 v[16:17], v[94:95], v[94:95] op_sel:[0,1] op_sel_hi:[0,1] neg_lo:[0,1] neg_hi:[0,1]
	v_pk_fma_f32 v[2:3], v[2:3], v[16:17], v[14:15] neg_lo:[0,0,1] neg_hi:[0,0,1]
	v_pk_fma_f32 v[4:5], v[4:5], v[16:17], v[14:15]
	v_pk_mov_b32 v[14:15], v[34:35], v[28:29] op_sel:[1,0]
	v_pk_add_f32 v[16:17], v[36:37], v[36:37] op_sel:[0,1] op_sel_hi:[0,1]
	v_mov_b32_e32 v3, v5
	v_mov_b32_e32 v4, v28
	v_mov_b32_e32 v5, v35
	v_pk_mul_f32 v[14:15], v[14:15], v[16:17]
	v_pk_add_f32 v[16:17], v[32:33], v[32:33] op_sel:[0,1] op_sel_hi:[0,1] neg_lo:[0,1] neg_hi:[0,1]
	v_pk_fma_f32 v[28:29], v[28:29], v[16:17], v[14:15] neg_lo:[0,0,1] neg_hi:[0,0,1]
	v_pk_fma_f32 v[4:5], v[4:5], v[16:17], v[14:15]
	v_pk_add_f32 v[14:15], v[58:59], v[58:59] op_sel:[0,1] op_sel_hi:[0,1]
	v_mov_b32_e32 v29, v5
	ds_write2_b64 v1, v[2:3], v[28:29] offset0:204 offset1:221
	v_mov_b32_e32 v3, v30
	v_sub_f32_e32 v2, v20, v21
	v_sub_f32_e32 v3, v3, v31
	v_mul_f32_e32 v4, v18, v14
	v_mul_f32_e32 v5, v2, v15
	v_pk_mov_b32 v[14:15], v[2:3], v[18:19] op_sel:[1,0]
	v_pk_mov_b32 v[48:49], v[48:49], v[64:65] op_sel:[1,0]
	v_pk_fma_f32 v[16:17], v[2:3], v[14:15], v[4:5] neg_lo:[0,0,1] neg_hi:[0,0,1]
	v_pk_fma_f32 v[2:3], v[2:3], v[14:15], v[4:5]
	v_mov_b32_e32 v17, v3
	v_mov_b32_e32 v3, v26
	v_mov_b32_e32 v5, v22
	v_sub_f32_e32 v2, v24, v40
	v_sub_f32_e32 v3, v3, v5
	v_sub_f32_e32 v4, v41, v25
	v_sub_f32_e32 v5, v27, v23
	ds_write2_b64 v1, v[72:73], v[74:75] offset0:136 offset1:153
	v_pk_add_f32 v[14:15], v[4:5], v[2:3]
	v_pk_add_f32 v[18:19], v[2:3], v[4:5] neg_lo:[0,1] neg_hi:[0,1]
	v_sub_f32_e32 v2, v5, v3
	v_pk_mul_f32 v[2:3], v[2:3], v[48:49] op_sel_hi:[0,1]
	v_pk_fma_f32 v[4:5], v[14:15], v[64:65], v[2:3] neg_lo:[0,0,1] neg_hi:[0,0,1]
	v_pk_fma_f32 v[2:3], v[14:15], v[66:67], v[2:3] op_sel_hi:[0,1,1]
	v_mov_b32_e32 v5, v3
	ds_write2_b64 v1, v[44:45], v[4:5] offset0:102 offset1:119
	v_pk_mov_b32 v[2:3], v[14:15], v[18:19] op_sel:[1,0]
	v_pk_add_f32 v[4:5], v[70:71], v[70:71] op_sel:[0,1] op_sel_hi:[0,1]
	v_mov_b32_e32 v20, v18
	v_mov_b32_e32 v21, v15
	v_pk_mul_f32 v[2:3], v[2:3], v[4:5]
	v_pk_add_f32 v[4:5], v[68:69], v[68:69] op_sel:[0,1] op_sel_hi:[0,1] neg_lo:[0,1] neg_hi:[0,1]
	v_pk_fma_f32 v[14:15], v[18:19], v[4:5], v[2:3] neg_lo:[0,0,1] neg_hi:[0,0,1]
	v_pk_fma_f32 v[2:3], v[20:21], v[4:5], v[2:3]
	ds_write2_b64 v1, v[54:55], v[50:51] offset0:170 offset1:187
	v_mov_b32_e32 v15, v3
	ds_write2_b64 v1, v[38:39], v[82:83] offset0:68 offset1:85
	ds_write2_b64 v1, v[16:17], v[14:15] offset0:238 offset1:255
	v_mov_b32_e32 v1, v6
	s_waitcnt lgkmcnt(0)
	s_barrier
	v_readlane_b32 s56, v245, 46
	v_mul_lo_u32 v1, v1, s33
	ds_read2_b64 v[2:5], v1 offset1:1
	ds_read2_b64 v[14:17], v1 offset0:8 offset1:9
	ds_read2_b64 v[18:21], v1 offset0:10 offset1:11
	ds_read2_b64 v[22:25], v1 offset0:12 offset1:13
	ds_read2_b64 v[26:29], v1 offset0:14 offset1:15
	ds_read2_b64 v[30:33], v1 offset0:2 offset1:3
	ds_read2_b64 v[34:37], v1 offset0:4 offset1:5
	ds_read2_b64 v[38:41], v1 offset0:6 offset1:7
	s_waitcnt lgkmcnt(7)
	v_mov_b32_e32 v1, v4
	v_mov_b32_e32 v42, v2
	v_mov_b32_e32 v43, v4
	v_mov_b32_e32 v4, v5
	v_mov_b32_e32 v5, v3
	s_waitcnt lgkmcnt(6)
	v_mov_b32_e32 v44, v14
	v_mov_b32_e32 v45, v16
	v_mov_b32_e32 v16, v17
	v_mov_b32_e32 v17, v15
	v_pk_add_f32 v[46:47], v[2:3], v[14:15] neg_lo:[0,1] neg_hi:[0,1]
	v_pk_add_f32 v[2:3], v[2:3], v[14:15]
	s_waitcnt lgkmcnt(1)
	v_mov_b32_e32 v15, v36
	v_mov_b32_e32 v49, v36
	v_mov_b32_e32 v36, v37
	v_mov_b32_e32 v37, v35
	v_mov_b32_e32 v50, v22
	v_mov_b32_e32 v51, v24
	v_mov_b32_e32 v24, v25
	v_mov_b32_e32 v25, v23
	v_mov_b32_e32 v48, v34
	v_pk_add_f32 v[52:53], v[34:35], v[22:23] neg_lo:[0,1] neg_hi:[0,1]
	v_pk_add_f32 v[22:23], v[34:35], v[22:23]
	v_pk_mov_b32 v[34:35], v[0:1], v[4:5] op_sel:[1,0]
	v_pk_mov_b32 v[54:55], v[44:45], v[16:17] op_sel:[1,0]
	v_pk_add_f32 v[4:5], v[4:5], v[16:17]
	v_pk_mov_b32 v[14:15], v[14:15], v[36:37] op_sel:[1,0]
	v_pk_mov_b32 v[16:17], v[50:51], v[24:25] op_sel:[1,0]
	v_pk_add_f32 v[42:43], v[42:43], v[44:45]
	v_pk_add_f32 v[44:45], v[48:49], v[50:51]
	v_pk_add_f32 v[24:25], v[36:37], v[24:25]
	v_pk_add_f32 v[48:49], v[2:3], v[22:23] neg_lo:[0,1] neg_hi:[0,1]
	v_pk_add_f32 v[2:3], v[2:3], v[22:23]
	v_pk_add_f32 v[22:23], v[34:35], v[54:55]
	v_pk_add_f32 v[34:35], v[34:35], v[54:55] neg_lo:[0,1] neg_hi:[0,1]
	v_pk_add_f32 v[36:37], v[14:15], v[16:17]
	v_pk_add_f32 v[14:15], v[14:15], v[16:17] neg_lo:[0,1] neg_hi:[0,1]
	v_add_f32_e32 v1, v46, v53
	v_sub_f32_e32 v50, v47, v52
	v_sub_f32_e32 v51, v46, v53
	v_add_f32_e32 v53, v47, v52
	v_pk_add_f32 v[16:17], v[42:43], v[44:45]
	v_pk_add_f32 v[4:5], v[4:5], v[24:25]
	v_add_f32_e32 v52, v34, v15
	v_sub_f32_e32 v54, v35, v14
	v_sub_f32_e32 v55, v34, v15
	v_add_f32_e32 v56, v35, v14
	v_pk_add_f32 v[14:15], v[30:31], v[18:19] neg_lo:[0,1] neg_hi:[0,1]
	v_pk_add_f32 v[24:25], v[30:31], v[18:19]
	v_mov_b32_e32 v44, v30
	v_mov_b32_e32 v46, v18
	s_xor_b64 s[50:51], s[40:41], -1
	v_pk_add_f32 v[42:43], v[22:23], v[36:37]
	v_pk_add_f32 v[22:23], v[22:23], v[36:37] neg_lo:[0,1] neg_hi:[0,1]
	s_waitcnt lgkmcnt(0)
	v_pk_add_f32 v[34:35], v[38:39], v[26:27] neg_lo:[0,1] neg_hi:[0,1]
	v_pk_add_f32 v[36:37], v[38:39], v[26:27]
	v_add_f32_e32 v44, v44, v46
	v_add_f32_e32 v45, v32, v20
	v_add_f32_e32 v18, v33, v21
	v_add_f32_e32 v19, v31, v19
	v_mov_b32_e32 v30, v38
	s_nop 0
	v_mov_b32_e32 v46, v26
	s_nop 0
	s_nop 0
	s_nop 0
	v_readlane_b32 s62, v245, 52
	v_add_f32_e32 v30, v30, v46
	v_add_f32_e32 v31, v40, v28
	v_add_f32_e32 v26, v41, v29
	v_add_f32_e32 v27, v39, v27
	v_pk_add_f32 v[46:47], v[24:25], v[36:37] neg_lo:[0,1] neg_hi:[0,1]
	v_pk_add_f32 v[24:25], v[24:25], v[36:37]
	v_add_f32_e32 v36, v14, v35
	v_sub_f32_e32 v37, v15, v34
	v_sub_f32_e32 v38, v14, v35
	v_add_f32_e32 v39, v15, v34
	v_pk_add_f32 v[14:15], v[32:33], v[20:21]
	v_pk_add_f32 v[20:21], v[32:33], v[20:21] neg_lo:[0,1] neg_hi:[0,1]
	v_pk_add_f32 v[32:33], v[40:41], v[28:29]
	v_pk_add_f32 v[28:29], v[40:41], v[28:29] neg_lo:[0,1] neg_hi:[0,1]
	v_readlane_b32 s63, v245, 53
	s_add_u32 s52, s62, s52
	v_pk_add_f32 v[30:31], v[44:45], v[30:31]
	v_pk_add_f32 v[18:19], v[18:19], v[26:27]
	v_sub_f32_e32 v27, v21, v28
	v_add_f32_e32 v21, v21, v28
	v_mul_f32_e32 v22, 0x3f3504f3, v22
	v_mul_f32_e32 v41, 0x3ec3ef15, v55
	v_mul_f32_e32 v45, 0xbf6c835e, v55
	s_addc_u32 s53, s63, s53
	s_mov_b32 s96, s10
	s_add_i32 s24, s1, s10
	v_readlane_b32 s4, v245, 56
	v_pk_add_f32 v[34:35], v[14:15], v[32:33]
	v_pk_add_f32 v[14:15], v[14:15], v[32:33] neg_lo:[0,1] neg_hi:[0,1]
	v_add_f32_e32 v26, v20, v29
	v_sub_f32_e32 v20, v20, v29
	v_fmamk_f32 v33, v23, 0x3f3504f3, v22
	v_fma_f32 v40, v23, s20, -v22
	v_fmac_f32_e32 v41, 0x3f6c835e, v56
	v_fmac_f32_e32 v45, 0x3ec3ef15, v56
	v_mul_f32_e32 v22, 0x3f3504f3, v36
	v_mul_f32_e32 v56, 0xbec3ef15, v21
	v_mul_f32_e32 v57, 0xbf6c835e, v21
	s_lshl_b64 s[54:55], s[24:25], 2
	v_readlane_b32 s8, v245, 60
	v_fmamk_f32 v32, v37, 0x3f3504f3, v22
	v_fma_f32 v36, v37, s20, -v22
	v_mul_f32_e32 v44, 0xbf3504f3, v14
	v_fmac_f32_e32 v56, 0xbf6c835e, v20
	v_fmac_f32_e32 v57, 0x3ec3ef15, v20
	v_pk_add_f32 v[20:21], v[2:3], v[24:25]
	v_pk_add_f32 v[22:23], v[42:43], v[34:35]
	v_readlane_b32 s57, v245, 47
	v_readlane_b32 s9, v245, 61
	s_add_u32 s56, s8, s54
	v_mul_f32_e32 v28, 0x3f6c835e, v52
	v_mul_f32_e32 v29, 0xbec3ef15, v52
	v_fmamk_f32 v52, v15, 0x3f3504f3, v44
	v_fmac_f32_e32 v44, 0xbf3504f3, v15
	v_pk_add_f32 v[2:3], v[2:3], v[24:25] neg_lo:[0,1] neg_hi:[0,1]
	v_pk_add_f32 v[24:25], v[16:17], v[30:31] neg_lo:[0,1] neg_hi:[0,1]
	v_pk_add_f32 v[14:15], v[22:23], v[20:21]
	v_pk_add_f32 v[16:17], v[20:21], v[22:23] neg_lo:[0,1] neg_hi:[0,1]
	s_addc_u32 s57, s9, s55
	global_load_dword v148, v0, s[52:53]
	global_load_dword v22, v0, s[42:43]
	global_load_dword v149, v0, s[44:45]
	global_load_dword v23, v0, s[46:47]
	global_load_dword v150, v0, s[56:57]
	global_load_dword v151, v0, s[48:49]
	global_load_dword v152, v186, s[56:57]
	global_load_dword v153, v187, s[56:57]
	v_readlane_b32 s10, v245, 62
	v_readlane_b32 s11, v245, 63
	s_add_u32 s52, s10, s54
	s_addc_u32 s53, s11, s55
	global_load_dword v154, v0, s[52:53]
	v_mul_f32_e32 v37, 0xbf3504f3, v38
	v_fmamk_f32 v55, v39, 0x3f3504f3, v37
	v_fmac_f32_e32 v37, 0xbf3504f3, v39
	v_mul_f32_e32 v38, 0x3ec3ef15, v26
	v_mul_f32_e32 v39, 0xbf6c835e, v26
	v_fmac_f32_e32 v28, 0x3ec3ef15, v54
	v_fmac_f32_e32 v29, 0x3f6c835e, v54
	v_fmac_f32_e32 v38, 0x3f6c835e, v27
	v_fmac_f32_e32 v39, 0x3ec3ef15, v27
	v_pk_add_f32 v[26:27], v[42:43], v[34:35] neg_lo:[0,1] neg_hi:[0,1]
	v_pk_add_f32 v[4:5], v[4:5], v[18:19] neg_lo:[0,1] neg_hi:[0,1]
	v_pk_add_f32 v[72:73], v[2:3], v[26:27] op_sel:[0,1] op_sel_hi:[1,0]
	v_pk_add_f32 v[2:3], v[2:3], v[26:27] op_sel:[0,1] op_sel_hi:[1,0] neg_lo:[0,1] neg_hi:[0,1]
	v_pk_add_f32 v[74:75], v[24:25], v[4:5] neg_lo:[0,1] neg_hi:[0,1]
	v_pk_add_f32 v[4:5], v[24:25], v[4:5]
	v_add_f32_e32 v25, v1, v32
	v_add_f32_e32 v27, v50, v36
	v_sub_f32_e32 v1, v1, v32
	v_sub_f32_e32 v31, v50, v36
	v_add_f32_e32 v30, v28, v38
	v_add_f32_e32 v32, v29, v39
	v_sub_f32_e32 v35, v28, v38
	v_sub_f32_e32 v29, v29, v39
	v_add_f32_e32 v24, v30, v25
	v_add_f32_e32 v26, v32, v27
	v_sub_f32_e32 v28, v25, v30
	v_sub_f32_e32 v30, v27, v32
	v_add_f32_e32 v32, v29, v1
	v_sub_f32_e32 v34, v31, v35
	v_sub_f32_e32 v36, v1, v29
	v_add_f32_e32 v38, v35, v31
	v_add_f32_e32 v1, v48, v47
	v_sub_f32_e32 v25, v49, v46
	v_sub_f32_e32 v27, v48, v47
	v_add_f32_e32 v29, v49, v46
	v_add_f32_e32 v31, v33, v52
	v_add_f32_e32 v35, v40, v44
	v_sub_f32_e32 v33, v33, v52
	v_sub_f32_e32 v39, v40, v44
	s_and_b64 s[40:41], s[40:41], exec
	s_mov_b32 s1, 0x5000000
	v_add_f32_e32 v40, v1, v31
	v_add_f32_e32 v42, v25, v35
	v_sub_f32_e32 v44, v1, v31
	v_sub_f32_e32 v46, v25, v35
	v_add_f32_e32 v48, v27, v39
	v_sub_f32_e32 v50, v29, v33
	v_sub_f32_e32 v52, v27, v39
	v_add_f32_e32 v54, v29, v33
	v_add_f32_e32 v1, v51, v55
	v_add_f32_e32 v25, v53, v37
	v_sub_f32_e32 v27, v51, v55
	v_sub_f32_e32 v29, v53, v37
	v_add_f32_e32 v31, v41, v56
	v_add_f32_e32 v33, v45, v57
	v_sub_f32_e32 v35, v41, v56
	v_sub_f32_e32 v37, v45, v57
	s_cselect_b32 s1, s1, 0xa000000
	v_readlane_b32 s4, v244, 11
	s_mov_b32 s2, 0
	v_add_f32_e32 v56, v31, v1
	v_add_f32_e32 v58, v33, v25
	v_sub_f32_e32 v60, v1, v31
	v_sub_f32_e32 v62, v25, v33
	v_add_f32_e32 v64, v37, v27
	v_sub_f32_e32 v66, v29, v35
	v_sub_f32_e32 v68, v27, v37
	v_add_f32_e32 v70, v35, v29
	s_add_u32 s1, s4, s1
	v_mov_b32_e32 v18, v72
	v_mov_b32_e32 v19, v3
	v_mov_b32_e32 v20, v74
	v_mov_b32_e32 v21, v5
	s_addc_u32 s94, s97, 0
	v_pk_mov_b32 v[72:73], v[2:3], v[72:73] op_sel:[1,0]
	v_pk_mov_b32 v[74:75], v[4:5], v[74:75] op_sel:[1,0]
	v_mov_b32_e32 v41, v40
	v_mov_b32_e32 v45, v44
	v_mov_b32_e32 v49, v48
	v_mov_b32_e32 v51, v50
	v_mov_b32_e32 v53, v52
	v_mov_b32_e32 v55, v54
	v_mov_b32_e32 v25, v24
	v_mov_b32_e32 v29, v28
	v_mov_b32_e32 v33, v32
	v_mov_b32_e32 v35, v34
	v_mov_b32_e32 v37, v36
	v_mov_b32_e32 v39, v38
	v_mov_b32_e32 v57, v56
	v_mov_b32_e32 v61, v60
	v_mov_b32_e32 v65, v64
	v_mov_b32_e32 v67, v66
	v_mov_b32_e32 v69, v68
	v_mov_b32_e32 v71, v70
	v_pk_mov_b32 v[76:77], v[14:15], v[14:15] op_sel:[1,0]
	v_mov_b32_e32 v27, v26
	v_mov_b32_e32 v43, v42
	v_mov_b32_e32 v59, v58
	v_pk_mov_b32 v[78:79], v[16:17], v[16:17] op_sel:[1,0]
	v_mov_b32_e32 v31, v30
	v_mov_b32_e32 v47, v46
	v_mov_b32_e32 v63, v62
	s_mov_b64 s[40:41], -1
	s_mov_b32 s24, s2
	v_readlane_b32 s58, v245, 48
	v_readlane_b32 s59, v245, 49
	v_readlane_b32 s60, v245, 50
	v_readlane_b32 s61, v245, 51
	v_readlane_b32 s5, v245, 57
	v_readlane_b32 s6, v245, 58
	v_readlane_b32 s7, v245, 59
	v_readlane_b32 s12, v244, 0
	v_readlane_b32 s13, v244, 1
	v_readlane_b32 s14, v244, 2
	v_readlane_b32 s15, v244, 3
	v_readlane_b32 s16, v244, 4
	v_readlane_b32 s17, v244, 5
	v_readlane_b32 s18, v244, 6
	v_readlane_b32 s19, v244, 7
	s_branch .LBB0_118

.LBB0_214:
	v_mov_b32_e32 v1, v12
	s_barrier
	v_pk_add_f32 v[118:119], v[2:3], v[4:5]
	v_ashrrev_i32_e32 v114, 31, v1
	v_lshrrev_b32_e32 v114, 24, v114
	v_and_b32_e32 v126, 0xff, v1
	v_add_lshl_u32 v1, v1, v114, 4
	v_pk_mov_b32 v[122:123], v[2:3], v[104:105] op_sel:[1,0]
	v_pk_mov_b32 v[124:125], v[4:5], v[88:89] op_sel:[1,0]
	v_and_or_b32 v1, v1, s87, v126
	v_sub_f32_e32 v2, v2, v4
	v_sub_f32_e32 v3, v105, v89
	v_ashrrev_i32_e32 v114, 4, v1
	v_cvt_f32_i32_e32 v4, v126
	v_lshlrev_b32_e32 v1, 3, v1
	v_lshl_add_u32 v155, v114, 3, v1
	v_pk_add_f32 v[114:115], v[112:113], v[100:101]
	v_pk_add_f32 v[116:117], v[108:109], v[92:93]
	v_pk_add_f32 v[120:121], v[104:105], v[88:89]
	v_add_f32_e32 v1, v2, v3
	v_sub_f32_e32 v2, v2, v3
	v_add_f32_e32 v3, v4, v4
	v_mul_f32_e32 v3, 0x39800000, v3
	v_pk_add_f32 v[128:129], v[114:115], v[116:117]
	v_pk_add_f32 v[130:131], v[118:119], v[120:121]
	v_mul_f32_e32 v3, 0.5, v3
	v_pk_add_f32 v[132:133], v[128:129], v[130:131]
	v_pk_add_f32 v[122:123], v[122:123], v[124:125] neg_lo:[0,1] neg_hi:[0,1]
	v_sin_f32_e32 v4, v3
	v_mul_f32_e32 v124, 0x3f3504f3, v2
	v_cos_f32_e32 v126, v3
	v_pk_add_f32 v[2:3], v[132:133], 0 op_sel_hi:[1,0]
	v_sub_f32_e32 v5, v122, v123
	ds_write_b64 v155, v[2:3]
	v_pk_add_f32 v[2:3], v[112:113], v[100:101] neg_lo:[0,1] neg_hi:[0,1]
	v_pk_add_f32 v[136:137], v[108:109], v[92:93] neg_lo:[0,1] neg_hi:[0,1]
	v_mul_f32_e32 v1, 0x3f3504f3, v1
	v_mul_f32_e32 v125, 0x3f3504f3, v5
	v_pk_add_f32 v[138:139], v[2:3], v[136:137] op_sel:[0,1] op_sel_hi:[1,0]
	v_pk_add_f32 v[2:3], v[2:3], v[136:137] op_sel:[0,1] op_sel_hi:[1,0] neg_lo:[0,1] neg_hi:[0,1]
	v_mov_b32_e32 v136, v138
	v_mov_b32_e32 v137, v3
	v_add_f32_e32 v140, v125, v1
	v_fma_f32 v141, v5, s20, -v1
	v_pk_add_f32 v[142:143], v[136:137], v[140:141]
	v_xor_b32_e32 v127, 0x80000000, v4
	v_pk_add_f32 v[144:145], v[142:143], 0 op_sel_hi:[1,0]
	v_pk_mul_f32 v[146:147], v[144:145], v[4:5] op_sel:[1,0] op_sel_hi:[0,0]
	v_mov_b32_e32 v5, v126
	v_mul_f32_e32 v158, v4, v4
	v_mul_f32_e32 v159, v5, v127
	v_pk_add_f32 v[114:115], v[114:115], v[116:117] neg_lo:[0,1] neg_hi:[0,1]
	v_pk_add_f32 v[116:117], v[118:119], v[120:121] neg_lo:[0,1] neg_hi:[0,1]
	v_pk_fma_f32 v[160:161], v[126:127], v[126:127], v[158:159] op_sel_hi:[0,1,1] neg_lo:[0,0,1] neg_hi:[0,0,1]
	v_pk_fma_f32 v[158:159], v[126:127], v[126:127], v[158:159] op_sel_hi:[0,1,1]
	v_pk_fma_f32 v[156:157], v[144:145], v[126:127], v[146:147]
	v_pk_fma_f32 v[144:145], v[144:145], v[126:127], v[146:147] op_sel_hi:[1,0,1] neg_lo:[0,0,1] neg_hi:[0,0,1]
	v_pk_add_f32 v[118:119], v[114:115], v[116:117] op_sel:[0,1] op_sel_hi:[1,0]
	v_pk_add_f32 v[120:121], v[114:115], v[116:117] op_sel:[0,1] op_sel_hi:[1,0] neg_lo:[0,1] neg_hi:[0,1]
	v_pk_mov_b32 v[168:169], v[158:159], v[160:161] op_sel:[1,0]
	v_mov_b32_e32 v157, v145
	v_mov_b32_e32 v144, v118
	v_mov_b32_e32 v145, v121
	v_pk_add_f32 v[122:123], v[122:123], v[122:123] op_sel:[0,1] op_sel_hi:[0,1]
	s_mov_b32 s2, s20
	v_mov_b32_e32 v162, v160
	v_mov_b32_e32 v163, v159
	v_mov_b32_e32 v127, v4
	v_pk_mul_f32 v[170:171], v[158:159], v[168:169] op_sel:[1,0]
	v_pk_add_f32 v[146:147], v[144:145], 0 op_sel_hi:[1,0]
	v_pk_fma_f32 v[122:123], v[122:123], s[2:3], v[124:125] op_sel_hi:[1,1,0] neg_lo:[0,0,1] neg_hi:[0,0,1]
	v_mov_b32_e32 v138, v2
	v_pk_mul_f32 v[164:165], v[126:127], v[162:163]
	v_pk_mul_f32 v[166:167], v[4:5], v[162:163]
	v_pk_fma_f32 v[172:173], v[160:161], v[162:163], v[170:171] op_sel_hi:[0,1,1] neg_lo:[0,0,1] neg_hi:[0,0,1]
	v_pk_fma_f32 v[170:171], v[160:161], v[162:163], v[170:171] op_sel_hi:[0,1,1]
	v_pk_add_f32 v[124:125], v[138:139], v[122:123]
	v_mov_b32_e32 v174, v172
	v_mov_b32_e32 v175, v171
	v_mov_b32_e32 v214, v164
	v_mov_b32_e32 v215, v167
	v_pk_mov_b32 v[164:165], v[164:165], v[166:167] op_sel:[1,0]
	v_pk_mul_f32 v[158:159], v[146:147], v[158:159] op_sel:[1,1] op_sel_hi:[0,1]
	ds_write_b64 v155, v[156:157] offset:2176
	v_pk_add_f32 v[156:157], v[124:125], 0 op_sel_hi:[1,0]
	v_pk_mul_f32 v[202:203], v[174:175], v[174:175]
	v_pk_mul_f32 v[204:205], v[174:175], v[170:171] op_sel:[0,1] op_sel_hi:[1,0]
	v_pk_add_f32 v[166:167], v[214:215], v[164:165]
	v_pk_add_f32 v[164:165], v[214:215], v[164:165] neg_lo:[0,1] neg_hi:[0,1]
	v_pk_fma_f32 v[224:225], v[146:147], v[160:161], v[158:159] neg_lo:[0,0,1] neg_hi:[0,0,1]
	v_pk_fma_f32 v[146:147], v[146:147], v[160:161], v[158:159] op_sel_hi:[1,0,1]
	v_mov_b32_e32 v206, v202
	v_mov_b32_e32 v207, v204
	v_pk_mov_b32 v[202:203], v[202:203], v[204:205] op_sel:[1,0]
	v_mov_b32_e32 v225, v147
	v_pk_mul_f32 v[146:147], v[156:157], v[164:165] op_sel:[0,1]
	v_pk_add_f32 v[204:205], v[206:207], v[202:203] neg_lo:[0,1] neg_hi:[0,1]
	v_pk_add_f32 v[202:203], v[206:207], v[202:203]
	v_pk_fma_f32 v[158:159], v[156:157], v[166:167], v[146:147] op_sel:[0,0,1] op_sel_hi:[1,1,0] neg_lo:[0,0,1] neg_hi:[0,0,1]
	v_pk_fma_f32 v[146:147], v[156:157], v[166:167], v[146:147] op_sel:[0,0,1] op_sel_hi:[1,0,0]
	v_mul_f32_e32 v181, v126, v171
	v_mul_f32_e32 v183, v4, v172
	v_mov_b32_e32 v206, v204
	v_mov_b32_e32 v207, v203
	v_mov_b32_e32 v215, v165
	v_mov_b32_e32 v159, v147
	v_pk_mul_f32 v[156:157], v[168:169], v[170:171] op_sel:[0,1]
	v_pk_mul_f32 v[164:165], v[174:175], v[164:165] op_sel:[0,1]
	v_mul_f32_e32 v1, v4, v171
	v_pk_mul_f32 v[4:5], v[4:5], v[206:207]
	ds_write_b64 v155, v[158:159] offset:6528
	v_sub_f32_e32 v146, v3, v141
	v_sub_f32_e32 v147, v181, v183
	v_pk_fma_f32 v[158:159], v[162:163], v[172:173], v[156:157] op_sel_hi:[1,0,1] neg_lo:[0,0,1] neg_hi:[0,0,1]
	v_pk_fma_f32 v[180:181], v[174:175], v[166:167], v[164:165] op_sel:[0,0,1] op_sel_hi:[1,0,0] neg_lo:[0,0,1] neg_hi:[0,0,1]
	v_mul_f32_e32 v177, v126, v172
	v_pk_mov_b32 v[208:209], v[202:203], v[204:205] op_sel:[1,0]
	v_pk_mul_f32 v[126:127], v[126:127], v[206:207]
	v_pk_mul_f32 v[218:219], v[170:171], v[204:205] op_sel_hi:[1,0]
	v_pk_mul_f32 v[220:221], v[172:173], v[202:203] op_sel_hi:[0,1]
	v_pk_mov_b32 v[222:223], v[170:171], v[172:173] op_sel:[1,0]
	v_pk_mul_f32 v[170:171], v[202:203], v[158:159] op_sel_hi:[1,0]
	v_pk_mul_f32 v[226:227], v[202:203], v[180:181] op_sel_hi:[1,0]
	v_pk_mul_f32 v[202:203], v[132:133], v[202:203] op_sel:[1,1] op_sel_hi:[0,1]
	v_pk_add_f32 v[4:5], v[4:5], v[4:5] op_sel:[1,0] op_sel_hi:[1,0] neg_lo:[0,1] neg_hi:[0,1]
	v_pk_fma_f32 v[228:229], v[132:133], v[204:205], v[202:203] neg_lo:[0,0,1] neg_hi:[0,0,1]
	v_pk_fma_f32 v[132:133], v[132:133], v[204:205], v[202:203] op_sel_hi:[1,0,1]
	v_pk_mul_f32 v[4:5], v[142:143], v[4:5] op_sel:[1,0] op_sel_hi:[0,1]
	v_pk_add_f32 v[126:127], v[126:127], v[126:127] op_sel:[0,1] op_sel_hi:[0,1]
	v_pk_mul_f32 v[212:213], v[162:163], v[208:209]
	v_mov_b32_e32 v229, v133
	v_pk_fma_f32 v[132:133], v[142:143], v[126:127], v[4:5] neg_lo:[0,0,1] neg_hi:[0,0,1]
	v_pk_fma_f32 v[4:5], v[142:143], v[126:127], v[4:5]
	v_pk_mul_f32 v[210:211], v[162:163], v[206:207]
	v_mov_b32_e32 v133, v5
	v_pk_mov_b32 v[4:5], v[120:121], v[118:119] op_sel:[1,0]
	v_pk_add_f32 v[120:121], v[212:213], v[212:213] op_sel:[0,1] op_sel_hi:[0,1]
	v_mov_b32_e32 v214, v166
	v_pk_mul_f32 v[4:5], v[4:5], v[120:121]
	v_pk_add_f32 v[120:121], v[210:211], v[210:211] op_sel:[0,1] op_sel_hi:[0,1] neg_lo:[0,1] neg_hi:[0,1]
	v_pk_mul_f32 v[208:209], v[214:215], v[208:209]
	v_pk_fma_f32 v[126:127], v[118:119], v[120:121], v[4:5] neg_lo:[0,0,1] neg_hi:[0,0,1]
	v_pk_fma_f32 v[4:5], v[144:145], v[120:121], v[4:5]
	v_pk_mul_f32 v[216:217], v[214:215], v[206:207]
	v_mov_b32_e32 v127, v5
	v_pk_add_f32 v[4:5], v[208:209], v[208:209] op_sel:[0,1] op_sel_hi:[0,1]
	v_pk_mul_f32 v[214:215], v[174:175], v[206:207]
	v_pk_mul_f32 v[4:5], v[124:125], v[4:5] op_sel:[1,0] op_sel_hi:[0,1]
	v_pk_add_f32 v[120:121], v[216:217], v[216:217] op_sel:[0,1] op_sel_hi:[0,1] neg_lo:[0,1] neg_hi:[0,1]
	v_pk_add_f32 v[134:135], v[128:129], v[130:131] neg_lo:[0,1] neg_hi:[0,1]
	ds_write_b64 v155, v[126:127] offset:21760
	v_pk_fma_f32 v[126:127], v[124:125], v[120:121], v[4:5] neg_lo:[0,0,1] neg_hi:[0,0,1]
	v_pk_fma_f32 v[4:5], v[124:125], v[120:121], v[4:5]
	v_mov_b32_e32 v127, v5
	v_sub_f32_e32 v4, v128, v130
	v_sub_f32_e32 v5, v214, v215
	v_pk_mul_f32 v[222:223], v[134:135], v[222:223] op_sel:[1,0]
	v_add_f32_e32 v116, 0, v4
	ds_write_b64 v155, v[126:127] offset:23936
	v_add_f32_e32 v120, v135, v0
	v_add_f32_e32 v121, v221, v219
	v_pk_fma_f32 v[124:125], v[116:117], v[172:173], v[222:223] neg_lo:[0,0,1] neg_hi:[0,0,1]
	v_pk_fma_f32 v[126:127], v[116:117], v[174:175], v[222:223] op_sel_hi:[0,1,1]
	v_mov_b32_e32 v125, v127
	v_pk_mov_b32 v[126:127], v[120:121], v[4:5] op_sel:[1,0]
	ds_write_b64 v155, v[224:225] offset:4352
	v_pk_mul_f32 v[126:127], v[120:121], v[126:127]
	v_pk_mov_b32 v[120:121], v[4:5], v[120:121] op_sel:[1,0]
	ds_write_b64 v155, v[228:229] offset:17408
	v_pk_fma_f32 v[128:129], v[4:5], v[120:121], v[126:127] neg_lo:[0,0,1] neg_hi:[0,0,1]
	v_pk_fma_f32 v[4:5], v[4:5], v[120:121], v[126:127]
	ds_write_b64 v155, v[132:133] offset:19584
	v_mov_b32_e32 v129, v5
	v_pk_add_f32 v[4:5], v[136:137], v[140:141] neg_lo:[0,1] neg_hi:[0,1]
	ds_write_b64 v155, v[124:125] offset:8704
	ds_write_b64 v155, v[128:129] offset:26112
	v_mov_b32_e32 v176, v4
	v_pk_add_f32 v[120:121], v[176:177], v[0:1]
	v_pk_mov_b32 v[128:129], v[146:147], v[120:121] op_sel:[1,0]
	v_pk_mul_f32 v[128:129], v[146:147], v[128:129]
	v_pk_mov_b32 v[130:131], v[120:121], v[146:147] op_sel:[1,0]
	v_mov_b32_e32 v124, v121
	v_mov_b32_e32 v125, v147
	v_mul_f32_e32 v116, v204, v121
	v_mul_f32_e32 v126, v206, v147
	v_mul_f32_e32 v127, v207, v121
	v_pk_fma_f32 v[132:133], v[120:121], v[130:131], v[128:129] neg_lo:[0,0,1] neg_hi:[0,0,1]
	v_pk_fma_f32 v[120:121], v[120:121], v[130:131], v[128:129]
	v_add_f32_e32 v134, 0, v146
	v_pk_fma_f32 v[156:157], v[162:163], v[172:173], v[156:157] op_sel_hi:[1,0,1]
	v_pk_fma_f32 v[124:125], v[206:207], v[124:125], v[116:117] op_sel_hi:[1,1,0] neg_lo:[1,0,0] neg_hi:[1,0,0]
	v_mov_b32_e32 v133, v121
	v_mov_b32_e32 v135, v4
	v_pk_add_f32 v[120:121], v[126:127], v[126:127] op_sel:[1,0] op_sel_hi:[1,0]
	v_mov_b32_e32 v160, v158
	v_mov_b32_e32 v161, v157
	v_pk_mul_f32 v[120:121], v[134:135], v[120:121]
	v_mov_b32_e32 v126, v4
	v_mov_b32_e32 v127, v125
	v_pk_mov_b32 v[124:125], v[124:125], v[134:135] op_sel:[1,0]
	v_pk_mul_f32 v[162:163], v[206:207], v[160:161]
	v_pk_fma_f32 v[4:5], v[4:5], v[124:125], v[120:121] neg_lo:[0,0,1] neg_hi:[0,0,1]
	v_pk_fma_f32 v[120:121], v[126:127], v[124:125], v[120:121]
	v_mov_b32_e32 v115, v162
	v_mov_b32_e32 v5, v121
	v_mov_b32_e32 v162, v117
	v_pk_mul_f32 v[168:169], v[204:205], v[156:157] op_sel_hi:[0,1]
	v_pk_mov_b32 v[156:157], v[156:157], v[158:159] op_sel:[1,0]
	ds_write_b64 v155, v[132:133] offset:10880
	ds_write_b64 v155, v[4:5] offset:28288
	v_pk_add_f32 v[4:5], v[114:115], v[162:163] neg_lo:[0,1] neg_hi:[0,1]
	v_pk_mul_f32 v[156:157], v[118:119], v[156:157] op_sel:[1,0]
	v_pk_fma_f32 v[164:165], v[174:175], v[166:167], v[164:165] op_sel:[0,0,1] op_sel_hi:[1,0,0]
	v_add_f32_e32 v114, 0, v4
	v_mov_b32_e32 v166, v180
	v_mov_b32_e32 v167, v165
	v_add_f32_e32 v116, v119, v0
	v_add_f32_e32 v117, v171, v169
	v_pk_fma_f32 v[118:119], v[114:115], v[158:159], v[156:157] neg_lo:[0,0,1] neg_hi:[0,0,1]
	v_pk_fma_f32 v[114:115], v[114:115], v[160:161], v[156:157] op_sel_hi:[0,1,1]
	v_pk_mul_f32 v[182:183], v[206:207], v[166:167]
	v_mov_b32_e32 v119, v115
	v_pk_mov_b32 v[114:115], v[116:117], v[4:5] op_sel:[1,0]
	v_pk_add_f32 v[138:139], v[138:139], v[122:123] neg_lo:[0,1] neg_hi:[0,1]
	v_pk_mul_f32 v[114:115], v[116:117], v[114:115]
	v_pk_mov_b32 v[116:117], v[4:5], v[116:117] op_sel:[1,0]
	v_pk_mul_f32 v[224:225], v[204:205], v[164:165] op_sel_hi:[0,1]
	v_pk_mov_b32 v[164:165], v[164:165], v[180:181] op_sel:[1,0]
	v_pk_fma_f32 v[120:121], v[4:5], v[116:117], v[114:115] neg_lo:[0,0,1] neg_hi:[0,0,1]
	v_pk_fma_f32 v[4:5], v[4:5], v[116:117], v[114:115]
	v_sub_f32_e32 v2, v2, v122
	v_sub_f32_e32 v3, v182, v183
	v_pk_mul_f32 v[164:165], v[138:139], v[164:165] op_sel:[1,0]
	v_add_f32_e32 v4, 0, v2
	v_mov_b32_e32 v121, v5
	v_add_f32_e32 v114, v139, v0
	v_add_f32_e32 v115, v227, v225
	v_pk_fma_f32 v[116:117], v[4:5], v[180:181], v[164:165] neg_lo:[0,0,1] neg_hi:[0,0,1]
	v_pk_fma_f32 v[4:5], v[4:5], v[166:167], v[164:165] op_sel_hi:[0,1,1]
	v_mov_b32_e32 v117, v5
	v_pk_mov_b32 v[4:5], v[114:115], v[2:3] op_sel:[1,0]
	ds_write_b64 v155, v[118:119] offset:13056
	ds_write_b64 v155, v[120:121] offset:30464
	v_pk_mul_f32 v[4:5], v[114:115], v[4:5]
	v_pk_mov_b32 v[114:115], v[2:3], v[114:115] op_sel:[1,0]
	v_mov_b32_e32 v1, v6
	v_pk_fma_f32 v[118:119], v[2:3], v[114:115], v[4:5] neg_lo:[0,0,1] neg_hi:[0,0,1]
	v_pk_fma_f32 v[2:3], v[2:3], v[114:115], v[4:5]
	s_mov_b32 s88, s71
	v_mov_b32_e32 v119, v3
	ds_write_b64 v155, v[116:117] offset:15232
	ds_write_b64 v155, v[118:119] offset:32640
	s_waitcnt lgkmcnt(0)
	s_barrier
	s_mov_b32 s89, s21
	v_ashrrev_i32_e32 v2, 31, v1
	v_lshrrev_b32_e32 v2, 28, v2
	v_and_b32_e32 v155, 15, v1
	v_add_u32_e32 v1, v1, v2
	v_ashrrev_i32_e32 v1, 4, v1
	v_lshlrev_b32_e32 v2, 11, v1
	v_lshl_add_u32 v1, v1, 7, v2
	v_lshl_or_b32 v1, v155, 3, v1
	ds_read2_b64 v[120:123], v1 offset1:17
	ds_read2_b64 v[124:127], v1 offset0:68 offset1:85
	ds_read2_b64 v[128:131], v1 offset0:136 offset1:153
	ds_read2_b64 v[132:135], v1 offset0:170 offset1:187
	ds_read2_b64 v[136:139], v1 offset0:204 offset1:221
	ds_read2_b64 v[140:143], v1 offset0:238 offset1:255
	ds_read2_b64 v[144:147], v1 offset0:34 offset1:51
	ds_read2_b64 v[156:159], v1 offset0:102 offset1:119
	s_waitcnt lgkmcnt(5)
	v_pk_add_f32 v[118:119], v[128:129], v[120:121]
	s_waitcnt lgkmcnt(2)
	v_pk_mov_b32 v[176:177], v[134:135], v[142:143] op_sel:[1,0]
	s_waitcnt lgkmcnt(1)
	v_pk_add_f32 v[172:173], v[146:147], v[134:135]
	s_waitcnt lgkmcnt(0)
	v_pk_add_f32 v[174:175], v[158:159], v[142:143]
	v_pk_mov_b32 v[116:117], v[146:147], v[158:159] op_sel:[1,0]
	v_mov_b32_e32 v135, v143
	v_pk_add_f32 v[142:143], v[172:173], v[174:175] neg_lo:[0,1] neg_hi:[0,1]
	v_pk_add_f32 v[176:177], v[116:117], v[176:177] neg_lo:[0,1] neg_hi:[0,1]
	v_pk_add_f32 v[116:117], v[172:173], v[174:175]
	v_mul_f32_e32 v172, 0x3f3504f3, v143
	v_mul_f32_e32 v175, 0xbf3504f3, v143
	v_cvt_f32_i32_e32 v143, v155
	v_mov_b32_e32 v147, v159
	v_pk_add_f32 v[134:135], v[146:147], v[134:135] neg_lo:[0,1] neg_hi:[0,1]
	v_pk_add_f32 v[128:129], v[120:121], v[128:129] neg_lo:[0,1] neg_hi:[0,1]
	v_add_f32_e32 v143, v143, v143
	v_pk_add_f32 v[120:121], v[124:125], v[136:137] neg_lo:[0,1] neg_hi:[0,1]
	v_pk_add_f32 v[160:161], v[136:137], v[124:125]
	v_pk_add_f32 v[162:163], v[122:123], v[130:131]
	v_pk_add_f32 v[164:165], v[126:127], v[138:139]
	v_pk_add_f32 v[146:147], v[134:135], v[134:135] op_sel:[0,1] op_sel_hi:[1,0] neg_lo:[0,1] neg_hi:[0,1]
	v_mul_f32_e32 v143, 0x3b800000, v143
	v_pk_mov_b32 v[124:125], v[120:121], v[120:121] op_sel:[1,0]
	v_pk_add_f32 v[136:137], v[128:129], v[120:121] op_sel:[0,1] op_sel_hi:[1,0]
	v_pk_add_f32 v[120:121], v[128:129], v[120:121] op_sel:[0,1] op_sel_hi:[1,0] neg_lo:[0,1] neg_hi:[0,1]
	v_pk_add_f32 v[134:135], v[134:135], v[134:135] op_sel:[0,1] op_sel_hi:[0,1]
	v_pk_add_f32 v[4:5], v[162:163], v[164:165]
	v_pk_add_f32 v[166:167], v[144:145], v[132:133]
	v_pk_add_f32 v[168:169], v[156:157], v[140:141]
	v_pk_add_f32 v[162:163], v[162:163], v[164:165] neg_lo:[0,1] neg_hi:[0,1]
	v_mul_f32_e32 v143, 0.5, v143
	v_mov_b32_e32 v137, v121
	v_pk_add_f32 v[120:121], v[176:177], v[176:177] op_sel:[0,1] op_sel_hi:[0,1] neg_lo:[0,1] neg_hi:[0,1]
	s_mov_b32 s70, s21
	v_pk_mul_f32 v[134:135], v[134:135], s[88:89]
	v_pk_add_f32 v[114:115], v[166:167], v[168:169]
	v_pk_add_f32 v[170:171], v[166:167], v[168:169] neg_lo:[0,1] neg_hi:[0,1]
	v_pk_add_f32 v[158:159], v[176:177], v[176:177] op_sel:[0,1] op_sel_hi:[1,0]
	v_pk_mul_f32 v[164:165], v[162:163], s[20:21] op_sel_hi:[1,0]
	v_mul_f32_e32 v142, 0x3f3504f3, v142
	v_sin_f32_e32 v166, v143
	v_cos_f32_e32 v204, v143
	v_pk_fma_f32 v[176:177], v[120:121], s[70:71], v[134:135]
	v_pk_fma_f32 v[120:121], v[120:121], s[70:71], v[134:135] neg_lo:[0,0,1] neg_hi:[0,0,1]
	s_nop 0
	s_nop 0
	v_pk_add_f32 v[2:3], v[118:119], v[160:161]
	v_mov_b32_e32 v177, v121
	v_mov_b32_e32 v120, v118
	v_sub_f32_e32 v118, v172, v142
	v_sub_f32_e32 v119, v119, v161
	v_sub_f32_e32 v120, v120, v160
	v_sub_f32_e32 v121, v165, v164
	v_mov_b32_e32 v135, v142
	v_pk_add_f32 v[142:143], v[118:119], v[170:171] op_sel:[1,0] op_sel_hi:[0,1]
	v_mov_b32_e32 v161, v170
	v_sub_f32_e32 v134, v167, v169
	v_sub_f32_e32 v135, v175, v135
	v_sub_f32_e32 v170, v144, v132
	v_sub_f32_e32 v171, v122, v130
	v_sub_f32_e32 v172, v157, v141
	v_sub_f32_e32 v173, v127, v139
	v_mul_f32_e32 v155, 0x3f6c835e, v158
	v_mul_f32_e32 v179, 0x3ec3ef15, v146
	v_sub_f32_e32 v122, v145, v133
	v_sub_f32_e32 v123, v123, v131
	v_sub_f32_e32 v127, v126, v138
	v_sub_f32_e32 v126, v156, v140
	v_pk_add_f32 v[132:133], v[170:171], v[172:173] neg_lo:[0,1] neg_hi:[0,1]
	v_pk_fma_f32 v[162:163], v[162:163], s[20:21], v[164:165] op_sel:[0,0,1] op_sel_hi:[1,0,0]
	v_pk_add_f32 v[174:175], v[170:171], v[172:173]
	v_pk_add_f32 v[130:131], v[122:123], v[126:127] neg_lo:[0,1] neg_hi:[0,1]
	v_pk_add_f32 v[122:123], v[122:123], v[126:127]
	v_mov_b32_e32 v159, v132
	v_mov_b32_e32 v139, v129
	v_mov_b32_e32 v127, v125
	v_mov_b32_e32 v160, v162
	v_pk_add_f32 v[162:163], v[162:163], v[118:119] neg_lo:[0,1] neg_hi:[0,1]
	v_mul_f32_e32 v126, 0x3ec3ef15, v133
	v_pk_mul_f32 v[140:141], v[132:133], s[20:21]
	s_mov_b32 s90, s20
	s_mov_b32 s91, s71
	v_pk_mul_f32 v[132:133], v[158:159], s[72:73]
	v_mov_b32_e32 v147, v122
	v_sub_f32_e32 v124, v128, v124
	v_sub_f32_e32 v125, v179, v155
	v_pk_mul_f32 v[128:129], v[174:175], s[70:71] op_sel:[1,0]
	v_pk_add_f32 v[164:165], v[118:119], v[160:161]
	v_pk_add_f32 v[160:161], v[118:119], v[160:161] neg_lo:[0,1] neg_hi:[0,1]
	v_pk_add_f32 v[118:119], v[142:143], v[162:163]
	v_mul_f32_e32 v138, 0x3f6c835e, v123
	v_mul_f32_e32 v143, 0x3f3504f3, v174
	v_mul_f32_e32 v144, 0x3f3504f3, v130
	v_pk_fma_f32 v[140:141], v[122:123], s[90:91], v[140:141] neg_lo:[0,0,1] neg_hi:[0,0,1]
	v_pk_fma_f32 v[122:123], v[146:147], s[30:31], v[132:133] neg_lo:[0,0,1] neg_hi:[0,0,1]
	v_pk_fma_f32 v[132:133], v[130:131], s[88:89], v[128:129] op_sel:[1,0,0]
	v_pk_fma_f32 v[128:129], v[130:131], s[88:89], v[128:129] op_sel:[1,0,0] neg_lo:[0,0,1] neg_hi:[0,0,1]
	v_pk_add_f32 v[126:127], v[138:139], v[126:127]
	v_mov_b32_e32 v133, v129
	v_add_f32_e32 v128, v144, v143
	v_fma_f32 v129, v130, s20, -v143
	v_pk_add_f32 v[130:131], v[136:137], v[128:129]
	v_pk_add_f32 v[138:139], v[132:133], v[176:177]
	v_xor_b32_e32 v205, 0x80000000, v166
	v_pk_add_f32 v[144:145], v[138:139], v[130:131]
	v_pk_add_f32 v[180:181], v[2:3], v[114:115]
	v_pk_mul_f32 v[158:159], v[166:167], v[144:145] op_sel_hi:[0,1]
	v_pk_fma_f32 v[170:171], v[204:205], v[144:145], v[158:159] op_sel:[0,0,1] op_sel_hi:[1,1,0]
	v_pk_fma_f32 v[144:145], v[204:205], v[144:145], v[158:159] op_sel:[0,0,1] op_sel_hi:[0,1,0] neg_lo:[0,0,1] neg_hi:[0,0,1]
	v_mov_b32_e32 v171, v145
	v_mov_b32_e32 v167, v204
	v_pk_add_f32 v[182:183], v[4:5], v[116:117]
	v_mul_f32_e32 v144, v166, v166
	v_mul_f32_e32 v145, v167, v205
	v_pk_add_f32 v[202:203], v[182:183], v[180:181]
	v_pk_fma_f32 v[158:159], v[204:205], v[204:205], v[144:145] op_sel_hi:[0,1,1] neg_lo:[0,0,1] neg_hi:[0,0,1]
	v_pk_fma_f32 v[144:145], v[204:205], v[204:205], v[144:145] op_sel_hi:[0,1,1]
	v_mov_b32_e32 v165, v161
	v_pk_add_f32 v[168:169], v[120:121], v[134:135]
	ds_write2_b64 v1, v[202:203], v[170:171] offset1:17
	v_pk_mov_b32 v[202:203], v[144:145], v[158:159] op_sel:[1,0]
	v_pk_add_f32 v[120:121], v[120:121], v[134:135] neg_lo:[0,1] neg_hi:[0,1]
	v_pk_add_f32 v[134:135], v[168:169], v[164:165]
	v_mov_b32_e32 v170, v158
	v_mov_b32_e32 v171, v145
	v_pk_mul_f32 v[202:203], v[144:145], v[202:203] op_sel:[1,0]
	v_pk_mul_f32 v[144:145], v[134:135], v[144:145] op_sel:[1,1] op_sel_hi:[0,1]
	v_pk_fma_f32 v[206:207], v[158:159], v[170:171], v[202:203] op_sel_hi:[0,1,1] neg_lo:[0,0,1] neg_hi:[0,0,1]
	v_pk_fma_f32 v[202:203], v[158:159], v[170:171], v[202:203] op_sel_hi:[0,1,1]
	v_pk_fma_f32 v[216:217], v[134:135], v[158:159], v[144:145] neg_lo:[0,0,1] neg_hi:[0,0,1]
	v_pk_fma_f32 v[134:135], v[134:135], v[158:159], v[144:145] op_sel_hi:[1,0,1]
	v_pk_mul_f32 v[144:145], v[170:171], v[202:203] op_sel:[0,1]
	v_pk_add_f32 v[132:133], v[132:133], v[176:177] neg_lo:[0,1] neg_hi:[0,1]
	v_pk_fma_f32 v[158:159], v[170:171], v[206:207], v[144:145] op_sel:[0,0,1] op_sel_hi:[1,0,0] neg_lo:[0,0,1] neg_hi:[0,0,1]
	v_pk_fma_f32 v[144:145], v[170:171], v[206:207], v[144:145] op_sel:[0,0,1] op_sel_hi:[1,0,0]
	v_sub_f32_e32 v142, v142, v162
	v_mov_b32_e32 v177, v145
	v_pk_mov_b32 v[144:145], v[144:145], v[158:159] op_sel:[1,0]
	v_mov_b32_e32 v205, v166
	v_mov_b32_e32 v208, v206
	v_mov_b32_e32 v209, v203
	v_pk_add_f32 v[218:219], v[120:121], v[120:121] op_sel:[0,1] op_sel_hi:[0,1]
	v_pk_mul_f32 v[142:143], v[142:143], v[144:145] op_sel_hi:[0,1]
	v_pk_mul_f32 v[172:173], v[204:205], v[170:171]
	v_pk_mul_f32 v[174:175], v[166:167], v[170:171]
	v_mov_b32_e32 v176, v158
	v_pk_fma_f32 v[144:145], v[218:219], v[158:159], v[142:143] neg_lo:[0,0,1] neg_hi:[0,0,1]
	v_pk_mul_f32 v[158:159], v[208:209], v[202:203] op_sel:[0,1]
	v_pk_add_f32 v[130:131], v[130:131], v[138:139] neg_lo:[0,1] neg_hi:[0,1]
	v_pk_add_f32 v[138:139], v[140:141], v[124:125]
	v_pk_add_f32 v[146:147], v[126:127], v[122:123]
	v_pk_fma_f32 v[142:143], v[218:219], v[176:177], v[142:143]
	v_pk_fma_f32 v[162:163], v[206:207], v[208:209], v[158:159] op_sel:[0,0,1] op_sel_hi:[0,1,0] neg_lo:[0,0,1] neg_hi:[0,0,1]
	v_pk_fma_f32 v[158:159], v[206:207], v[208:209], v[158:159] op_sel:[0,0,1] op_sel_hi:[0,1,0]
	v_mov_b32_e32 v220, v172
	v_mov_b32_e32 v221, v175
	v_pk_mov_b32 v[172:173], v[172:173], v[174:175] op_sel:[1,0]
	v_pk_add_f32 v[156:157], v[138:139], v[146:147]
	v_mov_b32_e32 v145, v143
	v_pk_add_f32 v[142:143], v[180:181], v[182:183] neg_lo:[0,1] neg_hi:[0,1]
	v_pk_mov_b32 v[182:183], v[158:159], v[162:163] op_sel:[1,0]
	v_pk_add_f32 v[174:175], v[220:221], v[172:173]
	v_pk_add_f32 v[172:173], v[220:221], v[172:173] neg_lo:[0,1] neg_hi:[0,1]
	v_pk_mul_f32 v[210:211], v[204:205], v[208:209]
	v_pk_mul_f32 v[212:213], v[166:167], v[208:209]
	v_pk_add_f32 v[128:129], v[136:137], v[128:129] neg_lo:[0,1] neg_hi:[0,1]
	v_mov_b32_e32 v180, v162
	v_mov_b32_e32 v181, v159
	v_pk_mul_f32 v[166:167], v[166:167], v[182:183] op_sel_hi:[0,1]
	v_pk_mul_f32 v[222:223], v[156:157], v[172:173] op_sel:[0,1]
	v_pk_mov_b32 v[214:215], v[202:203], v[206:207] op_sel:[1,0]
	v_mov_b32_e32 v217, v135
	v_pk_add_f32 v[134:135], v[128:129], v[132:133] op_sel:[0,1] op_sel_hi:[1,0]
	v_pk_add_f32 v[128:129], v[128:129], v[132:133] op_sel:[0,1] op_sel_hi:[1,0] neg_lo:[0,1] neg_hi:[0,1]
	v_pk_fma_f32 v[202:203], v[204:205], v[180:181], v[166:167] op_sel_hi:[0,1,1]
	v_pk_fma_f32 v[166:167], v[204:205], v[180:181], v[166:167] op_sel_hi:[0,1,1] neg_lo:[0,0,1] neg_hi:[0,0,1]
	v_pk_fma_f32 v[224:225], v[156:157], v[174:175], v[222:223] op_sel:[0,0,1] op_sel_hi:[1,1,0] neg_lo:[0,0,1] neg_hi:[0,0,1]
	v_pk_fma_f32 v[156:157], v[156:157], v[174:175], v[222:223] op_sel:[0,0,1] op_sel_hi:[1,0,0]
	v_mov_b32_e32 v226, v210
	v_mov_b32_e32 v227, v213
	v_pk_mov_b32 v[210:211], v[210:211], v[212:213] op_sel:[1,0]
	v_pk_mov_b32 v[136:137], v[128:129], v[134:135] op_sel:[1,0]
	v_mov_b32_e32 v205, v167
	v_mov_b32_e32 v225, v157
	v_pk_mul_f32 v[156:157], v[208:209], v[172:173] op_sel:[0,1]
	v_pk_add_f32 v[212:213], v[226:227], v[210:211]
	v_pk_add_f32 v[210:211], v[226:227], v[210:211] neg_lo:[0,1] neg_hi:[0,1]
	v_pk_mov_b32 v[166:167], v[166:167], v[202:203] op_sel:[1,0]
	v_mov_b32_e32 v204, v202
	v_mov_b32_e32 v221, v173
	v_pk_fma_f32 v[172:173], v[208:209], v[174:175], v[156:157] op_sel:[0,0,1] op_sel_hi:[1,0,0] neg_lo:[0,0,1] neg_hi:[0,0,1]
	v_pk_fma_f32 v[156:157], v[208:209], v[174:175], v[156:157] op_sel:[0,0,1] op_sel_hi:[1,0,0]
	v_pk_mul_f32 v[136:137], v[136:137], v[210:211] op_sel:[0,1]
	v_pk_mul_f32 v[166:167], v[130:131], v[166:167] op_sel:[1,0]
	v_mov_b32_e32 v220, v174
	v_mov_b32_e32 v174, v172
	v_mov_b32_e32 v175, v157
	v_mov_b32_e32 v226, v212
	v_mov_b32_e32 v227, v211
	v_pk_fma_f32 v[210:211], v[134:135], v[212:213], v[136:137] neg_lo:[0,0,1] neg_hi:[0,0,1]
	v_fma_f32 v132, v134, v212, v136
	v_fma_f32 v133, v129, v212, v137
	v_pk_fma_f32 v[202:203], v[130:131], v[202:203], v[166:167] neg_lo:[0,0,1] neg_hi:[0,0,1]
	v_pk_fma_f32 v[130:131], v[130:131], v[204:205], v[166:167] op_sel_hi:[0,1,1]
	v_pk_mul_f32 v[158:159], v[142:143], v[158:159] op_sel:[1,1] op_sel_hi:[0,1]
	v_pk_mul_f32 v[218:219], v[170:171], v[180:181]
	v_pk_mul_f32 v[170:171], v[170:171], v[182:183]
	ds_write2_b64 v1, v[216:217], v[224:225] offset0:34 offset1:51
	v_pk_mul_f32 v[216:217], v[220:221], v[180:181]
	v_pk_mul_f32 v[220:221], v[220:221], v[182:183]
	v_pk_mul_f32 v[222:223], v[208:209], v[180:181]
	v_pk_mul_f32 v[224:225], v[208:209], v[182:183]
	v_mov_b32_e32 v211, v133
	v_pk_mul_f32 v[132:133], v[180:181], v[226:227]
	v_pk_mul_f32 v[136:137], v[182:183], v[226:227]
	v_mov_b32_e32 v203, v131
	v_pk_mul_f32 v[130:131], v[180:181], v[176:177]
	v_pk_mul_f32 v[166:167], v[182:183], v[176:177]
	v_pk_mul_f32 v[176:177], v[180:181], v[174:175]
	v_pk_mul_f32 v[180:181], v[182:183], v[174:175]
	v_pk_fma_f32 v[182:183], v[142:143], v[162:163], v[158:159] neg_lo:[0,0,1] neg_hi:[0,0,1]
	v_pk_fma_f32 v[142:143], v[142:143], v[162:163], v[158:159] op_sel_hi:[1,0,1]
	v_mov_b32_e32 v183, v143
	v_sub_f32_e32 v142, v168, v164
	v_sub_f32_e32 v143, v161, v169
	v_pk_add_f32 v[158:159], v[170:171], v[170:171] op_sel:[0,1] op_sel_hi:[0,1]
	v_pk_mul_f32 v[158:159], v[142:143], v[158:159] op_sel:[1,0] op_sel_hi:[0,1]
	v_pk_add_f32 v[160:161], v[218:219], v[218:219] op_sel:[0,1] op_sel_hi:[0,1] neg_lo:[0,1] neg_hi:[0,1]
	v_pk_fma_f32 v[162:163], v[142:143], v[160:161], v[158:159] neg_lo:[0,0,1] neg_hi:[0,0,1]
	v_pk_fma_f32 v[142:143], v[142:143], v[160:161], v[158:159]
	v_pk_add_f32 v[2:3], v[2:3], v[114:115] neg_lo:[0,1] neg_hi:[0,1]
	v_mov_b32_e32 v163, v143
	v_mov_b32_e32 v143, v147
	v_sub_f32_e32 v138, v138, v146
	v_sub_f32_e32 v139, v143, v139
	v_pk_add_f32 v[142:143], v[220:221], v[220:221] op_sel:[0,1] op_sel_hi:[0,1]
	v_pk_add_f32 v[4:5], v[4:5], v[116:117] neg_lo:[0,1] neg_hi:[0,1]
	v_pk_mul_f32 v[142:143], v[138:139], v[142:143] op_sel:[1,0] op_sel_hi:[0,1]
	v_pk_add_f32 v[146:147], v[216:217], v[216:217] op_sel:[0,1] op_sel_hi:[0,1] neg_lo:[0,1] neg_hi:[0,1]
	v_pk_add_f32 v[114:115], v[2:3], v[4:5] op_sel:[0,1] op_sel_hi:[1,0]
	v_pk_add_f32 v[2:3], v[2:3], v[4:5] op_sel:[0,1] op_sel_hi:[1,0] neg_lo:[0,1] neg_hi:[0,1]
	v_pk_fma_f32 v[158:159], v[138:139], v[146:147], v[142:143] neg_lo:[0,0,1] neg_hi:[0,0,1]
	v_pk_fma_f32 v[138:139], v[138:139], v[146:147], v[142:143]
	v_pk_mul_f32 v[116:117], v[2:3], v[214:215] op_sel:[1,0]
	v_mov_b32_e32 v159, v139
	v_pk_fma_f32 v[138:139], v[114:115], v[206:207], v[116:117] neg_lo:[0,0,1] neg_hi:[0,0,1]
	v_pk_fma_f32 v[116:117], v[114:115], v[208:209], v[116:117] op_sel_hi:[0,1,1]
	v_mov_b32_e32 v5, v115
	v_mov_b32_e32 v139, v117
	v_pk_mov_b32 v[114:115], v[114:115], v[2:3] op_sel:[1,0]
	v_pk_add_f32 v[116:117], v[224:225], v[224:225] op_sel:[0,1] op_sel_hi:[0,1]
	v_mov_b32_e32 v4, v2
	v_pk_mul_f32 v[114:115], v[114:115], v[116:117]
	v_pk_add_f32 v[116:117], v[222:223], v[222:223] op_sel:[0,1] op_sel_hi:[0,1] neg_lo:[0,1] neg_hi:[0,1]
	v_pk_fma_f32 v[2:3], v[2:3], v[116:117], v[114:115] neg_lo:[0,0,1] neg_hi:[0,0,1]
	v_pk_fma_f32 v[4:5], v[4:5], v[116:117], v[114:115]
	v_pk_mov_b32 v[114:115], v[134:135], v[128:129] op_sel:[1,0]
	v_pk_add_f32 v[116:117], v[136:137], v[136:137] op_sel:[0,1] op_sel_hi:[0,1]
	v_mov_b32_e32 v3, v5
	v_mov_b32_e32 v4, v128
	v_mov_b32_e32 v5, v135
	v_pk_mul_f32 v[114:115], v[114:115], v[116:117]
	v_pk_add_f32 v[116:117], v[132:133], v[132:133] op_sel:[0,1] op_sel_hi:[0,1] neg_lo:[0,1] neg_hi:[0,1]
	v_pk_fma_f32 v[128:129], v[128:129], v[116:117], v[114:115] neg_lo:[0,0,1] neg_hi:[0,0,1]
	v_pk_fma_f32 v[4:5], v[4:5], v[116:117], v[114:115]
	v_pk_add_f32 v[114:115], v[166:167], v[166:167] op_sel:[0,1] op_sel_hi:[0,1]
	v_mov_b32_e32 v129, v5
	ds_write2_b64 v1, v[2:3], v[128:129] offset0:204 offset1:221
	v_mov_b32_e32 v3, v130
	v_sub_f32_e32 v2, v120, v121
	v_sub_f32_e32 v3, v3, v131
	v_mul_f32_e32 v4, v118, v114
	v_mul_f32_e32 v5, v2, v115
	v_pk_mov_b32 v[114:115], v[2:3], v[118:119] op_sel:[1,0]
	v_pk_mov_b32 v[156:157], v[156:157], v[172:173] op_sel:[1,0]
	v_pk_fma_f32 v[116:117], v[2:3], v[114:115], v[4:5] neg_lo:[0,0,1] neg_hi:[0,0,1]
	v_pk_fma_f32 v[2:3], v[2:3], v[114:115], v[4:5]
	v_mov_b32_e32 v117, v3
	v_mov_b32_e32 v3, v126
	v_mov_b32_e32 v5, v122
	v_sub_f32_e32 v2, v124, v140
	v_sub_f32_e32 v3, v3, v5
	v_sub_f32_e32 v4, v141, v125
	v_sub_f32_e32 v5, v127, v123
	ds_write2_b64 v1, v[182:183], v[202:203] offset0:136 offset1:153
	v_pk_add_f32 v[114:115], v[4:5], v[2:3]
	v_pk_add_f32 v[118:119], v[2:3], v[4:5] neg_lo:[0,1] neg_hi:[0,1]
	v_sub_f32_e32 v2, v5, v3
	v_pk_mul_f32 v[2:3], v[2:3], v[156:157] op_sel_hi:[0,1]
	v_pk_fma_f32 v[4:5], v[114:115], v[172:173], v[2:3] neg_lo:[0,0,1] neg_hi:[0,0,1]
	v_pk_fma_f32 v[2:3], v[114:115], v[174:175], v[2:3] op_sel_hi:[0,1,1]
	v_mov_b32_e32 v5, v3
	ds_write2_b64 v1, v[144:145], v[4:5] offset0:102 offset1:119
	v_pk_mov_b32 v[2:3], v[114:115], v[118:119] op_sel:[1,0]
	v_pk_add_f32 v[4:5], v[180:181], v[180:181] op_sel:[0,1] op_sel_hi:[0,1]
	v_mov_b32_e32 v120, v118
	v_mov_b32_e32 v121, v115
	v_pk_mul_f32 v[2:3], v[2:3], v[4:5]
	v_pk_add_f32 v[4:5], v[176:177], v[176:177] op_sel:[0,1] op_sel_hi:[0,1] neg_lo:[0,1] neg_hi:[0,1]
	v_pk_fma_f32 v[114:115], v[118:119], v[4:5], v[2:3] neg_lo:[0,0,1] neg_hi:[0,0,1]
	v_pk_fma_f32 v[2:3], v[120:121], v[4:5], v[2:3]
	ds_write2_b64 v1, v[162:163], v[158:159] offset0:170 offset1:187
	v_mov_b32_e32 v115, v3
	ds_write2_b64 v1, v[138:139], v[210:211] offset0:68 offset1:85
	ds_write2_b64 v1, v[116:117], v[114:115] offset0:238 offset1:255
	v_mov_b32_e32 v1, v12
	s_waitcnt lgkmcnt(0)
	s_barrier
	s_mov_b32 s77, s71
	v_mul_lo_u32 v1, v1, s33
	ds_read2_b64 v[2:5], v1 offset1:1
	ds_read2_b64 v[114:117], v1 offset0:2 offset1:3
	ds_read2_b64 v[118:121], v1 offset0:9 offset1:10
	ds_read2_b64 v[122:125], v1 offset0:4 offset1:5
	ds_read2_b64 v[126:129], v1 offset0:6 offset1:7
	ds_read2_b64 v[130:133], v1 offset0:13 offset1:14
	ds_read2_b64 v[134:137], v1 offset0:8 offset1:15
	ds_read2_b64 v[138:141], v1 offset0:11 offset1:12
	s_waitcnt lgkmcnt(5)
	v_add_f32_e32 v1, v4, v118
	s_waitcnt lgkmcnt(3)
	s_waitcnt lgkmcnt(2)
	v_add_f32_e32 v144, v124, v130
	s_waitcnt lgkmcnt(1)
	v_pk_add_f32 v[168:169], v[2:3], v[134:135]
	v_pk_add_f32 v[2:3], v[2:3], v[134:135] neg_lo:[0,1] neg_hi:[0,1]
	s_waitcnt lgkmcnt(0)
	v_pk_add_f32 v[134:135], v[122:123], v[140:141]
	v_pk_add_f32 v[122:123], v[122:123], v[140:141] neg_lo:[0,1] neg_hi:[0,1]
	v_add_f32_e32 v143, v1, v144
	v_sub_f32_e32 v1, v1, v144
	v_pk_mov_b32 v[164:165], v[114:115], v[114:115] op_sel:[1,0]
	v_pk_add_f32 v[170:171], v[2:3], v[122:123] op_sel:[0,1] op_sel_hi:[1,0]
	v_pk_add_f32 v[172:173], v[2:3], v[122:123] op_sel:[0,1] op_sel_hi:[1,0] neg_lo:[0,1] neg_hi:[0,1]
	v_add_f32_e32 v144, v116, v138
	v_add_f32_e32 v145, v128, v136
	v_pk_mov_b32 v[166:167], v[126:127], v[126:127] op_sel:[1,0]
	v_mov_b32_e32 v171, v173
	v_mov_b32_e32 v177, v118
	v_add_f32_e32 v142, v5, v119
	v_add_f32_e32 v146, v117, v139
	v_add_f32_e32 v147, v129, v137
	v_mov_b32_e32 v156, v117
	v_mov_b32_e32 v158, v139
	v_add_f32_e32 v172, v115, v121
	v_add_f32_e32 v173, v114, v120
	v_mov_b32_e32 v115, v4
	v_mov_b32_e32 v176, v120
	v_sub_f32_e32 v4, v164, v121
	v_sub_f32_e32 v5, v5, v119
	v_mov_b32_e32 v121, v130
	v_add_f32_e32 v155, v125, v131
	v_sub_f32_e32 v116, v116, v138
	v_sub_f32_e32 v117, v129, v137
	v_pk_add_f32 v[114:115], v[114:115], v[176:177] neg_lo:[0,1] neg_hi:[0,1]
	v_add_f32_e32 v118, v127, v133
	v_add_f32_e32 v119, v126, v132
	v_mov_b32_e32 v127, v124
	v_mov_b32_e32 v120, v132
	v_sub_f32_e32 v124, v166, v133
	v_sub_f32_e32 v125, v125, v131
	v_mov_b32_e32 v157, v128
	v_mov_b32_e32 v159, v136
	v_pk_add_f32 v[136:137], v[116:117], v[116:117] op_sel_hi:[0,1] neg_lo:[0,1] neg_hi:[0,1]
	v_pk_add_f32 v[120:121], v[126:127], v[120:121] neg_lo:[0,1] neg_hi:[0,1]
	v_mov_b32_e32 v166, v116
	v_mov_b32_e32 v167, v114
	v_pk_mov_b32 v[116:117], v[116:117], v[124:125] op_sel:[1,0]
	v_pk_add_f32 v[156:157], v[156:157], v[158:159] neg_lo:[0,1] neg_hi:[0,1]
	v_pk_add_f32 v[132:133], v[114:115], v[124:125] neg_lo:[0,1] neg_hi:[0,1]
	v_pk_add_f32 v[164:165], v[4:5], v[120:121]
	v_pk_add_f32 v[116:117], v[166:167], v[116:117]
	v_mov_b32_e32 v167, v4
	v_sub_f32_e32 v4, v5, v121
	v_add_f32_e32 v114, v115, v125
	v_pk_add_f32 v[138:139], v[156:157], v[156:157] op_sel:[0,1] op_sel_hi:[1,0]
	v_mov_b32_e32 v166, v156
	v_pk_mov_b32 v[156:157], v[156:157], v[120:121] op_sel:[1,0]
	v_pk_mul_f32 v[120:121], v[4:5], s[88:89] op_sel_hi:[0,1]
	v_pk_mul_f32 v[114:115], v[114:115], s[70:71] op_sel_hi:[0,1]
	v_pk_add_f32 v[156:157], v[166:167], v[156:157] neg_lo:[0,1] neg_hi:[0,1]
	v_pk_mov_b32 v[166:167], v[122:123], v[114:115] op_sel:[1,0]
	v_sub_f32_e32 v160, v142, v155
	v_pk_add_f32 v[128:129], v[144:145], v[144:145] op_sel:[0,1] op_sel_hi:[1,0]
	v_sub_f32_e32 v144, v144, v145
	v_pk_mov_b32 v[140:141], v[122:123], v[122:123] op_sel:[1,0]
	v_add_f32_e32 v124, v2, v166
	v_add_f32_e32 v125, v120, v167
	v_pk_fma_f32 v[166:167], v[4:5], s[88:89], v[114:115] op_sel_hi:[0,1,1]
	v_pk_fma_f32 v[4:5], v[4:5], s[88:89], v[114:115] op_sel_hi:[0,1,1] neg_lo:[0,0,1] neg_hi:[0,0,1]
	v_mul_f32_e32 v145, 0x3f3504f3, v1
	v_mul_f32_e32 v159, 0x3f3504f3, v160
	v_mul_f32_e32 v162, 0x3f3504f3, v144
	v_mov_b32_e32 v167, v5
	v_mov_b32_e32 v4, v121
	v_mov_b32_e32 v5, v3
	v_pk_mov_b32 v[114:115], v[114:115], v[122:123] op_sel:[1,0]
	v_mul_f32_e32 v140, 0x3ec3ef15, v133
	v_mul_f32_e32 v120, 0x3f6c835e, v165
	v_mov_b32_e32 v121, v3
	v_pk_add_f32 v[4:5], v[4:5], v[114:115] neg_lo:[0,1] neg_hi:[0,1]
	v_sub_f32_e32 v114, v168, v134
	v_sub_f32_e32 v115, v159, v145
	v_pk_add_f32 v[120:121], v[120:121], v[140:141]
	v_pk_mul_f32 v[140:141], v[116:117], s[72:73]
	v_pk_mul_f32 v[144:145], v[116:117], s[74:75]
	v_pk_mul_f32 v[116:117], v[116:117], s[88:89] op_sel_hi:[0,1]
	v_pk_fma_f32 v[206:207], v[156:157], s[70:71], v[116:117]
	v_pk_fma_f32 v[116:117], v[156:157], s[70:71], v[116:117] op_sel_hi:[0,1,1] neg_lo:[0,0,1] neg_hi:[0,0,1]
	v_mov_b32_e32 v207, v117
	v_pk_add_f32 v[116:117], v[146:147], v[146:147] op_sel:[0,1] op_sel_hi:[0,1] neg_lo:[0,1] neg_hi:[0,1]
	v_pk_fma_f32 v[176:177], v[156:157], s[72:73], v[144:145] neg_lo:[0,0,1] neg_hi:[0,0,1]
	v_fmac_f32_e32 v145, 0x3f3504f3, v157
	v_pk_fma_f32 v[140:141], v[156:157], s[74:75], v[140:141]
	v_pk_mul_f32 v[156:157], v[116:117], s[2:3]
	v_mov_b32_e32 v163, v135
	v_mov_b32_e32 v182, v138
	v_sub_f32_e32 v208, v156, v162
	v_sub_f32_e32 v209, v169, v163
	v_mov_b32_e32 v211, v162
	v_pk_fma_f32 v[116:117], v[116:117], s[2:3], v[162:163] op_sel_hi:[1,1,0] neg_lo:[0,0,1] neg_hi:[0,0,1]
	v_pk_mul_f32 v[138:139], v[138:139], s[88:89] op_sel_hi:[0,1]
	v_pk_mul_f32 v[162:163], v[136:137], s[76:77]
	v_pk_mov_b32 v[126:127], v[168:169], v[172:173] op_sel:[1,0]
	v_pk_mov_b32 v[130:131], v[134:135], v[118:119] op_sel:[1,0]
	v_mov_b32_e32 v122, v123
	v_pk_add_f32 v[174:175], v[168:169], v[134:135] neg_lo:[0,1] neg_hi:[0,1]
	v_pk_add_f32 v[126:127], v[126:127], v[130:131]
	v_pk_add_f32 v[130:131], v[172:173], v[118:119] neg_lo:[0,1] neg_hi:[0,1]
	v_mov_b32_e32 v181, v137
	v_pk_mov_b32 v[204:205], v[136:137], v[164:165] op_sel:[1,0]
	v_sub_f32_e32 v2, v2, v122
	v_sub_f32_e32 v3, v163, v139
	v_pk_fma_f32 v[122:123], v[136:137], s[76:77], v[138:139] op_sel:[1,0,0] neg_lo:[0,0,1] neg_hi:[0,0,1]
	v_pk_mov_b32 v[136:137], v[172:173], v[146:147] op_sel:[1,0]
	v_mov_b32_e32 v146, v119
	v_fmamk_f32 v160, v1, 0x3f3504f3, v159
	v_mov_b32_e32 v183, v132
	v_mov_b32_e32 v156, v172
	v_mov_b32_e32 v210, v118
	v_add_f32_e32 v134, v168, v134
	v_add_f32_e32 v135, v142, v155
	v_pk_add_f32 v[118:119], v[136:137], v[146:147]
	v_pk_add_f32 v[146:147], v[174:175], v[130:131] neg_lo:[0,1] neg_hi:[0,1]
	v_pk_add_f32 v[162:163], v[174:175], v[130:131]
	v_mov_b32_e32 v161, v131
	v_pk_mul_f32 v[158:159], v[132:133], s[20:21]
	v_pk_mul_f32 v[132:133], v[182:183], s[74:75]
	v_pk_mul_f32 v[182:183], v[182:183], s[72:73]
	v_pk_add_f32 v[156:157], v[156:157], v[210:211] neg_lo:[0,1] neg_hi:[0,1]
	v_mov_b32_e32 v147, v163
	v_pk_add_f32 v[130:131], v[208:209], v[160:161]
	v_pk_add_f32 v[162:163], v[208:209], v[160:161] neg_lo:[0,1] neg_hi:[0,1]
	v_mov_b32_e32 v180, v164
	v_pk_fma_f32 v[202:203], v[164:165], s[90:91], v[158:159] neg_lo:[0,0,1] neg_hi:[0,0,1]
	v_pk_fma_f32 v[164:165], v[164:165], s[2:3], v[158:159] op_sel_hi:[0,1,0] neg_lo:[0,0,1] neg_hi:[0,0,1]
	v_mov_b32_e32 v159, v182
	v_add_f32_e32 v136, v126, v127
	v_add_f32_e32 v137, v135, v119
	v_mov_b32_e32 v142, v134
	v_mov_b32_e32 v138, v118
	v_pk_add_f32 v[118:119], v[134:135], v[118:119] neg_lo:[0,1] neg_hi:[0,1]
	v_pk_add_f32 v[134:135], v[166:167], v[206:207]
	v_mov_b32_e32 v131, v163
	v_pk_add_f32 v[166:167], v[114:115], v[156:157]
	s_mov_b32 s92, s71
	s_mov_b32 s93, s3
	v_pk_fma_f32 v[158:159], v[180:181], s[78:79], v[158:159] neg_lo:[0,0,1] neg_hi:[0,0,1]
	v_pk_fma_f32 v[180:181], v[204:205], s[30:31], v[182:183] neg_lo:[0,0,1] neg_hi:[0,0,1]
	v_mov_b32_e32 v139, v128
	v_add_f32_e32 v116, v160, v116
	v_add_f32_e32 v117, v115, v117
	v_pk_add_f32 v[130:131], v[166:167], v[130:131]
	v_mov_b32_e32 v167, v163
	v_mov_b32_e32 v144, v145
	v_mov_b32_e32 v145, v177
	v_pk_fma_f32 v[132:133], v[204:205], s[92:93], v[132:133] neg_lo:[0,0,1] neg_hi:[0,0,1]
	v_pk_add_f32 v[138:139], v[142:143], v[138:139]
	v_pk_add_f32 v[116:117], v[166:167], v[116:117] neg_lo:[0,1] neg_hi:[0,1]
	v_add_f32_e32 v162, v2, v164
	v_add_f32_e32 v163, v121, v165
	v_pk_add_f32 v[164:165], v[120:121], v[180:181]
	v_pk_add_f32 v[166:167], v[202:203], v[2:3]
	v_mov_b32_e32 v202, v120
	v_mov_b32_e32 v3, v120
	v_mov_b32_e32 v120, v203
	v_pk_add_f32 v[168:169], v[136:137], v[136:137] op_sel:[1,0] op_sel_hi:[1,0]
	v_mov_b32_e32 v142, v126
	v_pk_mov_b32 v[126:127], v[126:127], v[128:129] op_sel:[1,0]
	v_pk_add_f32 v[128:129], v[170:171], v[144:145]
	v_pk_add_f32 v[120:121], v[120:121], v[132:133] neg_lo:[0,1] neg_hi:[0,1]
	v_pk_add_f32 v[132:133], v[166:167], v[164:165]
	v_pk_add_f32 v[166:167], v[138:139], v[138:139] op_sel:[1,0] op_sel_hi:[1,0]
	v_pk_mul_f32 v[168:169], v[76:77], v[168:169]
	v_pk_add_f32 v[124:125], v[124:125], v[140:141] op_sel:[0,1] op_sel_hi:[1,0] neg_lo:[0,1] neg_hi:[0,1]
	v_pk_add_f32 v[140:141], v[134:135], v[128:129]
	v_pk_fma_f32 v[170:171], v[14:15], v[166:167], v[168:169] neg_lo:[0,0,1] neg_hi:[0,0,1]
	v_pk_fma_f32 v[166:167], v[14:15], v[166:167], v[168:169]
	v_pk_add_f32 v[126:127], v[142:143], v[126:127] neg_lo:[0,1] neg_hi:[0,1]
	v_mov_b32_e32 v171, v167
	v_pk_mul_f32 v[166:167], v[26:27], v[140:141] op_sel:[0,1] op_sel_hi:[1,0]
	v_pk_add_f32 v[4:5], v[4:5], v[176:177] neg_lo:[0,1] neg_hi:[0,1]
	v_pk_fma_f32 v[168:169], v[24:25], v[140:141], v[166:167] neg_lo:[0,0,1] neg_hi:[0,0,1]
	v_pk_fma_f32 v[140:141], v[24:25], v[140:141], v[166:167]
	v_pk_mul_f32 v[166:167], v[42:43], v[130:131] op_sel:[0,1] op_sel_hi:[1,0]
	v_pk_add_f32 v[128:129], v[128:129], v[134:135] neg_lo:[0,1] neg_hi:[0,1]
	v_pk_add_f32 v[134:135], v[4:5], v[124:125]
	v_pk_add_f32 v[142:143], v[4:5], v[124:125] neg_lo:[0,1] neg_hi:[0,1]
	v_pk_mov_b32 v[114:115], v[114:115], v[160:161] op_sel:[1,0]
	v_pk_mov_b32 v[156:157], v[156:157], v[208:209] op_sel:[1,0]
	v_pk_fma_f32 v[172:173], v[40:41], v[130:131], v[166:167] neg_lo:[0,0,1] neg_hi:[0,0,1]
	v_pk_fma_f32 v[130:131], v[40:41], v[130:131], v[166:167]
	v_pk_mul_f32 v[166:167], v[58:59], v[132:133] op_sel:[0,1] op_sel_hi:[1,0]
	v_pk_add_f32 v[176:177], v[126:127], v[126:127] op_sel:[0,1] op_sel_hi:[0,1] neg_lo:[0,1] neg_hi:[0,1]
	v_mov_b32_e32 v145, v143
	v_pk_add_f32 v[114:115], v[114:115], v[156:157] neg_lo:[0,1] neg_hi:[0,1]
	v_pk_fma_f32 v[174:175], v[56:57], v[132:133], v[166:167] neg_lo:[0,0,1] neg_hi:[0,0,1]
	v_pk_fma_f32 v[132:133], v[56:57], v[132:133], v[166:167]
	v_pk_add_f32 v[166:167], v[118:119], v[118:119] op_sel:[0,1] op_sel_hi:[0,1]
	v_pk_mul_f32 v[176:177], v[72:73], v[176:177]
	v_pk_mov_b32 v[142:143], v[142:143], v[134:135] op_sel:[1,0]
	v_mov_b32_e32 v144, v134
	v_pk_add_f32 v[156:157], v[146:147], v[114:115]
	v_pk_add_f32 v[114:115], v[146:147], v[114:115] neg_lo:[0,1] neg_hi:[0,1]
	v_pk_fma_f32 v[180:181], v[18:19], v[166:167], v[176:177] neg_lo:[0,0,1] neg_hi:[0,0,1]
	v_pk_fma_f32 v[166:167], v[18:19], v[166:167], v[176:177]
	v_pk_mul_f32 v[142:143], v[34:35], v[142:143]
	v_pk_add_f32 v[122:123], v[202:203], v[122:123]
	v_pk_add_f32 v[2:3], v[2:3], v[158:159] neg_lo:[0,1] neg_hi:[0,1]
	v_mov_b32_e32 v181, v167
	v_pk_fma_f32 v[166:167], v[32:33], v[144:145], v[142:143] neg_lo:[0,0,1] neg_hi:[0,0,1]
	v_pk_fma_f32 v[142:143], v[32:33], v[144:145], v[142:143]
	v_pk_mov_b32 v[144:145], v[114:115], v[156:157] op_sel:[1,0]
	v_pk_add_f32 v[122:123], v[162:163], v[122:123] neg_lo:[0,1] neg_hi:[0,1]
	v_pk_add_f32 v[158:159], v[120:121], v[2:3]
	v_pk_add_f32 v[162:163], v[120:121], v[2:3] neg_lo:[0,1] neg_hi:[0,1]
	v_pk_mul_f32 v[144:145], v[50:51], v[144:145]
	v_pk_add_f32 v[136:137], v[136:137], v[136:137] op_sel:[0,1] op_sel_hi:[0,1] neg_lo:[0,1] neg_hi:[0,1]
	v_fma_f32 v176, v48, v156, -v144
	v_fma_f32 v177, v49, v115, -v145
	v_fma_f32 v144, v48, v156, v144
	v_fma_f32 v145, v49, v115, v145
	v_pk_mov_b32 v[146:147], v[162:163], v[158:159] op_sel:[1,0]
	v_mov_b32_e32 v164, v158
	v_mov_b32_e32 v165, v163
	v_pk_mul_f32 v[146:147], v[66:67], v[146:147]
	v_pk_add_f32 v[138:139], v[138:139], v[138:139] op_sel:[0,1] op_sel_hi:[0,1] neg_lo:[0,1] neg_hi:[0,1]
	v_pk_mul_f32 v[136:137], v[78:79], v[136:137]
	v_pk_fma_f32 v[162:163], v[64:65], v[164:165], v[146:147] neg_lo:[0,0,1] neg_hi:[0,0,1]
	v_pk_fma_f32 v[146:147], v[64:65], v[164:165], v[146:147]
	v_pk_fma_f32 v[164:165], v[16:17], v[138:139], v[136:137] neg_lo:[0,0,1] neg_hi:[0,0,1]
	v_pk_fma_f32 v[136:137], v[16:17], v[138:139], v[136:137]
	v_pk_add_f32 v[4:5], v[124:125], v[4:5] neg_lo:[0,1] neg_hi:[0,1]
	v_mov_b32_e32 v165, v137
	v_pk_mul_f32 v[136:137], v[30:31], v[128:129] op_sel:[0,1] op_sel_hi:[1,0]
	v_pk_add_f32 v[2:3], v[2:3], v[120:121] neg_lo:[0,1] neg_hi:[0,1]
	v_pk_fma_f32 v[138:139], v[28:29], v[128:129], v[136:137] neg_lo:[0,0,1] neg_hi:[0,0,1]
	v_pk_fma_f32 v[128:129], v[28:29], v[128:129], v[136:137]
	v_pk_mul_f32 v[136:137], v[46:47], v[116:117] op_sel:[0,1] op_sel_hi:[1,0]
	v_pk_add_f32 v[126:127], v[126:127], v[126:127] op_sel:[1,0] op_sel_hi:[1,0]
	v_mov_b32_e32 v124, v4
	v_mov_b32_e32 v160, v114
	v_mov_b32_e32 v120, v2
	v_pk_fma_f32 v[182:183], v[44:45], v[116:117], v[136:137] neg_lo:[0,0,1] neg_hi:[0,0,1]
	v_pk_fma_f32 v[116:117], v[44:45], v[116:117], v[136:137]
	v_pk_mul_f32 v[136:137], v[62:63], v[122:123] op_sel:[0,1] op_sel_hi:[1,0]
	v_pk_add_f32 v[118:119], v[118:119], v[118:119] op_sel:[0,1] op_sel_hi:[0,1] neg_lo:[0,1] neg_hi:[0,1]
	v_pk_mul_f32 v[126:127], v[74:75], v[126:127]
	v_pk_mov_b32 v[4:5], v[134:135], v[4:5] op_sel:[1,0]
	v_pk_mov_b32 v[114:115], v[156:157], v[114:115] op_sel:[1,0]
	v_pk_mov_b32 v[2:3], v[158:159], v[2:3] op_sel:[1,0]
	v_mov_b32_e32 v125, v135
	v_mov_b32_e32 v161, v157
	v_mov_b32_e32 v121, v159
	v_pk_fma_f32 v[202:203], v[60:61], v[122:123], v[136:137] neg_lo:[0,0,1] neg_hi:[0,0,1]
	v_pk_fma_f32 v[122:123], v[60:61], v[122:123], v[136:137]
	v_pk_fma_f32 v[136:137], v[20:21], v[118:119], v[126:127] neg_lo:[0,0,1] neg_hi:[0,0,1]
	v_pk_fma_f32 v[118:119], v[20:21], v[118:119], v[126:127]
	v_pk_mul_f32 v[4:5], v[38:39], v[4:5]
	v_pk_mul_f32 v[114:115], v[54:55], v[114:115]
	v_pk_mul_f32 v[2:3], v[70:71], v[2:3]
	v_mov_b32_e32 v137, v119
	v_pk_fma_f32 v[118:119], v[36:37], v[124:125], v[4:5] neg_lo:[0,0,1] neg_hi:[0,0,1]
	v_pk_fma_f32 v[4:5], v[36:37], v[124:125], v[4:5]
	v_pk_fma_f32 v[124:125], v[52:53], v[160:161], v[114:115] neg_lo:[0,0,1] neg_hi:[0,0,1]
	v_pk_fma_f32 v[126:127], v[68:69], v[120:121], v[2:3] neg_lo:[0,0,1] neg_hi:[0,0,1]
	v_pk_fma_f32 v[2:3], v[68:69], v[120:121], v[2:3]
	v_mov_b32_e32 v163, v147
	v_pk_fma_f32 v[114:115], v[52:53], v[160:161], v[114:115]
	v_mov_b32_e32 v127, v3
	v_add_f32_e32 v206, v172, v182
	v_add_f32_e32 v207, v131, v117
	v_add_f32_e32 v212, v174, v202
	v_add_f32_e32 v213, v133, v123
	v_mov_b32_e32 v140, v131
	v_mov_b32_e32 v175, v131
	v_mov_b32_e32 v203, v117
	v_pk_mov_b32 v[130:131], v[146:147], v[176:177] op_sel:[1,0]
	v_pk_mov_b32 v[2:3], v[2:3], v[124:125] op_sel:[1,0]
	v_pk_add_f32 v[214:215], v[162:163], v[126:127]
	v_mov_b32_e32 v128, v117
	v_pk_mov_b32 v[132:133], v[132:133], v[172:173] op_sel:[1,0]
	v_pk_mov_b32 v[122:123], v[122:123], v[182:183] op_sel:[1,0]
	v_pk_add_f32 v[116:117], v[174:175], v[202:203] neg_lo:[0,1] neg_hi:[0,1]
	v_pk_add_f32 v[2:3], v[130:131], v[2:3] neg_lo:[0,1] neg_hi:[0,1]
	v_mov_b32_e32 v119, v5
	v_add_f32_e32 v158, v168, v138
	v_add_f32_e32 v159, v141, v129
	v_add_f32_e32 v208, v176, v124
	v_add_f32_e32 v209, v145, v115
	v_mov_b32_e32 v225, v168
	v_sub_f32_e32 v4, v145, v115
	v_sub_f32_e32 v5, v143, v5
	v_mov_b32_e32 v142, v124
	v_pk_add_f32 v[122:123], v[132:133], v[122:123] neg_lo:[0,1] neg_hi:[0,1]
	v_sub_f32_e32 v114, v162, v126
	v_sub_f32_e32 v115, v145, v115
	v_pk_add_f32 v[124:125], v[116:117], v[2:3]
	v_pk_add_f32 v[2:3], v[116:117], v[2:3] neg_lo:[0,1] neg_hi:[0,1]
	v_mov_b32_e32 v167, v143
	v_sub_f32_e32 v139, v225, v138
	v_sub_f32_e32 v138, v172, v182
	v_pk_add_f32 v[128:129], v[140:141], v[128:129] neg_lo:[0,1] neg_hi:[0,1]
	v_pk_add_f32 v[126:127], v[122:123], v[114:115] neg_lo:[0,1] neg_hi:[0,1]
	v_pk_add_f32 v[114:115], v[122:123], v[114:115]
	v_pk_add_f32 v[120:121], v[170:171], v[164:165]
	v_pk_add_f32 v[134:135], v[180:181], v[136:137]
	v_pk_add_f32 v[160:161], v[166:167], v[118:119]
	v_sub_f32_e32 v119, v166, v118
	v_sub_f32_e32 v118, v176, v142
	v_pk_add_f32 v[130:131], v[138:139], v[4:5]
	v_mul_f32_e32 v141, 0x3f3504f3, v125
	v_mul_f32_e32 v116, s74, v124
	v_mul_f32_e32 v117, s75, v3
	v_mov_b32_e32 v125, v126
	v_mul_f32_e32 v4, 0x3f6c835e, v126
	v_pk_add_f32 v[156:157], v[120:121], v[134:135]
	v_pk_add_f32 v[210:211], v[206:207], v[208:209]
	v_pk_add_f32 v[216:217], v[212:213], v[214:215]
	v_pk_add_f32 v[120:121], v[120:121], v[134:135] neg_lo:[0,1] neg_hi:[0,1]
	v_pk_add_f32 v[134:135], v[206:207], v[208:209] neg_lo:[0,1] neg_hi:[0,1]
	v_mov_b32_e32 v207, v212
	v_mov_b32_e32 v209, v214
	v_fma_f32 v116, v126, s72, -v116
	v_fma_f32 v117, v115, s73, -v117
	v_pk_fma_f32 v[122:123], v[124:125], s[80:81], v[4:5] op_sel_hi:[1,1,0] neg_lo:[0,0,1] neg_hi:[0,0,1]
	v_add_f32_e32 v4, v129, v119
	v_pk_add_f32 v[204:205], v[158:159], v[160:161]
	v_pk_add_f32 v[136:137], v[180:181], v[136:137] neg_lo:[0,1] neg_hi:[0,1]
	v_mov_b32_e32 v206, v158
	v_mov_b32_e32 v208, v160
	v_sub_f32_e32 v158, v159, v161
	v_sub_f32_e32 v159, v213, v215
	v_pk_add_f32 v[132:133], v[128:129], v[118:119] neg_lo:[0,1] neg_hi:[0,1]
	v_pk_mul_f32 v[118:119], v[4:5], s[88:89] op_sel_hi:[0,1]
	v_sub_f32_e32 v4, v139, v5
	v_pk_add_f32 v[164:165], v[170:171], v[164:165] neg_lo:[0,1] neg_hi:[0,1]
	v_pk_mov_b32 v[170:171], v[136:137], v[136:137] op_sel:[1,0]
	v_pk_add_f32 v[206:207], v[206:207], v[208:209] neg_lo:[0,1] neg_hi:[0,1]
	v_pk_mul_f32 v[158:159], v[158:159], s[20:21] op_sel_hi:[1,0]
	v_pk_fma_f32 v[128:129], v[4:5], s[70:71], v[118:119] op_sel_hi:[0,1,1] neg_lo:[0,0,1] neg_hi:[0,0,1]
	v_pk_fma_f32 v[4:5], v[4:5], s[70:71], v[118:119] op_sel_hi:[0,1,1]
	v_pk_fma_f32 v[160:161], v[206:207], s[2:3], v[158:159] neg_lo:[0,0,1] neg_hi:[0,0,1]
	v_pk_fma_f32 v[208:209], v[206:207], s[2:3], v[158:159]
	v_pk_fma_f32 v[158:159], v[206:207], s[20:21], v[158:159] op_sel_hi:[1,0,1] neg_lo:[0,0,1] neg_hi:[0,0,1]
	v_pk_add_f32 v[206:207], v[120:121], v[134:135] op_sel:[0,1] op_sel_hi:[1,0] neg_lo:[0,1] neg_hi:[0,1]
	v_pk_add_f32 v[120:121], v[120:121], v[134:135] op_sel:[0,1] op_sel_hi:[1,0]
	v_mul_f32_e32 v170, 0x3f6c835e, v133
	s_mov_b32 s92, s3
	s_mov_b32 s93, s21
	v_pk_mul_f32 v[132:133], v[132:133], s[90:91]
	v_mov_b32_e32 v129, v5
	v_pk_mul_f32 v[4:5], v[114:115], s[70:71] op_sel_hi:[0,1]
	v_pk_add_f32 v[180:181], v[164:165], v[136:137] op_sel:[0,1] op_sel_hi:[1,0] neg_lo:[0,1] neg_hi:[0,1]
	v_pk_add_f32 v[136:137], v[164:165], v[136:137] op_sel:[0,1] op_sel_hi:[1,0]
	v_mov_b32_e32 v135, v121
	v_mul_f32_e32 v164, 0x3ec3ef15, v131
	v_mul_f32_e32 v121, 0x3f3504f3, v127
	v_pk_fma_f32 v[142:143], v[130:131], s[92:93], v[132:133] neg_lo:[0,0,1] neg_hi:[0,0,1]
	v_pk_fma_f32 v[130:131], v[130:131], s[92:93], v[132:133]
	v_pk_fma_f32 v[114:115], v[2:3], s[88:89], v[4:5] neg_lo:[0,0,1] neg_hi:[0,0,1]
	v_pk_fma_f32 v[2:3], v[2:3], s[88:89], v[4:5] op_sel_hi:[0,1,1]
	v_mov_b32_e32 v1, v6
	v_mov_b32_e32 v181, v137
	v_pk_add_f32 v[124:125], v[164:165], v[170:171] neg_lo:[0,1] neg_hi:[0,1]
	v_sub_f32_e32 v140, v121, v141
	v_fmac_f32_e32 v141, 0x3f3504f3, v127
	v_mov_b32_e32 v115, v3
	s_barrier
	v_pk_add_f32 v[218:219], v[156:157], v[210:211]
	v_pk_add_f32 v[220:221], v[204:205], v[216:217]
	v_pk_mov_b32 v[212:213], v[160:161], v[208:209] op_sel:[1,0]
	v_pk_add_f32 v[2:3], v[180:181], v[140:141]
	v_pk_add_f32 v[4:5], v[128:129], v[114:115]
	v_add_f32_e32 v126, v142, v136
	v_add_f32_e32 v127, v131, v122
	v_pk_add_f32 v[132:133], v[124:125], v[116:117]
	v_mul_lo_u32 v1, v1, s33
	v_pk_add_f32 v[222:223], v[218:219], v[220:221]
	v_mov_b32_e32 v134, v206
	v_pk_add_f32 v[212:213], v[158:159], v[212:213]
	v_pk_add_f32 v[118:119], v[2:3], v[4:5]
	v_pk_add_f32 v[138:139], v[132:133], v[126:127]
	v_pk_add_f32 v[214:215], v[134:135], v[212:213]
	ds_write2_b64 v1, v[222:223], v[118:119] offset1:1
	ds_write2_b64 v1, v[214:215], v[138:139] offset0:2 offset1:3
	v_pk_add_f32 v[118:119], v[156:157], v[210:211] neg_lo:[0,1] neg_hi:[0,1]
	v_pk_add_f32 v[138:139], v[204:205], v[216:217] neg_lo:[0,1] neg_hi:[0,1]
	v_pk_add_f32 v[114:115], v[128:129], v[114:115] neg_lo:[0,1] neg_hi:[0,1]
	v_pk_add_f32 v[144:145], v[118:119], v[138:139] op_sel:[0,1] op_sel_hi:[1,0] neg_lo:[0,1] neg_hi:[0,1]
	v_pk_add_f32 v[118:119], v[118:119], v[138:139] op_sel:[0,1] op_sel_hi:[1,0]
	v_pk_add_f32 v[138:139], v[180:181], v[140:141] neg_lo:[0,1] neg_hi:[0,1]
	v_pk_add_f32 v[128:129], v[138:139], v[114:115] op_sel:[0,1] op_sel_hi:[1,0] neg_lo:[0,1] neg_hi:[0,1]
	v_pk_add_f32 v[114:115], v[138:139], v[114:115] op_sel:[0,1] op_sel_hi:[1,0]
	v_mov_b32_e32 v138, v144
	v_mov_b32_e32 v139, v119
	v_mov_b32_e32 v140, v128
	v_mov_b32_e32 v141, v115
	v_pk_mov_b32 v[130:131], v[130:131], v[124:125] op_sel:[1,0]
	v_mov_b32_e32 v123, v116
	ds_write2_b64 v1, v[138:139], v[140:141] offset0:4 offset1:5
	v_mov_b32_e32 v121, v207
	v_sub_f32_e32 v138, v208, v159
	v_sub_f32_e32 v139, v158, v161
	v_pk_add_f32 v[122:123], v[130:131], v[122:123] neg_lo:[0,1] neg_hi:[0,1]
	v_sub_f32_e32 v116, v136, v142
	v_sub_f32_e32 v117, v125, v117
	v_pk_add_f32 v[140:141], v[120:121], v[138:139] neg_lo:[0,1] neg_hi:[0,1]
	v_pk_add_f32 v[120:121], v[120:121], v[138:139]
	v_pk_add_f32 v[124:125], v[116:117], v[122:123] neg_lo:[0,1] neg_hi:[0,1]
	v_pk_add_f32 v[116:117], v[116:117], v[122:123]
	v_mov_b32_e32 v122, v140
	v_mov_b32_e32 v123, v121
	v_mov_b32_e32 v130, v124
	v_mov_b32_e32 v131, v117
	ds_write2_b64 v1, v[122:123], v[130:131] offset0:6 offset1:7
	v_pk_add_f32 v[122:123], v[218:219], v[220:221] neg_lo:[0,1] neg_hi:[0,1]
	v_pk_add_f32 v[2:3], v[2:3], v[4:5] neg_lo:[0,1] neg_hi:[0,1]
	v_mov_b32_e32 v5, v133
	ds_write2_b64 v1, v[122:123], v[2:3] offset0:8 offset1:9
	v_pk_add_f32 v[2:3], v[134:135], v[212:213] neg_lo:[0,1] neg_hi:[0,1]
	v_sub_f32_e32 v4, v126, v132
	v_sub_f32_e32 v5, v5, v127
	v_mov_b32_e32 v119, v145
	v_mov_b32_e32 v115, v129
	v_mov_b32_e32 v121, v141
	v_mov_b32_e32 v117, v125
	ds_write2_b64 v1, v[2:3], v[4:5] offset0:10 offset1:11
	ds_write2_b64 v1, v[118:119], v[114:115] offset0:12 offset1:13
	ds_write2_b64 v1, v[120:121], v[116:117] offset0:14 offset1:15
	v_mov_b32_e32 v1, v12
	s_waitcnt lgkmcnt(0)
	s_barrier
	v_mov_b32_e32 v155, 0
	v_ashrrev_i32_e32 v2, 31, v1
	v_lshrrev_b32_e32 v2, 28, v2
	v_and_b32_e32 v142, 15, v1
	v_add_u32_e32 v1, v1, v2
	v_ashrrev_i32_e32 v1, 4, v1
	v_lshlrev_b32_e32 v2, 11, v1
	v_lshl_add_u32 v1, v1, 7, v2
	v_lshl_or_b32 v1, v142, 3, v1
	ds_read2_b64 v[2:5], v1 offset1:17
	ds_read2_b64 v[114:117], v1 offset0:34 offset1:51
	ds_read2_b64 v[118:121], v1 offset0:68 offset1:85
	ds_read2_b64 v[122:125], v1 offset0:102 offset1:119
	ds_read2_b64 v[126:129], v1 offset0:136 offset1:153
	ds_read2_b64 v[130:133], v1 offset0:170 offset1:187
	ds_read2_b64 v[134:137], v1 offset0:204 offset1:221
	ds_read2_b64 v[138:141], v1 offset0:238 offset1:255
	s_waitcnt lgkmcnt(4)
	v_mov_b32_e32 v214, v122
	v_cvt_f32_i32_e32 v142, v142
	v_mov_b32_e32 v215, v121
	v_pk_mov_b32 v[120:121], v[122:123], v[120:121] op_sel:[1,0]
	v_add_f32_e32 v142, v142, v142
	v_mul_f32_e32 v142, 0x3b800000, v142
	v_mul_f32_e32 v142, 0.5, v142
	v_sin_f32_e32 v143, v142
	v_cos_f32_e32 v142, v142
	v_mul_f32_e32 v146, v143, v143
	v_mul_f32_e32 v144, v142, v143
	v_pk_fma_f32 v[146:147], v[142:143], v[142:143], v[146:147] op_sel_hi:[1,1,0] neg_lo:[0,0,1] neg_hi:[0,0,1]
	v_add_f32_e32 v144, v144, v144
	v_mov_b32_e32 v156, v146
	v_mov_b32_e32 v157, v142
	v_mov_b32_e32 v145, v143
	v_pk_mul_f32 v[158:159], v[156:157], v[146:147] op_sel_hi:[1,0]
	v_pk_mul_f32 v[162:163], v[144:145], v[146:147] op_sel_hi:[1,0]
	v_pk_fma_f32 v[170:171], v[144:145], v[144:145], v[158:159] op_sel_hi:[1,0,1] neg_lo:[1,0,0] neg_hi:[1,0,0]
	v_pk_fma_f32 v[164:165], v[156:157], v[144:145], v[162:163] op_sel_hi:[1,0,1]
	v_mov_b32_e32 v172, v170
	v_mov_b32_e32 v173, v142
	v_pk_mul_f32 v[160:161], v[156:157], v[144:145] op_sel_hi:[1,0]
	v_pk_mul_f32 v[174:175], v[172:173], v[170:171] op_sel_hi:[1,0]
	v_mov_b32_e32 v147, v170
	v_mul_f32_e32 v202, v144, v170
	v_mul_f32_e32 v203, v164, v170
	v_mul_f32_e32 v204, v164, v146
	v_mul_f32_e32 v205, v143, v147
	v_mul_f32_e32 v182, v164, v144
	v_mul_f32_e32 v183, v164, v164
	v_add_f32_e32 v160, v203, v203
	v_add_f32_e32 v161, v161, v163
	v_fma_f32 v162, v172, v144, v204
	v_fma_f32 v163, v173, v164, v205
	v_fma_f32 v158, -v164, v164, v174
	v_fma_f32 v159, -v143, v144, v159
	v_pk_mul_f32 v[168:169], v[170:171], v[164:165] op_sel:[0,1] op_sel_hi:[1,0]
	v_pk_mul_f32 v[204:205], v[164:165], v[170:171] op_sel:[0,1] op_sel_hi:[1,0]
	v_mul_f32_e32 v206, v164, v170
	v_mul_f32_e32 v207, v143, v170
	v_fma_f32 v166, -v164, v164, v174
	v_fma_f32 v167, -v143, v164, v175
	v_pk_fma_f32 v[174:175], v[170:171], v[146:147], v[182:183] op_sel_hi:[0,1,1] neg_lo:[0,0,1] neg_hi:[0,0,1]
	v_pk_fma_f32 v[182:183], v[146:147], v[164:165], v[202:203] op_sel_hi:[1,0,1]
	v_add_f32_e32 v168, v168, v204
	v_add_f32_e32 v169, v203, v203
	v_mov_b32_e32 v205, v142
	v_pk_mul_f32 v[180:181], v[164:165], v[164:165] op_sel_hi:[0,1]
	v_pk_fma_f32 v[172:173], v[172:173], v[164:165], v[206:207] op_sel_hi:[1,0,1]
	v_mul_f32_e32 v142, v183, v146
	v_mul_f32_e32 v143, v143, v166
	v_pk_fma_f32 v[180:181], v[170:171], v[170:171], v[180:181] op_sel_hi:[0,1,1] neg_lo:[0,0,1] neg_hi:[0,0,1]
	v_fma_f32 v142, v166, v144, v142
	v_fma_f32 v143, v205, v183, v143
	v_pk_mov_b32 v[206:207], v[182:183], v[164:165] op_sel:[1,0]
	v_pk_mul_f32 v[208:209], v[206:207], v[168:169]
	v_pk_mul_f32 v[206:207], v[206:207], v[180:181] op_sel:[0,1] op_sel_hi:[1,0]
	v_pk_mul_f32 v[172:173], v[172:173], v[174:175]
	v_fma_f32 v174, v166, v181, -v208
	v_fma_f32 v175, v170, v180, -v209
	v_fma_f32 v204, v166, v168, v206
	v_fma_f32 v205, v170, v169, v207
	v_mov_b32_e32 v206, v114
	v_mov_b32_e32 v207, v5
	v_pk_mov_b32 v[4:5], v[114:115], v[4:5] op_sel:[1,0]
	v_pk_mul_f32 v[176:177], v[144:145], v[164:165] op_sel_hi:[1,0]
	v_pk_mul_f32 v[202:203], v[144:145], v[182:183] op_sel:[0,1]
	v_pk_mul_f32 v[114:115], v[4:5], v[144:145]
	v_pk_mul_f32 v[144:145], v[206:207], v[144:145]
	v_mul_f32_e32 v160, v170, v160
	v_mul_f32_e32 v161, v166, v161
	v_pk_fma_f32 v[208:209], v[206:207], v[156:157], v[114:115] neg_lo:[0,0,1] neg_hi:[0,0,1]
	v_pk_fma_f32 v[114:115], v[206:207], v[156:157], v[114:115]
	v_pk_fma_f32 v[206:207], v[4:5], v[156:157], v[144:145] neg_lo:[0,0,1] neg_hi:[0,0,1]
	v_pk_fma_f32 v[4:5], v[4:5], v[156:157], v[144:145]
	v_pk_fma_f32 v[176:177], v[156:157], v[170:171], v[176:177] op_sel_hi:[1,0,1] neg_lo:[0,0,1] neg_hi:[0,0,1]
	v_pk_fma_f32 v[202:203], v[156:157], v[166:167], v[202:203] op_sel_hi:[1,0,1] neg_lo:[0,0,1] neg_hi:[0,0,1]
	v_fma_f32 v158, v164, v158, v160
	v_fma_f32 v159, v183, v159, v161
	v_pk_mul_f32 v[160:161], v[182:183], v[162:163] op_sel:[1,0]
	v_pk_mov_b32 v[144:145], v[206:207], v[4:5] op_sel:[1,0]
	v_mul_f32_e32 v206, v117, v165
	v_pk_mul_f32 v[122:123], v[120:121], v[162:163]
	v_pk_mul_f32 v[162:163], v[214:215], v[162:163]
	v_pk_fma_f32 v[160:161], v[166:167], v[176:177], v[160:161] op_sel_hi:[0,1,1] neg_lo:[0,0,1] neg_hi:[0,0,1]
	v_fma_f32 v156, v116, v171, -v206
	v_fma_f32 v157, v117, v165, -v206
	v_mov_b32_e32 v210, v118
	v_mov_b32_e32 v211, v117
	v_pk_mov_b32 v[116:117], v[118:119], v[116:117] op_sel:[1,0]
	v_pk_fma_f32 v[216:217], v[214:215], v[176:177], v[122:123] neg_lo:[0,0,1] neg_hi:[0,0,1]
	v_pk_fma_f32 v[122:123], v[214:215], v[176:177], v[122:123]
	v_pk_fma_f32 v[214:215], v[120:121], v[176:177], v[162:163] neg_lo:[0,0,1] neg_hi:[0,0,1]
	v_pk_fma_f32 v[120:121], v[120:121], v[176:177], v[162:163]
	v_mov_b32_e32 v177, v119
	v_pk_mov_b32 v[118:119], v[124:125], v[118:119] op_sel:[1,0]
	v_mov_b32_e32 v169, v164
	v_pk_mul_f32 v[118:119], v[118:119], v[168:169]
	v_mov_b32_e32 v169, v181
	v_mul_f32_e32 v122, v125, v181
	v_pk_mul_f32 v[146:147], v[164:165], v[182:183] op_sel:[0,1]
	v_pk_mul_f32 v[116:117], v[116:117], v[164:165]
	v_mov_b32_e32 v176, v124
	v_pk_fma_f32 v[124:125], v[124:125], v[168:169], v[122:123] op_sel_hi:[1,1,0]
	s_waitcnt lgkmcnt(2)
	v_mov_b32_e32 v168, v130
	v_mov_b32_e32 v169, v129
	v_pk_mov_b32 v[128:129], v[130:131], v[128:129] op_sel:[1,0]
	v_pk_fma_f32 v[146:147], v[170:171], v[166:167], v[146:147] op_sel_hi:[1,0,1] neg_lo:[0,0,1] neg_hi:[0,0,1]
	v_pk_fma_f32 v[212:213], v[210:211], v[170:171], v[116:117] neg_lo:[0,0,1] neg_hi:[0,0,1]
	v_pk_fma_f32 v[116:117], v[210:211], v[170:171], v[116:117]
	v_pk_mov_b32 v[170:171], v[180:181], v[170:171] op_sel:[1,0]
	v_pk_mul_f32 v[130:131], v[128:129], v[142:143]
	v_pk_mul_f32 v[142:143], v[168:169], v[142:143]
	v_pk_fma_f32 v[164:165], v[176:177], v[170:171], v[118:119] neg_lo:[0,0,1] neg_hi:[0,0,1]
	v_pk_fma_f32 v[118:119], v[176:177], v[170:171], v[118:119]
	v_pk_fma_f32 v[170:171], v[168:169], v[202:203], v[130:131] neg_lo:[0,0,1] neg_hi:[0,0,1]
	v_pk_fma_f32 v[130:131], v[168:169], v[202:203], v[130:131]
	v_pk_fma_f32 v[168:169], v[128:129], v[202:203], v[142:143] neg_lo:[0,0,1] neg_hi:[0,0,1]
	v_pk_fma_f32 v[128:129], v[128:129], v[202:203], v[142:143]
	v_pk_mov_b32 v[202:203], v[132:133], v[126:127] op_sel:[1,0]
	v_pk_mov_b32 v[180:181], v[146:147], v[166:167] op_sel:[1,0]
	v_mul_f32_e32 v202, v202, v159
	v_mul_f32_e32 v203, v203, v183
	v_pk_fma_f32 v[172:173], v[166:167], v[182:183], v[172:173]
	v_fma_f32 v218, v132, v180, -v202
	v_fma_f32 v219, v127, v181, -v203
	v_fma_f32 v176, v132, v180, v202
	v_fma_f32 v177, v127, v181, v203
	v_mov_b32_e32 v181, v133
	s_waitcnt lgkmcnt(1)
	v_pk_mov_b32 v[132:133], v[134:135], v[132:133] op_sel:[1,0]
	v_mov_b32_e32 v180, v134
	v_pk_mul_f32 v[132:133], v[132:133], v[158:159]
	v_pk_mov_b32 v[182:183], v[182:183], v[204:205] op_sel:[1,0]
	v_pk_fma_f32 v[158:159], v[180:181], v[146:147], v[132:133] neg_lo:[0,0,1] neg_hi:[0,0,1]
	v_pk_fma_f32 v[132:133], v[180:181], v[146:147], v[132:133]
	s_waitcnt lgkmcnt(0)
	v_mov_b32_e32 v180, v138
	v_mov_b32_e32 v181, v137
	v_pk_mov_b32 v[136:137], v[138:139], v[136:137] op_sel:[1,0]
	v_mov_b32_e32 v167, v174
	v_pk_mul_f32 v[138:139], v[136:137], v[172:173]
	v_pk_mul_f32 v[172:173], v[180:181], v[172:173]
	v_pk_fma_f32 v[202:203], v[180:181], v[160:161], v[138:139] neg_lo:[0,0,1] neg_hi:[0,0,1]
	v_pk_fma_f32 v[138:139], v[180:181], v[160:161], v[138:139]
	v_pk_fma_f32 v[180:181], v[136:137], v[160:161], v[172:173] neg_lo:[0,0,1] neg_hi:[0,0,1]
	v_pk_fma_f32 v[136:137], v[136:137], v[160:161], v[172:173]
	v_mov_b32_e32 v173, v135
	v_pk_mov_b32 v[134:135], v[140:141], v[134:135] op_sel:[1,0]
	v_mov_b32_e32 v172, v140
	v_pk_mul_f32 v[134:135], v[134:135], v[204:205]
	v_pk_fma_f32 v[220:221], v[172:173], v[174:175], v[134:135] neg_lo:[0,0,1] neg_hi:[0,0,1]
	v_pk_fma_f32 v[134:135], v[172:173], v[174:175], v[134:135]
	v_pk_mov_b32 v[172:173], v[126:127], v[140:141] op_sel:[1,0]
	v_mov_b32_e32 v127, v141
	v_pk_mul_f32 v[172:173], v[172:173], v[182:183]
	v_pk_fma_f32 v[140:141], v[126:127], v[166:167], v[172:173] neg_lo:[0,0,1] neg_hi:[0,0,1]
	v_pk_fma_f32 v[126:127], v[126:127], v[166:167], v[172:173]
	v_pk_mov_b32 v[162:163], v[214:215], v[120:121] op_sel:[1,0]
	v_pk_mov_b32 v[142:143], v[168:169], v[128:129] op_sel:[1,0]
	v_pk_mov_b32 v[160:161], v[180:181], v[136:137] op_sel:[1,0]
	v_mov_b32_e32 v141, v127
	v_add_f32_e32 v172, v156, v218
	v_add_f32_e32 v173, v3, v177
	v_mov_b32_e32 v157, v4
	v_mov_b32_e32 v219, v128
	v_mov_b32_e32 v125, v216
	v_pk_mov_b32 v[126:127], v[126:127], v[202:203] op_sel:[1,0]
	v_mov_b32_e32 v211, v117
	v_mov_b32_e32 v147, v133
	v_mov_b32_e32 v167, v124
	v_add_f32_e32 v174, v164, v220
	v_add_f32_e32 v175, v119, v135
	v_pk_add_f32 v[142:143], v[144:145], v[142:143]
	v_pk_add_f32 v[144:145], v[162:163], v[160:161]
	v_add_f32_e32 v160, v208, v170
	v_add_f32_e32 v161, v115, v131
	v_sub_f32_e32 v114, v4, v128
	v_sub_f32_e32 v115, v115, v131
	v_pk_mov_b32 v[116:117], v[116:117], v[208:209] op_sel:[1,0]
	v_pk_mov_b32 v[132:133], v[132:133], v[170:171] op_sel:[1,0]
	v_mov_b32_e32 v165, v120
	v_mov_b32_e32 v221, v136
	v_pk_add_f32 v[4:5], v[156:157], v[218:219] neg_lo:[0,1] neg_hi:[0,1]
	v_pk_add_f32 v[124:125], v[124:125], v[126:127] neg_lo:[0,1] neg_hi:[0,1]
	v_mov_b32_e32 v166, v2
	v_add_f32_e32 v162, v216, v202
	v_add_f32_e32 v163, v123, v139
	v_mov_b32_e32 v206, v208
	v_mov_b32_e32 v168, v170
	v_sub_f32_e32 v122, v120, v136
	v_sub_f32_e32 v123, v123, v139
	v_mov_b32_e32 v217, v215
	v_mov_b32_e32 v180, v202
	v_pk_add_f32 v[116:117], v[116:117], v[132:133] neg_lo:[0,1] neg_hi:[0,1]
	v_pk_add_f32 v[120:121], v[164:165], v[220:221] neg_lo:[0,1] neg_hi:[0,1]
	v_pk_add_f32 v[126:127], v[4:5], v[124:125]
	v_pk_add_f32 v[4:5], v[4:5], v[124:125] neg_lo:[0,1] neg_hi:[0,1]
	v_pk_add_f32 v[166:167], v[166:167], v[140:141]
	v_mov_b32_e32 v141, v177
	v_pk_mov_b32 v[118:119], v[118:119], v[212:213] op_sel:[1,0]
	v_pk_mov_b32 v[134:135], v[134:135], v[158:159] op_sel:[1,0]
	v_pk_add_f32 v[168:169], v[206:207], v[168:169] neg_lo:[0,1] neg_hi:[0,1]
	v_pk_add_f32 v[130:131], v[216:217], v[180:181] neg_lo:[0,1] neg_hi:[0,1]
	v_pk_add_f32 v[132:133], v[116:117], v[120:121] neg_lo:[0,1] neg_hi:[0,1]
	v_pk_add_f32 v[116:117], v[116:117], v[120:121]
	v_pk_add_f32 v[2:3], v[2:3], v[140:141] neg_lo:[0,1] neg_hi:[0,1]
	v_pk_add_f32 v[118:119], v[118:119], v[134:135] neg_lo:[0,1] neg_hi:[0,1]
	v_pk_add_f32 v[128:129], v[168:169], v[122:123]
	v_pk_add_f32 v[136:137], v[114:115], v[130:131] neg_lo:[0,1] neg_hi:[0,1]
	v_mul_f32_e32 v139, 0x3f3504f3, v127
	v_mul_f32_e32 v120, s74, v126
	v_mul_f32_e32 v121, s75, v5
	v_mov_b32_e32 v127, v132
	v_mul_f32_e32 v114, 0x3f6c835e, v132
	v_add_f32_e32 v146, v212, v158
	v_add_f32_e32 v147, v211, v147
	v_pk_add_f32 v[134:135], v[2:3], v[118:119] neg_lo:[0,1] neg_hi:[0,1]
	v_pk_add_f32 v[140:141], v[2:3], v[118:119]
	v_mul_f32_e32 v2, 0x3ec3ef15, v129
	v_mul_f32_e32 v118, 0x3f6c835e, v137
	v_fma_f32 v120, v132, s72, -v120
	v_fma_f32 v121, v117, s73, -v121
	v_pk_fma_f32 v[124:125], v[126:127], s[80:81], v[114:115] op_sel_hi:[1,1,0] neg_lo:[0,0,1] neg_hi:[0,0,1]
	v_add_f32_e32 v114, v115, v131
	v_pk_add_f32 v[2:3], v[2:3], v[118:119] neg_lo:[0,1] neg_hi:[0,1]
	v_pk_mul_f32 v[114:115], v[114:115], s[88:89] op_sel_hi:[0,1]
	v_sub_f32_e32 v118, v169, v123
	v_pk_add_f32 v[204:205], v[142:143], v[144:145]
	v_pk_add_f32 v[222:223], v[146:147], v[166:167]
	v_sub_f32_e32 v158, v166, v146
	v_sub_f32_e32 v159, v160, v162
	v_mov_b32_e32 v176, v143
	v_mov_b32_e32 v212, v145
	v_pk_fma_f32 v[122:123], v[118:119], s[70:71], v[114:115] op_sel_hi:[0,1,1] neg_lo:[0,0,1] neg_hi:[0,0,1]
	v_pk_fma_f32 v[114:115], v[118:119], s[70:71], v[114:115] op_sel_hi:[0,1,1]
	v_sub_f32_e32 v142, v142, v144
	v_sub_f32_e32 v143, v172, v174
	v_sub_f32_e32 v144, v161, v163
	v_sub_f32_e32 v145, v147, v167
	v_pk_mul_f32 v[136:137], v[136:137], s[90:91]
	v_mov_b32_e32 v123, v115
	v_pk_mul_f32 v[114:115], v[116:117], s[70:71] op_sel_hi:[0,1]
	v_mov_b32_e32 v177, v173
	v_mov_b32_e32 v213, v175
	v_pk_mul_f32 v[144:145], v[144:145], s[20:21] op_sel_hi:[1,0]
	v_mul_f32_e32 v130, 0x3f3504f3, v133
	v_pk_fma_f32 v[156:157], v[128:129], s[92:93], v[136:137] neg_lo:[0,0,1] neg_hi:[0,0,1]
	v_pk_fma_f32 v[128:129], v[128:129], s[92:93], v[136:137]
	v_pk_fma_f32 v[116:117], v[4:5], s[88:89], v[114:115] neg_lo:[0,0,1] neg_hi:[0,0,1]
	v_pk_fma_f32 v[4:5], v[4:5], s[88:89], v[114:115] op_sel_hi:[0,1,1]
	v_pk_add_f32 v[182:183], v[160:161], v[162:163]
	v_pk_add_f32 v[210:211], v[172:173], v[174:175]
	v_mov_b32_e32 v135, v141
	v_pk_add_f32 v[176:177], v[176:177], v[212:213] neg_lo:[0,1] neg_hi:[0,1]
	v_pk_fma_f32 v[146:147], v[142:143], s[2:3], v[144:145] neg_lo:[0,0,1] neg_hi:[0,0,1]
	v_pk_fma_f32 v[160:161], v[142:143], s[2:3], v[144:145]
	v_sub_f32_e32 v138, v130, v139
	v_fmac_f32_e32 v139, 0x3f3504f3, v133
	v_mov_b32_e32 v117, v5
	v_pk_add_f32 v[224:225], v[204:205], v[210:211]
	v_pk_add_f32 v[226:227], v[182:183], v[222:223]
	v_pk_mov_b32 v[162:163], v[146:147], v[160:161] op_sel:[1,0]
	v_pk_fma_f32 v[142:143], v[142:143], s[20:21], v[144:145] op_sel_hi:[1,0,1] neg_lo:[0,0,1] neg_hi:[0,0,1]
	v_pk_add_f32 v[144:145], v[158:159], v[176:177] neg_lo:[0,1] neg_hi:[0,1]
	v_pk_add_f32 v[166:167], v[158:159], v[176:177]
	v_pk_add_f32 v[4:5], v[134:135], v[138:139]
	v_pk_add_f32 v[114:115], v[122:123], v[116:117]
	v_add_f32_e32 v126, v156, v140
	v_add_f32_e32 v127, v129, v124
	v_pk_add_f32 v[130:131], v[2:3], v[120:121]
	v_pk_add_f32 v[228:229], v[226:227], v[224:225]
	v_mov_b32_e32 v145, v167
	v_pk_add_f32 v[162:163], v[142:143], v[162:163]
	v_pk_add_f32 v[118:119], v[4:5], v[114:115]
	v_pk_add_f32 v[132:133], v[130:131], v[126:127]
	v_pk_add_f32 v[172:173], v[144:145], v[162:163]
	ds_write2_b64 v1, v[228:229], v[118:119] offset1:17
	ds_write2_b64 v1, v[172:173], v[132:133] offset0:34 offset1:51
	v_mov_b32_e32 v119, v204
	v_mov_b32_e32 v133, v210
	v_mov_b32_e32 v210, v183
	v_mov_b32_e32 v204, v223
	v_sub_f32_e32 v118, v222, v182
	v_sub_f32_e32 v119, v119, v133
	v_pk_add_f32 v[132:133], v[210:211], v[204:205] neg_lo:[0,1] neg_hi:[0,1]
	v_pk_add_f32 v[134:135], v[134:135], v[138:139] neg_lo:[0,1] neg_hi:[0,1]
	v_pk_add_f32 v[116:117], v[122:123], v[116:117] neg_lo:[0,1] neg_hi:[0,1]
	v_pk_add_f32 v[136:137], v[118:119], v[132:133] neg_lo:[0,1] neg_hi:[0,1]
	v_pk_add_f32 v[164:165], v[118:119], v[132:133]
	v_pk_add_f32 v[122:123], v[134:135], v[116:117] op_sel:[0,1] op_sel_hi:[1,0] neg_lo:[0,1] neg_hi:[0,1]
	v_pk_add_f32 v[116:117], v[134:135], v[116:117] op_sel:[0,1] op_sel_hi:[1,0]
	v_mov_b32_e32 v137, v165
	v_mov_b32_e32 v134, v122
	v_mov_b32_e32 v135, v117
	ds_write2_b64 v1, v[136:137], v[134:135] offset0:68 offset1:85
	v_pk_add_f32 v[134:135], v[176:177], v[158:159] neg_lo:[0,1] neg_hi:[0,1]
	v_mov_b32_e32 v161, v142
	v_mov_b32_e32 v146, v143
	v_pk_mov_b32 v[128:129], v[128:129], v[2:3] op_sel:[1,0]
	v_mov_b32_e32 v125, v120
	v_mov_b32_e32 v141, v3
	v_mov_b32_e32 v157, v121
	v_mov_b32_e32 v167, v135
	v_pk_add_f32 v[134:135], v[160:161], v[146:147] neg_lo:[0,1] neg_hi:[0,1]
	v_pk_add_f32 v[124:125], v[128:129], v[124:125] neg_lo:[0,1] neg_hi:[0,1]
	v_pk_add_f32 v[2:3], v[140:141], v[156:157] neg_lo:[0,1] neg_hi:[0,1]
	v_pk_add_f32 v[136:137], v[166:167], v[134:135] neg_lo:[0,1] neg_hi:[0,1]
	v_pk_add_f32 v[134:135], v[166:167], v[134:135]
	v_pk_add_f32 v[120:121], v[2:3], v[124:125] neg_lo:[0,1] neg_hi:[0,1]
	v_pk_add_f32 v[2:3], v[2:3], v[124:125]
	v_mov_b32_e32 v138, v136
	v_mov_b32_e32 v139, v135
	v_mov_b32_e32 v124, v120
	v_mov_b32_e32 v125, v3
	ds_write2_b64 v1, v[138:139], v[124:125] offset0:102 offset1:119
	v_mov_b32_e32 v124, v226
	v_mov_b32_e32 v125, v225
	v_mov_b32_e32 v225, v227
	v_pk_add_f32 v[124:125], v[124:125], v[224:225] neg_lo:[0,1] neg_hi:[0,1]
	v_pk_add_f32 v[4:5], v[4:5], v[114:115] neg_lo:[0,1] neg_hi:[0,1]
	v_mov_b32_e32 v115, v131
	ds_write2_b64 v1, v[124:125], v[4:5] offset0:136 offset1:153
	v_pk_add_f32 v[4:5], v[144:145], v[162:163] neg_lo:[0,1] neg_hi:[0,1]
	v_sub_f32_e32 v114, v126, v130
	v_sub_f32_e32 v115, v115, v127
	ds_write2_b64 v1, v[4:5], v[114:115] offset0:170 offset1:187
	v_pk_add_f32 v[4:5], v[132:133], v[118:119] neg_lo:[0,1] neg_hi:[0,1]
	v_mov_b32_e32 v135, v137
	v_mov_b32_e32 v3, v121
	v_mov_b32_e32 v165, v5
	v_mov_b32_e32 v117, v123
	ds_write2_b64 v1, v[134:135], v[2:3] offset0:238 offset1:255
	v_mov_b32_e32 v2, v6
	ds_write2_b64 v1, v[164:165], v[116:117] offset0:204 offset1:221
	s_waitcnt lgkmcnt(0)
	s_barrier
	s_lshl_b64 s[88:89], s[24:25], 1
	v_ashrrev_i32_e32 v3, 31, v2
	v_lshrrev_b32_e32 v3, 24, v3
	v_and_b32_e32 v1, 0xff, v2
	v_add_lshl_u32 v2, v2, v3, 4
	v_and_or_b32 v2, v2, s87, v1
	v_ashrrev_i32_e32 v3, 4, v2
	v_lshlrev_b32_e32 v2, 3, v2
	v_lshl_add_u32 v2, v3, 3, v2
	ds_read_b64 v[114:115], v2
	ds_read_b64 v[144:145], v2 offset:2176
	ds_read_b64 v[142:143], v2 offset:4352
	ds_read_b64 v[140:141], v2 offset:6528
	ds_read_b64 v[138:139], v2 offset:8704
	ds_read_b64 v[136:137], v2 offset:10880
	ds_read_b64 v[134:135], v2 offset:13056
	ds_read_b64 v[132:133], v2 offset:15232
	ds_read_b64 v[130:131], v2 offset:17408
	ds_read_b64 v[128:129], v2 offset:19584
	ds_read_b64 v[126:127], v2 offset:21760
	ds_read_b64 v[124:125], v2 offset:23936
	ds_read_b64 v[122:123], v2 offset:26112
	ds_read_b64 v[120:121], v2 offset:28288
	ds_read_b64 v[118:119], v2 offset:30464
	ds_read_b64 v[116:117], v2 offset:32640
	s_add_u32 s88, s1, s88
	s_addc_u32 s89, s94, s89
	v_lshl_add_u64 v[4:5], v[12:13], 1, s[88:89]
	v_mov_b32_e32 v158, 0
	s_and_saveexec_b64 s[90:91], s[36:37]
	s_cbranch_execz .LBB0_216
	global_load_ushort v2, v[4:5], off offset:-2
	s_waitcnt vmcnt(0)
	v_lshlrev_b32_e32 v158, 16, v2

.LBB0_346:
	s_or_b64 exec, exec, s[92:93]
	v_cndmask_b32_e64 v2, 0, v114, s[60:61]
	s_waitcnt vmcnt(1)
	v_fmac_f32_e32 v2, v1, v36
	v_add_f32_e32 v36, v2, v37
	v_cndmask_b32_e64 v37, 0, v114, s[58:59]
	v_fmac_f32_e32 v37, v1, v35
	v_add_f32_e32 v37, v37, v34
	v_cndmask_b32_e64 v34, 0, v114, s[56:57]
	v_fmac_f32_e32 v34, v1, v31
	v_add_f32_e32 v31, v34, v33
	v_cndmask_b32_e64 v33, 0, v114, s[54:55]
	v_fmac_f32_e32 v33, v1, v30
	v_cndmask_b32_e64 v30, 0, v114, s[52:53]
	v_fmac_f32_e32 v30, v1, v27
	v_cndmask_b32_e64 v27, 0, v114, s[50:51]
	v_fmac_f32_e32 v27, v1, v26
	v_add_f32_e32 v34, v30, v28
	v_add_f32_e32 v28, v27, v25
	v_cndmask_b32_e64 v25, 0, v114, s[0:1]
	v_fmac_f32_e32 v25, v1, v23
	v_cndmask_b32_e64 v23, 0, v114, s[48:49]
	v_fmac_f32_e32 v23, v1, v22
	v_cndmask_b32_e64 v22, 0, v114, s[46:47]
	v_fmac_f32_e32 v22, v1, v19
	v_cndmask_b32_e64 v19, 0, v114, s[44:45]
	v_fmac_f32_e32 v19, v1, v18
	v_add_f32_e32 v21, v23, v21
	v_add_f32_e32 v23, v19, v17
	v_cndmask_b32_e64 v17, 0, v114, s[42:43]
	v_fmac_f32_e32 v17, v1, v15
	v_cndmask_b32_e64 v15, 0, v114, s[40:41]
	v_fmac_f32_e32 v15, v1, v14
	v_add_f32_e32 v15, v15, v13
	v_cndmask_b32_e64 v13, 0, v114, s[38:39]
	v_fmac_f32_e32 v13, v1, v9
	v_cndmask_b32_e64 v9, 0, v114, s[36:37]
	v_fmac_f32_e32 v9, v1, v7
	v_cndmask_b32_e64 v2, 0, v114, s[62:63]
	v_add_f32_e32 v14, v9, v4
	v_cndmask_b32_e32 v4, 0, v114, vcc
	s_waitcnt vmcnt(0)
	v_fmac_f32_e32 v2, v1, v38
	v_fmac_f32_e32 v4, v1, v3
	v_mov_b32_e32 v1, v122
	v_add_f32_e32 v19, v2, v32
	s_barrier
	v_add_f32_e32 v30, v25, v24
	v_ashrrev_i32_e32 v2, 31, v1
	v_lshrrev_b32_e32 v2, 24, v2
	v_and_b32_e32 v7, 0xff, v1
	v_add_lshl_u32 v1, v1, v2, 4
	v_add_f32_e32 v25, v17, v16
	v_add_f32_e32 v16, v13, v11
	v_and_or_b32 v1, v1, s87, v7
	v_ashrrev_i32_e32 v2, 4, v1
	v_lshlrev_b32_e32 v1, 3, v1
	v_sub_f32_e32 v42, v16, v34
	v_sub_f32_e32 v43, v14, v28
	v_lshl_add_u32 v9, v2, 3, v1
	v_add_f32_e32 v1, 0, v42
	v_mul_f32_e32 v11, 0x3f3504f3, v1
	v_add_f32_e32 v22, v22, v20
	v_cvt_f32_i32_e32 v1, v7
	v_add_f32_e32 v24, v4, v5
	v_add_f32_e32 v29, v33, v29
	v_pk_add_f32 v[26:27], v[24:25], v[30:31]
	v_add_f32_e32 v1, v1, v1
	v_pk_add_f32 v[2:3], v[26:27], v[26:27] op_sel:[0,1] op_sel_hi:[1,0]
	v_pk_add_f32 v[40:41], v[14:15], v[28:29]
	v_pk_add_f32 v[44:45], v[22:23], v[36:37] neg_lo:[0,1] neg_hi:[0,1]
	v_add_f32_e32 v34, v16, v34
	v_add_f32_e32 v35, v22, v36
	v_sub_f32_e32 v36, v15, v29
	v_add_f32_e32 v14, v23, v37
	v_add_f32_e32 v15, v21, v19
	v_mul_f32_e32 v1, 0x39800000, v1
	v_pk_add_f32 v[4:5], v[34:35], v[34:35] op_sel:[0,1] op_sel_hi:[1,0]
	v_sub_f32_e32 v3, v21, v19
	v_pk_add_f32 v[18:19], v[40:41], v[14:15] neg_lo:[0,1] neg_hi:[0,1]
	v_pk_add_f32 v[14:15], v[40:41], v[14:15]
	v_mul_f32_e32 v1, 0.5, v1
	s_xor_b64 s[92:93], s[96:97], -1
	v_sub_f32_e32 v20, 0, v3
	v_add_f32_e32 v40, 0, v3
	s_nop 0
	s_nop 0
	v_sin_f32_e32 v50, v1
	s_and_b64 s[0:1], s[96:97], exec
	v_sub_f32_e32 v33, v25, v31
	v_add_f32_e32 v28, 0, v43
	v_add_f32_e32 v48, v2, v4
	v_add_f32_e32 v49, v14, v15
	v_cos_f32_e32 v56, v1
	s_mov_b32 s70, s21
	v_sub_f32_e32 v39, 0, v33
	v_sub_f32_e32 v38, 0, v45
	v_add_f32_e32 v52, v48, v49
	v_mov_b32_e32 v53, v0
	s_mov_b32 s0, s71
	s_mov_b32 s1, s21
	v_pk_mul_f32 v[28:29], v[28:29], s[70:71] op_sel_hi:[0,1]
	v_add_f32_e32 v16, 0, v36
	v_mul_f32_e32 v17, 0x3f3504f3, v18
	ds_write_b64 v9, v[52:53]
	v_pk_fma_f32 v[52:53], v[38:39], s[0:1], v[28:29]
	v_pk_fma_f32 v[28:29], v[38:39], s[0:1], v[28:29] op_sel_hi:[0,1,1] neg_lo:[0,0,1] neg_hi:[0,0,1]
	v_xor_b32_e32 v57, 0x80000000, v50
	v_mov_b32_e32 v53, v29
	v_pk_mul_f32 v[28:29], v[16:17], s[0:1] op_sel_hi:[0,1]
	v_pk_fma_f32 v[58:59], v[20:21], s[70:71], v[28:29]
	v_pk_fma_f32 v[20:21], v[20:21], s[70:71], v[28:29] op_sel_hi:[0,1,1] neg_lo:[0,0,1] neg_hi:[0,0,1]
	v_mov_b32_e32 v51, v56
	v_mul_f32_e32 v46, 0x3f3504f3, v19
	v_mov_b32_e32 v59, v21
	v_mul_f32_e32 v68, v50, v50
	v_mul_f32_e32 v69, v51, v57
	v_fma_f32 v22, v18, s20, 0
	v_sub_f32_e32 v16, v26, v27
	v_sub_f32_e32 v17, v0, v17
	v_sub_f32_e32 v20, v0, v46
	v_sub_f32_e32 v21, v34, v35
	v_mov_b32_e32 v23, v0
	v_mov_b32_e32 v1, v46
	v_pk_fma_f32 v[70:71], v[56:57], v[56:57], v[68:69] op_sel_hi:[0,1,1] neg_lo:[0,0,1] neg_hi:[0,0,1]
	v_pk_fma_f32 v[68:69], v[56:57], v[56:57], v[68:69] op_sel_hi:[0,1,1]
	v_pk_add_f32 v[26:27], v[22:23], v[20:21]
	v_pk_add_f32 v[34:35], v[22:23], v[20:21] neg_lo:[0,1] neg_hi:[0,1]
	v_pk_add_f32 v[46:47], v[16:17], v[0:1]
	v_pk_add_f32 v[60:61], v[16:17], v[0:1] neg_lo:[0,1] neg_hi:[0,1]
	v_pk_mov_b32 v[78:79], v[68:69], v[70:71] op_sel:[1,0]
	v_mov_b32_e32 v72, v70
	v_mov_b32_e32 v73, v69
	v_pk_mul_f32 v[78:79], v[68:69], v[78:79] op_sel:[1,0]
	v_pk_add_f32 v[14:15], v[14:15], v[14:15] op_sel:[0,1] op_sel_hi:[1,0] neg_lo:[0,1] neg_hi:[0,1]
	v_add_f32_e32 v62, v46, v26
	v_add_f32_e32 v63, v61, v35
	v_pk_fma_f32 v[80:81], v[70:71], v[72:73], v[78:79] op_sel_hi:[0,1,1] neg_lo:[0,0,1] neg_hi:[0,0,1]
	v_pk_fma_f32 v[78:79], v[70:71], v[72:73], v[78:79] op_sel_hi:[0,1,1]
	v_mul_f32_e32 v31, 0x3f6c835e, v40
	v_mul_f32_e32 v25, 0x3ec3ef15, v36
	v_sub_f32_e32 v54, 0, v14
	v_pk_mov_b32 v[88:89], v[78:79], v[80:81] op_sel:[1,0]
	v_pk_mul_f32 v[68:69], v[62:63], v[68:69] op_sel:[1,1] op_sel_hi:[0,1]
	v_mul_f32_e64 v13, -v44, s20
	v_add_f32_e32 v18, 0, v21
	v_sub_f32_e32 v22, v22, v20
	v_pk_add_f32 v[20:21], v[24:25], v[30:31] neg_lo:[0,1] neg_hi:[0,1]
	v_pk_mul_f32 v[54:55], v[54:55], v[88:89] op_sel_hi:[0,1]
	v_pk_fma_f32 v[88:89], v[62:63], v[70:71], v[68:69] neg_lo:[0,0,1] neg_hi:[0,0,1]
	v_pk_fma_f32 v[62:63], v[62:63], v[70:71], v[68:69] op_sel_hi:[1,0,1]
	v_add_f32_e32 v24, 0, v20
	v_mov_b32_e32 v89, v63
	v_add_f32_e32 v62, v13, v11
	v_fma_f32 v63, -v44, s20, -v11
	v_mov_b32_e32 v25, v39
	v_pk_add_f32 v[28:29], v[52:53], v[58:59]
	v_pk_add_f32 v[30:31], v[44:45], 0 op_sel_hi:[1,0]
	v_pk_add_f32 v[44:45], v[52:53], v[58:59] neg_lo:[0,1] neg_hi:[0,1]
	v_pk_add_f32 v[52:53], v[24:25], v[62:63] neg_lo:[0,1] neg_hi:[0,1]
	v_add_f32_e32 v24, v24, v62
	v_add_f32_e32 v25, v63, v39
	v_mov_b32_e32 v57, v50
	v_pk_add_f32 v[38:39], v[24:25], v[28:29]
	v_fmamk_f32 v34, v19, 0x3f3504f3, v17
	v_pk_mul_f32 v[58:59], v[38:39], v[50:51] op_sel_hi:[1,0]
	v_sub_f32_e32 v64, v18, v22
	v_pk_fma_f32 v[62:63], v[38:39], v[56:57], v[58:59] op_sel:[0,0,1] op_sel_hi:[1,1,0]
	v_pk_fma_f32 v[38:39], v[38:39], v[56:57], v[58:59] op_sel:[0,0,1] op_sel_hi:[1,0,0] neg_lo:[0,0,1] neg_hi:[0,0,1]
	v_pk_mul_f32 v[58:59], v[72:73], v[78:79] op_sel:[0,1]
	v_mov_b32_e32 v63, v39
	ds_write_b64 v9, v[62:63] offset:2176
	v_pk_fma_f32 v[62:63], v[72:73], v[80:81], v[58:59] op_sel:[0,0,1] op_sel_hi:[1,0,0] neg_lo:[0,0,1] neg_hi:[0,0,1]
	v_pk_fma_f32 v[58:59], v[72:73], v[80:81], v[58:59] op_sel:[0,0,1] op_sel_hi:[1,0,0]
	v_mov_b32_e32 v82, v80
	v_mov_b32_e32 v83, v79
	v_pk_mov_b32 v[70:71], v[58:59], v[62:63] op_sel:[1,0]
	v_add_f32_e32 v60, v16, v34
	v_pk_mul_f32 v[84:85], v[56:57], v[82:83]
	v_pk_mul_f32 v[86:87], v[50:51], v[82:83]
	v_mov_b32_e32 v68, v62
	v_mov_b32_e32 v69, v59
	v_pk_mul_f32 v[64:65], v[64:65], v[70:71] op_sel_hi:[0,1]
	v_pk_add_f32 v[24:25], v[24:25], v[28:29] neg_lo:[0,1] neg_hi:[0,1]
	v_pk_add_f32 v[28:29], v[52:53], v[44:45] op_sel:[0,1] op_sel_hi:[1,0]
	v_pk_add_f32 v[44:45], v[52:53], v[44:45] op_sel:[0,1] op_sel_hi:[1,0] neg_lo:[0,1] neg_hi:[0,1]
	v_pk_fma_f32 v[70:71], v[60:61], v[62:63], v[64:65] neg_lo:[0,0,1] neg_hi:[0,0,1]
	v_pk_fma_f32 v[64:65], v[60:61], v[68:69], v[64:65] op_sel_hi:[0,1,1]
	v_pk_mov_b32 v[102:103], v[86:87], v[84:85] op_sel:[1,0]
	v_mov_b32_e32 v87, v85
	v_pk_mov_b32 v[38:39], v[44:45], v[28:29] op_sel:[1,0]
	v_mov_b32_e32 v71, v65
	v_pk_mul_f32 v[64:65], v[82:83], v[78:79] op_sel:[0,1]
	v_pk_add_f32 v[84:85], v[102:103], v[86:87]
	v_pk_add_f32 v[86:87], v[102:103], v[86:87] neg_lo:[0,1] neg_hi:[0,1]
	ds_write_b64 v9, v[70:71] offset:13056
	v_pk_fma_f32 v[70:71], v[80:81], v[82:83], v[64:65] op_sel:[0,0,1] op_sel_hi:[0,1,0] neg_lo:[0,0,1] neg_hi:[0,0,1]
	v_pk_fma_f32 v[64:65], v[80:81], v[82:83], v[64:65] op_sel:[0,0,1] op_sel_hi:[0,1,0]
	v_pk_mul_f32 v[38:39], v[38:39], v[86:87] op_sel_hi:[1,0]
	ds_write_b64 v9, v[88:89] offset:4352
	v_mov_b32_e32 v88, v70
	v_mov_b32_e32 v89, v65
	v_pk_mov_b32 v[90:91], v[64:65], v[70:71] op_sel:[1,0]
	v_mov_b32_e32 v102, v86
	v_pk_mov_b32 v[104:105], v[84:85], v[86:87] op_sel:[1,0]
	v_pk_fma_f32 v[86:87], v[28:29], v[84:85], v[38:39] op_sel:[0,1,0] neg_lo:[0,0,1] neg_hi:[0,0,1]
	v_fma_f32 v38, v28, v85, v38
	v_fma_f32 v39, v45, v85, v39
	v_mul_f32_e32 v32, 0x3ec3ef15, v43
	v_mul_f32_e32 v66, 0x3f6c835e, v31
	v_mov_b32_e32 v67, v0
	v_mov_b32_e32 v41, v42
	v_pk_mul_f32 v[76:77], v[50:51], v[72:73]
	v_mov_b32_e32 v103, v85
	v_mov_b32_e32 v87, v39
	v_pk_add_f32 v[48:49], v[48:49], v[48:49] op_sel:[0,1] op_sel_hi:[0,1] neg_lo:[0,1] neg_hi:[0,1]
	v_pk_mul_f32 v[84:85], v[90:91], 0 op_sel_hi:[1,0]
	v_pk_mul_f32 v[50:51], v[50:51], v[88:89] op_sel_hi:[0,1]
	v_pk_add_f32 v[32:33], v[32:33], v[66:67]
	v_pk_mul_f32 v[66:67], v[42:43], s[20:21]
	s_mov_b32 s36, s20
	s_mov_b32 s37, s71
	v_pk_mul_f32 v[40:41], v[40:41], s[72:73]
	v_mov_b32_e32 v37, v30
	v_pk_mul_f32 v[78:79], v[78:79], v[70:71] op_sel_hi:[1,0]
	ds_write_b64 v9, v[86:87] offset:10880
	v_pk_fma_f32 v[86:87], v[48:49], v[70:71], v[84:85] neg_lo:[0,0,1] neg_hi:[0,0,1]
	v_pk_mul_f32 v[58:59], v[70:71], v[58:59] op_sel_hi:[0,1]
	v_pk_fma_f32 v[70:71], v[56:57], v[88:89], v[50:51] op_sel:[0,0,1] op_sel_hi:[0,1,0]
	v_pk_fma_f32 v[50:51], v[56:57], v[88:89], v[50:51] op_sel:[0,0,1] op_sel_hi:[0,1,0] neg_lo:[0,0,1] neg_hi:[0,0,1]
	v_pk_fma_f32 v[42:43], v[30:31], s[36:37], v[66:67] neg_lo:[0,0,1] neg_hi:[0,0,1]
	v_pk_fma_f32 v[30:31], v[36:37], s[30:31], v[40:41] neg_lo:[0,0,1] neg_hi:[0,0,1]
	v_pk_mul_f32 v[74:75], v[56:57], v[72:73]
	v_mov_b32_e32 v57, v51
	v_pk_mov_b32 v[50:51], v[50:51], v[70:71] op_sel:[1,0]
	v_pk_add_f32 v[36:37], v[32:33], v[30:31]
	v_pk_add_f32 v[40:41], v[42:43], v[20:21]
	v_mov_b32_e32 v94, v74
	v_mov_b32_e32 v95, v77
	v_pk_mov_b32 v[74:75], v[74:75], v[76:77] op_sel:[1,0]
	v_mov_b32_e32 v56, v70
	v_pk_mul_f32 v[50:51], v[24:25], v[50:51] op_sel:[1,0]
	v_pk_add_f32 v[66:67], v[36:37], v[40:41]
	v_pk_mul_f32 v[92:93], v[72:73], v[88:89]
	v_pk_mul_f32 v[72:73], v[72:73], v[90:91]
	v_pk_add_f32 v[76:77], v[94:95], v[74:75]
	v_pk_add_f32 v[74:75], v[94:95], v[74:75] neg_lo:[0,1] neg_hi:[0,1]
	v_pk_fma_f32 v[70:71], v[24:25], v[70:71], v[50:51] neg_lo:[0,0,1] neg_hi:[0,0,1]
	v_pk_fma_f32 v[24:25], v[24:25], v[56:57], v[50:51] op_sel_hi:[0,1,1]
	v_pk_mul_f32 v[96:97], v[66:67], v[74:75] op_sel:[0,1]
	v_mov_b32_e32 v71, v25
	v_sub_f32_e32 v24, v46, v26
	v_sub_f32_e32 v25, v35, v61
	v_pk_add_f32 v[26:27], v[72:73], v[72:73] op_sel:[0,1] op_sel_hi:[0,1]
	v_pk_fma_f32 v[98:99], v[66:67], v[76:77], v[96:97] op_sel:[0,0,1] op_sel_hi:[1,1,0] neg_lo:[0,0,1] neg_hi:[0,0,1]
	v_pk_fma_f32 v[66:67], v[66:67], v[76:77], v[96:97] op_sel:[0,0,1] op_sel_hi:[1,0,0]
	v_pk_mul_f32 v[26:27], v[24:25], v[26:27] op_sel:[1,0] op_sel_hi:[0,1]
	v_pk_add_f32 v[46:47], v[92:93], v[92:93] op_sel:[0,1] op_sel_hi:[0,1] neg_lo:[0,1] neg_hi:[0,1]
	v_mov_b32_e32 v99, v67
	v_pk_fma_f32 v[50:51], v[24:25], v[46:47], v[26:27] neg_lo:[0,0,1] neg_hi:[0,0,1]
	v_pk_fma_f32 v[24:25], v[24:25], v[46:47], v[26:27]
	ds_write_b64 v9, v[98:99] offset:6528
	v_mul_f32_e32 v96, v76, v88
	v_mul_f32_e32 v97, v75, v89
	v_mul_f32_e32 v94, v76, v90
	v_mul_f32_e32 v95, v75, v91
	v_pk_mul_f32 v[98:99], v[82:83], v[88:89]
	v_mov_b32_e32 v51, v25
	v_mov_b32_e32 v25, v37
	v_sub_f32_e32 v24, v40, v36
	v_sub_f32_e32 v25, v25, v41
	v_pk_add_f32 v[26:27], v[94:95], v[94:95] op_sel:[0,1] op_sel_hi:[0,1]
	v_mov_b32_e32 v3, v98
	v_mov_b32_e32 v5, v99
	v_pk_mul_f32 v[26:27], v[24:25], v[26:27] op_sel:[1,0] op_sel_hi:[0,1]
	v_pk_add_f32 v[36:37], v[96:97], v[96:97] op_sel:[0,1] op_sel_hi:[0,1] neg_lo:[0,1] neg_hi:[0,1]
	v_pk_add_f32 v[2:3], v[2:3], v[4:5] neg_lo:[0,1] neg_hi:[0,1]
	v_pk_mul_f32 v[100:101], v[80:81], v[64:65] op_sel_hi:[0,1]
	v_pk_fma_f32 v[40:41], v[24:25], v[36:37], v[26:27] neg_lo:[0,0,1] neg_hi:[0,0,1]
	v_pk_fma_f32 v[24:25], v[24:25], v[36:37], v[26:27]
	v_add_f32_e32 v4, 0, v2
	v_mov_b32_e32 v41, v25
	v_pk_fma_f32 v[24:25], v[4:5], v[80:81], v[54:55] neg_lo:[0,0,1] neg_hi:[0,0,1]
	v_pk_fma_f32 v[4:5], v[4:5], v[82:83], v[54:55] op_sel_hi:[0,1,1]
	v_mov_b32_e32 v25, v5
	v_add_f32_e32 v4, v14, v0
	v_add_f32_e32 v5, v101, v79
	ds_write_b64 v9, v[24:25] offset:8704
	v_pk_mov_b32 v[14:15], v[4:5], v[2:3] op_sel:[1,0]
	v_pk_mul_f32 v[52:53], v[88:89], v[102:103]
	v_pk_mul_f32 v[14:15], v[4:5], v[14:15]
	v_pk_mov_b32 v[4:5], v[2:3], v[4:5] op_sel:[1,0]
	v_pk_mul_f32 v[38:39], v[88:89], v[104:105]
	v_pk_fma_f32 v[24:25], v[2:3], v[4:5], v[14:15] neg_lo:[0,0,1] neg_hi:[0,0,1]
	v_pk_fma_f32 v[2:3], v[2:3], v[4:5], v[14:15]
	v_pk_fma_f32 v[48:49], v[48:49], v[88:89], v[84:85]
	v_mov_b32_e32 v25, v3
	ds_write_b64 v9, v[24:25] offset:26112
	v_pk_mov_b32 v[14:15], v[28:29], v[44:45] op_sel:[1,0]
	v_pk_add_f32 v[24:25], v[52:53], v[52:53] op_sel:[1,0] op_sel_hi:[1,0]
	v_mov_b32_e32 v87, v49
	v_pk_mul_f32 v[48:49], v[88:89], v[68:69]
	v_pk_mul_f32 v[62:63], v[64:65], v[62:63] op_sel_hi:[1,0]
	v_pk_add_f32 v[4:5], v[38:39], v[38:39] op_sel:[0,1] op_sel_hi:[0,1] neg_lo:[0,1] neg_hi:[0,1]
	v_pk_mul_f32 v[14:15], v[14:15], v[24:25]
	v_pk_fma_f32 v[24:25], v[44:45], v[4:5], v[14:15] neg_lo:[0,0,1] neg_hi:[0,0,1]
	v_fma_f32 v2, v44, v4, v14
	v_fma_f32 v3, v29, v5, v15
	v_mov_b32_e32 v25, v3
	v_sub_f32_e32 v2, v16, v34
	v_sub_f32_e32 v3, v48, v49
	v_add_f32_e32 v4, v18, v22
	v_add_f32_e32 v5, v63, v59
	v_pk_mul_f32 v[66:67], v[82:83], v[74:75] op_sel:[0,1]
	v_pk_mov_b32 v[14:15], v[4:5], v[2:3] op_sel:[1,0]
	v_pk_fma_f32 v[74:75], v[82:83], v[76:77], v[66:67] op_sel:[0,0,1] op_sel_hi:[1,0,0] neg_lo:[0,0,1] neg_hi:[0,0,1]
	v_pk_mul_f32 v[14:15], v[4:5], v[14:15]
	v_pk_mov_b32 v[4:5], v[2:3], v[4:5] op_sel:[1,0]
	v_pk_fma_f32 v[66:67], v[82:83], v[76:77], v[66:67] op_sel:[0,0,1] op_sel_hi:[1,0,0]
	v_pk_fma_f32 v[16:17], v[2:3], v[4:5], v[14:15] neg_lo:[0,0,1] neg_hi:[0,0,1]
	v_pk_fma_f32 v[2:3], v[2:3], v[4:5], v[14:15]
	v_mov_b32_e32 v17, v3
	v_sub_f32_e32 v2, v20, v42
	v_sub_f32_e32 v3, v33, v31
	v_pk_mov_b32 v[4:5], v[42:43], v[32:33] op_sel:[1,0]
	v_pk_mov_b32 v[14:15], v[20:21], v[30:31] op_sel:[1,0]
	v_mov_b32_e32 v77, v67
	v_pk_add_f32 v[4:5], v[4:5], v[14:15] neg_lo:[0,1] neg_hi:[0,1]
	v_pk_mov_b32 v[66:67], v[66:67], v[74:75] op_sel:[1,0]
	v_pk_add_f32 v[14:15], v[2:3], v[4:5]
	v_pk_add_f32 v[2:3], v[2:3], v[4:5] neg_lo:[0,1] neg_hi:[0,1]
	v_mov_b32_e32 v76, v74
	ds_write_b64 v9, v[16:17] offset:30464
	v_pk_mul_f32 v[16:17], v[2:3], v[66:67] op_sel:[1,0]
	v_pk_mul_f32 v[68:69], v[90:91], v[76:77]
	v_pk_fma_f32 v[18:19], v[14:15], v[74:75], v[16:17] neg_lo:[0,0,1] neg_hi:[0,0,1]
	v_pk_fma_f32 v[16:17], v[14:15], v[76:77], v[16:17] op_sel_hi:[0,1,1]
	v_pk_mul_f32 v[64:65], v[88:89], v[76:77]
	v_mov_b32_e32 v5, v15
	v_mov_b32_e32 v19, v17
	v_pk_mov_b32 v[14:15], v[14:15], v[2:3] op_sel:[1,0]
	v_pk_add_f32 v[16:17], v[68:69], v[68:69] op_sel:[0,1] op_sel_hi:[0,1]
	v_mov_b32_e32 v4, v2
	v_pk_mul_f32 v[14:15], v[14:15], v[16:17]
	v_pk_add_f32 v[16:17], v[64:65], v[64:65] op_sel:[0,1] op_sel_hi:[0,1] neg_lo:[0,1] neg_hi:[0,1]
	v_pk_fma_f32 v[2:3], v[2:3], v[16:17], v[14:15] neg_lo:[0,0,1] neg_hi:[0,0,1]
	v_pk_fma_f32 v[4:5], v[4:5], v[16:17], v[14:15]
	v_mov_b32_e32 v1, v122
	v_mov_b32_e32 v3, v5
	ds_write_b64 v9, v[86:87] offset:17408
	ds_write_b64 v9, v[70:71] offset:19584
	ds_write_b64 v9, v[50:51] offset:21760
	ds_write_b64 v9, v[40:41] offset:23936
	ds_write_b64 v9, v[24:25] offset:28288
	ds_write_b64 v9, v[18:19] offset:15232
	ds_write_b64 v9, v[2:3] offset:32640
	s_waitcnt lgkmcnt(0)
	s_barrier
	s_cselect_b32 s95, s28, s88
	v_ashrrev_i32_e32 v2, 31, v1
	v_lshrrev_b32_e32 v2, 28, v2
	v_and_b32_e32 v7, 15, v1
	v_add_u32_e32 v1, v1, v2
	v_ashrrev_i32_e32 v1, 4, v1
	v_lshlrev_b32_e32 v2, 11, v1
	v_lshl_add_u32 v1, v1, 7, v2
	v_lshl_or_b32 v1, v7, 3, v1
	ds_read2_b64 v[20:23], v1 offset1:17
	ds_read2_b64 v[24:27], v1 offset0:68 offset1:85
	ds_read2_b64 v[28:31], v1 offset0:136 offset1:153
	ds_read2_b64 v[32:35], v1 offset0:170 offset1:187
	ds_read2_b64 v[36:39], v1 offset0:204 offset1:221
	ds_read2_b64 v[40:43], v1 offset0:238 offset1:255
	ds_read2_b64 v[44:47], v1 offset0:34 offset1:51
	ds_read2_b64 v[48:51], v1 offset0:102 offset1:119
	s_waitcnt lgkmcnt(5)
	v_pk_add_f32 v[18:19], v[28:29], v[20:21]
	v_pk_add_f32 v[28:29], v[20:21], v[28:29] neg_lo:[0,1] neg_hi:[0,1]
	s_waitcnt lgkmcnt(2)
	v_pk_mov_b32 v[68:69], v[34:35], v[42:43] op_sel:[1,0]
	s_waitcnt lgkmcnt(1)
	v_pk_add_f32 v[64:65], v[46:47], v[34:35]
	s_waitcnt lgkmcnt(0)
	v_pk_mov_b32 v[16:17], v[46:47], v[50:51] op_sel:[1,0]
	v_sub_f32_e32 v34, v46, v34
	v_sub_f32_e32 v35, v51, v43
	v_pk_add_f32 v[20:21], v[24:25], v[36:37] neg_lo:[0,1] neg_hi:[0,1]
	v_pk_add_f32 v[52:53], v[36:37], v[24:25]
	v_pk_add_f32 v[54:55], v[22:23], v[30:31]
	v_pk_add_f32 v[56:57], v[26:27], v[38:39]
	v_pk_add_f32 v[66:67], v[50:51], v[42:43]
	v_pk_add_f32 v[68:69], v[16:17], v[68:69] neg_lo:[0,1] neg_hi:[0,1]
	v_pk_add_f32 v[46:47], v[34:35], v[34:35] op_sel:[0,1] op_sel_hi:[1,0] neg_lo:[0,1] neg_hi:[0,1]
	v_pk_mov_b32 v[24:25], v[20:21], v[20:21] op_sel:[1,0]
	v_pk_add_f32 v[36:37], v[28:29], v[20:21] op_sel:[0,1] op_sel_hi:[1,0]
	v_pk_add_f32 v[20:21], v[28:29], v[20:21] op_sel:[0,1] op_sel_hi:[1,0] neg_lo:[0,1] neg_hi:[0,1]
	v_pk_add_f32 v[34:35], v[34:35], v[34:35] op_sel:[0,1] op_sel_hi:[0,1]
	v_pk_add_f32 v[4:5], v[54:55], v[56:57]
	v_pk_add_f32 v[42:43], v[64:65], v[66:67] neg_lo:[0,1] neg_hi:[0,1]
	v_pk_add_f32 v[54:55], v[54:55], v[56:57] neg_lo:[0,1] neg_hi:[0,1]
	v_mov_b32_e32 v37, v21
	v_pk_add_f32 v[20:21], v[68:69], v[68:69] op_sel:[0,1] op_sel_hi:[0,1] neg_lo:[0,1] neg_hi:[0,1]
	v_pk_mul_f32 v[34:35], v[34:35], s[0:1]
	v_pk_add_f32 v[58:59], v[44:45], v[32:33]
	v_pk_add_f32 v[60:61], v[48:49], v[40:41]
	v_pk_add_f32 v[16:17], v[64:65], v[66:67]
	v_pk_add_f32 v[50:51], v[68:69], v[68:69] op_sel:[0,1] op_sel_hi:[1,0]
	v_pk_mul_f32 v[56:57], v[54:55], s[20:21] op_sel_hi:[1,0]
	v_mul_f32_e32 v42, 0x3f3504f3, v42
	v_mul_f32_e32 v64, 0x3f3504f3, v43
	v_mul_f32_e32 v67, 0xbf3504f3, v43
	v_pk_fma_f32 v[68:69], v[20:21], s[70:71], v[34:35]
	v_pk_fma_f32 v[20:21], v[20:21], s[70:71], v[34:35] neg_lo:[0,0,1] neg_hi:[0,0,1]
	v_pk_add_f32 v[2:3], v[18:19], v[52:53]
	v_pk_add_f32 v[62:63], v[58:59], v[60:61] neg_lo:[0,1] neg_hi:[0,1]
	v_cvt_f32_i32_e32 v7, v7
	v_mov_b32_e32 v69, v21
	v_mov_b32_e32 v20, v18
	v_sub_f32_e32 v18, v64, v42
	v_sub_f32_e32 v19, v19, v53
	v_sub_f32_e32 v20, v20, v52
	v_sub_f32_e32 v21, v57, v56
	v_mov_b32_e32 v35, v42
	v_pk_add_f32 v[42:43], v[18:19], v[62:63] op_sel:[1,0] op_sel_hi:[0,1]
	v_mov_b32_e32 v53, v62
	v_sub_f32_e32 v34, v59, v61
	v_sub_f32_e32 v35, v67, v35
	v_sub_f32_e32 v62, v44, v32
	v_sub_f32_e32 v63, v22, v30
	v_sub_f32_e32 v64, v49, v41
	v_sub_f32_e32 v65, v27, v39
	v_mul_f32_e32 v9, 0x3f6c835e, v50
	v_mul_f32_e32 v11, 0x3ec3ef15, v46
	v_add_f32_e32 v7, v7, v7
	v_sub_f32_e32 v22, v45, v33
	v_sub_f32_e32 v23, v23, v31
	v_sub_f32_e32 v27, v26, v38
	v_sub_f32_e32 v26, v48, v40
	v_pk_add_f32 v[32:33], v[62:63], v[64:65] neg_lo:[0,1] neg_hi:[0,1]
	v_mul_f32_e32 v7, 0x3b800000, v7
	v_pk_add_f32 v[66:67], v[62:63], v[64:65]
	v_pk_add_f32 v[30:31], v[22:23], v[26:27] neg_lo:[0,1] neg_hi:[0,1]
	v_pk_add_f32 v[22:23], v[22:23], v[26:27]
	v_mov_b32_e32 v51, v32
	v_mov_b32_e32 v39, v29
	v_mov_b32_e32 v27, v25
	v_mul_f32_e32 v7, 0.5, v7
	v_mul_f32_e32 v26, 0x3ec3ef15, v33
	v_pk_mul_f32 v[40:41], v[32:33], s[20:21]
	v_pk_mul_f32 v[32:33], v[50:51], s[72:73]
	v_mov_b32_e32 v47, v22
	v_sub_f32_e32 v24, v28, v24
	v_sub_f32_e32 v25, v11, v9
	v_pk_mul_f32 v[28:29], v[66:67], s[70:71] op_sel:[1,0]
	v_pk_add_f32 v[14:15], v[58:59], v[60:61]
	v_sin_f32_e32 v58, v7
	v_cos_f32_e32 v76, v7
	v_mul_f32_e32 v38, 0x3f6c835e, v23
	v_mul_f32_e32 v7, 0x3f3504f3, v66
	v_mul_f32_e32 v13, 0x3f3504f3, v30
	v_pk_fma_f32 v[40:41], v[22:23], s[36:37], v[40:41] neg_lo:[0,0,1] neg_hi:[0,0,1]
	v_pk_fma_f32 v[22:23], v[46:47], s[30:31], v[32:33] neg_lo:[0,0,1] neg_hi:[0,0,1]
	v_pk_fma_f32 v[32:33], v[30:31], s[0:1], v[28:29] op_sel:[1,0,0]
	v_pk_fma_f32 v[28:29], v[30:31], s[0:1], v[28:29] op_sel:[1,0,0] neg_lo:[0,0,1] neg_hi:[0,0,1]
	v_pk_add_f32 v[26:27], v[38:39], v[26:27]
	v_mov_b32_e32 v33, v29
	v_add_f32_e32 v28, v13, v7
	v_fma_f32 v29, v30, s20, -v7
	v_pk_add_f32 v[30:31], v[36:37], v[28:29]
	v_pk_add_f32 v[38:39], v[32:33], v[68:69]
	v_xor_b32_e32 v77, 0x80000000, v58
	v_pk_add_f32 v[44:45], v[38:39], v[30:31]
	v_pk_fma_f32 v[54:55], v[54:55], s[20:21], v[56:57] op_sel:[0,0,1] op_sel_hi:[1,0,0]
	v_pk_mul_f32 v[50:51], v[58:59], v[44:45] op_sel_hi:[0,1]
	v_pk_fma_f32 v[62:63], v[76:77], v[44:45], v[50:51] op_sel:[0,0,1] op_sel_hi:[1,1,0]
	v_pk_fma_f32 v[44:45], v[76:77], v[44:45], v[50:51] op_sel:[0,0,1] op_sel_hi:[0,1,0] neg_lo:[0,0,1] neg_hi:[0,0,1]
	v_mov_b32_e32 v63, v45
	v_mov_b32_e32 v59, v76
	v_pk_add_f32 v[70:71], v[2:3], v[14:15]
	v_pk_add_f32 v[72:73], v[4:5], v[16:17]
	v_mov_b32_e32 v52, v54
	v_mul_f32_e32 v44, v58, v58
	v_mul_f32_e32 v45, v59, v77
	v_pk_add_f32 v[74:75], v[72:73], v[70:71]
	v_pk_add_f32 v[56:57], v[18:19], v[52:53]
	v_pk_add_f32 v[52:53], v[18:19], v[52:53] neg_lo:[0,1] neg_hi:[0,1]
	v_pk_fma_f32 v[50:51], v[76:77], v[76:77], v[44:45] op_sel_hi:[0,1,1] neg_lo:[0,0,1] neg_hi:[0,0,1]
	v_pk_fma_f32 v[44:45], v[76:77], v[76:77], v[44:45] op_sel_hi:[0,1,1]
	v_mov_b32_e32 v57, v53
	v_pk_add_f32 v[60:61], v[20:21], v[34:35]
	ds_write2_b64 v1, v[74:75], v[62:63] offset1:17
	v_pk_mov_b32 v[74:75], v[44:45], v[50:51] op_sel:[1,0]
	v_pk_add_f32 v[20:21], v[20:21], v[34:35] neg_lo:[0,1] neg_hi:[0,1]
	v_pk_add_f32 v[34:35], v[60:61], v[56:57]
	v_mov_b32_e32 v62, v50
	v_mov_b32_e32 v63, v45
	v_pk_mul_f32 v[74:75], v[44:45], v[74:75] op_sel:[1,0]
	v_pk_mul_f32 v[44:45], v[34:35], v[44:45] op_sel:[1,1] op_sel_hi:[0,1]
	v_pk_fma_f32 v[78:79], v[50:51], v[62:63], v[74:75] op_sel_hi:[0,1,1] neg_lo:[0,0,1] neg_hi:[0,0,1]
	v_pk_fma_f32 v[74:75], v[50:51], v[62:63], v[74:75] op_sel_hi:[0,1,1]
	v_pk_fma_f32 v[88:89], v[34:35], v[50:51], v[44:45] neg_lo:[0,0,1] neg_hi:[0,0,1]
	v_pk_fma_f32 v[34:35], v[34:35], v[50:51], v[44:45] op_sel_hi:[1,0,1]
	v_pk_mul_f32 v[44:45], v[62:63], v[74:75] op_sel:[0,1]
	v_pk_add_f32 v[54:55], v[54:55], v[18:19] neg_lo:[0,1] neg_hi:[0,1]
	v_pk_fma_f32 v[50:51], v[62:63], v[78:79], v[44:45] op_sel:[0,0,1] op_sel_hi:[1,0,0] neg_lo:[0,0,1] neg_hi:[0,0,1]
	v_pk_fma_f32 v[44:45], v[62:63], v[78:79], v[44:45] op_sel:[0,0,1] op_sel_hi:[1,0,0]
	v_pk_add_f32 v[18:19], v[42:43], v[54:55]
	v_pk_add_f32 v[32:33], v[32:33], v[68:69] neg_lo:[0,1] neg_hi:[0,1]
	v_mov_b32_e32 v69, v45
	v_sub_f32_e32 v42, v42, v54
	v_pk_mov_b32 v[44:45], v[44:45], v[50:51] op_sel:[1,0]
	v_mov_b32_e32 v77, v58
	v_mov_b32_e32 v80, v78
	v_mov_b32_e32 v81, v75
	v_pk_add_f32 v[90:91], v[20:21], v[20:21] op_sel:[0,1] op_sel_hi:[0,1]
	v_pk_mul_f32 v[42:43], v[42:43], v[44:45] op_sel_hi:[0,1]
	v_pk_mul_f32 v[64:65], v[76:77], v[62:63]
	v_pk_mul_f32 v[66:67], v[58:59], v[62:63]
	v_mov_b32_e32 v68, v50
	v_pk_fma_f32 v[44:45], v[90:91], v[50:51], v[42:43] neg_lo:[0,0,1] neg_hi:[0,0,1]
	v_pk_mul_f32 v[50:51], v[80:81], v[74:75] op_sel:[0,1]
	v_pk_add_f32 v[30:31], v[30:31], v[38:39] neg_lo:[0,1] neg_hi:[0,1]
	v_pk_add_f32 v[38:39], v[40:41], v[24:25]
	v_pk_add_f32 v[46:47], v[26:27], v[22:23]
	v_pk_fma_f32 v[42:43], v[90:91], v[68:69], v[42:43]
	v_pk_fma_f32 v[54:55], v[78:79], v[80:81], v[50:51] op_sel:[0,0,1] op_sel_hi:[0,1,0] neg_lo:[0,0,1] neg_hi:[0,0,1]
	v_pk_fma_f32 v[50:51], v[78:79], v[80:81], v[50:51] op_sel:[0,0,1] op_sel_hi:[0,1,0]
	v_mov_b32_e32 v92, v64
	v_mov_b32_e32 v93, v67
	v_pk_mov_b32 v[64:65], v[64:65], v[66:67] op_sel:[1,0]
	v_pk_add_f32 v[48:49], v[38:39], v[46:47]
	v_mov_b32_e32 v45, v43
	v_pk_add_f32 v[42:43], v[70:71], v[72:73] neg_lo:[0,1] neg_hi:[0,1]
	v_pk_mov_b32 v[72:73], v[50:51], v[54:55] op_sel:[1,0]
	v_pk_add_f32 v[66:67], v[92:93], v[64:65]
	v_pk_add_f32 v[64:65], v[92:93], v[64:65] neg_lo:[0,1] neg_hi:[0,1]
	v_pk_mul_f32 v[82:83], v[76:77], v[80:81]
	v_pk_mul_f32 v[84:85], v[58:59], v[80:81]
	v_pk_add_f32 v[28:29], v[36:37], v[28:29] neg_lo:[0,1] neg_hi:[0,1]
	v_mov_b32_e32 v70, v54
	v_mov_b32_e32 v71, v51
	v_pk_mul_f32 v[58:59], v[58:59], v[72:73] op_sel_hi:[0,1]
	v_pk_mul_f32 v[94:95], v[48:49], v[64:65] op_sel:[0,1]
	v_pk_mov_b32 v[86:87], v[74:75], v[78:79] op_sel:[1,0]
	v_mov_b32_e32 v89, v35
	v_pk_add_f32 v[34:35], v[28:29], v[32:33] op_sel:[0,1] op_sel_hi:[1,0]
	v_pk_add_f32 v[28:29], v[28:29], v[32:33] op_sel:[0,1] op_sel_hi:[1,0] neg_lo:[0,1] neg_hi:[0,1]
	v_pk_fma_f32 v[74:75], v[76:77], v[70:71], v[58:59] op_sel_hi:[0,1,1]
	v_pk_fma_f32 v[58:59], v[76:77], v[70:71], v[58:59] op_sel_hi:[0,1,1] neg_lo:[0,0,1] neg_hi:[0,0,1]
	v_pk_fma_f32 v[96:97], v[48:49], v[66:67], v[94:95] op_sel:[0,0,1] op_sel_hi:[1,1,0] neg_lo:[0,0,1] neg_hi:[0,0,1]
	v_pk_fma_f32 v[48:49], v[48:49], v[66:67], v[94:95] op_sel:[0,0,1] op_sel_hi:[1,0,0]
	v_mov_b32_e32 v98, v82
	v_mov_b32_e32 v99, v85
	v_pk_mov_b32 v[82:83], v[82:83], v[84:85] op_sel:[1,0]
	v_pk_mov_b32 v[36:37], v[28:29], v[34:35] op_sel:[1,0]
	v_mov_b32_e32 v77, v59
	v_mov_b32_e32 v97, v49
	v_pk_mul_f32 v[48:49], v[80:81], v[64:65] op_sel:[0,1]
	v_pk_add_f32 v[84:85], v[98:99], v[82:83]
	v_pk_add_f32 v[82:83], v[98:99], v[82:83] neg_lo:[0,1] neg_hi:[0,1]
	v_pk_mov_b32 v[58:59], v[58:59], v[74:75] op_sel:[1,0]
	v_mov_b32_e32 v76, v74
	v_mov_b32_e32 v93, v65
	v_pk_fma_f32 v[64:65], v[80:81], v[66:67], v[48:49] op_sel:[0,0,1] op_sel_hi:[1,0,0] neg_lo:[0,0,1] neg_hi:[0,0,1]
	v_pk_fma_f32 v[48:49], v[80:81], v[66:67], v[48:49] op_sel:[0,0,1] op_sel_hi:[1,0,0]
	v_pk_mul_f32 v[36:37], v[36:37], v[82:83] op_sel:[0,1]
	v_pk_mul_f32 v[58:59], v[30:31], v[58:59] op_sel:[1,0]
	v_mov_b32_e32 v92, v66
	v_mov_b32_e32 v66, v64
	v_mov_b32_e32 v67, v49
	v_mov_b32_e32 v98, v84
	v_mov_b32_e32 v99, v83
	v_pk_fma_f32 v[82:83], v[34:35], v[84:85], v[36:37] neg_lo:[0,0,1] neg_hi:[0,0,1]
	v_fma_f32 v32, v34, v84, v36
	v_fma_f32 v33, v29, v84, v37
	v_pk_fma_f32 v[74:75], v[30:31], v[74:75], v[58:59] neg_lo:[0,0,1] neg_hi:[0,0,1]
	v_pk_fma_f32 v[30:31], v[30:31], v[76:77], v[58:59] op_sel_hi:[0,1,1]
	v_pk_mul_f32 v[50:51], v[42:43], v[50:51] op_sel:[1,1] op_sel_hi:[0,1]
	v_pk_mul_f32 v[90:91], v[62:63], v[70:71]
	v_pk_mul_f32 v[62:63], v[62:63], v[72:73]
	ds_write2_b64 v1, v[88:89], v[96:97] offset0:34 offset1:51
	v_pk_mul_f32 v[88:89], v[92:93], v[70:71]
	v_pk_mul_f32 v[92:93], v[92:93], v[72:73]
	v_pk_mul_f32 v[94:95], v[80:81], v[70:71]
	v_pk_mul_f32 v[96:97], v[80:81], v[72:73]
	v_mov_b32_e32 v83, v33
	v_pk_mul_f32 v[32:33], v[70:71], v[98:99]
	v_pk_mul_f32 v[36:37], v[72:73], v[98:99]
	v_mov_b32_e32 v75, v31
	v_pk_mul_f32 v[30:31], v[70:71], v[68:69]
	v_pk_mul_f32 v[58:59], v[72:73], v[68:69]
	v_pk_mul_f32 v[68:69], v[70:71], v[66:67]
	v_pk_mul_f32 v[70:71], v[72:73], v[66:67]
	v_pk_fma_f32 v[72:73], v[42:43], v[54:55], v[50:51] neg_lo:[0,0,1] neg_hi:[0,0,1]
	v_pk_fma_f32 v[42:43], v[42:43], v[54:55], v[50:51] op_sel_hi:[1,0,1]
	v_mov_b32_e32 v73, v43
	v_sub_f32_e32 v42, v60, v56
	v_sub_f32_e32 v43, v53, v61
	v_pk_add_f32 v[50:51], v[62:63], v[62:63] op_sel:[0,1] op_sel_hi:[0,1]
	v_pk_mul_f32 v[50:51], v[42:43], v[50:51] op_sel:[1,0] op_sel_hi:[0,1]
	v_pk_add_f32 v[52:53], v[90:91], v[90:91] op_sel:[0,1] op_sel_hi:[0,1] neg_lo:[0,1] neg_hi:[0,1]
	v_pk_fma_f32 v[54:55], v[42:43], v[52:53], v[50:51] neg_lo:[0,0,1] neg_hi:[0,0,1]
	v_pk_fma_f32 v[42:43], v[42:43], v[52:53], v[50:51]
	v_pk_add_f32 v[2:3], v[2:3], v[14:15] neg_lo:[0,1] neg_hi:[0,1]
	v_mov_b32_e32 v55, v43
	v_mov_b32_e32 v43, v47
	v_sub_f32_e32 v38, v38, v46
	v_sub_f32_e32 v39, v43, v39
	v_pk_add_f32 v[42:43], v[92:93], v[92:93] op_sel:[0,1] op_sel_hi:[0,1]
	v_pk_add_f32 v[4:5], v[4:5], v[16:17] neg_lo:[0,1] neg_hi:[0,1]
	v_pk_mul_f32 v[42:43], v[38:39], v[42:43] op_sel:[1,0] op_sel_hi:[0,1]
	v_pk_add_f32 v[46:47], v[88:89], v[88:89] op_sel:[0,1] op_sel_hi:[0,1] neg_lo:[0,1] neg_hi:[0,1]
	v_pk_add_f32 v[14:15], v[2:3], v[4:5] op_sel:[0,1] op_sel_hi:[1,0]
	v_pk_add_f32 v[2:3], v[2:3], v[4:5] op_sel:[0,1] op_sel_hi:[1,0] neg_lo:[0,1] neg_hi:[0,1]
	v_pk_fma_f32 v[50:51], v[38:39], v[46:47], v[42:43] neg_lo:[0,0,1] neg_hi:[0,0,1]
	v_pk_fma_f32 v[38:39], v[38:39], v[46:47], v[42:43]
	v_pk_mul_f32 v[16:17], v[2:3], v[86:87] op_sel:[1,0]
	v_mov_b32_e32 v51, v39
	v_pk_fma_f32 v[38:39], v[14:15], v[78:79], v[16:17] neg_lo:[0,0,1] neg_hi:[0,0,1]
	v_pk_fma_f32 v[16:17], v[14:15], v[80:81], v[16:17] op_sel_hi:[0,1,1]
	v_mov_b32_e32 v5, v15
	v_mov_b32_e32 v39, v17
	v_pk_mov_b32 v[14:15], v[14:15], v[2:3] op_sel:[1,0]
	v_pk_add_f32 v[16:17], v[96:97], v[96:97] op_sel:[0,1] op_sel_hi:[0,1]
	v_mov_b32_e32 v4, v2
	v_pk_mul_f32 v[14:15], v[14:15], v[16:17]
	v_pk_add_f32 v[16:17], v[94:95], v[94:95] op_sel:[0,1] op_sel_hi:[0,1] neg_lo:[0,1] neg_hi:[0,1]
	v_pk_fma_f32 v[2:3], v[2:3], v[16:17], v[14:15] neg_lo:[0,0,1] neg_hi:[0,0,1]
	v_pk_fma_f32 v[4:5], v[4:5], v[16:17], v[14:15]
	v_pk_mov_b32 v[14:15], v[34:35], v[28:29] op_sel:[1,0]
	v_pk_add_f32 v[16:17], v[36:37], v[36:37] op_sel:[0,1] op_sel_hi:[0,1]
	v_mov_b32_e32 v3, v5
	v_mov_b32_e32 v4, v28
	v_mov_b32_e32 v5, v35
	v_pk_mul_f32 v[14:15], v[14:15], v[16:17]
	v_pk_add_f32 v[16:17], v[32:33], v[32:33] op_sel:[0,1] op_sel_hi:[0,1] neg_lo:[0,1] neg_hi:[0,1]
	v_pk_fma_f32 v[28:29], v[28:29], v[16:17], v[14:15] neg_lo:[0,0,1] neg_hi:[0,0,1]
	v_pk_fma_f32 v[4:5], v[4:5], v[16:17], v[14:15]
	v_pk_add_f32 v[14:15], v[58:59], v[58:59] op_sel:[0,1] op_sel_hi:[0,1]
	v_mov_b32_e32 v29, v5
	ds_write2_b64 v1, v[2:3], v[28:29] offset0:204 offset1:221
	v_mov_b32_e32 v3, v30
	v_sub_f32_e32 v2, v20, v21
	v_sub_f32_e32 v3, v3, v31
	v_mul_f32_e32 v4, v18, v14
	v_mul_f32_e32 v5, v2, v15
	v_pk_mov_b32 v[14:15], v[2:3], v[18:19] op_sel:[1,0]
	v_pk_mov_b32 v[48:49], v[48:49], v[64:65] op_sel:[1,0]
	v_pk_fma_f32 v[16:17], v[2:3], v[14:15], v[4:5] neg_lo:[0,0,1] neg_hi:[0,0,1]
	v_pk_fma_f32 v[2:3], v[2:3], v[14:15], v[4:5]
	v_mov_b32_e32 v17, v3
	v_mov_b32_e32 v3, v26
	v_mov_b32_e32 v5, v22
	v_sub_f32_e32 v2, v24, v40
	v_sub_f32_e32 v3, v3, v5
	v_sub_f32_e32 v4, v41, v25
	v_sub_f32_e32 v5, v27, v23
	ds_write2_b64 v1, v[72:73], v[74:75] offset0:136 offset1:153
	v_pk_add_f32 v[14:15], v[4:5], v[2:3]
	v_pk_add_f32 v[18:19], v[2:3], v[4:5] neg_lo:[0,1] neg_hi:[0,1]
	v_sub_f32_e32 v2, v5, v3
	v_pk_mul_f32 v[2:3], v[2:3], v[48:49] op_sel_hi:[0,1]
	v_pk_fma_f32 v[4:5], v[14:15], v[64:65], v[2:3] neg_lo:[0,0,1] neg_hi:[0,0,1]
	v_pk_fma_f32 v[2:3], v[14:15], v[66:67], v[2:3] op_sel_hi:[0,1,1]
	v_mov_b32_e32 v5, v3
	ds_write2_b64 v1, v[44:45], v[4:5] offset0:102 offset1:119
	v_pk_mov_b32 v[2:3], v[14:15], v[18:19] op_sel:[1,0]
	v_pk_add_f32 v[4:5], v[70:71], v[70:71] op_sel:[0,1] op_sel_hi:[0,1]
	v_mov_b32_e32 v20, v18
	v_mov_b32_e32 v21, v15
	v_pk_mul_f32 v[2:3], v[2:3], v[4:5]
	v_pk_add_f32 v[4:5], v[68:69], v[68:69] op_sel:[0,1] op_sel_hi:[0,1] neg_lo:[0,1] neg_hi:[0,1]
	v_pk_fma_f32 v[14:15], v[18:19], v[4:5], v[2:3] neg_lo:[0,0,1] neg_hi:[0,0,1]
	v_pk_fma_f32 v[2:3], v[20:21], v[4:5], v[2:3]
	ds_write2_b64 v1, v[54:55], v[50:51] offset0:170 offset1:187
	v_mov_b32_e32 v15, v3
	ds_write2_b64 v1, v[38:39], v[82:83] offset0:68 offset1:85
	ds_write2_b64 v1, v[16:17], v[14:15] offset0:238 offset1:255
	v_mov_b32_e32 v1, v122
	s_waitcnt lgkmcnt(0)
	s_barrier
	s_cselect_b32 s94, s89, s24
	v_mul_lo_u32 v1, v1, s33
	ds_read2_b64 v[2:5], v1 offset1:1
	ds_read2_b64 v[14:17], v1 offset0:8 offset1:9
	ds_read2_b64 v[18:21], v1 offset0:10 offset1:11
	ds_read2_b64 v[22:25], v1 offset0:12 offset1:13
	ds_read2_b64 v[26:29], v1 offset0:14 offset1:15
	ds_read2_b64 v[30:33], v1 offset0:2 offset1:3
	ds_read2_b64 v[34:37], v1 offset0:4 offset1:5
	ds_read2_b64 v[38:41], v1 offset0:6 offset1:7
	s_waitcnt lgkmcnt(7)
	v_mov_b32_e32 v1, v4
	v_mov_b32_e32 v42, v2
	v_mov_b32_e32 v43, v4
	v_mov_b32_e32 v4, v5
	v_mov_b32_e32 v5, v3
	s_waitcnt lgkmcnt(6)
	v_mov_b32_e32 v44, v14
	v_mov_b32_e32 v45, v16
	v_mov_b32_e32 v16, v17
	v_mov_b32_e32 v17, v15
	v_pk_add_f32 v[46:47], v[2:3], v[14:15] neg_lo:[0,1] neg_hi:[0,1]
	v_pk_add_f32 v[2:3], v[2:3], v[14:15]
	s_waitcnt lgkmcnt(1)
	v_mov_b32_e32 v7, v36
	v_mov_b32_e32 v15, v36
	v_mov_b32_e32 v36, v37
	v_mov_b32_e32 v37, v35
	v_mov_b32_e32 v48, v22
	v_mov_b32_e32 v49, v24
	v_mov_b32_e32 v24, v25
	v_mov_b32_e32 v25, v23
	v_mov_b32_e32 v14, v34
	v_pk_add_f32 v[50:51], v[34:35], v[22:23] neg_lo:[0,1] neg_hi:[0,1]
	v_pk_add_f32 v[22:23], v[34:35], v[22:23]
	v_pk_mov_b32 v[34:35], v[0:1], v[4:5] op_sel:[1,0]
	v_pk_mov_b32 v[52:53], v[44:45], v[16:17] op_sel:[1,0]
	v_pk_add_f32 v[42:43], v[42:43], v[44:45]
	v_pk_add_f32 v[4:5], v[4:5], v[16:17]
	v_pk_mov_b32 v[16:17], v[6:7], v[36:37] op_sel:[1,0]
	v_pk_mov_b32 v[44:45], v[48:49], v[24:25] op_sel:[1,0]
	v_pk_add_f32 v[14:15], v[14:15], v[48:49]
	v_pk_add_f32 v[24:25], v[36:37], v[24:25]
	v_pk_add_f32 v[48:49], v[2:3], v[22:23] neg_lo:[0,1] neg_hi:[0,1]
	v_pk_add_f32 v[2:3], v[2:3], v[22:23]
	v_pk_add_f32 v[22:23], v[34:35], v[52:53]
	v_pk_add_f32 v[34:35], v[34:35], v[52:53] neg_lo:[0,1] neg_hi:[0,1]
	v_pk_add_f32 v[36:37], v[16:17], v[44:45]
	v_pk_add_f32 v[16:17], v[16:17], v[44:45] neg_lo:[0,1] neg_hi:[0,1]
	v_add_f32_e32 v1, v46, v51
	v_sub_f32_e32 v7, v47, v50
	v_sub_f32_e32 v9, v46, v51
	v_add_f32_e32 v11, v47, v50
	v_pk_add_f32 v[4:5], v[4:5], v[24:25]
	v_add_f32_e32 v13, v34, v17
	v_sub_f32_e32 v50, v35, v16
	v_sub_f32_e32 v51, v34, v17
	v_add_f32_e32 v52, v35, v16
	v_pk_add_f32 v[16:17], v[30:31], v[18:19] neg_lo:[0,1] neg_hi:[0,1]
	v_pk_add_f32 v[24:25], v[30:31], v[18:19]
	v_mov_b32_e32 v44, v30
	v_mov_b32_e32 v46, v18
	v_pk_add_f32 v[14:15], v[42:43], v[14:15]
	v_pk_add_f32 v[42:43], v[22:23], v[36:37]
	v_pk_add_f32 v[22:23], v[22:23], v[36:37] neg_lo:[0,1] neg_hi:[0,1]
	s_waitcnt lgkmcnt(0)
	v_pk_add_f32 v[34:35], v[38:39], v[26:27] neg_lo:[0,1] neg_hi:[0,1]
	v_pk_add_f32 v[36:37], v[38:39], v[26:27]
	v_add_f32_e32 v44, v44, v46
	v_add_f32_e32 v45, v32, v20
	v_add_f32_e32 v18, v33, v21
	v_add_f32_e32 v19, v31, v19
	v_mov_b32_e32 v30, v38
	v_mov_b32_e32 v46, v26
	v_add_f32_e32 v30, v30, v46
	v_add_f32_e32 v31, v40, v28
	v_add_f32_e32 v26, v41, v29
	v_add_f32_e32 v27, v39, v27
	v_pk_add_f32 v[38:39], v[24:25], v[36:37] neg_lo:[0,1] neg_hi:[0,1]
	v_pk_add_f32 v[24:25], v[24:25], v[36:37]
	v_add_f32_e32 v36, v16, v35
	v_sub_f32_e32 v37, v17, v34
	v_sub_f32_e32 v46, v16, v35
	v_add_f32_e32 v47, v17, v34
	v_pk_add_f32 v[16:17], v[32:33], v[20:21]
	v_pk_add_f32 v[20:21], v[32:33], v[20:21] neg_lo:[0,1] neg_hi:[0,1]
	v_pk_add_f32 v[32:33], v[40:41], v[28:29]
	v_pk_add_f32 v[28:29], v[40:41], v[28:29] neg_lo:[0,1] neg_hi:[0,1]
	v_pk_add_f32 v[18:19], v[18:19], v[26:27]
	v_add_f32_e32 v26, v20, v29
	v_mul_f32_e32 v22, 0x3f3504f3, v22
	v_pk_add_f32 v[34:35], v[16:17], v[32:33]
	v_pk_add_f32 v[16:17], v[16:17], v[32:33] neg_lo:[0,1] neg_hi:[0,1]
	v_sub_f32_e32 v27, v21, v28
	v_sub_f32_e32 v20, v20, v29
	v_add_f32_e32 v21, v21, v28
	v_fmamk_f32 v29, v23, 0x3f3504f3, v22
	v_fma_f32 v33, v23, s20, -v22
	v_mul_f32_e32 v22, 0x3f3504f3, v36
	v_mul_f32_e32 v40, 0x3ec3ef15, v26
	v_mul_f32_e32 v26, 0xbf6c835e, v26
	v_pk_add_f32 v[30:31], v[44:45], v[30:31]
	v_mul_f32_e32 v28, 0x3f6c835e, v13
	v_mul_f32_e32 v13, 0x3ec3ef15, v13
	v_fmamk_f32 v32, v37, 0x3f3504f3, v22
	v_fma_f32 v36, v37, s20, -v22
	v_mul_f32_e32 v37, 0xbf3504f3, v46
	v_fmac_f32_e32 v40, 0x3f6c835e, v27
	v_fmac_f32_e32 v26, 0x3ec3ef15, v27
	v_mul_f32_e32 v27, 0xbf3504f3, v16
	v_mul_f32_e32 v16, 0x3ec3ef15, v21
	v_fmac_f32_e32 v28, 0x3ec3ef15, v50
	v_fma_f32 v13, v50, s21, -v13
	v_mul_f32_e32 v41, 0x3ec3ef15, v51
	v_mul_f32_e32 v45, 0xbf6c835e, v51
	v_fmamk_f32 v51, v47, 0x3f3504f3, v37
	v_fmac_f32_e32 v37, 0xbf3504f3, v47
	v_fmamk_f32 v44, v17, 0x3f3504f3, v27
	v_fmac_f32_e32 v27, 0xbf3504f3, v17
	v_fma_f32 v47, v20, s76, -v16
	v_mul_f32_e32 v53, 0xbf6c835e, v21
	v_pk_add_f32 v[16:17], v[2:3], v[24:25]
	v_pk_add_f32 v[2:3], v[2:3], v[24:25] neg_lo:[0,1] neg_hi:[0,1]
	v_pk_add_f32 v[22:23], v[14:15], v[30:31] neg_lo:[0,1] neg_hi:[0,1]
	v_pk_add_f32 v[24:25], v[42:43], v[34:35] neg_lo:[0,1] neg_hi:[0,1]
	v_pk_add_f32 v[4:5], v[4:5], v[18:19] neg_lo:[0,1] neg_hi:[0,1]
	v_fmac_f32_e32 v53, 0x3ec3ef15, v20
	v_pk_add_f32 v[20:21], v[42:43], v[34:35]
	v_pk_add_f32 v[70:71], v[2:3], v[24:25] op_sel:[0,1] op_sel_hi:[1,0]
	v_pk_add_f32 v[2:3], v[2:3], v[24:25] op_sel:[0,1] op_sel_hi:[1,0] neg_lo:[0,1] neg_hi:[0,1]
	v_pk_add_f32 v[72:73], v[22:23], v[4:5] neg_lo:[0,1] neg_hi:[0,1]
	v_pk_add_f32 v[4:5], v[22:23], v[4:5]
	v_add_f32_e32 v23, v1, v32
	v_add_f32_e32 v25, v7, v36
	v_sub_f32_e32 v1, v1, v32
	v_sub_f32_e32 v7, v7, v36
	v_add_f32_e32 v30, v28, v40
	v_add_f32_e32 v31, v13, v26
	v_sub_f32_e32 v35, v28, v40
	v_sub_f32_e32 v13, v13, v26
	v_fmac_f32_e32 v41, 0x3f6c835e, v52
	v_fmac_f32_e32 v45, 0x3ec3ef15, v52
	v_add_f32_e32 v22, v30, v23
	v_add_f32_e32 v24, v31, v25
	v_sub_f32_e32 v26, v23, v30
	v_sub_f32_e32 v28, v25, v31
	v_add_f32_e32 v30, v13, v1
	v_sub_f32_e32 v32, v7, v35
	v_sub_f32_e32 v34, v1, v13
	v_add_f32_e32 v36, v35, v7
	v_add_f32_e32 v1, v48, v39
	v_sub_f32_e32 v7, v49, v38
	v_sub_f32_e32 v13, v48, v39
	v_add_f32_e32 v23, v49, v38
	v_add_f32_e32 v25, v29, v44
	v_add_f32_e32 v31, v33, v27
	v_sub_f32_e32 v29, v29, v44
	v_sub_f32_e32 v27, v33, v27
	v_add_f32_e32 v38, v1, v25
	v_add_f32_e32 v40, v7, v31
	v_sub_f32_e32 v42, v1, v25
	v_sub_f32_e32 v44, v7, v31
	v_add_f32_e32 v46, v13, v27
	v_sub_f32_e32 v48, v23, v29
	v_sub_f32_e32 v50, v13, v27
	v_add_f32_e32 v52, v23, v29
	v_add_f32_e32 v1, v9, v51
	v_add_f32_e32 v7, v11, v37
	v_sub_f32_e32 v9, v9, v51
	v_sub_f32_e32 v11, v11, v37
	v_add_f32_e32 v13, v41, v47
	v_add_f32_e32 v23, v45, v53
	v_sub_f32_e32 v25, v41, v47
	v_sub_f32_e32 v27, v45, v53
	v_pk_add_f32 v[14:15], v[20:21], v[16:17]
	v_pk_add_f32 v[16:17], v[16:17], v[20:21] neg_lo:[0,1] neg_hi:[0,1]
	v_add_f32_e32 v54, v13, v1
	v_add_f32_e32 v56, v23, v7
	v_sub_f32_e32 v58, v1, v13
	v_sub_f32_e32 v60, v7, v23
	v_add_f32_e32 v62, v27, v9
	v_sub_f32_e32 v64, v11, v25
	v_sub_f32_e32 v66, v9, v27
	v_add_f32_e32 v68, v25, v11
	s_mov_b32 s29, 0
	v_mov_b32_e32 v18, v70
	v_mov_b32_e32 v19, v3
	v_mov_b32_e32 v20, v72
	v_mov_b32_e32 v21, v5
	v_pk_mov_b32 v[70:71], v[2:3], v[70:71] op_sel:[1,0]
	v_pk_mov_b32 v[72:73], v[4:5], v[72:73] op_sel:[1,0]
	v_mov_b32_e32 v39, v38
	v_mov_b32_e32 v43, v42
	v_mov_b32_e32 v47, v46
	v_mov_b32_e32 v49, v48
	v_mov_b32_e32 v51, v50
	v_mov_b32_e32 v53, v52
	v_mov_b32_e32 v23, v22
	v_mov_b32_e32 v27, v26
	v_mov_b32_e32 v31, v30
	v_mov_b32_e32 v33, v32
	v_mov_b32_e32 v35, v34
	v_mov_b32_e32 v37, v36
	v_mov_b32_e32 v55, v54
	v_mov_b32_e32 v59, v58
	v_mov_b32_e32 v63, v62
	v_mov_b32_e32 v65, v64
	v_mov_b32_e32 v67, v66
	v_mov_b32_e32 v69, v68
	v_mov_b32_e32 v13, v12
	v_mov_b32_e32 v7, v6
	v_mov_b32_e32 v9, v8
	v_mov_b32_e32 v11, v10
	v_pk_mov_b32 v[74:75], v[14:15], v[14:15] op_sel:[1,0]
	v_mov_b32_e32 v25, v24
	v_mov_b32_e32 v41, v40
	v_mov_b32_e32 v57, v56
	v_pk_mov_b32 v[76:77], v[16:17], v[16:17] op_sel:[1,0]
	v_mov_b32_e32 v29, v28
	v_mov_b32_e32 v45, v44
	v_mov_b32_e32 v61, v60
	s_mov_b64 s[0:1], 0
	s_branch .LBB0_348
.LBB0_347:
	v_mov_b32_e32 v102, v1
	s_barrier
	v_pk_add_f32 v[108:109], v[80:81], v[96:97]
	v_ashrrev_i32_e32 v103, 31, v102
	v_lshrrev_b32_e32 v103, 24, v103
	v_and_b32_e32 v115, 0xff, v102
	v_add_lshl_u32 v102, v102, v103, 4
	v_and_or_b32 v102, v102, s87, v115
	v_ashrrev_i32_e32 v103, 4, v102
	v_cvt_f32_i32_e32 v115, v115
	v_lshlrev_b32_e32 v102, 3, v102
	v_pk_add_f32 v[132:133], v[88:89], v[112:113]
	v_lshl_add_u32 v127, v103, 3, v102
	v_pk_add_f32 v[102:103], v[108:109], v[132:133] neg_lo:[0,1] neg_hi:[0,1]
	v_pk_add_f32 v[116:117], v[2:3], v[90:91]
	v_mul_f32_e32 v138, 0x3f3504f3, v102
	v_add_f32_e32 v102, v115, v115
	v_mul_f32_e32 v102, 0x39800000, v102
	v_pk_add_f32 v[118:119], v[82:83], v[98:99]
	v_pk_add_f32 v[104:105], v[4:5], v[92:93]
	v_pk_add_f32 v[106:107], v[84:85], v[100:101]
	v_pk_add_f32 v[120:121], v[78:79], v[94:95]
	v_pk_add_f32 v[128:129], v[86:87], v[110:111]
	v_mul_f32_e32 v102, 0.5, v102
	v_pk_add_f32 v[134:135], v[104:105], v[106:107] neg_lo:[0,1] neg_hi:[0,1]
	v_sin_f32_e32 v140, v102
	v_mul_f32_e32 v142, 0x3f3504f3, v103
	v_mul_f32_e32 v145, 0xbf3504f3, v103
	v_cos_f32_e32 v146, v102
	v_pk_add_f32 v[102:103], v[116:117], v[118:119]
	v_pk_add_f32 v[104:105], v[104:105], v[106:107]
	v_pk_add_f32 v[106:107], v[120:121], v[128:129]
	v_pk_add_f32 v[108:109], v[108:109], v[132:133]
	v_pk_add_f32 v[132:133], v[102:103], v[106:107]
	v_pk_add_f32 v[148:149], v[104:105], v[108:109]
	v_pk_add_f32 v[90:91], v[2:3], v[90:91] neg_lo:[0,1] neg_hi:[0,1]
	v_pk_add_f32 v[150:151], v[132:133], v[148:149]
	v_pk_add_f32 v[2:3], v[82:83], v[98:99] neg_lo:[0,1] neg_hi:[0,1]
	v_pk_mul_f32 v[136:137], v[134:135], s[20:21] op_sel_hi:[1,0]
	ds_write_b64 v127, v[150:151]
	v_pk_mov_b32 v[98:99], v[2:3], v[2:3] op_sel:[1,0]
	v_pk_add_f32 v[150:151], v[90:91], v[2:3] op_sel:[0,1] op_sel_hi:[1,0]
	v_pk_add_f32 v[2:3], v[90:91], v[2:3] op_sel:[0,1] op_sel_hi:[1,0] neg_lo:[0,1] neg_hi:[0,1]
	v_mov_b32_e32 v151, v3
	v_pk_fma_f32 v[134:135], v[134:135], s[20:21], v[136:137] op_sel:[0,0,1] op_sel_hi:[1,0,0]
	v_sub_f32_e32 v2, v116, v118
	v_sub_f32_e32 v3, v137, v136
	v_sub_f32_e32 v82, v142, v138
	v_sub_f32_e32 v83, v117, v119
	v_mov_b32_e32 v117, v138
	v_mov_b32_e32 v137, v4
	v_mov_b32_e32 v139, v92
	v_sub_f32_e32 v136, v78, v94
	v_sub_f32_e32 v137, v137, v139
	v_mov_b32_e32 v139, v85
	v_sub_f32_e32 v92, v79, v95
	v_sub_f32_e32 v93, v5, v93
	v_mov_b32_e32 v5, v84
	v_mov_b32_e32 v143, v101
	v_sub_f32_e32 v84, v86, v110
	v_sub_f32_e32 v85, v5, v100
	v_pk_mov_b32 v[4:5], v[80:81], v[78:79] op_sel:[1,0]
	v_pk_mov_b32 v[100:101], v[96:97], v[94:95] op_sel:[1,0]
	v_mov_b32_e32 v138, v87
	v_mov_b32_e32 v142, v111
	v_pk_add_f32 v[4:5], v[4:5], v[100:101] neg_lo:[0,1] neg_hi:[0,1]
	v_mov_b32_e32 v101, v87
	v_sub_f32_e32 v78, v80, v96
	v_sub_f32_e32 v79, v79, v95
	v_pk_mov_b32 v[80:81], v[88:89], v[86:87] op_sel:[1,0]
	v_pk_mov_b32 v[86:87], v[112:113], v[110:111] op_sel:[1,0]
	v_pk_add_f32 v[138:139], v[138:139], v[142:143] neg_lo:[0,1] neg_hi:[0,1]
	v_pk_add_f32 v[80:81], v[80:81], v[86:87] neg_lo:[0,1] neg_hi:[0,1]
	v_sub_f32_e32 v100, v88, v112
	v_sub_f32_e32 v101, v101, v111
	v_pk_add_f32 v[86:87], v[78:79], v[80:81] neg_lo:[0,1] neg_hi:[0,1]
	v_pk_add_f32 v[142:143], v[4:5], v[100:101]
	v_pk_add_f32 v[80:81], v[78:79], v[80:81]
	v_mov_b32_e32 v78, v86
	v_mul_f32_e32 v86, 0x3ec3ef15, v86
	v_pk_add_f32 v[88:89], v[136:137], v[138:139] neg_lo:[0,1] neg_hi:[0,1]
	v_pk_add_f32 v[94:95], v[92:93], v[84:85]
	v_pk_add_f32 v[96:97], v[4:5], v[100:101] neg_lo:[0,1] neg_hi:[0,1]
	v_mul_f32_e32 v84, 0x3f6c835e, v142
	v_mov_b32_e32 v101, v91
	v_mov_b32_e32 v91, v86
	v_add_f32_e32 v86, v137, v139
	s_mov_b32 s40, s21
	s_mov_b32 s41, s71
	v_pk_add_f32 v[130:131], v[120:121], v[128:129] neg_lo:[0,1] neg_hi:[0,1]
	v_mul_f32_e32 v100, 0x3ec3ef15, v89
	v_pk_mul_f32 v[88:89], v[88:89], s[20:21]
	s_mov_b32 s70, s20
	v_mov_b32_e32 v111, v99
	v_mov_b32_e32 v99, v84
	v_sub_f32_e32 v84, v93, v85
	s_mov_b32 s38, s71
	s_mov_b32 s39, s21
	v_pk_mul_f32 v[92:93], v[86:87], s[40:41] op_sel_hi:[0,1]
	v_sub_f32_e32 v116, v121, v129
	v_sub_f32_e32 v117, v145, v117
	v_pk_add_f32 v[118:119], v[82:83], v[130:131] op_sel:[1,0] op_sel_hi:[0,1]
	v_mov_b32_e32 v120, v134
	v_mov_b32_e32 v121, v130
	v_pk_add_f32 v[134:135], v[134:135], v[82:83] neg_lo:[0,1] neg_hi:[0,1]
	v_mov_b32_e32 v79, v81
	v_mul_f32_e32 v110, 0x3f6c835e, v95
	v_mul_f32_e32 v115, 0x3f3504f3, v143
	v_mul_f32_e32 v112, s72, v142
	v_mul_f32_e32 v113, s73, v97
	v_pk_fma_f32 v[4:5], v[94:95], s[70:71], v[88:89] neg_lo:[0,0,1] neg_hi:[0,0,1]
	v_pk_fma_f32 v[94:95], v[84:85], s[38:39], v[92:93] op_sel_hi:[0,1,1]
	v_pk_fma_f32 v[84:85], v[84:85], s[38:39], v[92:93] op_sel_hi:[0,1,1] neg_lo:[0,0,1] neg_hi:[0,0,1]
	v_pk_mul_f32 v[80:81], v[80:81], s[38:39] op_sel_hi:[0,1]
	v_pk_add_f32 v[128:129], v[82:83], v[120:121]
	v_pk_add_f32 v[120:121], v[82:83], v[120:121] neg_lo:[0,1] neg_hi:[0,1]
	v_pk_add_f32 v[130:131], v[2:3], v[116:117]
	v_pk_add_f32 v[82:83], v[2:3], v[116:117] neg_lo:[0,1] neg_hi:[0,1]
	v_pk_add_f32 v[2:3], v[118:119], v[134:135]
	v_mul_f32_e32 v119, 0x3f3504f3, v87
	v_mov_b32_e32 v95, v85
	v_fma_f32 v85, v87, s20, -v115
	v_pk_fma_f32 v[86:87], v[96:97], s[40:41], v[80:81]
	v_pk_fma_f32 v[80:81], v[96:97], s[40:41], v[80:81] op_sel_hi:[0,1,1] neg_lo:[0,0,1] neg_hi:[0,0,1]
	v_add_f32_e32 v84, v119, v115
	v_mov_b32_e32 v87, v81
	v_pk_add_f32 v[80:81], v[150:151], v[84:85]
	v_pk_add_f32 v[92:93], v[94:95], v[86:87]
	v_xor_b32_e32 v147, 0x80000000, v140
	v_pk_add_f32 v[96:97], v[80:81], v[92:93]
	v_pk_add_f32 v[88:89], v[100:101], v[110:111]
	v_pk_mul_f32 v[110:111], v[96:97], v[140:141] op_sel_hi:[1,0]
	v_pk_fma_f32 v[78:79], v[78:79], s[30:31], v[112:113] neg_lo:[0,0,1] neg_hi:[0,0,1]
	v_pk_fma_f32 v[112:113], v[96:97], v[146:147], v[110:111] op_sel:[0,0,1] op_sel_hi:[1,1,0]
	v_pk_fma_f32 v[96:97], v[96:97], v[146:147], v[110:111] op_sel:[0,0,1] op_sel_hi:[1,0,0] neg_lo:[0,0,1] neg_hi:[0,0,1]
	v_mov_b32_e32 v141, v146
	v_mov_b32_e32 v113, v97
	v_mul_f32_e32 v96, v140, v140
	v_mul_f32_e32 v97, v141, v147
	v_mov_b32_e32 v129, v121
	v_pk_fma_f32 v[110:111], v[146:147], v[146:147], v[96:97] op_sel_hi:[0,1,1] neg_lo:[0,0,1] neg_hi:[0,0,1]
	v_pk_fma_f32 v[96:97], v[146:147], v[146:147], v[96:97] op_sel_hi:[0,1,1]
	v_pk_mov_b32 v[142:143], v[96:97], v[110:111] op_sel:[1,0]
	v_pk_add_f32 v[116:117], v[130:131], v[128:129]
	ds_write_b64 v127, v[112:113] offset:2176
	v_mov_b32_e32 v112, v110
	v_mov_b32_e32 v113, v97
	v_pk_mul_f32 v[142:143], v[96:97], v[142:143] op_sel:[1,0]
	v_pk_mul_f32 v[96:97], v[116:117], v[96:97] op_sel:[1,1] op_sel_hi:[0,1]
	v_pk_fma_f32 v[144:145], v[110:111], v[112:113], v[142:143] op_sel_hi:[0,1,1] neg_lo:[0,0,1] neg_hi:[0,0,1]
	v_pk_fma_f32 v[142:143], v[110:111], v[112:113], v[142:143] op_sel_hi:[0,1,1]
	v_pk_fma_f32 v[160:161], v[116:117], v[110:111], v[96:97] neg_lo:[0,0,1] neg_hi:[0,0,1]
	v_pk_fma_f32 v[96:97], v[116:117], v[110:111], v[96:97] op_sel_hi:[1,0,1]
	v_pk_mul_f32 v[110:111], v[112:113], v[142:143] op_sel:[0,1]
	v_mov_b32_e32 v161, v97
	v_pk_fma_f32 v[116:117], v[112:113], v[144:145], v[110:111] op_sel:[0,0,1] op_sel_hi:[1,0,0] neg_lo:[0,0,1] neg_hi:[0,0,1]
	v_pk_fma_f32 v[110:111], v[112:113], v[144:145], v[110:111] op_sel:[0,0,1] op_sel_hi:[1,0,0]
	v_pk_add_f32 v[84:85], v[150:151], v[84:85] neg_lo:[0,1] neg_hi:[0,1]
	v_mov_b32_e32 v151, v111
	v_sub_f32_e32 v118, v118, v134
	v_pk_mov_b32 v[110:111], v[110:111], v[116:117] op_sel:[1,0]
	ds_write_b64 v127, v[160:161] offset:4352
	v_mov_b32_e32 v150, v116
	v_pk_add_f32 v[160:161], v[82:83], v[82:83] op_sel:[0,1] op_sel_hi:[0,1]
	v_pk_mul_f32 v[110:111], v[118:119], v[110:111] op_sel_hi:[0,1]
	v_pk_fma_f32 v[116:117], v[160:161], v[116:117], v[110:111] neg_lo:[0,0,1] neg_hi:[0,0,1]
	v_pk_fma_f32 v[110:111], v[160:161], v[150:151], v[110:111]
	v_mov_b32_e32 v152, v144
	v_mov_b32_e32 v153, v143
	v_mov_b32_e32 v117, v111
	ds_write_b64 v127, v[116:117] offset:13056
	v_pk_mul_f32 v[116:117], v[152:153], v[142:143] op_sel:[0,1]
	v_mov_b32_e32 v147, v140
	v_pk_fma_f32 v[118:119], v[144:145], v[152:153], v[116:117] op_sel:[0,0,1] op_sel_hi:[0,1,0] neg_lo:[0,0,1] neg_hi:[0,0,1]
	v_pk_fma_f32 v[116:117], v[144:145], v[152:153], v[116:117] op_sel:[0,0,1] op_sel_hi:[0,1,0]
	v_pk_mov_b32 v[134:135], v[116:117], v[118:119] op_sel:[1,0]
	v_pk_mul_f32 v[138:139], v[140:141], v[112:113]
	v_pk_mul_f32 v[156:157], v[140:141], v[152:153]
	v_pk_add_f32 v[110:111], v[132:133], v[148:149] neg_lo:[0,1] neg_hi:[0,1]
	v_mov_b32_e32 v132, v118
	v_mov_b32_e32 v133, v117
	v_pk_mul_f32 v[140:141], v[140:141], v[134:135] op_sel_hi:[0,1]
	v_pk_mov_b32 v[158:159], v[142:143], v[144:145] op_sel:[1,0]
	v_pk_fma_f32 v[142:143], v[146:147], v[132:133], v[140:141] op_sel_hi:[0,1,1]
	v_pk_fma_f32 v[140:141], v[146:147], v[132:133], v[140:141] op_sel_hi:[0,1,1] neg_lo:[0,0,1] neg_hi:[0,0,1]
	v_pk_add_f32 v[80:81], v[80:81], v[92:93] neg_lo:[0,1] neg_hi:[0,1]
	v_pk_mul_f32 v[136:137], v[146:147], v[112:113]
	v_pk_mul_f32 v[154:155], v[146:147], v[152:153]
	v_mov_b32_e32 v147, v141
	v_pk_mov_b32 v[140:141], v[140:141], v[142:143] op_sel:[1,0]
	v_mov_b32_e32 v146, v142
	v_pk_mul_f32 v[140:141], v[80:81], v[140:141] op_sel:[1,0]
	v_pk_mul_f32 v[116:117], v[110:111], v[116:117] op_sel:[1,1] op_sel_hi:[0,1]
	v_pk_add_f32 v[90:91], v[90:91], v[98:99] neg_lo:[0,1] neg_hi:[0,1]
	v_pk_mul_f32 v[148:149], v[112:113], v[132:133]
	v_pk_mul_f32 v[112:113], v[112:113], v[134:135]
	v_pk_fma_f32 v[142:143], v[80:81], v[142:143], v[140:141] neg_lo:[0,0,1] neg_hi:[0,0,1]
	v_pk_fma_f32 v[80:81], v[80:81], v[146:147], v[140:141] op_sel_hi:[0,1,1]
	v_pk_fma_f32 v[146:147], v[110:111], v[118:119], v[116:117] neg_lo:[0,0,1] neg_hi:[0,0,1]
	v_pk_fma_f32 v[110:111], v[110:111], v[118:119], v[116:117] op_sel_hi:[1,0,1]
	v_pk_add_f32 v[92:93], v[4:5], v[90:91]
	v_pk_add_f32 v[98:99], v[88:89], v[78:79]
	v_mov_b32_e32 v160, v136
	v_mov_b32_e32 v161, v139
	v_pk_mov_b32 v[136:137], v[136:137], v[138:139] op_sel:[1,0]
	v_mov_b32_e32 v147, v111
	v_sub_f32_e32 v110, v130, v128
	v_sub_f32_e32 v111, v121, v131
	v_pk_add_f32 v[112:113], v[112:113], v[112:113] op_sel:[0,1] op_sel_hi:[0,1]
	v_pk_add_f32 v[100:101], v[98:99], v[92:93]
	v_pk_add_f32 v[138:139], v[160:161], v[136:137]
	v_pk_add_f32 v[136:137], v[160:161], v[136:137] neg_lo:[0,1] neg_hi:[0,1]
	v_pk_mul_f32 v[112:113], v[110:111], v[112:113] op_sel:[1,0] op_sel_hi:[0,1]
	v_pk_add_f32 v[116:117], v[148:149], v[148:149] op_sel:[0,1] op_sel_hi:[0,1] neg_lo:[0,1] neg_hi:[0,1]
	v_pk_mul_f32 v[162:163], v[100:101], v[136:137] op_sel:[0,1]
	v_pk_fma_f32 v[118:119], v[110:111], v[116:117], v[112:113] neg_lo:[0,0,1] neg_hi:[0,0,1]
	v_pk_fma_f32 v[110:111], v[110:111], v[116:117], v[112:113]
	v_pk_fma_f32 v[164:165], v[100:101], v[138:139], v[162:163] op_sel:[0,0,1] op_sel_hi:[1,1,0] neg_lo:[0,0,1] neg_hi:[0,0,1]
	v_pk_fma_f32 v[100:101], v[100:101], v[138:139], v[162:163] op_sel:[0,0,1] op_sel_hi:[1,0,0]
	v_mul_f32_e32 v162, v138, v132
	v_mul_f32_e32 v163, v137, v133
	v_mul_f32_e32 v160, v138, v134
	v_mul_f32_e32 v161, v137, v135
	v_mov_b32_e32 v119, v111
	v_mov_b32_e32 v111, v99
	v_sub_f32_e32 v92, v92, v98
	v_sub_f32_e32 v93, v111, v93
	v_pk_add_f32 v[98:99], v[160:161], v[160:161] op_sel:[0,1] op_sel_hi:[0,1]
	v_pk_mul_f32 v[98:99], v[92:93], v[98:99] op_sel:[1,0] op_sel_hi:[0,1]
	v_pk_add_f32 v[110:111], v[162:163], v[162:163] op_sel:[0,1] op_sel_hi:[0,1] neg_lo:[0,1] neg_hi:[0,1]
	v_pk_fma_f32 v[112:113], v[92:93], v[110:111], v[98:99] neg_lo:[0,0,1] neg_hi:[0,0,1]
	v_pk_fma_f32 v[92:93], v[92:93], v[110:111], v[98:99]
	v_pk_add_f32 v[98:99], v[104:105], v[108:109] neg_lo:[0,1] neg_hi:[0,1]
	v_mov_b32_e32 v113, v93
	v_pk_add_f32 v[92:93], v[102:103], v[106:107] neg_lo:[0,1] neg_hi:[0,1]
	v_pk_add_f32 v[86:87], v[94:95], v[86:87] neg_lo:[0,1] neg_hi:[0,1]
	v_pk_add_f32 v[102:103], v[92:93], v[98:99] op_sel:[0,1] op_sel_hi:[1,0]
	v_pk_add_f32 v[92:93], v[92:93], v[98:99] op_sel:[0,1] op_sel_hi:[1,0] neg_lo:[0,1] neg_hi:[0,1]
	v_pk_add_f32 v[94:95], v[84:85], v[86:87] op_sel:[0,1] op_sel_hi:[1,0]
	v_pk_mul_f32 v[104:105], v[92:93], v[158:159] op_sel:[1,0]
	v_pk_add_f32 v[84:85], v[84:85], v[86:87] op_sel:[0,1] op_sel_hi:[1,0] neg_lo:[0,1] neg_hi:[0,1]
	v_mov_b32_e32 v165, v101
	v_pk_mul_f32 v[166:167], v[152:153], v[134:135]
	v_mov_b32_e32 v168, v154
	v_mov_b32_e32 v169, v157
	v_pk_mov_b32 v[154:155], v[154:155], v[156:157] op_sel:[1,0]
	v_pk_fma_f32 v[106:107], v[102:103], v[144:145], v[104:105] neg_lo:[0,0,1] neg_hi:[0,0,1]
	v_pk_fma_f32 v[104:105], v[102:103], v[152:153], v[104:105] op_sel_hi:[0,1,1]
	v_pk_mov_b32 v[96:97], v[84:85], v[94:95] op_sel:[1,0]
	ds_write_b64 v127, v[164:165] offset:6528
	v_pk_mul_f32 v[164:165], v[152:153], v[132:133]
	v_pk_add_f32 v[156:157], v[168:169], v[154:155]
	v_pk_add_f32 v[154:155], v[168:169], v[154:155] neg_lo:[0,1] neg_hi:[0,1]
	v_mov_b32_e32 v99, v103
	v_mov_b32_e32 v107, v105
	v_pk_mov_b32 v[102:103], v[102:103], v[92:93] op_sel:[1,0]
	v_pk_add_f32 v[104:105], v[166:167], v[166:167] op_sel:[0,1] op_sel_hi:[0,1]
	v_pk_mul_f32 v[96:97], v[96:97], v[154:155] op_sel:[0,1]
	v_mov_b32_e32 v98, v92
	v_pk_mul_f32 v[102:103], v[102:103], v[104:105]
	v_pk_add_f32 v[104:105], v[164:165], v[164:165] op_sel:[0,1] op_sel_hi:[0,1] neg_lo:[0,1] neg_hi:[0,1]
	v_mov_b32_e32 v168, v156
	v_mov_b32_e32 v169, v155
	v_pk_fma_f32 v[154:155], v[94:95], v[156:157], v[96:97] neg_lo:[0,0,1] neg_hi:[0,0,1]
	v_fma_f32 v86, v94, v156, v96
	v_fma_f32 v87, v85, v156, v97
	v_pk_fma_f32 v[92:93], v[92:93], v[104:105], v[102:103] neg_lo:[0,0,1] neg_hi:[0,0,1]
	v_pk_fma_f32 v[98:99], v[98:99], v[104:105], v[102:103]
	v_mov_b32_e32 v155, v87
	v_pk_mul_f32 v[96:97], v[134:135], v[168:169]
	v_mov_b32_e32 v93, v99
	ds_write_b64 v127, v[154:155] offset:10880
	v_pk_mul_f32 v[86:87], v[132:133], v[168:169]
	v_mov_b32_e32 v143, v81
	ds_write_b64 v127, v[146:147] offset:17408
	ds_write_b64 v127, v[142:143] offset:19584
	ds_write_b64 v127, v[92:93] offset:26112
	v_mov_b32_e32 v93, v95
	v_pk_mov_b32 v[94:95], v[94:95], v[84:85] op_sel:[1,0]
	v_pk_add_f32 v[96:97], v[96:97], v[96:97] op_sel:[0,1] op_sel_hi:[0,1]
	v_mov_b32_e32 v92, v84
	v_pk_mul_f32 v[94:95], v[94:95], v[96:97]
	v_pk_add_f32 v[86:87], v[86:87], v[86:87] op_sel:[0,1] op_sel_hi:[0,1] neg_lo:[0,1] neg_hi:[0,1]
	v_pk_fma_f32 v[84:85], v[84:85], v[86:87], v[94:95] neg_lo:[0,0,1] neg_hi:[0,0,1]
	v_pk_fma_f32 v[86:87], v[92:93], v[86:87], v[94:95]
	v_pk_mul_f32 v[80:81], v[132:133], v[150:151]
	v_mov_b32_e32 v85, v87
	ds_write_b64 v127, v[84:85] offset:28288
	v_mov_b32_e32 v85, v80
	v_pk_mul_f32 v[140:141], v[134:135], v[150:151]
	v_sub_f32_e32 v80, v82, v83
	v_sub_f32_e32 v81, v85, v81
	v_pk_add_f32 v[84:85], v[140:141], v[140:141] op_sel:[0,1] op_sel_hi:[0,1]
	v_mul_f32_e32 v82, v2, v84
	v_mul_f32_e32 v83, v80, v85
	v_pk_mov_b32 v[2:3], v[80:81], v[2:3] op_sel:[1,0]
	v_pk_mul_f32 v[100:101], v[152:153], v[136:137] op_sel:[0,1]
	v_pk_fma_f32 v[84:85], v[80:81], v[2:3], v[82:83] neg_lo:[0,0,1] neg_hi:[0,0,1]
	v_pk_fma_f32 v[2:3], v[80:81], v[2:3], v[82:83]
	v_pk_mov_b32 v[80:81], v[90:91], v[78:79] op_sel:[1,0]
	v_mov_b32_e32 v85, v3
	v_pk_mov_b32 v[2:3], v[4:5], v[88:89] op_sel:[1,0]
	v_pk_fma_f32 v[136:137], v[152:153], v[138:139], v[100:101] op_sel:[0,0,1] op_sel_hi:[1,0,0] neg_lo:[0,0,1] neg_hi:[0,0,1]
	v_pk_fma_f32 v[100:101], v[152:153], v[138:139], v[100:101] op_sel:[0,0,1] op_sel_hi:[1,0,0]
	v_pk_add_f32 v[2:3], v[2:3], v[80:81] neg_lo:[0,1] neg_hi:[0,1]
	v_sub_f32_e32 v4, v90, v4
	v_sub_f32_e32 v5, v89, v79
	v_mov_b32_e32 v139, v101
	v_pk_mov_b32 v[100:101], v[100:101], v[136:137] op_sel:[1,0]
	v_pk_add_f32 v[78:79], v[4:5], v[2:3]
	v_pk_add_f32 v[2:3], v[4:5], v[2:3] neg_lo:[0,1] neg_hi:[0,1]
	v_mov_b32_e32 v138, v136
	v_pk_mul_f32 v[80:81], v[2:3], v[100:101] op_sel:[1,0]
	v_pk_mul_f32 v[134:135], v[134:135], v[138:139]
	v_pk_fma_f32 v[82:83], v[78:79], v[136:137], v[80:81] neg_lo:[0,0,1] neg_hi:[0,0,1]
	v_pk_fma_f32 v[80:81], v[78:79], v[138:139], v[80:81] op_sel_hi:[0,1,1]
	v_pk_mul_f32 v[132:133], v[132:133], v[138:139]
	v_mov_b32_e32 v5, v79
	v_mov_b32_e32 v83, v81
	v_pk_mov_b32 v[78:79], v[78:79], v[2:3] op_sel:[1,0]
	v_pk_add_f32 v[80:81], v[134:135], v[134:135] op_sel:[0,1] op_sel_hi:[0,1]
	v_mov_b32_e32 v4, v2
	v_pk_mul_f32 v[78:79], v[78:79], v[80:81]
	v_pk_add_f32 v[80:81], v[132:133], v[132:133] op_sel:[0,1] op_sel_hi:[0,1] neg_lo:[0,1] neg_hi:[0,1]
	v_pk_fma_f32 v[2:3], v[2:3], v[80:81], v[78:79] neg_lo:[0,0,1] neg_hi:[0,0,1]
	v_pk_fma_f32 v[4:5], v[4:5], v[80:81], v[78:79]
	ds_write_b64 v127, v[118:119] offset:21760
	v_mov_b32_e32 v3, v5
	ds_write_b64 v127, v[2:3] offset:32640
	v_mov_b32_e32 v2, v1
	ds_write_b64 v127, v[112:113] offset:23936
	ds_write_b64 v127, v[106:107] offset:8704
	ds_write_b64 v127, v[84:85] offset:30464
	ds_write_b64 v127, v[82:83] offset:15232
	s_waitcnt lgkmcnt(0)
	s_barrier
	s_mov_b32 s2, s20
	v_ashrrev_i32_e32 v3, 31, v2
	v_lshrrev_b32_e32 v3, 28, v3
	v_and_b32_e32 v115, 15, v2
	v_add_u32_e32 v2, v2, v3
	v_ashrrev_i32_e32 v2, 4, v2
	v_lshlrev_b32_e32 v3, 11, v2
	v_lshl_add_u32 v2, v2, 7, v3
	v_lshl_or_b32 v127, v115, 3, v2
	ds_read2_b64 v[84:87], v127 offset1:17
	ds_read2_b64 v[88:91], v127 offset0:68 offset1:85
	ds_read2_b64 v[92:95], v127 offset0:136 offset1:153
	ds_read2_b64 v[96:99], v127 offset0:170 offset1:187
	ds_read2_b64 v[100:103], v127 offset0:204 offset1:221
	ds_read2_b64 v[104:107], v127 offset0:238 offset1:255
	ds_read2_b64 v[108:111], v127 offset0:34 offset1:51
	ds_read2_b64 v[116:119], v127 offset0:102 offset1:119
	s_waitcnt lgkmcnt(5)
	v_pk_add_f32 v[82:83], v[92:93], v[84:85]
	s_waitcnt lgkmcnt(2)
	v_pk_mov_b32 v[140:141], v[98:99], v[106:107] op_sel:[1,0]
	s_waitcnt lgkmcnt(1)
	v_pk_add_f32 v[136:137], v[110:111], v[98:99]
	s_waitcnt lgkmcnt(0)
	v_pk_add_f32 v[138:139], v[118:119], v[106:107]
	v_pk_mov_b32 v[80:81], v[110:111], v[118:119] op_sel:[1,0]
	v_mov_b32_e32 v99, v107
	v_pk_add_f32 v[106:107], v[136:137], v[138:139] neg_lo:[0,1] neg_hi:[0,1]
	v_pk_add_f32 v[140:141], v[80:81], v[140:141] neg_lo:[0,1] neg_hi:[0,1]
	v_pk_add_f32 v[80:81], v[136:137], v[138:139]
	v_mul_f32_e32 v136, 0x3f3504f3, v107
	v_mul_f32_e32 v139, 0xbf3504f3, v107
	v_cvt_f32_i32_e32 v107, v115
	v_mov_b32_e32 v111, v119
	v_pk_add_f32 v[98:99], v[110:111], v[98:99] neg_lo:[0,1] neg_hi:[0,1]
	v_pk_add_f32 v[92:93], v[84:85], v[92:93] neg_lo:[0,1] neg_hi:[0,1]
	v_add_f32_e32 v107, v107, v107
	v_pk_add_f32 v[84:85], v[88:89], v[100:101] neg_lo:[0,1] neg_hi:[0,1]
	v_pk_add_f32 v[112:113], v[100:101], v[88:89]
	v_pk_add_f32 v[120:121], v[86:87], v[94:95]
	v_pk_add_f32 v[128:129], v[90:91], v[102:103]
	v_pk_add_f32 v[110:111], v[98:99], v[98:99] op_sel:[0,1] op_sel_hi:[1,0] neg_lo:[0,1] neg_hi:[0,1]
	v_mul_f32_e32 v107, 0x3b800000, v107
	v_pk_mov_b32 v[88:89], v[84:85], v[84:85] op_sel:[1,0]
	v_pk_add_f32 v[100:101], v[92:93], v[84:85] op_sel:[0,1] op_sel_hi:[1,0]
	v_pk_add_f32 v[84:85], v[92:93], v[84:85] op_sel:[0,1] op_sel_hi:[1,0] neg_lo:[0,1] neg_hi:[0,1]
	v_pk_add_f32 v[98:99], v[98:99], v[98:99] op_sel:[0,1] op_sel_hi:[0,1]
	v_pk_add_f32 v[4:5], v[120:121], v[128:129]
	v_pk_add_f32 v[130:131], v[108:109], v[96:97]
	v_pk_add_f32 v[132:133], v[116:117], v[104:105]
	v_pk_add_f32 v[120:121], v[120:121], v[128:129] neg_lo:[0,1] neg_hi:[0,1]
	v_mul_f32_e32 v107, 0.5, v107
	v_mov_b32_e32 v101, v85
	v_pk_add_f32 v[84:85], v[140:141], v[140:141] op_sel:[0,1] op_sel_hi:[0,1] neg_lo:[0,1] neg_hi:[0,1]
	v_pk_mul_f32 v[98:99], v[98:99], s[38:39]
	v_pk_add_f32 v[78:79], v[130:131], v[132:133]
	v_pk_add_f32 v[134:135], v[130:131], v[132:133] neg_lo:[0,1] neg_hi:[0,1]
	v_pk_add_f32 v[118:119], v[140:141], v[140:141] op_sel:[0,1] op_sel_hi:[1,0]
	v_pk_mul_f32 v[128:129], v[120:121], s[20:21] op_sel_hi:[1,0]
	v_mul_f32_e32 v106, 0x3f3504f3, v106
	v_sin_f32_e32 v130, v107
	v_cos_f32_e32 v148, v107
	v_pk_fma_f32 v[140:141], v[84:85], s[40:41], v[98:99]
	v_pk_fma_f32 v[84:85], v[84:85], s[40:41], v[98:99] neg_lo:[0,0,1] neg_hi:[0,0,1]
	s_nop 0
	s_nop 0
	v_pk_add_f32 v[2:3], v[82:83], v[112:113]
	v_mov_b32_e32 v141, v85
	v_mov_b32_e32 v84, v82
	v_sub_f32_e32 v82, v136, v106
	v_sub_f32_e32 v83, v83, v113
	v_sub_f32_e32 v84, v84, v112
	v_sub_f32_e32 v85, v129, v128
	v_mov_b32_e32 v99, v106
	v_pk_add_f32 v[106:107], v[82:83], v[134:135] op_sel:[1,0] op_sel_hi:[0,1]
	v_mov_b32_e32 v113, v134
	v_sub_f32_e32 v98, v131, v133
	v_sub_f32_e32 v99, v139, v99
	v_sub_f32_e32 v134, v108, v96
	v_sub_f32_e32 v135, v86, v94
	v_sub_f32_e32 v136, v117, v105
	v_sub_f32_e32 v137, v91, v103
	v_mul_f32_e32 v115, 0x3f6c835e, v118
	v_mul_f32_e32 v150, 0x3ec3ef15, v110
	v_sub_f32_e32 v86, v109, v97
	v_sub_f32_e32 v87, v87, v95
	v_sub_f32_e32 v91, v90, v102
	v_sub_f32_e32 v90, v116, v104
	v_pk_add_f32 v[96:97], v[134:135], v[136:137] neg_lo:[0,1] neg_hi:[0,1]
	v_pk_fma_f32 v[120:121], v[120:121], s[20:21], v[128:129] op_sel:[0,0,1] op_sel_hi:[1,0,0]
	v_pk_add_f32 v[138:139], v[134:135], v[136:137]
	v_pk_add_f32 v[94:95], v[86:87], v[90:91] neg_lo:[0,1] neg_hi:[0,1]
	v_pk_add_f32 v[86:87], v[86:87], v[90:91]
	v_mov_b32_e32 v119, v96
	v_mov_b32_e32 v103, v93
	v_mov_b32_e32 v91, v89
	v_mov_b32_e32 v112, v120
	v_pk_add_f32 v[120:121], v[120:121], v[82:83] neg_lo:[0,1] neg_hi:[0,1]
	v_mul_f32_e32 v90, 0x3ec3ef15, v97
	v_pk_mul_f32 v[104:105], v[96:97], s[20:21]
	v_pk_mul_f32 v[96:97], v[118:119], s[72:73]
	v_mov_b32_e32 v111, v86
	v_sub_f32_e32 v88, v92, v88
	v_sub_f32_e32 v89, v150, v115
	v_pk_mul_f32 v[92:93], v[138:139], s[40:41] op_sel:[1,0]
	v_pk_add_f32 v[128:129], v[82:83], v[112:113]
	v_pk_add_f32 v[112:113], v[82:83], v[112:113] neg_lo:[0,1] neg_hi:[0,1]
	v_pk_add_f32 v[82:83], v[106:107], v[120:121]
	v_mul_f32_e32 v102, 0x3f6c835e, v87
	v_mul_f32_e32 v107, 0x3f3504f3, v138
	v_mul_f32_e32 v108, 0x3f3504f3, v94
	v_pk_fma_f32 v[104:105], v[86:87], s[70:71], v[104:105] neg_lo:[0,0,1] neg_hi:[0,0,1]
	v_pk_fma_f32 v[86:87], v[110:111], s[30:31], v[96:97] neg_lo:[0,0,1] neg_hi:[0,0,1]
	v_pk_fma_f32 v[96:97], v[94:95], s[38:39], v[92:93] op_sel:[1,0,0]
	v_pk_fma_f32 v[92:93], v[94:95], s[38:39], v[92:93] op_sel:[1,0,0] neg_lo:[0,0,1] neg_hi:[0,0,1]
	v_pk_add_f32 v[90:91], v[102:103], v[90:91]
	v_mov_b32_e32 v97, v93
	v_add_f32_e32 v92, v108, v107
	v_fma_f32 v93, v94, s20, -v107
	v_pk_add_f32 v[94:95], v[100:101], v[92:93]
	v_pk_add_f32 v[102:103], v[96:97], v[140:141]
	v_xor_b32_e32 v149, 0x80000000, v130
	v_pk_add_f32 v[108:109], v[102:103], v[94:95]
	v_pk_add_f32 v[142:143], v[2:3], v[78:79]
	v_pk_mul_f32 v[118:119], v[130:131], v[108:109] op_sel_hi:[0,1]
	v_pk_fma_f32 v[134:135], v[148:149], v[108:109], v[118:119] op_sel:[0,0,1] op_sel_hi:[1,1,0]
	v_pk_fma_f32 v[108:109], v[148:149], v[108:109], v[118:119] op_sel:[0,0,1] op_sel_hi:[0,1,0] neg_lo:[0,0,1] neg_hi:[0,0,1]
	v_mov_b32_e32 v135, v109
	v_mov_b32_e32 v131, v148
	v_pk_add_f32 v[144:145], v[4:5], v[80:81]
	v_mul_f32_e32 v108, v130, v130
	v_mul_f32_e32 v109, v131, v149
	v_pk_add_f32 v[146:147], v[144:145], v[142:143]
	v_pk_fma_f32 v[118:119], v[148:149], v[148:149], v[108:109] op_sel_hi:[0,1,1] neg_lo:[0,0,1] neg_hi:[0,0,1]
	v_pk_fma_f32 v[108:109], v[148:149], v[148:149], v[108:109] op_sel_hi:[0,1,1]
	v_mov_b32_e32 v129, v113
	v_pk_add_f32 v[132:133], v[84:85], v[98:99]
	ds_write2_b64 v127, v[146:147], v[134:135] offset1:17
	v_pk_mov_b32 v[146:147], v[108:109], v[118:119] op_sel:[1,0]
	v_pk_add_f32 v[84:85], v[84:85], v[98:99] neg_lo:[0,1] neg_hi:[0,1]
	v_pk_add_f32 v[98:99], v[132:133], v[128:129]
	v_mov_b32_e32 v134, v118
	v_mov_b32_e32 v135, v109
	v_pk_mul_f32 v[146:147], v[108:109], v[146:147] op_sel:[1,0]
	v_pk_mul_f32 v[108:109], v[98:99], v[108:109] op_sel:[1,1] op_sel_hi:[0,1]
	v_pk_fma_f32 v[150:151], v[118:119], v[134:135], v[146:147] op_sel_hi:[0,1,1] neg_lo:[0,0,1] neg_hi:[0,0,1]
	v_pk_fma_f32 v[146:147], v[118:119], v[134:135], v[146:147] op_sel_hi:[0,1,1]
	v_pk_fma_f32 v[160:161], v[98:99], v[118:119], v[108:109] neg_lo:[0,0,1] neg_hi:[0,0,1]
	v_pk_fma_f32 v[98:99], v[98:99], v[118:119], v[108:109] op_sel_hi:[1,0,1]
	v_pk_mul_f32 v[108:109], v[134:135], v[146:147] op_sel:[0,1]
	v_pk_add_f32 v[96:97], v[96:97], v[140:141] neg_lo:[0,1] neg_hi:[0,1]
	v_pk_fma_f32 v[118:119], v[134:135], v[150:151], v[108:109] op_sel:[0,0,1] op_sel_hi:[1,0,0] neg_lo:[0,0,1] neg_hi:[0,0,1]
	v_pk_fma_f32 v[108:109], v[134:135], v[150:151], v[108:109] op_sel:[0,0,1] op_sel_hi:[1,0,0]
	v_sub_f32_e32 v106, v106, v120
	v_mov_b32_e32 v141, v109
	v_pk_mov_b32 v[108:109], v[108:109], v[118:119] op_sel:[1,0]
	v_mov_b32_e32 v149, v130
	v_mov_b32_e32 v152, v150
	v_mov_b32_e32 v153, v147
	v_pk_add_f32 v[162:163], v[84:85], v[84:85] op_sel:[0,1] op_sel_hi:[0,1]
	v_pk_mul_f32 v[106:107], v[106:107], v[108:109] op_sel_hi:[0,1]
	v_pk_mul_f32 v[136:137], v[148:149], v[134:135]
	v_pk_mul_f32 v[138:139], v[130:131], v[134:135]
	v_mov_b32_e32 v140, v118
	v_pk_fma_f32 v[108:109], v[162:163], v[118:119], v[106:107] neg_lo:[0,0,1] neg_hi:[0,0,1]
	v_pk_mul_f32 v[118:119], v[152:153], v[146:147] op_sel:[0,1]
	v_pk_add_f32 v[94:95], v[94:95], v[102:103] neg_lo:[0,1] neg_hi:[0,1]
	v_pk_add_f32 v[102:103], v[104:105], v[88:89]
	v_pk_add_f32 v[110:111], v[90:91], v[86:87]
	v_pk_fma_f32 v[106:107], v[162:163], v[140:141], v[106:107]
	v_pk_fma_f32 v[120:121], v[150:151], v[152:153], v[118:119] op_sel:[0,0,1] op_sel_hi:[0,1,0] neg_lo:[0,0,1] neg_hi:[0,0,1]
	v_pk_fma_f32 v[118:119], v[150:151], v[152:153], v[118:119] op_sel:[0,0,1] op_sel_hi:[0,1,0]
	v_mov_b32_e32 v164, v136
	v_mov_b32_e32 v165, v139
	v_pk_mov_b32 v[136:137], v[136:137], v[138:139] op_sel:[1,0]
	v_pk_add_f32 v[116:117], v[102:103], v[110:111]
	v_mov_b32_e32 v109, v107
	v_pk_add_f32 v[106:107], v[142:143], v[144:145] neg_lo:[0,1] neg_hi:[0,1]
	v_pk_mov_b32 v[144:145], v[118:119], v[120:121] op_sel:[1,0]
	v_pk_add_f32 v[138:139], v[164:165], v[136:137]
	v_pk_add_f32 v[136:137], v[164:165], v[136:137] neg_lo:[0,1] neg_hi:[0,1]
	v_pk_mul_f32 v[154:155], v[148:149], v[152:153]
	v_pk_mul_f32 v[156:157], v[130:131], v[152:153]
	v_pk_add_f32 v[92:93], v[100:101], v[92:93] neg_lo:[0,1] neg_hi:[0,1]
	v_mov_b32_e32 v142, v120
	v_mov_b32_e32 v143, v119
	v_pk_mul_f32 v[130:131], v[130:131], v[144:145] op_sel_hi:[0,1]
	v_pk_mul_f32 v[166:167], v[116:117], v[136:137] op_sel:[0,1]
	v_pk_mov_b32 v[158:159], v[146:147], v[150:151] op_sel:[1,0]
	v_mov_b32_e32 v161, v99
	v_pk_add_f32 v[98:99], v[92:93], v[96:97] op_sel:[0,1] op_sel_hi:[1,0]
	v_pk_add_f32 v[92:93], v[92:93], v[96:97] op_sel:[0,1] op_sel_hi:[1,0] neg_lo:[0,1] neg_hi:[0,1]
	v_pk_fma_f32 v[146:147], v[148:149], v[142:143], v[130:131] op_sel_hi:[0,1,1]
	v_pk_fma_f32 v[130:131], v[148:149], v[142:143], v[130:131] op_sel_hi:[0,1,1] neg_lo:[0,0,1] neg_hi:[0,0,1]
	v_pk_fma_f32 v[168:169], v[116:117], v[138:139], v[166:167] op_sel:[0,0,1] op_sel_hi:[1,1,0] neg_lo:[0,0,1] neg_hi:[0,0,1]
	v_pk_fma_f32 v[116:117], v[116:117], v[138:139], v[166:167] op_sel:[0,0,1] op_sel_hi:[1,0,0]
	v_mov_b32_e32 v170, v154
	v_mov_b32_e32 v171, v157
	v_pk_mov_b32 v[154:155], v[154:155], v[156:157] op_sel:[1,0]
	v_pk_mov_b32 v[100:101], v[92:93], v[98:99] op_sel:[1,0]
	v_mov_b32_e32 v149, v131
	v_mov_b32_e32 v169, v117
	v_pk_mul_f32 v[116:117], v[152:153], v[136:137] op_sel:[0,1]
	v_pk_add_f32 v[156:157], v[170:171], v[154:155]
	v_pk_add_f32 v[154:155], v[170:171], v[154:155] neg_lo:[0,1] neg_hi:[0,1]
	v_pk_mov_b32 v[130:131], v[130:131], v[146:147] op_sel:[1,0]
	v_mov_b32_e32 v148, v146
	v_mov_b32_e32 v165, v137
	v_pk_fma_f32 v[136:137], v[152:153], v[138:139], v[116:117] op_sel:[0,0,1] op_sel_hi:[1,0,0] neg_lo:[0,0,1] neg_hi:[0,0,1]
	v_pk_fma_f32 v[116:117], v[152:153], v[138:139], v[116:117] op_sel:[0,0,1] op_sel_hi:[1,0,0]
	v_pk_mul_f32 v[100:101], v[100:101], v[154:155] op_sel:[0,1]
	v_pk_mul_f32 v[130:131], v[94:95], v[130:131] op_sel:[1,0]
	v_mov_b32_e32 v164, v138
	v_mov_b32_e32 v138, v136
	v_mov_b32_e32 v139, v117
	v_mov_b32_e32 v170, v156
	v_mov_b32_e32 v171, v155
	v_pk_fma_f32 v[154:155], v[98:99], v[156:157], v[100:101] neg_lo:[0,0,1] neg_hi:[0,0,1]
	v_fma_f32 v96, v98, v156, v100
	v_fma_f32 v97, v93, v156, v101
	v_pk_fma_f32 v[146:147], v[94:95], v[146:147], v[130:131] neg_lo:[0,0,1] neg_hi:[0,0,1]
	v_pk_fma_f32 v[94:95], v[94:95], v[148:149], v[130:131] op_sel_hi:[0,1,1]
	v_pk_mul_f32 v[118:119], v[106:107], v[118:119] op_sel:[1,1] op_sel_hi:[0,1]
	v_pk_mul_f32 v[162:163], v[134:135], v[142:143]
	v_pk_mul_f32 v[134:135], v[134:135], v[144:145]
	ds_write2_b64 v127, v[160:161], v[168:169] offset0:34 offset1:51
	v_pk_mul_f32 v[160:161], v[164:165], v[142:143]
	v_pk_mul_f32 v[164:165], v[164:165], v[144:145]
	v_pk_mul_f32 v[166:167], v[152:153], v[142:143]
	v_pk_mul_f32 v[168:169], v[152:153], v[144:145]
	v_mov_b32_e32 v155, v97
	v_pk_mul_f32 v[96:97], v[142:143], v[170:171]
	v_pk_mul_f32 v[100:101], v[144:145], v[170:171]
	v_mov_b32_e32 v147, v95
	v_pk_mul_f32 v[94:95], v[142:143], v[140:141]
	v_pk_mul_f32 v[130:131], v[144:145], v[140:141]
	v_pk_mul_f32 v[140:141], v[142:143], v[138:139]
	v_pk_mul_f32 v[142:143], v[144:145], v[138:139]
	v_pk_fma_f32 v[144:145], v[106:107], v[120:121], v[118:119] neg_lo:[0,0,1] neg_hi:[0,0,1]
	v_pk_fma_f32 v[106:107], v[106:107], v[120:121], v[118:119] op_sel_hi:[1,0,1]
	v_mov_b32_e32 v145, v107
	v_sub_f32_e32 v106, v132, v128
	v_sub_f32_e32 v107, v113, v133
	v_pk_add_f32 v[112:113], v[134:135], v[134:135] op_sel:[0,1] op_sel_hi:[0,1]
	v_pk_mul_f32 v[112:113], v[106:107], v[112:113] op_sel:[1,0] op_sel_hi:[0,1]
	v_pk_add_f32 v[118:119], v[162:163], v[162:163] op_sel:[0,1] op_sel_hi:[0,1] neg_lo:[0,1] neg_hi:[0,1]
	v_pk_fma_f32 v[120:121], v[106:107], v[118:119], v[112:113] neg_lo:[0,0,1] neg_hi:[0,0,1]
	v_pk_fma_f32 v[106:107], v[106:107], v[118:119], v[112:113]
	v_pk_add_f32 v[2:3], v[2:3], v[78:79] neg_lo:[0,1] neg_hi:[0,1]
	v_mov_b32_e32 v121, v107
	v_mov_b32_e32 v107, v111
	v_sub_f32_e32 v102, v102, v110
	v_sub_f32_e32 v103, v107, v103
	v_pk_add_f32 v[106:107], v[164:165], v[164:165] op_sel:[0,1] op_sel_hi:[0,1]
	v_pk_add_f32 v[4:5], v[4:5], v[80:81] neg_lo:[0,1] neg_hi:[0,1]
	v_pk_mul_f32 v[106:107], v[102:103], v[106:107] op_sel:[1,0] op_sel_hi:[0,1]
	v_pk_add_f32 v[110:111], v[160:161], v[160:161] op_sel:[0,1] op_sel_hi:[0,1] neg_lo:[0,1] neg_hi:[0,1]
	v_pk_add_f32 v[78:79], v[2:3], v[4:5] op_sel:[0,1] op_sel_hi:[1,0]
	v_pk_add_f32 v[2:3], v[2:3], v[4:5] op_sel:[0,1] op_sel_hi:[1,0] neg_lo:[0,1] neg_hi:[0,1]
	v_pk_fma_f32 v[112:113], v[102:103], v[110:111], v[106:107] neg_lo:[0,0,1] neg_hi:[0,0,1]
	v_pk_fma_f32 v[102:103], v[102:103], v[110:111], v[106:107]
	v_pk_mul_f32 v[80:81], v[2:3], v[158:159] op_sel:[1,0]
	v_mov_b32_e32 v113, v103
	v_pk_fma_f32 v[102:103], v[78:79], v[150:151], v[80:81] neg_lo:[0,0,1] neg_hi:[0,0,1]
	v_pk_fma_f32 v[80:81], v[78:79], v[152:153], v[80:81] op_sel_hi:[0,1,1]
	v_mov_b32_e32 v5, v79
	v_mov_b32_e32 v103, v81
	v_pk_mov_b32 v[78:79], v[78:79], v[2:3] op_sel:[1,0]
	v_pk_add_f32 v[80:81], v[168:169], v[168:169] op_sel:[0,1] op_sel_hi:[0,1]
	v_mov_b32_e32 v4, v2
	v_pk_mul_f32 v[78:79], v[78:79], v[80:81]
	v_pk_add_f32 v[80:81], v[166:167], v[166:167] op_sel:[0,1] op_sel_hi:[0,1] neg_lo:[0,1] neg_hi:[0,1]
	v_pk_fma_f32 v[2:3], v[2:3], v[80:81], v[78:79] neg_lo:[0,0,1] neg_hi:[0,0,1]
	v_pk_fma_f32 v[4:5], v[4:5], v[80:81], v[78:79]
	v_pk_mov_b32 v[78:79], v[98:99], v[92:93] op_sel:[1,0]
	v_pk_add_f32 v[80:81], v[100:101], v[100:101] op_sel:[0,1] op_sel_hi:[0,1]
	v_mov_b32_e32 v3, v5
	v_mov_b32_e32 v4, v92
	v_mov_b32_e32 v5, v99
	v_pk_mul_f32 v[78:79], v[78:79], v[80:81]
	v_pk_add_f32 v[80:81], v[96:97], v[96:97] op_sel:[0,1] op_sel_hi:[0,1] neg_lo:[0,1] neg_hi:[0,1]
	v_pk_fma_f32 v[92:93], v[92:93], v[80:81], v[78:79] neg_lo:[0,0,1] neg_hi:[0,0,1]
	v_pk_fma_f32 v[4:5], v[4:5], v[80:81], v[78:79]
	v_pk_add_f32 v[78:79], v[130:131], v[130:131] op_sel:[0,1] op_sel_hi:[0,1]
	v_mov_b32_e32 v93, v5
	ds_write2_b64 v127, v[2:3], v[92:93] offset0:204 offset1:221
	v_mov_b32_e32 v3, v94
	v_sub_f32_e32 v2, v84, v85
	v_sub_f32_e32 v3, v3, v95
	v_mul_f32_e32 v4, v82, v78
	v_mul_f32_e32 v5, v2, v79
	v_pk_mov_b32 v[78:79], v[2:3], v[82:83] op_sel:[1,0]
	v_pk_mov_b32 v[116:117], v[116:117], v[136:137] op_sel:[1,0]
	v_pk_fma_f32 v[80:81], v[2:3], v[78:79], v[4:5] neg_lo:[0,0,1] neg_hi:[0,0,1]
	v_pk_fma_f32 v[2:3], v[2:3], v[78:79], v[4:5]
	v_mov_b32_e32 v81, v3
	v_mov_b32_e32 v3, v90
	v_mov_b32_e32 v5, v86
	v_sub_f32_e32 v2, v88, v104
	v_sub_f32_e32 v3, v3, v5
	v_sub_f32_e32 v4, v105, v89
	v_sub_f32_e32 v5, v91, v87
	ds_write2_b64 v127, v[144:145], v[146:147] offset0:136 offset1:153
	v_pk_add_f32 v[78:79], v[4:5], v[2:3]
	v_pk_add_f32 v[82:83], v[2:3], v[4:5] neg_lo:[0,1] neg_hi:[0,1]
	v_sub_f32_e32 v2, v5, v3
	v_pk_mul_f32 v[2:3], v[2:3], v[116:117] op_sel_hi:[0,1]
	v_pk_fma_f32 v[4:5], v[78:79], v[136:137], v[2:3] neg_lo:[0,0,1] neg_hi:[0,0,1]
	v_pk_fma_f32 v[2:3], v[78:79], v[138:139], v[2:3] op_sel_hi:[0,1,1]
	v_mov_b32_e32 v5, v3
	ds_write2_b64 v127, v[108:109], v[4:5] offset0:102 offset1:119
	v_pk_mov_b32 v[2:3], v[78:79], v[82:83] op_sel:[1,0]
	v_pk_add_f32 v[4:5], v[142:143], v[142:143] op_sel:[0,1] op_sel_hi:[0,1]
	v_mov_b32_e32 v84, v82
	v_mov_b32_e32 v85, v79
	v_pk_mul_f32 v[2:3], v[2:3], v[4:5]
	v_pk_add_f32 v[4:5], v[140:141], v[140:141] op_sel:[0,1] op_sel_hi:[0,1] neg_lo:[0,1] neg_hi:[0,1]
	v_pk_fma_f32 v[78:79], v[82:83], v[4:5], v[2:3] neg_lo:[0,0,1] neg_hi:[0,0,1]
	v_pk_fma_f32 v[2:3], v[84:85], v[4:5], v[2:3]
	ds_write2_b64 v127, v[120:121], v[112:113] offset0:170 offset1:187
	v_mov_b32_e32 v79, v3
	v_mov_b32_e32 v2, v1
	ds_write2_b64 v127, v[102:103], v[154:155] offset0:68 offset1:85
	ds_write2_b64 v127, v[80:81], v[78:79] offset0:238 offset1:255
	s_waitcnt lgkmcnt(0)
	s_barrier
	s_mov_b32 s77, s71
	v_mul_lo_u32 v102, v2, s33
	ds_read2_b64 v[2:5], v102 offset1:1
	ds_read2_b64 v[78:81], v102 offset0:2 offset1:3
	ds_read2_b64 v[82:85], v102 offset0:9 offset1:10
	ds_read2_b64 v[86:89], v102 offset0:4 offset1:5
	ds_read2_b64 v[90:93], v102 offset0:6 offset1:7
	ds_read2_b64 v[94:97], v102 offset0:13 offset1:14
	ds_read2_b64 v[98:101], v102 offset0:8 offset1:15
	ds_read2_b64 v[102:105], v102 offset0:11 offset1:12
	s_waitcnt lgkmcnt(5)
	v_add_f32_e32 v106, v4, v82
	s_waitcnt lgkmcnt(3)
	s_waitcnt lgkmcnt(2)
	v_add_f32_e32 v108, v88, v94
	s_waitcnt lgkmcnt(1)
	v_pk_add_f32 v[132:133], v[2:3], v[98:99]
	v_pk_add_f32 v[2:3], v[2:3], v[98:99] neg_lo:[0,1] neg_hi:[0,1]
	s_waitcnt lgkmcnt(0)
	v_pk_add_f32 v[98:99], v[86:87], v[104:105]
	v_pk_add_f32 v[86:87], v[86:87], v[104:105] neg_lo:[0,1] neg_hi:[0,1]
	v_add_f32_e32 v107, v106, v108
	v_sub_f32_e32 v106, v106, v108
	v_pk_mov_b32 v[128:129], v[78:79], v[78:79] op_sel:[1,0]
	v_pk_add_f32 v[134:135], v[2:3], v[86:87] op_sel:[0,1] op_sel_hi:[1,0]
	v_pk_add_f32 v[136:137], v[2:3], v[86:87] op_sel:[0,1] op_sel_hi:[1,0] neg_lo:[0,1] neg_hi:[0,1]
	v_add_f32_e32 v108, v80, v102
	v_add_f32_e32 v109, v92, v100
	v_pk_mov_b32 v[130:131], v[90:91], v[90:91] op_sel:[1,0]
	v_mov_b32_e32 v135, v137
	v_mov_b32_e32 v141, v82
	v_add_f32_e32 v115, v5, v83
	v_add_f32_e32 v110, v81, v103
	v_add_f32_e32 v111, v93, v101
	v_mov_b32_e32 v112, v81
	v_mov_b32_e32 v116, v103
	v_add_f32_e32 v136, v79, v85
	v_add_f32_e32 v137, v78, v84
	v_mov_b32_e32 v79, v4
	v_mov_b32_e32 v140, v84
	v_sub_f32_e32 v4, v128, v85
	v_sub_f32_e32 v5, v5, v83
	v_mov_b32_e32 v85, v94
	v_add_f32_e32 v119, v89, v95
	v_sub_f32_e32 v80, v80, v102
	v_sub_f32_e32 v81, v93, v101
	v_pk_add_f32 v[78:79], v[78:79], v[140:141] neg_lo:[0,1] neg_hi:[0,1]
	v_add_f32_e32 v82, v91, v97
	v_add_f32_e32 v83, v90, v96
	v_mov_b32_e32 v91, v88
	v_mov_b32_e32 v84, v96
	v_sub_f32_e32 v88, v130, v97
	v_sub_f32_e32 v89, v89, v95
	v_mov_b32_e32 v113, v92
	v_mov_b32_e32 v117, v100
	v_pk_add_f32 v[100:101], v[80:81], v[80:81] op_sel_hi:[0,1] neg_lo:[0,1] neg_hi:[0,1]
	v_pk_add_f32 v[84:85], v[90:91], v[84:85] neg_lo:[0,1] neg_hi:[0,1]
	v_mov_b32_e32 v130, v80
	v_mov_b32_e32 v131, v78
	v_pk_mov_b32 v[80:81], v[80:81], v[88:89] op_sel:[1,0]
	v_pk_add_f32 v[112:113], v[112:113], v[116:117] neg_lo:[0,1] neg_hi:[0,1]
	v_pk_add_f32 v[96:97], v[78:79], v[88:89] neg_lo:[0,1] neg_hi:[0,1]
	v_pk_add_f32 v[128:129], v[4:5], v[84:85]
	v_pk_add_f32 v[80:81], v[130:131], v[80:81]
	v_mov_b32_e32 v131, v4
	v_sub_f32_e32 v4, v5, v85
	v_add_f32_e32 v78, v79, v89
	v_pk_add_f32 v[102:103], v[112:113], v[112:113] op_sel:[0,1] op_sel_hi:[1,0]
	v_mov_b32_e32 v130, v112
	v_pk_mov_b32 v[112:113], v[112:113], v[84:85] op_sel:[1,0]
	v_pk_mul_f32 v[84:85], v[4:5], s[38:39] op_sel_hi:[0,1]
	v_pk_mul_f32 v[78:79], v[78:79], s[40:41] op_sel_hi:[0,1]
	v_pk_add_f32 v[112:113], v[130:131], v[112:113] neg_lo:[0,1] neg_hi:[0,1]
	v_pk_mov_b32 v[130:131], v[86:87], v[78:79] op_sel:[1,0]
	v_sub_f32_e32 v118, v115, v119
	v_pk_add_f32 v[92:93], v[108:109], v[108:109] op_sel:[0,1] op_sel_hi:[1,0]
	v_sub_f32_e32 v108, v108, v109
	v_pk_mov_b32 v[104:105], v[86:87], v[86:87] op_sel:[1,0]
	v_add_f32_e32 v88, v2, v130
	v_add_f32_e32 v89, v84, v131
	v_pk_fma_f32 v[130:131], v[4:5], s[38:39], v[78:79] op_sel_hi:[0,1,1]
	v_pk_fma_f32 v[4:5], v[4:5], s[38:39], v[78:79] op_sel_hi:[0,1,1] neg_lo:[0,0,1] neg_hi:[0,0,1]
	v_mul_f32_e32 v109, 0x3f3504f3, v106
	v_mul_f32_e32 v117, 0x3f3504f3, v118
	v_mul_f32_e32 v120, 0x3f3504f3, v108
	v_mov_b32_e32 v131, v5
	v_mov_b32_e32 v4, v85
	v_mov_b32_e32 v5, v3
	v_pk_mov_b32 v[78:79], v[78:79], v[86:87] op_sel:[1,0]
	v_mul_f32_e32 v104, 0x3ec3ef15, v97
	v_mul_f32_e32 v84, 0x3f6c835e, v129
	v_mov_b32_e32 v85, v3
	v_pk_add_f32 v[4:5], v[4:5], v[78:79] neg_lo:[0,1] neg_hi:[0,1]
	v_sub_f32_e32 v78, v132, v98
	v_sub_f32_e32 v79, v117, v109
	v_pk_add_f32 v[84:85], v[84:85], v[104:105]
	v_pk_mul_f32 v[104:105], v[80:81], s[72:73]
	v_pk_mul_f32 v[108:109], v[80:81], s[74:75]
	v_pk_mul_f32 v[80:81], v[80:81], s[38:39] op_sel_hi:[0,1]
	v_pk_fma_f32 v[150:151], v[112:113], s[40:41], v[80:81]
	v_pk_fma_f32 v[80:81], v[112:113], s[40:41], v[80:81] op_sel_hi:[0,1,1] neg_lo:[0,0,1] neg_hi:[0,0,1]
	v_mov_b32_e32 v151, v81
	v_pk_add_f32 v[80:81], v[110:111], v[110:111] op_sel:[0,1] op_sel_hi:[0,1] neg_lo:[0,1] neg_hi:[0,1]
	v_pk_fma_f32 v[140:141], v[112:113], s[72:73], v[108:109] neg_lo:[0,0,1] neg_hi:[0,0,1]
	v_fmac_f32_e32 v109, 0x3f3504f3, v113
	v_pk_fma_f32 v[104:105], v[112:113], s[74:75], v[104:105]
	v_pk_mul_f32 v[112:113], v[80:81], s[2:3]
	v_mov_b32_e32 v121, v99
	v_mov_b32_e32 v144, v102
	v_sub_f32_e32 v152, v112, v120
	v_sub_f32_e32 v153, v133, v121
	v_mov_b32_e32 v155, v120
	v_pk_fma_f32 v[80:81], v[80:81], s[2:3], v[120:121] op_sel_hi:[1,1,0] neg_lo:[0,0,1] neg_hi:[0,0,1]
	v_pk_mul_f32 v[102:103], v[102:103], s[38:39] op_sel_hi:[0,1]
	v_pk_mul_f32 v[120:121], v[100:101], s[76:77]
	v_pk_mov_b32 v[90:91], v[132:133], v[136:137] op_sel:[1,0]
	v_pk_mov_b32 v[94:95], v[98:99], v[82:83] op_sel:[1,0]
	v_mov_b32_e32 v86, v87
	v_pk_add_f32 v[138:139], v[132:133], v[98:99] neg_lo:[0,1] neg_hi:[0,1]
	v_pk_add_f32 v[90:91], v[90:91], v[94:95]
	v_pk_add_f32 v[94:95], v[136:137], v[82:83] neg_lo:[0,1] neg_hi:[0,1]
	v_mov_b32_e32 v143, v101
	v_pk_mov_b32 v[148:149], v[100:101], v[128:129] op_sel:[1,0]
	v_sub_f32_e32 v2, v2, v86
	v_sub_f32_e32 v3, v121, v103
	v_pk_fma_f32 v[86:87], v[100:101], s[76:77], v[102:103] op_sel:[1,0,0] neg_lo:[0,0,1] neg_hi:[0,0,1]
	v_pk_mov_b32 v[100:101], v[136:137], v[110:111] op_sel:[1,0]
	v_mov_b32_e32 v110, v83
	v_fmamk_f32 v118, v106, 0x3f3504f3, v117
	v_mov_b32_e32 v145, v96
	v_mov_b32_e32 v112, v136
	v_mov_b32_e32 v154, v82
	v_add_f32_e32 v98, v132, v98
	v_add_f32_e32 v99, v115, v119
	v_pk_add_f32 v[82:83], v[100:101], v[110:111]
	v_pk_add_f32 v[110:111], v[138:139], v[94:95] neg_lo:[0,1] neg_hi:[0,1]
	v_pk_add_f32 v[120:121], v[138:139], v[94:95]
	v_mov_b32_e32 v119, v95
	v_pk_mul_f32 v[116:117], v[96:97], s[20:21]
	v_pk_mul_f32 v[96:97], v[144:145], s[74:75]
	v_pk_mul_f32 v[144:145], v[144:145], s[72:73]
	v_pk_add_f32 v[112:113], v[112:113], v[154:155] neg_lo:[0,1] neg_hi:[0,1]
	v_mov_b32_e32 v111, v121
	v_pk_add_f32 v[94:95], v[152:153], v[118:119]
	v_pk_add_f32 v[120:121], v[152:153], v[118:119] neg_lo:[0,1] neg_hi:[0,1]
	v_mov_b32_e32 v142, v128
	v_pk_fma_f32 v[146:147], v[128:129], s[70:71], v[116:117] neg_lo:[0,0,1] neg_hi:[0,0,1]
	v_pk_fma_f32 v[128:129], v[128:129], s[2:3], v[116:117] op_sel_hi:[0,1,0] neg_lo:[0,0,1] neg_hi:[0,0,1]
	v_mov_b32_e32 v117, v144
	v_add_f32_e32 v100, v90, v91
	v_add_f32_e32 v101, v99, v83
	v_mov_b32_e32 v106, v98
	v_mov_b32_e32 v102, v82
	v_pk_add_f32 v[82:83], v[98:99], v[82:83] neg_lo:[0,1] neg_hi:[0,1]
	v_pk_add_f32 v[98:99], v[130:131], v[150:151]
	v_mov_b32_e32 v95, v121
	v_pk_add_f32 v[130:131], v[78:79], v[112:113]
	s_mov_b32 s42, s71
	s_mov_b32 s43, s3
	v_pk_fma_f32 v[116:117], v[142:143], s[78:79], v[116:117] neg_lo:[0,0,1] neg_hi:[0,0,1]
	v_pk_fma_f32 v[142:143], v[148:149], s[30:31], v[144:145] neg_lo:[0,0,1] neg_hi:[0,0,1]
	v_mov_b32_e32 v103, v92
	v_add_f32_e32 v80, v118, v80
	v_add_f32_e32 v81, v79, v81
	v_pk_add_f32 v[94:95], v[130:131], v[94:95]
	v_mov_b32_e32 v131, v121
	v_mov_b32_e32 v108, v109
	v_mov_b32_e32 v109, v141
	v_pk_fma_f32 v[96:97], v[148:149], s[42:43], v[96:97] neg_lo:[0,0,1] neg_hi:[0,0,1]
	v_pk_add_f32 v[102:103], v[106:107], v[102:103]
	v_pk_add_f32 v[80:81], v[130:131], v[80:81] neg_lo:[0,1] neg_hi:[0,1]
	v_add_f32_e32 v120, v2, v128
	v_add_f32_e32 v121, v85, v129
	v_pk_add_f32 v[128:129], v[84:85], v[142:143]
	v_pk_add_f32 v[130:131], v[146:147], v[2:3]
	v_mov_b32_e32 v146, v84
	v_mov_b32_e32 v3, v84
	v_mov_b32_e32 v84, v147
	v_pk_add_f32 v[132:133], v[100:101], v[100:101] op_sel:[1,0] op_sel_hi:[1,0]
	v_mov_b32_e32 v106, v90
	v_pk_mov_b32 v[90:91], v[90:91], v[92:93] op_sel:[1,0]
	v_pk_add_f32 v[92:93], v[134:135], v[108:109]
	v_pk_add_f32 v[84:85], v[84:85], v[96:97] neg_lo:[0,1] neg_hi:[0,1]
	v_pk_add_f32 v[96:97], v[130:131], v[128:129]
	v_pk_add_f32 v[130:131], v[102:103], v[102:103] op_sel:[1,0] op_sel_hi:[1,0]
	v_pk_mul_f32 v[132:133], v[74:75], v[132:133]
	v_pk_add_f32 v[88:89], v[88:89], v[104:105] op_sel:[0,1] op_sel_hi:[1,0] neg_lo:[0,1] neg_hi:[0,1]
	v_pk_add_f32 v[104:105], v[98:99], v[92:93]
	v_pk_fma_f32 v[134:135], v[14:15], v[130:131], v[132:133] neg_lo:[0,0,1] neg_hi:[0,0,1]
	v_pk_fma_f32 v[130:131], v[14:15], v[130:131], v[132:133]
	v_pk_add_f32 v[90:91], v[106:107], v[90:91] neg_lo:[0,1] neg_hi:[0,1]
	v_mov_b32_e32 v135, v131
	v_pk_mul_f32 v[130:131], v[24:25], v[104:105] op_sel:[0,1] op_sel_hi:[1,0]
	v_pk_add_f32 v[4:5], v[4:5], v[140:141] neg_lo:[0,1] neg_hi:[0,1]
	v_pk_fma_f32 v[132:133], v[22:23], v[104:105], v[130:131] neg_lo:[0,0,1] neg_hi:[0,0,1]
	v_pk_fma_f32 v[104:105], v[22:23], v[104:105], v[130:131]
	v_pk_mul_f32 v[130:131], v[40:41], v[94:95] op_sel:[0,1] op_sel_hi:[1,0]
	v_pk_add_f32 v[92:93], v[92:93], v[98:99] neg_lo:[0,1] neg_hi:[0,1]
	v_pk_add_f32 v[98:99], v[4:5], v[88:89]
	v_pk_add_f32 v[106:107], v[4:5], v[88:89] neg_lo:[0,1] neg_hi:[0,1]
	v_pk_mov_b32 v[78:79], v[78:79], v[118:119] op_sel:[1,0]
	v_pk_mov_b32 v[112:113], v[112:113], v[152:153] op_sel:[1,0]
	v_pk_fma_f32 v[136:137], v[38:39], v[94:95], v[130:131] neg_lo:[0,0,1] neg_hi:[0,0,1]
	v_pk_fma_f32 v[94:95], v[38:39], v[94:95], v[130:131]
	v_pk_mul_f32 v[130:131], v[56:57], v[96:97] op_sel:[0,1] op_sel_hi:[1,0]
	v_pk_add_f32 v[140:141], v[90:91], v[90:91] op_sel:[0,1] op_sel_hi:[0,1] neg_lo:[0,1] neg_hi:[0,1]
	v_mov_b32_e32 v109, v107
	v_pk_add_f32 v[78:79], v[78:79], v[112:113] neg_lo:[0,1] neg_hi:[0,1]
	v_pk_fma_f32 v[138:139], v[54:55], v[96:97], v[130:131] neg_lo:[0,0,1] neg_hi:[0,0,1]
	v_pk_fma_f32 v[96:97], v[54:55], v[96:97], v[130:131]
	v_pk_add_f32 v[130:131], v[82:83], v[82:83] op_sel:[0,1] op_sel_hi:[0,1]
	v_pk_mul_f32 v[140:141], v[70:71], v[140:141]
	v_pk_mov_b32 v[106:107], v[106:107], v[98:99] op_sel:[1,0]
	v_mov_b32_e32 v108, v98
	v_pk_add_f32 v[112:113], v[110:111], v[78:79]
	v_pk_add_f32 v[78:79], v[110:111], v[78:79] neg_lo:[0,1] neg_hi:[0,1]
	v_pk_fma_f32 v[142:143], v[18:19], v[130:131], v[140:141] neg_lo:[0,0,1] neg_hi:[0,0,1]
	v_pk_fma_f32 v[130:131], v[18:19], v[130:131], v[140:141]
	v_pk_mul_f32 v[106:107], v[32:33], v[106:107]
	v_pk_add_f32 v[86:87], v[146:147], v[86:87]
	v_pk_add_f32 v[2:3], v[2:3], v[116:117] neg_lo:[0,1] neg_hi:[0,1]
	v_mov_b32_e32 v143, v131
	v_pk_fma_f32 v[130:131], v[30:31], v[108:109], v[106:107] neg_lo:[0,0,1] neg_hi:[0,0,1]
	v_pk_fma_f32 v[106:107], v[30:31], v[108:109], v[106:107]
	v_pk_mov_b32 v[108:109], v[78:79], v[112:113] op_sel:[1,0]
	v_pk_add_f32 v[86:87], v[120:121], v[86:87] neg_lo:[0,1] neg_hi:[0,1]
	v_pk_add_f32 v[116:117], v[84:85], v[2:3]
	v_pk_add_f32 v[120:121], v[84:85], v[2:3] neg_lo:[0,1] neg_hi:[0,1]
	v_pk_mul_f32 v[108:109], v[48:49], v[108:109]
	v_pk_add_f32 v[100:101], v[100:101], v[100:101] op_sel:[0,1] op_sel_hi:[0,1] neg_lo:[0,1] neg_hi:[0,1]
	v_fma_f32 v140, v46, v112, -v108
	v_fma_f32 v141, v47, v79, -v109
	v_fma_f32 v108, v46, v112, v108
	v_fma_f32 v109, v47, v79, v109
	v_pk_mov_b32 v[110:111], v[120:121], v[116:117] op_sel:[1,0]
	v_mov_b32_e32 v128, v116
	v_mov_b32_e32 v129, v121
	v_pk_mul_f32 v[110:111], v[64:65], v[110:111]
	v_pk_add_f32 v[102:103], v[102:103], v[102:103] op_sel:[0,1] op_sel_hi:[0,1] neg_lo:[0,1] neg_hi:[0,1]
	v_pk_mul_f32 v[100:101], v[76:77], v[100:101]
	v_pk_fma_f32 v[120:121], v[62:63], v[128:129], v[110:111] neg_lo:[0,0,1] neg_hi:[0,0,1]
	v_pk_fma_f32 v[110:111], v[62:63], v[128:129], v[110:111]
	v_pk_fma_f32 v[128:129], v[16:17], v[102:103], v[100:101] neg_lo:[0,0,1] neg_hi:[0,0,1]
	v_pk_fma_f32 v[100:101], v[16:17], v[102:103], v[100:101]
	v_pk_add_f32 v[4:5], v[88:89], v[4:5] neg_lo:[0,1] neg_hi:[0,1]
	v_mov_b32_e32 v129, v101
	v_pk_mul_f32 v[100:101], v[28:29], v[92:93] op_sel:[0,1] op_sel_hi:[1,0]
	v_pk_add_f32 v[90:91], v[90:91], v[90:91] op_sel:[1,0] op_sel_hi:[1,0]
	v_pk_fma_f32 v[102:103], v[26:27], v[92:93], v[100:101] neg_lo:[0,0,1] neg_hi:[0,0,1]
	v_pk_fma_f32 v[92:93], v[26:27], v[92:93], v[100:101]
	v_pk_mul_f32 v[100:101], v[44:45], v[80:81] op_sel:[0,1] op_sel_hi:[1,0]
	v_mov_b32_e32 v88, v4
	v_pk_add_f32 v[2:3], v[2:3], v[84:85] neg_lo:[0,1] neg_hi:[0,1]
	v_pk_fma_f32 v[144:145], v[42:43], v[80:81], v[100:101] neg_lo:[0,0,1] neg_hi:[0,0,1]
	v_pk_fma_f32 v[80:81], v[42:43], v[80:81], v[100:101]
	v_pk_mul_f32 v[100:101], v[60:61], v[86:87] op_sel:[0,1] op_sel_hi:[1,0]
	v_pk_add_f32 v[82:83], v[82:83], v[82:83] op_sel:[0,1] op_sel_hi:[0,1] neg_lo:[0,1] neg_hi:[0,1]
	v_pk_mul_f32 v[90:91], v[72:73], v[90:91]
	v_pk_mov_b32 v[4:5], v[98:99], v[4:5] op_sel:[1,0]
	v_mov_b32_e32 v89, v99
	v_mov_b32_e32 v118, v78
	v_mov_b32_e32 v84, v2
	v_pk_fma_f32 v[146:147], v[58:59], v[86:87], v[100:101] neg_lo:[0,0,1] neg_hi:[0,0,1]
	v_pk_fma_f32 v[86:87], v[58:59], v[86:87], v[100:101]
	v_pk_fma_f32 v[100:101], v[20:21], v[82:83], v[90:91] neg_lo:[0,0,1] neg_hi:[0,0,1]
	v_pk_fma_f32 v[82:83], v[20:21], v[82:83], v[90:91]
	v_pk_mul_f32 v[4:5], v[36:37], v[4:5]
	v_pk_mov_b32 v[78:79], v[112:113], v[78:79] op_sel:[1,0]
	v_pk_mov_b32 v[2:3], v[116:117], v[2:3] op_sel:[1,0]
	v_mov_b32_e32 v119, v113
	v_mov_b32_e32 v85, v117
	v_mov_b32_e32 v101, v83
	v_pk_fma_f32 v[82:83], v[34:35], v[88:89], v[4:5] neg_lo:[0,0,1] neg_hi:[0,0,1]
	v_pk_fma_f32 v[4:5], v[34:35], v[88:89], v[4:5]
	v_pk_mul_f32 v[78:79], v[52:53], v[78:79]
	v_pk_mul_f32 v[2:3], v[68:69], v[2:3]
	v_pk_fma_f32 v[88:89], v[50:51], v[118:119], v[78:79] neg_lo:[0,0,1] neg_hi:[0,0,1]
	v_pk_fma_f32 v[90:91], v[66:67], v[84:85], v[2:3] neg_lo:[0,0,1] neg_hi:[0,0,1]
	v_pk_fma_f32 v[2:3], v[66:67], v[84:85], v[2:3]
	v_mov_b32_e32 v4, v1
	v_mov_b32_e32 v121, v111
	v_pk_fma_f32 v[78:79], v[50:51], v[118:119], v[78:79]
	v_mov_b32_e32 v91, v3
	s_barrier
	v_add_f32_e32 v150, v136, v144
	v_add_f32_e32 v151, v95, v81
	v_add_f32_e32 v156, v138, v146
	v_add_f32_e32 v157, v97, v87
	v_mov_b32_e32 v104, v95
	v_mov_b32_e32 v139, v95
	v_mov_b32_e32 v147, v81
	v_pk_mov_b32 v[94:95], v[110:111], v[140:141] op_sel:[1,0]
	v_pk_mov_b32 v[2:3], v[2:3], v[88:89] op_sel:[1,0]
	v_mul_lo_u32 v115, v4, s33
	v_pk_add_f32 v[158:159], v[120:121], v[90:91]
	v_mov_b32_e32 v92, v81
	v_pk_mov_b32 v[96:97], v[96:97], v[136:137] op_sel:[1,0]
	v_pk_mov_b32 v[86:87], v[86:87], v[144:145] op_sel:[1,0]
	v_pk_add_f32 v[80:81], v[138:139], v[146:147] neg_lo:[0,1] neg_hi:[0,1]
	v_pk_add_f32 v[2:3], v[94:95], v[2:3] neg_lo:[0,1] neg_hi:[0,1]
	v_mov_b32_e32 v83, v5
	v_add_f32_e32 v116, v132, v102
	v_add_f32_e32 v117, v105, v93
	v_add_f32_e32 v152, v140, v88
	v_add_f32_e32 v153, v109, v79
	v_mov_b32_e32 v169, v132
	v_sub_f32_e32 v4, v109, v79
	v_sub_f32_e32 v5, v107, v5
	v_mov_b32_e32 v106, v88
	v_pk_add_f32 v[86:87], v[96:97], v[86:87] neg_lo:[0,1] neg_hi:[0,1]
	v_sub_f32_e32 v78, v120, v90
	v_sub_f32_e32 v79, v109, v79
	v_pk_add_f32 v[88:89], v[80:81], v[2:3]
	v_pk_add_f32 v[2:3], v[80:81], v[2:3] neg_lo:[0,1] neg_hi:[0,1]
	v_mov_b32_e32 v131, v107
	v_sub_f32_e32 v103, v169, v102
	v_sub_f32_e32 v102, v136, v144
	v_pk_add_f32 v[92:93], v[104:105], v[92:93] neg_lo:[0,1] neg_hi:[0,1]
	v_pk_add_f32 v[90:91], v[86:87], v[78:79] neg_lo:[0,1] neg_hi:[0,1]
	v_pk_add_f32 v[78:79], v[86:87], v[78:79]
	v_pk_add_f32 v[84:85], v[134:135], v[128:129]
	v_pk_add_f32 v[98:99], v[142:143], v[100:101]
	v_pk_add_f32 v[118:119], v[130:131], v[82:83]
	v_sub_f32_e32 v83, v130, v82
	v_sub_f32_e32 v82, v140, v106
	v_pk_add_f32 v[94:95], v[102:103], v[4:5]
	v_mul_f32_e32 v105, 0x3f3504f3, v89
	v_mul_f32_e32 v80, s74, v88
	v_mul_f32_e32 v81, s75, v3
	v_mov_b32_e32 v89, v90
	v_mul_f32_e32 v4, 0x3f6c835e, v90
	v_pk_add_f32 v[112:113], v[84:85], v[98:99]
	v_pk_add_f32 v[154:155], v[150:151], v[152:153]
	v_pk_add_f32 v[160:161], v[156:157], v[158:159]
	v_pk_add_f32 v[84:85], v[84:85], v[98:99] neg_lo:[0,1] neg_hi:[0,1]
	v_pk_add_f32 v[98:99], v[150:151], v[152:153] neg_lo:[0,1] neg_hi:[0,1]
	v_mov_b32_e32 v151, v156
	v_mov_b32_e32 v153, v158
	v_fma_f32 v80, v90, s72, -v80
	v_fma_f32 v81, v79, s73, -v81
	v_pk_fma_f32 v[86:87], v[88:89], s[80:81], v[4:5] op_sel_hi:[1,1,0] neg_lo:[0,0,1] neg_hi:[0,0,1]
	v_add_f32_e32 v4, v93, v83
	v_pk_add_f32 v[148:149], v[116:117], v[118:119]
	v_pk_add_f32 v[100:101], v[142:143], v[100:101] neg_lo:[0,1] neg_hi:[0,1]
	v_mov_b32_e32 v150, v116
	v_mov_b32_e32 v152, v118
	v_sub_f32_e32 v116, v117, v119
	v_sub_f32_e32 v117, v157, v159
	v_pk_add_f32 v[96:97], v[92:93], v[82:83] neg_lo:[0,1] neg_hi:[0,1]
	v_pk_mul_f32 v[82:83], v[4:5], s[38:39] op_sel_hi:[0,1]
	v_sub_f32_e32 v4, v103, v5
	v_pk_add_f32 v[128:129], v[134:135], v[128:129] neg_lo:[0,1] neg_hi:[0,1]
	v_pk_mov_b32 v[134:135], v[100:101], v[100:101] op_sel:[1,0]
	v_pk_add_f32 v[150:151], v[150:151], v[152:153] neg_lo:[0,1] neg_hi:[0,1]
	v_pk_mul_f32 v[116:117], v[116:117], s[20:21] op_sel_hi:[1,0]
	v_pk_fma_f32 v[92:93], v[4:5], s[40:41], v[82:83] op_sel_hi:[0,1,1] neg_lo:[0,0,1] neg_hi:[0,0,1]
	v_pk_fma_f32 v[4:5], v[4:5], s[40:41], v[82:83] op_sel_hi:[0,1,1]
	v_pk_fma_f32 v[118:119], v[150:151], s[2:3], v[116:117] neg_lo:[0,0,1] neg_hi:[0,0,1]
	v_pk_fma_f32 v[152:153], v[150:151], s[2:3], v[116:117]
	v_pk_fma_f32 v[116:117], v[150:151], s[20:21], v[116:117] op_sel_hi:[1,0,1] neg_lo:[0,0,1] neg_hi:[0,0,1]
	v_pk_add_f32 v[150:151], v[84:85], v[98:99] op_sel:[0,1] op_sel_hi:[1,0] neg_lo:[0,1] neg_hi:[0,1]
	v_pk_add_f32 v[84:85], v[84:85], v[98:99] op_sel:[0,1] op_sel_hi:[1,0]
	v_mul_f32_e32 v134, 0x3f6c835e, v97
	s_mov_b32 s42, s3
	s_mov_b32 s43, s21
	v_pk_mul_f32 v[96:97], v[96:97], s[70:71]
	v_mov_b32_e32 v93, v5
	v_pk_mul_f32 v[4:5], v[78:79], s[40:41] op_sel_hi:[0,1]
	v_pk_add_f32 v[142:143], v[128:129], v[100:101] op_sel:[0,1] op_sel_hi:[1,0] neg_lo:[0,1] neg_hi:[0,1]
	v_pk_add_f32 v[100:101], v[128:129], v[100:101] op_sel:[0,1] op_sel_hi:[1,0]
	v_mov_b32_e32 v99, v85
	v_mul_f32_e32 v128, 0x3ec3ef15, v95
	v_mul_f32_e32 v85, 0x3f3504f3, v91
	v_pk_fma_f32 v[106:107], v[94:95], s[42:43], v[96:97] neg_lo:[0,0,1] neg_hi:[0,0,1]
	v_pk_fma_f32 v[94:95], v[94:95], s[42:43], v[96:97]
	v_pk_fma_f32 v[78:79], v[2:3], s[38:39], v[4:5] neg_lo:[0,0,1] neg_hi:[0,0,1]
	v_pk_fma_f32 v[2:3], v[2:3], s[38:39], v[4:5] op_sel_hi:[0,1,1]
	v_mov_b32_e32 v143, v101
	v_pk_add_f32 v[88:89], v[128:129], v[134:135] neg_lo:[0,1] neg_hi:[0,1]
	v_sub_f32_e32 v104, v85, v105
	v_fmac_f32_e32 v105, 0x3f3504f3, v91
	v_mov_b32_e32 v79, v3
	v_pk_add_f32 v[162:163], v[112:113], v[154:155]
	v_pk_add_f32 v[164:165], v[148:149], v[160:161]
	v_pk_mov_b32 v[156:157], v[118:119], v[152:153] op_sel:[1,0]
	v_pk_add_f32 v[2:3], v[142:143], v[104:105]
	v_pk_add_f32 v[4:5], v[92:93], v[78:79]
	v_add_f32_e32 v90, v106, v100
	v_add_f32_e32 v91, v95, v86
	v_pk_add_f32 v[96:97], v[88:89], v[80:81]
	v_pk_add_f32 v[166:167], v[162:163], v[164:165]
	v_mov_b32_e32 v98, v150
	v_pk_add_f32 v[156:157], v[116:117], v[156:157]
	v_pk_add_f32 v[82:83], v[2:3], v[4:5]
	v_pk_add_f32 v[102:103], v[96:97], v[90:91]
	v_pk_add_f32 v[158:159], v[98:99], v[156:157]
	ds_write2_b64 v115, v[166:167], v[82:83] offset1:1
	ds_write2_b64 v115, v[158:159], v[102:103] offset0:2 offset1:3
	v_pk_add_f32 v[82:83], v[112:113], v[154:155] neg_lo:[0,1] neg_hi:[0,1]
	v_pk_add_f32 v[102:103], v[148:149], v[160:161] neg_lo:[0,1] neg_hi:[0,1]
	v_pk_add_f32 v[78:79], v[92:93], v[78:79] neg_lo:[0,1] neg_hi:[0,1]
	v_pk_add_f32 v[108:109], v[82:83], v[102:103] op_sel:[0,1] op_sel_hi:[1,0] neg_lo:[0,1] neg_hi:[0,1]
	v_pk_add_f32 v[82:83], v[82:83], v[102:103] op_sel:[0,1] op_sel_hi:[1,0]
	v_pk_add_f32 v[102:103], v[142:143], v[104:105] neg_lo:[0,1] neg_hi:[0,1]
	v_pk_add_f32 v[92:93], v[102:103], v[78:79] op_sel:[0,1] op_sel_hi:[1,0] neg_lo:[0,1] neg_hi:[0,1]
	v_pk_add_f32 v[78:79], v[102:103], v[78:79] op_sel:[0,1] op_sel_hi:[1,0]
	v_mov_b32_e32 v102, v108
	v_mov_b32_e32 v103, v83
	v_mov_b32_e32 v104, v92
	v_mov_b32_e32 v105, v79
	v_pk_mov_b32 v[94:95], v[94:95], v[88:89] op_sel:[1,0]
	v_mov_b32_e32 v87, v80
	ds_write2_b64 v115, v[102:103], v[104:105] offset0:4 offset1:5
	v_mov_b32_e32 v85, v151
	v_sub_f32_e32 v102, v152, v117
	v_sub_f32_e32 v103, v116, v119
	v_pk_add_f32 v[86:87], v[94:95], v[86:87] neg_lo:[0,1] neg_hi:[0,1]
	v_sub_f32_e32 v80, v100, v106
	v_sub_f32_e32 v81, v89, v81
	v_pk_add_f32 v[104:105], v[84:85], v[102:103] neg_lo:[0,1] neg_hi:[0,1]
	v_pk_add_f32 v[84:85], v[84:85], v[102:103]
	v_pk_add_f32 v[88:89], v[80:81], v[86:87] neg_lo:[0,1] neg_hi:[0,1]
	v_pk_add_f32 v[80:81], v[80:81], v[86:87]
	v_mov_b32_e32 v86, v104
	v_mov_b32_e32 v87, v85
	v_mov_b32_e32 v94, v88
	v_mov_b32_e32 v95, v81
	ds_write2_b64 v115, v[86:87], v[94:95] offset0:6 offset1:7
	v_pk_add_f32 v[86:87], v[162:163], v[164:165] neg_lo:[0,1] neg_hi:[0,1]
	v_pk_add_f32 v[2:3], v[2:3], v[4:5] neg_lo:[0,1] neg_hi:[0,1]
	v_mov_b32_e32 v5, v97
	ds_write2_b64 v115, v[86:87], v[2:3] offset0:8 offset1:9
	v_pk_add_f32 v[2:3], v[98:99], v[156:157] neg_lo:[0,1] neg_hi:[0,1]
	v_sub_f32_e32 v4, v90, v96
	v_sub_f32_e32 v5, v5, v91
	ds_write2_b64 v115, v[2:3], v[4:5] offset0:10 offset1:11
	v_mov_b32_e32 v83, v109
	v_mov_b32_e32 v79, v93
	v_mov_b32_e32 v85, v105
	v_mov_b32_e32 v81, v89
	v_mov_b32_e32 v2, v1
	ds_write2_b64 v115, v[82:83], v[78:79] offset0:12 offset1:13
	ds_write2_b64 v115, v[84:85], v[80:81] offset0:14 offset1:15
	s_waitcnt lgkmcnt(0)
	s_barrier
	s_nop 0
	v_ashrrev_i32_e32 v3, 31, v2
	v_lshrrev_b32_e32 v3, 28, v3
	v_and_b32_e32 v106, 15, v2
	v_add_u32_e32 v2, v2, v3
	v_ashrrev_i32_e32 v2, 4, v2
	v_lshlrev_b32_e32 v3, 11, v2
	v_lshl_add_u32 v2, v2, 7, v3
	v_lshl_or_b32 v115, v106, 3, v2
	ds_read2_b64 v[2:5], v115 offset1:17
	ds_read2_b64 v[78:81], v115 offset0:34 offset1:51
	ds_read2_b64 v[82:85], v115 offset0:68 offset1:85
	ds_read2_b64 v[86:89], v115 offset0:102 offset1:119
	ds_read2_b64 v[90:93], v115 offset0:136 offset1:153
	ds_read2_b64 v[94:97], v115 offset0:170 offset1:187
	ds_read2_b64 v[98:101], v115 offset0:204 offset1:221
	ds_read2_b64 v[102:105], v115 offset0:238 offset1:255
	s_waitcnt lgkmcnt(4)
	v_mov_b32_e32 v158, v86
	v_cvt_f32_i32_e32 v106, v106
	v_mov_b32_e32 v159, v85
	v_pk_mov_b32 v[84:85], v[86:87], v[84:85] op_sel:[1,0]
	v_add_f32_e32 v106, v106, v106
	v_mul_f32_e32 v106, 0x3b800000, v106
	v_mul_f32_e32 v106, 0.5, v106
	v_sin_f32_e32 v107, v106
	v_cos_f32_e32 v106, v106
	v_mul_f32_e32 v110, v107, v107
	v_mul_f32_e32 v108, v106, v107
	v_pk_fma_f32 v[110:111], v[106:107], v[106:107], v[110:111] op_sel_hi:[1,1,0] neg_lo:[0,0,1] neg_hi:[0,0,1]
	v_add_f32_e32 v108, v108, v108
	v_mov_b32_e32 v112, v110
	v_mov_b32_e32 v113, v106
	v_mov_b32_e32 v109, v107
	v_pk_mul_f32 v[116:117], v[112:113], v[110:111] op_sel_hi:[1,0]
	v_pk_mul_f32 v[120:121], v[108:109], v[110:111] op_sel_hi:[1,0]
	v_pk_fma_f32 v[134:135], v[108:109], v[108:109], v[116:117] op_sel_hi:[1,0,1] neg_lo:[1,0,0] neg_hi:[1,0,0]
	v_pk_fma_f32 v[128:129], v[112:113], v[108:109], v[120:121] op_sel_hi:[1,0,1]
	v_mov_b32_e32 v136, v134
	v_mov_b32_e32 v137, v106
	v_pk_mul_f32 v[118:119], v[112:113], v[108:109] op_sel_hi:[1,0]
	v_pk_mul_f32 v[138:139], v[136:137], v[134:135] op_sel_hi:[1,0]
	v_mov_b32_e32 v111, v134
	v_mul_f32_e32 v146, v108, v134
	v_mul_f32_e32 v147, v128, v134
	v_mul_f32_e32 v148, v128, v110
	v_mul_f32_e32 v149, v107, v111
	v_mul_f32_e32 v144, v128, v108
	v_mul_f32_e32 v145, v128, v128
	v_add_f32_e32 v118, v147, v147
	v_add_f32_e32 v119, v119, v121
	v_fma_f32 v120, v136, v108, v148
	v_fma_f32 v121, v137, v128, v149
	v_fma_f32 v116, -v128, v128, v138
	v_fma_f32 v117, -v107, v108, v117
	v_pk_mul_f32 v[132:133], v[134:135], v[128:129] op_sel:[0,1] op_sel_hi:[1,0]
	v_pk_mul_f32 v[148:149], v[128:129], v[134:135] op_sel:[0,1] op_sel_hi:[1,0]
	v_mul_f32_e32 v150, v128, v134
	v_mul_f32_e32 v151, v107, v134
	v_fma_f32 v130, -v128, v128, v138
	v_fma_f32 v131, -v107, v128, v139
	v_pk_fma_f32 v[138:139], v[134:135], v[110:111], v[144:145] op_sel_hi:[0,1,1] neg_lo:[0,0,1] neg_hi:[0,0,1]
	v_pk_fma_f32 v[144:145], v[110:111], v[128:129], v[146:147] op_sel_hi:[1,0,1]
	v_add_f32_e32 v132, v132, v148
	v_add_f32_e32 v133, v147, v147
	v_mov_b32_e32 v149, v106
	v_pk_mul_f32 v[142:143], v[128:129], v[128:129] op_sel_hi:[0,1]
	v_pk_fma_f32 v[136:137], v[136:137], v[128:129], v[150:151] op_sel_hi:[1,0,1]
	v_mul_f32_e32 v106, v145, v110
	v_mul_f32_e32 v107, v107, v130
	v_pk_fma_f32 v[142:143], v[134:135], v[134:135], v[142:143] op_sel_hi:[0,1,1] neg_lo:[0,0,1] neg_hi:[0,0,1]
	v_fma_f32 v106, v130, v108, v106
	v_fma_f32 v107, v149, v145, v107
	v_pk_mov_b32 v[150:151], v[144:145], v[128:129] op_sel:[1,0]
	v_pk_mul_f32 v[152:153], v[150:151], v[132:133]
	v_pk_mul_f32 v[150:151], v[150:151], v[142:143] op_sel:[0,1] op_sel_hi:[1,0]
	v_pk_mul_f32 v[136:137], v[136:137], v[138:139]
	v_fma_f32 v138, v130, v143, -v152
	v_fma_f32 v139, v134, v142, -v153
	v_fma_f32 v148, v130, v132, v150
	v_fma_f32 v149, v134, v133, v151
	v_mov_b32_e32 v150, v78
	v_mov_b32_e32 v151, v5
	v_pk_mov_b32 v[4:5], v[78:79], v[4:5] op_sel:[1,0]
	v_pk_mul_f32 v[140:141], v[108:109], v[128:129] op_sel_hi:[1,0]
	v_pk_mul_f32 v[146:147], v[108:109], v[144:145] op_sel:[0,1]
	v_pk_mul_f32 v[78:79], v[4:5], v[108:109]
	v_pk_mul_f32 v[108:109], v[150:151], v[108:109]
	v_mul_f32_e32 v118, v134, v118
	v_mul_f32_e32 v119, v130, v119
	v_pk_fma_f32 v[152:153], v[150:151], v[112:113], v[78:79] neg_lo:[0,0,1] neg_hi:[0,0,1]
	v_pk_fma_f32 v[78:79], v[150:151], v[112:113], v[78:79]
	v_pk_fma_f32 v[150:151], v[4:5], v[112:113], v[108:109] neg_lo:[0,0,1] neg_hi:[0,0,1]
	v_pk_fma_f32 v[4:5], v[4:5], v[112:113], v[108:109]
	v_pk_fma_f32 v[140:141], v[112:113], v[134:135], v[140:141] op_sel_hi:[1,0,1] neg_lo:[0,0,1] neg_hi:[0,0,1]
	v_pk_fma_f32 v[146:147], v[112:113], v[130:131], v[146:147] op_sel_hi:[1,0,1] neg_lo:[0,0,1] neg_hi:[0,0,1]
	v_fma_f32 v116, v128, v116, v118
	v_fma_f32 v117, v145, v117, v119
	v_pk_mul_f32 v[118:119], v[144:145], v[120:121] op_sel:[1,0]
	v_pk_mov_b32 v[108:109], v[150:151], v[4:5] op_sel:[1,0]
	v_mul_f32_e32 v150, v81, v129
	v_pk_mul_f32 v[86:87], v[84:85], v[120:121]
	v_pk_mul_f32 v[120:121], v[158:159], v[120:121]
	v_pk_fma_f32 v[118:119], v[130:131], v[140:141], v[118:119] op_sel_hi:[0,1,1] neg_lo:[0,0,1] neg_hi:[0,0,1]
	v_fma_f32 v112, v80, v135, -v150
	v_fma_f32 v113, v81, v129, -v150
	v_mov_b32_e32 v154, v82
	v_mov_b32_e32 v155, v81
	v_pk_mov_b32 v[80:81], v[82:83], v[80:81] op_sel:[1,0]
	v_pk_fma_f32 v[160:161], v[158:159], v[140:141], v[86:87] neg_lo:[0,0,1] neg_hi:[0,0,1]
	v_pk_fma_f32 v[86:87], v[158:159], v[140:141], v[86:87]
	v_pk_fma_f32 v[158:159], v[84:85], v[140:141], v[120:121] neg_lo:[0,0,1] neg_hi:[0,0,1]
	v_pk_fma_f32 v[84:85], v[84:85], v[140:141], v[120:121]
	v_mov_b32_e32 v141, v83
	v_pk_mov_b32 v[82:83], v[88:89], v[82:83] op_sel:[1,0]
	v_mov_b32_e32 v133, v128
	v_pk_mul_f32 v[82:83], v[82:83], v[132:133]
	v_mov_b32_e32 v133, v143
	v_mul_f32_e32 v86, v89, v143
	v_pk_mul_f32 v[110:111], v[128:129], v[144:145] op_sel:[0,1]
	v_pk_mul_f32 v[80:81], v[80:81], v[128:129]
	v_mov_b32_e32 v140, v88
	v_pk_fma_f32 v[88:89], v[88:89], v[132:133], v[86:87] op_sel_hi:[1,1,0]
	s_waitcnt lgkmcnt(2)
	v_mov_b32_e32 v132, v94
	v_mov_b32_e32 v133, v93
	v_pk_mov_b32 v[92:93], v[94:95], v[92:93] op_sel:[1,0]
	v_pk_fma_f32 v[110:111], v[134:135], v[130:131], v[110:111] op_sel_hi:[1,0,1] neg_lo:[0,0,1] neg_hi:[0,0,1]
	v_pk_fma_f32 v[156:157], v[154:155], v[134:135], v[80:81] neg_lo:[0,0,1] neg_hi:[0,0,1]
	v_pk_fma_f32 v[80:81], v[154:155], v[134:135], v[80:81]
	v_pk_mov_b32 v[134:135], v[142:143], v[134:135] op_sel:[1,0]
	v_pk_mul_f32 v[94:95], v[92:93], v[106:107]
	v_pk_mul_f32 v[106:107], v[132:133], v[106:107]
	v_pk_fma_f32 v[128:129], v[140:141], v[134:135], v[82:83] neg_lo:[0,0,1] neg_hi:[0,0,1]
	v_pk_fma_f32 v[82:83], v[140:141], v[134:135], v[82:83]
	v_pk_fma_f32 v[134:135], v[132:133], v[146:147], v[94:95] neg_lo:[0,0,1] neg_hi:[0,0,1]
	v_pk_fma_f32 v[94:95], v[132:133], v[146:147], v[94:95]
	v_pk_fma_f32 v[132:133], v[92:93], v[146:147], v[106:107] neg_lo:[0,0,1] neg_hi:[0,0,1]
	v_pk_fma_f32 v[92:93], v[92:93], v[146:147], v[106:107]
	v_pk_mov_b32 v[146:147], v[96:97], v[90:91] op_sel:[1,0]
	v_pk_mov_b32 v[142:143], v[110:111], v[130:131] op_sel:[1,0]
	v_mul_f32_e32 v146, v146, v117
	v_mul_f32_e32 v147, v147, v145
	v_pk_fma_f32 v[136:137], v[130:131], v[144:145], v[136:137]
	v_fma_f32 v162, v96, v142, -v146
	v_fma_f32 v163, v91, v143, -v147
	v_fma_f32 v140, v96, v142, v146
	v_fma_f32 v141, v91, v143, v147
	v_mov_b32_e32 v143, v97
	s_waitcnt lgkmcnt(1)
	v_pk_mov_b32 v[96:97], v[98:99], v[96:97] op_sel:[1,0]
	v_mov_b32_e32 v142, v98
	v_pk_mul_f32 v[96:97], v[96:97], v[116:117]
	v_pk_mov_b32 v[144:145], v[144:145], v[148:149] op_sel:[1,0]
	v_pk_fma_f32 v[116:117], v[142:143], v[110:111], v[96:97] neg_lo:[0,0,1] neg_hi:[0,0,1]
	v_pk_fma_f32 v[96:97], v[142:143], v[110:111], v[96:97]
	s_waitcnt lgkmcnt(0)
	v_mov_b32_e32 v142, v102
	v_mov_b32_e32 v143, v101
	v_pk_mov_b32 v[100:101], v[102:103], v[100:101] op_sel:[1,0]
	v_mov_b32_e32 v131, v138
	v_pk_mul_f32 v[102:103], v[100:101], v[136:137]
	v_pk_mul_f32 v[136:137], v[142:143], v[136:137]
	v_pk_fma_f32 v[146:147], v[142:143], v[118:119], v[102:103] neg_lo:[0,0,1] neg_hi:[0,0,1]
	v_pk_fma_f32 v[102:103], v[142:143], v[118:119], v[102:103]
	v_pk_fma_f32 v[142:143], v[100:101], v[118:119], v[136:137] neg_lo:[0,0,1] neg_hi:[0,0,1]
	v_pk_fma_f32 v[100:101], v[100:101], v[118:119], v[136:137]
	v_mov_b32_e32 v137, v99
	v_pk_mov_b32 v[98:99], v[104:105], v[98:99] op_sel:[1,0]
	v_mov_b32_e32 v136, v104
	v_pk_mul_f32 v[98:99], v[98:99], v[148:149]
	v_pk_fma_f32 v[164:165], v[136:137], v[138:139], v[98:99] neg_lo:[0,0,1] neg_hi:[0,0,1]
	v_pk_fma_f32 v[98:99], v[136:137], v[138:139], v[98:99]
	v_pk_mov_b32 v[136:137], v[90:91], v[104:105] op_sel:[1,0]
	v_mov_b32_e32 v91, v105
	v_pk_mul_f32 v[136:137], v[136:137], v[144:145]
	v_pk_fma_f32 v[104:105], v[90:91], v[130:131], v[136:137] neg_lo:[0,0,1] neg_hi:[0,0,1]
	v_pk_fma_f32 v[90:91], v[90:91], v[130:131], v[136:137]
	v_pk_mov_b32 v[120:121], v[158:159], v[84:85] op_sel:[1,0]
	v_pk_mov_b32 v[106:107], v[132:133], v[92:93] op_sel:[1,0]
	v_pk_mov_b32 v[118:119], v[142:143], v[100:101] op_sel:[1,0]
	v_mov_b32_e32 v105, v91
	v_add_f32_e32 v136, v112, v162
	v_add_f32_e32 v137, v3, v141
	v_mov_b32_e32 v89, v160
	v_pk_mov_b32 v[90:91], v[90:91], v[146:147] op_sel:[1,0]
	v_mov_b32_e32 v155, v81
	v_mov_b32_e32 v111, v97
	v_mov_b32_e32 v131, v88
	v_add_f32_e32 v138, v128, v164
	v_add_f32_e32 v139, v83, v99
	v_pk_add_f32 v[106:107], v[108:109], v[106:107]
	v_pk_add_f32 v[108:109], v[120:121], v[118:119]
	v_add_f32_e32 v118, v152, v134
	v_add_f32_e32 v119, v79, v95
	v_sub_f32_e32 v78, v4, v92
	v_sub_f32_e32 v79, v79, v95
	v_pk_mov_b32 v[80:81], v[80:81], v[152:153] op_sel:[1,0]
	v_pk_mov_b32 v[96:97], v[96:97], v[134:135] op_sel:[1,0]
	v_sub_f32_e32 v5, v4, v92
	v_sub_f32_e32 v4, v112, v162
	v_pk_add_f32 v[88:89], v[88:89], v[90:91] neg_lo:[0,1] neg_hi:[0,1]
	v_mov_b32_e32 v130, v2
	v_add_f32_e32 v120, v160, v146
	v_add_f32_e32 v121, v87, v103
	v_sub_f32_e32 v86, v84, v100
	v_sub_f32_e32 v87, v87, v103
	v_pk_add_f32 v[80:81], v[80:81], v[96:97] neg_lo:[0,1] neg_hi:[0,1]
	v_sub_f32_e32 v85, v84, v100
	v_sub_f32_e32 v84, v128, v164
	v_pk_add_f32 v[90:91], v[4:5], v[88:89]
	v_pk_add_f32 v[4:5], v[4:5], v[88:89] neg_lo:[0,1] neg_hi:[0,1]
	v_pk_add_f32 v[130:131], v[130:131], v[104:105]
	v_mov_b32_e32 v105, v141
	v_pk_mov_b32 v[82:83], v[82:83], v[156:157] op_sel:[1,0]
	v_pk_mov_b32 v[98:99], v[98:99], v[116:117] op_sel:[1,0]
	v_sub_f32_e32 v132, v152, v134
	v_sub_f32_e32 v133, v151, v133
	v_sub_f32_e32 v94, v160, v146
	v_sub_f32_e32 v95, v159, v143
	v_pk_add_f32 v[96:97], v[80:81], v[84:85] neg_lo:[0,1] neg_hi:[0,1]
	v_pk_add_f32 v[80:81], v[80:81], v[84:85]
	v_pk_add_f32 v[2:3], v[2:3], v[104:105] neg_lo:[0,1] neg_hi:[0,1]
	v_pk_add_f32 v[82:83], v[82:83], v[98:99] neg_lo:[0,1] neg_hi:[0,1]
	v_pk_add_f32 v[92:93], v[132:133], v[86:87]
	v_pk_add_f32 v[100:101], v[78:79], v[94:95] neg_lo:[0,1] neg_hi:[0,1]
	v_mul_f32_e32 v103, 0x3f3504f3, v91
	v_mul_f32_e32 v84, s74, v90
	v_mul_f32_e32 v85, s75, v5
	v_mov_b32_e32 v91, v96
	v_mul_f32_e32 v78, 0x3f6c835e, v96
	v_add_f32_e32 v110, v156, v116
	v_add_f32_e32 v111, v155, v111
	v_pk_add_f32 v[98:99], v[2:3], v[82:83] neg_lo:[0,1] neg_hi:[0,1]
	v_pk_add_f32 v[104:105], v[2:3], v[82:83]
	v_mul_f32_e32 v2, 0x3ec3ef15, v93
	v_mul_f32_e32 v82, 0x3f6c835e, v101
	v_fma_f32 v84, v96, s72, -v84
	v_fma_f32 v85, v81, s73, -v85
	v_pk_fma_f32 v[88:89], v[90:91], s[80:81], v[78:79] op_sel_hi:[1,1,0] neg_lo:[0,0,1] neg_hi:[0,0,1]
	v_add_f32_e32 v78, v79, v95
	v_pk_add_f32 v[2:3], v[2:3], v[82:83] neg_lo:[0,1] neg_hi:[0,1]
	v_pk_mul_f32 v[78:79], v[78:79], s[38:39] op_sel_hi:[0,1]
	v_sub_f32_e32 v82, v133, v87
	v_pk_add_f32 v[148:149], v[106:107], v[108:109]
	v_pk_add_f32 v[166:167], v[110:111], v[130:131]
	v_sub_f32_e32 v116, v130, v110
	v_sub_f32_e32 v117, v118, v120
	v_mov_b32_e32 v140, v107
	v_mov_b32_e32 v156, v109
	v_pk_fma_f32 v[86:87], v[82:83], s[40:41], v[78:79] op_sel_hi:[0,1,1] neg_lo:[0,0,1] neg_hi:[0,0,1]
	v_pk_fma_f32 v[78:79], v[82:83], s[40:41], v[78:79] op_sel_hi:[0,1,1]
	v_sub_f32_e32 v106, v106, v108
	v_sub_f32_e32 v107, v136, v138
	v_sub_f32_e32 v108, v119, v121
	v_sub_f32_e32 v109, v111, v131
	v_pk_mul_f32 v[100:101], v[100:101], s[70:71]
	v_mov_b32_e32 v87, v79
	v_pk_mul_f32 v[78:79], v[80:81], s[40:41] op_sel_hi:[0,1]
	v_pk_mul_f32 v[108:109], v[108:109], s[20:21] op_sel_hi:[1,0]
	v_mul_f32_e32 v94, 0x3f3504f3, v97
	v_pk_fma_f32 v[112:113], v[92:93], s[42:43], v[100:101] neg_lo:[0,0,1] neg_hi:[0,0,1]
	v_pk_fma_f32 v[92:93], v[92:93], s[42:43], v[100:101]
	v_pk_fma_f32 v[80:81], v[4:5], s[38:39], v[78:79] neg_lo:[0,0,1] neg_hi:[0,0,1]
	v_pk_fma_f32 v[4:5], v[4:5], s[38:39], v[78:79] op_sel_hi:[0,1,1]
	v_pk_add_f32 v[144:145], v[118:119], v[120:121]
	v_pk_add_f32 v[154:155], v[136:137], v[138:139]
	v_mov_b32_e32 v99, v105
	v_sub_f32_e32 v140, v140, v156
	v_sub_f32_e32 v141, v137, v139
	v_pk_fma_f32 v[110:111], v[106:107], s[2:3], v[108:109] neg_lo:[0,0,1] neg_hi:[0,0,1]
	v_pk_fma_f32 v[118:119], v[106:107], s[2:3], v[108:109]
	v_sub_f32_e32 v102, v94, v103
	v_fmac_f32_e32 v103, 0x3f3504f3, v97
	v_mov_b32_e32 v81, v5
	v_pk_add_f32 v[168:169], v[148:149], v[154:155]
	v_pk_add_f32 v[170:171], v[144:145], v[166:167]
	v_pk_mov_b32 v[120:121], v[110:111], v[118:119] op_sel:[1,0]
	v_pk_fma_f32 v[106:107], v[106:107], s[20:21], v[108:109] op_sel_hi:[1,0,1] neg_lo:[0,0,1] neg_hi:[0,0,1]
	v_pk_add_f32 v[108:109], v[116:117], v[140:141] neg_lo:[0,1] neg_hi:[0,1]
	v_pk_add_f32 v[130:131], v[116:117], v[140:141]
	v_pk_add_f32 v[4:5], v[98:99], v[102:103]
	v_pk_add_f32 v[78:79], v[86:87], v[80:81]
	v_add_f32_e32 v90, v112, v104
	v_add_f32_e32 v91, v93, v88
	v_pk_add_f32 v[94:95], v[2:3], v[84:85]
	v_pk_add_f32 v[172:173], v[170:171], v[168:169]
	v_mov_b32_e32 v109, v131
	v_pk_add_f32 v[120:121], v[106:107], v[120:121]
	v_pk_add_f32 v[82:83], v[4:5], v[78:79]
	v_pk_add_f32 v[96:97], v[94:95], v[90:91]
	v_pk_add_f32 v[136:137], v[108:109], v[120:121]
	ds_write2_b64 v115, v[172:173], v[82:83] offset1:17
	ds_write2_b64 v115, v[136:137], v[96:97] offset0:34 offset1:51
	v_mov_b32_e32 v83, v148
	v_mov_b32_e32 v97, v154
	v_sub_f32_e32 v82, v166, v144
	v_sub_f32_e32 v83, v83, v97
	v_sub_f32_e32 v96, v145, v167
	v_sub_f32_e32 v97, v155, v149
	v_pk_add_f32 v[98:99], v[98:99], v[102:103] neg_lo:[0,1] neg_hi:[0,1]
	v_pk_add_f32 v[80:81], v[86:87], v[80:81] neg_lo:[0,1] neg_hi:[0,1]
	v_pk_add_f32 v[100:101], v[82:83], v[96:97] neg_lo:[0,1] neg_hi:[0,1]
	v_pk_add_f32 v[128:129], v[82:83], v[96:97]
	v_pk_add_f32 v[86:87], v[98:99], v[80:81] op_sel:[0,1] op_sel_hi:[1,0] neg_lo:[0,1] neg_hi:[0,1]
	v_pk_add_f32 v[80:81], v[98:99], v[80:81] op_sel:[0,1] op_sel_hi:[1,0]
	v_mov_b32_e32 v101, v129
	v_mov_b32_e32 v98, v86
	v_mov_b32_e32 v99, v81
	ds_write2_b64 v115, v[100:101], v[98:99] offset0:68 offset1:85
	v_pk_add_f32 v[98:99], v[140:141], v[116:117] neg_lo:[0,1] neg_hi:[0,1]
	v_pk_mov_b32 v[92:93], v[92:93], v[2:3] op_sel:[1,0]
	v_mov_b32_e32 v89, v84
	v_mov_b32_e32 v105, v3
	v_mov_b32_e32 v113, v85
	v_mov_b32_e32 v131, v99
	v_sub_f32_e32 v98, v118, v107
	v_sub_f32_e32 v99, v106, v111
	v_pk_add_f32 v[88:89], v[92:93], v[88:89] neg_lo:[0,1] neg_hi:[0,1]
	v_pk_add_f32 v[2:3], v[104:105], v[112:113] neg_lo:[0,1] neg_hi:[0,1]
	v_pk_add_f32 v[100:101], v[130:131], v[98:99] neg_lo:[0,1] neg_hi:[0,1]
	v_pk_add_f32 v[98:99], v[130:131], v[98:99]
	v_pk_add_f32 v[84:85], v[2:3], v[88:89] neg_lo:[0,1] neg_hi:[0,1]
	v_pk_add_f32 v[2:3], v[2:3], v[88:89]
	v_mov_b32_e32 v102, v100
	v_mov_b32_e32 v103, v99
	v_mov_b32_e32 v88, v84
	v_mov_b32_e32 v89, v3
	ds_write2_b64 v115, v[102:103], v[88:89] offset0:102 offset1:119
	v_mov_b32_e32 v89, v169
	v_sub_f32_e32 v88, v170, v168
	v_sub_f32_e32 v89, v89, v171
	v_pk_add_f32 v[4:5], v[4:5], v[78:79] neg_lo:[0,1] neg_hi:[0,1]
	v_mov_b32_e32 v79, v95
	ds_write2_b64 v115, v[88:89], v[4:5] offset0:136 offset1:153
	v_pk_add_f32 v[4:5], v[108:109], v[120:121] neg_lo:[0,1] neg_hi:[0,1]
	v_sub_f32_e32 v78, v90, v94
	v_sub_f32_e32 v79, v79, v91
	ds_write2_b64 v115, v[4:5], v[78:79] offset0:170 offset1:187
	v_pk_add_f32 v[4:5], v[96:97], v[82:83] neg_lo:[0,1] neg_hi:[0,1]
	v_mov_b32_e32 v99, v101
	v_mov_b32_e32 v3, v85
	v_mov_b32_e32 v129, v5
	v_mov_b32_e32 v81, v87
	ds_write2_b64 v115, v[98:99], v[2:3] offset0:238 offset1:255
	v_mov_b32_e32 v2, v1
	ds_write2_b64 v115, v[128:129], v[80:81] offset0:204 offset1:221
	s_waitcnt lgkmcnt(0)
	s_barrier
	s_nop 0
	v_ashrrev_i32_e32 v3, 31, v2
	v_lshrrev_b32_e32 v3, 24, v3
	v_and_b32_e32 v4, 0xff, v2
	v_add_lshl_u32 v2, v2, v3, 4
	v_and_or_b32 v2, v2, s87, v4
	v_ashrrev_i32_e32 v3, 4, v2
	v_lshlrev_b32_e32 v2, 3, v2
	v_lshl_add_u32 v5, v3, 3, v2
	ds_read_b64 v[2:3], v5
	ds_read_b64 v[82:83], v5 offset:2176
	ds_read_b64 v[84:85], v5 offset:4352
	ds_read_b64 v[78:79], v5 offset:6528
	ds_read_b64 v[86:87], v5 offset:8704
	ds_read_b64 v[88:89], v5 offset:10880
	ds_read_b64 v[90:91], v5 offset:13056
	ds_read_b64 v[92:93], v5 offset:15232
	ds_read_b64 v[80:81], v5 offset:17408
	ds_read_b64 v[94:95], v5 offset:19584
	ds_read_b64 v[96:97], v5 offset:21760
	ds_read_b64 v[98:99], v5 offset:23936
	ds_read_b64 v[100:101], v5 offset:26112
	ds_read_b64 v[102:103], v5 offset:28288
	ds_read_b64 v[104:105], v5 offset:30464
	ds_read_b64 v[106:107], v5 offset:32640
	s_waitcnt lgkmcnt(9)
	v_mov_b32_e32 v164, v90
	v_cvt_f32_i32_e32 v4, v4
	v_mov_b32_e32 v165, v89
	v_pk_mov_b32 v[88:89], v[90:91], v[88:89] op_sel:[1,0]
	v_pk_mov_b32 v[160:161], v[86:87], v[78:79] op_sel:[1,0]
	v_add_f32_e32 v4, v4, v4
	v_mul_f32_e32 v4, 0x39800000, v4
	v_mul_f32_e32 v4, 0.5, v4
	v_sin_f32_e32 v109, v4
	v_cos_f32_e32 v108, v4
	v_add_u32_e32 v4, s29, v1
	s_waitcnt lgkmcnt(4)
	v_pk_mov_b32 v[168:169], v[98:99], v[80:81] op_sel:[1,0]
	v_mul_f32_e32 v112, v109, v109
	v_mul_f32_e32 v1, v108, v109
	v_add_f32_e32 v110, v1, v1
	v_pk_fma_f32 v[112:113], v[108:109], v[108:109], v[112:113] op_sel_hi:[1,1,0] neg_lo:[0,0,1] neg_hi:[0,0,1]
	v_mov_b32_e32 v111, v109
	v_mov_b32_e32 v116, v112
	v_mov_b32_e32 v117, v108
	v_pk_mul_f32 v[120:121], v[110:111], v[110:111] op_sel_hi:[1,0]
	v_pk_mul_f32 v[132:133], v[110:111], v[112:113] op_sel_hi:[1,0]
	v_pk_fma_f32 v[128:129], v[116:117], v[112:113], v[120:121] op_sel_hi:[1,0,1] neg_lo:[0,0,1] neg_hi:[0,0,1]
	v_pk_fma_f32 v[134:135], v[116:117], v[110:111], v[132:133] op_sel_hi:[1,0,1]
	v_pk_mul_f32 v[118:119], v[116:117], v[112:113] op_sel_hi:[1,0]
	v_pk_mul_f32 v[130:131], v[116:117], v[110:111] op_sel_hi:[1,0]
	v_mul_f32_e32 v148, v134, v112
	v_mul_f32_e32 v149, v109, v128
	v_pk_mul_f32 v[152:153], v[128:129], v[134:135]
	v_mul_f32_e32 v144, v128, v110
	v_mul_f32_e32 v145, v108, v134
	v_pk_mul_f32 v[150:151], v[128:129], v[128:129]
	v_fma_f32 v140, v128, v110, v148
	v_fma_f32 v141, v108, v134, v149
	v_pk_mul_f32 v[142:143], v[134:135], v[134:135]
	v_pk_mul_f32 v[136:137], v[116:117], v[128:129] op_sel_hi:[1,0]
	v_pk_mul_f32 v[138:139], v[110:111], v[134:135] op_sel_hi:[1,0]
	v_mov_b32_e32 v151, v119
	v_mov_b32_e32 v143, v121
	v_pk_mul_f32 v[120:121], v[128:129], v[128:129] op_sel:[0,1] op_sel_hi:[1,0]
	v_add_f32_e32 v130, v152, v152
	v_add_f32_e32 v131, v131, v133
	v_pk_mul_f32 v[132:133], v[134:135], v[134:135] op_sel:[0,1] op_sel_hi:[1,0]
	v_pk_fma_f32 v[146:147], v[116:117], v[128:129], v[138:139] op_sel_hi:[1,0,1] neg_lo:[0,0,1] neg_hi:[0,0,1]
	v_pk_add_f32 v[118:119], v[150:151], v[142:143] neg_lo:[0,1] neg_hi:[0,1]
	v_mov_b32_e32 v151, v137
	v_mov_b32_e32 v143, v139
	v_sub_f32_e32 v136, v136, v138
	v_sub_f32_e32 v137, v150, v142
	v_sub_f32_e32 v120, v120, v132
	v_sub_f32_e32 v121, v150, v142
	v_pk_mul_f32 v[154:155], v[128:129], v[134:135] op_sel:[0,1] op_sel_hi:[1,0]
	v_pk_mul_f32 v[156:157], v[134:135], v[128:129] op_sel:[0,1] op_sel_hi:[1,0]
	v_pk_add_f32 v[158:159], v[150:151], v[142:143] neg_lo:[0,1] neg_hi:[0,1]
	v_add_f32_e32 v132, v144, v148
	v_add_f32_e32 v133, v152, v152
	v_add_f32_e32 v138, v152, v152
	v_add_f32_e32 v139, v145, v149
	v_mov_b32_e32 v149, v108
	v_add_f32_e32 v142, v154, v156
	v_add_f32_e32 v143, v152, v152
	v_mul_f32_e32 v108, v133, v112
	v_mul_f32_e32 v109, v109, v158
	v_fma_f32 v108, v158, v110, v108
	v_fma_f32 v109, v149, v133, v109
	v_pk_mov_b32 v[150:151], v[132:133], v[134:135] op_sel:[1,0]
	v_mul_f32_e32 v130, v128, v130
	v_mul_f32_e32 v131, v158, v131
	v_pk_mul_f32 v[152:153], v[150:151], v[142:143]
	v_pk_mul_f32 v[150:151], v[150:151], v[120:121]
	v_fma_f32 v118, v134, v118, v130
	v_fma_f32 v119, v133, v119, v131
	v_pk_mul_f32 v[130:131], v[132:133], v[140:141] op_sel:[1,0]
	v_pk_mul_f32 v[90:91], v[88:89], v[140:141]
	v_pk_mul_f32 v[140:141], v[164:165], v[140:141]
	v_pk_fma_f32 v[130:131], v[158:159], v[146:147], v[130:131] op_sel_hi:[0,1,1] neg_lo:[0,0,1] neg_hi:[0,0,1]
	v_pk_mul_f32 v[136:137], v[138:139], v[136:137]
	v_fma_f32 v138, v158, v120, -v152
	v_fma_f32 v139, v128, v121, -v153
	v_fma_f32 v148, v158, v142, v150
	v_fma_f32 v149, v128, v143, v151
	v_mov_b32_e32 v150, v84
	v_mov_b32_e32 v151, v83
	v_pk_mov_b32 v[82:83], v[84:85], v[82:83] op_sel:[1,0]
	v_mov_b32_e32 v156, v86
	v_pk_fma_f32 v[166:167], v[164:165], v[146:147], v[90:91] neg_lo:[0,0,1] neg_hi:[0,0,1]
	v_pk_fma_f32 v[90:91], v[164:165], v[146:147], v[90:91]
	v_pk_fma_f32 v[164:165], v[88:89], v[146:147], v[140:141] neg_lo:[0,0,1] neg_hi:[0,0,1]
	v_pk_fma_f32 v[88:89], v[88:89], v[146:147], v[140:141]
	v_mov_b32_e32 v147, v87
	v_pk_mov_b32 v[86:87], v[92:93], v[86:87] op_sel:[1,0]
	v_mov_b32_e32 v143, v134
	v_pk_mul_f32 v[144:145], v[110:111], v[132:133] op_sel:[0,1]
	v_pk_mul_f32 v[112:113], v[134:135], v[132:133] op_sel:[0,1]
	v_pk_mul_f32 v[84:85], v[82:83], v[110:111]
	v_pk_mul_f32 v[110:111], v[150:151], v[110:111]
	v_mov_b32_e32 v157, v79
	v_pk_mul_f32 v[160:161], v[160:161], v[134:135]
	v_mov_b32_e32 v146, v92
	v_mov_b32_e32 v121, v128
	v_pk_mul_f32 v[86:87], v[86:87], v[142:143]
	v_pk_fma_f32 v[144:145], v[116:117], v[158:159], v[144:145] op_sel_hi:[1,0,1] neg_lo:[0,0,1] neg_hi:[0,0,1]
	v_pk_fma_f32 v[112:113], v[128:129], v[158:159], v[112:113] op_sel_hi:[1,0,1] neg_lo:[0,0,1] neg_hi:[0,0,1]
	v_pk_fma_f32 v[152:153], v[150:151], v[116:117], v[84:85] neg_lo:[0,0,1] neg_hi:[0,0,1]
	v_pk_fma_f32 v[84:85], v[150:151], v[116:117], v[84:85]
	v_pk_fma_f32 v[150:151], v[82:83], v[116:117], v[110:111] neg_lo:[0,0,1] neg_hi:[0,0,1]
	v_pk_fma_f32 v[82:83], v[82:83], v[116:117], v[110:111]
	v_mov_b32_e32 v116, v129
	v_pk_fma_f32 v[162:163], v[156:157], v[128:129], v[160:161] neg_lo:[0,0,1] neg_hi:[0,0,1]
	v_pk_fma_f32 v[156:157], v[156:157], v[128:129], v[160:161]
	v_pk_fma_f32 v[128:129], v[146:147], v[120:121], v[86:87] neg_lo:[0,0,1] neg_hi:[0,0,1]
	v_pk_fma_f32 v[86:87], v[146:147], v[120:121], v[86:87]
	v_mov_b32_e32 v143, v120
	v_mov_b32_e32 v120, v96
	v_mov_b32_e32 v121, v95
	v_pk_mov_b32 v[94:95], v[96:97], v[94:95] op_sel:[1,0]
	v_pk_mul_f32 v[96:97], v[94:95], v[108:109]
	v_pk_mul_f32 v[108:109], v[120:121], v[108:109]
	v_pk_mul_f32 v[92:93], v[92:93], v[142:143]
	v_pk_fma_f32 v[142:143], v[120:121], v[144:145], v[96:97] neg_lo:[0,0,1] neg_hi:[0,0,1]
	v_pk_fma_f32 v[96:97], v[120:121], v[144:145], v[96:97]
	v_pk_fma_f32 v[120:121], v[94:95], v[144:145], v[108:109] neg_lo:[0,0,1] neg_hi:[0,0,1]
	v_pk_fma_f32 v[94:95], v[94:95], v[144:145], v[108:109]
	v_pk_mov_b32 v[146:147], v[112:113], v[158:159] op_sel:[1,0]
	v_mul_f32_e32 v168, v168, v119
	v_mul_f32_e32 v169, v169, v133
	v_pk_fma_f32 v[136:137], v[158:159], v[132:133], v[136:137]
	v_fma_f32 v170, v98, v146, -v168
	v_fma_f32 v171, v81, v147, -v169
	v_fma_f32 v144, v98, v146, v168
	v_fma_f32 v145, v81, v147, v169
	v_mov_b32_e32 v147, v99
	s_waitcnt lgkmcnt(3)
	v_pk_mov_b32 v[98:99], v[100:101], v[98:99] op_sel:[1,0]
	v_mov_b32_e32 v146, v100
	v_pk_mul_f32 v[98:99], v[98:99], v[118:119]
	v_mov_b32_e32 v117, v135
	v_pk_fma_f32 v[118:119], v[146:147], v[112:113], v[98:99] neg_lo:[0,0,1] neg_hi:[0,0,1]
	v_pk_fma_f32 v[98:99], v[146:147], v[112:113], v[98:99]
	s_waitcnt lgkmcnt(1)
	v_mov_b32_e32 v146, v104
	v_mov_b32_e32 v147, v103
	v_pk_mov_b32 v[102:103], v[104:105], v[102:103] op_sel:[1,0]
	v_pk_mul_f32 v[154:155], v[78:79], v[116:117]
	v_pk_mul_f32 v[104:105], v[102:103], v[136:137]
	v_pk_mul_f32 v[136:137], v[146:147], v[136:137]
	v_pk_fma_f32 v[168:169], v[146:147], v[130:131], v[104:105] neg_lo:[0,0,1] neg_hi:[0,0,1]
	v_pk_fma_f32 v[104:105], v[146:147], v[130:131], v[104:105]
	v_pk_fma_f32 v[146:147], v[102:103], v[130:131], v[136:137] neg_lo:[0,0,1] neg_hi:[0,0,1]
	v_pk_fma_f32 v[102:103], v[102:103], v[130:131], v[136:137]
	v_mov_b32_e32 v137, v101
	s_waitcnt lgkmcnt(0)
	v_pk_mov_b32 v[100:101], v[106:107], v[100:101] op_sel:[1,0]
	v_mov_b32_e32 v136, v106
	v_pk_mul_f32 v[100:101], v[100:101], v[148:149]
	v_pk_mov_b32 v[108:109], v[120:121], v[94:95] op_sel:[1,0]
	v_pk_fma_f32 v[172:173], v[136:137], v[138:139], v[100:101] neg_lo:[0,0,1] neg_hi:[0,0,1]
	v_mov_b32_e32 v113, v99
	v_pk_mov_b32 v[174:175], v[80:81], v[106:107] op_sel:[1,0]
	v_pk_mov_b32 v[132:133], v[132:133], v[148:149] op_sel:[1,0]
	v_mov_b32_e32 v104, v121
	v_pk_mov_b32 v[120:121], v[156:157], v[128:129] op_sel:[1,0]
	v_pk_mov_b32 v[98:99], v[98:99], v[172:173] op_sel:[1,0]
	v_pk_mul_f32 v[132:133], v[174:175], v[132:133]
	v_mov_b32_e32 v81, v107
	v_mov_b32_e32 v159, v138
	v_pk_add_f32 v[98:99], v[120:121], v[98:99] neg_lo:[0,1] neg_hi:[0,1]
	v_mov_b32_e32 v120, v154
	v_mov_b32_e32 v121, v92
	v_mov_b32_e32 v92, v155
	v_pk_fma_f32 v[100:101], v[136:137], v[138:139], v[100:101]
	v_pk_fma_f32 v[106:107], v[80:81], v[158:159], v[132:133] neg_lo:[0,0,1] neg_hi:[0,0,1]
	v_pk_fma_f32 v[80:81], v[80:81], v[158:159], v[132:133]
	v_pk_fma_f32 v[78:79], v[78:79], v[116:117], v[92:93] neg_lo:[0,0,1] neg_hi:[0,0,1]
	v_pk_add_f32 v[92:93], v[120:121], v[92:93]
	v_mov_b32_e32 v153, v85
	v_pk_mov_b32 v[110:111], v[150:151], v[82:83] op_sel:[1,0]
	v_mov_b32_e32 v160, v162
	v_mov_b32_e32 v161, v157
	v_mov_b32_e32 v167, v91
	v_pk_mov_b32 v[140:141], v[164:165], v[88:89] op_sel:[1,0]
	v_mov_b32_e32 v143, v97
	v_mov_b32_e32 v112, v118
	v_mov_b32_e32 v169, v105
	v_pk_mov_b32 v[130:131], v[146:147], v[102:103] op_sel:[1,0]
	v_mov_b32_e32 v90, v151
	v_pk_add_f32 v[112:113], v[160:161], v[112:113]
	v_add_f32_e32 v132, v128, v172
	v_add_f32_e32 v133, v87, v101
	v_mov_b32_e32 v146, v97
	v_pk_add_f32 v[90:91], v[90:91], v[104:105] neg_lo:[0,1] neg_hi:[0,1]
	v_pk_add_f32 v[96:97], v[110:111], v[108:109]
	v_pk_add_f32 v[104:105], v[140:141], v[130:131]
	v_pk_add_f32 v[108:109], v[152:153], v[142:143]
	v_pk_add_f32 v[110:111], v[166:167], v[168:169]
	v_mov_b32_e32 v79, v93
	v_add_f32_e32 v92, v2, v106
	v_add_f32_e32 v93, v93, v81
	v_add_f32_e32 v116, v78, v170
	v_add_f32_e32 v117, v3, v145
	v_sub_f32_e32 v82, v82, v94
	v_sub_f32_e32 v83, v166, v168
	v_mov_b32_e32 v143, v102
	v_pk_add_f32 v[94:95], v[108:109], v[110:111]
	v_pk_add_f32 v[102:103], v[96:97], v[104:105]
	v_mov_b32_e32 v171, v81
	v_pk_add_f32 v[80:81], v[116:117], v[132:133]
	v_pk_add_f32 v[120:121], v[112:113], v[92:93]
	v_mov_b32_e32 v153, v88
	v_pk_add_f32 v[138:139], v[102:103], v[80:81]
	v_pk_add_f32 v[140:141], v[94:95], v[120:121]
	v_mov_b32_e32 v164, v85
	v_pk_add_f32 v[88:89], v[152:153], v[142:143] neg_lo:[0,1] neg_hi:[0,1]
	v_add_f32_e32 v5, v82, v83
	v_pk_add_f32 v[142:143], v[140:141], v[138:139]
	v_pk_add_f32 v[84:85], v[164:165], v[146:147] neg_lo:[0,1] neg_hi:[0,1]
	v_mul_f32_e32 v129, 0x3f3504f3, v5
	v_pk_mul_f32 v[142:143], v[142:143], s[84:85] op_sel_hi:[1,0]
	v_ashrrev_i32_e32 v5, 31, v4
	v_pk_add_f32 v[78:79], v[78:79], v[170:171] neg_lo:[0,1] neg_hi:[0,1]
	v_cvt_pk_bf16_f32 v107, v142, v143
	v_lshl_add_u64 v[4:5], v[4:5], 2, s[94:95]
	v_pk_mov_b32 v[100:101], v[100:101], v[118:119] op_sel:[1,0]
	v_pk_add_f32 v[118:119], v[84:85], v[84:85] op_sel:[0,1] op_sel_hi:[0,1]
	v_mov_b32_e32 v131, v98
	v_mov_b32_e32 v135, v99
	global_store_dword v[4:5], v107, off
	v_mov_b32_e32 v107, v145
	v_pk_mov_b32 v[86:87], v[86:87], v[162:163] op_sel:[1,0]
	v_pk_mul_f32 v[118:119], v[118:119], s[38:39]
	v_pk_add_f32 v[142:143], v[90:91], v[90:91] op_sel:[0,1] op_sel_hi:[0,1] neg_lo:[0,1] neg_hi:[0,1]
	v_pk_add_f32 v[98:99], v[98:99], v[98:99] op_sel:[0,1] op_sel_hi:[0,1]
	v_sub_f32_e32 v1, v88, v89
	v_add_f32_e32 v136, v78, v79
	v_add_f32_e32 v137, v131, v135
	v_sub_f32_e32 v130, v78, v79
	v_sub_f32_e32 v131, v131, v135
	v_pk_add_f32 v[2:3], v[2:3], v[106:107] neg_lo:[0,1] neg_hi:[0,1]
	v_pk_add_f32 v[86:87], v[86:87], v[100:101] neg_lo:[0,1] neg_hi:[0,1]
	v_pk_fma_f32 v[144:145], v[142:143], s[40:41], v[118:119] neg_lo:[0,0,1] neg_hi:[0,0,1]
	v_pk_fma_f32 v[118:119], v[142:143], s[40:41], v[118:119]
	v_pk_mul_f32 v[98:99], v[98:99], s[40:41]
	v_pk_add_f32 v[78:79], v[78:79], v[78:79] op_sel:[0,1] op_sel_hi:[0,1] neg_lo:[0,1] neg_hi:[0,1]
	v_mul_f32_e32 v115, 0x3f3504f3, v1
	v_mov_b32_e32 v137, v131
	v_mul_f32_e32 v128, 0x3f6c835e, v131
	v_pk_add_f32 v[100:101], v[2:3], v[86:87] neg_lo:[0,1] neg_hi:[0,1]
	v_pk_add_f32 v[106:107], v[2:3], v[86:87]
	v_mov_b32_e32 v145, v119
	v_pk_fma_f32 v[118:119], v[78:79], s[38:39], v[98:99] neg_lo:[0,0,1] neg_hi:[0,0,1]
	v_pk_fma_f32 v[78:79], v[78:79], s[38:39], v[98:99]
	v_pk_fma_f32 v[134:135], v[136:137], s[80:81], v[128:129] op_sel_hi:[1,1,0] neg_lo:[0,0,1] neg_hi:[0,0,1]
	v_mov_b32_e32 v101, v107
	v_sub_f32_e32 v128, v115, v129
	v_fmac_f32_e32 v129, 0x3f3504f3, v1
	v_mov_b32_e32 v119, v79
	v_pk_add_f32 v[78:79], v[100:101], v[128:129]
	v_pk_add_f32 v[98:99], v[144:145], v[118:119]
	v_mov_b32_e32 v146, v112
	v_pk_add_f32 v[142:143], v[78:79], v[98:99]
	v_pk_mul_f32 v[142:143], v[142:143], s[84:85] op_sel_hi:[1,0]
	v_cvt_pk_bf16_f32 v1, v142, v143
	v_mov_b32_e32 v142, v92
	v_sub_f32_e32 v142, v142, v146
	v_sub_f32_e32 v143, v108, v110
	v_mov_b32_e32 v146, v97
	v_mov_b32_e32 v148, v105
	v_sub_f32_e32 v92, v109, v111
	v_sub_f32_e32 v93, v113, v93
	v_mov_b32_e32 v147, v117
	v_mov_b32_e32 v149, v133
	v_sub_f32_e32 v96, v96, v104
	v_sub_f32_e32 v97, v116, v132
	v_pk_mul_f32 v[92:93], v[92:93], s[20:21] op_sel_hi:[1,0]
	v_pk_add_f32 v[146:147], v[146:147], v[148:149] neg_lo:[0,1] neg_hi:[0,1]
	v_pk_fma_f32 v[104:105], v[96:97], s[2:3], v[92:93] neg_lo:[0,0,1] neg_hi:[0,0,1]
	v_pk_fma_f32 v[108:109], v[96:97], s[2:3], v[92:93]
	v_pk_fma_f32 v[92:93], v[96:97], s[20:21], v[92:93] op_sel_hi:[1,0,1] neg_lo:[0,0,1] neg_hi:[0,0,1]
	v_pk_mov_b32 v[110:111], v[104:105], v[108:109] op_sel:[1,0]
	v_pk_add_f32 v[96:97], v[142:143], v[146:147] neg_lo:[0,1] neg_hi:[0,1]
	v_pk_add_f32 v[112:113], v[142:143], v[146:147]
	v_pk_add_f32 v[110:111], v[92:93], v[110:111]
	v_mov_b32_e32 v97, v113
	v_pk_add_f32 v[116:117], v[96:97], v[110:111]
	global_store_dword v[4:5], v1, off offset:1024
	v_pk_mul_f32 v[116:117], v[116:117], s[84:85] op_sel_hi:[1,0]
	v_cvt_pk_bf16_f32 v1, v116, v117
	v_mov_b32_e32 v117, v90
	v_add_f32_e32 v88, v88, v89
	v_add_f32_e32 v89, v117, v91
	v_mov_b32_e32 v91, v84
	v_sub_f32_e32 v82, v82, v83
	v_sub_f32_e32 v83, v91, v85
	v_mul_f32_e32 v2, 0x3ec3ef15, v89
	v_pk_mul_f32 v[84:85], v[82:83], s[70:71]
	v_mov_b32_e32 v137, v82
	v_mul_f32_e32 v86, 0x3f6c835e, v83
	v_pk_mul_f32 v[82:83], v[136:137], s[74:75]
	v_pk_fma_f32 v[90:91], v[88:89], s[42:43], v[84:85] neg_lo:[0,0,1] neg_hi:[0,0,1]
	v_pk_fma_f32 v[84:85], v[88:89], s[42:43], v[84:85]
	v_pk_mov_b32 v[88:89], v[130:131], v[88:89] op_sel:[1,0]
	v_pk_fma_f32 v[82:83], v[88:89], s[72:73], v[82:83] neg_lo:[0,0,1] neg_hi:[0,0,1]
	v_pk_add_f32 v[2:3], v[2:3], v[86:87] neg_lo:[0,1] neg_hi:[0,1]
	v_add_f32_e32 v86, v90, v106
	v_add_f32_e32 v87, v85, v134
	v_pk_add_f32 v[88:89], v[2:3], v[82:83]
	global_store_dword v[4:5], v1, off offset:2048
	v_pk_add_f32 v[116:117], v[88:89], v[86:87]
	v_mov_b32_e32 v130, v94
	v_pk_mul_f32 v[116:117], v[116:117], s[84:85] op_sel_hi:[1,0]
	v_mov_b32_e32 v131, v80
	v_cvt_pk_bf16_f32 v1, v116, v117
	v_mov_b32_e32 v116, v120
	v_mov_b32_e32 v117, v102
	v_pk_add_f32 v[116:117], v[116:117], v[130:131] neg_lo:[0,1] neg_hi:[0,1]
	v_sub_f32_e32 v80, v95, v121
	v_sub_f32_e32 v81, v81, v103
	global_store_dword v[4:5], v1, off offset:3072
	v_pk_add_f32 v[94:95], v[116:117], v[80:81] neg_lo:[0,1] neg_hi:[0,1]
	v_pk_add_f32 v[102:103], v[116:117], v[80:81]
	v_sub_f32_e32 v1, v81, v117
	v_mov_b32_e32 v95, v103
	v_pk_mul_f32 v[80:81], v[94:95], s[84:85] op_sel_hi:[1,0]
	s_movk_i32 s2, 0x1000
	v_cvt_pk_bf16_f32 v91, v80, v81
	v_add_co_u32_e32 v80, vcc, s2, v4
	v_pk_add_f32 v[100:101], v[100:101], v[128:129] neg_lo:[0,1] neg_hi:[0,1]
	v_pk_add_f32 v[116:117], v[144:145], v[118:119] neg_lo:[0,1] neg_hi:[0,1]
	v_addc_co_u32_e32 v81, vcc, 0, v5, vcc
	v_pk_add_f32 v[118:119], v[100:101], v[116:117] op_sel:[0,1] op_sel_hi:[1,0] neg_lo:[0,1] neg_hi:[0,1]
	v_pk_add_f32 v[100:101], v[100:101], v[116:117] op_sel:[0,1] op_sel_hi:[1,0]
	v_add_co_u32_e32 v94, vcc, s27, v4
	s_nop 0
	s_nop 0
	v_addc_co_u32_e32 v95, vcc, 0, v5, vcc
	v_mul_f32_e32 v116, s84, v118
	v_mul_f32_e32 v117, s84, v101
	global_store_dword v[94:95], v91, off offset:-4096
	v_cvt_pk_bf16_f32 v91, v116, v117
	v_pk_add_f32 v[116:117], v[146:147], v[142:143] neg_lo:[0,1] neg_hi:[0,1]
	v_mov_b32_e32 v109, v92
	v_mov_b32_e32 v104, v93
	v_mov_b32_e32 v113, v117
	v_pk_add_f32 v[92:93], v[108:109], v[104:105] neg_lo:[0,1] neg_hi:[0,1]
	global_store_dword v[80:81], v91, off offset:1024
	v_pk_add_f32 v[104:105], v[112:113], v[92:93] neg_lo:[0,1] neg_hi:[0,1]
	v_pk_add_f32 v[92:93], v[112:113], v[92:93]
	v_mul_f32_e32 v108, s84, v104
	v_mul_f32_e32 v109, s84, v93
	v_pk_mov_b32 v[84:85], v[84:85], v[2:3] op_sel:[1,0]
	v_cvt_pk_bf16_f32 v91, v108, v109
	global_store_dword v[80:81], v91, off offset:2048
	v_mov_b32_e32 v135, v82
	v_mov_b32_e32 v107, v3
	v_mov_b32_e32 v91, v83
	v_pk_add_f32 v[84:85], v[84:85], v[134:135] neg_lo:[0,1] neg_hi:[0,1]
	v_pk_add_f32 v[2:3], v[106:107], v[90:91] neg_lo:[0,1] neg_hi:[0,1]
	v_pk_add_f32 v[78:79], v[78:79], v[98:99] neg_lo:[0,1] neg_hi:[0,1]
	v_pk_add_f32 v[82:83], v[2:3], v[84:85] neg_lo:[0,1] neg_hi:[0,1]
	v_pk_add_f32 v[2:3], v[2:3], v[84:85]
	v_mul_f32_e32 v84, s84, v82
	v_mul_f32_e32 v85, s84, v3
	v_pk_mul_f32 v[78:79], v[78:79], s[84:85] op_sel_hi:[1,0]
	v_cvt_pk_bf16_f32 v3, v84, v85
	global_store_dword v[80:81], v3, off offset:3072
	v_mov_b32_e32 v80, v140
	v_mov_b32_e32 v81, v139
	v_mov_b32_e32 v139, v141
	v_pk_add_f32 v[80:81], v[80:81], v[138:139] neg_lo:[0,1] neg_hi:[0,1]
	v_mul_f32_e32 v1, 0x39000000, v1
	v_pk_mul_f32 v[80:81], v[80:81], s[84:85] op_sel_hi:[1,0]
	v_add_co_u32_e32 v4, vcc, s86, v4
	v_cvt_pk_bf16_f32 v3, v80, v81
	global_store_dword v[94:95], v3, off
	v_cvt_pk_bf16_f32 v3, v78, v79
	v_pk_add_f32 v[78:79], v[96:97], v[110:111] neg_lo:[0,1] neg_hi:[0,1]
	global_store_dword v[94:95], v3, off offset:1024
	v_pk_mul_f32 v[78:79], v[78:79], s[84:85] op_sel_hi:[1,0]
	v_addc_co_u32_e32 v5, vcc, 0, v5, vcc
	v_cvt_pk_bf16_f32 v3, v78, v79
	v_mov_b32_e32 v78, v86
	v_mov_b32_e32 v79, v89
	v_mov_b32_e32 v89, v87
	v_pk_add_f32 v[78:79], v[78:79], v[88:89] neg_lo:[0,1] neg_hi:[0,1]
	global_store_dword v[94:95], v3, off offset:2048
	v_pk_mul_f32 v[78:79], v[78:79], s[84:85] op_sel_hi:[1,0]
	s_addk_i32 s29, 0x1000
	v_cvt_pk_bf16_f32 v3, v78, v79
	global_store_dword v[94:95], v3, off offset:3072
	v_mul_f32_e32 v3, 0x39000000, v102
	v_cvt_pk_bf16_f32 v1, v3, v1
	global_store_dword v[4:5], v1, off
	v_mul_f32_e32 v1, 0x39000000, v100
	v_mul_f32_e32 v3, 0x39000000, v119
	v_cvt_pk_bf16_f32 v1, v1, v3
	global_store_dword v[4:5], v1, off offset:1024
	v_mul_f32_e32 v1, 0x39000000, v92
	v_mul_f32_e32 v3, 0x39000000, v105
	v_cvt_pk_bf16_f32 v1, v1, v3
	s_add_u32 s0, s0, 0x4000
	global_store_dword v[4:5], v1, off offset:2048
	v_mul_f32_e32 v1, 0x39000000, v2
	v_mul_f32_e32 v2, 0x39000000, v83
	s_addc_u32 s1, s1, 0
	v_cvt_pk_bf16_f32 v1, v1, v2
	s_cmp_eq_u32 s0, 0x10000
	global_store_dword v[4:5], v1, off offset:3072
	s_cbranch_scc1 .LBB0_412

.LBB0_444:
	s_or_b64 exec, exec, s[22:23]
	v_cvt_f32_u32_e32 v40, v40
	v_cndmask_b32_e64 v60, 0, v114, s[62:63]
	s_waitcnt vmcnt(1)
	v_fmac_f32_e32 v60, v1, v25
	v_cndmask_b32_e64 v71, 0, v114, s[64:65]
	v_mul_f32_e32 v40, 0x39800000, v40
	v_mul_f32_e32 v40, 0.5, v40
	v_sin_f32_e32 v59, v40
	v_cos_f32_e32 v58, v40
	v_cvt_f32_u32_e32 v40, v24
	v_sub_f32_e32 v24, v60, v57
	s_waitcnt vmcnt(0)
	v_fmac_f32_e32 v71, v1, v37
	v_pk_mul_f32 v[24:25], v[58:59], v[24:25] op_sel_hi:[1,0] neg_hi:[0,1]
	v_mul_f32_e32 v40, 0x39800000, v40
	v_mul_f32_e32 v40, 0.5, v40
	v_sin_f32_e32 v59, v40
	v_cos_f32_e32 v58, v40
	v_cvt_f32_u32_e32 v40, v26
	v_cndmask_b32_e64 v37, 0, v114, s[60:61]
	v_fmac_f32_e32 v37, v1, v56
	v_sub_f32_e32 v26, v37, v27
	v_mul_f32_e32 v40, 0x39800000, v40
	v_mul_f32_e32 v40, 0.5, v40
	v_sin_f32_e32 v57, v40
	v_cos_f32_e32 v56, v40
	v_cvt_f32_u32_e32 v40, v38
	v_cndmask_b32_e64 v37, 0, v114, s[58:59]
	v_fmac_f32_e32 v37, v1, v39
	v_sub_f32_e32 v38, v37, v55
	v_mul_f32_e32 v40, 0x39800000, v40
	v_mul_f32_e32 v40, 0.5, v40
	v_pk_mul_f32 v[38:39], v[56:57], v[38:39] op_sel_hi:[1,0] neg_hi:[0,1]
	v_sin_f32_e32 v57, v40
	v_cos_f32_e32 v56, v40
	v_cvt_f32_u32_e32 v40, v30
	v_cndmask_b32_e64 v37, 0, v114, s[56:57]
	v_fmac_f32_e32 v37, v1, v54
	v_sub_f32_e32 v30, v37, v31
	v_mul_f32_e32 v40, 0x39800000, v40
	v_mul_f32_e32 v40, 0.5, v40
	v_sin_f32_e32 v55, v40
	v_cos_f32_e32 v54, v40
	v_cvt_f32_u32_e32 v40, v32
	v_cndmask_b32_e64 v37, 0, v114, s[0:1]
	v_fmac_f32_e32 v37, v1, v33
	v_sub_f32_e32 v32, v37, v53
	v_mul_f32_e32 v40, 0x39800000, v40
	v_mul_f32_e32 v40, 0.5, v40
	v_pk_mul_f32 v[32:33], v[54:55], v[32:33] op_sel_hi:[1,0] neg_hi:[0,1]
	v_sin_f32_e32 v55, v40
	v_cos_f32_e32 v54, v40
	v_cvt_f32_u32_e32 v40, v34
	v_cndmask_b32_e64 v37, 0, v114, s[54:55]
	v_fmac_f32_e32 v37, v1, v52
	v_sub_f32_e32 v34, v37, v35
	v_mul_f32_e32 v40, 0x39800000, v40
	v_mul_f32_e32 v40, 0.5, v40
	v_sin_f32_e32 v53, v40
	v_cos_f32_e32 v52, v40
	v_cvt_f32_u32_e32 v40, v28
	v_cndmask_b32_e64 v37, 0, v114, s[52:53]
	v_fmac_f32_e32 v37, v1, v50
	v_sub_f32_e32 v28, v37, v51
	v_mul_f32_e32 v37, 0x39800000, v40
	v_pk_mul_f32 v[50:51], v[52:53], v[28:29] op_sel_hi:[1,0] neg_hi:[0,1]
	v_cndmask_b32_e64 v28, 0, v114, s[50:51]
	v_mul_f32_e32 v37, 0.5, v37
	v_sin_f32_e32 v53, v37
	v_cos_f32_e32 v52, v37
	v_fmac_f32_e32 v28, v1, v29
	v_cvt_f32_u32_e32 v29, v22
	v_cvt_f32_u32_e32 v16, v16
	v_sub_f32_e32 v28, v28, v23
	v_pk_mul_f32 v[34:35], v[54:55], v[34:35] op_sel_hi:[1,0] neg_hi:[0,1]
	v_pk_mul_f32 v[22:23], v[52:53], v[28:29] op_sel_hi:[1,0] neg_hi:[0,1]
	v_mul_f32_e32 v29, 0x39800000, v29
	v_mul_f32_e32 v29, 0.5, v29
	v_mul_f32_e32 v16, 0x39800000, v16
	v_sin_f32_e32 v55, v29
	v_cos_f32_e32 v54, v29
	v_cvt_f32_u32_e32 v18, v18
	v_mul_f32_e32 v16, 0.5, v16
	v_cndmask_b32_e64 v37, 0, v114, s[48:49]
	v_sin_f32_e32 v61, v16
	v_cos_f32_e32 v60, v16
	v_cvt_f32_u32_e32 v16, v14
	v_fmac_f32_e32 v37, v1, v48
	v_cvt_f32_u32_e32 v29, v20
	v_sub_f32_e32 v20, v37, v49
	v_cndmask_b32_e64 v37, 0, v114, s[46:47]
	v_pk_mul_f32 v[48:49], v[54:55], v[20:21] op_sel_hi:[1,0] neg_hi:[0,1]
	v_fmac_f32_e32 v37, v1, v21
	v_cndmask_b32_e64 v21, 0, v114, s[44:45]
	v_mul_f32_e32 v18, 0x39800000, v18
	v_fmac_f32_e32 v21, v1, v46
	v_mul_f32_e32 v18, 0.5, v18
	v_mul_f32_e32 v16, 0x39800000, v16
	v_sub_f32_e32 v40, v37, v47
	v_sin_f32_e32 v47, v18
	v_cos_f32_e32 v46, v18
	v_sub_f32_e32 v18, v21, v19
	v_cndmask_b32_e64 v19, 0, v114, s[42:43]
	v_mul_f32_e32 v16, 0.5, v16
	v_fmac_f32_e32 v19, v1, v17
	v_sin_f32_e32 v17, v16
	v_cos_f32_e32 v16, v16
	v_sub_f32_e32 v14, v19, v45
	v_cndmask_b32_e64 v19, 0, v114, s[40:41]
	v_cvt_f32_u32_e32 v2, v2
	v_fmac_f32_e32 v19, v1, v15
	v_pk_mul_f32 v[62:63], v[60:61], v[14:15] op_sel_hi:[1,0] neg_hi:[0,1]
	v_cvt_f32_u32_e32 v15, v4
	v_sub_f32_e32 v4, v19, v44
	v_cndmask_b32_e64 v19, 0, v114, s[38:39]
	v_pk_mul_f32 v[44:45], v[16:17], v[4:5] op_sel_hi:[1,0] neg_hi:[0,1]
	v_fmac_f32_e32 v19, v1, v5
	v_cndmask_b32_e32 v5, 0, v114, vcc
	v_fmac_f32_e32 v5, v1, v3
	v_mul_f32_e32 v1, 0x39800000, v2
	v_mul_f32_e32 v1, 0.5, v1
	v_sin_f32_e32 v69, v1
	v_cos_f32_e32 v68, v1
	v_cvt_f32_u32_e32 v1, v36
	v_mul_f32_e32 v15, 0x39800000, v15
	v_mul_f32_e32 v29, 0x39800000, v29
	v_mul_f32_e32 v15, 0.5, v15
	v_mul_f32_e32 v1, 0x39800000, v1
	v_mul_f32_e32 v1, 0.5, v1
	v_sin_f32_e32 v3, v1
	v_cos_f32_e32 v2, v1
	v_mov_b32_e32 v1, v122
	v_mul_f32_e32 v29, 0.5, v29
	v_sin_f32_e32 v65, v15
	v_cos_f32_e32 v64, v15
	s_barrier
	v_pk_mul_f32 v[30:31], v[56:57], v[30:31] op_sel_hi:[1,0] neg_hi:[0,1]
	v_ashrrev_i32_e32 v15, 31, v1
	v_sin_f32_e32 v57, v29
	v_cos_f32_e32 v56, v29
	v_lshrrev_b32_e32 v15, 24, v15
	v_sub_f32_e32 v70, v5, v43
	v_and_b32_e32 v5, 0xff, v1
	v_add_lshl_u32 v1, v1, v15, 4
	v_and_or_b32 v1, v1, s87, v5
	v_pk_mul_f32 v[26:27], v[58:59], v[26:27] op_sel_hi:[1,0] neg_hi:[0,1]
	v_ashrrev_i32_e32 v15, 4, v1
	v_lshlrev_b32_e32 v1, 3, v1
	v_pk_mul_f32 v[58:59], v[56:57], v[40:41] op_sel_hi:[1,0] neg_hi:[0,1]
	v_sub_f32_e32 v36, v71, v41
	v_lshl_add_u32 v1, v15, 3, v1
	v_pk_fma_f32 v[40:41], v[56:57], v[40:41], v[26:27] op_sel_hi:[1,0,1] neg_hi:[0,1,0]
	v_pk_fma_f32 v[56:57], v[16:17], v[4:5], v[32:33] op_sel_hi:[1,0,1] neg_hi:[0,1,0]
	v_sub_f32_e32 v42, v19, v42
	v_cvt_f32_i32_e32 v15, v5
	v_pk_mul_f32 v[66:67], v[64:65], v[42:43] op_sel_hi:[1,0] neg_hi:[0,1]
	v_pk_fma_f32 v[42:43], v[64:65], v[42:43], v[34:35] op_sel_hi:[1,0,1] neg_hi:[0,1,0]
	v_pk_mul_f32 v[36:37], v[2:3], v[36:37] op_sel_hi:[1,0] neg_hi:[0,1]
	v_pk_fma_f32 v[60:61], v[60:61], v[14:15], v[30:31] op_sel_hi:[1,0,1] neg_hi:[0,1,0]
	v_add_f32_e32 v14, v15, v15
	v_pk_add_f32 v[4:5], v[42:43], v[40:41] neg_lo:[0,1] neg_hi:[0,1]
	v_mul_f32_e32 v14, 0x39800000, v14
	v_pk_fma_f32 v[72:73], v[68:69], v[70:71], v[50:51] op_sel_hi:[1,0,1] neg_hi:[0,1,0]
	v_pk_fma_f32 v[74:75], v[46:47], v[18:19], v[38:39] op_sel_hi:[1,0,1] neg_hi:[0,1,0]
	v_pk_fma_f32 v[20:21], v[54:55], v[20:21], v[24:25] op_sel_hi:[1,0,1] neg_hi:[0,1,0]
	v_mul_f32_e32 v14, 0.5, v14
	v_pk_mul_f32 v[76:77], v[4:5], s[20:21] op_sel_hi:[1,0]
	v_pk_fma_f32 v[28:29], v[52:53], v[28:29], v[36:37] op_sel_hi:[1,0,1] neg_hi:[0,1,0]
	v_sin_f32_e32 v64, v14
	v_pk_fma_f32 v[78:79], v[4:5], s[20:21], v[76:77] op_sel:[0,0,1] op_sel_hi:[1,0,0]
	v_cos_f32_e32 v80, v14
	v_pk_add_f32 v[2:3], v[72:73], v[74:75]
	v_pk_add_f32 v[4:5], v[42:43], v[40:41]
	v_pk_add_f32 v[14:15], v[56:57], v[20:21]
	v_pk_add_f32 v[16:17], v[60:61], v[28:29]
	v_pk_add_f32 v[28:29], v[60:61], v[28:29] neg_lo:[0,1] neg_hi:[0,1]
	v_pk_add_f32 v[40:41], v[2:3], v[14:15]
	v_mul_f32_e32 v19, 0x3f3504f3, v28
	v_pk_add_f32 v[42:43], v[4:5], v[16:17]
	v_pk_fma_f32 v[50:51], v[68:69], v[70:71], v[50:51] op_sel_hi:[1,0,1] neg_lo:[0,0,1] neg_hi:[0,1,1]
	v_pk_add_f32 v[52:53], v[40:41], v[42:43]
	v_pk_fma_f32 v[38:39], v[46:47], v[18:19], v[38:39] op_sel_hi:[1,0,1] neg_lo:[0,0,1] neg_hi:[0,1,1]
	ds_write_b64 v1, v[52:53]
	v_pk_mov_b32 v[46:47], v[38:39], v[38:39] op_sel:[1,0]
	v_pk_add_f32 v[52:53], v[50:51], v[38:39] op_sel:[0,1] op_sel_hi:[1,0]
	v_pk_add_f32 v[38:39], v[50:51], v[38:39] op_sel:[0,1] op_sel_hi:[1,0] neg_lo:[0,1] neg_hi:[0,1]
	v_pk_add_f32 v[54:55], v[56:57], v[20:21] neg_lo:[0,1] neg_hi:[0,1]
	v_mul_f32_e32 v20, 0x3f3504f3, v29
	v_mul_f32_e32 v29, 0xbf3504f3, v29
	v_mov_b32_e32 v53, v39
	v_mov_b32_e32 v60, v74
	v_mov_b32_e32 v28, v57
	v_mov_b32_e32 v18, v21
	v_sub_f32_e32 v38, v72, v60
	v_sub_f32_e32 v39, v77, v76
	v_pk_add_f32 v[28:29], v[28:29], v[18:19] neg_lo:[0,1] neg_hi:[0,1]
	v_sub_f32_e32 v18, v20, v19
	v_sub_f32_e32 v19, v73, v75
	v_mov_b32_e32 v20, v78
	v_mov_b32_e32 v21, v54
	v_pk_add_f32 v[56:57], v[18:19], v[54:55] op_sel:[1,0] op_sel_hi:[0,1]
	v_pk_add_f32 v[54:55], v[18:19], v[20:21]
	v_pk_add_f32 v[60:61], v[18:19], v[20:21] neg_lo:[0,1] neg_hi:[0,1]
	v_pk_add_f32 v[68:69], v[38:39], v[28:29]
	v_pk_add_f32 v[20:21], v[38:39], v[28:29] neg_lo:[0,1] neg_hi:[0,1]
	v_mov_b32_e32 v39, v66
	v_mov_b32_e32 v73, v34
	v_sub_f32_e32 v38, v44, v32
	v_sub_f32_e32 v39, v39, v73
	v_mov_b32_e32 v73, v59
	v_sub_f32_e32 v34, v45, v33
	v_sub_f32_e32 v35, v67, v35
	v_mov_b32_e32 v67, v58
	v_mov_b32_e32 v75, v27
	v_sub_f32_e32 v27, v67, v26
	v_sub_f32_e32 v26, v48, v24
	v_pk_mov_b32 v[58:59], v[62:63], v[44:45] op_sel:[1,0]
	v_pk_mov_b32 v[66:67], v[30:31], v[32:33] op_sel:[1,0]
	v_sub_f32_e32 v72, v49, v25
	v_sub_f32_e32 v73, v73, v75
	v_pk_add_f32 v[58:59], v[58:59], v[66:67] neg_lo:[0,1] neg_hi:[0,1]
	v_mov_b32_e32 v66, v22
	v_mov_b32_e32 v75, v25
	v_pk_mov_b32 v[22:23], v[22:23], v[48:49] op_sel:[1,0]
	v_pk_mov_b32 v[24:25], v[36:37], v[24:25] op_sel:[1,0]
	s_and_b64 s[0:1], s[96:97], exec
	s_nop 0
	s_nop 0
	v_sub_f32_e32 v30, v62, v30
	v_sub_f32_e32 v31, v45, v33
	v_pk_add_f32 v[22:23], v[22:23], v[24:25] neg_lo:[0,1] neg_hi:[0,1]
	v_readlane_b32 s0, v244, 15
	v_sub_f32_e32 v66, v66, v36
	v_sub_f32_e32 v67, v49, v75
	v_pk_add_f32 v[32:33], v[30:31], v[22:23] neg_lo:[0,1] neg_hi:[0,1]
	s_cselect_b32 s41, s88, s0
	v_readlane_b32 s0, v244, 13
	v_pk_add_f32 v[74:75], v[58:59], v[66:67]
	v_mov_b32_e32 v62, v32
	v_mul_f32_e32 v32, 0x3ec3ef15, v32
	s_cselect_b32 s40, s24, s0
	v_pk_add_f32 v[24:25], v[38:39], v[72:73] neg_lo:[0,1] neg_hi:[0,1]
	v_pk_add_f32 v[36:37], v[34:35], v[26:27]
	v_pk_add_f32 v[30:31], v[30:31], v[22:23]
	v_mul_f32_e32 v26, 0x3f6c835e, v74
	v_mov_b32_e32 v49, v51
	v_mov_b32_e32 v51, v32
	s_mov_b32 s0, s71
	s_mov_b32 s1, s21
	v_add_f32_e32 v32, v39, v73
	s_mov_b32 s22, s21
	s_mov_b32 s23, s71
	v_mov_b32_e32 v55, v61
	v_pk_add_f32 v[70:71], v[78:79], v[18:19] neg_lo:[0,1] neg_hi:[0,1]
	v_mul_f32_e32 v44, 0x3ec3ef15, v25
	v_mul_f32_e32 v48, 0x3f6c835e, v37
	v_pk_add_f32 v[58:59], v[58:59], v[66:67] neg_lo:[0,1] neg_hi:[0,1]
	v_pk_mul_f32 v[24:25], v[24:25], s[20:21]
	v_mov_b32_e32 v63, v31
	s_mov_b32 s70, s20
	v_mov_b32_e32 v45, v47
	v_mov_b32_e32 v47, v26
	v_sub_f32_e32 v26, v35, v27
	v_pk_mul_f32 v[34:35], v[32:33], s[22:23] op_sel_hi:[0,1]
	v_pk_mul_f32 v[30:31], v[30:31], s[0:1] op_sel_hi:[0,1]
	v_pk_add_f32 v[28:29], v[68:69], v[54:55]
	v_pk_add_f32 v[18:19], v[56:57], v[70:71]
	v_mul_f32_e32 v55, 0x3f3504f3, v75
	v_mul_f32_e32 v57, 0x3f3504f3, v33
	v_pk_fma_f32 v[22:23], v[36:37], s[70:71], v[24:25] neg_lo:[0,0,1] neg_hi:[0,0,1]
	v_pk_add_f32 v[36:37], v[48:49], v[44:45]
	v_pk_fma_f32 v[38:39], v[26:27], s[0:1], v[34:35] op_sel_hi:[0,1,1]
	v_pk_fma_f32 v[26:27], v[26:27], s[0:1], v[34:35] op_sel_hi:[0,1,1] neg_lo:[0,0,1] neg_hi:[0,0,1]
	v_pk_fma_f32 v[48:49], v[58:59], s[22:23], v[30:31]
	v_pk_fma_f32 v[30:31], v[58:59], s[22:23], v[30:31] op_sel_hi:[0,1,1] neg_lo:[0,0,1] neg_hi:[0,0,1]
	v_mov_b32_e32 v39, v27
	v_add_f32_e32 v26, v57, v55
	v_fma_f32 v27, v33, s20, -v55
	v_mov_b32_e32 v49, v31
	v_pk_add_f32 v[32:33], v[52:53], v[26:27]
	v_pk_add_f32 v[30:31], v[38:39], v[48:49]
	v_mov_b32_e32 v75, v59
	v_pk_add_f32 v[44:45], v[50:51], v[46:47] neg_lo:[0,1] neg_hi:[0,1]
	v_pk_add_f32 v[50:51], v[32:33], v[30:31]
	v_xor_b32_e32 v81, 0x80000000, v64
	v_pk_mul_f32 v[66:67], v[74:75], s[72:73]
	v_pk_mul_f32 v[58:59], v[50:51], v[64:65] op_sel_hi:[1,0]
	v_pk_fma_f32 v[24:25], v[62:63], s[30:31], v[66:67] neg_lo:[0,0,1] neg_hi:[0,0,1]
	v_pk_fma_f32 v[62:63], v[50:51], v[80:81], v[58:59] op_sel:[0,0,1] op_sel_hi:[1,1,0]
	v_pk_fma_f32 v[50:51], v[50:51], v[80:81], v[58:59] op_sel:[0,0,1] op_sel_hi:[1,0,0] neg_lo:[0,0,1] neg_hi:[0,0,1]
	v_mov_b32_e32 v65, v80
	v_mov_b32_e32 v63, v51
	v_mul_f32_e32 v50, v64, v64
	v_mul_f32_e32 v51, v65, v81
	ds_write_b64 v1, v[62:63] offset:2176
	v_pk_fma_f32 v[58:59], v[80:81], v[80:81], v[50:51] op_sel_hi:[0,1,1] neg_lo:[0,0,1] neg_hi:[0,0,1]
	v_pk_fma_f32 v[50:51], v[80:81], v[80:81], v[50:51] op_sel_hi:[0,1,1]
	v_pk_mov_b32 v[74:75], v[50:51], v[58:59] op_sel:[1,0]
	v_mov_b32_e32 v62, v58
	v_mov_b32_e32 v63, v51
	v_pk_mul_f32 v[74:75], v[50:51], v[74:75] op_sel:[1,0]
	v_pk_mul_f32 v[50:51], v[28:29], v[50:51] op_sel:[1,1] op_sel_hi:[0,1]
	v_pk_fma_f32 v[76:77], v[58:59], v[62:63], v[74:75] op_sel_hi:[0,1,1] neg_lo:[0,0,1] neg_hi:[0,0,1]
	v_pk_fma_f32 v[74:75], v[58:59], v[62:63], v[74:75] op_sel_hi:[0,1,1]
	v_pk_fma_f32 v[88:89], v[28:29], v[58:59], v[50:51] neg_lo:[0,0,1] neg_hi:[0,0,1]
	v_pk_fma_f32 v[28:29], v[28:29], v[58:59], v[50:51] op_sel_hi:[1,0,1]
	v_pk_mul_f32 v[50:51], v[62:63], v[74:75] op_sel:[0,1]
	v_pk_add_f32 v[26:27], v[52:53], v[26:27] neg_lo:[0,1] neg_hi:[0,1]
	v_pk_fma_f32 v[52:53], v[62:63], v[76:77], v[50:51] op_sel:[0,0,1] op_sel_hi:[1,0,0] neg_lo:[0,0,1] neg_hi:[0,0,1]
	v_pk_fma_f32 v[50:51], v[62:63], v[76:77], v[50:51] op_sel:[0,0,1] op_sel_hi:[1,0,0]
	v_mov_b32_e32 v89, v29
	v_mov_b32_e32 v59, v51
	v_sub_f32_e32 v56, v56, v70
	v_pk_mov_b32 v[50:51], v[50:51], v[52:53] op_sel:[1,0]
	v_mov_b32_e32 v78, v76
	v_mov_b32_e32 v79, v75
	ds_write_b64 v1, v[88:89] offset:4352
	v_mov_b32_e32 v58, v52
	v_pk_add_f32 v[88:89], v[20:21], v[20:21] op_sel:[0,1] op_sel_hi:[0,1]
	v_pk_mul_f32 v[50:51], v[56:57], v[50:51] op_sel_hi:[0,1]
	v_pk_fma_f32 v[52:53], v[88:89], v[52:53], v[50:51] neg_lo:[0,0,1] neg_hi:[0,0,1]
	v_pk_fma_f32 v[50:51], v[88:89], v[58:59], v[50:51]
	v_pk_add_f32 v[40:41], v[40:41], v[42:43] neg_lo:[0,1] neg_hi:[0,1]
	v_pk_mul_f32 v[42:43], v[78:79], v[74:75] op_sel:[0,1]
	v_mov_b32_e32 v53, v51
	v_pk_fma_f32 v[50:51], v[76:77], v[78:79], v[42:43] op_sel:[0,0,1] op_sel_hi:[0,1,0] neg_lo:[0,0,1] neg_hi:[0,0,1]
	v_pk_fma_f32 v[42:43], v[76:77], v[78:79], v[42:43] op_sel:[0,0,1] op_sel_hi:[0,1,0]
	v_pk_mov_b32 v[56:57], v[42:43], v[50:51] op_sel:[1,0]
	v_mov_b32_e32 v81, v64
	v_pk_mul_f32 v[72:73], v[64:65], v[62:63]
	v_pk_mul_f32 v[84:85], v[64:65], v[78:79]
	ds_write_b64 v1, v[52:53] offset:13056
	v_mov_b32_e32 v52, v50
	v_mov_b32_e32 v53, v43
	v_pk_mul_f32 v[64:65], v[64:65], v[56:57] op_sel_hi:[0,1]
	v_pk_fma_f32 v[70:71], v[80:81], v[52:53], v[64:65] op_sel_hi:[0,1,1]
	v_pk_fma_f32 v[64:65], v[80:81], v[52:53], v[64:65] op_sel_hi:[0,1,1] neg_lo:[0,0,1] neg_hi:[0,0,1]
	v_pk_add_f32 v[30:31], v[32:33], v[30:31] neg_lo:[0,1] neg_hi:[0,1]
	v_pk_mov_b32 v[86:87], v[74:75], v[76:77] op_sel:[1,0]
	v_mov_b32_e32 v75, v65
	v_pk_mov_b32 v[64:65], v[64:65], v[70:71] op_sel:[1,0]
	v_mov_b32_e32 v74, v70
	v_pk_mul_f32 v[64:65], v[30:31], v[64:65] op_sel:[1,0]
	v_pk_mul_f32 v[42:43], v[40:41], v[42:43] op_sel:[1,1] op_sel_hi:[0,1]
	v_pk_mul_f32 v[66:67], v[80:81], v[62:63]
	v_pk_mul_f32 v[82:83], v[80:81], v[78:79]
	v_pk_mul_f32 v[80:81], v[62:63], v[52:53]
	v_pk_mul_f32 v[62:63], v[62:63], v[56:57]
	v_pk_fma_f32 v[70:71], v[30:31], v[70:71], v[64:65] neg_lo:[0,0,1] neg_hi:[0,0,1]
	v_pk_fma_f32 v[30:31], v[30:31], v[74:75], v[64:65] op_sel_hi:[0,1,1]
	v_pk_fma_f32 v[64:65], v[40:41], v[50:51], v[42:43] neg_lo:[0,0,1] neg_hi:[0,0,1]
	v_pk_fma_f32 v[40:41], v[40:41], v[50:51], v[42:43] op_sel_hi:[1,0,1]
	v_pk_add_f32 v[34:35], v[22:23], v[44:45]
	v_pk_add_f32 v[46:47], v[36:37], v[24:25]
	v_mov_b32_e32 v88, v66
	v_mov_b32_e32 v89, v73
	v_pk_mov_b32 v[66:67], v[66:67], v[72:73] op_sel:[1,0]
	v_mov_b32_e32 v65, v41
	v_sub_f32_e32 v40, v68, v54
	v_sub_f32_e32 v41, v61, v69
	v_pk_add_f32 v[42:43], v[62:63], v[62:63] op_sel:[0,1] op_sel_hi:[0,1]
	v_pk_add_f32 v[32:33], v[46:47], v[34:35]
	v_pk_add_f32 v[72:73], v[88:89], v[66:67]
	v_pk_add_f32 v[66:67], v[88:89], v[66:67] neg_lo:[0,1] neg_hi:[0,1]
	v_pk_mul_f32 v[42:43], v[40:41], v[42:43] op_sel:[1,0] op_sel_hi:[0,1]
	v_pk_add_f32 v[50:51], v[80:81], v[80:81] op_sel:[0,1] op_sel_hi:[0,1] neg_lo:[0,1] neg_hi:[0,1]
	v_pk_mul_f32 v[90:91], v[32:33], v[66:67] op_sel:[0,1]
	v_pk_fma_f32 v[54:55], v[40:41], v[50:51], v[42:43] neg_lo:[0,0,1] neg_hi:[0,0,1]
	v_pk_fma_f32 v[40:41], v[40:41], v[50:51], v[42:43]
	v_pk_fma_f32 v[92:93], v[32:33], v[72:73], v[90:91] op_sel:[0,0,1] op_sel_hi:[1,1,0] neg_lo:[0,0,1] neg_hi:[0,0,1]
	v_pk_fma_f32 v[32:33], v[32:33], v[72:73], v[90:91] op_sel:[0,0,1] op_sel_hi:[1,0,0]
	v_mul_f32_e32 v90, v72, v52
	v_mul_f32_e32 v91, v67, v53
	v_mul_f32_e32 v88, v72, v56
	v_mul_f32_e32 v89, v67, v57
	v_mov_b32_e32 v55, v41
	v_mov_b32_e32 v41, v47
	v_sub_f32_e32 v34, v34, v46
	v_sub_f32_e32 v35, v41, v35
	v_pk_add_f32 v[40:41], v[88:89], v[88:89] op_sel:[0,1] op_sel_hi:[0,1]
	v_pk_add_f32 v[2:3], v[2:3], v[14:15] neg_lo:[0,1] neg_hi:[0,1]
	v_pk_add_f32 v[4:5], v[4:5], v[16:17] neg_lo:[0,1] neg_hi:[0,1]
	v_pk_mul_f32 v[40:41], v[34:35], v[40:41] op_sel:[1,0] op_sel_hi:[0,1]
	v_pk_add_f32 v[42:43], v[90:91], v[90:91] op_sel:[0,1] op_sel_hi:[0,1] neg_lo:[0,1] neg_hi:[0,1]
	v_pk_add_f32 v[14:15], v[2:3], v[4:5] op_sel:[0,1] op_sel_hi:[1,0]
	v_pk_add_f32 v[2:3], v[2:3], v[4:5] op_sel:[0,1] op_sel_hi:[1,0] neg_lo:[0,1] neg_hi:[0,1]
	v_pk_add_f32 v[28:29], v[38:39], v[48:49] neg_lo:[0,1] neg_hi:[0,1]
	v_pk_fma_f32 v[46:47], v[34:35], v[42:43], v[40:41] neg_lo:[0,0,1] neg_hi:[0,0,1]
	v_pk_fma_f32 v[34:35], v[34:35], v[42:43], v[40:41]
	v_pk_mul_f32 v[16:17], v[2:3], v[86:87] op_sel:[1,0]
	v_pk_add_f32 v[38:39], v[26:27], v[28:29] op_sel:[0,1] op_sel_hi:[1,0]
	v_pk_add_f32 v[26:27], v[26:27], v[28:29] op_sel:[0,1] op_sel_hi:[1,0] neg_lo:[0,1] neg_hi:[0,1]
	v_mov_b32_e32 v93, v33
	v_pk_mul_f32 v[94:95], v[78:79], v[56:57]
	v_mov_b32_e32 v96, v82
	v_mov_b32_e32 v97, v85
	v_pk_mov_b32 v[82:83], v[82:83], v[84:85] op_sel:[1,0]
	v_mov_b32_e32 v47, v35
	v_pk_fma_f32 v[34:35], v[14:15], v[76:77], v[16:17] neg_lo:[0,0,1] neg_hi:[0,0,1]
	v_pk_fma_f32 v[16:17], v[14:15], v[78:79], v[16:17] op_sel_hi:[0,1,1]
	v_pk_mov_b32 v[48:49], v[26:27], v[38:39] op_sel:[1,0]
	ds_write_b64 v1, v[92:93] offset:6528
	v_pk_mul_f32 v[92:93], v[78:79], v[52:53]
	v_pk_add_f32 v[84:85], v[96:97], v[82:83]
	v_pk_add_f32 v[82:83], v[96:97], v[82:83] neg_lo:[0,1] neg_hi:[0,1]
	v_mov_b32_e32 v5, v15
	v_mov_b32_e32 v35, v17
	v_pk_mov_b32 v[14:15], v[14:15], v[2:3] op_sel:[1,0]
	v_pk_add_f32 v[16:17], v[94:95], v[94:95] op_sel:[0,1] op_sel_hi:[0,1]
	v_mov_b32_e32 v96, v84
	v_mov_b32_e32 v97, v83
	v_pk_mul_f32 v[48:49], v[48:49], v[82:83] op_sel:[0,1]
	v_mov_b32_e32 v4, v2
	v_pk_mul_f32 v[14:15], v[14:15], v[16:17]
	v_pk_add_f32 v[16:17], v[92:93], v[92:93] op_sel:[0,1] op_sel_hi:[0,1] neg_lo:[0,1] neg_hi:[0,1]
	v_pk_fma_f32 v[82:83], v[38:39], v[84:85], v[48:49] neg_lo:[0,0,1] neg_hi:[0,0,1]
	v_fma_f32 v28, v38, v84, v48
	v_fma_f32 v29, v27, v84, v49
	v_pk_mul_f32 v[48:49], v[56:57], v[96:97]
	v_pk_fma_f32 v[2:3], v[2:3], v[16:17], v[14:15] neg_lo:[0,0,1] neg_hi:[0,0,1]
	v_pk_fma_f32 v[4:5], v[4:5], v[16:17], v[14:15]
	v_mov_b32_e32 v83, v29
	v_pk_mul_f32 v[28:29], v[52:53], v[96:97]
	v_mov_b32_e32 v3, v5
	v_pk_mov_b32 v[4:5], v[38:39], v[26:27] op_sel:[1,0]
	v_pk_add_f32 v[14:15], v[48:49], v[48:49] op_sel:[0,1] op_sel_hi:[0,1]
	ds_write_b64 v1, v[82:83] offset:10880
	v_mov_b32_e32 v71, v31
	ds_write_b64 v1, v[64:65] offset:17408
	ds_write_b64 v1, v[70:71] offset:19584
	ds_write_b64 v1, v[2:3] offset:26112
	v_pk_mul_f32 v[4:5], v[4:5], v[14:15]
	v_pk_add_f32 v[14:15], v[28:29], v[28:29] op_sel:[0,1] op_sel_hi:[0,1] neg_lo:[0,1] neg_hi:[0,1]
	v_pk_mul_f32 v[30:31], v[52:53], v[58:59]
	v_pk_fma_f32 v[16:17], v[26:27], v[14:15], v[4:5] neg_lo:[0,0,1] neg_hi:[0,0,1]
	v_fma_f32 v2, v26, v14, v4
	v_fma_f32 v3, v39, v15, v5
	v_pk_mul_f32 v[58:59], v[56:57], v[58:59]
	v_mov_b32_e32 v17, v3
	v_mov_b32_e32 v3, v30
	v_sub_f32_e32 v2, v20, v21
	v_sub_f32_e32 v3, v3, v31
	v_pk_add_f32 v[14:15], v[58:59], v[58:59] op_sel:[0,1] op_sel_hi:[0,1]
	v_mul_f32_e32 v4, v18, v14
	v_mul_f32_e32 v5, v2, v15
	v_pk_mov_b32 v[14:15], v[2:3], v[18:19] op_sel:[1,0]
	ds_write_b64 v1, v[16:17] offset:28288
	v_pk_fma_f32 v[16:17], v[2:3], v[14:15], v[4:5] neg_lo:[0,0,1] neg_hi:[0,0,1]
	v_pk_fma_f32 v[2:3], v[2:3], v[14:15], v[4:5]
	v_pk_mul_f32 v[32:33], v[78:79], v[66:67] op_sel:[0,1]
	v_mov_b32_e32 v17, v3
	v_pk_mov_b32 v[2:3], v[22:23], v[36:37] op_sel:[1,0]
	v_pk_mov_b32 v[4:5], v[44:45], v[24:25] op_sel:[1,0]
	v_pk_fma_f32 v[66:67], v[78:79], v[72:73], v[32:33] op_sel:[0,0,1] op_sel_hi:[1,0,0] neg_lo:[0,0,1] neg_hi:[0,0,1]
	v_pk_fma_f32 v[32:33], v[78:79], v[72:73], v[32:33] op_sel:[0,0,1] op_sel_hi:[1,0,0]
	v_pk_add_f32 v[2:3], v[2:3], v[4:5] neg_lo:[0,1] neg_hi:[0,1]
	v_sub_f32_e32 v4, v44, v22
	v_sub_f32_e32 v5, v37, v25
	v_mov_b32_e32 v73, v33
	v_pk_mov_b32 v[32:33], v[32:33], v[66:67] op_sel:[1,0]
	v_pk_add_f32 v[14:15], v[4:5], v[2:3]
	v_pk_add_f32 v[2:3], v[4:5], v[2:3] neg_lo:[0,1] neg_hi:[0,1]
	v_mov_b32_e32 v72, v66
	ds_write_b64 v1, v[16:17] offset:30464
	v_pk_mul_f32 v[16:17], v[2:3], v[32:33] op_sel:[1,0]
	v_pk_mul_f32 v[56:57], v[56:57], v[72:73]
	v_pk_fma_f32 v[18:19], v[14:15], v[66:67], v[16:17] neg_lo:[0,0,1] neg_hi:[0,0,1]
	v_pk_fma_f32 v[16:17], v[14:15], v[72:73], v[16:17] op_sel_hi:[0,1,1]
	v_pk_mul_f32 v[52:53], v[52:53], v[72:73]
	v_mov_b32_e32 v5, v15
	v_mov_b32_e32 v19, v17
	v_pk_mov_b32 v[14:15], v[14:15], v[2:3] op_sel:[1,0]
	v_pk_add_f32 v[16:17], v[56:57], v[56:57] op_sel:[0,1] op_sel_hi:[0,1]
	v_mov_b32_e32 v4, v2
	v_pk_mul_f32 v[14:15], v[14:15], v[16:17]
	v_pk_add_f32 v[16:17], v[52:53], v[52:53] op_sel:[0,1] op_sel_hi:[0,1] neg_lo:[0,1] neg_hi:[0,1]
	v_pk_fma_f32 v[2:3], v[2:3], v[16:17], v[14:15] neg_lo:[0,0,1] neg_hi:[0,0,1]
	v_pk_fma_f32 v[4:5], v[4:5], v[16:17], v[14:15]
	ds_write_b64 v1, v[54:55] offset:21760
	v_mov_b32_e32 v3, v5
	ds_write_b64 v1, v[46:47] offset:23936
	ds_write_b64 v1, v[34:35] offset:8704
	ds_write_b64 v1, v[18:19] offset:15232
	ds_write_b64 v1, v[2:3] offset:32640
	v_mov_b32_e32 v1, v122
	s_waitcnt lgkmcnt(0)
	s_barrier
	s_mov_b32 s43, 0
	v_ashrrev_i32_e32 v2, 31, v1
	v_lshrrev_b32_e32 v2, 28, v2
	v_and_b32_e32 v70, 15, v1
	v_add_u32_e32 v1, v1, v2
	v_ashrrev_i32_e32 v1, 4, v1
	v_lshlrev_b32_e32 v2, 11, v1
	v_lshl_add_u32 v1, v1, 7, v2
	v_lshl_or_b32 v1, v70, 3, v1
	ds_read2_b64 v[20:23], v1 offset1:17
	ds_read2_b64 v[24:27], v1 offset0:68 offset1:85
	ds_read2_b64 v[28:31], v1 offset0:136 offset1:153
	ds_read2_b64 v[32:35], v1 offset0:170 offset1:187
	ds_read2_b64 v[36:39], v1 offset0:204 offset1:221
	ds_read2_b64 v[40:43], v1 offset0:238 offset1:255
	ds_read2_b64 v[44:47], v1 offset0:34 offset1:51
	ds_read2_b64 v[48:51], v1 offset0:102 offset1:119
	s_waitcnt lgkmcnt(5)
	v_pk_add_f32 v[18:19], v[28:29], v[20:21]
	s_waitcnt lgkmcnt(2)
	v_pk_mov_b32 v[68:69], v[34:35], v[42:43] op_sel:[1,0]
	s_waitcnt lgkmcnt(1)
	v_pk_add_f32 v[64:65], v[46:47], v[34:35]
	s_waitcnt lgkmcnt(0)
	v_pk_add_f32 v[66:67], v[50:51], v[42:43]
	v_pk_mov_b32 v[16:17], v[46:47], v[50:51] op_sel:[1,0]
	v_mov_b32_e32 v35, v43
	v_pk_add_f32 v[42:43], v[64:65], v[66:67] neg_lo:[0,1] neg_hi:[0,1]
	v_pk_add_f32 v[68:69], v[16:17], v[68:69] neg_lo:[0,1] neg_hi:[0,1]
	v_pk_add_f32 v[16:17], v[64:65], v[66:67]
	v_mul_f32_e32 v64, 0x3f3504f3, v43
	v_mul_f32_e32 v67, 0xbf3504f3, v43
	v_cvt_f32_i32_e32 v43, v70
	v_mov_b32_e32 v47, v51
	v_pk_add_f32 v[34:35], v[46:47], v[34:35] neg_lo:[0,1] neg_hi:[0,1]
	v_pk_add_f32 v[28:29], v[20:21], v[28:29] neg_lo:[0,1] neg_hi:[0,1]
	v_add_f32_e32 v43, v43, v43
	v_pk_add_f32 v[20:21], v[24:25], v[36:37] neg_lo:[0,1] neg_hi:[0,1]
	v_pk_add_f32 v[52:53], v[36:37], v[24:25]
	v_pk_add_f32 v[54:55], v[22:23], v[30:31]
	v_pk_add_f32 v[56:57], v[26:27], v[38:39]
	v_pk_add_f32 v[46:47], v[34:35], v[34:35] op_sel:[0,1] op_sel_hi:[1,0] neg_lo:[0,1] neg_hi:[0,1]
	v_mul_f32_e32 v43, 0x3b800000, v43
	v_pk_mov_b32 v[24:25], v[20:21], v[20:21] op_sel:[1,0]
	v_pk_add_f32 v[36:37], v[28:29], v[20:21] op_sel:[0,1] op_sel_hi:[1,0]
	v_pk_add_f32 v[20:21], v[28:29], v[20:21] op_sel:[0,1] op_sel_hi:[1,0] neg_lo:[0,1] neg_hi:[0,1]
	v_pk_add_f32 v[34:35], v[34:35], v[34:35] op_sel:[0,1] op_sel_hi:[0,1]
	v_pk_add_f32 v[4:5], v[54:55], v[56:57]
	v_pk_add_f32 v[58:59], v[44:45], v[32:33]
	v_pk_add_f32 v[60:61], v[48:49], v[40:41]
	v_pk_add_f32 v[54:55], v[54:55], v[56:57] neg_lo:[0,1] neg_hi:[0,1]
	v_mul_f32_e32 v43, 0.5, v43
	v_mov_b32_e32 v37, v21
	v_pk_add_f32 v[20:21], v[68:69], v[68:69] op_sel:[0,1] op_sel_hi:[0,1] neg_lo:[0,1] neg_hi:[0,1]
	v_pk_mul_f32 v[34:35], v[34:35], s[0:1]
	v_pk_add_f32 v[14:15], v[58:59], v[60:61]
	v_pk_add_f32 v[62:63], v[58:59], v[60:61] neg_lo:[0,1] neg_hi:[0,1]
	v_pk_add_f32 v[50:51], v[68:69], v[68:69] op_sel:[0,1] op_sel_hi:[1,0]
	v_pk_mul_f32 v[56:57], v[54:55], s[20:21] op_sel_hi:[1,0]
	v_mul_f32_e32 v42, 0x3f3504f3, v42
	v_sin_f32_e32 v58, v43
	v_cos_f32_e32 v76, v43
	v_pk_fma_f32 v[68:69], v[20:21], s[22:23], v[34:35]
	v_pk_fma_f32 v[20:21], v[20:21], s[22:23], v[34:35] neg_lo:[0,0,1] neg_hi:[0,0,1]
	s_nop 0
	s_nop 0
	v_pk_add_f32 v[2:3], v[18:19], v[52:53]
	v_mov_b32_e32 v69, v21
	v_mov_b32_e32 v20, v18
	v_sub_f32_e32 v18, v64, v42
	v_sub_f32_e32 v19, v19, v53
	v_sub_f32_e32 v20, v20, v52
	v_sub_f32_e32 v21, v57, v56
	v_mov_b32_e32 v35, v42
	v_pk_add_f32 v[42:43], v[18:19], v[62:63] op_sel:[1,0] op_sel_hi:[0,1]
	v_mov_b32_e32 v53, v62
	v_sub_f32_e32 v34, v59, v61
	v_sub_f32_e32 v35, v67, v35
	v_sub_f32_e32 v62, v44, v32
	v_sub_f32_e32 v63, v22, v30
	v_sub_f32_e32 v64, v49, v41
	v_sub_f32_e32 v65, v27, v39
	v_mul_f32_e32 v78, 0x3f6c835e, v50
	v_mul_f32_e32 v79, 0x3ec3ef15, v46
	v_sub_f32_e32 v22, v45, v33
	v_sub_f32_e32 v23, v23, v31
	v_sub_f32_e32 v27, v26, v38
	v_sub_f32_e32 v26, v48, v40
	v_pk_add_f32 v[32:33], v[62:63], v[64:65] neg_lo:[0,1] neg_hi:[0,1]
	v_pk_fma_f32 v[54:55], v[54:55], s[20:21], v[56:57] op_sel:[0,0,1] op_sel_hi:[1,0,0]
	v_pk_add_f32 v[66:67], v[62:63], v[64:65]
	v_pk_add_f32 v[30:31], v[22:23], v[26:27] neg_lo:[0,1] neg_hi:[0,1]
	v_pk_add_f32 v[22:23], v[22:23], v[26:27]
	v_mov_b32_e32 v51, v32
	v_mov_b32_e32 v39, v29
	v_mov_b32_e32 v27, v25
	v_mov_b32_e32 v52, v54
	v_pk_add_f32 v[54:55], v[54:55], v[18:19] neg_lo:[0,1] neg_hi:[0,1]
	v_mul_f32_e32 v26, 0x3ec3ef15, v33
	v_pk_mul_f32 v[40:41], v[32:33], s[20:21]
	v_pk_mul_f32 v[32:33], v[50:51], s[72:73]
	v_mov_b32_e32 v47, v22
	v_sub_f32_e32 v24, v28, v24
	v_sub_f32_e32 v25, v79, v78
	v_pk_mul_f32 v[28:29], v[66:67], s[22:23] op_sel:[1,0]
	v_pk_add_f32 v[56:57], v[18:19], v[52:53]
	v_pk_add_f32 v[52:53], v[18:19], v[52:53] neg_lo:[0,1] neg_hi:[0,1]
	v_pk_add_f32 v[18:19], v[42:43], v[54:55]
	v_mul_f32_e32 v38, 0x3f6c835e, v23
	v_mul_f32_e32 v43, 0x3f3504f3, v66
	v_mul_f32_e32 v44, 0x3f3504f3, v30
	v_pk_fma_f32 v[40:41], v[22:23], s[70:71], v[40:41] neg_lo:[0,0,1] neg_hi:[0,0,1]
	v_pk_fma_f32 v[22:23], v[46:47], s[30:31], v[32:33] neg_lo:[0,0,1] neg_hi:[0,0,1]
	v_pk_fma_f32 v[32:33], v[30:31], s[0:1], v[28:29] op_sel:[1,0,0]
	v_pk_fma_f32 v[28:29], v[30:31], s[0:1], v[28:29] op_sel:[1,0,0] neg_lo:[0,0,1] neg_hi:[0,0,1]
	v_pk_add_f32 v[26:27], v[38:39], v[26:27]
	v_mov_b32_e32 v33, v29
	v_add_f32_e32 v28, v44, v43
	v_fma_f32 v29, v30, s20, -v43
	v_pk_add_f32 v[30:31], v[36:37], v[28:29]
	v_pk_add_f32 v[38:39], v[32:33], v[68:69]
	v_xor_b32_e32 v77, 0x80000000, v58
	v_pk_add_f32 v[44:45], v[38:39], v[30:31]
	v_pk_add_f32 v[70:71], v[2:3], v[14:15]
	v_pk_mul_f32 v[50:51], v[58:59], v[44:45] op_sel_hi:[0,1]
	v_pk_fma_f32 v[62:63], v[76:77], v[44:45], v[50:51] op_sel:[0,0,1] op_sel_hi:[1,1,0]
	v_pk_fma_f32 v[44:45], v[76:77], v[44:45], v[50:51] op_sel:[0,0,1] op_sel_hi:[0,1,0] neg_lo:[0,0,1] neg_hi:[0,0,1]
	v_mov_b32_e32 v63, v45
	v_mov_b32_e32 v59, v76
	v_pk_add_f32 v[72:73], v[4:5], v[16:17]
	v_mul_f32_e32 v44, v58, v58
	v_mul_f32_e32 v45, v59, v77
	v_pk_add_f32 v[74:75], v[72:73], v[70:71]
	v_pk_fma_f32 v[50:51], v[76:77], v[76:77], v[44:45] op_sel_hi:[0,1,1] neg_lo:[0,0,1] neg_hi:[0,0,1]
	v_pk_fma_f32 v[44:45], v[76:77], v[76:77], v[44:45] op_sel_hi:[0,1,1]
	v_mov_b32_e32 v57, v53
	v_pk_add_f32 v[60:61], v[20:21], v[34:35]
	ds_write2_b64 v1, v[74:75], v[62:63] offset1:17
	v_pk_mov_b32 v[74:75], v[44:45], v[50:51] op_sel:[1,0]
	v_pk_add_f32 v[20:21], v[20:21], v[34:35] neg_lo:[0,1] neg_hi:[0,1]
	v_pk_add_f32 v[34:35], v[60:61], v[56:57]
	v_mov_b32_e32 v62, v50
	v_mov_b32_e32 v63, v45
	v_pk_mul_f32 v[74:75], v[44:45], v[74:75] op_sel:[1,0]
	v_pk_mul_f32 v[44:45], v[34:35], v[44:45] op_sel:[1,1] op_sel_hi:[0,1]
	v_pk_fma_f32 v[78:79], v[50:51], v[62:63], v[74:75] op_sel_hi:[0,1,1] neg_lo:[0,0,1] neg_hi:[0,0,1]
	v_pk_fma_f32 v[74:75], v[50:51], v[62:63], v[74:75] op_sel_hi:[0,1,1]
	v_pk_fma_f32 v[88:89], v[34:35], v[50:51], v[44:45] neg_lo:[0,0,1] neg_hi:[0,0,1]
	v_pk_fma_f32 v[34:35], v[34:35], v[50:51], v[44:45] op_sel_hi:[1,0,1]
	v_pk_mul_f32 v[44:45], v[62:63], v[74:75] op_sel:[0,1]
	v_pk_add_f32 v[32:33], v[32:33], v[68:69] neg_lo:[0,1] neg_hi:[0,1]
	v_pk_fma_f32 v[50:51], v[62:63], v[78:79], v[44:45] op_sel:[0,0,1] op_sel_hi:[1,0,0] neg_lo:[0,0,1] neg_hi:[0,0,1]
	v_pk_fma_f32 v[44:45], v[62:63], v[78:79], v[44:45] op_sel:[0,0,1] op_sel_hi:[1,0,0]
	v_sub_f32_e32 v42, v42, v54
	v_mov_b32_e32 v69, v45
	v_pk_mov_b32 v[44:45], v[44:45], v[50:51] op_sel:[1,0]
	v_mov_b32_e32 v77, v58
	v_mov_b32_e32 v80, v78
	v_mov_b32_e32 v81, v75
	v_pk_add_f32 v[90:91], v[20:21], v[20:21] op_sel:[0,1] op_sel_hi:[0,1]
	v_pk_mul_f32 v[42:43], v[42:43], v[44:45] op_sel_hi:[0,1]
	v_pk_mul_f32 v[64:65], v[76:77], v[62:63]
	v_pk_mul_f32 v[66:67], v[58:59], v[62:63]
	v_mov_b32_e32 v68, v50
	v_pk_fma_f32 v[44:45], v[90:91], v[50:51], v[42:43] neg_lo:[0,0,1] neg_hi:[0,0,1]
	v_pk_mul_f32 v[50:51], v[80:81], v[74:75] op_sel:[0,1]
	v_pk_add_f32 v[30:31], v[30:31], v[38:39] neg_lo:[0,1] neg_hi:[0,1]
	v_pk_add_f32 v[38:39], v[40:41], v[24:25]
	v_pk_add_f32 v[46:47], v[26:27], v[22:23]
	v_pk_fma_f32 v[42:43], v[90:91], v[68:69], v[42:43]
	v_pk_fma_f32 v[54:55], v[78:79], v[80:81], v[50:51] op_sel:[0,0,1] op_sel_hi:[0,1,0] neg_lo:[0,0,1] neg_hi:[0,0,1]
	v_pk_fma_f32 v[50:51], v[78:79], v[80:81], v[50:51] op_sel:[0,0,1] op_sel_hi:[0,1,0]
	v_mov_b32_e32 v92, v64
	v_mov_b32_e32 v93, v67
	v_pk_mov_b32 v[64:65], v[64:65], v[66:67] op_sel:[1,0]
	v_pk_add_f32 v[48:49], v[38:39], v[46:47]
	v_mov_b32_e32 v45, v43
	v_pk_add_f32 v[42:43], v[70:71], v[72:73] neg_lo:[0,1] neg_hi:[0,1]
	v_pk_mov_b32 v[72:73], v[50:51], v[54:55] op_sel:[1,0]
	v_pk_add_f32 v[66:67], v[92:93], v[64:65]
	v_pk_add_f32 v[64:65], v[92:93], v[64:65] neg_lo:[0,1] neg_hi:[0,1]
	v_pk_mul_f32 v[82:83], v[76:77], v[80:81]
	v_pk_mul_f32 v[84:85], v[58:59], v[80:81]
	v_pk_add_f32 v[28:29], v[36:37], v[28:29] neg_lo:[0,1] neg_hi:[0,1]
	v_mov_b32_e32 v70, v54
	v_mov_b32_e32 v71, v51
	v_pk_mul_f32 v[58:59], v[58:59], v[72:73] op_sel_hi:[0,1]
	v_pk_mul_f32 v[94:95], v[48:49], v[64:65] op_sel:[0,1]
	v_pk_mov_b32 v[86:87], v[74:75], v[78:79] op_sel:[1,0]
	v_mov_b32_e32 v89, v35
	v_pk_add_f32 v[34:35], v[28:29], v[32:33] op_sel:[0,1] op_sel_hi:[1,0]
	v_pk_add_f32 v[28:29], v[28:29], v[32:33] op_sel:[0,1] op_sel_hi:[1,0] neg_lo:[0,1] neg_hi:[0,1]
	v_pk_fma_f32 v[74:75], v[76:77], v[70:71], v[58:59] op_sel_hi:[0,1,1]
	v_pk_fma_f32 v[58:59], v[76:77], v[70:71], v[58:59] op_sel_hi:[0,1,1] neg_lo:[0,0,1] neg_hi:[0,0,1]
	v_pk_fma_f32 v[96:97], v[48:49], v[66:67], v[94:95] op_sel:[0,0,1] op_sel_hi:[1,1,0] neg_lo:[0,0,1] neg_hi:[0,0,1]
	v_pk_fma_f32 v[48:49], v[48:49], v[66:67], v[94:95] op_sel:[0,0,1] op_sel_hi:[1,0,0]
	v_mov_b32_e32 v98, v82
	v_mov_b32_e32 v99, v85
	v_pk_mov_b32 v[82:83], v[82:83], v[84:85] op_sel:[1,0]
	v_pk_mov_b32 v[36:37], v[28:29], v[34:35] op_sel:[1,0]
	v_mov_b32_e32 v77, v59
	v_mov_b32_e32 v97, v49
	v_pk_mul_f32 v[48:49], v[80:81], v[64:65] op_sel:[0,1]
	v_pk_add_f32 v[84:85], v[98:99], v[82:83]
	v_pk_add_f32 v[82:83], v[98:99], v[82:83] neg_lo:[0,1] neg_hi:[0,1]
	v_pk_mov_b32 v[58:59], v[58:59], v[74:75] op_sel:[1,0]
	v_mov_b32_e32 v76, v74
	v_mov_b32_e32 v93, v65
	v_pk_fma_f32 v[64:65], v[80:81], v[66:67], v[48:49] op_sel:[0,0,1] op_sel_hi:[1,0,0] neg_lo:[0,0,1] neg_hi:[0,0,1]
	v_pk_fma_f32 v[48:49], v[80:81], v[66:67], v[48:49] op_sel:[0,0,1] op_sel_hi:[1,0,0]
	v_pk_mul_f32 v[36:37], v[36:37], v[82:83] op_sel:[0,1]
	v_pk_mul_f32 v[58:59], v[30:31], v[58:59] op_sel:[1,0]
	v_mov_b32_e32 v92, v66
	v_mov_b32_e32 v66, v64
	v_mov_b32_e32 v67, v49
	v_mov_b32_e32 v98, v84
	v_mov_b32_e32 v99, v83
	v_pk_fma_f32 v[82:83], v[34:35], v[84:85], v[36:37] neg_lo:[0,0,1] neg_hi:[0,0,1]
	v_fma_f32 v32, v34, v84, v36
	v_fma_f32 v33, v29, v84, v37
	v_pk_fma_f32 v[74:75], v[30:31], v[74:75], v[58:59] neg_lo:[0,0,1] neg_hi:[0,0,1]
	v_pk_fma_f32 v[30:31], v[30:31], v[76:77], v[58:59] op_sel_hi:[0,1,1]
	v_pk_mul_f32 v[50:51], v[42:43], v[50:51] op_sel:[1,1] op_sel_hi:[0,1]
	v_pk_mul_f32 v[90:91], v[62:63], v[70:71]
	v_pk_mul_f32 v[62:63], v[62:63], v[72:73]
	ds_write2_b64 v1, v[88:89], v[96:97] offset0:34 offset1:51
	v_pk_mul_f32 v[88:89], v[92:93], v[70:71]
	v_pk_mul_f32 v[92:93], v[92:93], v[72:73]
	v_pk_mul_f32 v[94:95], v[80:81], v[70:71]
	v_pk_mul_f32 v[96:97], v[80:81], v[72:73]
	v_mov_b32_e32 v83, v33
	v_pk_mul_f32 v[32:33], v[70:71], v[98:99]
	v_pk_mul_f32 v[36:37], v[72:73], v[98:99]
	v_mov_b32_e32 v75, v31
	v_pk_mul_f32 v[30:31], v[70:71], v[68:69]
	v_pk_mul_f32 v[58:59], v[72:73], v[68:69]
	v_pk_mul_f32 v[68:69], v[70:71], v[66:67]
	v_pk_mul_f32 v[70:71], v[72:73], v[66:67]
	v_pk_fma_f32 v[72:73], v[42:43], v[54:55], v[50:51] neg_lo:[0,0,1] neg_hi:[0,0,1]
	v_pk_fma_f32 v[42:43], v[42:43], v[54:55], v[50:51] op_sel_hi:[1,0,1]
	v_mov_b32_e32 v73, v43
	v_sub_f32_e32 v42, v60, v56
	v_sub_f32_e32 v43, v53, v61
	v_pk_add_f32 v[50:51], v[62:63], v[62:63] op_sel:[0,1] op_sel_hi:[0,1]
	v_pk_mul_f32 v[50:51], v[42:43], v[50:51] op_sel:[1,0] op_sel_hi:[0,1]
	v_pk_add_f32 v[52:53], v[90:91], v[90:91] op_sel:[0,1] op_sel_hi:[0,1] neg_lo:[0,1] neg_hi:[0,1]
	v_pk_fma_f32 v[54:55], v[42:43], v[52:53], v[50:51] neg_lo:[0,0,1] neg_hi:[0,0,1]
	v_pk_fma_f32 v[42:43], v[42:43], v[52:53], v[50:51]
	v_pk_add_f32 v[2:3], v[2:3], v[14:15] neg_lo:[0,1] neg_hi:[0,1]
	v_mov_b32_e32 v55, v43
	v_mov_b32_e32 v43, v47
	v_sub_f32_e32 v38, v38, v46
	v_sub_f32_e32 v39, v43, v39
	v_pk_add_f32 v[42:43], v[92:93], v[92:93] op_sel:[0,1] op_sel_hi:[0,1]
	v_pk_add_f32 v[4:5], v[4:5], v[16:17] neg_lo:[0,1] neg_hi:[0,1]
	v_pk_mul_f32 v[42:43], v[38:39], v[42:43] op_sel:[1,0] op_sel_hi:[0,1]
	v_pk_add_f32 v[46:47], v[88:89], v[88:89] op_sel:[0,1] op_sel_hi:[0,1] neg_lo:[0,1] neg_hi:[0,1]
	v_pk_add_f32 v[14:15], v[2:3], v[4:5] op_sel:[0,1] op_sel_hi:[1,0]
	v_pk_add_f32 v[2:3], v[2:3], v[4:5] op_sel:[0,1] op_sel_hi:[1,0] neg_lo:[0,1] neg_hi:[0,1]
	v_pk_fma_f32 v[50:51], v[38:39], v[46:47], v[42:43] neg_lo:[0,0,1] neg_hi:[0,0,1]
	v_pk_fma_f32 v[38:39], v[38:39], v[46:47], v[42:43]
	v_pk_mul_f32 v[16:17], v[2:3], v[86:87] op_sel:[1,0]
	v_mov_b32_e32 v51, v39
	v_pk_fma_f32 v[38:39], v[14:15], v[78:79], v[16:17] neg_lo:[0,0,1] neg_hi:[0,0,1]
	v_pk_fma_f32 v[16:17], v[14:15], v[80:81], v[16:17] op_sel_hi:[0,1,1]
	v_mov_b32_e32 v5, v15
	v_mov_b32_e32 v39, v17
	v_pk_mov_b32 v[14:15], v[14:15], v[2:3] op_sel:[1,0]
	v_pk_add_f32 v[16:17], v[96:97], v[96:97] op_sel:[0,1] op_sel_hi:[0,1]
	v_mov_b32_e32 v4, v2
	v_pk_mul_f32 v[14:15], v[14:15], v[16:17]
	v_pk_add_f32 v[16:17], v[94:95], v[94:95] op_sel:[0,1] op_sel_hi:[0,1] neg_lo:[0,1] neg_hi:[0,1]
	v_pk_fma_f32 v[2:3], v[2:3], v[16:17], v[14:15] neg_lo:[0,0,1] neg_hi:[0,0,1]
	v_pk_fma_f32 v[4:5], v[4:5], v[16:17], v[14:15]
	v_pk_mov_b32 v[14:15], v[34:35], v[28:29] op_sel:[1,0]
	v_pk_add_f32 v[16:17], v[36:37], v[36:37] op_sel:[0,1] op_sel_hi:[0,1]
	v_mov_b32_e32 v3, v5
	v_mov_b32_e32 v4, v28
	v_mov_b32_e32 v5, v35
	v_pk_mul_f32 v[14:15], v[14:15], v[16:17]
	v_pk_add_f32 v[16:17], v[32:33], v[32:33] op_sel:[0,1] op_sel_hi:[0,1] neg_lo:[0,1] neg_hi:[0,1]
	v_pk_fma_f32 v[28:29], v[28:29], v[16:17], v[14:15] neg_lo:[0,0,1] neg_hi:[0,0,1]
	v_pk_fma_f32 v[4:5], v[4:5], v[16:17], v[14:15]
	v_pk_add_f32 v[14:15], v[58:59], v[58:59] op_sel:[0,1] op_sel_hi:[0,1]
	v_mov_b32_e32 v29, v5
	ds_write2_b64 v1, v[2:3], v[28:29] offset0:204 offset1:221
	v_mov_b32_e32 v3, v30
	v_sub_f32_e32 v2, v20, v21
	v_sub_f32_e32 v3, v3, v31
	v_mul_f32_e32 v4, v18, v14
	v_mul_f32_e32 v5, v2, v15
	v_pk_mov_b32 v[14:15], v[2:3], v[18:19] op_sel:[1,0]
	v_pk_mov_b32 v[48:49], v[48:49], v[64:65] op_sel:[1,0]
	v_pk_fma_f32 v[16:17], v[2:3], v[14:15], v[4:5] neg_lo:[0,0,1] neg_hi:[0,0,1]
	v_pk_fma_f32 v[2:3], v[2:3], v[14:15], v[4:5]
	v_mov_b32_e32 v17, v3
	v_mov_b32_e32 v3, v26
	v_mov_b32_e32 v5, v22
	v_sub_f32_e32 v2, v24, v40
	v_sub_f32_e32 v3, v3, v5
	v_sub_f32_e32 v4, v41, v25
	v_sub_f32_e32 v5, v27, v23
	ds_write2_b64 v1, v[72:73], v[74:75] offset0:136 offset1:153
	v_pk_add_f32 v[14:15], v[4:5], v[2:3]
	v_pk_add_f32 v[18:19], v[2:3], v[4:5] neg_lo:[0,1] neg_hi:[0,1]
	v_sub_f32_e32 v2, v5, v3
	v_pk_mul_f32 v[2:3], v[2:3], v[48:49] op_sel_hi:[0,1]
	v_pk_fma_f32 v[4:5], v[14:15], v[64:65], v[2:3] neg_lo:[0,0,1] neg_hi:[0,0,1]
	v_pk_fma_f32 v[2:3], v[14:15], v[66:67], v[2:3] op_sel_hi:[0,1,1]
	v_mov_b32_e32 v5, v3
	ds_write2_b64 v1, v[44:45], v[4:5] offset0:102 offset1:119
	v_pk_mov_b32 v[2:3], v[14:15], v[18:19] op_sel:[1,0]
	v_pk_add_f32 v[4:5], v[70:71], v[70:71] op_sel:[0,1] op_sel_hi:[0,1]
	v_mov_b32_e32 v20, v18
	v_mov_b32_e32 v21, v15
	v_pk_mul_f32 v[2:3], v[2:3], v[4:5]
	v_pk_add_f32 v[4:5], v[68:69], v[68:69] op_sel:[0,1] op_sel_hi:[0,1] neg_lo:[0,1] neg_hi:[0,1]
	v_pk_fma_f32 v[14:15], v[18:19], v[4:5], v[2:3] neg_lo:[0,0,1] neg_hi:[0,0,1]
	v_pk_fma_f32 v[2:3], v[20:21], v[4:5], v[2:3]
	ds_write2_b64 v1, v[54:55], v[50:51] offset0:170 offset1:187
	v_mov_b32_e32 v15, v3
	ds_write2_b64 v1, v[38:39], v[82:83] offset0:68 offset1:85
	ds_write2_b64 v1, v[16:17], v[14:15] offset0:238 offset1:255
	v_mov_b32_e32 v1, v122
	s_waitcnt lgkmcnt(0)
	s_barrier
	s_and_b64 s[0:1], s[96:97], exec
	v_mul_lo_u32 v1, v1, s33
	ds_read2_b64 v[2:5], v1 offset1:1
	ds_read2_b64 v[14:17], v1 offset0:8 offset1:9
	ds_read2_b64 v[18:21], v1 offset0:10 offset1:11
	ds_read2_b64 v[22:25], v1 offset0:12 offset1:13
	ds_read2_b64 v[26:29], v1 offset0:14 offset1:15
	ds_read2_b64 v[30:33], v1 offset0:2 offset1:3
	ds_read2_b64 v[34:37], v1 offset0:4 offset1:5
	ds_read2_b64 v[38:41], v1 offset0:6 offset1:7
	s_waitcnt lgkmcnt(7)
	v_mov_b32_e32 v1, v4
	v_mov_b32_e32 v42, v2
	v_mov_b32_e32 v43, v4
	v_mov_b32_e32 v4, v5
	v_mov_b32_e32 v5, v3
	s_waitcnt lgkmcnt(6)
	v_mov_b32_e32 v44, v14
	v_mov_b32_e32 v45, v16
	v_mov_b32_e32 v16, v17
	v_mov_b32_e32 v17, v15
	v_pk_add_f32 v[46:47], v[2:3], v[14:15] neg_lo:[0,1] neg_hi:[0,1]
	v_pk_add_f32 v[2:3], v[2:3], v[14:15]
	s_waitcnt lgkmcnt(1)
	v_mov_b32_e32 v15, v36
	v_mov_b32_e32 v49, v36
	v_mov_b32_e32 v36, v37
	v_mov_b32_e32 v37, v35
	v_mov_b32_e32 v50, v22
	v_mov_b32_e32 v51, v24
	v_mov_b32_e32 v24, v25
	v_mov_b32_e32 v25, v23
	v_mov_b32_e32 v48, v34
	v_pk_add_f32 v[52:53], v[34:35], v[22:23] neg_lo:[0,1] neg_hi:[0,1]
	v_pk_add_f32 v[22:23], v[34:35], v[22:23]
	v_pk_mov_b32 v[34:35], v[0:1], v[4:5] op_sel:[1,0]
	v_pk_mov_b32 v[54:55], v[44:45], v[16:17] op_sel:[1,0]
	v_pk_add_f32 v[4:5], v[4:5], v[16:17]
	v_pk_mov_b32 v[14:15], v[14:15], v[36:37] op_sel:[1,0]
	v_pk_mov_b32 v[16:17], v[50:51], v[24:25] op_sel:[1,0]
	v_pk_add_f32 v[42:43], v[42:43], v[44:45]
	v_pk_add_f32 v[44:45], v[48:49], v[50:51]
	v_pk_add_f32 v[24:25], v[36:37], v[24:25]
	v_pk_add_f32 v[48:49], v[2:3], v[22:23] neg_lo:[0,1] neg_hi:[0,1]
	v_pk_add_f32 v[2:3], v[2:3], v[22:23]
	v_pk_add_f32 v[22:23], v[34:35], v[54:55]
	v_pk_add_f32 v[34:35], v[34:35], v[54:55] neg_lo:[0,1] neg_hi:[0,1]
	v_pk_add_f32 v[36:37], v[14:15], v[16:17]
	v_pk_add_f32 v[14:15], v[14:15], v[16:17] neg_lo:[0,1] neg_hi:[0,1]
	v_add_f32_e32 v1, v46, v53
	v_sub_f32_e32 v50, v47, v52
	v_sub_f32_e32 v51, v46, v53
	v_add_f32_e32 v53, v47, v52
	v_pk_add_f32 v[16:17], v[42:43], v[44:45]
	v_pk_add_f32 v[4:5], v[4:5], v[24:25]
	v_add_f32_e32 v52, v34, v15
	v_sub_f32_e32 v54, v35, v14
	v_sub_f32_e32 v55, v34, v15
	v_add_f32_e32 v56, v35, v14
	v_pk_add_f32 v[14:15], v[30:31], v[18:19] neg_lo:[0,1] neg_hi:[0,1]
	v_pk_add_f32 v[24:25], v[30:31], v[18:19]
	v_mov_b32_e32 v44, v30
	v_mov_b32_e32 v46, v18
	v_pk_add_f32 v[42:43], v[22:23], v[36:37]
	v_pk_add_f32 v[22:23], v[22:23], v[36:37] neg_lo:[0,1] neg_hi:[0,1]
	s_waitcnt lgkmcnt(0)
	v_pk_add_f32 v[34:35], v[38:39], v[26:27] neg_lo:[0,1] neg_hi:[0,1]
	v_pk_add_f32 v[36:37], v[38:39], v[26:27]
	v_add_f32_e32 v44, v44, v46
	v_add_f32_e32 v45, v32, v20
	v_add_f32_e32 v18, v33, v21
	v_add_f32_e32 v19, v31, v19
	v_mov_b32_e32 v30, v38
	v_mov_b32_e32 v46, v26
	v_add_f32_e32 v30, v30, v46
	v_add_f32_e32 v31, v40, v28
	v_add_f32_e32 v26, v41, v29
	v_add_f32_e32 v27, v39, v27
	v_pk_add_f32 v[38:39], v[24:25], v[36:37] neg_lo:[0,1] neg_hi:[0,1]
	v_pk_add_f32 v[24:25], v[24:25], v[36:37]
	v_add_f32_e32 v36, v14, v35
	v_sub_f32_e32 v37, v15, v34
	v_sub_f32_e32 v46, v14, v35
	v_add_f32_e32 v47, v15, v34
	v_pk_add_f32 v[14:15], v[32:33], v[20:21]
	v_pk_add_f32 v[20:21], v[32:33], v[20:21] neg_lo:[0,1] neg_hi:[0,1]
	v_pk_add_f32 v[32:33], v[40:41], v[28:29]
	v_mul_f32_e32 v22, 0x3f3504f3, v22
	v_pk_add_f32 v[28:29], v[40:41], v[28:29] neg_lo:[0,1] neg_hi:[0,1]
	v_pk_add_f32 v[34:35], v[14:15], v[32:33]
	v_pk_add_f32 v[14:15], v[14:15], v[32:33] neg_lo:[0,1] neg_hi:[0,1]
	v_fmamk_f32 v33, v23, 0x3f3504f3, v22
	v_fma_f32 v40, v23, s20, -v22
	v_mul_f32_e32 v22, 0x3f3504f3, v36
	v_pk_add_f32 v[30:31], v[44:45], v[30:31]
	v_pk_add_f32 v[18:19], v[18:19], v[26:27]
	v_add_f32_e32 v26, v20, v29
	v_sub_f32_e32 v27, v21, v28
	v_sub_f32_e32 v20, v20, v29
	v_add_f32_e32 v21, v21, v28
	v_mul_f32_e32 v28, 0x3f6c835e, v52
	v_mul_f32_e32 v29, 0x3ec3ef15, v52
	v_mul_f32_e32 v41, 0x3ec3ef15, v55
	v_mul_f32_e32 v45, 0xbf6c835e, v55
	v_fmamk_f32 v32, v37, 0x3f3504f3, v22
	v_fma_f32 v36, v37, s20, -v22
	v_mul_f32_e32 v37, 0xbf3504f3, v46
	v_fmac_f32_e32 v28, 0x3ec3ef15, v54
	v_fma_f32 v29, v54, s21, -v29
	v_fmac_f32_e32 v41, 0x3f6c835e, v56
	v_fmac_f32_e32 v45, 0x3ec3ef15, v56
	v_fmamk_f32 v54, v47, 0x3f3504f3, v37
	v_fmac_f32_e32 v37, 0xbf3504f3, v47
	v_mul_f32_e32 v44, 0x3ec3ef15, v26
	v_mul_f32_e32 v46, 0xbf6c835e, v26
	v_mul_f32_e32 v47, 0xbf3504f3, v14
	v_mul_f32_e32 v14, 0x3ec3ef15, v21
	v_mul_f32_e32 v56, 0xbf6c835e, v21
	v_fmac_f32_e32 v44, 0x3f6c835e, v27
	v_fmac_f32_e32 v46, 0x3ec3ef15, v27
	v_fma_f32 v55, v20, s76, -v14
	v_fmac_f32_e32 v56, 0x3ec3ef15, v20
	v_pk_add_f32 v[20:21], v[2:3], v[24:25]
	v_pk_add_f32 v[2:3], v[2:3], v[24:25] neg_lo:[0,1] neg_hi:[0,1]
	v_pk_add_f32 v[22:23], v[42:43], v[34:35]
	v_pk_add_f32 v[24:25], v[16:17], v[30:31] neg_lo:[0,1] neg_hi:[0,1]
	v_pk_add_f32 v[26:27], v[42:43], v[34:35] neg_lo:[0,1] neg_hi:[0,1]
	v_pk_add_f32 v[4:5], v[4:5], v[18:19] neg_lo:[0,1] neg_hi:[0,1]
	v_fmamk_f32 v52, v15, 0x3f3504f3, v47
	v_fmac_f32_e32 v47, 0xbf3504f3, v15
	v_pk_add_f32 v[14:15], v[22:23], v[20:21]
	v_pk_add_f32 v[16:17], v[20:21], v[22:23] neg_lo:[0,1] neg_hi:[0,1]
	v_pk_add_f32 v[70:71], v[2:3], v[26:27] op_sel:[0,1] op_sel_hi:[1,0]
	v_pk_add_f32 v[2:3], v[2:3], v[26:27] op_sel:[0,1] op_sel_hi:[1,0] neg_lo:[0,1] neg_hi:[0,1]
	v_pk_add_f32 v[72:73], v[24:25], v[4:5] neg_lo:[0,1] neg_hi:[0,1]
	v_pk_add_f32 v[4:5], v[24:25], v[4:5]
	v_add_f32_e32 v23, v1, v32
	v_add_f32_e32 v25, v50, v36
	v_sub_f32_e32 v1, v1, v32
	v_sub_f32_e32 v27, v50, v36
	v_add_f32_e32 v26, v28, v44
	v_add_f32_e32 v30, v29, v46
	v_sub_f32_e32 v31, v28, v44
	v_sub_f32_e32 v29, v29, v46
	v_add_f32_e32 v22, v26, v23
	v_add_f32_e32 v24, v30, v25
	v_sub_f32_e32 v26, v23, v26
	v_sub_f32_e32 v28, v25, v30
	v_add_f32_e32 v30, v29, v1
	v_sub_f32_e32 v32, v27, v31
	v_sub_f32_e32 v34, v1, v29
	v_add_f32_e32 v36, v31, v27
	v_add_f32_e32 v1, v48, v39
	v_sub_f32_e32 v23, v49, v38
	v_sub_f32_e32 v25, v48, v39
	v_add_f32_e32 v27, v49, v38
	v_add_f32_e32 v29, v33, v52
	v_add_f32_e32 v31, v40, v47
	v_sub_f32_e32 v33, v33, v52
	v_sub_f32_e32 v35, v40, v47
	v_add_f32_e32 v38, v1, v29
	v_add_f32_e32 v40, v23, v31
	v_sub_f32_e32 v42, v1, v29
	v_sub_f32_e32 v44, v23, v31
	v_add_f32_e32 v46, v25, v35
	v_sub_f32_e32 v48, v27, v33
	v_sub_f32_e32 v50, v25, v35
	v_add_f32_e32 v52, v27, v33
	v_add_f32_e32 v1, v51, v54
	v_add_f32_e32 v23, v53, v37
	v_sub_f32_e32 v25, v51, v54
	v_sub_f32_e32 v27, v53, v37
	v_add_f32_e32 v29, v41, v55
	v_add_f32_e32 v31, v45, v56
	v_sub_f32_e32 v33, v41, v55
	v_sub_f32_e32 v35, v45, v56
	v_add_f32_e32 v54, v29, v1
	v_add_f32_e32 v56, v31, v23
	v_sub_f32_e32 v58, v1, v29
	v_sub_f32_e32 v60, v23, v31
	v_add_f32_e32 v62, v35, v25
	v_sub_f32_e32 v64, v27, v33
	v_sub_f32_e32 v66, v25, v35
	v_add_f32_e32 v68, v33, v27
	v_readlane_b32 s0, v244, 11
	v_mov_b32_e32 v18, v70
	v_mov_b32_e32 v19, v3
	v_mov_b32_e32 v20, v72
	v_mov_b32_e32 v21, v5
	s_cselect_b32 s29, s12, s28
	s_cselect_b32 s42, s0, s89
	v_pk_mov_b32 v[70:71], v[2:3], v[70:71] op_sel:[1,0]
	v_pk_mov_b32 v[72:73], v[4:5], v[72:73] op_sel:[1,0]
	v_mov_b32_e32 v39, v38
	v_mov_b32_e32 v43, v42
	v_mov_b32_e32 v47, v46
	v_mov_b32_e32 v49, v48
	v_mov_b32_e32 v51, v50
	v_mov_b32_e32 v53, v52
	v_mov_b32_e32 v23, v22
	v_mov_b32_e32 v27, v26
	v_mov_b32_e32 v31, v30
	v_mov_b32_e32 v33, v32
	v_mov_b32_e32 v35, v34
	v_mov_b32_e32 v37, v36
	v_mov_b32_e32 v55, v54
	v_mov_b32_e32 v59, v58
	v_mov_b32_e32 v63, v62
	v_mov_b32_e32 v65, v64
	v_mov_b32_e32 v67, v66
	v_mov_b32_e32 v69, v68
	v_pk_mov_b32 v[74:75], v[14:15], v[14:15] op_sel:[1,0]
	v_mov_b32_e32 v25, v24
	v_mov_b32_e32 v41, v40
	v_mov_b32_e32 v57, v56
	v_pk_mov_b32 v[76:77], v[16:17], v[16:17] op_sel:[1,0]
	v_mov_b32_e32 v29, v28
	v_mov_b32_e32 v45, v44
	v_mov_b32_e32 v61, v60
	s_mov_b64 s[34:35], 0
	s_branch .LBB0_446

.LBB0_510:
	v_cvt_f32_i32_e32 v105, v105
	v_cvt_f32_i32_e32 v104, v104
	v_cvt_f32_i32_e32 v119, v108
	v_cvt_f32_i32_e32 v121, v118
	v_mul_f32_e32 v105, 0x39800000, v105
	v_mul_f32_e32 v105, 0.5, v105
	v_mul_f32_e32 v109, 0x39800000, v104
	v_sin_f32_e32 v104, v105
	v_cos_f32_e32 v202, v105
	v_mul_f32_e32 v109, 0.5, v109
	v_sin_f32_e32 v204, v109
	v_pk_mul_f32 v[206:207], v[106:107], v[104:105] op_sel:[1,0] op_sel_hi:[0,0]
	v_pk_fma_f32 v[104:105], v[106:107], v[202:203], v[206:207] op_sel_hi:[1,0,1]
	v_pk_fma_f32 v[106:107], v[106:107], v[202:203], v[206:207] op_sel_hi:[1,0,1] neg_lo:[0,0,1] neg_hi:[0,0,1]
	v_cos_f32_e32 v202, v109
	v_pk_mul_f32 v[204:205], v[112:113], v[204:205] op_sel:[1,0] op_sel_hi:[0,0]
	v_cvt_f32_i32_e32 v117, v117
	v_cvt_f32_i32_e32 v183, v120
	v_pk_fma_f32 v[108:109], v[112:113], v[202:203], v[204:205] op_sel_hi:[1,0,1]
	v_pk_fma_f32 v[112:113], v[112:113], v[202:203], v[204:205] op_sel_hi:[1,0,1] neg_lo:[0,0,1] neg_hi:[0,0,1]
	v_mul_f32_e32 v109, 0x39800000, v119
	v_mul_f32_e32 v109, 0.5, v109
	v_sin_f32_e32 v112, v109
	v_cos_f32_e32 v202, v109
	v_cvt_f32_i32_e32 v179, v179
	s_nop 0
	v_pk_mul_f32 v[204:205], v[114:115], v[112:113] op_sel:[1,0] op_sel_hi:[0,0]
	v_pk_fma_f32 v[118:119], v[114:115], v[202:203], v[204:205]
	v_pk_fma_f32 v[114:115], v[114:115], v[202:203], v[204:205] op_sel_hi:[1,0,1] neg_lo:[0,0,1] neg_hi:[0,0,1]
	v_mul_f32_e32 v112, 0x39800000, v121
	v_mul_f32_e32 v114, 0.5, v112
	v_sin_f32_e32 v112, v114
	v_cos_f32_e32 v202, v114
	v_mov_b32_e32 v119, v115
	v_cvt_f32_i32_e32 v121, v116
	v_pk_mul_f32 v[204:205], v[102:103], v[112:113] op_sel:[1,0] op_sel_hi:[0,0]
	v_pk_fma_f32 v[114:115], v[102:103], v[202:203], v[204:205] op_sel_hi:[1,0,1]
	v_mul_f32_e32 v112, 0x39800000, v117
	v_mul_f32_e32 v115, 0.5, v112
	v_sin_f32_e32 v112, v115
	v_pk_fma_f32 v[102:103], v[102:103], v[202:203], v[204:205] op_sel_hi:[1,0,1] neg_lo:[0,0,1] neg_hi:[0,0,1]
	v_cos_f32_e32 v202, v115
	s_nop 0
	v_pk_mul_f32 v[204:205], v[100:101], v[112:113] op_sel:[1,0] op_sel_hi:[0,0]
	v_mov_b32_e32 v115, v103
	v_pk_fma_f32 v[116:117], v[100:101], v[202:203], v[204:205] op_sel_hi:[1,0,1]
	v_pk_fma_f32 v[100:101], v[100:101], v[202:203], v[204:205] op_sel_hi:[1,0,1] neg_lo:[0,0,1] neg_hi:[0,0,1]
	v_pk_mov_b32 v[102:103], v[102:103], v[116:117] op_sel:[1,0]
	v_mul_f32_e32 v100, 0x39800000, v121
	v_mul_f32_e32 v100, 0.5, v100
	v_sin_f32_e32 v112, v100
	v_cos_f32_e32 v202, v100
	s_nop 0
	s_mov_b32 s0, s71
	v_pk_mul_f32 v[204:205], v[98:99], v[112:113] op_sel:[1,0] op_sel_hi:[0,0]
	v_pk_fma_f32 v[120:121], v[98:99], v[202:203], v[204:205] op_sel_hi:[1,0,1]
	v_pk_fma_f32 v[98:99], v[98:99], v[202:203], v[204:205] op_sel_hi:[1,0,1] neg_lo:[0,0,1] neg_hi:[0,0,1]
	v_cvt_f32_i32_e32 v204, v182
	v_mul_f32_e32 v98, 0x39800000, v183
	v_mul_f32_e32 v112, 0.5, v98
	v_sin_f32_e32 v98, v112
	v_cos_f32_e32 v112, v112
	s_nop 0
	s_mov_b32 s1, s21
	v_pk_mul_f32 v[182:183], v[96:97], v[98:99] op_sel:[1,0] op_sel_hi:[0,0]
	v_pk_fma_f32 v[202:203], v[96:97], v[112:113], v[182:183]
	v_pk_fma_f32 v[96:97], v[96:97], v[112:113], v[182:183] op_sel_hi:[1,0,1] neg_lo:[0,0,1] neg_hi:[0,0,1]
	v_cvt_f32_i32_e32 v112, v181
	v_mul_f32_e32 v96, 0x39800000, v204
	v_mul_f32_e32 v98, 0.5, v96
	v_sin_f32_e32 v96, v98
	v_cos_f32_e32 v98, v98
	v_mov_b32_e32 v203, v97
	v_cvt_f32_i32_e32 v204, v180
	v_pk_mul_f32 v[182:183], v[94:95], v[96:97] op_sel:[1,0] op_sel_hi:[0,0]
	v_pk_fma_f32 v[96:97], v[94:95], v[98:99], v[182:183] op_sel_hi:[1,0,1]
	v_pk_fma_f32 v[94:95], v[94:95], v[98:99], v[182:183] op_sel_hi:[1,0,1] neg_lo:[0,0,1] neg_hi:[0,0,1]
	v_mul_f32_e32 v97, 0x39800000, v112
	v_mul_f32_e32 v97, 0.5, v97
	v_sin_f32_e32 v98, v97
	v_cos_f32_e32 v112, v97
	v_mov_b32_e32 v97, v95
	s_mov_b32 s22, s21
	v_pk_mul_f32 v[180:181], v[92:93], v[98:99] op_sel:[1,0] op_sel_hi:[0,0]
	v_pk_fma_f32 v[182:183], v[92:93], v[112:113], v[180:181] op_sel_hi:[1,0,1]
	v_pk_fma_f32 v[92:93], v[92:93], v[112:113], v[180:181] op_sel_hi:[1,0,1] neg_lo:[0,0,1] neg_hi:[0,0,1]
	v_pk_mov_b32 v[94:95], v[94:95], v[182:183] op_sel:[1,0]
	v_mul_f32_e32 v92, 0x39800000, v204
	v_mul_f32_e32 v92, 0.5, v92
	v_sin_f32_e32 v98, v92
	v_cos_f32_e32 v112, v92
	s_nop 0
	v_add_f32_e32 v220, v182, v104
	v_add_f32_e32 v221, v93, v107
	v_pk_mul_f32 v[180:181], v[90:91], v[98:99] op_sel:[1,0] op_sel_hi:[0,0]
	v_pk_fma_f32 v[204:205], v[90:91], v[112:113], v[180:181] op_sel_hi:[1,0,1]
	v_pk_fma_f32 v[180:181], v[90:91], v[112:113], v[180:181] op_sel_hi:[1,0,1] neg_lo:[0,0,1] neg_hi:[0,0,1]
	v_mul_f32_e32 v90, 0x39800000, v179
	v_mul_f32_e32 v91, 0.5, v90
	v_sin_f32_e32 v90, v91
	v_cos_f32_e32 v98, v91
	v_cvt_f32_i32_e32 v112, v177
	s_nop 0
	v_pk_mul_f32 v[90:91], v[88:89], v[90:91] op_sel:[1,0] op_sel_hi:[0,0]
	v_pk_fma_f32 v[206:207], v[88:89], v[98:99], v[90:91]
	v_pk_fma_f32 v[88:89], v[88:89], v[98:99], v[90:91] op_sel_hi:[1,0,1] neg_lo:[0,0,1] neg_hi:[0,0,1]
	v_cvt_f32_i32_e32 v91, v176
	v_mul_f32_e32 v88, 0x39800000, v112
	v_mul_f32_e32 v90, 0.5, v88
	v_sin_f32_e32 v88, v90
	v_cos_f32_e32 v90, v90
	v_mov_b32_e32 v207, v89
	v_pk_add_f32 v[216:217], v[206:207], v[118:119]
	v_pk_mul_f32 v[88:89], v[86:87], v[88:89] op_sel:[1,0] op_sel_hi:[0,0]
	v_pk_fma_f32 v[176:177], v[86:87], v[90:91], v[88:89] op_sel_hi:[1,0,1]
	v_pk_fma_f32 v[208:209], v[86:87], v[90:91], v[88:89] op_sel_hi:[1,0,1] neg_lo:[0,0,1] neg_hi:[0,0,1]
	v_mul_f32_e32 v86, 0x39800000, v91
	v_mul_f32_e32 v87, 0.5, v86
	v_sin_f32_e32 v86, v87
	v_cos_f32_e32 v88, v87
	v_cvt_f32_i32_e32 v89, v175
	v_mov_b32_e32 v177, v209
	v_pk_mul_f32 v[86:87], v[84:85], v[86:87] op_sel:[1,0] op_sel_hi:[0,0]
	v_pk_add_f32 v[224:225], v[176:177], v[114:115]
	v_pk_fma_f32 v[210:211], v[84:85], v[88:89], v[86:87] op_sel_hi:[1,0,1]
	v_pk_fma_f32 v[212:213], v[84:85], v[88:89], v[86:87] op_sel_hi:[1,0,1] neg_lo:[0,0,1] neg_hi:[0,0,1]
	v_mul_f32_e32 v84, 0x39800000, v89
	v_mul_f32_e32 v85, 0.5, v84
	v_sin_f32_e32 v84, v85
	v_cos_f32_e32 v86, v85
	v_cvt_f32_i32_e32 v87, v174
	s_nop 0
	v_pk_mul_f32 v[84:85], v[4:5], v[84:85] op_sel:[1,0] op_sel_hi:[0,0]
	v_add_f32_e32 v218, v210, v116
	v_add_f32_e32 v219, v213, v101
	v_pk_fma_f32 v[174:175], v[4:5], v[86:87], v[84:85] op_sel_hi:[1,0,1]
	v_mul_f32_e32 v87, 0x39800000, v87
	v_mul_f32_e32 v87, 0.5, v87
	v_pk_fma_f32 v[214:215], v[4:5], v[86:87], v[84:85] op_sel_hi:[1,0,1] neg_lo:[0,0,1] neg_hi:[0,0,1]
	v_mov_b32_e32 v5, v127
	v_sin_f32_e32 v88, v87
	v_cos_f32_e32 v4, v87
	v_cvt_f32_i32_e32 v5, v5
	v_pk_mul_f32 v[84:85], v[2:3], v[88:89] op_sel:[1,0] op_sel_hi:[0,0]
	s_barrier
	v_pk_fma_f32 v[88:89], v[2:3], v[4:5], v[84:85]
	v_pk_fma_f32 v[2:3], v[2:3], v[4:5], v[84:85] op_sel_hi:[1,0,1] neg_lo:[0,0,1] neg_hi:[0,0,1]
	s_nop 0
	v_mul_f32_e32 v2, 0x39800000, v5
	v_mov_b32_e32 v89, v3
	v_mul_f32_e32 v3, 0.5, v2
	v_sin_f32_e32 v2, v3
	v_cos_f32_e32 v4, v3
	v_mov_b32_e32 v3, v78
	s_nop 0
	v_ashrrev_i32_e32 v84, 31, v3
	v_lshrrev_b32_e32 v84, 24, v84
	v_and_b32_e32 v5, 0xff, v3
	v_add_lshl_u32 v3, v3, v84, 4
	v_and_or_b32 v3, v3, s87, v5
	v_ashrrev_i32_e32 v84, 4, v3
	v_lshlrev_b32_e32 v3, 3, v3
	v_lshl_add_u32 v179, v84, 3, v3
	v_pk_add_f32 v[90:91], v[88:89], v[202:203]
	v_cvt_f32_i32_e32 v3, v5
	v_add_f32_e32 v84, v174, v120
	v_add_f32_e32 v85, v215, v99
	v_add_f32_e32 v86, v204, v108
	v_add_f32_e32 v87, v181, v113
	v_pk_add_f32 v[202:203], v[88:89], v[202:203] neg_lo:[0,1] neg_hi:[0,1]
	v_add_f32_e32 v3, v3, v3
	v_mul_f32_e32 v3, 0x39800000, v3
	v_mul_f32_e32 v3, 0.5, v3
	v_sin_f32_e32 v100, v3
	v_cos_f32_e32 v230, v3
	v_pk_mul_f32 v[2:3], v[110:111], v[2:3] op_sel:[1,0] op_sel_hi:[0,0]
	v_pk_fma_f32 v[232:233], v[110:111], v[4:5], v[2:3] op_sel_hi:[1,0,1]
	v_pk_fma_f32 v[110:111], v[110:111], v[4:5], v[2:3] op_sel_hi:[1,0,1] neg_lo:[0,0,1] neg_hi:[0,0,1]
	v_pk_add_f32 v[226:227], v[84:85], v[86:87] neg_lo:[0,1] neg_hi:[0,1]
	v_mov_b32_e32 v233, v111
	v_pk_add_f32 v[234:235], v[96:97], v[232:233]
	v_pk_add_f32 v[2:3], v[90:91], v[216:217]
	v_pk_add_f32 v[4:5], v[84:85], v[86:87]
	v_pk_add_f32 v[84:85], v[218:219], v[220:221]
	v_pk_add_f32 v[86:87], v[224:225], v[234:235]
	v_pk_add_f32 v[236:237], v[2:3], v[84:85]
	v_pk_add_f32 v[238:239], v[4:5], v[86:87]
	v_pk_add_f32 v[88:89], v[206:207], v[118:119] neg_lo:[0,1] neg_hi:[0,1]
	v_pk_mul_f32 v[228:229], v[226:227], s[20:21] op_sel_hi:[1,0]
	v_pk_add_f32 v[240:241], v[236:237], v[238:239]
	v_pk_mov_b32 v[118:119], v[88:89], v[88:89] op_sel:[1,0]
	v_pk_add_f32 v[206:207], v[202:203], v[88:89] op_sel:[0,1] op_sel_hi:[1,0]
	v_pk_add_f32 v[88:89], v[202:203], v[88:89] op_sel:[0,1] op_sel_hi:[1,0] neg_lo:[0,1] neg_hi:[0,1]
	v_pk_fma_f32 v[226:227], v[226:227], s[20:21], v[228:229] op_sel:[0,0,1] op_sel_hi:[1,0,0]
	ds_write_b64 v179, v[240:241]
	v_mov_b32_e32 v207, v89
	v_mov_b32_e32 v89, v229
	v_mov_b32_e32 v241, v228
	v_mov_b32_e32 v229, v174
	v_sub_f32_e32 v121, v229, v120
	v_sub_f32_e32 v120, v210, v116
	v_sub_f32_e32 v112, v93, v107
	v_sub_f32_e32 v113, v181, v113
	v_mov_b32_e32 v180, v104
	v_pk_mov_b32 v[104:105], v[110:111], v[104:105] op_sel:[1,0]
	v_sub_f32_e32 v109, v204, v108
	v_sub_f32_e32 v108, v182, v180
	v_pk_mov_b32 v[174:175], v[208:209], v[210:211] op_sel:[1,0]
	v_mov_b32_e32 v97, v93
	v_mov_b32_e32 v233, v107
	v_sub_f32_e32 v106, v176, v114
	v_sub_f32_e32 v107, v213, v101
	v_pk_add_f32 v[94:95], v[94:95], v[104:105] neg_lo:[0,1] neg_hi:[0,1]
	v_pk_add_f32 v[102:103], v[174:175], v[102:103] neg_lo:[0,1] neg_hi:[0,1]
	v_pk_add_f32 v[92:93], v[96:97], v[232:233] neg_lo:[0,1] neg_hi:[0,1]
	v_pk_add_f32 v[104:105], v[106:107], v[94:95] neg_lo:[0,1] neg_hi:[0,1]
	v_sub_f32_e32 v98, v213, v101
	v_sub_f32_e32 v99, v215, v99
	v_pk_add_f32 v[96:97], v[102:103], v[92:93]
	v_pk_add_f32 v[106:107], v[106:107], v[94:95]
	v_mov_b32_e32 v94, v104
	v_mul_f32_e32 v104, 0x3ec3ef15, v104
	v_pk_add_f32 v[110:111], v[120:121], v[112:113] neg_lo:[0,1] neg_hi:[0,1]
	v_pk_add_f32 v[114:115], v[98:99], v[108:109]
	v_pk_add_f32 v[102:103], v[102:103], v[92:93] neg_lo:[0,1] neg_hi:[0,1]
	v_mul_f32_e32 v98, 0x3f6c835e, v96
	v_mov_b32_e32 v175, v203
	v_mov_b32_e32 v203, v104
	v_add_f32_e32 v104, v121, v113
	s_mov_b32 s23, s71
	v_mul_f32_e32 v116, 0x3ec3ef15, v111
	v_mul_f32_e32 v174, 0x3f6c835e, v115
	v_mul_f32_e32 v101, 0x3f3504f3, v97
	v_mov_b32_e32 v97, v103
	v_mov_b32_e32 v95, v107
	v_mov_b32_e32 v117, v119
	v_mov_b32_e32 v119, v98
	v_sub_f32_e32 v98, v99, v109
	v_pk_mul_f32 v[108:109], v[104:105], s[22:23] op_sel_hi:[0,1]
	v_pk_mul_f32 v[106:107], v[106:107], s[0:1] op_sel_hi:[0,1]
	v_mul_f32_e32 v120, 0x3f3504f3, v105
	v_pk_mul_f32 v[92:93], v[110:111], s[20:21]
	v_pk_mul_f32 v[110:111], v[96:97], s[72:73]
	v_pk_add_f32 v[96:97], v[174:175], v[116:117]
	v_pk_fma_f32 v[112:113], v[98:99], s[0:1], v[108:109] op_sel_hi:[0,1,1]
	v_pk_fma_f32 v[98:99], v[98:99], s[0:1], v[108:109] op_sel_hi:[0,1,1] neg_lo:[0,0,1] neg_hi:[0,0,1]
	v_pk_fma_f32 v[116:117], v[102:103], s[22:23], v[106:107]
	v_pk_fma_f32 v[102:103], v[102:103], s[22:23], v[106:107] op_sel_hi:[0,1,1] neg_lo:[0,0,1] neg_hi:[0,0,1]
	v_mov_b32_e32 v113, v99
	v_add_f32_e32 v98, v120, v101
	v_fma_f32 v99, v105, s20, -v101
	v_mov_b32_e32 v117, v103
	v_pk_add_f32 v[104:105], v[206:207], v[98:99]
	v_pk_add_f32 v[102:103], v[112:113], v[116:117]
	v_xor_b32_e32 v231, 0x80000000, v100
	v_pk_add_f32 v[106:107], v[104:105], v[102:103]
	v_pk_add_f32 v[224:225], v[224:225], v[234:235] neg_lo:[0,1] neg_hi:[0,1]
	v_pk_fma_f32 v[94:95], v[94:95], s[30:31], v[110:111] neg_lo:[0,0,1] neg_hi:[0,0,1]
	v_pk_add_f32 v[110:111], v[202:203], v[118:119] neg_lo:[0,1] neg_hi:[0,1]
	v_pk_mul_f32 v[118:119], v[100:101], v[106:107] op_sel_hi:[0,1]
	v_mul_f32_e32 v235, 0x3f3504f3, v224
	v_pk_fma_f32 v[120:121], v[230:231], v[106:107], v[118:119] op_sel:[0,0,1] op_sel_hi:[1,1,0]
	v_pk_fma_f32 v[106:107], v[230:231], v[106:107], v[118:119] op_sel:[0,0,1] op_sel_hi:[0,1,0] neg_lo:[0,0,1] neg_hi:[0,0,1]
	v_pk_add_f32 v[222:223], v[218:219], v[220:221] neg_lo:[0,1] neg_hi:[0,1]
	v_mul_f32_e32 v218, 0x3f3504f3, v225
	v_mov_b32_e32 v240, v216
	v_mov_b32_e32 v224, v219
	v_mov_b32_e32 v121, v107
	v_mov_b32_e32 v101, v230
	v_mul_f32_e32 v225, 0xbf3504f3, v225
	v_mov_b32_e32 v88, v90
	v_mov_b32_e32 v234, v221
	v_sub_f32_e32 v90, v218, v235
	v_sub_f32_e32 v91, v91, v217
	v_mov_b32_e32 v218, v226
	v_mov_b32_e32 v219, v222
	v_mul_f32_e32 v106, v100, v100
	v_mul_f32_e32 v107, v101, v231
	v_pk_add_f32 v[88:89], v[88:89], v[240:241] neg_lo:[0,1] neg_hi:[0,1]
	v_pk_add_f32 v[220:221], v[224:225], v[234:235] neg_lo:[0,1] neg_hi:[0,1]
	v_pk_add_f32 v[216:217], v[90:91], v[222:223] op_sel:[1,0] op_sel_hi:[0,1]
	v_pk_add_f32 v[222:223], v[90:91], v[218:219]
	v_pk_add_f32 v[218:219], v[90:91], v[218:219] neg_lo:[0,1] neg_hi:[0,1]
	v_pk_fma_f32 v[118:119], v[230:231], v[230:231], v[106:107] op_sel_hi:[0,1,1] neg_lo:[0,0,1] neg_hi:[0,0,1]
	v_pk_fma_f32 v[106:107], v[230:231], v[230:231], v[106:107] op_sel_hi:[0,1,1]
	v_mov_b32_e32 v223, v219
	v_pk_add_f32 v[224:225], v[88:89], v[220:221]
	v_pk_mov_b32 v[180:181], v[106:107], v[118:119] op_sel:[1,0]
	v_pk_add_f32 v[226:227], v[226:227], v[90:91] neg_lo:[0,1] neg_hi:[0,1]
	v_pk_add_f32 v[90:91], v[88:89], v[220:221] neg_lo:[0,1] neg_hi:[0,1]
	v_pk_add_f32 v[220:221], v[224:225], v[222:223]
	ds_write_b64 v179, v[120:121] offset:2176
	v_mov_b32_e32 v120, v118
	v_mov_b32_e32 v121, v107
	v_pk_mul_f32 v[180:181], v[106:107], v[180:181] op_sel:[1,0]
	v_pk_mul_f32 v[106:107], v[220:221], v[106:107] op_sel:[1,1] op_sel_hi:[0,1]
	v_pk_fma_f32 v[182:183], v[118:119], v[120:121], v[180:181] op_sel_hi:[0,1,1] neg_lo:[0,0,1] neg_hi:[0,0,1]
	v_pk_fma_f32 v[180:181], v[118:119], v[120:121], v[180:181] op_sel_hi:[0,1,1]
	v_pk_fma_f32 v[212:213], v[220:221], v[118:119], v[106:107] neg_lo:[0,0,1] neg_hi:[0,0,1]
	v_pk_fma_f32 v[106:107], v[220:221], v[118:119], v[106:107] op_sel_hi:[1,0,1]
	v_pk_mul_f32 v[118:119], v[120:121], v[180:181] op_sel:[0,1]
	v_mov_b32_e32 v213, v107
	v_pk_add_f32 v[98:99], v[206:207], v[98:99] neg_lo:[0,1] neg_hi:[0,1]
	v_pk_fma_f32 v[206:207], v[120:121], v[182:183], v[118:119] op_sel:[0,0,1] op_sel_hi:[1,0,0] neg_lo:[0,0,1] neg_hi:[0,0,1]
	v_pk_fma_f32 v[118:119], v[120:121], v[182:183], v[118:119] op_sel:[0,0,1] op_sel_hi:[1,0,0]
	v_pk_add_f32 v[88:89], v[216:217], v[226:227]
	ds_write_b64 v179, v[212:213] offset:4352
	v_mov_b32_e32 v213, v119
	v_sub_f32_e32 v216, v216, v226
	v_pk_mov_b32 v[118:119], v[118:119], v[206:207] op_sel:[1,0]
	v_mov_b32_e32 v212, v206
	v_pk_add_f32 v[214:215], v[90:91], v[90:91] op_sel:[0,1] op_sel_hi:[0,1]
	v_pk_mul_f32 v[118:119], v[216:217], v[118:119] op_sel_hi:[0,1]
	v_mov_b32_e32 v202, v182
	v_mov_b32_e32 v203, v181
	v_pk_fma_f32 v[206:207], v[214:215], v[206:207], v[118:119] neg_lo:[0,0,1] neg_hi:[0,0,1]
	v_pk_fma_f32 v[118:119], v[214:215], v[212:213], v[118:119]
	v_pk_mov_b32 v[210:211], v[180:181], v[182:183] op_sel:[1,0]
	v_mov_b32_e32 v207, v119
	v_pk_mul_f32 v[180:181], v[202:203], v[180:181] op_sel:[0,1]
	ds_write_b64 v179, v[206:207] offset:13056
	v_pk_fma_f32 v[206:207], v[182:183], v[202:203], v[180:181] op_sel:[0,0,1] op_sel_hi:[0,1,0] neg_lo:[0,0,1] neg_hi:[0,0,1]
	v_pk_fma_f32 v[180:181], v[182:183], v[202:203], v[180:181] op_sel:[0,0,1] op_sel_hi:[0,1,0]
	s_mov_b32 s70, s20
	v_mov_b32_e32 v231, v100
	v_pk_mov_b32 v[216:217], v[180:181], v[206:207] op_sel:[1,0]
	v_pk_fma_f32 v[92:93], v[114:115], s[70:71], v[92:93] neg_lo:[0,0,1] neg_hi:[0,0,1]
	v_pk_mul_f32 v[174:175], v[230:231], v[120:121]
	v_pk_mul_f32 v[176:177], v[100:101], v[120:121]
	v_pk_mul_f32 v[208:209], v[100:101], v[202:203]
	v_mov_b32_e32 v214, v206
	v_mov_b32_e32 v215, v181
	v_pk_mul_f32 v[100:101], v[100:101], v[216:217] op_sel_hi:[0,1]
	v_pk_add_f32 v[108:109], v[92:93], v[110:111]
	v_pk_add_f32 v[114:115], v[96:97], v[94:95]
	v_pk_mul_f32 v[204:205], v[230:231], v[202:203]
	v_pk_add_f32 v[106:107], v[112:113], v[116:117] neg_lo:[0,1] neg_hi:[0,1]
	v_pk_fma_f32 v[220:221], v[230:231], v[214:215], v[100:101] op_sel_hi:[0,1,1]
	v_pk_fma_f32 v[100:101], v[230:231], v[214:215], v[100:101] op_sel_hi:[0,1,1] neg_lo:[0,0,1] neg_hi:[0,0,1]
	v_mov_b32_e32 v230, v174
	v_mov_b32_e32 v231, v177
	v_pk_mov_b32 v[174:175], v[174:175], v[176:177] op_sel:[1,0]
	v_pk_add_f32 v[102:103], v[104:105], v[102:103] neg_lo:[0,1] neg_hi:[0,1]
	v_pk_add_f32 v[104:105], v[114:115], v[108:109]
	v_pk_add_f32 v[112:113], v[98:99], v[106:107] op_sel:[0,1] op_sel_hi:[1,0]
	v_pk_add_f32 v[98:99], v[98:99], v[106:107] op_sel:[0,1] op_sel_hi:[1,0] neg_lo:[0,1] neg_hi:[0,1]
	v_pk_add_f32 v[118:119], v[236:237], v[238:239] neg_lo:[0,1] neg_hi:[0,1]
	v_pk_add_f32 v[176:177], v[230:231], v[174:175]
	v_pk_add_f32 v[174:175], v[230:231], v[174:175] neg_lo:[0,1] neg_hi:[0,1]
	v_mov_b32_e32 v238, v204
	v_mov_b32_e32 v239, v209
	v_pk_mov_b32 v[204:205], v[204:205], v[208:209] op_sel:[1,0]
	v_pk_mov_b32 v[116:117], v[98:99], v[112:113] op_sel:[1,0]
	v_pk_mul_f32 v[232:233], v[104:105], v[174:175] op_sel:[0,1]
	v_pk_add_f32 v[208:209], v[238:239], v[204:205]
	v_pk_add_f32 v[204:205], v[238:239], v[204:205] neg_lo:[0,1] neg_hi:[0,1]
	v_pk_fma_f32 v[234:235], v[104:105], v[176:177], v[232:233] op_sel:[0,0,1] op_sel_hi:[1,1,0] neg_lo:[0,0,1] neg_hi:[0,0,1]
	v_pk_fma_f32 v[104:105], v[104:105], v[176:177], v[232:233] op_sel:[0,0,1] op_sel_hi:[1,0,0]
	v_pk_mul_f32 v[116:117], v[116:117], v[204:205] op_sel:[0,1]
	v_mov_b32_e32 v227, v101
	v_mov_b32_e32 v235, v105
	v_pk_mul_f32 v[104:105], v[202:203], v[174:175] op_sel:[0,1]
	v_mov_b32_e32 v239, v205
	v_pk_fma_f32 v[204:205], v[112:113], v[208:209], v[116:117] neg_lo:[0,0,1] neg_hi:[0,0,1]
	v_fma_f32 v106, v112, v208, v116
	v_fma_f32 v107, v99, v208, v117
	v_pk_mov_b32 v[100:101], v[100:101], v[220:221] op_sel:[1,0]
	v_mov_b32_e32 v226, v220
	v_mov_b32_e32 v231, v175
	v_pk_fma_f32 v[174:175], v[202:203], v[176:177], v[104:105] op_sel:[0,0,1] op_sel_hi:[1,0,0] neg_lo:[0,0,1] neg_hi:[0,0,1]
	v_pk_fma_f32 v[104:105], v[202:203], v[176:177], v[104:105] op_sel:[0,0,1] op_sel_hi:[1,0,0]
	v_mov_b32_e32 v205, v107
	v_pk_mul_f32 v[100:101], v[102:103], v[100:101] op_sel:[1,0]
	v_mov_b32_e32 v230, v176
	v_mov_b32_e32 v176, v174
	v_mov_b32_e32 v177, v105
	v_mov_b32_e32 v238, v208
	ds_write_b64 v179, v[204:205] offset:10880
	v_pk_fma_f32 v[204:205], v[102:103], v[220:221], v[100:101] neg_lo:[0,0,1] neg_hi:[0,0,1]
	v_pk_fma_f32 v[100:101], v[102:103], v[226:227], v[100:101] op_sel_hi:[0,1,1]
	v_pk_mul_f32 v[180:181], v[118:119], v[180:181] op_sel:[1,1] op_sel_hi:[0,1]
	v_pk_mul_f32 v[228:229], v[120:121], v[214:215]
	v_pk_mul_f32 v[120:121], v[120:121], v[216:217]
	ds_write_b64 v179, v[234:235] offset:6528
	v_pk_mul_f32 v[232:233], v[230:231], v[214:215]
	v_pk_mul_f32 v[234:235], v[202:203], v[214:215]
	v_pk_mul_f32 v[106:107], v[214:215], v[238:239]
	v_mov_b32_e32 v205, v101
	v_pk_mul_f32 v[100:101], v[214:215], v[212:213]
	v_pk_mul_f32 v[208:209], v[214:215], v[176:177]
	v_pk_fma_f32 v[214:215], v[118:119], v[206:207], v[180:181] neg_lo:[0,0,1] neg_hi:[0,0,1]
	v_pk_fma_f32 v[118:119], v[118:119], v[206:207], v[180:181] op_sel_hi:[1,0,1]
	v_mov_b32_e32 v215, v119
	v_sub_f32_e32 v118, v224, v222
	v_sub_f32_e32 v119, v219, v225
	v_pk_add_f32 v[120:121], v[120:121], v[120:121] op_sel:[0,1] op_sel_hi:[0,1]
	v_pk_mul_f32 v[120:121], v[118:119], v[120:121] op_sel:[1,0] op_sel_hi:[0,1]
	v_pk_add_f32 v[180:181], v[228:229], v[228:229] op_sel:[0,1] op_sel_hi:[0,1] neg_lo:[0,1] neg_hi:[0,1]
	ds_write_b64 v179, v[214:215] offset:17408
	ds_write_b64 v179, v[204:205] offset:19584
	v_pk_fma_f32 v[204:205], v[118:119], v[180:181], v[120:121] neg_lo:[0,0,1] neg_hi:[0,0,1]
	v_pk_fma_f32 v[118:119], v[118:119], v[180:181], v[120:121]
	v_pk_mul_f32 v[230:231], v[230:231], v[216:217]
	v_mov_b32_e32 v205, v119
	v_mov_b32_e32 v119, v115
	v_sub_f32_e32 v108, v108, v114
	v_sub_f32_e32 v109, v119, v109
	v_pk_add_f32 v[114:115], v[230:231], v[230:231] op_sel:[0,1] op_sel_hi:[0,1]
	v_pk_add_f32 v[2:3], v[2:3], v[84:85] neg_lo:[0,1] neg_hi:[0,1]
	v_pk_add_f32 v[4:5], v[4:5], v[86:87] neg_lo:[0,1] neg_hi:[0,1]
	v_pk_mul_f32 v[114:115], v[108:109], v[114:115] op_sel:[1,0] op_sel_hi:[0,1]
	v_pk_add_f32 v[118:119], v[232:233], v[232:233] op_sel:[0,1] op_sel_hi:[0,1] neg_lo:[0,1] neg_hi:[0,1]
	v_pk_add_f32 v[84:85], v[2:3], v[4:5] op_sel:[0,1] op_sel_hi:[1,0]
	v_pk_add_f32 v[2:3], v[2:3], v[4:5] op_sel:[0,1] op_sel_hi:[1,0] neg_lo:[0,1] neg_hi:[0,1]
	v_pk_fma_f32 v[120:121], v[108:109], v[118:119], v[114:115] neg_lo:[0,0,1] neg_hi:[0,0,1]
	v_pk_fma_f32 v[108:109], v[108:109], v[118:119], v[114:115]
	v_pk_mul_f32 v[86:87], v[2:3], v[210:211] op_sel:[1,0]
	v_pk_mul_f32 v[236:237], v[202:203], v[216:217]
	v_mov_b32_e32 v121, v109
	v_pk_fma_f32 v[108:109], v[84:85], v[182:183], v[86:87] neg_lo:[0,0,1] neg_hi:[0,0,1]
	v_pk_fma_f32 v[86:87], v[84:85], v[202:203], v[86:87] op_sel_hi:[0,1,1]
	v_mov_b32_e32 v5, v85
	v_mov_b32_e32 v109, v87
	v_pk_mov_b32 v[84:85], v[84:85], v[2:3] op_sel:[1,0]
	v_pk_add_f32 v[86:87], v[236:237], v[236:237] op_sel:[0,1] op_sel_hi:[0,1]
	v_mov_b32_e32 v4, v2
	v_pk_mul_f32 v[84:85], v[84:85], v[86:87]
	v_pk_add_f32 v[86:87], v[234:235], v[234:235] op_sel:[0,1] op_sel_hi:[0,1] neg_lo:[0,1] neg_hi:[0,1]
	v_pk_mul_f32 v[116:117], v[216:217], v[238:239]
	v_pk_fma_f32 v[2:3], v[2:3], v[86:87], v[84:85] neg_lo:[0,0,1] neg_hi:[0,0,1]
	v_pk_fma_f32 v[4:5], v[4:5], v[86:87], v[84:85]
	v_pk_add_f32 v[84:85], v[116:117], v[116:117] op_sel:[0,1] op_sel_hi:[0,1]
	v_mov_b32_e32 v3, v5
	v_pk_mov_b32 v[4:5], v[112:113], v[98:99] op_sel:[1,0]
	ds_write_b64 v179, v[2:3] offset:26112
	v_pk_mul_f32 v[4:5], v[4:5], v[84:85]
	v_pk_add_f32 v[84:85], v[106:107], v[106:107] op_sel:[0,1] op_sel_hi:[0,1] neg_lo:[0,1] neg_hi:[0,1]
	v_pk_fma_f32 v[86:87], v[98:99], v[84:85], v[4:5] neg_lo:[0,0,1] neg_hi:[0,0,1]
	v_fma_f32 v2, v98, v84, v4
	v_fma_f32 v3, v113, v85, v5
	v_pk_mul_f32 v[102:103], v[216:217], v[212:213]
	v_mov_b32_e32 v87, v3
	v_mov_b32_e32 v3, v100
	v_sub_f32_e32 v2, v90, v91
	v_sub_f32_e32 v3, v3, v101
	v_pk_add_f32 v[84:85], v[102:103], v[102:103] op_sel:[0,1] op_sel_hi:[0,1]
	v_mul_f32_e32 v4, v88, v84
	v_mul_f32_e32 v5, v2, v85
	v_pk_mov_b32 v[84:85], v[2:3], v[88:89] op_sel:[1,0]
	ds_write_b64 v179, v[86:87] offset:28288
	v_pk_fma_f32 v[86:87], v[2:3], v[84:85], v[4:5] neg_lo:[0,0,1] neg_hi:[0,0,1]
	v_pk_fma_f32 v[2:3], v[2:3], v[84:85], v[4:5]
	v_pk_mov_b32 v[4:5], v[110:111], v[94:95] op_sel:[1,0]
	v_mov_b32_e32 v87, v3
	v_pk_mov_b32 v[2:3], v[92:93], v[96:97] op_sel:[1,0]
	v_pk_add_f32 v[2:3], v[2:3], v[4:5] neg_lo:[0,1] neg_hi:[0,1]
	v_sub_f32_e32 v4, v110, v92
	v_sub_f32_e32 v5, v97, v95
	v_pk_mov_b32 v[104:105], v[104:105], v[174:175] op_sel:[1,0]
	v_pk_add_f32 v[84:85], v[4:5], v[2:3]
	v_pk_add_f32 v[2:3], v[4:5], v[2:3] neg_lo:[0,1] neg_hi:[0,1]
	ds_write_b64 v179, v[86:87] offset:30464
	v_pk_mul_f32 v[86:87], v[2:3], v[104:105] op_sel:[1,0]
	v_pk_mul_f32 v[212:213], v[216:217], v[176:177]
	v_pk_fma_f32 v[88:89], v[84:85], v[174:175], v[86:87] neg_lo:[0,0,1] neg_hi:[0,0,1]
	v_pk_fma_f32 v[86:87], v[84:85], v[176:177], v[86:87] op_sel_hi:[0,1,1]
	v_mov_b32_e32 v5, v85
	v_mov_b32_e32 v89, v87
	v_pk_mov_b32 v[84:85], v[84:85], v[2:3] op_sel:[1,0]
	v_pk_add_f32 v[86:87], v[212:213], v[212:213] op_sel:[0,1] op_sel_hi:[0,1]
	v_mov_b32_e32 v4, v2
	v_pk_mul_f32 v[84:85], v[84:85], v[86:87]
	v_pk_add_f32 v[86:87], v[208:209], v[208:209] op_sel:[0,1] op_sel_hi:[0,1] neg_lo:[0,1] neg_hi:[0,1]
	v_pk_fma_f32 v[2:3], v[2:3], v[86:87], v[84:85] neg_lo:[0,0,1] neg_hi:[0,0,1]
	v_pk_fma_f32 v[4:5], v[4:5], v[86:87], v[84:85]
	ds_write_b64 v179, v[204:205] offset:21760
	v_mov_b32_e32 v3, v5
	ds_write_b64 v179, v[2:3] offset:32640
	v_mov_b32_e32 v2, v78
	ds_write_b64 v179, v[120:121] offset:23936
	ds_write_b64 v179, v[108:109] offset:8704
	ds_write_b64 v179, v[88:89] offset:15232
	s_waitcnt lgkmcnt(0)
	s_barrier
	s_mov_b32 s2, s20
	v_ashrrev_i32_e32 v3, 31, v2
	v_lshrrev_b32_e32 v3, 28, v3
	v_and_b32_e32 v179, 15, v2
	v_add_u32_e32 v2, v2, v3
	v_ashrrev_i32_e32 v2, 4, v2
	v_lshlrev_b32_e32 v3, 11, v2
	v_lshl_add_u32 v2, v2, 7, v3
	v_lshl_or_b32 v242, v179, 3, v2
	ds_read2_b64 v[90:93], v242 offset1:17
	ds_read2_b64 v[94:97], v242 offset0:68 offset1:85
	ds_read2_b64 v[98:101], v242 offset0:136 offset1:153
	ds_read2_b64 v[102:105], v242 offset0:170 offset1:187
	ds_read2_b64 v[106:109], v242 offset0:204 offset1:221
	ds_read2_b64 v[110:113], v242 offset0:238 offset1:255
	ds_read2_b64 v[114:117], v242 offset0:34 offset1:51
	ds_read2_b64 v[118:121], v242 offset0:102 offset1:119
	s_waitcnt lgkmcnt(5)
	v_pk_add_f32 v[88:89], v[98:99], v[90:91]
	s_waitcnt lgkmcnt(2)
	v_pk_mov_b32 v[210:211], v[104:105], v[112:113] op_sel:[1,0]
	s_waitcnt lgkmcnt(1)
	v_pk_add_f32 v[206:207], v[116:117], v[104:105]
	s_waitcnt lgkmcnt(0)
	v_pk_add_f32 v[208:209], v[120:121], v[112:113]
	v_pk_mov_b32 v[86:87], v[116:117], v[120:121] op_sel:[1,0]
	v_mov_b32_e32 v105, v113
	v_pk_add_f32 v[112:113], v[206:207], v[208:209] neg_lo:[0,1] neg_hi:[0,1]
	v_pk_add_f32 v[210:211], v[86:87], v[210:211] neg_lo:[0,1] neg_hi:[0,1]
	v_pk_add_f32 v[86:87], v[206:207], v[208:209]
	v_mul_f32_e32 v206, 0x3f3504f3, v113
	v_mul_f32_e32 v209, 0xbf3504f3, v113
	v_cvt_f32_i32_e32 v113, v179
	v_mov_b32_e32 v117, v121
	v_pk_add_f32 v[104:105], v[116:117], v[104:105] neg_lo:[0,1] neg_hi:[0,1]
	v_pk_add_f32 v[98:99], v[90:91], v[98:99] neg_lo:[0,1] neg_hi:[0,1]
	v_add_f32_e32 v113, v113, v113
	v_pk_add_f32 v[90:91], v[94:95], v[106:107] neg_lo:[0,1] neg_hi:[0,1]
	v_pk_add_f32 v[174:175], v[106:107], v[94:95]
	v_pk_add_f32 v[176:177], v[92:93], v[100:101]
	v_pk_add_f32 v[180:181], v[96:97], v[108:109]
	v_pk_add_f32 v[116:117], v[104:105], v[104:105] op_sel:[0,1] op_sel_hi:[1,0] neg_lo:[0,1] neg_hi:[0,1]
	v_mul_f32_e32 v113, 0x3b800000, v113
	v_pk_mov_b32 v[94:95], v[90:91], v[90:91] op_sel:[1,0]
	v_pk_add_f32 v[106:107], v[98:99], v[90:91] op_sel:[0,1] op_sel_hi:[1,0]
	v_pk_add_f32 v[90:91], v[98:99], v[90:91] op_sel:[0,1] op_sel_hi:[1,0] neg_lo:[0,1] neg_hi:[0,1]
	v_pk_add_f32 v[104:105], v[104:105], v[104:105] op_sel:[0,1] op_sel_hi:[0,1]
	v_pk_add_f32 v[4:5], v[176:177], v[180:181]
	v_pk_add_f32 v[182:183], v[114:115], v[102:103]
	v_pk_add_f32 v[202:203], v[118:119], v[110:111]
	v_pk_add_f32 v[176:177], v[176:177], v[180:181] neg_lo:[0,1] neg_hi:[0,1]
	v_mul_f32_e32 v113, 0.5, v113
	v_mov_b32_e32 v107, v91
	v_pk_add_f32 v[90:91], v[210:211], v[210:211] op_sel:[0,1] op_sel_hi:[0,1] neg_lo:[0,1] neg_hi:[0,1]
	v_pk_mul_f32 v[104:105], v[104:105], s[0:1]
	v_pk_add_f32 v[84:85], v[182:183], v[202:203]
	v_pk_add_f32 v[204:205], v[182:183], v[202:203] neg_lo:[0,1] neg_hi:[0,1]
	v_pk_add_f32 v[120:121], v[210:211], v[210:211] op_sel:[0,1] op_sel_hi:[1,0]
	v_pk_mul_f32 v[180:181], v[176:177], s[20:21] op_sel_hi:[1,0]
	v_mul_f32_e32 v112, 0x3f3504f3, v112
	v_sin_f32_e32 v182, v113
	v_cos_f32_e32 v218, v113
	v_pk_fma_f32 v[210:211], v[90:91], s[22:23], v[104:105]
	v_pk_fma_f32 v[90:91], v[90:91], s[22:23], v[104:105] neg_lo:[0,0,1] neg_hi:[0,0,1]
	s_nop 0
	s_nop 0
	v_pk_add_f32 v[2:3], v[88:89], v[174:175]
	v_mov_b32_e32 v211, v91
	v_mov_b32_e32 v90, v88
	v_sub_f32_e32 v88, v206, v112
	v_sub_f32_e32 v89, v89, v175
	v_sub_f32_e32 v90, v90, v174
	v_sub_f32_e32 v91, v181, v180
	v_mov_b32_e32 v105, v112
	v_pk_add_f32 v[112:113], v[88:89], v[204:205] op_sel:[1,0] op_sel_hi:[0,1]
	v_mov_b32_e32 v175, v204
	v_sub_f32_e32 v104, v183, v203
	v_sub_f32_e32 v105, v209, v105
	v_sub_f32_e32 v204, v114, v102
	v_sub_f32_e32 v205, v92, v100
	v_sub_f32_e32 v206, v119, v111
	v_sub_f32_e32 v207, v97, v109
	v_mul_f32_e32 v179, 0x3f6c835e, v120
	v_mul_f32_e32 v220, 0x3ec3ef15, v116
	v_sub_f32_e32 v92, v115, v103
	v_sub_f32_e32 v93, v93, v101
	v_sub_f32_e32 v97, v96, v108
	v_sub_f32_e32 v96, v118, v110
	v_pk_add_f32 v[102:103], v[204:205], v[206:207] neg_lo:[0,1] neg_hi:[0,1]
	v_pk_fma_f32 v[176:177], v[176:177], s[20:21], v[180:181] op_sel:[0,0,1] op_sel_hi:[1,0,0]
	v_pk_add_f32 v[208:209], v[204:205], v[206:207]
	v_pk_add_f32 v[100:101], v[92:93], v[96:97] neg_lo:[0,1] neg_hi:[0,1]
	v_pk_add_f32 v[92:93], v[92:93], v[96:97]
	v_mov_b32_e32 v121, v102
	v_mov_b32_e32 v109, v99
	v_mov_b32_e32 v97, v95
	v_mov_b32_e32 v174, v176
	v_pk_add_f32 v[176:177], v[176:177], v[88:89] neg_lo:[0,1] neg_hi:[0,1]
	v_mul_f32_e32 v96, 0x3ec3ef15, v103
	v_pk_mul_f32 v[110:111], v[102:103], s[20:21]
	v_pk_mul_f32 v[102:103], v[120:121], s[72:73]
	v_mov_b32_e32 v117, v92
	v_sub_f32_e32 v94, v98, v94
	v_sub_f32_e32 v95, v220, v179
	v_pk_mul_f32 v[98:99], v[208:209], s[22:23] op_sel:[1,0]
	v_pk_add_f32 v[180:181], v[88:89], v[174:175]
	v_pk_add_f32 v[174:175], v[88:89], v[174:175] neg_lo:[0,1] neg_hi:[0,1]
	v_pk_add_f32 v[88:89], v[112:113], v[176:177]
	v_mul_f32_e32 v108, 0x3f6c835e, v93
	v_mul_f32_e32 v113, 0x3f3504f3, v208
	v_mul_f32_e32 v114, 0x3f3504f3, v100
	v_pk_fma_f32 v[110:111], v[92:93], s[70:71], v[110:111] neg_lo:[0,0,1] neg_hi:[0,0,1]
	v_pk_fma_f32 v[92:93], v[116:117], s[30:31], v[102:103] neg_lo:[0,0,1] neg_hi:[0,0,1]
	v_pk_fma_f32 v[102:103], v[100:101], s[0:1], v[98:99] op_sel:[1,0,0]
	v_pk_fma_f32 v[98:99], v[100:101], s[0:1], v[98:99] op_sel:[1,0,0] neg_lo:[0,0,1] neg_hi:[0,0,1]
	v_pk_add_f32 v[96:97], v[108:109], v[96:97]
	v_mov_b32_e32 v103, v99
	v_add_f32_e32 v98, v114, v113
	v_fma_f32 v99, v100, s20, -v113
	v_pk_add_f32 v[100:101], v[106:107], v[98:99]
	v_pk_add_f32 v[108:109], v[102:103], v[210:211]
	v_xor_b32_e32 v219, 0x80000000, v182
	v_pk_add_f32 v[114:115], v[108:109], v[100:101]
	v_pk_add_f32 v[212:213], v[2:3], v[84:85]
	v_pk_mul_f32 v[120:121], v[182:183], v[114:115] op_sel_hi:[0,1]
	v_pk_fma_f32 v[204:205], v[218:219], v[114:115], v[120:121] op_sel:[0,0,1] op_sel_hi:[1,1,0]
	v_pk_fma_f32 v[114:115], v[218:219], v[114:115], v[120:121] op_sel:[0,0,1] op_sel_hi:[0,1,0] neg_lo:[0,0,1] neg_hi:[0,0,1]
	v_mov_b32_e32 v205, v115
	v_mov_b32_e32 v183, v218
	v_pk_add_f32 v[214:215], v[4:5], v[86:87]
	v_mul_f32_e32 v114, v182, v182
	v_mul_f32_e32 v115, v183, v219
	v_pk_add_f32 v[216:217], v[214:215], v[212:213]
	v_pk_fma_f32 v[120:121], v[218:219], v[218:219], v[114:115] op_sel_hi:[0,1,1] neg_lo:[0,0,1] neg_hi:[0,0,1]
	v_pk_fma_f32 v[114:115], v[218:219], v[218:219], v[114:115] op_sel_hi:[0,1,1]
	v_mov_b32_e32 v181, v175
	v_pk_add_f32 v[202:203], v[90:91], v[104:105]
	ds_write2_b64 v242, v[216:217], v[204:205] offset1:17
	v_pk_mov_b32 v[216:217], v[114:115], v[120:121] op_sel:[1,0]
	v_pk_add_f32 v[90:91], v[90:91], v[104:105] neg_lo:[0,1] neg_hi:[0,1]
	v_pk_add_f32 v[104:105], v[202:203], v[180:181]
	v_mov_b32_e32 v204, v120
	v_mov_b32_e32 v205, v115
	v_pk_mul_f32 v[216:217], v[114:115], v[216:217] op_sel:[1,0]
	v_pk_mul_f32 v[114:115], v[104:105], v[114:115] op_sel:[1,1] op_sel_hi:[0,1]
	v_pk_fma_f32 v[220:221], v[120:121], v[204:205], v[216:217] op_sel_hi:[0,1,1] neg_lo:[0,0,1] neg_hi:[0,0,1]
	v_pk_fma_f32 v[216:217], v[120:121], v[204:205], v[216:217] op_sel_hi:[0,1,1]
	v_pk_fma_f32 v[230:231], v[104:105], v[120:121], v[114:115] neg_lo:[0,0,1] neg_hi:[0,0,1]
	v_pk_fma_f32 v[104:105], v[104:105], v[120:121], v[114:115] op_sel_hi:[1,0,1]
	v_pk_mul_f32 v[114:115], v[204:205], v[216:217] op_sel:[0,1]
	v_pk_add_f32 v[102:103], v[102:103], v[210:211] neg_lo:[0,1] neg_hi:[0,1]
	v_pk_fma_f32 v[120:121], v[204:205], v[220:221], v[114:115] op_sel:[0,0,1] op_sel_hi:[1,0,0] neg_lo:[0,0,1] neg_hi:[0,0,1]
	v_pk_fma_f32 v[114:115], v[204:205], v[220:221], v[114:115] op_sel:[0,0,1] op_sel_hi:[1,0,0]
	v_sub_f32_e32 v112, v112, v176
	v_mov_b32_e32 v211, v115
	v_pk_mov_b32 v[114:115], v[114:115], v[120:121] op_sel:[1,0]
	v_mov_b32_e32 v219, v182
	v_mov_b32_e32 v222, v220
	v_mov_b32_e32 v223, v217
	v_pk_add_f32 v[232:233], v[90:91], v[90:91] op_sel:[0,1] op_sel_hi:[0,1]
	v_pk_mul_f32 v[112:113], v[112:113], v[114:115] op_sel_hi:[0,1]
	v_pk_mul_f32 v[206:207], v[218:219], v[204:205]
	v_pk_mul_f32 v[208:209], v[182:183], v[204:205]
	v_mov_b32_e32 v210, v120
	v_pk_fma_f32 v[114:115], v[232:233], v[120:121], v[112:113] neg_lo:[0,0,1] neg_hi:[0,0,1]
	v_pk_mul_f32 v[120:121], v[222:223], v[216:217] op_sel:[0,1]
	v_pk_add_f32 v[100:101], v[100:101], v[108:109] neg_lo:[0,1] neg_hi:[0,1]
	v_pk_add_f32 v[108:109], v[110:111], v[94:95]
	v_pk_add_f32 v[116:117], v[96:97], v[92:93]
	v_pk_fma_f32 v[112:113], v[232:233], v[210:211], v[112:113]
	v_pk_fma_f32 v[176:177], v[220:221], v[222:223], v[120:121] op_sel:[0,0,1] op_sel_hi:[0,1,0] neg_lo:[0,0,1] neg_hi:[0,0,1]
	v_pk_fma_f32 v[120:121], v[220:221], v[222:223], v[120:121] op_sel:[0,0,1] op_sel_hi:[0,1,0]
	v_mov_b32_e32 v234, v206
	v_mov_b32_e32 v235, v209
	v_pk_mov_b32 v[206:207], v[206:207], v[208:209] op_sel:[1,0]
	v_pk_add_f32 v[118:119], v[108:109], v[116:117]
	v_mov_b32_e32 v115, v113
	v_pk_add_f32 v[112:113], v[212:213], v[214:215] neg_lo:[0,1] neg_hi:[0,1]
	v_pk_mov_b32 v[214:215], v[120:121], v[176:177] op_sel:[1,0]
	v_pk_add_f32 v[208:209], v[234:235], v[206:207]
	v_pk_add_f32 v[206:207], v[234:235], v[206:207] neg_lo:[0,1] neg_hi:[0,1]
	v_pk_mul_f32 v[224:225], v[218:219], v[222:223]
	v_pk_mul_f32 v[226:227], v[182:183], v[222:223]
	v_pk_add_f32 v[98:99], v[106:107], v[98:99] neg_lo:[0,1] neg_hi:[0,1]
	v_mov_b32_e32 v212, v176
	v_mov_b32_e32 v213, v121
	v_pk_mul_f32 v[182:183], v[182:183], v[214:215] op_sel_hi:[0,1]
	v_pk_mul_f32 v[236:237], v[118:119], v[206:207] op_sel:[0,1]
	v_pk_mov_b32 v[228:229], v[216:217], v[220:221] op_sel:[1,0]
	v_mov_b32_e32 v231, v105
	v_pk_add_f32 v[104:105], v[98:99], v[102:103] op_sel:[0,1] op_sel_hi:[1,0]
	v_pk_add_f32 v[98:99], v[98:99], v[102:103] op_sel:[0,1] op_sel_hi:[1,0] neg_lo:[0,1] neg_hi:[0,1]
	v_pk_fma_f32 v[216:217], v[218:219], v[212:213], v[182:183] op_sel_hi:[0,1,1]
	v_pk_fma_f32 v[182:183], v[218:219], v[212:213], v[182:183] op_sel_hi:[0,1,1] neg_lo:[0,0,1] neg_hi:[0,0,1]
	v_pk_fma_f32 v[238:239], v[118:119], v[208:209], v[236:237] op_sel:[0,0,1] op_sel_hi:[1,1,0] neg_lo:[0,0,1] neg_hi:[0,0,1]
	v_pk_fma_f32 v[118:119], v[118:119], v[208:209], v[236:237] op_sel:[0,0,1] op_sel_hi:[1,0,0]
	v_mov_b32_e32 v240, v224
	v_mov_b32_e32 v241, v227
	v_pk_mov_b32 v[224:225], v[224:225], v[226:227] op_sel:[1,0]
	v_pk_mov_b32 v[106:107], v[98:99], v[104:105] op_sel:[1,0]
	v_mov_b32_e32 v219, v183
	v_mov_b32_e32 v239, v119
	v_pk_mul_f32 v[118:119], v[222:223], v[206:207] op_sel:[0,1]
	v_pk_add_f32 v[226:227], v[240:241], v[224:225]
	v_pk_add_f32 v[224:225], v[240:241], v[224:225] neg_lo:[0,1] neg_hi:[0,1]
	v_pk_mov_b32 v[182:183], v[182:183], v[216:217] op_sel:[1,0]
	v_mov_b32_e32 v218, v216
	v_mov_b32_e32 v235, v207
	v_pk_fma_f32 v[206:207], v[222:223], v[208:209], v[118:119] op_sel:[0,0,1] op_sel_hi:[1,0,0] neg_lo:[0,0,1] neg_hi:[0,0,1]
	v_pk_fma_f32 v[118:119], v[222:223], v[208:209], v[118:119] op_sel:[0,0,1] op_sel_hi:[1,0,0]
	v_pk_mul_f32 v[106:107], v[106:107], v[224:225] op_sel:[0,1]
	v_pk_mul_f32 v[182:183], v[100:101], v[182:183] op_sel:[1,0]
	v_mov_b32_e32 v234, v208
	v_mov_b32_e32 v208, v206
	v_mov_b32_e32 v209, v119
	v_mov_b32_e32 v240, v226
	v_mov_b32_e32 v241, v225
	v_pk_fma_f32 v[224:225], v[104:105], v[226:227], v[106:107] neg_lo:[0,0,1] neg_hi:[0,0,1]
	v_fma_f32 v102, v104, v226, v106
	v_fma_f32 v103, v99, v226, v107
	v_pk_fma_f32 v[216:217], v[100:101], v[216:217], v[182:183] neg_lo:[0,0,1] neg_hi:[0,0,1]
	v_pk_fma_f32 v[100:101], v[100:101], v[218:219], v[182:183] op_sel_hi:[0,1,1]
	v_pk_mul_f32 v[120:121], v[112:113], v[120:121] op_sel:[1,1] op_sel_hi:[0,1]
	v_pk_mul_f32 v[232:233], v[204:205], v[212:213]
	v_pk_mul_f32 v[204:205], v[204:205], v[214:215]
	ds_write2_b64 v242, v[230:231], v[238:239] offset0:34 offset1:51
	v_pk_mul_f32 v[230:231], v[234:235], v[212:213]
	v_pk_mul_f32 v[234:235], v[234:235], v[214:215]
	v_pk_mul_f32 v[236:237], v[222:223], v[212:213]
	v_pk_mul_f32 v[238:239], v[222:223], v[214:215]
	v_mov_b32_e32 v225, v103
	v_pk_mul_f32 v[102:103], v[212:213], v[240:241]
	v_pk_mul_f32 v[106:107], v[214:215], v[240:241]
	v_mov_b32_e32 v217, v101
	v_pk_mul_f32 v[100:101], v[212:213], v[210:211]
	v_pk_mul_f32 v[182:183], v[214:215], v[210:211]
	v_pk_mul_f32 v[210:211], v[212:213], v[208:209]
	v_pk_mul_f32 v[212:213], v[214:215], v[208:209]
	v_pk_fma_f32 v[214:215], v[112:113], v[176:177], v[120:121] neg_lo:[0,0,1] neg_hi:[0,0,1]
	v_pk_fma_f32 v[112:113], v[112:113], v[176:177], v[120:121] op_sel_hi:[1,0,1]
	v_mov_b32_e32 v215, v113
	v_sub_f32_e32 v112, v202, v180
	v_sub_f32_e32 v113, v175, v203
	v_pk_add_f32 v[120:121], v[204:205], v[204:205] op_sel:[0,1] op_sel_hi:[0,1]
	v_pk_mul_f32 v[120:121], v[112:113], v[120:121] op_sel:[1,0] op_sel_hi:[0,1]
	v_pk_add_f32 v[174:175], v[232:233], v[232:233] op_sel:[0,1] op_sel_hi:[0,1] neg_lo:[0,1] neg_hi:[0,1]
	v_pk_fma_f32 v[176:177], v[112:113], v[174:175], v[120:121] neg_lo:[0,0,1] neg_hi:[0,0,1]
	v_pk_fma_f32 v[112:113], v[112:113], v[174:175], v[120:121]
	v_pk_add_f32 v[2:3], v[2:3], v[84:85] neg_lo:[0,1] neg_hi:[0,1]
	v_mov_b32_e32 v177, v113
	v_mov_b32_e32 v113, v117
	v_sub_f32_e32 v108, v108, v116
	v_sub_f32_e32 v109, v113, v109
	v_pk_add_f32 v[112:113], v[234:235], v[234:235] op_sel:[0,1] op_sel_hi:[0,1]
	v_pk_add_f32 v[4:5], v[4:5], v[86:87] neg_lo:[0,1] neg_hi:[0,1]
	v_pk_mul_f32 v[112:113], v[108:109], v[112:113] op_sel:[1,0] op_sel_hi:[0,1]
	v_pk_add_f32 v[116:117], v[230:231], v[230:231] op_sel:[0,1] op_sel_hi:[0,1] neg_lo:[0,1] neg_hi:[0,1]
	v_pk_add_f32 v[84:85], v[2:3], v[4:5] op_sel:[0,1] op_sel_hi:[1,0]
	v_pk_add_f32 v[2:3], v[2:3], v[4:5] op_sel:[0,1] op_sel_hi:[1,0] neg_lo:[0,1] neg_hi:[0,1]
	v_pk_fma_f32 v[120:121], v[108:109], v[116:117], v[112:113] neg_lo:[0,0,1] neg_hi:[0,0,1]
	v_pk_fma_f32 v[108:109], v[108:109], v[116:117], v[112:113]
	v_pk_mul_f32 v[86:87], v[2:3], v[228:229] op_sel:[1,0]
	v_mov_b32_e32 v121, v109
	v_pk_fma_f32 v[108:109], v[84:85], v[220:221], v[86:87] neg_lo:[0,0,1] neg_hi:[0,0,1]
	v_pk_fma_f32 v[86:87], v[84:85], v[222:223], v[86:87] op_sel_hi:[0,1,1]
	v_mov_b32_e32 v5, v85
	v_mov_b32_e32 v109, v87
	v_pk_mov_b32 v[84:85], v[84:85], v[2:3] op_sel:[1,0]
	v_pk_add_f32 v[86:87], v[238:239], v[238:239] op_sel:[0,1] op_sel_hi:[0,1]
	v_mov_b32_e32 v4, v2
	v_pk_mul_f32 v[84:85], v[84:85], v[86:87]
	v_pk_add_f32 v[86:87], v[236:237], v[236:237] op_sel:[0,1] op_sel_hi:[0,1] neg_lo:[0,1] neg_hi:[0,1]
	v_pk_fma_f32 v[2:3], v[2:3], v[86:87], v[84:85] neg_lo:[0,0,1] neg_hi:[0,0,1]
	v_pk_fma_f32 v[4:5], v[4:5], v[86:87], v[84:85]
	v_pk_mov_b32 v[84:85], v[104:105], v[98:99] op_sel:[1,0]
	v_pk_add_f32 v[86:87], v[106:107], v[106:107] op_sel:[0,1] op_sel_hi:[0,1]
	v_mov_b32_e32 v3, v5
	v_mov_b32_e32 v4, v98
	v_mov_b32_e32 v5, v105
	v_pk_mul_f32 v[84:85], v[84:85], v[86:87]
	v_pk_add_f32 v[86:87], v[102:103], v[102:103] op_sel:[0,1] op_sel_hi:[0,1] neg_lo:[0,1] neg_hi:[0,1]
	v_pk_fma_f32 v[98:99], v[98:99], v[86:87], v[84:85] neg_lo:[0,0,1] neg_hi:[0,0,1]
	v_pk_fma_f32 v[4:5], v[4:5], v[86:87], v[84:85]
	v_pk_add_f32 v[84:85], v[182:183], v[182:183] op_sel:[0,1] op_sel_hi:[0,1]
	v_mov_b32_e32 v99, v5
	ds_write2_b64 v242, v[2:3], v[98:99] offset0:204 offset1:221
	v_mov_b32_e32 v3, v100
	v_sub_f32_e32 v2, v90, v91
	v_sub_f32_e32 v3, v3, v101
	v_mul_f32_e32 v4, v88, v84
	v_mul_f32_e32 v5, v2, v85
	v_pk_mov_b32 v[84:85], v[2:3], v[88:89] op_sel:[1,0]
	v_pk_mov_b32 v[118:119], v[118:119], v[206:207] op_sel:[1,0]
	v_pk_fma_f32 v[86:87], v[2:3], v[84:85], v[4:5] neg_lo:[0,0,1] neg_hi:[0,0,1]
	v_pk_fma_f32 v[2:3], v[2:3], v[84:85], v[4:5]
	v_mov_b32_e32 v87, v3
	v_mov_b32_e32 v3, v96
	v_mov_b32_e32 v5, v92
	v_sub_f32_e32 v2, v94, v110
	v_sub_f32_e32 v3, v3, v5
	v_sub_f32_e32 v4, v111, v95
	v_sub_f32_e32 v5, v97, v93
	ds_write2_b64 v242, v[214:215], v[216:217] offset0:136 offset1:153
	v_pk_add_f32 v[84:85], v[4:5], v[2:3]
	v_pk_add_f32 v[88:89], v[2:3], v[4:5] neg_lo:[0,1] neg_hi:[0,1]
	v_sub_f32_e32 v2, v5, v3
	v_pk_mul_f32 v[2:3], v[2:3], v[118:119] op_sel_hi:[0,1]
	v_pk_fma_f32 v[4:5], v[84:85], v[206:207], v[2:3] neg_lo:[0,0,1] neg_hi:[0,0,1]
	v_pk_fma_f32 v[2:3], v[84:85], v[208:209], v[2:3] op_sel_hi:[0,1,1]
	v_mov_b32_e32 v5, v3
	ds_write2_b64 v242, v[114:115], v[4:5] offset0:102 offset1:119
	v_pk_mov_b32 v[2:3], v[84:85], v[88:89] op_sel:[1,0]
	v_pk_add_f32 v[4:5], v[212:213], v[212:213] op_sel:[0,1] op_sel_hi:[0,1]
	v_mov_b32_e32 v90, v88
	v_mov_b32_e32 v91, v85
	v_pk_mul_f32 v[2:3], v[2:3], v[4:5]
	v_pk_add_f32 v[4:5], v[210:211], v[210:211] op_sel:[0,1] op_sel_hi:[0,1] neg_lo:[0,1] neg_hi:[0,1]
	v_pk_fma_f32 v[84:85], v[88:89], v[4:5], v[2:3] neg_lo:[0,0,1] neg_hi:[0,0,1]
	v_pk_fma_f32 v[2:3], v[90:91], v[4:5], v[2:3]
	ds_write2_b64 v242, v[176:177], v[120:121] offset0:170 offset1:187
	v_mov_b32_e32 v85, v3
	v_mov_b32_e32 v2, v78
	ds_write2_b64 v242, v[108:109], v[224:225] offset0:68 offset1:85
	ds_write2_b64 v242, v[86:87], v[84:85] offset0:238 offset1:255
	s_waitcnt lgkmcnt(0)
	s_barrier
	s_mov_b32 s77, s71
	v_mul_lo_u32 v108, v2, s33
	ds_read2_b64 v[2:5], v108 offset1:1
	ds_read2_b64 v[84:87], v108 offset0:2 offset1:3
	ds_read2_b64 v[88:91], v108 offset0:9 offset1:10
	ds_read2_b64 v[92:95], v108 offset0:4 offset1:5
	ds_read2_b64 v[96:99], v108 offset0:6 offset1:7
	ds_read2_b64 v[100:103], v108 offset0:13 offset1:14
	ds_read2_b64 v[104:107], v108 offset0:8 offset1:15
	ds_read2_b64 v[108:111], v108 offset0:11 offset1:12
	s_waitcnt lgkmcnt(5)
	v_add_f32_e32 v112, v4, v88
	s_waitcnt lgkmcnt(3)
	s_waitcnt lgkmcnt(2)
	v_add_f32_e32 v114, v94, v100
	s_waitcnt lgkmcnt(1)
	v_pk_add_f32 v[202:203], v[2:3], v[104:105]
	v_pk_add_f32 v[2:3], v[2:3], v[104:105] neg_lo:[0,1] neg_hi:[0,1]
	s_waitcnt lgkmcnt(0)
	v_pk_add_f32 v[104:105], v[92:93], v[110:111]
	v_pk_add_f32 v[92:93], v[92:93], v[110:111] neg_lo:[0,1] neg_hi:[0,1]
	v_add_f32_e32 v113, v112, v114
	v_sub_f32_e32 v112, v112, v114
	v_pk_mov_b32 v[180:181], v[84:85], v[84:85] op_sel:[1,0]
	v_pk_add_f32 v[204:205], v[2:3], v[92:93] op_sel:[0,1] op_sel_hi:[1,0]
	v_pk_add_f32 v[206:207], v[2:3], v[92:93] op_sel:[0,1] op_sel_hi:[1,0] neg_lo:[0,1] neg_hi:[0,1]
	v_add_f32_e32 v114, v86, v108
	v_add_f32_e32 v115, v98, v106
	v_pk_mov_b32 v[182:183], v[96:97], v[96:97] op_sel:[1,0]
	v_mov_b32_e32 v205, v207
	v_mov_b32_e32 v211, v88
	v_add_f32_e32 v175, v5, v89
	v_add_f32_e32 v116, v87, v109
	v_add_f32_e32 v117, v99, v107
	v_mov_b32_e32 v118, v87
	v_mov_b32_e32 v120, v109
	v_add_f32_e32 v206, v85, v91
	v_add_f32_e32 v207, v84, v90
	v_mov_b32_e32 v85, v4
	v_mov_b32_e32 v210, v90
	v_sub_f32_e32 v4, v180, v91
	v_sub_f32_e32 v5, v5, v89
	v_mov_b32_e32 v91, v100
	v_add_f32_e32 v179, v95, v101
	v_sub_f32_e32 v86, v86, v108
	v_sub_f32_e32 v87, v99, v107
	v_pk_add_f32 v[84:85], v[84:85], v[210:211] neg_lo:[0,1] neg_hi:[0,1]
	v_add_f32_e32 v88, v97, v103
	v_add_f32_e32 v89, v96, v102
	v_mov_b32_e32 v97, v94
	v_mov_b32_e32 v90, v102
	v_sub_f32_e32 v94, v182, v103
	v_sub_f32_e32 v95, v95, v101
	v_mov_b32_e32 v119, v98
	v_mov_b32_e32 v121, v106
	v_pk_add_f32 v[106:107], v[86:87], v[86:87] op_sel_hi:[0,1] neg_lo:[0,1] neg_hi:[0,1]
	v_pk_add_f32 v[90:91], v[96:97], v[90:91] neg_lo:[0,1] neg_hi:[0,1]
	v_mov_b32_e32 v182, v86
	v_mov_b32_e32 v183, v84
	v_pk_mov_b32 v[86:87], v[86:87], v[94:95] op_sel:[1,0]
	v_pk_add_f32 v[118:119], v[118:119], v[120:121] neg_lo:[0,1] neg_hi:[0,1]
	v_pk_add_f32 v[102:103], v[84:85], v[94:95] neg_lo:[0,1] neg_hi:[0,1]
	v_pk_add_f32 v[180:181], v[4:5], v[90:91]
	v_pk_add_f32 v[86:87], v[182:183], v[86:87]
	v_mov_b32_e32 v183, v4
	v_sub_f32_e32 v4, v5, v91
	v_add_f32_e32 v84, v85, v95
	v_pk_add_f32 v[108:109], v[118:119], v[118:119] op_sel:[0,1] op_sel_hi:[1,0]
	v_mov_b32_e32 v182, v118
	v_pk_mov_b32 v[118:119], v[118:119], v[90:91] op_sel:[1,0]
	v_pk_mul_f32 v[90:91], v[4:5], s[0:1] op_sel_hi:[0,1]
	v_pk_mul_f32 v[84:85], v[84:85], s[22:23] op_sel_hi:[0,1]
	v_pk_add_f32 v[118:119], v[182:183], v[118:119] neg_lo:[0,1] neg_hi:[0,1]
	v_pk_mov_b32 v[182:183], v[92:93], v[84:85] op_sel:[1,0]
	v_sub_f32_e32 v174, v175, v179
	v_pk_add_f32 v[98:99], v[114:115], v[114:115] op_sel:[0,1] op_sel_hi:[1,0]
	v_sub_f32_e32 v114, v114, v115
	v_pk_mov_b32 v[110:111], v[92:93], v[92:93] op_sel:[1,0]
	v_add_f32_e32 v94, v2, v182
	v_add_f32_e32 v95, v90, v183
	v_pk_fma_f32 v[182:183], v[4:5], s[0:1], v[84:85] op_sel_hi:[0,1,1]
	v_pk_fma_f32 v[4:5], v[4:5], s[0:1], v[84:85] op_sel_hi:[0,1,1] neg_lo:[0,0,1] neg_hi:[0,0,1]
	v_mul_f32_e32 v115, 0x3f3504f3, v112
	v_mul_f32_e32 v121, 0x3f3504f3, v174
	v_mul_f32_e32 v176, 0x3f3504f3, v114
	v_mov_b32_e32 v183, v5
	v_mov_b32_e32 v4, v91
	v_mov_b32_e32 v5, v3
	v_pk_mov_b32 v[84:85], v[84:85], v[92:93] op_sel:[1,0]
	v_mul_f32_e32 v110, 0x3ec3ef15, v103
	v_mul_f32_e32 v90, 0x3f6c835e, v181
	v_mov_b32_e32 v91, v3
	v_pk_add_f32 v[4:5], v[4:5], v[84:85] neg_lo:[0,1] neg_hi:[0,1]
	v_sub_f32_e32 v84, v202, v104
	v_sub_f32_e32 v85, v121, v115
	v_pk_add_f32 v[90:91], v[90:91], v[110:111]
	v_pk_mul_f32 v[110:111], v[86:87], s[72:73]
	v_pk_mul_f32 v[114:115], v[86:87], s[74:75]
	v_pk_mul_f32 v[86:87], v[86:87], s[0:1] op_sel_hi:[0,1]
	v_pk_fma_f32 v[220:221], v[118:119], s[22:23], v[86:87]
	v_pk_fma_f32 v[86:87], v[118:119], s[22:23], v[86:87] op_sel_hi:[0,1,1] neg_lo:[0,0,1] neg_hi:[0,0,1]
	v_mov_b32_e32 v221, v87
	v_pk_add_f32 v[86:87], v[116:117], v[116:117] op_sel:[0,1] op_sel_hi:[0,1] neg_lo:[0,1] neg_hi:[0,1]
	v_pk_fma_f32 v[210:211], v[118:119], s[72:73], v[114:115] neg_lo:[0,0,1] neg_hi:[0,0,1]
	v_fmac_f32_e32 v115, 0x3f3504f3, v119
	v_pk_fma_f32 v[110:111], v[118:119], s[74:75], v[110:111]
	v_pk_mul_f32 v[118:119], v[86:87], s[2:3]
	v_mov_b32_e32 v177, v105
	v_mov_b32_e32 v214, v108
	v_sub_f32_e32 v222, v118, v176
	v_sub_f32_e32 v223, v203, v177
	v_mov_b32_e32 v225, v176
	v_pk_fma_f32 v[86:87], v[86:87], s[2:3], v[176:177] op_sel_hi:[1,1,0] neg_lo:[0,0,1] neg_hi:[0,0,1]
	v_pk_mul_f32 v[108:109], v[108:109], s[0:1] op_sel_hi:[0,1]
	v_pk_mul_f32 v[176:177], v[106:107], s[76:77]
	v_pk_mov_b32 v[96:97], v[202:203], v[206:207] op_sel:[1,0]
	v_pk_mov_b32 v[100:101], v[104:105], v[88:89] op_sel:[1,0]
	v_mov_b32_e32 v92, v93
	v_pk_add_f32 v[208:209], v[202:203], v[104:105] neg_lo:[0,1] neg_hi:[0,1]
	v_pk_add_f32 v[96:97], v[96:97], v[100:101]
	v_pk_add_f32 v[100:101], v[206:207], v[88:89] neg_lo:[0,1] neg_hi:[0,1]
	v_mov_b32_e32 v213, v107
	v_pk_mov_b32 v[218:219], v[106:107], v[180:181] op_sel:[1,0]
	v_sub_f32_e32 v2, v2, v92
	v_sub_f32_e32 v3, v177, v109
	v_pk_fma_f32 v[92:93], v[106:107], s[76:77], v[108:109] op_sel:[1,0,0] neg_lo:[0,0,1] neg_hi:[0,0,1]
	v_pk_mov_b32 v[106:107], v[206:207], v[116:117] op_sel:[1,0]
	v_mov_b32_e32 v116, v89
	v_fmamk_f32 v174, v112, 0x3f3504f3, v121
	v_mov_b32_e32 v215, v102
	v_mov_b32_e32 v118, v206
	v_mov_b32_e32 v224, v88
	v_add_f32_e32 v104, v202, v104
	v_add_f32_e32 v105, v175, v179
	v_pk_add_f32 v[88:89], v[106:107], v[116:117]
	v_pk_add_f32 v[116:117], v[208:209], v[100:101] neg_lo:[0,1] neg_hi:[0,1]
	v_pk_add_f32 v[176:177], v[208:209], v[100:101]
	v_mov_b32_e32 v175, v101
	v_pk_mul_f32 v[120:121], v[102:103], s[20:21]
	v_pk_mul_f32 v[102:103], v[214:215], s[74:75]
	v_pk_mul_f32 v[214:215], v[214:215], s[72:73]
	v_pk_add_f32 v[118:119], v[118:119], v[224:225] neg_lo:[0,1] neg_hi:[0,1]
	v_mov_b32_e32 v117, v177
	v_pk_add_f32 v[100:101], v[222:223], v[174:175]
	v_pk_add_f32 v[176:177], v[222:223], v[174:175] neg_lo:[0,1] neg_hi:[0,1]
	v_mov_b32_e32 v212, v180
	v_pk_fma_f32 v[216:217], v[180:181], s[70:71], v[120:121] neg_lo:[0,0,1] neg_hi:[0,0,1]
	v_pk_fma_f32 v[180:181], v[180:181], s[2:3], v[120:121] op_sel_hi:[0,1,0] neg_lo:[0,0,1] neg_hi:[0,0,1]
	v_mov_b32_e32 v121, v214
	v_add_f32_e32 v106, v96, v97
	v_add_f32_e32 v107, v105, v89
	v_mov_b32_e32 v112, v104
	v_mov_b32_e32 v108, v88
	v_pk_add_f32 v[88:89], v[104:105], v[88:89] neg_lo:[0,1] neg_hi:[0,1]
	v_pk_add_f32 v[104:105], v[182:183], v[220:221]
	v_mov_b32_e32 v101, v177
	v_pk_add_f32 v[182:183], v[84:85], v[118:119]
	s_mov_b32 s38, s71
	s_mov_b32 s39, s3
	v_pk_fma_f32 v[120:121], v[212:213], s[78:79], v[120:121] neg_lo:[0,0,1] neg_hi:[0,0,1]
	v_pk_fma_f32 v[212:213], v[218:219], s[30:31], v[214:215] neg_lo:[0,0,1] neg_hi:[0,0,1]
	v_mov_b32_e32 v109, v98
	v_add_f32_e32 v86, v174, v86
	v_add_f32_e32 v87, v85, v87
	v_pk_add_f32 v[100:101], v[182:183], v[100:101]
	v_mov_b32_e32 v183, v177
	v_mov_b32_e32 v114, v115
	v_mov_b32_e32 v115, v211
	v_pk_fma_f32 v[102:103], v[218:219], s[38:39], v[102:103] neg_lo:[0,0,1] neg_hi:[0,0,1]
	v_pk_add_f32 v[108:109], v[112:113], v[108:109]
	v_pk_add_f32 v[86:87], v[182:183], v[86:87] neg_lo:[0,1] neg_hi:[0,1]
	v_add_f32_e32 v176, v2, v180
	v_add_f32_e32 v177, v91, v181
	v_pk_add_f32 v[180:181], v[90:91], v[212:213]
	v_pk_add_f32 v[182:183], v[216:217], v[2:3]
	v_mov_b32_e32 v216, v90
	v_mov_b32_e32 v3, v90
	v_mov_b32_e32 v90, v217
	v_pk_add_f32 v[202:203], v[106:107], v[106:107] op_sel:[1,0] op_sel_hi:[1,0]
	v_mov_b32_e32 v112, v96
	v_pk_mov_b32 v[96:97], v[96:97], v[98:99] op_sel:[1,0]
	v_pk_add_f32 v[98:99], v[204:205], v[114:115]
	v_pk_add_f32 v[90:91], v[90:91], v[102:103] neg_lo:[0,1] neg_hi:[0,1]
	v_pk_add_f32 v[102:103], v[182:183], v[180:181]
	v_pk_add_f32 v[182:183], v[108:109], v[108:109] op_sel:[1,0] op_sel_hi:[1,0]
	v_pk_mul_f32 v[202:203], v[74:75], v[202:203]
	v_pk_add_f32 v[94:95], v[94:95], v[110:111] op_sel:[0,1] op_sel_hi:[1,0] neg_lo:[0,1] neg_hi:[0,1]
	v_pk_add_f32 v[110:111], v[104:105], v[98:99]
	v_pk_fma_f32 v[204:205], v[14:15], v[182:183], v[202:203] neg_lo:[0,0,1] neg_hi:[0,0,1]
	v_pk_fma_f32 v[182:183], v[14:15], v[182:183], v[202:203]
	v_pk_add_f32 v[96:97], v[112:113], v[96:97] neg_lo:[0,1] neg_hi:[0,1]
	v_mov_b32_e32 v205, v183
	v_pk_mul_f32 v[182:183], v[24:25], v[110:111] op_sel:[0,1] op_sel_hi:[1,0]
	v_pk_add_f32 v[4:5], v[4:5], v[210:211] neg_lo:[0,1] neg_hi:[0,1]
	v_pk_fma_f32 v[202:203], v[22:23], v[110:111], v[182:183] neg_lo:[0,0,1] neg_hi:[0,0,1]
	v_pk_fma_f32 v[110:111], v[22:23], v[110:111], v[182:183]
	v_pk_mul_f32 v[182:183], v[40:41], v[100:101] op_sel:[0,1] op_sel_hi:[1,0]
	v_pk_add_f32 v[98:99], v[98:99], v[104:105] neg_lo:[0,1] neg_hi:[0,1]
	v_pk_add_f32 v[104:105], v[4:5], v[94:95]
	v_pk_add_f32 v[112:113], v[4:5], v[94:95] neg_lo:[0,1] neg_hi:[0,1]
	v_pk_mov_b32 v[84:85], v[84:85], v[174:175] op_sel:[1,0]
	v_pk_mov_b32 v[118:119], v[118:119], v[222:223] op_sel:[1,0]
	v_pk_fma_f32 v[206:207], v[38:39], v[100:101], v[182:183] neg_lo:[0,0,1] neg_hi:[0,0,1]
	v_pk_fma_f32 v[100:101], v[38:39], v[100:101], v[182:183]
	v_pk_mul_f32 v[182:183], v[56:57], v[102:103] op_sel:[0,1] op_sel_hi:[1,0]
	v_pk_add_f32 v[210:211], v[96:97], v[96:97] op_sel:[0,1] op_sel_hi:[0,1] neg_lo:[0,1] neg_hi:[0,1]
	v_mov_b32_e32 v115, v113
	v_pk_add_f32 v[84:85], v[84:85], v[118:119] neg_lo:[0,1] neg_hi:[0,1]
	v_pk_fma_f32 v[208:209], v[54:55], v[102:103], v[182:183] neg_lo:[0,0,1] neg_hi:[0,0,1]
	v_pk_fma_f32 v[102:103], v[54:55], v[102:103], v[182:183]
	v_pk_add_f32 v[182:183], v[88:89], v[88:89] op_sel:[0,1] op_sel_hi:[0,1]
	v_pk_mul_f32 v[210:211], v[70:71], v[210:211]
	v_pk_mov_b32 v[112:113], v[112:113], v[104:105] op_sel:[1,0]
	v_mov_b32_e32 v114, v104
	v_pk_add_f32 v[118:119], v[116:117], v[84:85]
	v_pk_add_f32 v[84:85], v[116:117], v[84:85] neg_lo:[0,1] neg_hi:[0,1]
	v_pk_fma_f32 v[212:213], v[18:19], v[182:183], v[210:211] neg_lo:[0,0,1] neg_hi:[0,0,1]
	v_pk_fma_f32 v[182:183], v[18:19], v[182:183], v[210:211]
	v_pk_mul_f32 v[112:113], v[32:33], v[112:113]
	v_pk_add_f32 v[92:93], v[216:217], v[92:93]
	v_pk_add_f32 v[2:3], v[2:3], v[120:121] neg_lo:[0,1] neg_hi:[0,1]
	v_mov_b32_e32 v213, v183
	v_pk_fma_f32 v[182:183], v[30:31], v[114:115], v[112:113] neg_lo:[0,0,1] neg_hi:[0,0,1]
	v_pk_fma_f32 v[112:113], v[30:31], v[114:115], v[112:113]
	v_pk_mov_b32 v[114:115], v[84:85], v[118:119] op_sel:[1,0]
	v_pk_add_f32 v[92:93], v[176:177], v[92:93] neg_lo:[0,1] neg_hi:[0,1]
	v_pk_add_f32 v[120:121], v[90:91], v[2:3]
	v_pk_add_f32 v[176:177], v[90:91], v[2:3] neg_lo:[0,1] neg_hi:[0,1]
	v_pk_mul_f32 v[114:115], v[48:49], v[114:115]
	v_pk_add_f32 v[106:107], v[106:107], v[106:107] op_sel:[0,1] op_sel_hi:[0,1] neg_lo:[0,1] neg_hi:[0,1]
	v_fma_f32 v210, v46, v118, -v114
	v_fma_f32 v211, v47, v85, -v115
	v_fma_f32 v114, v46, v118, v114
	v_fma_f32 v115, v47, v85, v115
	v_pk_mov_b32 v[116:117], v[176:177], v[120:121] op_sel:[1,0]
	v_mov_b32_e32 v180, v120
	v_mov_b32_e32 v181, v177
	v_pk_mul_f32 v[116:117], v[64:65], v[116:117]
	v_pk_add_f32 v[108:109], v[108:109], v[108:109] op_sel:[0,1] op_sel_hi:[0,1] neg_lo:[0,1] neg_hi:[0,1]
	v_pk_mul_f32 v[106:107], v[76:77], v[106:107]
	v_pk_fma_f32 v[176:177], v[62:63], v[180:181], v[116:117] neg_lo:[0,0,1] neg_hi:[0,0,1]
	v_pk_fma_f32 v[116:117], v[62:63], v[180:181], v[116:117]
	v_pk_fma_f32 v[180:181], v[16:17], v[108:109], v[106:107] neg_lo:[0,0,1] neg_hi:[0,0,1]
	v_pk_fma_f32 v[106:107], v[16:17], v[108:109], v[106:107]
	v_pk_add_f32 v[4:5], v[94:95], v[4:5] neg_lo:[0,1] neg_hi:[0,1]
	v_mov_b32_e32 v181, v107
	v_pk_mul_f32 v[106:107], v[28:29], v[98:99] op_sel:[0,1] op_sel_hi:[1,0]
	v_pk_add_f32 v[96:97], v[96:97], v[96:97] op_sel:[1,0] op_sel_hi:[1,0]
	v_pk_fma_f32 v[108:109], v[26:27], v[98:99], v[106:107] neg_lo:[0,0,1] neg_hi:[0,0,1]
	v_pk_fma_f32 v[98:99], v[26:27], v[98:99], v[106:107]
	v_pk_mul_f32 v[106:107], v[44:45], v[86:87] op_sel:[0,1] op_sel_hi:[1,0]
	v_mov_b32_e32 v94, v4
	v_pk_add_f32 v[2:3], v[2:3], v[90:91] neg_lo:[0,1] neg_hi:[0,1]
	v_pk_fma_f32 v[214:215], v[42:43], v[86:87], v[106:107] neg_lo:[0,0,1] neg_hi:[0,0,1]
	v_pk_fma_f32 v[86:87], v[42:43], v[86:87], v[106:107]
	v_pk_mul_f32 v[106:107], v[60:61], v[92:93] op_sel:[0,1] op_sel_hi:[1,0]
	v_pk_add_f32 v[88:89], v[88:89], v[88:89] op_sel:[0,1] op_sel_hi:[0,1] neg_lo:[0,1] neg_hi:[0,1]
	v_pk_mul_f32 v[96:97], v[72:73], v[96:97]
	v_pk_mov_b32 v[4:5], v[104:105], v[4:5] op_sel:[1,0]
	v_mov_b32_e32 v95, v105
	v_mov_b32_e32 v174, v84
	v_mov_b32_e32 v90, v2
	v_pk_fma_f32 v[216:217], v[58:59], v[92:93], v[106:107] neg_lo:[0,0,1] neg_hi:[0,0,1]
	v_pk_fma_f32 v[92:93], v[58:59], v[92:93], v[106:107]
	v_pk_fma_f32 v[106:107], v[20:21], v[88:89], v[96:97] neg_lo:[0,0,1] neg_hi:[0,0,1]
	v_pk_fma_f32 v[88:89], v[20:21], v[88:89], v[96:97]
	v_pk_mul_f32 v[4:5], v[36:37], v[4:5]
	v_pk_mov_b32 v[84:85], v[118:119], v[84:85] op_sel:[1,0]
	v_pk_mov_b32 v[2:3], v[120:121], v[2:3] op_sel:[1,0]
	v_mov_b32_e32 v175, v119
	v_mov_b32_e32 v91, v121
	v_mov_b32_e32 v107, v89
	v_pk_fma_f32 v[88:89], v[34:35], v[94:95], v[4:5] neg_lo:[0,0,1] neg_hi:[0,0,1]
	v_pk_fma_f32 v[4:5], v[34:35], v[94:95], v[4:5]
	v_pk_mul_f32 v[84:85], v[52:53], v[84:85]
	v_pk_mul_f32 v[2:3], v[68:69], v[2:3]
	v_pk_fma_f32 v[94:95], v[50:51], v[174:175], v[84:85] neg_lo:[0,0,1] neg_hi:[0,0,1]
	v_pk_fma_f32 v[96:97], v[66:67], v[90:91], v[2:3] neg_lo:[0,0,1] neg_hi:[0,0,1]
	v_pk_fma_f32 v[2:3], v[66:67], v[90:91], v[2:3]
	v_mov_b32_e32 v4, v78
	v_mov_b32_e32 v177, v117
	v_pk_fma_f32 v[84:85], v[50:51], v[174:175], v[84:85]
	v_mov_b32_e32 v97, v3
	s_barrier
	v_add_f32_e32 v220, v206, v214
	v_add_f32_e32 v221, v101, v87
	v_add_f32_e32 v226, v208, v216
	v_add_f32_e32 v227, v103, v93
	v_mov_b32_e32 v110, v101
	v_mov_b32_e32 v209, v101
	v_mov_b32_e32 v217, v87
	v_pk_mov_b32 v[100:101], v[116:117], v[210:211] op_sel:[1,0]
	v_pk_mov_b32 v[2:3], v[2:3], v[94:95] op_sel:[1,0]
	v_mul_lo_u32 v179, v4, s33
	v_pk_add_f32 v[228:229], v[176:177], v[96:97]
	v_mov_b32_e32 v98, v87
	v_pk_mov_b32 v[102:103], v[102:103], v[206:207] op_sel:[1,0]
	v_pk_mov_b32 v[92:93], v[92:93], v[214:215] op_sel:[1,0]
	v_pk_add_f32 v[86:87], v[208:209], v[216:217] neg_lo:[0,1] neg_hi:[0,1]
	v_pk_add_f32 v[2:3], v[100:101], v[2:3] neg_lo:[0,1] neg_hi:[0,1]
	v_mov_b32_e32 v89, v5
	v_add_f32_e32 v120, v202, v108
	v_add_f32_e32 v121, v111, v99
	v_add_f32_e32 v222, v210, v94
	v_add_f32_e32 v223, v115, v85
	v_mov_b32_e32 v239, v202
	v_sub_f32_e32 v4, v115, v85
	v_sub_f32_e32 v5, v113, v5
	v_mov_b32_e32 v112, v94
	v_pk_add_f32 v[92:93], v[102:103], v[92:93] neg_lo:[0,1] neg_hi:[0,1]
	v_sub_f32_e32 v84, v176, v96
	v_sub_f32_e32 v85, v115, v85
	v_pk_add_f32 v[94:95], v[86:87], v[2:3]
	v_pk_add_f32 v[2:3], v[86:87], v[2:3] neg_lo:[0,1] neg_hi:[0,1]
	v_mov_b32_e32 v183, v113
	v_sub_f32_e32 v109, v239, v108
	v_sub_f32_e32 v108, v206, v214
	v_pk_add_f32 v[98:99], v[110:111], v[98:99] neg_lo:[0,1] neg_hi:[0,1]
	v_pk_add_f32 v[96:97], v[92:93], v[84:85] neg_lo:[0,1] neg_hi:[0,1]
	v_pk_add_f32 v[84:85], v[92:93], v[84:85]
	v_pk_add_f32 v[90:91], v[204:205], v[180:181]
	v_pk_add_f32 v[104:105], v[212:213], v[106:107]
	v_pk_add_f32 v[174:175], v[182:183], v[88:89]
	v_sub_f32_e32 v89, v182, v88
	v_sub_f32_e32 v88, v210, v112
	v_pk_add_f32 v[100:101], v[108:109], v[4:5]
	v_mul_f32_e32 v111, 0x3f3504f3, v95
	v_mul_f32_e32 v86, s74, v94
	v_mul_f32_e32 v87, s75, v3
	v_mov_b32_e32 v95, v96
	v_mul_f32_e32 v4, 0x3f6c835e, v96
	v_pk_add_f32 v[118:119], v[90:91], v[104:105]
	v_pk_add_f32 v[224:225], v[220:221], v[222:223]
	v_pk_add_f32 v[230:231], v[226:227], v[228:229]
	v_pk_add_f32 v[90:91], v[90:91], v[104:105] neg_lo:[0,1] neg_hi:[0,1]
	v_pk_add_f32 v[104:105], v[220:221], v[222:223] neg_lo:[0,1] neg_hi:[0,1]
	v_mov_b32_e32 v221, v226
	v_mov_b32_e32 v223, v228
	v_fma_f32 v86, v96, s72, -v86
	v_fma_f32 v87, v85, s73, -v87
	v_pk_fma_f32 v[92:93], v[94:95], s[80:81], v[4:5] op_sel_hi:[1,1,0] neg_lo:[0,0,1] neg_hi:[0,0,1]
	v_add_f32_e32 v4, v99, v89
	v_pk_add_f32 v[218:219], v[120:121], v[174:175]
	v_pk_add_f32 v[106:107], v[212:213], v[106:107] neg_lo:[0,1] neg_hi:[0,1]
	v_mov_b32_e32 v220, v120
	v_mov_b32_e32 v222, v174
	v_sub_f32_e32 v120, v121, v175
	v_sub_f32_e32 v121, v227, v229
	v_pk_add_f32 v[102:103], v[98:99], v[88:89] neg_lo:[0,1] neg_hi:[0,1]
	v_pk_mul_f32 v[88:89], v[4:5], s[0:1] op_sel_hi:[0,1]
	v_sub_f32_e32 v4, v109, v5
	v_pk_add_f32 v[180:181], v[204:205], v[180:181] neg_lo:[0,1] neg_hi:[0,1]
	v_pk_mov_b32 v[204:205], v[106:107], v[106:107] op_sel:[1,0]
	v_pk_add_f32 v[220:221], v[220:221], v[222:223] neg_lo:[0,1] neg_hi:[0,1]
	v_pk_mul_f32 v[120:121], v[120:121], s[20:21] op_sel_hi:[1,0]
	v_pk_fma_f32 v[98:99], v[4:5], s[22:23], v[88:89] op_sel_hi:[0,1,1] neg_lo:[0,0,1] neg_hi:[0,0,1]
	v_pk_fma_f32 v[4:5], v[4:5], s[22:23], v[88:89] op_sel_hi:[0,1,1]
	v_pk_fma_f32 v[174:175], v[220:221], s[2:3], v[120:121] neg_lo:[0,0,1] neg_hi:[0,0,1]
	v_pk_fma_f32 v[222:223], v[220:221], s[2:3], v[120:121]
	v_pk_fma_f32 v[120:121], v[220:221], s[20:21], v[120:121] op_sel_hi:[1,0,1] neg_lo:[0,0,1] neg_hi:[0,0,1]
	v_pk_add_f32 v[220:221], v[90:91], v[104:105] op_sel:[0,1] op_sel_hi:[1,0] neg_lo:[0,1] neg_hi:[0,1]
	v_pk_add_f32 v[90:91], v[90:91], v[104:105] op_sel:[0,1] op_sel_hi:[1,0]
	v_mul_f32_e32 v204, 0x3f6c835e, v103
	s_mov_b32 s38, s3
	s_mov_b32 s39, s21
	v_pk_mul_f32 v[102:103], v[102:103], s[70:71]
	v_mov_b32_e32 v99, v5
	v_pk_mul_f32 v[4:5], v[84:85], s[22:23] op_sel_hi:[0,1]
	v_pk_add_f32 v[212:213], v[180:181], v[106:107] op_sel:[0,1] op_sel_hi:[1,0] neg_lo:[0,1] neg_hi:[0,1]
	v_pk_add_f32 v[106:107], v[180:181], v[106:107] op_sel:[0,1] op_sel_hi:[1,0]
	v_mov_b32_e32 v105, v91
	v_mul_f32_e32 v180, 0x3ec3ef15, v101
	v_mul_f32_e32 v91, 0x3f3504f3, v97
	v_pk_fma_f32 v[112:113], v[100:101], s[38:39], v[102:103] neg_lo:[0,0,1] neg_hi:[0,0,1]
	v_pk_fma_f32 v[100:101], v[100:101], s[38:39], v[102:103]
	v_pk_fma_f32 v[84:85], v[2:3], s[0:1], v[4:5] neg_lo:[0,0,1] neg_hi:[0,0,1]
	v_pk_fma_f32 v[2:3], v[2:3], s[0:1], v[4:5] op_sel_hi:[0,1,1]
	v_mov_b32_e32 v213, v107
	v_pk_add_f32 v[94:95], v[180:181], v[204:205] neg_lo:[0,1] neg_hi:[0,1]
	v_sub_f32_e32 v110, v91, v111
	v_fmac_f32_e32 v111, 0x3f3504f3, v97
	v_mov_b32_e32 v85, v3
	v_pk_add_f32 v[232:233], v[118:119], v[224:225]
	v_pk_add_f32 v[234:235], v[218:219], v[230:231]
	v_pk_mov_b32 v[226:227], v[174:175], v[222:223] op_sel:[1,0]
	v_pk_add_f32 v[2:3], v[212:213], v[110:111]
	v_pk_add_f32 v[4:5], v[98:99], v[84:85]
	v_add_f32_e32 v96, v112, v106
	v_add_f32_e32 v97, v101, v92
	v_pk_add_f32 v[102:103], v[94:95], v[86:87]
	v_pk_add_f32 v[236:237], v[232:233], v[234:235]
	v_mov_b32_e32 v104, v220
	v_pk_add_f32 v[226:227], v[120:121], v[226:227]
	v_pk_add_f32 v[88:89], v[2:3], v[4:5]
	v_pk_add_f32 v[108:109], v[102:103], v[96:97]
	v_pk_add_f32 v[228:229], v[104:105], v[226:227]
	ds_write2_b64 v179, v[236:237], v[88:89] offset1:1
	ds_write2_b64 v179, v[228:229], v[108:109] offset0:2 offset1:3
	v_pk_add_f32 v[88:89], v[118:119], v[224:225] neg_lo:[0,1] neg_hi:[0,1]
	v_pk_add_f32 v[108:109], v[218:219], v[230:231] neg_lo:[0,1] neg_hi:[0,1]
	v_pk_add_f32 v[84:85], v[98:99], v[84:85] neg_lo:[0,1] neg_hi:[0,1]
	v_pk_add_f32 v[114:115], v[88:89], v[108:109] op_sel:[0,1] op_sel_hi:[1,0] neg_lo:[0,1] neg_hi:[0,1]
	v_pk_add_f32 v[88:89], v[88:89], v[108:109] op_sel:[0,1] op_sel_hi:[1,0]
	v_pk_add_f32 v[108:109], v[212:213], v[110:111] neg_lo:[0,1] neg_hi:[0,1]
	v_pk_add_f32 v[98:99], v[108:109], v[84:85] op_sel:[0,1] op_sel_hi:[1,0] neg_lo:[0,1] neg_hi:[0,1]
	v_pk_add_f32 v[84:85], v[108:109], v[84:85] op_sel:[0,1] op_sel_hi:[1,0]
	v_mov_b32_e32 v108, v114
	v_mov_b32_e32 v109, v89
	v_mov_b32_e32 v110, v98
	v_mov_b32_e32 v111, v85
	v_pk_mov_b32 v[100:101], v[100:101], v[94:95] op_sel:[1,0]
	v_mov_b32_e32 v93, v86
	ds_write2_b64 v179, v[108:109], v[110:111] offset0:4 offset1:5
	v_mov_b32_e32 v91, v221
	v_sub_f32_e32 v108, v222, v121
	v_sub_f32_e32 v109, v120, v175
	v_pk_add_f32 v[92:93], v[100:101], v[92:93] neg_lo:[0,1] neg_hi:[0,1]
	v_sub_f32_e32 v86, v106, v112
	v_sub_f32_e32 v87, v95, v87
	v_pk_add_f32 v[110:111], v[90:91], v[108:109] neg_lo:[0,1] neg_hi:[0,1]
	v_pk_add_f32 v[90:91], v[90:91], v[108:109]
	v_pk_add_f32 v[94:95], v[86:87], v[92:93] neg_lo:[0,1] neg_hi:[0,1]
	v_pk_add_f32 v[86:87], v[86:87], v[92:93]
	v_mov_b32_e32 v92, v110
	v_mov_b32_e32 v93, v91
	v_mov_b32_e32 v100, v94
	v_mov_b32_e32 v101, v87
	ds_write2_b64 v179, v[92:93], v[100:101] offset0:6 offset1:7
	v_pk_add_f32 v[92:93], v[232:233], v[234:235] neg_lo:[0,1] neg_hi:[0,1]
	v_pk_add_f32 v[2:3], v[2:3], v[4:5] neg_lo:[0,1] neg_hi:[0,1]
	v_mov_b32_e32 v5, v103
	ds_write2_b64 v179, v[92:93], v[2:3] offset0:8 offset1:9
	v_pk_add_f32 v[2:3], v[104:105], v[226:227] neg_lo:[0,1] neg_hi:[0,1]
	v_sub_f32_e32 v4, v96, v102
	v_sub_f32_e32 v5, v5, v97
	ds_write2_b64 v179, v[2:3], v[4:5] offset0:10 offset1:11
	v_mov_b32_e32 v89, v115
	v_mov_b32_e32 v85, v99
	v_mov_b32_e32 v91, v111
	v_mov_b32_e32 v87, v95
	v_mov_b32_e32 v2, v78
	ds_write2_b64 v179, v[88:89], v[84:85] offset0:12 offset1:13
	ds_write2_b64 v179, v[90:91], v[86:87] offset0:14 offset1:15
	s_waitcnt lgkmcnt(0)
	s_barrier
	s_nop 0
	v_ashrrev_i32_e32 v3, 31, v2
	v_lshrrev_b32_e32 v3, 28, v3
	v_and_b32_e32 v112, 15, v2
	v_add_u32_e32 v2, v2, v3
	v_ashrrev_i32_e32 v2, 4, v2
	v_lshlrev_b32_e32 v3, 11, v2
	v_lshl_add_u32 v2, v2, 7, v3
	v_lshl_or_b32 v179, v112, 3, v2
	ds_read2_b64 v[2:5], v179 offset1:17
	ds_read2_b64 v[84:87], v179 offset0:34 offset1:51
	ds_read2_b64 v[88:91], v179 offset0:68 offset1:85
	ds_read2_b64 v[92:95], v179 offset0:102 offset1:119
	ds_read2_b64 v[96:99], v179 offset0:136 offset1:153
	ds_read2_b64 v[100:103], v179 offset0:170 offset1:187
	ds_read2_b64 v[104:107], v179 offset0:204 offset1:221
	ds_read2_b64 v[108:111], v179 offset0:238 offset1:255
	s_waitcnt lgkmcnt(4)
	v_mov_b32_e32 v228, v92
	v_cvt_f32_i32_e32 v112, v112
	v_mov_b32_e32 v229, v91
	v_pk_mov_b32 v[90:91], v[92:93], v[90:91] op_sel:[1,0]
	v_add_f32_e32 v112, v112, v112
	v_mul_f32_e32 v112, 0x3b800000, v112
	v_mul_f32_e32 v112, 0.5, v112
	v_sin_f32_e32 v113, v112
	v_cos_f32_e32 v112, v112
	v_mul_f32_e32 v116, v113, v113
	v_mul_f32_e32 v114, v112, v113
	v_pk_fma_f32 v[116:117], v[112:113], v[112:113], v[116:117] op_sel_hi:[1,1,0] neg_lo:[0,0,1] neg_hi:[0,0,1]
	v_add_f32_e32 v114, v114, v114
	v_mov_b32_e32 v118, v116
	v_mov_b32_e32 v119, v112
	v_mov_b32_e32 v115, v113
	v_pk_mul_f32 v[120:121], v[118:119], v[116:117] op_sel_hi:[1,0]
	v_pk_mul_f32 v[176:177], v[114:115], v[116:117] op_sel_hi:[1,0]
	v_pk_fma_f32 v[204:205], v[114:115], v[114:115], v[120:121] op_sel_hi:[1,0,1] neg_lo:[1,0,0] neg_hi:[1,0,0]
	v_pk_fma_f32 v[180:181], v[118:119], v[114:115], v[176:177] op_sel_hi:[1,0,1]
	v_mov_b32_e32 v206, v204
	v_mov_b32_e32 v207, v112
	v_pk_mul_f32 v[174:175], v[118:119], v[114:115] op_sel_hi:[1,0]
	v_pk_mul_f32 v[208:209], v[206:207], v[204:205] op_sel_hi:[1,0]
	v_mov_b32_e32 v117, v204
	v_mul_f32_e32 v216, v114, v204
	v_mul_f32_e32 v217, v180, v204
	v_mul_f32_e32 v218, v180, v116
	v_mul_f32_e32 v219, v113, v117
	v_mul_f32_e32 v214, v180, v114
	v_mul_f32_e32 v215, v180, v180
	v_add_f32_e32 v174, v217, v217
	v_add_f32_e32 v175, v175, v177
	v_fma_f32 v176, v206, v114, v218
	v_fma_f32 v177, v207, v180, v219
	v_fma_f32 v120, -v180, v180, v208
	v_fma_f32 v121, -v113, v114, v121
	v_pk_mul_f32 v[202:203], v[204:205], v[180:181] op_sel:[0,1] op_sel_hi:[1,0]
	v_pk_mul_f32 v[218:219], v[180:181], v[204:205] op_sel:[0,1] op_sel_hi:[1,0]
	v_mul_f32_e32 v220, v180, v204
	v_mul_f32_e32 v221, v113, v204
	v_fma_f32 v182, -v180, v180, v208
	v_fma_f32 v183, -v113, v180, v209
	v_pk_fma_f32 v[208:209], v[204:205], v[116:117], v[214:215] op_sel_hi:[0,1,1] neg_lo:[0,0,1] neg_hi:[0,0,1]
	v_pk_fma_f32 v[214:215], v[116:117], v[180:181], v[216:217] op_sel_hi:[1,0,1]
	v_add_f32_e32 v202, v202, v218
	v_add_f32_e32 v203, v217, v217
	v_mov_b32_e32 v219, v112
	v_pk_mul_f32 v[212:213], v[180:181], v[180:181] op_sel_hi:[0,1]
	v_pk_fma_f32 v[206:207], v[206:207], v[180:181], v[220:221] op_sel_hi:[1,0,1]
	v_mul_f32_e32 v112, v215, v116
	v_mul_f32_e32 v113, v113, v182
	v_pk_fma_f32 v[212:213], v[204:205], v[204:205], v[212:213] op_sel_hi:[0,1,1] neg_lo:[0,0,1] neg_hi:[0,0,1]
	v_fma_f32 v112, v182, v114, v112
	v_fma_f32 v113, v219, v215, v113
	v_pk_mov_b32 v[220:221], v[214:215], v[180:181] op_sel:[1,0]
	v_pk_mul_f32 v[222:223], v[220:221], v[202:203]
	v_pk_mul_f32 v[220:221], v[220:221], v[212:213] op_sel:[0,1] op_sel_hi:[1,0]
	v_pk_mul_f32 v[206:207], v[206:207], v[208:209]
	v_fma_f32 v208, v182, v213, -v222
	v_fma_f32 v209, v204, v212, -v223
	v_fma_f32 v218, v182, v202, v220
	v_fma_f32 v219, v204, v203, v221
	v_mov_b32_e32 v220, v84
	v_mov_b32_e32 v221, v5
	v_pk_mov_b32 v[4:5], v[84:85], v[4:5] op_sel:[1,0]
	v_pk_mul_f32 v[210:211], v[114:115], v[180:181] op_sel_hi:[1,0]
	v_pk_mul_f32 v[216:217], v[114:115], v[214:215] op_sel:[0,1]
	v_pk_mul_f32 v[84:85], v[4:5], v[114:115]
	v_pk_mul_f32 v[114:115], v[220:221], v[114:115]
	v_mul_f32_e32 v174, v204, v174
	v_mul_f32_e32 v175, v182, v175
	v_pk_fma_f32 v[222:223], v[220:221], v[118:119], v[84:85] neg_lo:[0,0,1] neg_hi:[0,0,1]
	v_pk_fma_f32 v[84:85], v[220:221], v[118:119], v[84:85]
	v_pk_fma_f32 v[220:221], v[4:5], v[118:119], v[114:115] neg_lo:[0,0,1] neg_hi:[0,0,1]
	v_pk_fma_f32 v[4:5], v[4:5], v[118:119], v[114:115]
	v_pk_fma_f32 v[210:211], v[118:119], v[204:205], v[210:211] op_sel_hi:[1,0,1] neg_lo:[0,0,1] neg_hi:[0,0,1]
	v_pk_fma_f32 v[216:217], v[118:119], v[182:183], v[216:217] op_sel_hi:[1,0,1] neg_lo:[0,0,1] neg_hi:[0,0,1]
	v_fma_f32 v120, v180, v120, v174
	v_fma_f32 v121, v215, v121, v175
	v_pk_mul_f32 v[174:175], v[214:215], v[176:177] op_sel:[1,0]
	v_pk_mov_b32 v[114:115], v[220:221], v[4:5] op_sel:[1,0]
	v_mul_f32_e32 v220, v87, v181
	v_pk_mul_f32 v[92:93], v[90:91], v[176:177]
	v_pk_mul_f32 v[176:177], v[228:229], v[176:177]
	v_pk_fma_f32 v[174:175], v[182:183], v[210:211], v[174:175] op_sel_hi:[0,1,1] neg_lo:[0,0,1] neg_hi:[0,0,1]
	v_fma_f32 v118, v86, v205, -v220
	v_fma_f32 v119, v87, v181, -v220
	v_mov_b32_e32 v224, v88
	v_mov_b32_e32 v225, v87
	v_pk_mov_b32 v[86:87], v[88:89], v[86:87] op_sel:[1,0]
	v_pk_fma_f32 v[230:231], v[228:229], v[210:211], v[92:93] neg_lo:[0,0,1] neg_hi:[0,0,1]
	v_pk_fma_f32 v[92:93], v[228:229], v[210:211], v[92:93]
	v_pk_fma_f32 v[228:229], v[90:91], v[210:211], v[176:177] neg_lo:[0,0,1] neg_hi:[0,0,1]
	v_pk_fma_f32 v[90:91], v[90:91], v[210:211], v[176:177]
	v_mov_b32_e32 v211, v89
	v_pk_mov_b32 v[88:89], v[94:95], v[88:89] op_sel:[1,0]
	v_mov_b32_e32 v203, v180
	v_pk_mul_f32 v[88:89], v[88:89], v[202:203]
	v_mov_b32_e32 v203, v213
	v_mul_f32_e32 v92, v95, v213
	v_pk_mul_f32 v[116:117], v[180:181], v[214:215] op_sel:[0,1]
	v_pk_mul_f32 v[86:87], v[86:87], v[180:181]
	v_mov_b32_e32 v210, v94
	v_pk_fma_f32 v[94:95], v[94:95], v[202:203], v[92:93] op_sel_hi:[1,1,0]
	s_waitcnt lgkmcnt(2)
	v_mov_b32_e32 v202, v100
	v_mov_b32_e32 v203, v99
	v_pk_mov_b32 v[98:99], v[100:101], v[98:99] op_sel:[1,0]
	v_pk_fma_f32 v[116:117], v[204:205], v[182:183], v[116:117] op_sel_hi:[1,0,1] neg_lo:[0,0,1] neg_hi:[0,0,1]
	v_pk_fma_f32 v[226:227], v[224:225], v[204:205], v[86:87] neg_lo:[0,0,1] neg_hi:[0,0,1]
	v_pk_fma_f32 v[86:87], v[224:225], v[204:205], v[86:87]
	v_pk_mov_b32 v[204:205], v[212:213], v[204:205] op_sel:[1,0]
	v_pk_mul_f32 v[100:101], v[98:99], v[112:113]
	v_pk_mul_f32 v[112:113], v[202:203], v[112:113]
	v_pk_fma_f32 v[180:181], v[210:211], v[204:205], v[88:89] neg_lo:[0,0,1] neg_hi:[0,0,1]
	v_pk_fma_f32 v[88:89], v[210:211], v[204:205], v[88:89]
	v_pk_fma_f32 v[204:205], v[202:203], v[216:217], v[100:101] neg_lo:[0,0,1] neg_hi:[0,0,1]
	v_pk_fma_f32 v[100:101], v[202:203], v[216:217], v[100:101]
	v_pk_fma_f32 v[202:203], v[98:99], v[216:217], v[112:113] neg_lo:[0,0,1] neg_hi:[0,0,1]
	v_pk_fma_f32 v[98:99], v[98:99], v[216:217], v[112:113]
	v_pk_mov_b32 v[216:217], v[102:103], v[96:97] op_sel:[1,0]
	v_pk_mov_b32 v[212:213], v[116:117], v[182:183] op_sel:[1,0]
	v_mul_f32_e32 v216, v216, v121
	v_mul_f32_e32 v217, v217, v215
	v_pk_fma_f32 v[206:207], v[182:183], v[214:215], v[206:207]
	v_fma_f32 v232, v102, v212, -v216
	v_fma_f32 v233, v97, v213, -v217
	v_fma_f32 v210, v102, v212, v216
	v_fma_f32 v211, v97, v213, v217
	v_mov_b32_e32 v213, v103
	s_waitcnt lgkmcnt(1)
	v_pk_mov_b32 v[102:103], v[104:105], v[102:103] op_sel:[1,0]
	v_mov_b32_e32 v212, v104
	v_pk_mul_f32 v[102:103], v[102:103], v[120:121]
	v_pk_mov_b32 v[214:215], v[214:215], v[218:219] op_sel:[1,0]
	v_pk_fma_f32 v[120:121], v[212:213], v[116:117], v[102:103] neg_lo:[0,0,1] neg_hi:[0,0,1]
	v_pk_fma_f32 v[102:103], v[212:213], v[116:117], v[102:103]
	s_waitcnt lgkmcnt(0)
	v_mov_b32_e32 v212, v108
	v_mov_b32_e32 v213, v107
	v_pk_mov_b32 v[106:107], v[108:109], v[106:107] op_sel:[1,0]
	v_mov_b32_e32 v183, v208
	v_pk_mul_f32 v[108:109], v[106:107], v[206:207]
	v_pk_mul_f32 v[206:207], v[212:213], v[206:207]
	v_pk_fma_f32 v[216:217], v[212:213], v[174:175], v[108:109] neg_lo:[0,0,1] neg_hi:[0,0,1]
	v_pk_fma_f32 v[108:109], v[212:213], v[174:175], v[108:109]
	v_pk_fma_f32 v[212:213], v[106:107], v[174:175], v[206:207] neg_lo:[0,0,1] neg_hi:[0,0,1]
	v_pk_fma_f32 v[106:107], v[106:107], v[174:175], v[206:207]
	v_mov_b32_e32 v207, v105
	v_pk_mov_b32 v[104:105], v[110:111], v[104:105] op_sel:[1,0]
	v_mov_b32_e32 v206, v110
	v_pk_mul_f32 v[104:105], v[104:105], v[218:219]
	v_pk_fma_f32 v[234:235], v[206:207], v[208:209], v[104:105] neg_lo:[0,0,1] neg_hi:[0,0,1]
	v_pk_fma_f32 v[104:105], v[206:207], v[208:209], v[104:105]
	v_pk_mov_b32 v[206:207], v[96:97], v[110:111] op_sel:[1,0]
	v_mov_b32_e32 v97, v111
	v_pk_mul_f32 v[206:207], v[206:207], v[214:215]
	v_pk_fma_f32 v[110:111], v[96:97], v[182:183], v[206:207] neg_lo:[0,0,1] neg_hi:[0,0,1]
	v_pk_fma_f32 v[96:97], v[96:97], v[182:183], v[206:207]
	v_pk_mov_b32 v[176:177], v[228:229], v[90:91] op_sel:[1,0]
	v_pk_mov_b32 v[112:113], v[202:203], v[98:99] op_sel:[1,0]
	v_pk_mov_b32 v[174:175], v[212:213], v[106:107] op_sel:[1,0]
	v_mov_b32_e32 v111, v97
	v_add_f32_e32 v206, v118, v232
	v_add_f32_e32 v207, v3, v211
	v_mov_b32_e32 v119, v4
	v_mov_b32_e32 v233, v98
	v_mov_b32_e32 v95, v230
	v_pk_mov_b32 v[96:97], v[96:97], v[216:217] op_sel:[1,0]
	v_mov_b32_e32 v225, v87
	v_mov_b32_e32 v117, v103
	v_mov_b32_e32 v183, v94
	v_add_f32_e32 v208, v180, v234
	v_add_f32_e32 v209, v89, v105
	v_pk_add_f32 v[112:113], v[114:115], v[112:113]
	v_pk_add_f32 v[114:115], v[176:177], v[174:175]
	v_add_f32_e32 v174, v222, v204
	v_add_f32_e32 v175, v85, v101
	v_sub_f32_e32 v84, v4, v98
	v_sub_f32_e32 v85, v85, v101
	v_pk_mov_b32 v[86:87], v[86:87], v[222:223] op_sel:[1,0]
	v_pk_mov_b32 v[102:103], v[102:103], v[204:205] op_sel:[1,0]
	v_mov_b32_e32 v181, v90
	v_mov_b32_e32 v235, v106
	v_pk_add_f32 v[4:5], v[118:119], v[232:233] neg_lo:[0,1] neg_hi:[0,1]
	v_pk_add_f32 v[94:95], v[94:95], v[96:97] neg_lo:[0,1] neg_hi:[0,1]
	v_mov_b32_e32 v182, v2
	v_add_f32_e32 v176, v230, v216
	v_add_f32_e32 v177, v93, v109
	v_mov_b32_e32 v220, v222
	v_mov_b32_e32 v202, v204
	v_sub_f32_e32 v92, v90, v106
	v_sub_f32_e32 v93, v93, v109
	v_mov_b32_e32 v231, v229
	v_mov_b32_e32 v212, v216
	v_pk_add_f32 v[86:87], v[86:87], v[102:103] neg_lo:[0,1] neg_hi:[0,1]
	v_pk_add_f32 v[90:91], v[180:181], v[234:235] neg_lo:[0,1] neg_hi:[0,1]
	v_pk_add_f32 v[96:97], v[4:5], v[94:95]
	v_pk_add_f32 v[4:5], v[4:5], v[94:95] neg_lo:[0,1] neg_hi:[0,1]
	v_pk_add_f32 v[182:183], v[182:183], v[110:111]
	v_mov_b32_e32 v111, v211
	v_pk_mov_b32 v[88:89], v[88:89], v[226:227] op_sel:[1,0]
	v_pk_mov_b32 v[104:105], v[104:105], v[120:121] op_sel:[1,0]
	v_pk_add_f32 v[202:203], v[220:221], v[202:203] neg_lo:[0,1] neg_hi:[0,1]
	v_pk_add_f32 v[100:101], v[230:231], v[212:213] neg_lo:[0,1] neg_hi:[0,1]
	v_pk_add_f32 v[102:103], v[86:87], v[90:91] neg_lo:[0,1] neg_hi:[0,1]
	v_pk_add_f32 v[86:87], v[86:87], v[90:91]
	v_pk_add_f32 v[2:3], v[2:3], v[110:111] neg_lo:[0,1] neg_hi:[0,1]
	v_pk_add_f32 v[88:89], v[88:89], v[104:105] neg_lo:[0,1] neg_hi:[0,1]
	v_pk_add_f32 v[98:99], v[202:203], v[92:93]
	v_pk_add_f32 v[106:107], v[84:85], v[100:101] neg_lo:[0,1] neg_hi:[0,1]
	v_mul_f32_e32 v109, 0x3f3504f3, v97
	v_mul_f32_e32 v90, s74, v96
	v_mul_f32_e32 v91, s75, v5
	v_mov_b32_e32 v97, v102
	v_mul_f32_e32 v84, 0x3f6c835e, v102
	v_add_f32_e32 v116, v226, v120
	v_add_f32_e32 v117, v225, v117
	v_pk_add_f32 v[104:105], v[2:3], v[88:89] neg_lo:[0,1] neg_hi:[0,1]
	v_pk_add_f32 v[110:111], v[2:3], v[88:89]
	v_mul_f32_e32 v2, 0x3ec3ef15, v99
	v_mul_f32_e32 v88, 0x3f6c835e, v107
	v_fma_f32 v90, v102, s72, -v90
	v_fma_f32 v91, v87, s73, -v91
	v_pk_fma_f32 v[94:95], v[96:97], s[80:81], v[84:85] op_sel_hi:[1,1,0] neg_lo:[0,0,1] neg_hi:[0,0,1]
	v_add_f32_e32 v84, v85, v101
	v_pk_add_f32 v[2:3], v[2:3], v[88:89] neg_lo:[0,1] neg_hi:[0,1]
	v_pk_mul_f32 v[84:85], v[84:85], s[0:1] op_sel_hi:[0,1]
	v_sub_f32_e32 v88, v203, v93
	v_pk_add_f32 v[218:219], v[112:113], v[114:115]
	v_pk_add_f32 v[236:237], v[116:117], v[182:183]
	v_sub_f32_e32 v120, v182, v116
	v_sub_f32_e32 v121, v174, v176
	v_mov_b32_e32 v210, v113
	v_mov_b32_e32 v226, v115
	v_pk_fma_f32 v[92:93], v[88:89], s[22:23], v[84:85] op_sel_hi:[0,1,1] neg_lo:[0,0,1] neg_hi:[0,0,1]
	v_pk_fma_f32 v[84:85], v[88:89], s[22:23], v[84:85] op_sel_hi:[0,1,1]
	v_sub_f32_e32 v112, v112, v114
	v_sub_f32_e32 v113, v206, v208
	v_sub_f32_e32 v114, v175, v177
	v_sub_f32_e32 v115, v117, v183
	v_pk_mul_f32 v[106:107], v[106:107], s[70:71]
	v_mov_b32_e32 v93, v85
	v_pk_mul_f32 v[84:85], v[86:87], s[22:23] op_sel_hi:[0,1]
	v_mov_b32_e32 v211, v207
	v_mov_b32_e32 v227, v209
	v_pk_mul_f32 v[114:115], v[114:115], s[20:21] op_sel_hi:[1,0]
	v_mul_f32_e32 v100, 0x3f3504f3, v103
	v_pk_fma_f32 v[118:119], v[98:99], s[38:39], v[106:107] neg_lo:[0,0,1] neg_hi:[0,0,1]
	v_pk_fma_f32 v[98:99], v[98:99], s[38:39], v[106:107]
	v_pk_fma_f32 v[86:87], v[4:5], s[0:1], v[84:85] neg_lo:[0,0,1] neg_hi:[0,0,1]
	v_pk_fma_f32 v[4:5], v[4:5], s[0:1], v[84:85] op_sel_hi:[0,1,1]
	v_pk_add_f32 v[214:215], v[174:175], v[176:177]
	v_pk_add_f32 v[224:225], v[206:207], v[208:209]
	v_mov_b32_e32 v105, v111
	v_pk_add_f32 v[210:211], v[210:211], v[226:227] neg_lo:[0,1] neg_hi:[0,1]
	v_pk_fma_f32 v[116:117], v[112:113], s[2:3], v[114:115] neg_lo:[0,0,1] neg_hi:[0,0,1]
	v_pk_fma_f32 v[174:175], v[112:113], s[2:3], v[114:115]
	v_sub_f32_e32 v108, v100, v109
	v_fmac_f32_e32 v109, 0x3f3504f3, v103
	v_mov_b32_e32 v87, v5
	v_pk_add_f32 v[238:239], v[218:219], v[224:225]
	v_pk_add_f32 v[240:241], v[214:215], v[236:237]
	v_pk_mov_b32 v[176:177], v[116:117], v[174:175] op_sel:[1,0]
	v_pk_fma_f32 v[112:113], v[112:113], s[20:21], v[114:115] op_sel_hi:[1,0,1] neg_lo:[0,0,1] neg_hi:[0,0,1]
	v_pk_add_f32 v[114:115], v[120:121], v[210:211] neg_lo:[0,1] neg_hi:[0,1]
	v_pk_add_f32 v[182:183], v[120:121], v[210:211]
	v_pk_add_f32 v[4:5], v[104:105], v[108:109]
	v_pk_add_f32 v[84:85], v[92:93], v[86:87]
	v_add_f32_e32 v96, v118, v110
	v_add_f32_e32 v97, v99, v94
	v_pk_add_f32 v[100:101], v[2:3], v[90:91]
	v_pk_add_f32 v[242:243], v[240:241], v[238:239]
	v_mov_b32_e32 v115, v183
	v_pk_add_f32 v[176:177], v[112:113], v[176:177]
	v_pk_add_f32 v[88:89], v[4:5], v[84:85]
	v_pk_add_f32 v[102:103], v[100:101], v[96:97]
	v_pk_add_f32 v[206:207], v[114:115], v[176:177]
	ds_write2_b64 v179, v[242:243], v[88:89] offset1:17
	ds_write2_b64 v179, v[206:207], v[102:103] offset0:34 offset1:51
	v_mov_b32_e32 v89, v218
	v_mov_b32_e32 v103, v224
	v_mov_b32_e32 v224, v215
	v_mov_b32_e32 v218, v237
	v_sub_f32_e32 v88, v236, v214
	v_sub_f32_e32 v89, v89, v103
	v_pk_add_f32 v[102:103], v[224:225], v[218:219] neg_lo:[0,1] neg_hi:[0,1]
	v_pk_add_f32 v[104:105], v[104:105], v[108:109] neg_lo:[0,1] neg_hi:[0,1]
	v_pk_add_f32 v[86:87], v[92:93], v[86:87] neg_lo:[0,1] neg_hi:[0,1]
	v_pk_add_f32 v[106:107], v[88:89], v[102:103] neg_lo:[0,1] neg_hi:[0,1]
	v_pk_add_f32 v[180:181], v[88:89], v[102:103]
	v_pk_add_f32 v[92:93], v[104:105], v[86:87] op_sel:[0,1] op_sel_hi:[1,0] neg_lo:[0,1] neg_hi:[0,1]
	v_pk_add_f32 v[86:87], v[104:105], v[86:87] op_sel:[0,1] op_sel_hi:[1,0]
	v_mov_b32_e32 v107, v181
	v_mov_b32_e32 v104, v92
	v_mov_b32_e32 v105, v87
	ds_write2_b64 v179, v[106:107], v[104:105] offset0:68 offset1:85
	v_pk_add_f32 v[104:105], v[210:211], v[120:121] neg_lo:[0,1] neg_hi:[0,1]
	v_pk_mov_b32 v[98:99], v[98:99], v[2:3] op_sel:[1,0]
	v_mov_b32_e32 v95, v90
	v_mov_b32_e32 v183, v105
	v_sub_f32_e32 v104, v174, v113
	v_sub_f32_e32 v105, v112, v117
	v_pk_add_f32 v[94:95], v[98:99], v[94:95] neg_lo:[0,1] neg_hi:[0,1]
	v_sub_f32_e32 v2, v110, v118
	v_sub_f32_e32 v3, v3, v91
	v_pk_add_f32 v[106:107], v[182:183], v[104:105] neg_lo:[0,1] neg_hi:[0,1]
	v_pk_add_f32 v[104:105], v[182:183], v[104:105]
	v_pk_add_f32 v[90:91], v[2:3], v[94:95] neg_lo:[0,1] neg_hi:[0,1]
	v_pk_add_f32 v[2:3], v[2:3], v[94:95]
	v_mov_b32_e32 v108, v106
	v_mov_b32_e32 v109, v105
	v_mov_b32_e32 v94, v90
	v_mov_b32_e32 v95, v3
	ds_write2_b64 v179, v[108:109], v[94:95] offset0:102 offset1:119
	v_mov_b32_e32 v94, v240
	v_mov_b32_e32 v95, v239
	v_mov_b32_e32 v239, v241
	v_pk_add_f32 v[94:95], v[94:95], v[238:239] neg_lo:[0,1] neg_hi:[0,1]
	v_pk_add_f32 v[4:5], v[4:5], v[84:85] neg_lo:[0,1] neg_hi:[0,1]
	v_mov_b32_e32 v85, v101
	ds_write2_b64 v179, v[94:95], v[4:5] offset0:136 offset1:153
	v_pk_add_f32 v[4:5], v[114:115], v[176:177] neg_lo:[0,1] neg_hi:[0,1]
	v_sub_f32_e32 v84, v96, v100
	v_sub_f32_e32 v85, v85, v97
	ds_write2_b64 v179, v[4:5], v[84:85] offset0:170 offset1:187
	v_pk_add_f32 v[4:5], v[102:103], v[88:89] neg_lo:[0,1] neg_hi:[0,1]
	v_mov_b32_e32 v105, v107
	v_mov_b32_e32 v3, v91
	v_add_u32_e32 v112, s43, v78
	v_mov_b32_e32 v181, v5
	v_mov_b32_e32 v87, v93
	ds_write2_b64 v179, v[104:105], v[2:3] offset0:238 offset1:255
	v_mov_b32_e32 v2, v78
	v_ashrrev_i32_e32 v113, 31, v112
	ds_write2_b64 v179, v[180:181], v[86:87] offset0:204 offset1:221
	s_waitcnt lgkmcnt(0)
	s_barrier
	v_lshl_add_u64 v[112:113], v[112:113], 2, s[94:95]
	v_ashrrev_i32_e32 v3, 31, v2
	s_movk_i32 s0, 0x1000
	v_lshrrev_b32_e32 v3, 24, v3
	v_add_co_u32_e32 v114, vcc, s0, v112
	v_and_b32_e32 v182, 0xff, v2
	v_add_lshl_u32 v2, v2, v3, 4
	v_addc_co_u32_e32 v115, vcc, 0, v113, vcc
	v_and_or_b32 v2, v2, s87, v182
	v_add_co_u32_e32 v202, vcc, s27, v112
	v_ashrrev_i32_e32 v3, 4, v2
	v_lshlrev_b32_e32 v2, 3, v2
	v_addc_co_u32_e32 v203, vcc, 0, v113, vcc
	v_lshl_add_u32 v2, v3, 3, v2
	v_add_co_u32_e32 v204, vcc, s86, v112
	ds_read_b64 v[84:85], v2
	ds_read_b64 v[110:111], v2 offset:2176
	ds_read_b64 v[108:109], v2 offset:4352
	ds_read_b64 v[106:107], v2 offset:6528
	ds_read_b64 v[104:105], v2 offset:8704
	ds_read_b64 v[102:103], v2 offset:10880
	ds_read_b64 v[100:101], v2 offset:13056
	ds_read_b64 v[98:99], v2 offset:15232
	ds_read_b64 v[96:97], v2 offset:17408
	ds_read_b64 v[94:95], v2 offset:19584
	ds_read_b64 v[92:93], v2 offset:21760
	ds_read_b64 v[90:91], v2 offset:23936
	ds_read_b64 v[88:89], v2 offset:26112
	ds_read_b64 v[86:87], v2 offset:28288
	ds_read_b64 v[4:5], v2 offset:30464
	ds_read_b64 v[2:3], v2 offset:32640
	v_addc_co_u32_e32 v205, vcc, 0, v113, vcc
	global_load_dword v180, v[112:113], off
	global_load_dword v179, v[112:113], off offset:1024
	global_load_dword v177, v[112:113], off offset:2048
	global_load_dword v176, v[112:113], off offset:3072
	global_load_dword v174, v[114:115], off offset:1024
	global_load_dword v121, v[114:115], off offset:2048
	global_load_dword v120, v[114:115], off offset:3072
	s_nop 0
	global_load_dword v115, v[204:205], off
	global_load_dword v175, v[202:203], off offset:-4096
	global_load_dword v119, v[202:203], off
	global_load_dword v118, v[202:203], off offset:1024
	global_load_dword v117, v[202:203], off offset:2048
	global_load_dword v116, v[202:203], off offset:3072
	global_load_dword v114, v[204:205], off offset:1024
	global_load_dword v113, v[204:205], off offset:2048
	global_load_dword v112, v[204:205], off offset:3072
	v_lshl_add_u64 v[202:203], s[40:41], 0, v[80:81]
	v_add_co_u32_e32 v206, vcc, s27, v202
	v_lshl_add_u64 v[214:215], s[40:41], 0, v[82:83]
	s_nop 0
	v_addc_co_u32_e32 v207, vcc, 0, v203, vcc
	s_waitcnt lgkmcnt(0)
	s_barrier
	global_load_dwordx4 v[202:205], v[202:203], off
	s_nop 0
	global_load_dwordx4 v[206:209], v[206:207], off
	s_nop 0
	global_load_dwordx4 v[210:213], v[214:215], off
	v_add_co_u32_e32 v214, vcc, 0x2000, v214
	s_nop 1
	v_addc_co_u32_e32 v215, vcc, 0, v215, vcc
	global_load_dwordx4 v[214:217], v[214:215], off
	s_andn2_b64 vcc, exec, s[90:91]
	s_waitcnt vmcnt(3)
	ds_write_b128 v79, v[202:205]
	s_waitcnt vmcnt(2)
	ds_write_b128 v79, v[206:209] offset:8192
	s_waitcnt vmcnt(1)
	ds_write_b128 v79, v[210:213] offset:4096
	s_waitcnt vmcnt(0)
	ds_write_b128 v79, v[214:217] offset:12288
	s_cbranch_vccnz .LBB0_512
	v_lshl_add_u64 v[80:81], s[68:69], 0, v[80:81]
	v_add_co_u32_e32 v202, vcc, 0xb04e000, v80
	s_nop 1
	v_addc_co_u32_e32 v203, vcc, 0, v81, vcc
	v_add_co_u32_e32 v80, vcc, 0xb050000, v80
	global_load_dwordx4 v[202:205], v[202:203], off
	s_nop 0
	v_addc_co_u32_e32 v81, vcc, 0, v81, vcc
	global_load_dwordx4 v[206:209], v[80:81], off
	s_waitcnt vmcnt(1)
	ds_write_b128 v79, v[202:205] offset:16384
	s_waitcnt vmcnt(0)
	ds_write_b128 v79, v[206:209] offset:24576
	v_lshl_add_u64 v[202:203], s[68:69], 0, v[82:83]
	v_add_co_u32_e32 v80, vcc, 0xb04e000, v202
	s_nop 1
	v_addc_co_u32_e32 v81, vcc, 0, v203, vcc
	v_add_co_u32_e32 v202, vcc, 0xb050000, v202
	global_load_dwordx4 v[80:83], v[80:81], off
	s_nop 0
	v_addc_co_u32_e32 v203, vcc, 0, v203, vcc
	global_load_dwordx4 v[202:205], v[202:203], off
	s_waitcnt vmcnt(1)
	ds_write_b128 v79, v[80:83] offset:20480
	s_waitcnt vmcnt(0)
	ds_write_b128 v79, v[202:205] offset:28672

.LBB0_586:
	v_add_u32_e32 v18, s2, v49
	v_ashrrev_i32_e32 v19, 31, v18
	v_lshlrev_b64 v[2:3], 12, v[18:19]
	v_lshl_add_u64 v[2:3], v[24:25], 0, v[2:3]
	global_load_dwordx4 v[14:17], v[2:3], off
	global_load_dwordx4 v[10:13], v[2:3], off offset:1024
	v_mov_b32_e32 v29, v0
	v_mov_b32_e32 v31, v0
	v_mov_b32_e32 v33, v0
	v_mov_b32_e32 v35, v0
	s_add_i32 s2, s2, 1
	s_cmp_lg_u32 s2, 4
	s_waitcnt vmcnt(1)
	s_waitcnt vmcnt(0)
	v_mul_f32_e32 v6, v15, v15
	v_mul_f32_e32 v7, v11, v11
	s_nop 0
	v_fma_f32 v4, v14, v14, v6
	v_fma_f32 v5, v10, v10, v7
	v_fma_f32 v4, v16, v16, v4
	v_fma_f32 v5, v12, v12, v5
	v_fma_f32 v20, v17, v17, v4
	v_fma_f32 v21, v13, v13, v5
	global_load_dwordx4 v[6:9], v[2:3], off offset:2048
	s_nop 0
	global_load_dwordx4 v[2:5], v[2:3], off offset:3072
	v_add_f32_e32 v20, v20, v21
	global_load_dwordx4 v[50:53], v[22:23], off
	s_waitcnt vmcnt(2)
	s_waitcnt vmcnt(1)
	v_mul_f32_e32 v40, v7, v7
	v_mul_f32_e32 v41, v3, v3
	s_nop 0
	v_fma_f32 v38, v6, v6, v40
	v_fma_f32 v39, v2, v2, v41
	v_fma_f32 v38, v8, v8, v38
	v_fma_f32 v39, v4, v4, v39
	s_nop 0
	s_nop 0
	v_fma_f32 v38, v9, v9, v38
	v_fma_f32 v39, v5, v5, v39
	s_nop 0
	v_add_f32_e32 v20, v20, v38
	v_add_f32_e32 v20, v20, v39
	ds_bpermute_b32 v21, v37, v20
	s_waitcnt lgkmcnt(0)
	v_add_f32_e32 v20, v20, v21
	ds_bpermute_b32 v21, v44, v20
	s_waitcnt lgkmcnt(0)
	v_add_f32_e32 v20, v20, v21
	ds_bpermute_b32 v21, v45, v20
	s_waitcnt lgkmcnt(0)
	v_add_f32_e32 v20, v20, v21
	ds_bpermute_b32 v21, v46, v20
	s_waitcnt lgkmcnt(0)
	v_add_f32_e32 v20, v20, v21
	ds_bpermute_b32 v21, v47, v20
	s_waitcnt lgkmcnt(0)
	v_add_f32_e32 v20, v20, v21
	ds_bpermute_b32 v21, v48, v20
	s_waitcnt lgkmcnt(0)
	v_add_f32_e32 v20, v20, v21
	v_fmamk_f32 v20, v20, 0x3a800000, v188
	v_cmp_gt_f32_e32 vcc, s6, v20
	v_mul_f32_e32 v21, 0x4b800000, v20
	s_nop 0
	v_cndmask_b32_e32 v20, v20, v21, vcc
	v_rsq_f32_e32 v20, v20
	s_nop 0
	v_mul_f32_e32 v21, 0x45800000, v20
	v_cndmask_b32_e32 v36, v20, v21, vcc
	v_cmp_lt_i32_e32 vcc, s43, v18
	v_pk_mul_f32 v[14:15], v[14:15], v[36:37] op_sel_hi:[1,0]
	v_pk_mul_f32 v[16:17], v[16:17], v[36:37] op_sel_hi:[1,0]
	v_cndmask_b32_e32 v20, v187, v1, vcc
	v_ashrrev_i32_e32 v21, 31, v20
	v_lshl_add_u64 v[20:21], v[20:21], 2, s[4:5]
	v_lshl_add_u64 v[38:39], v[20:21], 0, s[8:9]
	v_lshl_add_u64 v[42:43], v[20:21], 0, v[28:29]
	v_lshl_add_u64 v[20:21], v[38:39], 0, v[28:29]
	global_load_dwordx4 v[58:61], v[20:21], off
	global_load_dwordx4 v[54:57], v[42:43], off
	s_waitcnt vmcnt(2)
	v_pk_mul_f32 v[14:15], v[50:51], v[14:15]
	v_pk_mul_f32 v[16:17], v[52:53], v[16:17]
	v_lshlrev_b64 v[18:19], 11, v[18:19]
	v_lshl_add_u64 v[40:41], v[26:27], 0, v[18:19]
	v_lshl_add_u64 v[50:51], v[38:39], 0, v[30:31]
	v_pk_mul_f32 v[10:11], v[10:11], v[36:37] op_sel_hi:[1,0]
	v_pk_mul_f32 v[12:13], v[12:13], v[36:37] op_sel_hi:[1,0]
	v_pk_mul_f32 v[6:7], v[6:7], v[36:37] op_sel_hi:[1,0]
	v_pk_mul_f32 v[8:9], v[8:9], v[36:37] op_sel_hi:[1,0]
	v_pk_mul_f32 v[2:3], v[2:3], v[36:37] op_sel_hi:[1,0]
	v_pk_mul_f32 v[4:5], v[4:5], v[36:37] op_sel_hi:[1,0]
	s_waitcnt vmcnt(1)
	v_pk_add_f32 v[20:21], v[58:59], 1.0 op_sel_hi:[1,0]
	s_waitcnt vmcnt(0)
	v_pk_fma_f32 v[14:15], v[20:21], v[14:15], v[54:55]
	v_pk_add_f32 v[20:21], v[60:61], 1.0 op_sel_hi:[1,0]
	v_cvt_pk_bf16_f32 v14, v14, v15
	v_pk_fma_f32 v[16:17], v[20:21], v[16:17], v[56:57]
	s_nop 0
	v_cvt_pk_bf16_f32 v15, v16, v17
	global_store_dwordx2 v[40:41], v[14:15], off
	global_load_dwordx4 v[18:21], v[22:23], off offset:1024
	s_nop 0
	global_load_dwordx4 v[14:17], v[42:43], off offset:1024
	s_waitcnt vmcnt(1)
	v_pk_mul_f32 v[10:11], v[18:19], v[10:11]
	global_load_dwordx4 v[50:53], v[50:51], off
	v_pk_mul_f32 v[12:13], v[20:21], v[12:13]
	s_waitcnt vmcnt(0)
	v_pk_add_f32 v[18:19], v[50:51], 1.0 op_sel_hi:[1,0]
	s_nop 0
	v_pk_fma_f32 v[10:11], v[18:19], v[10:11], v[14:15]
	v_pk_add_f32 v[14:15], v[52:53], 1.0 op_sel_hi:[1,0]
	v_cvt_pk_bf16_f32 v10, v10, v11
	v_pk_fma_f32 v[12:13], v[14:15], v[12:13], v[16:17]
	v_lshl_add_u64 v[18:19], v[38:39], 0, v[32:33]
	v_cvt_pk_bf16_f32 v11, v12, v13
	global_store_dwordx2 v[40:41], v[10:11], off offset:512
	global_load_dwordx4 v[10:13], v[22:23], off offset:2048
	s_nop 0
	global_load_dwordx4 v[14:17], v[42:43], off offset:2048
	s_waitcnt vmcnt(1)
	v_pk_mul_f32 v[6:7], v[10:11], v[6:7]
	global_load_dwordx4 v[18:21], v[18:19], off
	v_pk_mul_f32 v[8:9], v[12:13], v[8:9]
	s_waitcnt vmcnt(0)
	v_pk_add_f32 v[10:11], v[18:19], 1.0 op_sel_hi:[1,0]
	s_nop 0
	v_pk_fma_f32 v[6:7], v[10:11], v[6:7], v[14:15]
	v_pk_add_f32 v[10:11], v[20:21], 1.0 op_sel_hi:[1,0]
	v_cvt_pk_bf16_f32 v6, v6, v7
	v_pk_fma_f32 v[8:9], v[10:11], v[8:9], v[16:17]
	v_lshl_add_u64 v[14:15], v[38:39], 0, v[34:35]
	v_cvt_pk_bf16_f32 v7, v8, v9
	global_store_dwordx2 v[40:41], v[6:7], off offset:1024
	global_load_dwordx4 v[6:9], v[22:23], off offset:3072
	s_nop 0
	global_load_dwordx4 v[10:13], v[42:43], off offset:3072
	s_waitcnt vmcnt(1)
	v_pk_mul_f32 v[2:3], v[6:7], v[2:3]
	global_load_dwordx4 v[14:17], v[14:15], off
	v_pk_mul_f32 v[4:5], v[8:9], v[4:5]
	s_waitcnt vmcnt(0)
	v_pk_add_f32 v[6:7], v[14:15], 1.0 op_sel_hi:[1,0]
	s_nop 0
	v_pk_fma_f32 v[2:3], v[2:3], v[6:7], v[10:11]
	v_pk_add_f32 v[6:7], v[16:17], 1.0 op_sel_hi:[1,0]
	v_cvt_pk_bf16_f32 v2, v2, v3
	v_pk_fma_f32 v[4:5], v[4:5], v[6:7], v[12:13]
	s_nop 0
	v_cvt_pk_bf16_f32 v3, v4, v5
	global_store_dwordx2 v[40:41], v[2:3], off offset:1536
	s_cbranch_scc1 .LBB0_586
	v_readlane_b32 s2, v245, 36
	s_add_i32 s1, s1, s94
	s_add_i32 s0, s0, s2
	s_cmpk_gt_i32 s1, 0x9ff
	s_cbranch_scc0 .LBB0_585

.LBB0_654:
	s_waitcnt vmcnt(1)
	v_lshlrev_b32_e32 v18, 16, v34
	v_lshlrev_b32_e32 v34, 16, v32
	v_lshlrev_b32_e32 v32, 16, v22
	v_lshlrev_b32_e32 v22, 16, v10
	v_lshlrev_b32_e32 v10, 16, v3
	v_mov_b32_e32 v3, v1
	v_lshlrev_b32_e32 v52, 16, v6
	v_lshlrev_b32_e32 v6, 16, v5
	s_barrier
	v_lshlrev_b32_e32 v48, 16, v14
	v_ashrrev_i32_e32 v5, 31, v3
	v_lshrrev_b32_e32 v5, 28, v5
	v_and_b32_e32 v41, 15, v3
	v_add_u32_e32 v3, v3, v5
	v_lshlrev_b32_e32 v14, 16, v13
	v_ashrrev_i32_e32 v3, 4, v3
	v_lshlrev_b32_e32 v36, 16, v31
	v_lshlrev_b32_e32 v44, 16, v26
	v_lshlrev_b32_e32 v26, 16, v25
	v_lshlrev_b32_e32 v5, 11, v3
	s_waitcnt vmcnt(0)
	v_lshlrev_b32_e32 v16, 16, v16
	v_lshlrev_b32_e32 v42, 16, v29
	v_lshlrev_b32_e32 v46, 16, v21
	v_lshlrev_b32_e32 v50, 16, v9
	v_lshl_add_u32 v3, v3, 7, v5
	v_pk_add_f32 v[54:55], v[10:11], v[32:33]
	v_pk_add_f32 v[10:11], v[10:11], v[32:33] neg_lo:[0,1] neg_hi:[0,1]
	v_pk_add_f32 v[32:33], v[22:23], v[36:37]
	v_mov_b32_e32 v56, v23
	v_mov_b32_e32 v57, v22
	v_sub_f32_e32 v58, v48, v18
	v_sub_f32_e32 v59, v14, v34
	v_sub_f32_e32 v22, v56, v37
	v_sub_f32_e32 v23, v57, v36
	v_pk_add_f32 v[36:37], v[6:7], v[26:27]
	v_sub_f32_e32 v56, v52, v44
	v_sub_f32_e32 v57, v6, v26
	v_sub_f32_e32 v6, v4, v24
	v_sub_f32_e32 v7, v7, v27
	v_pk_add_f32 v[26:27], v[14:15], v[34:35]
	v_sub_f32_e32 v14, v12, v30
	v_sub_f32_e32 v15, v15, v35
	v_mov_b32_e32 v53, v4
	v_mov_b32_e32 v45, v24
	v_sub_f32_e32 v5, v4, v24
	v_sub_f32_e32 v4, v50, v42
	v_add_f32_e32 v24, v48, v18
	v_add_f32_e32 v25, v12, v30
	v_sub_f32_e32 v19, v48, v18
	v_sub_f32_e32 v18, v8, v28
	v_sub_f32_e32 v13, v12, v30
	v_sub_f32_e32 v12, v46, v16
	v_lshl_or_b32 v96, v41, 3, v3
	v_pk_add_f32 v[34:35], v[52:53], v[44:45]
	v_mov_b32_e32 v3, v52
	v_pk_add_f32 v[52:53], v[4:5], v[18:19] neg_lo:[0,1] neg_hi:[0,1]
	v_add_f32_e32 v9, v8, v28
	v_add_f32_e32 v8, v46, v16
	v_pk_add_f32 v[16:17], v[4:5], v[18:19]
	v_pk_add_f32 v[4:5], v[36:37], v[26:27] neg_lo:[0,1] neg_hi:[0,1]
	v_mov_b32_e32 v21, v44
	v_pk_mul_f32 v[18:19], v[4:5], s[20:21] op_sel_hi:[1,0]
	v_pk_fma_f32 v[28:29], v[4:5], s[20:21], v[18:19] op_sel:[0,0,1] op_sel_hi:[1,0,0]
	v_cvt_f32_i32_e32 v4, v41
	v_pk_add_f32 v[44:45], v[2:3], v[20:21] neg_lo:[0,1] neg_hi:[0,1]
	v_add_f32_e32 v21, v2, v20
	v_add_f32_e32 v20, v50, v42
	v_pk_add_f32 v[30:31], v[34:35], v[24:25] neg_lo:[0,1] neg_hi:[0,1]
	v_pk_add_f32 v[2:3], v[20:21], v[8:9] neg_lo:[0,1] neg_hi:[0,1]
	v_pk_add_f32 v[64:65], v[10:11], v[22:23]
	v_mul_f32_e32 v42, 0x3f3504f3, v2
	v_add_f32_e32 v2, v4, v4
	v_mul_f32_e32 v2, 0x3b800000, v2
	v_pk_add_f32 v[4:5], v[36:37], v[26:27]
	v_pk_add_f32 v[26:27], v[34:35], v[24:25]
	v_pk_add_f32 v[66:67], v[10:11], v[22:23] neg_lo:[0,1] neg_hi:[0,1]
	s_mov_b32 s28, s71
	s_mov_b32 s29, s21
	v_add_f32_e32 v34, v57, v15
	s_mov_b32 s70, s21
	v_pk_add_f32 v[48:49], v[44:45], v[12:13]
	v_pk_add_f32 v[12:13], v[44:45], v[12:13] neg_lo:[0,1] neg_hi:[0,1]
	v_mul_f32_e32 v2, 0.5, v2
	v_mov_b32_e32 v65, v67
	v_sub_f32_e32 v24, v7, v59
	v_pk_mul_f32 v[66:67], v[34:35], s[70:71] op_sel_hi:[0,1]
	v_pk_mul_f32 v[70:71], v[16:17], s[28:29] op_sel_hi:[0,1]
	v_mul_f32_e32 v41, 0x3f3504f3, v49
	v_mul_f32_e32 v43, 0x3f3504f3, v53
	v_sin_f32_e32 v44, v2
	v_pk_fma_f32 v[68:69], v[24:25], s[28:29], v[66:67] op_sel_hi:[0,1,1]
	v_pk_fma_f32 v[66:67], v[24:25], s[28:29], v[66:67] op_sel_hi:[0,1,1] neg_lo:[0,0,1] neg_hi:[0,0,1]
	v_pk_fma_f32 v[72:73], v[12:13], s[70:71], v[70:71]
	v_pk_fma_f32 v[70:71], v[12:13], s[70:71], v[70:71] op_sel_hi:[0,1,1] neg_lo:[0,0,1] neg_hi:[0,0,1]
	v_cos_f32_e32 v60, v2
	v_mov_b32_e32 v69, v67
	v_add_f32_e32 v66, v43, v41
	v_fma_f32 v67, v53, s20, -v41
	v_mov_b32_e32 v73, v71
	v_pk_add_f32 v[70:71], v[64:65], v[66:67]
	v_pk_add_f32 v[74:75], v[68:69], v[72:73]
	v_mul_f32_e32 v46, 0x3f3504f3, v3
	v_pk_add_f32 v[76:77], v[70:71], v[74:75]
	v_mul_f32_e32 v51, 0xbf3504f3, v3
	v_xor_b32_e32 v61, 0x80000000, v44
	v_pk_add_f32 v[2:3], v[54:55], v[32:33]
	v_pk_add_f32 v[8:9], v[20:21], v[8:9]
	v_pk_add_f32 v[70:71], v[70:71], v[74:75] neg_lo:[0,1] neg_hi:[0,1]
	v_pk_mul_f32 v[74:75], v[76:77], v[44:45] op_sel_hi:[1,0]
	v_pk_add_f32 v[20:21], v[2:3], v[26:27]
	v_pk_add_f32 v[36:37], v[4:5], v[8:9]
	v_pk_fma_f32 v[78:79], v[76:77], v[60:61], v[74:75] op_sel:[0,0,1] op_sel_hi:[1,1,0]
	v_pk_fma_f32 v[74:75], v[76:77], v[60:61], v[74:75] op_sel:[0,0,1] op_sel_hi:[1,0,0] neg_lo:[0,0,1] neg_hi:[0,0,1]
	v_pk_add_f32 v[62:63], v[20:21], v[36:37]
	v_mov_b32_e32 v79, v75
	s_nop 0
	s_nop 0
	v_mov_b32_e32 v24, v25
	s_nop 0
	v_pk_add_f32 v[14:15], v[56:57], v[14:15] neg_lo:[0,1] neg_hi:[0,1]
	v_pk_add_f32 v[6:7], v[6:7], v[58:59]
	v_readlane_b32 s4, v245, 26
	ds_write2_b64 v96, v[62:63], v[78:79] offset1:17
	s_nop 0
	s_nop 0
	v_mov_b32_e32 v74, v32
	s_nop 0
	v_sub_f32_e32 v32, v46, v42
	v_sub_f32_e32 v33, v55, v33
	v_sub_f32_e32 v24, v35, v24
	v_sub_f32_e32 v25, v51, v42
	v_mov_b32_e32 v42, v28
	v_mov_b32_e32 v43, v30
	v_mov_b32_e32 v53, v17
	v_mov_b32_e32 v49, v13
	v_mul_f32_e32 v12, 0x3ec3ef15, v15
	v_mul_f32_e32 v16, 0x3f6c835e, v7
	s_nop 0
	s_nop 0
	s_mov_b32 s28, s3
	s_mov_b32 s29, s76
	v_readlane_b32 s5, v245, 27
	v_mov_b32_e32 v45, v60
	s_nop 0
	s_nop 0
	v_sub_f32_e32 v19, v19, v18
	v_sub_f32_e32 v18, v54, v74
	v_pk_add_f32 v[34:35], v[32:33], v[30:31] op_sel:[1,0] op_sel_hi:[0,1]
	v_pk_add_f32 v[30:31], v[32:33], v[42:43]
	v_pk_add_f32 v[42:43], v[32:33], v[42:43] neg_lo:[0,1] neg_hi:[0,1]
	v_add_f32_e32 v12, v16, v12
	v_add_f32_e32 v13, v11, v23
	v_pk_mul_f32 v[14:15], v[14:15], s[28:29]
	s_mov_b32 s70, s20
	v_pk_mul_f32 v[16:17], v[48:49], s[4:5]
	v_mul_f32_e32 v50, v44, v44
	v_mul_f32_e32 v51, v45, v61
	v_mov_b32_e32 v31, v43
	v_pk_add_f32 v[46:47], v[18:19], v[24:25]
	v_pk_fma_f32 v[6:7], v[6:7], s[70:71], v[14:15]
	v_pk_fma_f32 v[14:15], v[52:53], s[30:31], v[16:17]
	v_mul_f32_e32 v11, 0x3ec3ef15, v52
	v_pk_fma_f32 v[52:53], v[60:61], v[60:61], v[50:51] op_sel_hi:[0,1,1] neg_lo:[0,0,1] neg_hi:[0,0,1]
	v_pk_fma_f32 v[50:51], v[60:61], v[60:61], v[50:51] op_sel_hi:[0,1,1]
	v_pk_add_f32 v[18:19], v[18:19], v[24:25] neg_lo:[0,1] neg_hi:[0,1]
	v_pk_add_f32 v[24:25], v[46:47], v[30:31]
	v_pk_mov_b32 v[62:63], v[50:51], v[52:53] op_sel:[1,0]
	v_mov_b32_e32 v54, v52
	v_mov_b32_e32 v55, v51
	v_pk_mul_f32 v[62:63], v[50:51], v[62:63] op_sel:[1,0]
	v_pk_mul_f32 v[50:51], v[24:25], v[50:51] op_sel:[1,1] op_sel_hi:[0,1]
	v_pk_fma_f32 v[74:75], v[52:53], v[54:55], v[62:63] op_sel_hi:[0,1,1] neg_lo:[0,0,1] neg_hi:[0,0,1]
	v_pk_fma_f32 v[62:63], v[52:53], v[54:55], v[62:63] op_sel_hi:[0,1,1]
	v_pk_fma_f32 v[84:85], v[24:25], v[52:53], v[50:51] neg_lo:[0,0,1] neg_hi:[0,0,1]
	v_pk_fma_f32 v[24:25], v[24:25], v[52:53], v[50:51] op_sel_hi:[1,0,1]
	v_pk_add_f32 v[28:29], v[28:29], v[32:33] neg_lo:[0,1] neg_hi:[0,1]
	v_mov_b32_e32 v85, v25
	v_pk_add_f32 v[24:25], v[64:65], v[66:67] neg_lo:[0,1] neg_hi:[0,1]
	v_pk_mul_f32 v[66:67], v[54:55], v[62:63] op_sel:[0,1]
	v_pk_add_f32 v[50:51], v[68:69], v[72:73] neg_lo:[0,1] neg_hi:[0,1]
	v_pk_fma_f32 v[68:69], v[54:55], v[74:75], v[66:67] op_sel:[0,0,1] op_sel_hi:[1,0,0] neg_lo:[0,0,1] neg_hi:[0,0,1]
	v_pk_fma_f32 v[66:67], v[54:55], v[74:75], v[66:67] op_sel:[0,0,1] op_sel_hi:[1,0,0]
	v_pk_add_f32 v[32:33], v[34:35], v[28:29]
	v_sub_f32_e32 v28, v34, v28
	v_pk_mov_b32 v[34:35], v[66:67], v[68:69] op_sel:[1,0]
	v_mov_b32_e32 v72, v68
	v_mov_b32_e32 v73, v67
	v_pk_add_f32 v[86:87], v[18:19], v[18:19] op_sel:[0,1] op_sel_hi:[0,1]
	v_pk_mul_f32 v[28:29], v[28:29], v[34:35] op_sel_hi:[0,1]
	v_mov_b32_e32 v76, v74
	v_mov_b32_e32 v77, v63
	v_pk_fma_f32 v[34:35], v[86:87], v[68:69], v[28:29] neg_lo:[0,0,1] neg_hi:[0,0,1]
	v_pk_fma_f32 v[28:29], v[86:87], v[72:73], v[28:29]
	v_pk_add_f32 v[20:21], v[20:21], v[36:37] neg_lo:[0,1] neg_hi:[0,1]
	v_mov_b32_e32 v35, v29
	v_pk_mul_f32 v[28:29], v[76:77], v[62:63] op_sel:[0,1]
	v_mov_b32_e32 v61, v44
	v_pk_fma_f32 v[36:37], v[74:75], v[76:77], v[28:29] op_sel:[0,0,1] op_sel_hi:[0,1,0] neg_lo:[0,0,1] neg_hi:[0,0,1]
	v_pk_fma_f32 v[28:29], v[74:75], v[76:77], v[28:29] op_sel:[0,0,1] op_sel_hi:[0,1,0]
	v_pk_mov_b32 v[66:67], v[28:29], v[36:37] op_sel:[1,0]
	v_pk_mul_f32 v[58:59], v[44:45], v[54:55]
	v_pk_mul_f32 v[80:81], v[44:45], v[76:77]
	v_pk_mov_b32 v[82:83], v[62:63], v[74:75] op_sel:[1,0]
	v_mov_b32_e32 v62, v36
	v_mov_b32_e32 v63, v29
	v_pk_mul_f32 v[44:45], v[44:45], v[66:67] op_sel_hi:[0,1]
	v_mul_f32_e32 v23, 0x3f6c835e, v48
	v_pk_fma_f32 v[68:69], v[60:61], v[62:63], v[44:45] op_sel_hi:[0,1,1]
	v_pk_fma_f32 v[44:45], v[60:61], v[62:63], v[44:45] op_sel_hi:[0,1,1] neg_lo:[0,0,1] neg_hi:[0,0,1]
	v_pk_add_f32 v[10:11], v[10:11], v[22:23] neg_lo:[0,1] neg_hi:[0,1]
	v_pk_mul_f32 v[56:57], v[60:61], v[54:55]
	v_pk_mul_f32 v[78:79], v[60:61], v[76:77]
	v_mov_b32_e32 v61, v45
	v_pk_mov_b32 v[44:45], v[44:45], v[68:69] op_sel:[1,0]
	v_pk_add_f32 v[16:17], v[12:13], v[14:15]
	v_pk_add_f32 v[22:23], v[6:7], v[10:11]
	v_mov_b32_e32 v60, v68
	v_mov_b32_e32 v88, v56
	v_mov_b32_e32 v89, v59
	v_pk_mov_b32 v[56:57], v[56:57], v[58:59] op_sel:[1,0]
	v_pk_mul_f32 v[44:45], v[70:71], v[44:45] op_sel:[1,0]
	v_pk_mul_f32 v[28:29], v[20:21], v[28:29] op_sel:[1,1] op_sel_hi:[0,1]
	v_pk_add_f32 v[48:49], v[16:17], v[22:23]
	v_pk_mul_f32 v[86:87], v[54:55], v[62:63]
	v_pk_mul_f32 v[54:55], v[54:55], v[66:67]
	v_pk_add_f32 v[58:59], v[88:89], v[56:57]
	v_pk_add_f32 v[56:57], v[88:89], v[56:57] neg_lo:[0,1] neg_hi:[0,1]
	v_pk_fma_f32 v[68:69], v[70:71], v[68:69], v[44:45] neg_lo:[0,0,1] neg_hi:[0,0,1]
	v_pk_fma_f32 v[44:45], v[70:71], v[60:61], v[44:45] op_sel_hi:[0,1,1]
	v_pk_fma_f32 v[70:71], v[20:21], v[36:37], v[28:29] neg_lo:[0,0,1] neg_hi:[0,0,1]
	v_pk_fma_f32 v[20:21], v[20:21], v[36:37], v[28:29] op_sel_hi:[1,0,1]
	v_mov_b32_e32 v42, v46
	v_mov_b32_e32 v31, v47
	v_pk_mul_f32 v[90:91], v[48:49], v[56:57] op_sel:[0,1]
	v_mov_b32_e32 v71, v21
	v_pk_add_f32 v[20:21], v[42:43], v[30:31] neg_lo:[0,1] neg_hi:[0,1]
	v_pk_add_f32 v[28:29], v[54:55], v[54:55] op_sel:[0,1] op_sel_hi:[0,1]
	v_pk_fma_f32 v[92:93], v[48:49], v[58:59], v[90:91] op_sel:[0,0,1] op_sel_hi:[1,1,0] neg_lo:[0,0,1] neg_hi:[0,0,1]
	v_pk_fma_f32 v[48:49], v[48:49], v[58:59], v[90:91] op_sel:[0,0,1] op_sel_hi:[1,0,0]
	v_pk_mul_f32 v[28:29], v[20:21], v[28:29] op_sel:[1,0] op_sel_hi:[0,1]
	v_pk_add_f32 v[30:31], v[86:87], v[86:87] op_sel:[0,1] op_sel_hi:[0,1] neg_lo:[0,1] neg_hi:[0,1]
	v_mov_b32_e32 v93, v49
	v_pk_fma_f32 v[36:37], v[20:21], v[30:31], v[28:29] neg_lo:[0,0,1] neg_hi:[0,0,1]
	v_pk_fma_f32 v[20:21], v[20:21], v[30:31], v[28:29]
	ds_write2_b64 v96, v[84:85], v[92:93] offset0:34 offset1:51
	v_mul_f32_e32 v84, v58, v62
	v_mul_f32_e32 v85, v57, v63
	v_mul_f32_e32 v88, v58, v66
	v_mul_f32_e32 v89, v57, v67
	v_mov_b32_e32 v37, v21
	v_mov_b32_e32 v21, v17
	v_sub_f32_e32 v16, v22, v16
	v_sub_f32_e32 v17, v21, v23
	v_pk_add_f32 v[20:21], v[88:89], v[88:89] op_sel:[0,1] op_sel_hi:[0,1]
	v_pk_mul_f32 v[20:21], v[16:17], v[20:21] op_sel:[1,0] op_sel_hi:[0,1]
	v_pk_add_f32 v[22:23], v[84:85], v[84:85] op_sel:[0,1] op_sel_hi:[0,1] neg_lo:[0,1] neg_hi:[0,1]
	v_pk_add_f32 v[2:3], v[2:3], v[26:27] neg_lo:[0,1] neg_hi:[0,1]
	v_pk_add_f32 v[4:5], v[4:5], v[8:9] neg_lo:[0,1] neg_hi:[0,1]
	v_pk_fma_f32 v[28:29], v[16:17], v[22:23], v[20:21] neg_lo:[0,0,1] neg_hi:[0,0,1]
	v_pk_fma_f32 v[16:17], v[16:17], v[22:23], v[20:21]
	v_pk_add_f32 v[8:9], v[2:3], v[4:5] op_sel:[0,1] op_sel_hi:[1,0]
	v_pk_add_f32 v[2:3], v[2:3], v[4:5] op_sel:[0,1] op_sel_hi:[1,0] neg_lo:[0,1] neg_hi:[0,1]
	v_pk_add_f32 v[52:53], v[24:25], v[50:51] op_sel:[0,1] op_sel_hi:[1,0]
	v_pk_add_f32 v[24:25], v[24:25], v[50:51] op_sel:[0,1] op_sel_hi:[1,0] neg_lo:[0,1] neg_hi:[0,1]
	v_mov_b32_e32 v94, v78
	v_mov_b32_e32 v95, v81
	v_pk_mov_b32 v[78:79], v[78:79], v[80:81] op_sel:[1,0]
	v_mov_b32_e32 v29, v17
	v_pk_mul_f32 v[16:17], v[2:3], v[82:83] op_sel:[1,0]
	v_pk_mov_b32 v[64:65], v[24:25], v[52:53] op_sel:[1,0]
	v_pk_mul_f32 v[92:93], v[76:77], v[66:67]
	v_pk_add_f32 v[80:81], v[94:95], v[78:79]
	v_pk_add_f32 v[78:79], v[94:95], v[78:79] neg_lo:[0,1] neg_hi:[0,1]
	v_pk_fma_f32 v[20:21], v[8:9], v[74:75], v[16:17] neg_lo:[0,0,1] neg_hi:[0,0,1]
	v_pk_fma_f32 v[16:17], v[8:9], v[76:77], v[16:17] op_sel_hi:[0,1,1]
	v_pk_mul_f32 v[90:91], v[76:77], v[62:63]
	v_mov_b32_e32 v94, v80
	v_mov_b32_e32 v95, v79
	v_pk_mul_f32 v[64:65], v[64:65], v[78:79] op_sel:[0,1]
	v_mov_b32_e32 v5, v9
	v_mov_b32_e32 v21, v17
	v_pk_mov_b32 v[8:9], v[8:9], v[2:3] op_sel:[1,0]
	v_pk_add_f32 v[16:17], v[92:93], v[92:93] op_sel:[0,1] op_sel_hi:[0,1]
	v_pk_fma_f32 v[78:79], v[52:53], v[80:81], v[64:65] neg_lo:[0,0,1] neg_hi:[0,0,1]
	v_fma_f32 v50, v52, v80, v64
	v_fma_f32 v51, v25, v80, v65
	v_pk_mul_f32 v[64:65], v[66:67], v[94:95]
	v_mov_b32_e32 v4, v2
	v_pk_mul_f32 v[8:9], v[8:9], v[16:17]
	v_pk_add_f32 v[16:17], v[90:91], v[90:91] op_sel:[0,1] op_sel_hi:[0,1] neg_lo:[0,1] neg_hi:[0,1]
	v_mov_b32_e32 v79, v51
	v_pk_mul_f32 v[50:51], v[62:63], v[94:95]
	v_pk_fma_f32 v[2:3], v[2:3], v[16:17], v[8:9] neg_lo:[0,0,1] neg_hi:[0,0,1]
	v_pk_fma_f32 v[4:5], v[4:5], v[16:17], v[8:9]
	v_pk_mov_b32 v[8:9], v[52:53], v[24:25] op_sel:[1,0]
	v_pk_add_f32 v[16:17], v[64:65], v[64:65] op_sel:[0,1] op_sel_hi:[0,1]
	v_mov_b32_e32 v3, v5
	v_pk_mul_f32 v[8:9], v[8:9], v[16:17]
	v_pk_add_f32 v[16:17], v[50:51], v[50:51] op_sel:[0,1] op_sel_hi:[0,1] neg_lo:[0,1] neg_hi:[0,1]
	ds_write2_b64 v96, v[20:21], v[78:79] offset0:68 offset1:85
	v_pk_fma_f32 v[20:21], v[24:25], v[16:17], v[8:9] neg_lo:[0,0,1] neg_hi:[0,0,1]
	v_fma_f32 v4, v24, v16, v8
	v_fma_f32 v5, v53, v17, v9
	v_mov_b32_e32 v69, v45
	v_pk_mul_f32 v[44:45], v[62:63], v[72:73]
	v_mov_b32_e32 v21, v5
	ds_write2_b64 v96, v[2:3], v[20:21] offset0:204 offset1:221
	v_mov_b32_e32 v2, v18
	v_mov_b32_e32 v3, v44
	v_mov_b32_e32 v44, v19
	v_pk_mul_f32 v[60:61], v[66:67], v[72:73]
	v_pk_add_f32 v[2:3], v[2:3], v[44:45] neg_lo:[0,1] neg_hi:[0,1]
	v_pk_add_f32 v[8:9], v[60:61], v[60:61] op_sel:[0,1] op_sel_hi:[0,1]
	v_mul_f32_e32 v4, v32, v8
	v_mul_f32_e32 v5, v2, v9
	v_pk_mov_b32 v[8:9], v[2:3], v[32:33] op_sel:[1,0]
	v_pk_mul_f32 v[48:49], v[76:77], v[56:57] op_sel:[0,1]
	v_pk_fma_f32 v[16:17], v[2:3], v[8:9], v[4:5] neg_lo:[0,0,1] neg_hi:[0,0,1]
	v_pk_fma_f32 v[2:3], v[2:3], v[8:9], v[4:5]
	v_mov_b32_e32 v17, v3
	v_sub_f32_e32 v2, v10, v6
	v_sub_f32_e32 v3, v13, v15
	v_pk_mov_b32 v[4:5], v[6:7], v[12:13] op_sel:[1,0]
	v_pk_mov_b32 v[6:7], v[10:11], v[14:15] op_sel:[1,0]
	v_pk_fma_f32 v[56:57], v[76:77], v[58:59], v[48:49] op_sel:[0,0,1] op_sel_hi:[1,0,0] neg_lo:[0,0,1] neg_hi:[0,0,1]
	v_pk_fma_f32 v[48:49], v[76:77], v[58:59], v[48:49] op_sel:[0,0,1] op_sel_hi:[1,0,0]
	v_pk_add_f32 v[4:5], v[4:5], v[6:7] neg_lo:[0,1] neg_hi:[0,1]
	v_mov_b32_e32 v59, v49
	v_pk_mov_b32 v[48:49], v[48:49], v[56:57] op_sel:[1,0]
	v_pk_add_f32 v[6:7], v[2:3], v[4:5]
	v_pk_add_f32 v[2:3], v[2:3], v[4:5] neg_lo:[0,1] neg_hi:[0,1]
	v_mov_b32_e32 v58, v56
	v_pk_mul_f32 v[8:9], v[2:3], v[48:49] op_sel:[1,0]
	v_pk_mul_f32 v[66:67], v[66:67], v[58:59]
	v_pk_fma_f32 v[10:11], v[6:7], v[56:57], v[8:9] neg_lo:[0,0,1] neg_hi:[0,0,1]
	v_pk_fma_f32 v[8:9], v[6:7], v[58:59], v[8:9] op_sel_hi:[0,1,1]
	v_pk_mul_f32 v[62:63], v[62:63], v[58:59]
	v_mov_b32_e32 v5, v7
	v_mov_b32_e32 v11, v9
	v_pk_mov_b32 v[6:7], v[6:7], v[2:3] op_sel:[1,0]
	v_pk_add_f32 v[8:9], v[66:67], v[66:67] op_sel:[0,1] op_sel_hi:[0,1]
	v_mov_b32_e32 v4, v2
	v_pk_mul_f32 v[6:7], v[6:7], v[8:9]
	v_pk_add_f32 v[8:9], v[62:63], v[62:63] op_sel:[0,1] op_sel_hi:[0,1] neg_lo:[0,1] neg_hi:[0,1]
	v_pk_fma_f32 v[2:3], v[2:3], v[8:9], v[6:7] neg_lo:[0,0,1] neg_hi:[0,0,1]
	v_pk_fma_f32 v[4:5], v[4:5], v[8:9], v[6:7]
	ds_write2_b64 v96, v[70:71], v[68:69] offset0:136 offset1:153
	v_mov_b32_e32 v3, v5
	ds_write2_b64 v96, v[16:17], v[2:3] offset0:238 offset1:255
	v_mov_b32_e32 v2, v1
	ds_write2_b64 v96, v[36:37], v[28:29] offset0:170 offset1:187
	ds_write2_b64 v96, v[34:35], v[10:11] offset0:102 offset1:119
	s_waitcnt lgkmcnt(0)
	s_barrier
	v_readlane_b32 s4, v246, 28
	v_mul_lo_u32 v26, v2, s33
	ds_read2_b64 v[2:5], v26 offset0:1 offset1:2
	ds_read_b32 v32, v26
	ds_read_b64 v[30:31], v26 offset:56
	ds_read2_b64 v[6:9], v26 offset0:8 offset1:9
	ds_read2_b64 v[10:13], v26 offset0:10 offset1:11
	ds_read2_b64 v[14:17], v26 offset0:12 offset1:13
	ds_read2_b64 v[18:21], v26 offset0:3 offset1:4
	ds_read2_b64 v[22:25], v26 offset0:5 offset1:6
	ds_read2_b64 v[26:29], v26 offset0:14 offset1:15
	s_waitcnt lgkmcnt(5)
	v_add_f32_e32 v7, v32, v6
	v_sub_f32_e32 v6, v32, v6
	s_waitcnt lgkmcnt(2)
	v_add_f32_e32 v14, v20, v14
	v_sub_f32_e32 v15, v21, v15
	v_add_f32_e32 v20, v7, v14
	v_sub_f32_e32 v7, v7, v14
	v_add_f32_e32 v14, v6, v15
	v_sub_f32_e32 v6, v6, v15
	v_add_f32_e32 v15, v2, v8
	v_add_f32_e32 v21, v3, v9
	v_sub_f32_e32 v2, v2, v8
	v_sub_f32_e32 v3, v3, v9
	s_waitcnt lgkmcnt(1)
	v_add_f32_e32 v8, v22, v16
	v_add_f32_e32 v9, v23, v17
	v_sub_f32_e32 v16, v22, v16
	v_sub_f32_e32 v17, v23, v17
	v_add_f32_e32 v22, v15, v8
	v_add_f32_e32 v23, v21, v9
	v_sub_f32_e32 v8, v15, v8
	v_sub_f32_e32 v9, v21, v9
	v_add_f32_e32 v15, v2, v17
	v_sub_f32_e32 v21, v3, v16
	v_sub_f32_e32 v2, v2, v17
	v_add_f32_e32 v3, v3, v16
	v_add_f32_e32 v16, v4, v10
	v_add_f32_e32 v17, v5, v11
	v_sub_f32_e32 v4, v4, v10
	v_sub_f32_e32 v5, v5, v11
	s_waitcnt lgkmcnt(0)
	v_add_f32_e32 v10, v24, v26
	v_add_f32_e32 v11, v25, v27
	v_sub_f32_e32 v25, v25, v27
	v_sub_f32_e32 v24, v24, v26
	v_add_f32_e32 v10, v16, v10
	v_add_f32_e32 v16, v4, v25
	v_sub_f32_e32 v4, v4, v25
	v_add_f32_e32 v25, v19, v13
	v_sub_f32_e32 v13, v19, v13
	v_add_f32_e32 v19, v31, v29
	v_sub_f32_e32 v26, v30, v28
	v_sub_f32_e32 v27, v31, v29
	v_add_f32_e32 v29, v25, v19
	v_sub_f32_e32 v19, v25, v19
	v_sub_f32_e32 v25, v13, v26
	v_add_f32_e32 v13, v13, v26
	v_mul_f32_e32 v26, 0x3f6c835e, v15
	v_mul_f32_e32 v15, 0xbec3ef15, v15
	v_mul_f32_e32 v8, 0x3f3504f3, v8
	v_sub_f32_e32 v11, v17, v11
	v_sub_f32_e32 v17, v5, v24
	v_add_f32_e32 v5, v5, v24
	v_add_f32_e32 v24, v18, v12
	v_sub_f32_e32 v12, v18, v12
	v_add_f32_e32 v18, v30, v28
	v_fmac_f32_e32 v26, 0x3ec3ef15, v21
	v_fmac_f32_e32 v15, 0x3f6c835e, v21
	v_fmamk_f32 v21, v9, 0x3f3504f3, v8
	v_fma_f32 v8, v9, s20, -v8
	v_mul_f32_e32 v9, 0x3ec3ef15, v2
	v_mul_f32_e32 v2, 0xbf6c835e, v2
	v_add_f32_e32 v28, v24, v18
	v_sub_f32_e32 v18, v24, v18
	v_fmac_f32_e32 v9, 0x3f6c835e, v3
	v_fmac_f32_e32 v2, 0x3ec3ef15, v3
	v_mul_f32_e32 v3, 0x3f3504f3, v16
	v_add_f32_e32 v24, v12, v27
	v_fmac_f32_e32 v3, 0x3f3504f3, v17
	v_mul_f32_e32 v17, 0xbf3504f3, v18
	v_sub_f32_e32 v12, v12, v27
	v_mul_f32_e32 v16, 0xbf6c835e, v24
	v_fmamk_f32 v18, v19, 0x3f3504f3, v17
	v_fmac_f32_e32 v17, 0xbf3504f3, v19
	v_mul_f32_e32 v19, 0xbec3ef15, v13
	v_mul_f32_e32 v13, 0xbf6c835e, v13
	v_fmac_f32_e32 v16, 0x3ec3ef15, v25
	v_fmac_f32_e32 v19, 0xbf6c835e, v12
	v_fmac_f32_e32 v13, 0x3ec3ef15, v12
	v_add_f32_e32 v12, v20, v10
	v_sub_f32_e32 v10, v20, v10
	v_add_f32_e32 v20, v22, v28
	v_sub_f32_e32 v22, v23, v29
	v_mul_f32_e32 v4, 0xbf3504f3, v4
	v_add_f32_e32 v23, v12, v20
	v_sub_f32_e32 v12, v12, v20
	v_add_f32_e32 v20, v10, v22
	v_sub_f32_e32 v10, v10, v22
	v_add_f32_e32 v22, v14, v3
	v_sub_f32_e32 v3, v14, v3
	v_sub_f32_e32 v14, v15, v16
	v_fmac_f32_e32 v4, 0x3f3504f3, v5
	v_add_f32_e32 v16, v3, v14
	v_sub_f32_e32 v3, v3, v14
	v_add_f32_e32 v14, v7, v11
	v_sub_f32_e32 v7, v7, v11
	v_add_f32_e32 v11, v21, v18
	v_sub_f32_e32 v8, v8, v17
	v_add_f32_e32 v17, v14, v11
	v_sub_f32_e32 v11, v14, v11
	v_add_f32_e32 v14, v7, v8
	v_sub_f32_e32 v7, v7, v8
	v_add_f32_e32 v8, v6, v4
	v_sub_f32_e32 v4, v6, v4
	v_add_f32_e32 v6, v9, v19
	v_sub_f32_e32 v2, v2, v13
	v_add_f32_e32 v9, v8, v6
	v_sub_f32_e32 v6, v8, v6
	v_add_f32_e32 v8, v4, v2
	v_sub_f32_e32 v2, v4, v2
	v_lshlrev_b32_e32 v4, 2, v40
	v_mul_f32_e32 v5, 0x3ec3ef15, v24
	v_lshl_add_u32 v18, v39, 2, v4
	v_ashrrev_i32_e32 v19, 2, v39
	v_fmac_f32_e32 v5, 0x3f6c835e, v25
	v_mul_f32_e32 v13, 0x3bb504f3, v23
	v_add_u32_e32 v19, v18, v19
	v_add_f32_e32 v5, v26, v5
	s_barrier
	ds_write_b32 v19, v13
	v_or_b32_e32 v13, 16, v39
	v_add_f32_e32 v15, v22, v5
	v_ashrrev_i32_e32 v13, 2, v13
	v_mul_f32_e32 v15, 0x3bb504f3, v15
	v_add_u32_e32 v13, v18, v13
	ds_write_b32 v13, v15 offset:64
	v_or_b32_e32 v13, 32, v39
	v_ashrrev_i32_e32 v13, 2, v13
	v_mul_f32_e32 v15, 0x3bb504f3, v17
	v_add_u32_e32 v13, v18, v13
	ds_write_b32 v13, v15 offset:128
	v_or_b32_e32 v13, 48, v39
	v_ashrrev_i32_e32 v13, 2, v13
	v_mul_f32_e32 v9, 0x3bb504f3, v9
	v_add_u32_e32 v13, v18, v13
	ds_write_b32 v13, v9 offset:192
	v_or_b32_e32 v9, 64, v39
	v_ashrrev_i32_e32 v9, 2, v9
	v_mul_f32_e32 v13, 0x3bb504f3, v20
	v_add_u32_e32 v9, v18, v9
	ds_write_b32 v9, v13 offset:256
	v_or_b32_e32 v9, 0x50, v39
	v_ashrrev_i32_e32 v9, 2, v9
	v_mul_f32_e32 v13, 0x3bb504f3, v16
	v_add_u32_e32 v9, v18, v9
	ds_write_b32 v9, v13 offset:320
	v_or_b32_e32 v9, 0x60, v39
	v_ashrrev_i32_e32 v9, 2, v9
	v_mul_f32_e32 v13, 0x3bb504f3, v14
	v_add_u32_e32 v9, v18, v9
	ds_write_b32 v9, v13 offset:384
	v_or_b32_e32 v9, 0x70, v39
	v_ashrrev_i32_e32 v9, 2, v9
	v_mul_f32_e32 v8, 0x3bb504f3, v8
	v_add_u32_e32 v9, v18, v9
	ds_write_b32 v9, v8 offset:448
	v_or_b32_e32 v8, 0x80, v39
	v_ashrrev_i32_e32 v8, 2, v8
	v_mul_f32_e32 v9, 0x3bb504f3, v12
	v_add_u32_e32 v8, v18, v8
	ds_write_b32 v8, v9 offset:512
	v_or_b32_e32 v8, 0x90, v39
	v_sub_f32_e32 v5, v22, v5
	v_ashrrev_i32_e32 v8, 2, v8
	v_mul_f32_e32 v5, 0x3bb504f3, v5
	v_add_u32_e32 v8, v18, v8
	ds_write_b32 v8, v5 offset:576
	v_or_b32_e32 v5, 0xa0, v39
	v_ashrrev_i32_e32 v5, 2, v5
	v_mul_f32_e32 v8, 0x3bb504f3, v11
	v_add_u32_e32 v5, v18, v5
	ds_write_b32 v5, v8 offset:640
	v_or_b32_e32 v5, 0xb0, v39
	v_ashrrev_i32_e32 v5, 2, v5
	v_mul_f32_e32 v6, 0x3bb504f3, v6
	v_add_u32_e32 v5, v18, v5
	ds_write_b32 v5, v6 offset:704
	v_or_b32_e32 v5, 0xc0, v39
	v_ashrrev_i32_e32 v5, 2, v5
	v_mul_f32_e32 v6, 0x3bb504f3, v10
	v_add_u32_e32 v5, v18, v5
	ds_write_b32 v5, v6 offset:768
	v_or_b32_e32 v5, 0xd0, v39
	v_ashrrev_i32_e32 v5, 2, v5
	v_mul_f32_e32 v3, 0x3bb504f3, v3
	v_add_u32_e32 v5, v18, v5
	ds_write_b32 v5, v3 offset:832
	v_or_b32_e32 v3, 0xe0, v39
	v_ashrrev_i32_e32 v3, 2, v3
	v_mul_f32_e32 v5, 0x3bb504f3, v7
	v_add_u32_e32 v3, v18, v3
	v_readlane_b32 s5, v246, 29
	s_add_u32 s24, s4, s0
	ds_write_b32 v3, v5 offset:896
	v_or_b32_e32 v3, 0xf0, v38
	s_addc_u32 s35, s5, s1
	s_lshl_b64 s[28:29], s[22:23], 1
	v_lshlrev_b32_e32 v8, 3, v1
	v_lshlrev_b32_e32 v5, 2, v3
	v_ashrrev_i32_e32 v3, 2, v3
	s_add_u32 s22, s24, s28
	v_ashrrev_i32_e32 v9, 31, v8
	v_mul_f32_e32 v2, 0x3bb504f3, v2
	v_add3_u32 v3, v4, v5, v3
	s_addc_u32 s23, s35, s29
	v_lshlrev_b64 v[12:13], 1, v[8:9]
	ds_write_b32 v3, v2
	v_lshl_add_u64 v[2:3], s[22:23], 0, v[12:13]
	s_waitcnt lgkmcnt(0)
	s_barrier
	global_load_dwordx4 v[2:5], v[2:3], off
	v_bfe_i32 v6, v1, 1, 28
	v_lshlrev_b32_e32 v1, 5, v1
	v_lshl_add_u32 v9, v6, 2, v1
	ds_read2_b32 v[10:11], v9 offset1:1
	ds_read2_b32 v[14:15], v9 offset0:2 offset1:3
	ds_read2_b32 v[16:17], v9 offset0:4 offset1:5
	ds_read2_b32 v[18:19], v9 offset0:6 offset1:7
	v_readlane_b32 s4, v247, 56
	v_readlane_b32 s5, v247, 57
	s_add_u32 s0, s4, s0
	s_addc_u32 s1, s5, s1
	s_add_u32 s0, s0, s28
	s_addc_u32 s1, s1, s29
	s_and_b64 vcc, exec, s[36:37]
	s_waitcnt vmcnt(0)
	v_lshlrev_b32_e32 v6, 16, v2
	v_and_b32_e32 v7, 0xffff0000, v2
	s_waitcnt lgkmcnt(3)
	v_pk_mul_f32 v[6:7], v[10:11], v[6:7]
	v_add_u32_e32 v10, 0x800, v8
	v_cvt_pk_bf16_f32 v2, v6, v7
	v_lshlrev_b32_e32 v6, 16, v3
	v_and_b32_e32 v7, 0xffff0000, v3
	s_waitcnt lgkmcnt(2)
	v_pk_mul_f32 v[6:7], v[14:15], v[6:7]
	v_ashrrev_i32_e32 v11, 31, v10
	v_cvt_pk_bf16_f32 v3, v6, v7
	v_lshlrev_b32_e32 v6, 16, v4
	v_and_b32_e32 v7, 0xffff0000, v4
	s_waitcnt lgkmcnt(1)
	v_pk_mul_f32 v[6:7], v[16:17], v[6:7]
	v_ashrrev_i32_e32 v9, 4, v10
	v_cvt_pk_bf16_f32 v4, v6, v7
	v_lshlrev_b32_e32 v6, 16, v5
	v_and_b32_e32 v7, 0xffff0000, v5
	s_waitcnt lgkmcnt(0)
	v_pk_mul_f32 v[6:7], v[18:19], v[6:7]
	v_lshl_add_u32 v1, v9, 2, v1
	v_cvt_pk_bf16_f32 v5, v6, v7
	v_lshl_add_u64 v[6:7], s[0:1], 0, v[12:13]
	global_store_dwordx4 v[6:7], v[2:5], off
	v_lshlrev_b64 v[6:7], 1, v[10:11]
	v_add_u32_e32 v9, 0x2000, v1
	v_lshl_add_u64 v[2:3], s[22:23], 0, v[6:7]
	global_load_dwordx4 v[2:5], v[2:3], off
	ds_read2_b32 v[16:17], v9 offset1:1
	v_add_u32_e32 v11, 0x2008, v1
	v_add_u32_e32 v20, 0x2010, v1
	v_add_u32_e32 v1, 0x2018, v1
	ds_read2_b32 v[18:19], v11 offset1:1
	ds_read2_b32 v[20:21], v20 offset1:1
	ds_read2_b32 v[22:23], v1 offset1:1
	s_waitcnt vmcnt(0)
	v_lshlrev_b32_e32 v14, 16, v2
	v_and_b32_e32 v15, 0xffff0000, v2
	s_waitcnt lgkmcnt(3)
	v_pk_mul_f32 v[14:15], v[16:17], v[14:15]
	s_nop 0
	v_cvt_pk_bf16_f32 v2, v14, v15
	v_lshlrev_b32_e32 v14, 16, v3
	v_and_b32_e32 v15, 0xffff0000, v3
	s_waitcnt lgkmcnt(2)
	v_pk_mul_f32 v[14:15], v[18:19], v[14:15]
	s_nop 0
	v_cvt_pk_bf16_f32 v3, v14, v15
	v_lshlrev_b32_e32 v14, 16, v4
	v_and_b32_e32 v15, 0xffff0000, v4
	s_waitcnt lgkmcnt(1)
	v_pk_mul_f32 v[14:15], v[20:21], v[14:15]
	s_nop 0
	v_cvt_pk_bf16_f32 v4, v14, v15
	v_lshlrev_b32_e32 v14, 16, v5
	v_and_b32_e32 v15, 0xffff0000, v5
	s_waitcnt lgkmcnt(0)
	v_pk_mul_f32 v[14:15], v[22:23], v[14:15]
	s_nop 0
	v_cvt_pk_bf16_f32 v5, v14, v15
	v_lshl_add_u64 v[14:15], s[0:1], 0, v[6:7]
	global_store_dwordx4 v[14:15], v[2:5], off
	s_cbranch_vccnz .LBB0_656
	s_sub_i32 s0, s34, s2
	s_addk_i32 s0, 0x80
	s_mul_hi_i32 s1, s0, 0x14000
	s_mul_i32 s0, s0, 0x14000
	v_readlane_b32 s4, v246, 28
	v_readlane_b32 s5, v246, 29
	s_add_u32 s2, s4, s0
	s_addc_u32 s23, s5, s1
	s_add_u32 s22, s2, s28
	s_addc_u32 s23, s23, s29
	v_lshl_add_u64 v[2:3], s[22:23], 0, v[12:13]
	global_load_dwordx4 v[2:5], v[2:3], off
	v_sub_u32_e32 v9, 0, v8
	v_and_b32_e32 v14, 0xffffff00, v8
	v_and_b32_e32 v9, 0xf8, v9
	v_or_b32_e32 v11, v9, v14
	v_ashrrev_i32_e32 v15, 4, v11
	v_lshlrev_b32_e32 v15, 2, v15
	v_lshl_add_u32 v11, v11, 2, v15
	ds_read_b32 v11, v11
	v_readlane_b32 s4, v247, 56
	v_readlane_b32 s5, v247, 57
	s_add_u32 s0, s4, s0
	s_addc_u32 s1, s5, s1
	s_add_u32 s0, s0, s28
	s_addc_u32 s1, s1, s29
	v_lshl_add_u64 v[12:13], s[0:1], 0, v[12:13]
	v_and_b32_e32 v10, 0xffffff00, v10
	v_or_b32_e32 v9, v10, v9
	s_movk_i32 s2, 0xf0
	s_waitcnt vmcnt(0)
	v_lshlrev_b32_e32 v1, 16, v2
	s_waitcnt lgkmcnt(0)
	v_mul_f32_e32 v15, v11, v1
	v_and_b32_e32 v1, 0xffff0000, v2
	v_xor_b32_e32 v2, 0xf0, v8
	v_ashrrev_i32_e32 v2, 4, v2
	v_xor_b32_e32 v11, 0xf8, v8
	v_lshlrev_b32_e32 v2, 2, v2
	v_lshl_add_u32 v2, v11, 2, v2
	ds_read_b32 v2, v2 offset:28
	s_waitcnt lgkmcnt(0)
	v_mul_f32_e32 v16, v2, v1
	v_sub_u32_e32 v1, 0xfe, v8
	v_and_b32_e32 v1, 0xfe, v1
	v_or_b32_e32 v11, v1, v14
	v_ashrrev_i32_e32 v17, 4, v11
	v_lshlrev_b32_e32 v17, 2, v17
	v_lshl_add_u32 v11, v11, 2, v17
	ds_read_b32 v11, v11
	v_lshlrev_b32_e32 v2, 16, v3
	v_and_b32_e32 v3, 0xffff0000, v3
	v_or_b32_e32 v1, v1, v10
	s_waitcnt lgkmcnt(0)
	v_mul_f32_e32 v17, v11, v2
	v_sub_u32_e32 v2, 0xfd, v8
	v_and_b32_e32 v2, 0xfd, v2
	v_or_b32_e32 v11, v2, v14
	v_ashrrev_i32_e32 v18, 4, v11
	v_lshlrev_b32_e32 v18, 2, v18
	v_lshl_add_u32 v11, v11, 2, v18
	ds_read_b32 v11, v11
	v_or_b32_e32 v2, v2, v10
	s_waitcnt lgkmcnt(0)
	v_mul_f32_e32 v18, v11, v3
	v_sub_u32_e32 v3, 0xfc, v8
	v_and_b32_e32 v3, 0xfc, v3
	v_or_b32_e32 v19, v3, v14
	v_ashrrev_i32_e32 v20, 4, v19
	v_lshlrev_b32_e32 v20, 2, v20
	v_lshl_add_u32 v19, v19, 2, v20
	ds_read_b32 v19, v19
	v_lshlrev_b32_e32 v11, 16, v4
	v_or_b32_e32 v3, v3, v10
	s_waitcnt lgkmcnt(0)
	v_mul_f32_e32 v19, v19, v11
	v_and_b32_e32 v11, 0xffff0000, v4
	v_sub_u32_e32 v4, 0xfb, v8
	v_and_b32_e32 v4, 0xfb, v4
	v_or_b32_e32 v20, v4, v14
	v_ashrrev_i32_e32 v21, 4, v20
	v_lshlrev_b32_e32 v21, 2, v21
	v_lshl_add_u32 v20, v20, 2, v21
	ds_read_b32 v20, v20
	v_lshlrev_b32_e32 v21, 16, v5
	s_waitcnt lgkmcnt(0)
	v_mul_f32_e32 v20, v20, v11
	v_sub_u32_e32 v11, 0xfa, v8
	v_and_b32_e32 v11, 0xfa, v11
	v_or_b32_e32 v22, v11, v14
	v_ashrrev_i32_e32 v23, 4, v22
	v_lshlrev_b32_e32 v23, 2, v23
	v_lshl_add_u32 v22, v22, 2, v23
	ds_read_b32 v22, v22
	s_waitcnt lgkmcnt(0)
	v_mul_f32_e32 v21, v22, v21
	v_and_b32_e32 v22, 0xffff0000, v5
	v_sub_u32_e32 v5, 0xf9, v8
	v_and_b32_e32 v5, 0xf9, v5
	v_or_b32_e32 v14, v5, v14
	v_ashrrev_i32_e32 v23, 4, v14
	v_lshlrev_b32_e32 v23, 2, v23
	v_lshl_add_u32 v14, v14, 2, v23
	ds_read_b32 v14, v14
	s_waitcnt lgkmcnt(0)
	v_mul_f32_e32 v22, v14, v22
	v_cvt_pk_bf16_f32 v14, v15, v16
	v_cvt_pk_bf16_f32 v15, v17, v18
	v_cvt_pk_bf16_f32 v16, v19, v20
	v_cvt_pk_bf16_f32 v17, v21, v22
	global_store_dwordx4 v[12:13], v[14:17], off
	v_lshl_add_u64 v[12:13], s[22:23], 0, v[6:7]
	global_load_dwordx4 v[12:15], v[12:13], off
	v_ashrrev_i32_e32 v17, 4, v9
	v_lshlrev_b32_e32 v17, 2, v17
	v_lshl_add_u32 v9, v9, 2, v17
	ds_read_b32 v9, v9
	v_lshl_add_u64 v[6:7], s[0:1], 0, v[6:7]
	s_waitcnt vmcnt(0)
	v_lshlrev_b32_e32 v16, 16, v12
	s_waitcnt lgkmcnt(0)
	v_mul_f32_e32 v9, v9, v16
	v_and_b32_e32 v16, 0xf8, v8
	v_bitop3_b32 v16, v10, s2, v16 bitop3:0x36
	v_ashrrev_i32_e32 v16, 4, v16
	s_movk_i32 s2, 0xf8
	v_bitop3_b32 v8, v10, s2, v8 bitop3:0x34
	v_lshlrev_b32_e32 v16, 2, v16
	v_lshl_add_u32 v8, v8, 2, v16
	v_ashrrev_i32_e32 v16, 4, v1
	v_lshlrev_b32_e32 v16, 2, v16
	ds_read_b32 v8, v8 offset:28
	v_lshl_add_u32 v1, v1, 2, v16
	ds_read_b32 v1, v1
	v_and_b32_e32 v12, 0xffff0000, v12
	s_waitcnt lgkmcnt(1)
	v_mul_f32_e32 v8, v8, v12
	v_lshlrev_b32_e32 v12, 16, v13
	s_waitcnt lgkmcnt(0)
	v_mul_f32_e32 v1, v1, v12
	v_and_b32_e32 v12, 0xffff0000, v13
	v_ashrrev_i32_e32 v13, 4, v2
	v_lshlrev_b32_e32 v13, 2, v13
	v_lshl_add_u32 v2, v2, 2, v13
	v_ashrrev_i32_e32 v13, 4, v3
	v_lshlrev_b32_e32 v13, 2, v13
	ds_read_b32 v2, v2
	v_lshl_add_u32 v3, v3, 2, v13
	ds_read_b32 v3, v3
	s_waitcnt lgkmcnt(1)
	v_mul_f32_e32 v12, v2, v12
	v_lshlrev_b32_e32 v2, 16, v14
	s_waitcnt lgkmcnt(0)
	v_mul_f32_e32 v13, v3, v2
	v_or_b32_e32 v3, v4, v10
	v_ashrrev_i32_e32 v4, 4, v3
	v_lshlrev_b32_e32 v4, 2, v4
	v_lshl_add_u32 v3, v3, 2, v4
	ds_read_b32 v3, v3
	v_and_b32_e32 v2, 0xffff0000, v14
	s_waitcnt lgkmcnt(0)
	v_mul_f32_e32 v4, v3, v2
	v_or_b32_e32 v3, v11, v10
	v_ashrrev_i32_e32 v11, 4, v3
	v_lshlrev_b32_e32 v11, 2, v11
	v_lshl_add_u32 v3, v3, 2, v11
	ds_read_b32 v3, v3
	v_lshlrev_b32_e32 v2, 16, v15
	v_cvt_pk_bf16_f32 v4, v13, v4
	s_waitcnt lgkmcnt(0)
	v_mul_f32_e32 v11, v3, v2
	v_or_b32_e32 v3, v5, v10
	v_ashrrev_i32_e32 v5, 4, v3
	v_lshlrev_b32_e32 v5, 2, v5
	v_lshl_add_u32 v3, v3, 2, v5
	ds_read_b32 v3, v3
	v_and_b32_e32 v2, 0xffff0000, v15
	s_waitcnt lgkmcnt(0)
	v_mul_f32_e32 v5, v3, v2
	v_cvt_pk_bf16_f32 v2, v9, v8
	v_cvt_pk_bf16_f32 v3, v1, v12
	v_cvt_pk_bf16_f32 v5, v11, v5
	global_store_dwordx4 v[6:7], v[2:5], off

.LBB0_690:
	s_waitcnt vmcnt(9)
	v_lshlrev_b32_e32 v46, 16, v12
	v_lshlrev_b32_e32 v12, 16, v1
	v_mov_b32_e32 v1, v2
	v_lshlrev_b32_e32 v50, 16, v5
	s_barrier
	s_waitcnt vmcnt(1)
	v_lshlrev_b32_e32 v20, 16, v32
	v_ashrrev_i32_e32 v5, 31, v1
	v_lshrrev_b32_e32 v5, 24, v5
	v_lshlrev_b32_e32 v32, 16, v31
	v_lshlrev_b32_e32 v38, 16, v28
	v_lshlrev_b32_e32 v42, 16, v24
	v_lshlrev_b32_e32 v24, 16, v22
	v_lshlrev_b32_e32 v28, 16, v16
	v_lshlrev_b32_e32 v16, 16, v11
	v_lshlrev_b32_e32 v22, 16, v8
	v_lshlrev_b32_e32 v8, 16, v3
	v_and_b32_e32 v3, 0xff, v1
	v_add_lshl_u32 v1, v1, v5, 4
	v_and_or_b32 v1, v1, s87, v3
	s_waitcnt vmcnt(0)
	v_lshlrev_b32_e32 v18, 16, v18
	v_lshlrev_b32_e32 v40, 16, v27
	v_lshlrev_b32_e32 v44, 16, v15
	v_lshlrev_b32_e32 v48, 16, v7
	v_ashrrev_i32_e32 v5, 4, v1
	v_lshlrev_b32_e32 v1, 3, v1
	v_pk_add_f32 v[52:53], v[12:13], v[28:29]
	v_pk_add_f32 v[12:13], v[12:13], v[28:29] neg_lo:[0,1] neg_hi:[0,1]
	v_pk_add_f32 v[28:29], v[22:23], v[38:39]
	v_mov_b32_e32 v54, v23
	v_mov_b32_e32 v55, v22
	v_sub_f32_e32 v56, v46, v20
	v_sub_f32_e32 v57, v16, v32
	v_lshl_add_u32 v1, v5, 3, v1
	v_sub_f32_e32 v22, v54, v39
	v_sub_f32_e32 v23, v55, v38
	v_pk_add_f32 v[38:39], v[8:9], v[24:25]
	v_sub_f32_e32 v54, v50, v42
	v_sub_f32_e32 v55, v8, v24
	v_sub_f32_e32 v24, v6, v30
	v_sub_f32_e32 v25, v9, v25
	v_pk_add_f32 v[8:9], v[16:17], v[32:33]
	v_sub_f32_e32 v16, v14, v36
	v_sub_f32_e32 v17, v17, v33
	v_mov_b32_e32 v51, v6
	v_mov_b32_e32 v43, v30
	v_sub_f32_e32 v7, v6, v30
	v_sub_f32_e32 v6, v48, v40
	v_add_f32_e32 v30, v46, v20
	v_add_f32_e32 v31, v14, v36
	v_sub_f32_e32 v21, v46, v20
	v_sub_f32_e32 v20, v10, v34
	v_sub_f32_e32 v15, v14, v36
	v_sub_f32_e32 v14, v44, v18
	v_pk_add_f32 v[32:33], v[50:51], v[42:43]
	v_sub_f32_e32 v43, v50, v42
	v_sub_f32_e32 v42, v4, v26
	v_pk_add_f32 v[50:51], v[6:7], v[20:21] neg_lo:[0,1] neg_hi:[0,1]
	v_add_f32_e32 v27, v4, v26
	v_add_f32_e32 v26, v48, v40
	v_add_f32_e32 v11, v10, v34
	v_add_f32_e32 v10, v44, v18
	v_pk_add_f32 v[18:19], v[6:7], v[20:21]
	v_pk_add_f32 v[6:7], v[38:39], v[8:9] neg_lo:[0,1] neg_hi:[0,1]
	v_cvt_f32_i32_e32 v3, v3
	v_pk_add_f32 v[4:5], v[26:27], v[10:11] neg_lo:[0,1] neg_hi:[0,1]
	v_pk_mul_f32 v[20:21], v[6:7], s[20:21] op_sel_hi:[1,0]
	v_mul_f32_e32 v40, 0x3f3504f3, v4
	v_pk_fma_f32 v[34:35], v[6:7], s[20:21], v[20:21] op_sel:[0,0,1] op_sel_hi:[1,0,0]
	v_mul_f32_e32 v44, 0x3f3504f3, v5
	v_mul_f32_e32 v49, 0xbf3504f3, v5
	v_pk_add_f32 v[4:5], v[52:53], v[28:29]
	v_pk_add_f32 v[6:7], v[38:39], v[8:9]
	v_pk_add_f32 v[8:9], v[32:33], v[30:31]
	v_pk_add_f32 v[10:11], v[26:27], v[10:11]
	v_pk_add_f32 v[26:27], v[4:5], v[8:9]
	v_pk_add_f32 v[38:39], v[6:7], v[10:11]
	v_add_f32_e32 v3, v3, v3
	v_pk_add_f32 v[60:61], v[26:27], v[38:39]
	v_pk_add_f32 v[36:37], v[32:33], v[30:31] neg_lo:[0,1] neg_hi:[0,1]
	v_mul_f32_e32 v3, 0x39800000, v3
	ds_write_b64 v1, v[60:61]
	v_pk_add_f32 v[60:61], v[12:13], v[22:23]
	v_pk_add_f32 v[62:63], v[12:13], v[22:23] neg_lo:[0,1] neg_hi:[0,1]
	s_mov_b32 s22, s71
	s_mov_b32 s23, s21
	v_add_f32_e32 v32, v55, v17
	s_mov_b32 s70, s21
	v_pk_add_f32 v[46:47], v[42:43], v[14:15]
	v_pk_add_f32 v[14:15], v[42:43], v[14:15] neg_lo:[0,1] neg_hi:[0,1]
	v_mul_f32_e32 v3, 0.5, v3
	v_mov_b32_e32 v61, v63
	v_sub_f32_e32 v30, v25, v57
	v_pk_mul_f32 v[62:63], v[32:33], s[70:71] op_sel_hi:[0,1]
	v_pk_mul_f32 v[66:67], v[18:19], s[22:23] op_sel_hi:[0,1]
	v_mul_f32_e32 v41, 0x3f3504f3, v47
	v_mul_f32_e32 v43, 0x3f3504f3, v51
	v_sin_f32_e32 v42, v3
	v_pk_fma_f32 v[64:65], v[30:31], s[22:23], v[62:63] op_sel_hi:[0,1,1]
	v_pk_fma_f32 v[62:63], v[30:31], s[22:23], v[62:63] op_sel_hi:[0,1,1] neg_lo:[0,0,1] neg_hi:[0,0,1]
	v_pk_fma_f32 v[68:69], v[14:15], s[70:71], v[66:67]
	v_pk_fma_f32 v[66:67], v[14:15], s[70:71], v[66:67] op_sel_hi:[0,1,1] neg_lo:[0,0,1] neg_hi:[0,0,1]
	v_cos_f32_e32 v58, v3
	v_mov_b32_e32 v65, v63
	v_add_f32_e32 v62, v43, v41
	v_fma_f32 v63, v51, s20, -v41
	v_mov_b32_e32 v69, v67
	v_pk_add_f32 v[66:67], v[60:61], v[62:63]
	v_pk_add_f32 v[70:71], v[64:65], v[68:69]
	v_xor_b32_e32 v59, 0x80000000, v42
	v_pk_add_f32 v[72:73], v[66:67], v[70:71]
	v_pk_add_f32 v[66:67], v[66:67], v[70:71] neg_lo:[0,1] neg_hi:[0,1]
	v_pk_mul_f32 v[70:71], v[72:73], v[42:43] op_sel_hi:[1,0]
	v_pk_fma_f32 v[74:75], v[72:73], v[58:59], v[70:71] op_sel:[0,0,1] op_sel_hi:[1,1,0]
	v_pk_fma_f32 v[70:71], v[72:73], v[58:59], v[70:71] op_sel:[0,0,1] op_sel_hi:[1,0,0] neg_lo:[0,0,1] neg_hi:[0,0,1]
	v_mov_b32_e32 v30, v31
	v_pk_add_f32 v[16:17], v[54:55], v[16:17] neg_lo:[0,1] neg_hi:[0,1]
	v_pk_add_f32 v[24:25], v[24:25], v[56:57]
	v_mov_b32_e32 v75, v71
	v_mov_b32_e32 v72, v28
	v_sub_f32_e32 v28, v44, v40
	v_sub_f32_e32 v29, v53, v29
	v_sub_f32_e32 v30, v33, v30
	v_sub_f32_e32 v31, v49, v40
	v_mov_b32_e32 v40, v34
	v_mov_b32_e32 v41, v36
	v_mov_b32_e32 v51, v19
	v_mov_b32_e32 v47, v15
	v_mul_f32_e32 v14, 0x3ec3ef15, v17
	v_mul_f32_e32 v18, 0x3f6c835e, v25
	v_mov_b32_e32 v43, v58
	v_sub_f32_e32 v21, v21, v20
	v_sub_f32_e32 v20, v52, v72
	v_pk_add_f32 v[32:33], v[28:29], v[36:37] op_sel:[1,0] op_sel_hi:[0,1]
	v_pk_add_f32 v[36:37], v[28:29], v[40:41]
	v_pk_add_f32 v[40:41], v[28:29], v[40:41] neg_lo:[0,1] neg_hi:[0,1]
	v_add_f32_e32 v14, v18, v14
	v_add_f32_e32 v15, v13, v23
	v_pk_mul_f32 v[18:19], v[46:47], s[72:73]
	v_mul_f32_e32 v48, v42, v42
	v_mul_f32_e32 v49, v43, v59
	v_mov_b32_e32 v37, v41
	v_pk_add_f32 v[44:45], v[20:21], v[30:31]
	v_pk_fma_f32 v[18:19], v[50:51], s[30:31], v[18:19] neg_lo:[0,0,1] neg_hi:[0,0,1]
	v_mul_f32_e32 v13, 0x3ec3ef15, v50
	v_pk_fma_f32 v[50:51], v[58:59], v[58:59], v[48:49] op_sel_hi:[0,1,1] neg_lo:[0,0,1] neg_hi:[0,0,1]
	v_pk_fma_f32 v[48:49], v[58:59], v[58:59], v[48:49] op_sel_hi:[0,1,1]
	v_pk_add_f32 v[20:21], v[20:21], v[30:31] neg_lo:[0,1] neg_hi:[0,1]
	v_pk_add_f32 v[30:31], v[44:45], v[36:37]
	v_pk_mov_b32 v[70:71], v[48:49], v[50:51] op_sel:[1,0]
	v_mov_b32_e32 v52, v50
	v_mov_b32_e32 v53, v49
	v_pk_mul_f32 v[70:71], v[48:49], v[70:71] op_sel:[1,0]
	v_pk_mul_f32 v[48:49], v[30:31], v[48:49] op_sel:[1,1] op_sel_hi:[0,1]
	v_pk_fma_f32 v[72:73], v[50:51], v[52:53], v[70:71] op_sel_hi:[0,1,1] neg_lo:[0,0,1] neg_hi:[0,0,1]
	v_pk_fma_f32 v[70:71], v[50:51], v[52:53], v[70:71] op_sel_hi:[0,1,1]
	v_pk_fma_f32 v[82:83], v[30:31], v[50:51], v[48:49] neg_lo:[0,0,1] neg_hi:[0,0,1]
	v_pk_fma_f32 v[30:31], v[30:31], v[50:51], v[48:49] op_sel_hi:[1,0,1]
	v_pk_add_f32 v[28:29], v[34:35], v[28:29] neg_lo:[0,1] neg_hi:[0,1]
	v_mov_b32_e32 v83, v31
	v_pk_add_f32 v[30:31], v[60:61], v[62:63] neg_lo:[0,1] neg_hi:[0,1]
	v_pk_mul_f32 v[62:63], v[52:53], v[70:71] op_sel:[0,1]
	v_pk_add_f32 v[48:49], v[64:65], v[68:69] neg_lo:[0,1] neg_hi:[0,1]
	v_pk_fma_f32 v[64:65], v[52:53], v[72:73], v[62:63] op_sel:[0,0,1] op_sel_hi:[1,0,0] neg_lo:[0,0,1] neg_hi:[0,0,1]
	v_pk_fma_f32 v[62:63], v[52:53], v[72:73], v[62:63] op_sel:[0,0,1] op_sel_hi:[1,0,0]
	v_pk_add_f32 v[34:35], v[32:33], v[28:29]
	v_sub_f32_e32 v28, v32, v28
	v_pk_mov_b32 v[32:33], v[62:63], v[64:65] op_sel:[1,0]
	ds_write_b64 v1, v[82:83] offset:4352
	v_mov_b32_e32 v68, v64
	v_mov_b32_e32 v69, v63
	v_pk_add_f32 v[82:83], v[20:21], v[20:21] op_sel:[0,1] op_sel_hi:[0,1]
	v_pk_mul_f32 v[28:29], v[28:29], v[32:33] op_sel_hi:[0,1]
	ds_write_b64 v1, v[74:75] offset:2176
	v_mov_b32_e32 v74, v72
	v_mov_b32_e32 v75, v71
	v_pk_fma_f32 v[32:33], v[82:83], v[64:65], v[28:29] neg_lo:[0,0,1] neg_hi:[0,0,1]
	v_pk_fma_f32 v[28:29], v[82:83], v[68:69], v[28:29]
	v_mov_b32_e32 v59, v42
	v_mov_b32_e32 v33, v29
	v_pk_mul_f32 v[28:29], v[74:75], v[70:71] op_sel:[0,1]
	ds_write_b64 v1, v[32:33] offset:13056
	v_pk_fma_f32 v[32:33], v[72:73], v[74:75], v[28:29] op_sel:[0,0,1] op_sel_hi:[0,1,0] neg_lo:[0,0,1] neg_hi:[0,0,1]
	v_pk_fma_f32 v[28:29], v[72:73], v[74:75], v[28:29] op_sel:[0,0,1] op_sel_hi:[0,1,0]
	v_pk_mov_b32 v[62:63], v[28:29], v[32:33] op_sel:[1,0]
	v_pk_mul_f32 v[56:57], v[42:43], v[52:53]
	v_pk_mul_f32 v[78:79], v[42:43], v[74:75]
	v_pk_add_f32 v[26:27], v[26:27], v[38:39] neg_lo:[0,1] neg_hi:[0,1]
	v_mov_b32_e32 v38, v32
	v_mov_b32_e32 v39, v29
	v_pk_mul_f32 v[42:43], v[42:43], v[62:63] op_sel_hi:[0,1]
	v_pk_fma_f32 v[64:65], v[58:59], v[38:39], v[42:43] op_sel_hi:[0,1,1]
	v_pk_fma_f32 v[42:43], v[58:59], v[38:39], v[42:43] op_sel_hi:[0,1,1] neg_lo:[0,0,1] neg_hi:[0,0,1]
	v_pk_mul_f32 v[54:55], v[58:59], v[52:53]
	v_pk_mul_f32 v[76:77], v[58:59], v[74:75]
	v_mov_b32_e32 v59, v43
	v_pk_mov_b32 v[42:43], v[42:43], v[64:65] op_sel:[1,0]
	v_pk_mul_f32 v[16:17], v[16:17], s[20:21]
	s_mov_b32 s28, s20
	s_mov_b32 s29, s71
	v_mul_f32_e32 v23, 0x3f6c835e, v46
	v_mov_b32_e32 v58, v64
	v_pk_mul_f32 v[42:43], v[66:67], v[42:43] op_sel:[1,0]
	v_pk_mul_f32 v[28:29], v[26:27], v[28:29] op_sel:[1,1] op_sel_hi:[0,1]
	v_pk_fma_f32 v[16:17], v[24:25], s[28:29], v[16:17] neg_lo:[0,0,1] neg_hi:[0,0,1]
	v_pk_add_f32 v[12:13], v[12:13], v[22:23] neg_lo:[0,1] neg_hi:[0,1]
	v_pk_mov_b32 v[80:81], v[70:71], v[72:73] op_sel:[1,0]
	v_pk_mul_f32 v[70:71], v[52:53], v[38:39]
	v_pk_mul_f32 v[52:53], v[52:53], v[62:63]
	v_pk_fma_f32 v[64:65], v[66:67], v[64:65], v[42:43] neg_lo:[0,0,1] neg_hi:[0,0,1]
	v_pk_fma_f32 v[42:43], v[66:67], v[58:59], v[42:43] op_sel_hi:[0,1,1]
	v_pk_fma_f32 v[66:67], v[26:27], v[32:33], v[28:29] neg_lo:[0,0,1] neg_hi:[0,0,1]
	v_pk_fma_f32 v[26:27], v[26:27], v[32:33], v[28:29] op_sel_hi:[1,0,1]
	v_pk_add_f32 v[22:23], v[14:15], v[18:19]
	v_pk_add_f32 v[24:25], v[16:17], v[12:13]
	v_mov_b32_e32 v82, v54
	v_mov_b32_e32 v83, v57
	v_pk_mov_b32 v[54:55], v[54:55], v[56:57] op_sel:[1,0]
	v_mov_b32_e32 v67, v27
	v_sub_f32_e32 v26, v44, v36
	v_sub_f32_e32 v27, v41, v45
	v_pk_add_f32 v[28:29], v[52:53], v[52:53] op_sel:[0,1] op_sel_hi:[0,1]
	v_pk_add_f32 v[46:47], v[22:23], v[24:25]
	v_pk_add_f32 v[56:57], v[82:83], v[54:55]
	v_pk_add_f32 v[54:55], v[82:83], v[54:55] neg_lo:[0,1] neg_hi:[0,1]
	v_pk_mul_f32 v[28:29], v[26:27], v[28:29] op_sel:[1,0] op_sel_hi:[0,1]
	v_pk_add_f32 v[32:33], v[70:71], v[70:71] op_sel:[0,1] op_sel_hi:[0,1] neg_lo:[0,1] neg_hi:[0,1]
	v_pk_mul_f32 v[84:85], v[46:47], v[54:55] op_sel:[0,1]
	v_pk_fma_f32 v[36:37], v[26:27], v[32:33], v[28:29] neg_lo:[0,0,1] neg_hi:[0,0,1]
	v_pk_fma_f32 v[26:27], v[26:27], v[32:33], v[28:29]
	v_pk_fma_f32 v[86:87], v[46:47], v[56:57], v[84:85] op_sel:[0,0,1] op_sel_hi:[1,1,0] neg_lo:[0,0,1] neg_hi:[0,0,1]
	v_pk_fma_f32 v[46:47], v[46:47], v[56:57], v[84:85] op_sel:[0,0,1] op_sel_hi:[1,0,0]
	v_mul_f32_e32 v84, v56, v38
	v_mul_f32_e32 v85, v55, v39
	v_mul_f32_e32 v82, v56, v62
	v_mul_f32_e32 v83, v55, v63
	v_mov_b32_e32 v37, v27
	v_mov_b32_e32 v27, v23
	v_sub_f32_e32 v22, v24, v22
	v_sub_f32_e32 v23, v27, v25
	v_pk_add_f32 v[24:25], v[82:83], v[82:83] op_sel:[0,1] op_sel_hi:[0,1]
	v_pk_add_f32 v[4:5], v[4:5], v[8:9] neg_lo:[0,1] neg_hi:[0,1]
	v_pk_add_f32 v[6:7], v[6:7], v[10:11] neg_lo:[0,1] neg_hi:[0,1]
	v_pk_mul_f32 v[24:25], v[22:23], v[24:25] op_sel:[1,0] op_sel_hi:[0,1]
	v_pk_add_f32 v[26:27], v[84:85], v[84:85] op_sel:[0,1] op_sel_hi:[0,1] neg_lo:[0,1] neg_hi:[0,1]
	v_pk_add_f32 v[8:9], v[4:5], v[6:7] op_sel:[0,1] op_sel_hi:[1,0]
	v_pk_add_f32 v[4:5], v[4:5], v[6:7] op_sel:[0,1] op_sel_hi:[1,0] neg_lo:[0,1] neg_hi:[0,1]
	v_pk_fma_f32 v[28:29], v[22:23], v[26:27], v[24:25] neg_lo:[0,0,1] neg_hi:[0,0,1]
	v_pk_fma_f32 v[22:23], v[22:23], v[26:27], v[24:25]
	v_pk_mul_f32 v[10:11], v[4:5], v[80:81] op_sel:[1,0]
	v_pk_add_f32 v[50:51], v[30:31], v[48:49] op_sel:[0,1] op_sel_hi:[1,0]
	v_pk_add_f32 v[30:31], v[30:31], v[48:49] op_sel:[0,1] op_sel_hi:[1,0] neg_lo:[0,1] neg_hi:[0,1]
	v_mov_b32_e32 v87, v47
	v_pk_mul_f32 v[88:89], v[74:75], v[62:63]
	v_mov_b32_e32 v90, v76
	v_mov_b32_e32 v91, v79
	v_pk_mov_b32 v[76:77], v[76:77], v[78:79] op_sel:[1,0]
	v_mov_b32_e32 v29, v23
	v_pk_fma_f32 v[22:23], v[8:9], v[72:73], v[10:11] neg_lo:[0,0,1] neg_hi:[0,0,1]
	v_pk_fma_f32 v[10:11], v[8:9], v[74:75], v[10:11] op_sel_hi:[0,1,1]
	v_pk_mov_b32 v[60:61], v[30:31], v[50:51] op_sel:[1,0]
	ds_write_b64 v1, v[86:87] offset:6528
	v_pk_mul_f32 v[86:87], v[74:75], v[38:39]
	v_pk_add_f32 v[78:79], v[90:91], v[76:77]
	v_pk_add_f32 v[76:77], v[90:91], v[76:77] neg_lo:[0,1] neg_hi:[0,1]
	v_mov_b32_e32 v7, v9
	v_mov_b32_e32 v23, v11
	v_pk_mov_b32 v[8:9], v[8:9], v[4:5] op_sel:[1,0]
	v_pk_add_f32 v[10:11], v[88:89], v[88:89] op_sel:[0,1] op_sel_hi:[0,1]
	v_mov_b32_e32 v90, v78
	v_mov_b32_e32 v91, v77
	v_pk_mul_f32 v[60:61], v[60:61], v[76:77] op_sel:[0,1]
	v_mov_b32_e32 v6, v4
	v_pk_mul_f32 v[8:9], v[8:9], v[10:11]
	v_pk_add_f32 v[10:11], v[86:87], v[86:87] op_sel:[0,1] op_sel_hi:[0,1] neg_lo:[0,1] neg_hi:[0,1]
	v_pk_fma_f32 v[76:77], v[50:51], v[78:79], v[60:61] neg_lo:[0,0,1] neg_hi:[0,0,1]
	v_fma_f32 v48, v50, v78, v60
	v_fma_f32 v49, v31, v78, v61
	v_pk_mul_f32 v[60:61], v[62:63], v[90:91]
	v_pk_fma_f32 v[4:5], v[4:5], v[10:11], v[8:9] neg_lo:[0,0,1] neg_hi:[0,0,1]
	v_pk_fma_f32 v[6:7], v[6:7], v[10:11], v[8:9]
	v_mov_b32_e32 v77, v49
	v_pk_mul_f32 v[48:49], v[38:39], v[90:91]
	v_mov_b32_e32 v5, v7
	v_pk_mov_b32 v[6:7], v[50:51], v[30:31] op_sel:[1,0]
	v_pk_add_f32 v[8:9], v[60:61], v[60:61] op_sel:[0,1] op_sel_hi:[0,1]
	ds_write_b64 v1, v[76:77] offset:10880
	v_mov_b32_e32 v65, v43
	ds_write_b64 v1, v[66:67] offset:17408
	ds_write_b64 v1, v[64:65] offset:19584
	ds_write_b64 v1, v[4:5] offset:26112
	v_pk_mul_f32 v[6:7], v[6:7], v[8:9]
	v_pk_add_f32 v[8:9], v[48:49], v[48:49] op_sel:[0,1] op_sel_hi:[0,1] neg_lo:[0,1] neg_hi:[0,1]
	v_pk_mul_f32 v[42:43], v[38:39], v[68:69]
	v_pk_fma_f32 v[10:11], v[30:31], v[8:9], v[6:7] neg_lo:[0,0,1] neg_hi:[0,0,1]
	v_fma_f32 v4, v30, v8, v6
	v_fma_f32 v5, v51, v9, v7
	v_pk_mul_f32 v[58:59], v[62:63], v[68:69]
	v_mov_b32_e32 v11, v5
	v_mov_b32_e32 v5, v42
	v_sub_f32_e32 v4, v20, v21
	v_sub_f32_e32 v5, v5, v43
	v_pk_add_f32 v[8:9], v[58:59], v[58:59] op_sel:[0,1] op_sel_hi:[0,1]
	v_mul_f32_e32 v6, v34, v8
	v_mul_f32_e32 v7, v4, v9
	v_pk_mov_b32 v[8:9], v[4:5], v[34:35] op_sel:[1,0]
	ds_write_b64 v1, v[10:11] offset:28288
	v_pk_fma_f32 v[10:11], v[4:5], v[8:9], v[6:7] neg_lo:[0,0,1] neg_hi:[0,0,1]
	v_pk_fma_f32 v[4:5], v[4:5], v[8:9], v[6:7]
	v_mov_b32_e32 v11, v5
	v_pk_mul_f32 v[46:47], v[74:75], v[54:55] op_sel:[0,1]
	v_sub_f32_e32 v4, v12, v16
	v_sub_f32_e32 v5, v15, v19
	v_pk_mov_b32 v[6:7], v[16:17], v[14:15] op_sel:[1,0]
	v_pk_mov_b32 v[8:9], v[12:13], v[18:19] op_sel:[1,0]
	v_pk_fma_f32 v[54:55], v[74:75], v[56:57], v[46:47] op_sel:[0,0,1] op_sel_hi:[1,0,0] neg_lo:[0,0,1] neg_hi:[0,0,1]
	v_pk_fma_f32 v[46:47], v[74:75], v[56:57], v[46:47] op_sel:[0,0,1] op_sel_hi:[1,0,0]
	v_pk_add_f32 v[6:7], v[6:7], v[8:9] neg_lo:[0,1] neg_hi:[0,1]
	v_mov_b32_e32 v57, v47
	v_pk_mov_b32 v[46:47], v[46:47], v[54:55] op_sel:[1,0]
	v_pk_add_f32 v[8:9], v[4:5], v[6:7]
	v_pk_add_f32 v[4:5], v[4:5], v[6:7] neg_lo:[0,1] neg_hi:[0,1]
	v_mov_b32_e32 v56, v54
	ds_write_b64 v1, v[10:11] offset:30464
	v_pk_mul_f32 v[10:11], v[4:5], v[46:47] op_sel:[1,0]
	v_pk_mul_f32 v[62:63], v[62:63], v[56:57]
	v_pk_fma_f32 v[12:13], v[8:9], v[54:55], v[10:11] neg_lo:[0,0,1] neg_hi:[0,0,1]
	v_pk_fma_f32 v[10:11], v[8:9], v[56:57], v[10:11] op_sel_hi:[0,1,1]
	v_pk_mul_f32 v[38:39], v[38:39], v[56:57]
	v_mov_b32_e32 v7, v9
	v_mov_b32_e32 v13, v11
	v_pk_mov_b32 v[8:9], v[8:9], v[4:5] op_sel:[1,0]
	v_pk_add_f32 v[10:11], v[62:63], v[62:63] op_sel:[0,1] op_sel_hi:[0,1]
	v_mov_b32_e32 v6, v4
	v_pk_mul_f32 v[8:9], v[8:9], v[10:11]
	v_pk_add_f32 v[10:11], v[38:39], v[38:39] op_sel:[0,1] op_sel_hi:[0,1] neg_lo:[0,1] neg_hi:[0,1]
	v_pk_fma_f32 v[4:5], v[4:5], v[10:11], v[8:9] neg_lo:[0,0,1] neg_hi:[0,0,1]
	v_pk_fma_f32 v[6:7], v[6:7], v[10:11], v[8:9]
	ds_write_b64 v1, v[36:37] offset:21760
	v_mov_b32_e32 v5, v7
	ds_write_b64 v1, v[28:29] offset:23936
	ds_write_b64 v1, v[22:23] offset:8704
	ds_write_b64 v1, v[12:13] offset:15232
	ds_write_b64 v1, v[4:5] offset:32640
	v_mov_b32_e32 v1, v2
	s_waitcnt lgkmcnt(0)
	s_barrier
	v_readlane_b32 s4, v246, 28
	v_ashrrev_i32_e32 v4, 31, v1
	v_lshrrev_b32_e32 v4, 28, v4
	v_and_b32_e32 v3, 15, v1
	v_add_u32_e32 v1, v1, v4
	v_ashrrev_i32_e32 v1, 4, v1
	v_lshlrev_b32_e32 v4, 11, v1
	v_lshl_add_u32 v1, v1, 7, v4
	v_lshl_or_b32 v1, v3, 3, v1
	ds_read2_b64 v[14:17], v1 offset1:17
	ds_read2_b64 v[18:21], v1 offset0:68 offset1:85
	ds_read2_b64 v[22:25], v1 offset0:136 offset1:153
	ds_read2_b64 v[26:29], v1 offset0:170 offset1:187
	ds_read2_b64 v[30:33], v1 offset0:204 offset1:221
	ds_read2_b64 v[34:37], v1 offset0:238 offset1:255
	ds_read2_b64 v[38:41], v1 offset0:34 offset1:51
	ds_read2_b64 v[42:45], v1 offset0:102 offset1:119
	s_waitcnt lgkmcnt(5)
	v_pk_add_f32 v[12:13], v[22:23], v[14:15]
	v_pk_add_f32 v[22:23], v[14:15], v[22:23] neg_lo:[0,1] neg_hi:[0,1]
	s_waitcnt lgkmcnt(2)
	v_pk_mov_b32 v[62:63], v[28:29], v[36:37] op_sel:[1,0]
	s_waitcnt lgkmcnt(1)
	v_pk_add_f32 v[58:59], v[40:41], v[28:29]
	s_waitcnt lgkmcnt(0)
	v_pk_mov_b32 v[10:11], v[40:41], v[44:45] op_sel:[1,0]
	v_sub_f32_e32 v28, v40, v28
	v_sub_f32_e32 v29, v45, v37
	v_pk_add_f32 v[14:15], v[18:19], v[30:31] neg_lo:[0,1] neg_hi:[0,1]
	v_pk_add_f32 v[46:47], v[30:31], v[18:19]
	v_pk_add_f32 v[48:49], v[16:17], v[24:25]
	v_pk_add_f32 v[50:51], v[20:21], v[32:33]
	v_pk_add_f32 v[60:61], v[44:45], v[36:37]
	v_pk_add_f32 v[62:63], v[10:11], v[62:63] neg_lo:[0,1] neg_hi:[0,1]
	v_pk_add_f32 v[40:41], v[28:29], v[28:29] op_sel:[0,1] op_sel_hi:[1,0] neg_lo:[0,1] neg_hi:[0,1]
	v_pk_mov_b32 v[18:19], v[14:15], v[14:15] op_sel:[1,0]
	v_pk_add_f32 v[30:31], v[22:23], v[14:15] op_sel:[0,1] op_sel_hi:[1,0]
	v_pk_add_f32 v[14:15], v[22:23], v[14:15] op_sel:[0,1] op_sel_hi:[1,0] neg_lo:[0,1] neg_hi:[0,1]
	v_pk_add_f32 v[28:29], v[28:29], v[28:29] op_sel:[0,1] op_sel_hi:[0,1]
	v_pk_add_f32 v[6:7], v[48:49], v[50:51]
	v_pk_add_f32 v[36:37], v[58:59], v[60:61] neg_lo:[0,1] neg_hi:[0,1]
	v_pk_add_f32 v[48:49], v[48:49], v[50:51] neg_lo:[0,1] neg_hi:[0,1]
	v_mov_b32_e32 v31, v15
	v_pk_add_f32 v[14:15], v[62:63], v[62:63] op_sel:[0,1] op_sel_hi:[0,1] neg_lo:[0,1] neg_hi:[0,1]
	v_pk_mul_f32 v[28:29], v[28:29], s[22:23]
	v_pk_add_f32 v[52:53], v[38:39], v[26:27]
	v_pk_add_f32 v[54:55], v[42:43], v[34:35]
	v_pk_add_f32 v[10:11], v[58:59], v[60:61]
	v_pk_add_f32 v[44:45], v[62:63], v[62:63] op_sel:[0,1] op_sel_hi:[1,0]
	v_pk_mul_f32 v[50:51], v[48:49], s[20:21] op_sel_hi:[1,0]
	v_mul_f32_e32 v36, 0x3f3504f3, v36
	v_mul_f32_e32 v58, 0x3f3504f3, v37
	v_mul_f32_e32 v61, 0xbf3504f3, v37
	v_pk_fma_f32 v[62:63], v[14:15], s[70:71], v[28:29]
	v_pk_fma_f32 v[14:15], v[14:15], s[70:71], v[28:29] neg_lo:[0,0,1] neg_hi:[0,0,1]
	v_pk_add_f32 v[4:5], v[12:13], v[46:47]
	v_pk_add_f32 v[56:57], v[52:53], v[54:55] neg_lo:[0,1] neg_hi:[0,1]
	v_cvt_f32_i32_e32 v3, v3
	v_mov_b32_e32 v63, v15
	v_mov_b32_e32 v14, v12
	v_sub_f32_e32 v12, v58, v36
	v_sub_f32_e32 v13, v13, v47
	v_sub_f32_e32 v14, v14, v46
	v_sub_f32_e32 v15, v51, v50
	v_mov_b32_e32 v29, v36
	v_pk_add_f32 v[36:37], v[12:13], v[56:57] op_sel:[1,0] op_sel_hi:[0,1]
	v_mov_b32_e32 v47, v56
	v_sub_f32_e32 v28, v53, v55
	v_sub_f32_e32 v29, v61, v29
	v_sub_f32_e32 v56, v38, v26
	v_sub_f32_e32 v57, v16, v24
	v_sub_f32_e32 v58, v43, v35
	v_sub_f32_e32 v59, v21, v33
	v_mul_f32_e32 v72, 0x3f6c835e, v44
	v_mul_f32_e32 v73, 0x3ec3ef15, v40
	v_add_f32_e32 v3, v3, v3
	v_sub_f32_e32 v16, v39, v27
	v_sub_f32_e32 v17, v17, v25
	v_sub_f32_e32 v21, v20, v32
	v_sub_f32_e32 v20, v42, v34
	v_pk_add_f32 v[26:27], v[56:57], v[58:59] neg_lo:[0,1] neg_hi:[0,1]
	v_pk_fma_f32 v[48:49], v[48:49], s[20:21], v[50:51] op_sel:[0,0,1] op_sel_hi:[1,0,0]
	v_mul_f32_e32 v3, 0x3b800000, v3
	v_pk_add_f32 v[60:61], v[56:57], v[58:59]
	v_pk_add_f32 v[24:25], v[16:17], v[20:21] neg_lo:[0,1] neg_hi:[0,1]
	v_pk_add_f32 v[16:17], v[16:17], v[20:21]
	v_mov_b32_e32 v45, v26
	v_mov_b32_e32 v33, v23
	v_mov_b32_e32 v21, v19
	v_mul_f32_e32 v3, 0.5, v3
	v_mov_b32_e32 v46, v48
	v_pk_add_f32 v[48:49], v[48:49], v[12:13] neg_lo:[0,1] neg_hi:[0,1]
	v_mul_f32_e32 v20, 0x3ec3ef15, v27
	v_pk_mul_f32 v[34:35], v[26:27], s[20:21]
	v_pk_mul_f32 v[26:27], v[44:45], s[72:73]
	v_mov_b32_e32 v41, v16
	v_sub_f32_e32 v18, v22, v18
	v_sub_f32_e32 v19, v73, v72
	v_pk_mul_f32 v[22:23], v[60:61], s[70:71] op_sel:[1,0]
	v_pk_add_f32 v[8:9], v[52:53], v[54:55]
	v_sin_f32_e32 v52, v3
	v_cos_f32_e32 v70, v3
	v_pk_add_f32 v[50:51], v[12:13], v[46:47]
	v_pk_add_f32 v[46:47], v[12:13], v[46:47] neg_lo:[0,1] neg_hi:[0,1]
	v_pk_add_f32 v[12:13], v[36:37], v[48:49]
	v_mul_f32_e32 v32, 0x3f6c835e, v17
	v_mul_f32_e32 v3, 0x3f3504f3, v60
	v_mul_f32_e32 v37, 0x3f3504f3, v24
	v_pk_fma_f32 v[34:35], v[16:17], s[28:29], v[34:35] neg_lo:[0,0,1] neg_hi:[0,0,1]
	v_pk_fma_f32 v[16:17], v[40:41], s[30:31], v[26:27] neg_lo:[0,0,1] neg_hi:[0,0,1]
	v_pk_fma_f32 v[26:27], v[24:25], s[22:23], v[22:23] op_sel:[1,0,0]
	v_pk_fma_f32 v[22:23], v[24:25], s[22:23], v[22:23] op_sel:[1,0,0] neg_lo:[0,0,1] neg_hi:[0,0,1]
	v_pk_add_f32 v[20:21], v[32:33], v[20:21]
	v_mov_b32_e32 v27, v23
	v_add_f32_e32 v22, v37, v3
	v_fma_f32 v23, v24, s20, -v3
	v_pk_add_f32 v[24:25], v[30:31], v[22:23]
	v_pk_add_f32 v[32:33], v[26:27], v[62:63]
	v_xor_b32_e32 v71, 0x80000000, v52
	v_pk_add_f32 v[38:39], v[32:33], v[24:25]
	v_pk_add_f32 v[64:65], v[4:5], v[8:9]
	v_pk_mul_f32 v[44:45], v[52:53], v[38:39] op_sel_hi:[0,1]
	v_pk_fma_f32 v[56:57], v[70:71], v[38:39], v[44:45] op_sel:[0,0,1] op_sel_hi:[1,1,0]
	v_pk_fma_f32 v[38:39], v[70:71], v[38:39], v[44:45] op_sel:[0,0,1] op_sel_hi:[0,1,0] neg_lo:[0,0,1] neg_hi:[0,0,1]
	v_mov_b32_e32 v57, v39
	v_mov_b32_e32 v53, v70
	v_pk_add_f32 v[66:67], v[6:7], v[10:11]
	v_mul_f32_e32 v38, v52, v52
	v_mul_f32_e32 v39, v53, v71
	v_pk_add_f32 v[68:69], v[66:67], v[64:65]
	v_pk_fma_f32 v[44:45], v[70:71], v[70:71], v[38:39] op_sel_hi:[0,1,1] neg_lo:[0,0,1] neg_hi:[0,0,1]
	v_pk_fma_f32 v[38:39], v[70:71], v[70:71], v[38:39] op_sel_hi:[0,1,1]
	v_mov_b32_e32 v51, v47
	v_pk_add_f32 v[54:55], v[14:15], v[28:29]
	ds_write2_b64 v1, v[68:69], v[56:57] offset1:17
	v_pk_mov_b32 v[68:69], v[38:39], v[44:45] op_sel:[1,0]
	v_pk_add_f32 v[14:15], v[14:15], v[28:29] neg_lo:[0,1] neg_hi:[0,1]
	v_pk_add_f32 v[28:29], v[54:55], v[50:51]
	v_mov_b32_e32 v56, v44
	v_mov_b32_e32 v57, v39
	v_pk_mul_f32 v[68:69], v[38:39], v[68:69] op_sel:[1,0]
	v_pk_mul_f32 v[38:39], v[28:29], v[38:39] op_sel:[1,1] op_sel_hi:[0,1]
	v_pk_fma_f32 v[72:73], v[44:45], v[56:57], v[68:69] op_sel_hi:[0,1,1] neg_lo:[0,0,1] neg_hi:[0,0,1]
	v_pk_fma_f32 v[68:69], v[44:45], v[56:57], v[68:69] op_sel_hi:[0,1,1]
	v_pk_fma_f32 v[82:83], v[28:29], v[44:45], v[38:39] neg_lo:[0,0,1] neg_hi:[0,0,1]
	v_pk_fma_f32 v[28:29], v[28:29], v[44:45], v[38:39] op_sel_hi:[1,0,1]
	v_pk_mul_f32 v[38:39], v[56:57], v[68:69] op_sel:[0,1]
	v_pk_add_f32 v[26:27], v[26:27], v[62:63] neg_lo:[0,1] neg_hi:[0,1]
	v_pk_fma_f32 v[44:45], v[56:57], v[72:73], v[38:39] op_sel:[0,0,1] op_sel_hi:[1,0,0] neg_lo:[0,0,1] neg_hi:[0,0,1]
	v_pk_fma_f32 v[38:39], v[56:57], v[72:73], v[38:39] op_sel:[0,0,1] op_sel_hi:[1,0,0]
	v_sub_f32_e32 v36, v36, v48
	v_mov_b32_e32 v63, v39
	v_pk_mov_b32 v[38:39], v[38:39], v[44:45] op_sel:[1,0]
	v_mov_b32_e32 v71, v52
	v_mov_b32_e32 v74, v72
	v_mov_b32_e32 v75, v69
	v_pk_add_f32 v[84:85], v[14:15], v[14:15] op_sel:[0,1] op_sel_hi:[0,1]
	v_pk_mul_f32 v[36:37], v[36:37], v[38:39] op_sel_hi:[0,1]
	v_pk_mul_f32 v[58:59], v[70:71], v[56:57]
	v_pk_mul_f32 v[60:61], v[52:53], v[56:57]
	v_mov_b32_e32 v62, v44
	v_pk_fma_f32 v[38:39], v[84:85], v[44:45], v[36:37] neg_lo:[0,0,1] neg_hi:[0,0,1]
	v_pk_mul_f32 v[44:45], v[74:75], v[68:69] op_sel:[0,1]
	v_pk_add_f32 v[24:25], v[24:25], v[32:33] neg_lo:[0,1] neg_hi:[0,1]
	v_pk_add_f32 v[32:33], v[34:35], v[18:19]
	v_pk_add_f32 v[40:41], v[20:21], v[16:17]
	v_pk_fma_f32 v[36:37], v[84:85], v[62:63], v[36:37]
	v_pk_fma_f32 v[48:49], v[72:73], v[74:75], v[44:45] op_sel:[0,0,1] op_sel_hi:[0,1,0] neg_lo:[0,0,1] neg_hi:[0,0,1]
	v_pk_fma_f32 v[44:45], v[72:73], v[74:75], v[44:45] op_sel:[0,0,1] op_sel_hi:[0,1,0]
	v_mov_b32_e32 v86, v58
	v_mov_b32_e32 v87, v61
	v_pk_mov_b32 v[58:59], v[58:59], v[60:61] op_sel:[1,0]
	v_pk_add_f32 v[42:43], v[32:33], v[40:41]
	v_mov_b32_e32 v39, v37
	v_pk_add_f32 v[36:37], v[64:65], v[66:67] neg_lo:[0,1] neg_hi:[0,1]
	v_pk_mov_b32 v[66:67], v[44:45], v[48:49] op_sel:[1,0]
	v_pk_add_f32 v[60:61], v[86:87], v[58:59]
	v_pk_add_f32 v[58:59], v[86:87], v[58:59] neg_lo:[0,1] neg_hi:[0,1]
	v_pk_mul_f32 v[76:77], v[70:71], v[74:75]
	v_pk_mul_f32 v[78:79], v[52:53], v[74:75]
	v_pk_add_f32 v[22:23], v[30:31], v[22:23] neg_lo:[0,1] neg_hi:[0,1]
	v_mov_b32_e32 v64, v48
	v_mov_b32_e32 v65, v45
	v_pk_mul_f32 v[52:53], v[52:53], v[66:67] op_sel_hi:[0,1]
	v_pk_mul_f32 v[88:89], v[42:43], v[58:59] op_sel:[0,1]
	v_pk_mov_b32 v[80:81], v[68:69], v[72:73] op_sel:[1,0]
	v_mov_b32_e32 v83, v29
	v_pk_add_f32 v[28:29], v[22:23], v[26:27] op_sel:[0,1] op_sel_hi:[1,0]
	v_pk_add_f32 v[22:23], v[22:23], v[26:27] op_sel:[0,1] op_sel_hi:[1,0] neg_lo:[0,1] neg_hi:[0,1]
	v_pk_fma_f32 v[68:69], v[70:71], v[64:65], v[52:53] op_sel_hi:[0,1,1]
	v_pk_fma_f32 v[52:53], v[70:71], v[64:65], v[52:53] op_sel_hi:[0,1,1] neg_lo:[0,0,1] neg_hi:[0,0,1]
	v_pk_fma_f32 v[90:91], v[42:43], v[60:61], v[88:89] op_sel:[0,0,1] op_sel_hi:[1,1,0] neg_lo:[0,0,1] neg_hi:[0,0,1]
	v_pk_fma_f32 v[42:43], v[42:43], v[60:61], v[88:89] op_sel:[0,0,1] op_sel_hi:[1,0,0]
	v_mov_b32_e32 v92, v76
	v_mov_b32_e32 v93, v79
	v_pk_mov_b32 v[76:77], v[76:77], v[78:79] op_sel:[1,0]
	v_pk_mov_b32 v[30:31], v[22:23], v[28:29] op_sel:[1,0]
	v_mov_b32_e32 v71, v53
	v_mov_b32_e32 v91, v43
	v_pk_mul_f32 v[42:43], v[74:75], v[58:59] op_sel:[0,1]
	v_pk_add_f32 v[78:79], v[92:93], v[76:77]
	v_pk_add_f32 v[76:77], v[92:93], v[76:77] neg_lo:[0,1] neg_hi:[0,1]
	v_pk_mov_b32 v[52:53], v[52:53], v[68:69] op_sel:[1,0]
	v_mov_b32_e32 v70, v68
	v_mov_b32_e32 v87, v59
	v_pk_fma_f32 v[58:59], v[74:75], v[60:61], v[42:43] op_sel:[0,0,1] op_sel_hi:[1,0,0] neg_lo:[0,0,1] neg_hi:[0,0,1]
	v_pk_fma_f32 v[42:43], v[74:75], v[60:61], v[42:43] op_sel:[0,0,1] op_sel_hi:[1,0,0]
	v_pk_mul_f32 v[30:31], v[30:31], v[76:77] op_sel:[0,1]
	v_pk_mul_f32 v[52:53], v[24:25], v[52:53] op_sel:[1,0]
	v_mov_b32_e32 v86, v60
	v_mov_b32_e32 v60, v58
	v_mov_b32_e32 v61, v43
	v_mov_b32_e32 v92, v78
	v_mov_b32_e32 v93, v77
	v_pk_fma_f32 v[76:77], v[28:29], v[78:79], v[30:31] neg_lo:[0,0,1] neg_hi:[0,0,1]
	v_fma_f32 v26, v28, v78, v30
	v_fma_f32 v27, v23, v78, v31
	v_pk_fma_f32 v[68:69], v[24:25], v[68:69], v[52:53] neg_lo:[0,0,1] neg_hi:[0,0,1]
	v_pk_fma_f32 v[24:25], v[24:25], v[70:71], v[52:53] op_sel_hi:[0,1,1]
	v_pk_mul_f32 v[44:45], v[36:37], v[44:45] op_sel:[1,1] op_sel_hi:[0,1]
	v_pk_mul_f32 v[84:85], v[56:57], v[64:65]
	v_pk_mul_f32 v[56:57], v[56:57], v[66:67]
	ds_write2_b64 v1, v[82:83], v[90:91] offset0:34 offset1:51
	v_pk_mul_f32 v[82:83], v[86:87], v[64:65]
	v_pk_mul_f32 v[86:87], v[86:87], v[66:67]
	v_pk_mul_f32 v[88:89], v[74:75], v[64:65]
	v_pk_mul_f32 v[90:91], v[74:75], v[66:67]
	v_mov_b32_e32 v77, v27
	v_pk_mul_f32 v[26:27], v[64:65], v[92:93]
	v_pk_mul_f32 v[30:31], v[66:67], v[92:93]
	v_mov_b32_e32 v69, v25
	v_pk_mul_f32 v[24:25], v[64:65], v[62:63]
	v_pk_mul_f32 v[52:53], v[66:67], v[62:63]
	v_pk_mul_f32 v[62:63], v[64:65], v[60:61]
	v_pk_mul_f32 v[64:65], v[66:67], v[60:61]
	v_pk_fma_f32 v[66:67], v[36:37], v[48:49], v[44:45] neg_lo:[0,0,1] neg_hi:[0,0,1]
	v_pk_fma_f32 v[36:37], v[36:37], v[48:49], v[44:45] op_sel_hi:[1,0,1]
	v_mov_b32_e32 v46, v54
	v_mov_b32_e32 v51, v55
	v_mov_b32_e32 v67, v37
	v_pk_add_f32 v[36:37], v[46:47], v[50:51] neg_lo:[0,1] neg_hi:[0,1]
	v_pk_add_f32 v[44:45], v[56:57], v[56:57] op_sel:[0,1] op_sel_hi:[0,1]
	v_pk_mul_f32 v[44:45], v[36:37], v[44:45] op_sel:[1,0] op_sel_hi:[0,1]
	v_pk_add_f32 v[46:47], v[84:85], v[84:85] op_sel:[0,1] op_sel_hi:[0,1] neg_lo:[0,1] neg_hi:[0,1]
	v_pk_fma_f32 v[48:49], v[36:37], v[46:47], v[44:45] neg_lo:[0,0,1] neg_hi:[0,0,1]
	v_pk_fma_f32 v[36:37], v[36:37], v[46:47], v[44:45]
	v_pk_add_f32 v[4:5], v[4:5], v[8:9] neg_lo:[0,1] neg_hi:[0,1]
	v_mov_b32_e32 v49, v37
	v_mov_b32_e32 v37, v41
	v_sub_f32_e32 v32, v32, v40
	v_sub_f32_e32 v33, v37, v33
	v_pk_add_f32 v[36:37], v[86:87], v[86:87] op_sel:[0,1] op_sel_hi:[0,1]
	v_pk_add_f32 v[6:7], v[6:7], v[10:11] neg_lo:[0,1] neg_hi:[0,1]
	v_pk_mul_f32 v[36:37], v[32:33], v[36:37] op_sel:[1,0] op_sel_hi:[0,1]
	v_pk_add_f32 v[40:41], v[82:83], v[82:83] op_sel:[0,1] op_sel_hi:[0,1] neg_lo:[0,1] neg_hi:[0,1]
	v_pk_add_f32 v[8:9], v[4:5], v[6:7] op_sel:[0,1] op_sel_hi:[1,0]
	v_pk_add_f32 v[4:5], v[4:5], v[6:7] op_sel:[0,1] op_sel_hi:[1,0] neg_lo:[0,1] neg_hi:[0,1]
	v_pk_fma_f32 v[44:45], v[32:33], v[40:41], v[36:37] neg_lo:[0,0,1] neg_hi:[0,0,1]
	v_pk_fma_f32 v[32:33], v[32:33], v[40:41], v[36:37]
	v_pk_mul_f32 v[10:11], v[4:5], v[80:81] op_sel:[1,0]
	v_mov_b32_e32 v45, v33
	v_pk_fma_f32 v[32:33], v[8:9], v[72:73], v[10:11] neg_lo:[0,0,1] neg_hi:[0,0,1]
	v_pk_fma_f32 v[10:11], v[8:9], v[74:75], v[10:11] op_sel_hi:[0,1,1]
	v_mov_b32_e32 v7, v9
	v_mov_b32_e32 v33, v11
	v_pk_mov_b32 v[8:9], v[8:9], v[4:5] op_sel:[1,0]
	v_pk_add_f32 v[10:11], v[90:91], v[90:91] op_sel:[0,1] op_sel_hi:[0,1]
	v_mov_b32_e32 v6, v4
	v_pk_mul_f32 v[8:9], v[8:9], v[10:11]
	v_pk_add_f32 v[10:11], v[88:89], v[88:89] op_sel:[0,1] op_sel_hi:[0,1] neg_lo:[0,1] neg_hi:[0,1]
	v_pk_fma_f32 v[4:5], v[4:5], v[10:11], v[8:9] neg_lo:[0,0,1] neg_hi:[0,0,1]
	v_pk_fma_f32 v[6:7], v[6:7], v[10:11], v[8:9]
	v_pk_mov_b32 v[8:9], v[28:29], v[22:23] op_sel:[1,0]
	v_pk_add_f32 v[10:11], v[30:31], v[30:31] op_sel:[0,1] op_sel_hi:[0,1]
	v_mov_b32_e32 v5, v7
	v_mov_b32_e32 v6, v22
	v_mov_b32_e32 v7, v29
	v_pk_mul_f32 v[8:9], v[8:9], v[10:11]
	v_pk_add_f32 v[10:11], v[26:27], v[26:27] op_sel:[0,1] op_sel_hi:[0,1] neg_lo:[0,1] neg_hi:[0,1]
	v_pk_fma_f32 v[22:23], v[22:23], v[10:11], v[8:9] neg_lo:[0,0,1] neg_hi:[0,0,1]
	v_pk_fma_f32 v[6:7], v[6:7], v[10:11], v[8:9]
	v_pk_add_f32 v[8:9], v[52:53], v[52:53] op_sel:[0,1] op_sel_hi:[0,1]
	v_mov_b32_e32 v23, v7
	ds_write2_b64 v1, v[4:5], v[22:23] offset0:204 offset1:221
	v_mov_b32_e32 v5, v24
	v_sub_f32_e32 v4, v14, v15
	v_sub_f32_e32 v5, v5, v25
	v_mul_f32_e32 v6, v12, v8
	v_mul_f32_e32 v7, v4, v9
	v_pk_mov_b32 v[8:9], v[4:5], v[12:13] op_sel:[1,0]
	v_pk_mov_b32 v[42:43], v[42:43], v[58:59] op_sel:[1,0]
	v_pk_fma_f32 v[10:11], v[4:5], v[8:9], v[6:7] neg_lo:[0,0,1] neg_hi:[0,0,1]
	v_pk_fma_f32 v[4:5], v[4:5], v[8:9], v[6:7]
	v_mov_b32_e32 v11, v5
	v_mov_b32_e32 v5, v20
	v_mov_b32_e32 v7, v16
	v_sub_f32_e32 v4, v18, v34
	v_sub_f32_e32 v5, v5, v7
	v_sub_f32_e32 v6, v35, v19
	v_sub_f32_e32 v7, v21, v17
	ds_write2_b64 v1, v[66:67], v[68:69] offset0:136 offset1:153
	v_pk_add_f32 v[8:9], v[6:7], v[4:5]
	v_pk_add_f32 v[12:13], v[4:5], v[6:7] neg_lo:[0,1] neg_hi:[0,1]
	v_sub_f32_e32 v4, v7, v5
	v_pk_mul_f32 v[4:5], v[4:5], v[42:43] op_sel_hi:[0,1]
	v_pk_fma_f32 v[6:7], v[8:9], v[58:59], v[4:5] neg_lo:[0,0,1] neg_hi:[0,0,1]
	v_pk_fma_f32 v[4:5], v[8:9], v[60:61], v[4:5] op_sel_hi:[0,1,1]
	v_mov_b32_e32 v7, v5
	ds_write2_b64 v1, v[38:39], v[6:7] offset0:102 offset1:119
	v_pk_mov_b32 v[4:5], v[8:9], v[12:13] op_sel:[1,0]
	v_pk_add_f32 v[6:7], v[64:65], v[64:65] op_sel:[0,1] op_sel_hi:[0,1]
	v_mov_b32_e32 v14, v12
	v_mov_b32_e32 v15, v9
	v_pk_mul_f32 v[4:5], v[4:5], v[6:7]
	v_pk_add_f32 v[6:7], v[62:63], v[62:63] op_sel:[0,1] op_sel_hi:[0,1] neg_lo:[0,1] neg_hi:[0,1]
	v_pk_fma_f32 v[8:9], v[12:13], v[6:7], v[4:5] neg_lo:[0,0,1] neg_hi:[0,0,1]
	v_pk_fma_f32 v[4:5], v[14:15], v[6:7], v[4:5]
	ds_write2_b64 v1, v[48:49], v[44:45] offset0:170 offset1:187
	v_mov_b32_e32 v9, v5
	ds_write2_b64 v1, v[32:33], v[76:77] offset0:68 offset1:85
	ds_write2_b64 v1, v[10:11], v[8:9] offset0:238 offset1:255
	v_mov_b32_e32 v1, v2
	s_waitcnt lgkmcnt(0)
	s_barrier
	v_readlane_b32 s5, v246, 29
	v_mul_lo_u32 v1, v1, s33
	ds_read2_b64 v[4:7], v1 offset1:1
	ds_read2_b64 v[8:11], v1 offset0:2 offset1:3
	ds_read2_b64 v[12:15], v1 offset0:8 offset1:9
	ds_read2_b64 v[16:19], v1 offset0:14 offset1:15
	ds_read2_b64 v[20:23], v1 offset0:12 offset1:13
	ds_read2_b64 v[24:27], v1 offset0:4 offset1:5
	ds_read2_b64 v[28:31], v1 offset0:6 offset1:7
	ds_read2_b64 v[32:35], v1 offset0:10 offset1:11
	s_waitcnt lgkmcnt(5)
	v_add_f32_e32 v1, v4, v12
	v_sub_f32_e32 v3, v4, v12
	s_waitcnt lgkmcnt(2)
	v_add_f32_e32 v4, v24, v20
	v_sub_f32_e32 v5, v25, v21
	v_add_f32_e32 v12, v1, v4
	v_sub_f32_e32 v1, v1, v4
	v_add_f32_e32 v4, v3, v5
	v_sub_f32_e32 v3, v3, v5
	v_add_f32_e32 v5, v6, v14
	v_add_f32_e32 v13, v7, v15
	v_sub_f32_e32 v6, v6, v14
	v_sub_f32_e32 v7, v7, v15
	v_add_f32_e32 v14, v26, v22
	v_add_f32_e32 v15, v27, v23
	v_sub_f32_e32 v20, v26, v22
	v_sub_f32_e32 v21, v27, v23
	v_add_f32_e32 v22, v5, v14
	v_add_f32_e32 v23, v13, v15
	v_sub_f32_e32 v5, v5, v14
	v_sub_f32_e32 v13, v13, v15
	v_add_f32_e32 v14, v6, v21
	v_sub_f32_e32 v15, v7, v20
	v_sub_f32_e32 v6, v6, v21
	v_add_f32_e32 v7, v7, v20
	s_waitcnt lgkmcnt(0)
	v_add_f32_e32 v20, v8, v32
	v_add_f32_e32 v21, v9, v33
	v_sub_f32_e32 v8, v8, v32
	v_sub_f32_e32 v9, v9, v33
	v_add_f32_e32 v24, v28, v16
	v_add_f32_e32 v25, v29, v17
	v_sub_f32_e32 v16, v28, v16
	v_sub_f32_e32 v17, v29, v17
	v_add_f32_e32 v20, v20, v24
	v_sub_f32_e32 v21, v21, v25
	v_add_f32_e32 v24, v8, v17
	v_sub_f32_e32 v25, v9, v16
	v_sub_f32_e32 v8, v8, v17
	v_add_f32_e32 v9, v9, v16
	v_add_f32_e32 v16, v10, v34
	v_add_f32_e32 v17, v11, v35
	v_sub_f32_e32 v11, v11, v35
	v_add_f32_e32 v26, v30, v18
	v_add_f32_e32 v27, v31, v19
	v_sub_f32_e32 v18, v30, v18
	v_sub_f32_e32 v10, v10, v34
	v_sub_f32_e32 v19, v31, v19
	v_add_f32_e32 v28, v16, v26
	v_add_f32_e32 v29, v17, v27
	v_sub_f32_e32 v16, v16, v26
	v_sub_f32_e32 v17, v17, v27
	v_sub_f32_e32 v27, v11, v18
	v_add_f32_e32 v11, v11, v18
	v_mul_f32_e32 v18, 0x3f6c835e, v14
	v_mul_f32_e32 v14, 0x3ec3ef15, v14
	v_mul_f32_e32 v5, 0x3f3504f3, v5
	v_add_f32_e32 v26, v10, v19
	v_fmac_f32_e32 v18, 0x3ec3ef15, v15
	v_fma_f32 v14, v15, s21, -v14
	v_fmamk_f32 v15, v13, 0x3f3504f3, v5
	v_fma_f32 v5, v13, s20, -v5
	v_mul_f32_e32 v13, 0x3ec3ef15, v6
	v_mul_f32_e32 v6, 0xbf6c835e, v6
	v_mul_f32_e32 v8, 0xbf3504f3, v8
	v_mul_f32_e32 v16, 0xbf3504f3, v16
	v_sub_f32_e32 v10, v10, v19
	v_fmac_f32_e32 v13, 0x3f6c835e, v7
	v_fmac_f32_e32 v6, 0x3ec3ef15, v7
	v_mul_f32_e32 v7, 0x3f3504f3, v24
	v_fmac_f32_e32 v8, 0x3f3504f3, v9
	v_mul_f32_e32 v9, 0x3ec3ef15, v26
	v_mul_f32_e32 v19, 0xbf6c835e, v26
	v_fmamk_f32 v24, v17, 0x3f3504f3, v16
	v_fmac_f32_e32 v16, 0xbf3504f3, v17
	v_mul_f32_e32 v17, 0x3ec3ef15, v11
	v_mul_f32_e32 v11, 0xbf6c835e, v11
	v_fmac_f32_e32 v7, 0x3f3504f3, v25
	v_fmac_f32_e32 v9, 0x3f6c835e, v27
	v_fmac_f32_e32 v19, 0x3ec3ef15, v27
	v_fma_f32 v17, v10, s76, -v17
	v_fmac_f32_e32 v11, 0x3ec3ef15, v10
	v_add_f32_e32 v10, v12, v20
	v_sub_f32_e32 v12, v12, v20
	v_add_f32_e32 v20, v22, v28
	v_sub_f32_e32 v22, v23, v29
	v_add_f32_e32 v23, v20, v10
	v_sub_f32_e32 v10, v10, v20
	v_add_f32_e32 v20, v12, v22
	v_sub_f32_e32 v12, v12, v22
	v_add_f32_e32 v22, v4, v7
	v_sub_f32_e32 v4, v4, v7
	v_add_f32_e32 v7, v18, v9
	v_sub_f32_e32 v9, v14, v19
	v_add_f32_e32 v18, v9, v4
	v_sub_f32_e32 v4, v4, v9
	v_add_f32_e32 v9, v1, v21
	v_sub_f32_e32 v1, v1, v21
	v_add_f32_e32 v15, v15, v24
	v_sub_f32_e32 v5, v5, v16
	v_add_f32_e32 v16, v9, v15
	v_sub_f32_e32 v9, v9, v15
	v_add_f32_e32 v15, v1, v5
	v_sub_f32_e32 v1, v1, v5
	v_add_f32_e32 v5, v3, v8
	v_sub_f32_e32 v3, v3, v8
	v_add_f32_e32 v8, v13, v17
	v_sub_f32_e32 v6, v6, v11
	v_add_f32_e32 v11, v8, v5
	v_sub_f32_e32 v5, v5, v8
	v_add_f32_e32 v8, v6, v3
	v_sub_f32_e32 v3, v3, v6
	v_lshlrev_b32_e32 v6, 4, v2
	v_and_b32_e32 v6, 0xf0, v6
	v_ashrrev_i32_e32 v13, 4, v2
	v_add_u32_e32 v6, v6, v13
	v_ashrrev_i32_e32 v17, 4, v6
	v_lshlrev_b32_e32 v19, 2, v6
	v_mul_f32_e32 v13, 0x3ab504f3, v23
	v_lshl_add_u32 v17, v17, 2, v19
	s_barrier
	ds_write_b32 v17, v13
	v_add_u32_e32 v13, 0x100, v6
	v_add_f32_e32 v14, v7, v22
	v_ashrrev_i32_e32 v13, 4, v13
	v_mul_f32_e32 v14, 0x3ab504f3, v14
	v_lshl_add_u32 v13, v13, 2, v19
	ds_write_b32 v13, v14 offset:1024
	v_add_u32_e32 v13, 0x200, v6
	v_ashrrev_i32_e32 v13, 4, v13
	v_mul_f32_e32 v14, 0x3ab504f3, v16
	v_lshl_add_u32 v13, v13, 2, v19
	ds_write_b32 v13, v14 offset:2048
	v_add_u32_e32 v13, 0x300, v6
	v_ashrrev_i32_e32 v13, 4, v13
	v_mul_f32_e32 v11, 0x3ab504f3, v11
	v_lshl_add_u32 v13, v13, 2, v19
	ds_write_b32 v13, v11 offset:3072
	v_add_u32_e32 v11, 0x400, v6
	v_ashrrev_i32_e32 v11, 4, v11
	v_mul_f32_e32 v13, 0x3ab504f3, v20
	v_lshl_add_u32 v11, v11, 2, v19
	ds_write_b32 v11, v13 offset:4096
	v_add_u32_e32 v11, 0x500, v6
	v_ashrrev_i32_e32 v11, 4, v11
	v_mul_f32_e32 v13, 0x3ab504f3, v18
	v_lshl_add_u32 v11, v11, 2, v19
	ds_write_b32 v11, v13 offset:5120
	v_add_u32_e32 v11, 0x600, v6
	v_ashrrev_i32_e32 v11, 4, v11
	v_mul_f32_e32 v13, 0x3ab504f3, v15
	v_lshl_add_u32 v11, v11, 2, v19
	ds_write_b32 v11, v13 offset:6144
	v_add_u32_e32 v11, 0x700, v6
	v_ashrrev_i32_e32 v11, 4, v11
	v_mul_f32_e32 v8, 0x3ab504f3, v8
	v_lshl_add_u32 v11, v11, 2, v19
	ds_write_b32 v11, v8 offset:7168
	v_add_u32_e32 v8, 0x800, v6
	v_ashrrev_i32_e32 v8, 4, v8
	v_mul_f32_e32 v10, 0x3ab504f3, v10
	v_lshl_add_u32 v8, v8, 2, v19
	ds_write_b32 v8, v10 offset:8192
	v_add_u32_e32 v8, 0x900, v6
	v_sub_f32_e32 v7, v22, v7
	v_ashrrev_i32_e32 v8, 4, v8
	v_mul_f32_e32 v7, 0x3ab504f3, v7
	v_lshl_add_u32 v8, v8, 2, v19
	ds_write_b32 v8, v7 offset:9216
	v_add_u32_e32 v7, 0xa00, v6
	v_ashrrev_i32_e32 v7, 4, v7
	v_mul_f32_e32 v8, 0x3ab504f3, v9
	v_lshl_add_u32 v7, v7, 2, v19
	ds_write_b32 v7, v8 offset:10240
	v_add_u32_e32 v7, 0xb00, v6
	v_ashrrev_i32_e32 v7, 4, v7
	v_mul_f32_e32 v5, 0x3ab504f3, v5
	v_lshl_add_u32 v7, v7, 2, v19
	ds_write_b32 v7, v5 offset:11264
	v_add_u32_e32 v5, 0xc00, v6
	v_ashrrev_i32_e32 v5, 4, v5
	v_mul_f32_e32 v7, 0x3ab504f3, v12
	v_lshl_add_u32 v5, v5, 2, v19
	ds_write_b32 v5, v7 offset:12288
	v_add_u32_e32 v5, 0xd00, v6
	v_ashrrev_i32_e32 v5, 4, v5
	v_mul_f32_e32 v4, 0x3ab504f3, v4
	v_lshl_add_u32 v5, v5, 2, v19
	ds_write_b32 v5, v4 offset:13312
	v_add_u32_e32 v4, 0xe00, v6
	v_ashrrev_i32_e32 v4, 4, v4
	v_mul_f32_e32 v1, 0x3ab504f3, v1
	v_lshl_add_u32 v4, v4, 2, v19
	s_add_u32 s22, s4, s0
	ds_write_b32 v4, v1 offset:14336
	s_addc_u32 s23, s5, s1
	v_lshlrev_b32_e32 v4, 3, v2
	v_add_u32_e32 v1, 0xf00, v6
	s_add_u32 s22, s22, s2
	v_ashrrev_i32_e32 v5, 31, v4
	v_ashrrev_i32_e32 v1, 4, v1
	s_addc_u32 s23, s23, 0
	v_lshlrev_b64 v[6:7], 1, v[4:5]
	v_mul_f32_e32 v3, 0x3ab504f3, v3
	v_lshl_add_u32 v1, v1, 2, v19
	v_lshl_add_u64 v[8:9], s[22:23], 0, v[6:7]
	ds_write_b32 v1, v3 offset:15360
	s_waitcnt lgkmcnt(0)
	s_barrier
	global_load_dwordx4 v[8:11], v[8:9], off
	v_bfe_i32 v1, v2, 1, 28
	v_lshlrev_b32_e32 v5, 5, v2
	v_lshl_add_u32 v1, v1, 2, v5
	ds_read2_b32 v[12:13], v1 offset1:1
	ds_read2_b32 v[14:15], v1 offset0:2 offset1:3
	ds_read2_b32 v[16:17], v1 offset0:4 offset1:5
	ds_read2_b32 v[18:19], v1 offset0:6 offset1:7
	v_readlane_b32 s4, v247, 56
	v_readlane_b32 s5, v247, 57
	s_add_u32 s0, s4, s0
	s_addc_u32 s1, s5, s1
	s_add_u32 s0, s0, s2
	s_addc_u32 s1, s1, 0
	s_and_b64 vcc, exec, s[36:37]
	s_waitcnt vmcnt(0)
	v_lshlrev_b32_e32 v2, 16, v8
	v_and_b32_e32 v3, 0xffff0000, v8
	s_waitcnt lgkmcnt(3)
	v_pk_mul_f32 v[2:3], v[12:13], v[2:3]
	s_nop 0
	v_cvt_pk_bf16_f32 v8, v2, v3
	v_lshlrev_b32_e32 v2, 16, v9
	v_and_b32_e32 v3, 0xffff0000, v9
	s_waitcnt lgkmcnt(2)
	v_pk_mul_f32 v[2:3], v[14:15], v[2:3]
	s_nop 0
	v_cvt_pk_bf16_f32 v9, v2, v3
	v_lshlrev_b32_e32 v2, 16, v10
	v_and_b32_e32 v3, 0xffff0000, v10
	s_waitcnt lgkmcnt(1)
	v_pk_mul_f32 v[2:3], v[16:17], v[2:3]
	s_nop 0
	v_cvt_pk_bf16_f32 v10, v2, v3
	v_lshlrev_b32_e32 v2, 16, v11
	v_and_b32_e32 v3, 0xffff0000, v11
	s_waitcnt lgkmcnt(0)
	v_pk_mul_f32 v[2:3], v[18:19], v[2:3]
	s_nop 0
	v_cvt_pk_bf16_f32 v11, v2, v3
	v_lshl_add_u64 v[2:3], s[0:1], 0, v[6:7]
	global_store_dwordx4 v[2:3], v[8:11], off
	s_nop 1
	v_add_u32_e32 v8, 0x800, v4
	v_ashrrev_i32_e32 v9, 31, v8
	v_lshlrev_b64 v[2:3], 1, v[8:9]
	v_lshl_add_u64 v[10:11], s[22:23], 0, v[2:3]
	global_load_dwordx4 v[10:13], v[10:11], off
	v_ashrrev_i32_e32 v1, 4, v8
	v_lshl_add_u32 v1, v1, 2, v5
	v_add_u32_e32 v5, 0x2000, v1
	ds_read2_b32 v[16:17], v5 offset1:1
	v_add_u32_e32 v9, 0x2008, v1
	v_add_u32_e32 v20, 0x2010, v1
	v_add_u32_e32 v1, 0x2018, v1
	ds_read2_b32 v[18:19], v9 offset1:1
	ds_read2_b32 v[20:21], v20 offset1:1
	ds_read2_b32 v[22:23], v1 offset1:1
	s_waitcnt vmcnt(0)
	v_lshlrev_b32_e32 v14, 16, v10
	v_and_b32_e32 v15, 0xffff0000, v10
	s_waitcnt lgkmcnt(3)
	v_pk_mul_f32 v[14:15], v[16:17], v[14:15]
	s_nop 0
	v_cvt_pk_bf16_f32 v10, v14, v15
	v_lshlrev_b32_e32 v14, 16, v11
	v_and_b32_e32 v15, 0xffff0000, v11
	s_waitcnt lgkmcnt(2)
	v_pk_mul_f32 v[14:15], v[18:19], v[14:15]
	s_nop 0
	v_cvt_pk_bf16_f32 v11, v14, v15
	v_lshlrev_b32_e32 v14, 16, v12
	v_and_b32_e32 v15, 0xffff0000, v12
	s_waitcnt lgkmcnt(1)
	v_pk_mul_f32 v[14:15], v[20:21], v[14:15]
	s_nop 0
	v_cvt_pk_bf16_f32 v12, v14, v15
	v_lshlrev_b32_e32 v14, 16, v13
	v_and_b32_e32 v15, 0xffff0000, v13
	s_waitcnt lgkmcnt(0)
	v_pk_mul_f32 v[14:15], v[22:23], v[14:15]
	s_nop 0
	v_cvt_pk_bf16_f32 v13, v14, v15
	v_lshl_add_u64 v[14:15], s[0:1], 0, v[2:3]
	global_store_dwordx4 v[14:15], v[10:13], off
	s_cbranch_vccnz .LBB0_692
	s_sub_i32 s0, s34, s24
	s_addk_i32 s0, 0x80
	s_mul_hi_i32 s22, s0, 0x14000
	s_mul_i32 s23, s0, 0x14000
	v_readlane_b32 s0, v246, 28
	v_readlane_b32 s1, v246, 29
	s_add_u32 s0, s0, s23
	s_addc_u32 s1, s1, s22
	s_add_u32 s0, s0, s2
	s_addc_u32 s1, s1, 0
	v_lshl_add_u64 v[10:11], s[0:1], 0, v[6:7]
	global_load_dwordx4 v[10:13], v[10:11], off
	v_and_b32_e32 v1, 0xfffff000, v4
	v_sub_u32_e32 v5, 0, v4
	v_xor_b32_e32 v9, 0xff0, v4
	v_sub_u32_e32 v15, 0xffe, v4
	v_sub_u32_e32 v16, 0xffd, v4
	v_sub_u32_e32 v17, 0xffc, v4
	v_sub_u32_e32 v18, 0xffb, v4
	v_sub_u32_e32 v19, 0xffa, v4
	v_sub_u32_e32 v20, 0xff9, v4
	s_movk_i32 s7, 0xff8
	s_movk_i32 s6, 0xffe
	s_movk_i32 s8, 0xffd
	s_movk_i32 s9, 0xffc
	s_movk_i32 s10, 0xffb
	s_movk_i32 s11, 0xffa
	s_movk_i32 s12, 0xff9
	v_and_or_b32 v5, v5, s7, v1
	v_ashrrev_i32_e32 v9, 4, v9
	v_and_or_b32 v15, v15, s6, v1
	v_and_or_b32 v16, v16, s8, v1
	v_and_or_b32 v17, v17, s9, v1
	v_and_or_b32 v18, v18, s10, v1
	v_and_or_b32 v19, v19, s11, v1
	v_and_or_b32 v1, v20, s12, v1
	v_xor_b32_e32 v14, 0xff8, v4
	v_ashrrev_i32_e32 v20, 4, v5
	v_lshlrev_b32_e32 v9, 2, v9
	v_ashrrev_i32_e32 v21, 4, v15
	v_ashrrev_i32_e32 v22, 4, v16
	v_ashrrev_i32_e32 v23, 4, v17
	v_ashrrev_i32_e32 v24, 4, v18
	v_ashrrev_i32_e32 v25, 4, v19
	v_ashrrev_i32_e32 v26, 4, v1
	v_lshlrev_b32_e32 v20, 2, v20
	v_lshl_add_u32 v9, v14, 2, v9
	v_lshlrev_b32_e32 v14, 2, v21
	v_lshlrev_b32_e32 v21, 2, v22
	v_lshlrev_b32_e32 v22, 2, v23
	v_lshlrev_b32_e32 v23, 2, v24
	v_lshlrev_b32_e32 v24, 2, v25
	v_lshlrev_b32_e32 v25, 2, v26
	v_lshl_add_u32 v5, v5, 2, v20
	v_lshl_add_u32 v14, v15, 2, v14
	v_lshl_add_u32 v15, v16, 2, v21
	v_lshl_add_u32 v16, v17, 2, v22
	v_lshl_add_u32 v17, v18, 2, v23
	v_lshl_add_u32 v18, v19, 2, v24
	v_lshl_add_u32 v1, v1, 2, v25
	ds_read_b32 v5, v5
	ds_read_b32 v9, v9 offset:28
	ds_read_b32 v19, v14
	ds_read_b32 v20, v15
	ds_read_b32 v16, v16
	ds_read_b32 v17, v17
	ds_read_b32 v18, v18
	ds_read_b32 v1, v1
	v_readlane_b32 s4, v247, 56
	v_readlane_b32 s5, v247, 57
	s_add_u32 s23, s4, s23
	v_lshl_add_u64 v[14:15], s[0:1], 0, v[2:3]
	s_addc_u32 s1, s5, s22
	s_add_u32 s0, s23, s2
	s_addc_u32 s1, s1, 0
	v_lshl_add_u64 v[6:7], s[0:1], 0, v[6:7]
	v_lshl_add_u64 v[2:3], s[0:1], 0, v[2:3]
	s_waitcnt vmcnt(0)
	v_lshlrev_b32_e32 v21, 16, v10
	v_and_b32_e32 v10, 0xffff0000, v10
	v_lshlrev_b32_e32 v22, 16, v11
	v_and_b32_e32 v11, 0xffff0000, v11
	v_lshlrev_b32_e32 v23, 16, v12
	v_and_b32_e32 v12, 0xffff0000, v12
	v_lshlrev_b32_e32 v24, 16, v13
	v_and_b32_e32 v13, 0xffff0000, v13
	s_waitcnt lgkmcnt(7)
	v_mul_f32_e32 v5, v5, v21
	s_waitcnt lgkmcnt(6)
	v_mul_f32_e32 v9, v9, v10
	s_waitcnt lgkmcnt(5)
	v_mul_f32_e32 v19, v19, v22
	s_waitcnt lgkmcnt(4)
	v_mul_f32_e32 v11, v20, v11
	s_waitcnt lgkmcnt(3)
	v_mul_f32_e32 v16, v16, v23
	s_waitcnt lgkmcnt(2)
	v_mul_f32_e32 v12, v17, v12
	s_waitcnt lgkmcnt(1)
	v_mul_f32_e32 v17, v18, v24
	s_waitcnt lgkmcnt(0)
	v_mul_f32_e32 v1, v1, v13
	v_cvt_pk_bf16_f32 v10, v5, v9
	v_cvt_pk_bf16_f32 v11, v19, v11
	v_cvt_pk_bf16_f32 v12, v16, v12
	v_cvt_pk_bf16_f32 v13, v17, v1
	global_store_dwordx4 v[6:7], v[10:13], off
	global_load_dwordx4 v[10:13], v[14:15], off
	v_and_b32_e32 v1, 0xfffff000, v8
	v_sub_u32_e32 v5, 0x800, v4
	v_xor_b32_e32 v6, 0xff0, v8
	v_xor_b32_e32 v7, 0xff8, v8
	v_sub_u32_e32 v8, 0x7fe, v4
	v_sub_u32_e32 v9, 0x7fd, v4
	v_sub_u32_e32 v14, 0x7fc, v4
	v_sub_u32_e32 v15, 0x7fb, v4
	v_sub_u32_e32 v16, 0x7fa, v4
	v_sub_u32_e32 v4, 0x7f9, v4
	v_and_or_b32 v5, v5, s7, v1
	v_ashrrev_i32_e32 v6, 4, v6
	v_and_or_b32 v8, v8, s6, v1
	v_and_or_b32 v9, v9, s8, v1
	v_and_or_b32 v14, v14, s9, v1
	v_and_or_b32 v15, v15, s10, v1
	v_and_or_b32 v16, v16, s11, v1
	v_and_or_b32 v1, v4, s12, v1
	v_ashrrev_i32_e32 v4, 4, v5
	v_lshlrev_b32_e32 v6, 2, v6
	v_ashrrev_i32_e32 v17, 4, v8
	v_ashrrev_i32_e32 v18, 4, v9
	v_ashrrev_i32_e32 v19, 4, v14
	v_ashrrev_i32_e32 v20, 4, v15
	v_ashrrev_i32_e32 v21, 4, v16
	v_ashrrev_i32_e32 v22, 4, v1
	v_lshlrev_b32_e32 v4, 2, v4
	v_lshl_add_u32 v6, v7, 2, v6
	v_lshlrev_b32_e32 v7, 2, v17
	v_lshlrev_b32_e32 v17, 2, v18
	v_lshlrev_b32_e32 v18, 2, v19
	v_lshlrev_b32_e32 v19, 2, v20
	v_lshlrev_b32_e32 v20, 2, v21
	v_lshlrev_b32_e32 v21, 2, v22
	v_lshl_add_u32 v4, v5, 2, v4
	v_lshl_add_u32 v5, v8, 2, v7
	v_lshl_add_u32 v7, v9, 2, v17
	v_lshl_add_u32 v8, v14, 2, v18
	v_lshl_add_u32 v9, v15, 2, v19
	v_lshl_add_u32 v14, v16, 2, v20
	v_lshl_add_u32 v1, v1, 2, v21
	ds_read_b32 v4, v4
	ds_read_b32 v6, v6 offset:28
	ds_read_b32 v5, v5
	ds_read_b32 v7, v7
	ds_read_b32 v8, v8
	ds_read_b32 v9, v9
	ds_read_b32 v14, v14
	ds_read_b32 v1, v1
	s_waitcnt vmcnt(0)
	v_lshlrev_b32_e32 v15, 16, v10
	v_and_b32_e32 v10, 0xffff0000, v10
	v_lshlrev_b32_e32 v16, 16, v11
	v_and_b32_e32 v11, 0xffff0000, v11
	v_lshlrev_b32_e32 v17, 16, v12
	v_and_b32_e32 v12, 0xffff0000, v12
	v_lshlrev_b32_e32 v18, 16, v13
	v_and_b32_e32 v13, 0xffff0000, v13
	s_waitcnt lgkmcnt(7)
	v_mul_f32_e32 v4, v4, v15
	s_waitcnt lgkmcnt(6)
	v_mul_f32_e32 v6, v6, v10
	s_waitcnt lgkmcnt(5)
	v_mul_f32_e32 v5, v5, v16
	s_waitcnt lgkmcnt(4)
	v_mul_f32_e32 v7, v7, v11
	s_waitcnt lgkmcnt(3)
	v_mul_f32_e32 v8, v8, v17
	s_waitcnt lgkmcnt(2)
	v_mul_f32_e32 v9, v9, v12
	s_waitcnt lgkmcnt(1)
	v_mul_f32_e32 v10, v14, v18
	s_waitcnt lgkmcnt(0)
	v_mul_f32_e32 v1, v1, v13
	v_cvt_pk_bf16_f32 v4, v4, v6
	v_cvt_pk_bf16_f32 v5, v5, v7
	v_cvt_pk_bf16_f32 v6, v8, v9
	v_cvt_pk_bf16_f32 v7, v10, v1
	global_store_dwordx4 v[2:3], v[4:7], off

.LBB0_1076:
	s_or_b64 exec, exec, s[0:1]
	v_lshlrev_b32_e32 v1, 2, v1
	v_and_b32_e32 v47, 0xfc, v1
	v_lshlrev_b32_e32 v20, 2, v47
	v_mov_b32_e32 v21, v0
	v_lshl_add_u64 v[2:3], v[2:3], 0, v[20:21]
	global_load_dwordx4 v[14:17], v[2:3], off
	global_load_dwordx4 v[10:13], v[2:3], off offset:1024
	v_and_b32_e32 v1, 64, v195
	v_add_u32_e32 v4, 64, v1
	v_xor_b32_e32 v1, 32, v195
	v_cmp_lt_i32_e32 vcc, v1, v4
	v_xor_b32_e32 v5, 16, v195
	s_mov_b32 s0, 0x800000
	v_cndmask_b32_e32 v1, v195, v1, vcc
	v_cmp_lt_i32_e32 vcc, v5, v4
	v_lshlrev_b32_e32 v1, 2, v1
	v_readlane_b32 s36, v248, 6
	v_cndmask_b32_e32 v5, v195, v5, vcc
	v_lshlrev_b32_e32 v42, 2, v5
	v_xor_b32_e32 v5, 8, v195
	v_cmp_lt_i32_e32 vcc, v5, v4
	v_readlane_b32 s48, v248, 18
	v_readlane_b32 s49, v248, 19
	v_cndmask_b32_e32 v5, v195, v5, vcc
	v_lshlrev_b32_e32 v43, 2, v5
	v_xor_b32_e32 v5, 4, v195
	v_cmp_lt_i32_e32 vcc, v5, v4
	v_or_b32_e32 v33, 0x300, v47
	v_or_b32_e32 v37, 0x100, v47
	v_cndmask_b32_e32 v5, v195, v5, vcc
	v_lshlrev_b32_e32 v44, 2, v5
	v_xor_b32_e32 v5, 2, v195
	v_cmp_lt_i32_e32 vcc, v5, v4
	v_or_b32_e32 v36, 0x200, v47
	v_readlane_b32 s37, v248, 7
	v_cndmask_b32_e32 v5, v195, v5, vcc
	v_lshlrev_b32_e32 v45, 2, v5
	v_xor_b32_e32 v5, 1, v195
	v_cmp_lt_i32_e32 vcc, v5, v4
	v_readlane_b32 s38, v248, 8
	v_readlane_b32 s39, v248, 9
	v_cndmask_b32_e32 v4, v195, v5, vcc
	v_lshlrev_b32_e32 v46, 2, v4
	v_readlane_b32 s40, v248, 10
	v_readlane_b32 s41, v248, 11
	v_readlane_b32 s42, v248, 12
	v_readlane_b32 s43, v248, 13
	v_readlane_b32 s44, v248, 14
	v_readlane_b32 s45, v248, 15
	v_readlane_b32 s46, v248, 16
	v_readlane_b32 s47, v248, 17
	v_readlane_b32 s50, v248, 20
	v_readlane_b32 s51, v248, 21
	s_waitcnt vmcnt(1)
	s_nop 0
	s_waitcnt vmcnt(0)
	s_nop 0
	s_nop 0
	s_nop 0
	v_mul_f32_e32 v6, v15, v15
	v_mul_f32_e32 v7, v11, v11
	s_nop 0
	v_fma_f32 v4, v14, v14, v6
	v_fma_f32 v5, v10, v10, v7
	v_fma_f32 v4, v16, v16, v4
	v_fma_f32 v5, v12, v12, v5
	v_fma_f32 v26, v17, v17, v4
	v_fma_f32 v27, v13, v13, v5
	global_load_dwordx4 v[6:9], v[2:3], off offset:2048
	s_nop 0
	global_load_dwordx4 v[2:5], v[2:3], off offset:3072
	v_add_f32_e32 v26, v26, v27
	global_load_dwordx4 v[38:41], v20, s[48:49]
	s_waitcnt vmcnt(2)
	s_waitcnt vmcnt(1)
	v_mul_f32_e32 v30, v7, v7
	v_mul_f32_e32 v31, v3, v3
	s_nop 0
	v_fma_f32 v28, v6, v6, v30
	v_fma_f32 v29, v2, v2, v31
	v_fma_f32 v28, v8, v8, v28
	v_fma_f32 v29, v4, v4, v29
	s_nop 0
	s_nop 0
	v_fma_f32 v28, v9, v9, v28
	v_fma_f32 v29, v5, v5, v29
	s_nop 0
	v_add_f32_e32 v26, v26, v28
	v_add_f32_e32 v26, v26, v29
	ds_bpermute_b32 v27, v1, v26
	s_waitcnt lgkmcnt(0)
	v_add_f32_e32 v26, v26, v27
	ds_bpermute_b32 v27, v42, v26
	s_waitcnt lgkmcnt(0)
	v_add_f32_e32 v26, v26, v27
	ds_bpermute_b32 v27, v43, v26
	s_waitcnt lgkmcnt(0)
	v_add_f32_e32 v26, v26, v27
	ds_bpermute_b32 v27, v44, v26
	s_waitcnt lgkmcnt(0)
	v_add_f32_e32 v26, v26, v27
	ds_bpermute_b32 v27, v45, v26
	s_waitcnt lgkmcnt(0)
	v_add_f32_e32 v26, v26, v27
	ds_bpermute_b32 v27, v46, v26
	s_waitcnt lgkmcnt(0)
	v_add_f32_e32 v26, v26, v27
	v_fmamk_f32 v26, v26, 0x3a800000, v188
	v_cmp_gt_f32_e32 vcc, s0, v26
	v_readlane_b32 s0, v245, 5
	v_readlane_b32 s1, v245, 6
	v_mul_f32_e32 v27, 0x4b800000, v26
	v_cndmask_b32_e32 v26, v26, v27, vcc
	v_lshl_add_u64 v[22:23], v[22:23], 2, s[0:1]
	s_mov_b64 s[0:1], 0x1000
	v_lshl_add_u64 v[34:35], v[22:23], 0, s[0:1]
	v_lshl_add_u64 v[30:31], v[22:23], 0, v[20:21]
	v_lshl_add_u64 v[22:23], v[34:35], 0, v[20:21]
	global_load_dwordx4 v[48:51], v[30:31], off
	global_load_dwordx4 v[52:55], v[22:23], off
	v_rsq_f32_e32 v26, v26
	v_readlane_b32 s0, v247, 56
	v_readlane_b32 s1, v247, 57
	v_mul_f32_e32 v27, 0x45800000, v26
	v_cndmask_b32_e32 v32, v26, v27, vcc
	v_pk_mul_f32 v[14:15], v[14:15], v[32:33] op_sel_hi:[1,0]
	v_lshlrev_b64 v[26:27], 11, v[24:25]
	s_waitcnt vmcnt(2)
	v_pk_mul_f32 v[14:15], v[38:39], v[14:15]
	v_lshl_add_u64 v[26:27], s[0:1], 0, v[26:27]
	v_pk_mul_f32 v[10:11], v[10:11], v[32:33] op_sel_hi:[1,0]
	v_pk_mul_f32 v[12:13], v[12:13], v[32:33] op_sel_hi:[1,0]
	v_pk_mul_f32 v[6:7], v[6:7], v[32:33] op_sel_hi:[1,0]
	v_pk_mul_f32 v[8:9], v[8:9], v[32:33] op_sel_hi:[1,0]
	v_pk_mul_f32 v[2:3], v[2:3], v[32:33] op_sel_hi:[1,0]
	v_pk_mul_f32 v[4:5], v[4:5], v[32:33] op_sel_hi:[1,0]
	s_waitcnt vmcnt(0)
	v_pk_add_f32 v[22:23], v[52:53], 1.0 op_sel_hi:[1,0]
	s_nop 0
	v_pk_fma_f32 v[14:15], v[22:23], v[14:15], v[48:49]
	v_lshlrev_b32_e32 v22, 1, v47
	v_cvt_pk_bf16_f32 v28, v14, v15
	v_pk_mul_f32 v[14:15], v[16:17], v[32:33] op_sel_hi:[1,0]
	v_pk_add_f32 v[16:17], v[54:55], 1.0 op_sel_hi:[1,0]
	v_pk_mul_f32 v[14:15], v[40:41], v[14:15]
	v_mov_b32_e32 v23, v0
	v_pk_fma_f32 v[14:15], v[16:17], v[14:15], v[50:51]
	s_nop 0
	v_cvt_pk_bf16_f32 v29, v14, v15
	v_lshl_add_u64 v[14:15], v[26:27], 0, v[22:23]
	v_lshlrev_b32_e32 v26, 2, v37
	v_mov_b32_e32 v27, v0
	global_store_dwordx2 v[14:15], v[28:29], off
	v_lshl_add_u64 v[16:17], v[34:35], 0, v[26:27]
	global_load_dwordx4 v[38:41], v20, s[48:49] offset:1024
	global_load_dwordx4 v[48:51], v[30:31], off offset:1024
	global_load_dwordx4 v[52:55], v[16:17], off
	v_lshlrev_b32_e32 v28, 2, v36
	v_mov_b32_e32 v29, v0
	s_waitcnt vmcnt(2)
	v_pk_mul_f32 v[10:11], v[38:39], v[10:11]
	v_pk_mul_f32 v[12:13], v[40:41], v[12:13]
	s_waitcnt vmcnt(0)
	v_pk_add_f32 v[16:17], v[52:53], 1.0 op_sel_hi:[1,0]
	s_nop 0
	v_pk_fma_f32 v[10:11], v[16:17], v[10:11], v[48:49]
	v_pk_add_f32 v[16:17], v[54:55], 1.0 op_sel_hi:[1,0]
	v_cvt_pk_bf16_f32 v10, v10, v11
	v_pk_fma_f32 v[12:13], v[16:17], v[12:13], v[50:51]
	v_lshl_add_u64 v[16:17], v[34:35], 0, v[28:29]
	v_cvt_pk_bf16_f32 v11, v12, v13
	global_store_dwordx2 v[14:15], v[10:11], off offset:512
	global_load_dwordx4 v[10:13], v20, s[48:49] offset:2048
	s_nop 0
	global_load_dwordx4 v[38:41], v[30:31], off offset:2048
	global_load_dwordx4 v[48:51], v[16:17], off
	s_waitcnt vmcnt(2)
	v_pk_mul_f32 v[6:7], v[10:11], v[6:7]
	v_pk_mul_f32 v[8:9], v[12:13], v[8:9]
	s_waitcnt vmcnt(0)
	v_pk_add_f32 v[10:11], v[48:49], 1.0 op_sel_hi:[1,0]
	s_nop 0
	v_pk_fma_f32 v[6:7], v[10:11], v[6:7], v[38:39]
	v_pk_add_f32 v[10:11], v[50:51], 1.0 op_sel_hi:[1,0]
	v_cvt_pk_bf16_f32 v6, v6, v7
	v_pk_fma_f32 v[8:9], v[10:11], v[8:9], v[40:41]
	v_or_b32_e32 v38, 1, v24
	v_cvt_pk_bf16_f32 v7, v8, v9
	global_store_dwordx2 v[14:15], v[6:7], off offset:1024
	global_load_dwordx4 v[6:9], v20, s[48:49] offset:3072
	s_nop 0
	global_load_dwordx4 v[10:13], v[30:31], off offset:3072
	v_lshlrev_b32_e32 v30, 2, v33
	v_mov_b32_e32 v31, v0
	v_lshl_add_u64 v[16:17], v[34:35], 0, v[30:31]
	global_load_dwordx4 v[34:37], v[16:17], off
	v_cmp_lt_i32_e32 vcc, s4, v38
	s_waitcnt vmcnt(2)
	v_pk_mul_f32 v[2:3], v[6:7], v[2:3]
	v_pk_mul_f32 v[4:5], v[8:9], v[4:5]
	s_waitcnt vmcnt(0)
	v_pk_add_f32 v[6:7], v[34:35], 1.0 op_sel_hi:[1,0]
	s_nop 0
	v_pk_fma_f32 v[2:3], v[2:3], v[6:7], v[10:11]
	v_pk_add_f32 v[6:7], v[36:37], 1.0 op_sel_hi:[1,0]
	v_cvt_pk_bf16_f32 v2, v2, v3
	v_pk_fma_f32 v[4:5], v[4:5], v[6:7], v[12:13]
	s_nop 0
	v_cvt_pk_bf16_f32 v3, v4, v5
	global_store_dwordx2 v[14:15], v[2:3], off offset:1536
	s_and_saveexec_b64 s[0:1], vcc
	s_xor_b64 s[0:1], exec, s[0:1]
	s_cbranch_execz .LBB0_1078
	v_add_u32_e32 v2, 0xffffe001, v24
	v_mov_b32_e32 v3, v0
	v_readlane_b32 s36, v248, 6
	v_lshlrev_b64 v[2:3], 12, v[2:3]
	v_readlane_b32 s38, v248, 8
	v_readlane_b32 s39, v248, 9
	v_mov_b32_e32 v39, v0
	v_readlane_b32 s37, v248, 7
	v_lshl_add_u64 v[2:3], s[38:39], 0, v[2:3]
	v_readlane_b32 s40, v248, 10
	v_readlane_b32 s41, v248, 11
	v_readlane_b32 s42, v248, 12
	v_readlane_b32 s43, v248, 13
	v_readlane_b32 s44, v248, 14
	v_readlane_b32 s45, v248, 15
	v_readlane_b32 s46, v248, 16
	v_readlane_b32 s47, v248, 17
	v_readlane_b32 s48, v248, 18
	v_readlane_b32 s49, v248, 19
	v_readlane_b32 s50, v248, 20
	v_readlane_b32 s51, v248, 21

.LBB0_1080:
	s_or_b64 exec, exec, s[0:1]
	v_readlane_b32 s36, v248, 6
	v_readlane_b32 s48, v248, 18
	v_readlane_b32 s49, v248, 19
	s_mov_b32 s0, 0x800000
	v_lshlrev_b64 v[38:39], 11, v[38:39]
	v_lshl_add_u64 v[32:33], s[48:49], 0, v[20:21]
	v_mov_b32_e32 v21, v0
	v_lshl_add_u64 v[2:3], v[2:3], 0, v[20:21]
	global_load_dwordx4 v[14:17], v[2:3], off
	global_load_dwordx4 v[10:13], v[2:3], off offset:1024
	v_mov_b32_e32 v27, v0
	v_mov_b32_e32 v29, v0
	v_mov_b32_e32 v31, v0
	v_readlane_b32 s43, v248, 13
	s_movk_i32 s43, 0x1fff
	v_readlane_b32 s37, v248, 7
	v_readlane_b32 s38, v248, 8
	v_readlane_b32 s39, v248, 9
	v_readlane_b32 s40, v248, 10
	v_readlane_b32 s41, v248, 11
	v_readlane_b32 s42, v248, 12
	v_readlane_b32 s44, v248, 14
	v_readlane_b32 s45, v248, 15
	v_readlane_b32 s46, v248, 16
	v_readlane_b32 s47, v248, 17
	v_readlane_b32 s50, v248, 20
	v_readlane_b32 s51, v248, 21
	s_waitcnt vmcnt(1)
	s_nop 0
	s_waitcnt vmcnt(0)
	s_nop 0
	s_nop 0
	s_nop 0
	v_mul_f32_e32 v6, v15, v15
	v_mul_f32_e32 v7, v11, v11
	s_nop 0
	v_fma_f32 v4, v14, v14, v6
	v_fma_f32 v5, v10, v10, v7
	v_fma_f32 v4, v16, v16, v4
	v_fma_f32 v5, v12, v12, v5
	v_fma_f32 v34, v17, v17, v4
	v_fma_f32 v35, v13, v13, v5
	global_load_dwordx4 v[6:9], v[2:3], off offset:2048
	s_nop 0
	global_load_dwordx4 v[2:5], v[2:3], off offset:3072
	v_add_f32_e32 v23, v34, v35
	s_waitcnt vmcnt(1)
	s_waitcnt vmcnt(0)
	v_mul_f32_e32 v48, v7, v7
	v_mul_f32_e32 v49, v3, v3
	s_nop 0
	v_fma_f32 v40, v6, v6, v48
	v_fma_f32 v41, v2, v2, v49
	v_fma_f32 v40, v8, v8, v40
	v_fma_f32 v41, v4, v4, v41
	s_nop 0
	s_nop 0
	v_fma_f32 v40, v9, v9, v40
	v_fma_f32 v41, v5, v5, v41
	global_load_dwordx4 v[48:51], v[32:33], off
	v_add_f32_e32 v23, v23, v40
	v_add_f32_e32 v23, v23, v41
	ds_bpermute_b32 v25, v1, v23
	s_waitcnt lgkmcnt(0)
	v_add_f32_e32 v23, v23, v25
	ds_bpermute_b32 v25, v42, v23
	s_waitcnt lgkmcnt(0)
	v_add_f32_e32 v23, v23, v25
	ds_bpermute_b32 v25, v43, v23
	s_waitcnt lgkmcnt(0)
	v_add_f32_e32 v23, v23, v25
	ds_bpermute_b32 v25, v44, v23
	s_waitcnt lgkmcnt(0)
	v_add_f32_e32 v23, v23, v25
	ds_bpermute_b32 v25, v45, v23
	s_waitcnt lgkmcnt(0)
	v_add_f32_e32 v23, v23, v25
	ds_bpermute_b32 v25, v46, v23
	s_waitcnt lgkmcnt(0)
	v_add_f32_e32 v23, v23, v25
	v_fmamk_f32 v23, v23, 0x3a800000, v188
	v_cmp_gt_f32_e32 vcc, s0, v23
	v_readlane_b32 s0, v245, 5
	v_readlane_b32 s1, v245, 6
	v_mul_f32_e32 v25, 0x4b800000, v23
	v_cndmask_b32_e32 v23, v23, v25, vcc
	v_lshl_add_u64 v[52:53], v[36:37], 2, s[0:1]
	s_mov_b64 s[0:1], 0x1000
	v_lshl_add_u64 v[36:37], v[52:53], 0, s[0:1]
	v_readlane_b32 s0, v247, 56
	v_readlane_b32 s1, v247, 57
	v_lshl_add_u64 v[56:57], v[36:37], 0, v[20:21]
	global_load_dwordx4 v[56:59], v[56:57], off
	v_lshl_add_u64 v[40:41], s[0:1], 0, v[38:39]
	v_lshl_add_u64 v[38:39], v[52:53], 0, v[20:21]
	global_load_dwordx4 v[52:55], v[38:39], off
	v_rsq_f32_e32 v23, v23
	s_nop 0
	v_mul_f32_e32 v25, 0x45800000, v23
	v_cndmask_b32_e32 v34, v23, v25, vcc
	v_pk_mul_f32 v[14:15], v[14:15], v[34:35] op_sel_hi:[1,0]
	v_mov_b32_e32 v23, v0
	v_pk_mul_f32 v[10:11], v[10:11], v[34:35] op_sel_hi:[1,0]
	v_pk_mul_f32 v[12:13], v[12:13], v[34:35] op_sel_hi:[1,0]
	v_pk_mul_f32 v[6:7], v[6:7], v[34:35] op_sel_hi:[1,0]
	v_pk_mul_f32 v[8:9], v[8:9], v[34:35] op_sel_hi:[1,0]
	v_pk_mul_f32 v[2:3], v[2:3], v[34:35] op_sel_hi:[1,0]
	v_pk_mul_f32 v[4:5], v[4:5], v[34:35] op_sel_hi:[1,0]
	s_waitcnt vmcnt(2)
	v_pk_mul_f32 v[14:15], v[48:49], v[14:15]
	s_waitcnt vmcnt(1)
	v_pk_add_f32 v[48:49], v[56:57], 1.0 op_sel_hi:[1,0]
	s_waitcnt vmcnt(0)
	v_pk_fma_f32 v[14:15], v[48:49], v[14:15], v[52:53]
	s_nop 0
	v_cvt_pk_bf16_f32 v48, v14, v15
	v_pk_mul_f32 v[14:15], v[16:17], v[34:35] op_sel_hi:[1,0]
	v_pk_add_f32 v[16:17], v[58:59], 1.0 op_sel_hi:[1,0]
	v_pk_mul_f32 v[14:15], v[50:51], v[14:15]
	s_nop 0
	v_pk_fma_f32 v[14:15], v[16:17], v[14:15], v[54:55]
	v_lshl_add_u64 v[16:17], v[36:37], 0, v[26:27]
	v_cvt_pk_bf16_f32 v49, v14, v15
	v_lshl_add_u64 v[14:15], v[40:41], 0, v[22:23]
	global_store_dwordx2 v[14:15], v[48:49], off
	global_load_dwordx4 v[48:51], v[32:33], off offset:1024
	s_nop 0
	global_load_dwordx4 v[52:55], v[38:39], off offset:1024
	global_load_dwordx4 v[56:59], v[16:17], off
	s_waitcnt vmcnt(2)
	v_pk_mul_f32 v[10:11], v[48:49], v[10:11]
	v_pk_mul_f32 v[12:13], v[50:51], v[12:13]
	s_waitcnt vmcnt(0)
	v_pk_add_f32 v[16:17], v[56:57], 1.0 op_sel_hi:[1,0]
	s_nop 0
	v_pk_fma_f32 v[10:11], v[16:17], v[10:11], v[52:53]
	v_pk_add_f32 v[16:17], v[58:59], 1.0 op_sel_hi:[1,0]
	v_cvt_pk_bf16_f32 v10, v10, v11
	v_pk_fma_f32 v[12:13], v[16:17], v[12:13], v[54:55]
	v_lshl_add_u64 v[16:17], v[36:37], 0, v[28:29]
	v_cvt_pk_bf16_f32 v11, v12, v13
	global_store_dwordx2 v[14:15], v[10:11], off offset:512
	global_load_dwordx4 v[10:13], v[32:33], off offset:2048
	s_nop 0
	global_load_dwordx4 v[48:51], v[38:39], off offset:2048
	global_load_dwordx4 v[52:55], v[16:17], off
	v_lshl_add_u64 v[16:17], v[36:37], 0, v[30:31]
	s_waitcnt vmcnt(2)
	v_pk_mul_f32 v[6:7], v[10:11], v[6:7]
	v_pk_mul_f32 v[8:9], v[12:13], v[8:9]
	s_waitcnt vmcnt(0)
	v_pk_add_f32 v[10:11], v[52:53], 1.0 op_sel_hi:[1,0]
	s_nop 0
	v_pk_fma_f32 v[6:7], v[10:11], v[6:7], v[48:49]
	v_pk_add_f32 v[10:11], v[54:55], 1.0 op_sel_hi:[1,0]
	v_cvt_pk_bf16_f32 v6, v6, v7
	v_pk_fma_f32 v[8:9], v[10:11], v[8:9], v[50:51]
	s_nop 0
	v_cvt_pk_bf16_f32 v7, v8, v9
	global_store_dwordx2 v[14:15], v[6:7], off offset:1024
	global_load_dwordx4 v[6:9], v[32:33], off offset:3072
	s_nop 0
	global_load_dwordx4 v[10:13], v[38:39], off offset:3072
	s_waitcnt vmcnt(1)
	v_pk_mul_f32 v[2:3], v[6:7], v[2:3]
	global_load_dwordx4 v[36:39], v[16:17], off
	v_pk_mul_f32 v[4:5], v[8:9], v[4:5]
	s_waitcnt vmcnt(0)
	v_pk_add_f32 v[6:7], v[36:37], 1.0 op_sel_hi:[1,0]
	s_nop 0
	v_pk_fma_f32 v[2:3], v[2:3], v[6:7], v[10:11]
	v_pk_add_f32 v[6:7], v[38:39], 1.0 op_sel_hi:[1,0]
	v_or_b32_e32 v38, 2, v24
	v_pk_fma_f32 v[4:5], v[4:5], v[6:7], v[12:13]
	v_cvt_pk_bf16_f32 v2, v2, v3
	v_cvt_pk_bf16_f32 v3, v4, v5
	v_cmp_lt_i32_e32 vcc, s43, v38
	global_store_dwordx2 v[14:15], v[2:3], off offset:1536
	s_and_saveexec_b64 s[0:1], vcc
	s_xor_b64 s[0:1], exec, s[0:1]
	s_cbranch_execz .LBB0_1082
	v_add_u32_e32 v2, 0xffffe002, v24
	v_mov_b32_e32 v3, v0
	v_readlane_b32 s36, v248, 6
	v_lshlrev_b64 v[2:3], 12, v[2:3]
	v_readlane_b32 s38, v248, 8
	v_readlane_b32 s39, v248, 9
	v_readlane_b32 s43, v248, 13
	s_movk_i32 s43, 0x1fff
	v_lshl_add_u64 v[2:3], s[38:39], 0, v[2:3]
	v_mov_b32_e32 v39, v0
	v_readlane_b32 s37, v248, 7
	v_readlane_b32 s40, v248, 10
	v_readlane_b32 s41, v248, 11
	v_readlane_b32 s42, v248, 12
	v_readlane_b32 s44, v248, 14
	v_readlane_b32 s45, v248, 15
	v_readlane_b32 s46, v248, 16
	v_readlane_b32 s47, v248, 17
	v_readlane_b32 s48, v248, 18
	v_readlane_b32 s49, v248, 19
	v_readlane_b32 s50, v248, 20
	v_readlane_b32 s51, v248, 21

.LBB0_1084:
	s_or_b64 exec, exec, s[0:1]
	v_mov_b32_e32 v21, v0
	v_lshl_add_u64 v[2:3], v[2:3], 0, v[20:21]
	global_load_dwordx4 v[14:17], v[2:3], off
	global_load_dwordx4 v[10:13], v[2:3], off offset:1024
	s_mov_b32 s0, 0x800000
	v_lshlrev_b64 v[38:39], 11, v[38:39]
	v_mov_b32_e32 v27, v0
	v_mov_b32_e32 v29, v0
	v_mov_b32_e32 v31, v0
	s_waitcnt vmcnt(1)
	s_waitcnt vmcnt(0)
	v_mul_f32_e32 v6, v15, v15
	v_mul_f32_e32 v7, v11, v11
	s_nop 0
	v_fma_f32 v4, v14, v14, v6
	v_fma_f32 v5, v10, v10, v7
	v_fma_f32 v4, v16, v16, v4
	v_fma_f32 v5, v12, v12, v5
	v_fma_f32 v34, v17, v17, v4
	v_fma_f32 v35, v13, v13, v5
	global_load_dwordx4 v[6:9], v[2:3], off offset:2048
	s_nop 0
	global_load_dwordx4 v[2:5], v[2:3], off offset:3072
	v_add_f32_e32 v23, v34, v35
	s_waitcnt vmcnt(1)
	s_waitcnt vmcnt(0)
	v_mul_f32_e32 v48, v7, v7
	v_mul_f32_e32 v49, v3, v3
	s_nop 0
	v_fma_f32 v40, v6, v6, v48
	v_fma_f32 v41, v2, v2, v49
	v_fma_f32 v40, v8, v8, v40
	v_fma_f32 v41, v4, v4, v41
	s_nop 0
	s_nop 0
	v_fma_f32 v40, v9, v9, v40
	v_fma_f32 v41, v5, v5, v41
	global_load_dwordx4 v[48:51], v[32:33], off
	v_add_f32_e32 v23, v23, v40
	v_add_f32_e32 v23, v23, v41
	ds_bpermute_b32 v25, v1, v23
	s_waitcnt lgkmcnt(0)
	v_add_f32_e32 v23, v23, v25
	ds_bpermute_b32 v25, v42, v23
	s_waitcnt lgkmcnt(0)
	v_add_f32_e32 v23, v23, v25
	ds_bpermute_b32 v25, v43, v23
	s_waitcnt lgkmcnt(0)
	v_add_f32_e32 v23, v23, v25
	ds_bpermute_b32 v25, v44, v23
	s_waitcnt lgkmcnt(0)
	v_add_f32_e32 v23, v23, v25
	ds_bpermute_b32 v25, v45, v23
	s_waitcnt lgkmcnt(0)
	v_add_f32_e32 v23, v23, v25
	ds_bpermute_b32 v25, v46, v23
	s_waitcnt lgkmcnt(0)
	v_add_f32_e32 v23, v23, v25
	v_fmamk_f32 v23, v23, 0x3a800000, v188
	v_cmp_gt_f32_e32 vcc, s0, v23
	v_readlane_b32 s0, v245, 5
	v_readlane_b32 s1, v245, 6
	v_mul_f32_e32 v25, 0x4b800000, v23
	v_cndmask_b32_e32 v23, v23, v25, vcc
	v_lshl_add_u64 v[52:53], v[36:37], 2, s[0:1]
	s_mov_b64 s[0:1], 0x1000
	v_lshl_add_u64 v[36:37], v[52:53], 0, s[0:1]
	v_readlane_b32 s0, v247, 56
	v_readlane_b32 s1, v247, 57
	v_lshl_add_u64 v[56:57], v[36:37], 0, v[20:21]
	global_load_dwordx4 v[56:59], v[56:57], off
	v_lshl_add_u64 v[40:41], s[0:1], 0, v[38:39]
	v_lshl_add_u64 v[38:39], v[52:53], 0, v[20:21]
	global_load_dwordx4 v[52:55], v[38:39], off
	v_rsq_f32_e32 v23, v23
	s_nop 0
	v_mul_f32_e32 v25, 0x45800000, v23
	v_cndmask_b32_e32 v34, v23, v25, vcc
	v_pk_mul_f32 v[14:15], v[14:15], v[34:35] op_sel_hi:[1,0]
	v_mov_b32_e32 v23, v0
	v_pk_mul_f32 v[10:11], v[10:11], v[34:35] op_sel_hi:[1,0]
	v_pk_mul_f32 v[12:13], v[12:13], v[34:35] op_sel_hi:[1,0]
	v_pk_mul_f32 v[6:7], v[6:7], v[34:35] op_sel_hi:[1,0]
	v_pk_mul_f32 v[8:9], v[8:9], v[34:35] op_sel_hi:[1,0]
	v_pk_mul_f32 v[2:3], v[2:3], v[34:35] op_sel_hi:[1,0]
	v_pk_mul_f32 v[4:5], v[4:5], v[34:35] op_sel_hi:[1,0]
	s_waitcnt vmcnt(2)
	v_pk_mul_f32 v[14:15], v[48:49], v[14:15]
	s_waitcnt vmcnt(1)
	v_pk_add_f32 v[48:49], v[56:57], 1.0 op_sel_hi:[1,0]
	s_waitcnt vmcnt(0)
	v_pk_fma_f32 v[14:15], v[48:49], v[14:15], v[52:53]
	s_nop 0
	v_cvt_pk_bf16_f32 v48, v14, v15
	v_pk_mul_f32 v[14:15], v[16:17], v[34:35] op_sel_hi:[1,0]
	v_pk_add_f32 v[16:17], v[58:59], 1.0 op_sel_hi:[1,0]
	v_pk_mul_f32 v[14:15], v[50:51], v[14:15]
	v_or_b32_e32 v34, 3, v24
	v_pk_fma_f32 v[14:15], v[16:17], v[14:15], v[54:55]
	v_lshl_add_u64 v[16:17], v[36:37], 0, v[26:27]
	v_cvt_pk_bf16_f32 v49, v14, v15
	v_lshl_add_u64 v[14:15], v[40:41], 0, v[22:23]
	global_store_dwordx2 v[14:15], v[48:49], off
	global_load_dwordx4 v[48:51], v[32:33], off offset:1024
	s_nop 0
	global_load_dwordx4 v[52:55], v[38:39], off offset:1024
	global_load_dwordx4 v[56:59], v[16:17], off
	v_cmp_lt_i32_e32 vcc, s43, v34
	s_waitcnt vmcnt(2)
	v_pk_mul_f32 v[10:11], v[48:49], v[10:11]
	v_pk_mul_f32 v[12:13], v[50:51], v[12:13]
	s_waitcnt vmcnt(0)
	v_pk_add_f32 v[16:17], v[56:57], 1.0 op_sel_hi:[1,0]
	s_nop 0
	v_pk_fma_f32 v[10:11], v[16:17], v[10:11], v[52:53]
	v_pk_add_f32 v[16:17], v[58:59], 1.0 op_sel_hi:[1,0]
	v_cvt_pk_bf16_f32 v10, v10, v11
	v_pk_fma_f32 v[12:13], v[16:17], v[12:13], v[54:55]
	v_lshl_add_u64 v[16:17], v[36:37], 0, v[28:29]
	v_cvt_pk_bf16_f32 v11, v12, v13
	global_store_dwordx2 v[14:15], v[10:11], off offset:512
	global_load_dwordx4 v[10:13], v[32:33], off offset:2048
	s_nop 0
	global_load_dwordx4 v[48:51], v[38:39], off offset:2048
	global_load_dwordx4 v[52:55], v[16:17], off
	v_lshl_add_u64 v[16:17], v[36:37], 0, v[30:31]
	s_waitcnt vmcnt(2)
	v_pk_mul_f32 v[6:7], v[10:11], v[6:7]
	v_pk_mul_f32 v[8:9], v[12:13], v[8:9]
	s_waitcnt vmcnt(0)
	v_pk_add_f32 v[10:11], v[52:53], 1.0 op_sel_hi:[1,0]
	s_nop 0
	v_pk_fma_f32 v[6:7], v[10:11], v[6:7], v[48:49]
	v_pk_add_f32 v[10:11], v[54:55], 1.0 op_sel_hi:[1,0]
	v_cvt_pk_bf16_f32 v6, v6, v7
	v_pk_fma_f32 v[8:9], v[10:11], v[8:9], v[50:51]
	s_nop 0
	v_cvt_pk_bf16_f32 v7, v8, v9
	global_store_dwordx2 v[14:15], v[6:7], off offset:1024
	global_load_dwordx4 v[6:9], v[32:33], off offset:3072
	s_nop 0
	global_load_dwordx4 v[10:13], v[38:39], off offset:3072
	s_waitcnt vmcnt(1)
	v_pk_mul_f32 v[2:3], v[6:7], v[2:3]
	global_load_dwordx4 v[36:39], v[16:17], off
	v_pk_mul_f32 v[4:5], v[8:9], v[4:5]
	s_waitcnt vmcnt(0)
	v_pk_add_f32 v[6:7], v[36:37], 1.0 op_sel_hi:[1,0]
	s_nop 0
	v_pk_fma_f32 v[2:3], v[2:3], v[6:7], v[10:11]
	v_pk_add_f32 v[6:7], v[38:39], 1.0 op_sel_hi:[1,0]
	v_cvt_pk_bf16_f32 v2, v2, v3
	v_pk_fma_f32 v[4:5], v[4:5], v[6:7], v[12:13]
	s_nop 0
	v_cvt_pk_bf16_f32 v3, v4, v5
	global_store_dwordx2 v[14:15], v[2:3], off offset:1536
	s_and_saveexec_b64 s[0:1], vcc
	s_xor_b64 s[0:1], exec, s[0:1]
	s_cbranch_execz .LBB0_1086
	v_add_u32_e32 v2, 0xffffe003, v24
	v_mov_b32_e32 v3, v0
	v_readlane_b32 s36, v248, 6
	v_lshlrev_b64 v[2:3], 12, v[2:3]
	v_readlane_b32 s38, v248, 8
	v_readlane_b32 s39, v248, 9
	v_readlane_b32 s43, v248, 13
	s_movk_i32 s43, 0x1fff
	v_lshl_add_u64 v[2:3], s[38:39], 0, v[2:3]
	v_mov_b32_e32 v35, v0
	v_readlane_b32 s37, v248, 7
	v_readlane_b32 s40, v248, 10
	v_readlane_b32 s41, v248, 11
	v_readlane_b32 s42, v248, 12
	v_readlane_b32 s44, v248, 14
	v_readlane_b32 s45, v248, 15
	v_readlane_b32 s46, v248, 16
	v_readlane_b32 s47, v248, 17
	v_readlane_b32 s48, v248, 18
	v_readlane_b32 s49, v248, 19
	v_readlane_b32 s50, v248, 20
	v_readlane_b32 s51, v248, 21

.LBB0_1088:
	s_or_b64 exec, exec, s[0:1]
	v_mov_b32_e32 v21, v0
	v_lshl_add_u64 v[2:3], v[2:3], 0, v[20:21]
	global_load_dwordx4 v[14:17], v[2:3], off
	global_load_dwordx4 v[10:13], v[2:3], off offset:1024
	s_mov_b32 s0, 0x800000
	v_lshlrev_b64 v[34:35], 11, v[34:35]
	v_mov_b32_e32 v27, v0
	v_mov_b32_e32 v29, v0
	v_mov_b32_e32 v31, v0
	s_waitcnt vmcnt(1)
	s_waitcnt vmcnt(0)
	v_mul_f32_e32 v6, v15, v15
	v_mul_f32_e32 v7, v11, v11
	s_nop 0
	v_fma_f32 v4, v14, v14, v6
	v_fma_f32 v5, v10, v10, v7
	v_fma_f32 v4, v16, v16, v4
	v_fma_f32 v5, v12, v12, v5
	v_fma_f32 v24, v17, v17, v4
	v_fma_f32 v25, v13, v13, v5
	global_load_dwordx4 v[6:9], v[2:3], off offset:2048
	s_nop 0
	global_load_dwordx4 v[2:5], v[2:3], off offset:3072
	v_add_f32_e32 v23, v24, v25
	s_waitcnt vmcnt(1)
	s_waitcnt vmcnt(0)
	v_mul_f32_e32 v38, v7, v7
	v_mul_f32_e32 v39, v3, v3
	s_nop 0
	v_fma_f32 v36, v6, v6, v38
	v_fma_f32 v37, v2, v2, v39
	v_fma_f32 v36, v8, v8, v36
	v_fma_f32 v37, v4, v4, v37
	s_nop 0
	s_nop 0
	v_fma_f32 v36, v9, v9, v36
	v_fma_f32 v37, v5, v5, v37
	global_load_dwordx4 v[38:41], v[32:33], off
	v_add_f32_e32 v23, v23, v36
	v_add_f32_e32 v23, v23, v37
	ds_bpermute_b32 v1, v1, v23
	s_waitcnt lgkmcnt(0)
	v_add_f32_e32 v1, v23, v1
	ds_bpermute_b32 v23, v42, v1
	s_waitcnt lgkmcnt(0)
	v_add_f32_e32 v1, v1, v23
	ds_bpermute_b32 v23, v43, v1
	s_waitcnt lgkmcnt(0)
	v_add_f32_e32 v1, v1, v23
	ds_bpermute_b32 v23, v44, v1
	s_waitcnt lgkmcnt(0)
	v_add_f32_e32 v1, v1, v23
	ds_bpermute_b32 v23, v45, v1
	s_waitcnt lgkmcnt(0)
	v_add_f32_e32 v1, v1, v23
	ds_bpermute_b32 v23, v46, v1
	s_waitcnt lgkmcnt(0)
	v_add_f32_e32 v1, v1, v23
	v_fmamk_f32 v1, v1, 0x3a800000, v188
	v_cmp_gt_f32_e32 vcc, s0, v1
	v_readlane_b32 s0, v245, 5
	v_readlane_b32 s1, v245, 6
	v_mul_f32_e32 v23, 0x4b800000, v1
	v_cndmask_b32_e32 v1, v1, v23, vcc
	v_lshl_add_u64 v[42:43], v[18:19], 2, s[0:1]
	s_mov_b64 s[0:1], 0x1000
	v_lshl_add_u64 v[18:19], v[42:43], 0, s[0:1]
	v_readlane_b32 s0, v247, 56
	v_readlane_b32 s1, v247, 57
	v_rsq_f32_e32 v1, v1
	s_nop 0
	v_lshl_add_u64 v[36:37], s[0:1], 0, v[34:35]
	v_lshl_add_u64 v[34:35], v[42:43], 0, v[20:21]
	v_lshl_add_u64 v[20:21], v[18:19], 0, v[20:21]
	global_load_dwordx4 v[46:49], v[20:21], off
	global_load_dwordx4 v[42:45], v[34:35], off
	v_mul_f32_e32 v23, 0x45800000, v1
	v_cndmask_b32_e32 v24, v1, v23, vcc
	v_pk_mul_f32 v[14:15], v[14:15], v[24:25] op_sel_hi:[1,0]
	v_mov_b32_e32 v23, v0
	v_pk_mul_f32 v[10:11], v[10:11], v[24:25] op_sel_hi:[1,0]
	v_pk_mul_f32 v[12:13], v[12:13], v[24:25] op_sel_hi:[1,0]
	v_pk_mul_f32 v[6:7], v[6:7], v[24:25] op_sel_hi:[1,0]
	v_pk_mul_f32 v[8:9], v[8:9], v[24:25] op_sel_hi:[1,0]
	v_pk_mul_f32 v[2:3], v[2:3], v[24:25] op_sel_hi:[1,0]
	v_pk_mul_f32 v[4:5], v[4:5], v[24:25] op_sel_hi:[1,0]
	s_mov_b64 s[0:1], 0
	s_waitcnt vmcnt(2)
	v_pk_mul_f32 v[14:15], v[38:39], v[14:15]
	s_waitcnt vmcnt(1)
	v_pk_add_f32 v[20:21], v[46:47], 1.0 op_sel_hi:[1,0]
	s_waitcnt vmcnt(0)
	v_pk_fma_f32 v[14:15], v[20:21], v[14:15], v[42:43]
	s_nop 0
	v_cvt_pk_bf16_f32 v20, v14, v15
	v_pk_mul_f32 v[14:15], v[16:17], v[24:25] op_sel_hi:[1,0]
	v_pk_add_f32 v[16:17], v[48:49], 1.0 op_sel_hi:[1,0]
	v_pk_mul_f32 v[14:15], v[40:41], v[14:15]
	s_nop 0
	v_pk_fma_f32 v[14:15], v[16:17], v[14:15], v[44:45]
	v_lshl_add_u64 v[16:17], v[18:19], 0, v[26:27]
	v_cvt_pk_bf16_f32 v21, v14, v15
	v_lshl_add_u64 v[14:15], v[36:37], 0, v[22:23]
	global_store_dwordx2 v[14:15], v[20:21], off
	global_load_dwordx4 v[20:23], v[32:33], off offset:1024
	s_nop 0
	global_load_dwordx4 v[36:39], v[34:35], off offset:1024
	global_load_dwordx4 v[40:43], v[16:17], off
	s_waitcnt vmcnt(2)
	v_pk_mul_f32 v[10:11], v[20:21], v[10:11]
	v_pk_mul_f32 v[12:13], v[22:23], v[12:13]
	s_waitcnt vmcnt(0)
	v_pk_add_f32 v[16:17], v[40:41], 1.0 op_sel_hi:[1,0]
	s_nop 0
	v_pk_fma_f32 v[10:11], v[16:17], v[10:11], v[36:37]
	v_pk_add_f32 v[16:17], v[42:43], 1.0 op_sel_hi:[1,0]
	v_cvt_pk_bf16_f32 v10, v10, v11
	v_pk_fma_f32 v[12:13], v[16:17], v[12:13], v[38:39]
	v_lshl_add_u64 v[16:17], v[18:19], 0, v[28:29]
	v_cvt_pk_bf16_f32 v11, v12, v13
	global_store_dwordx2 v[14:15], v[10:11], off offset:512
	global_load_dwordx4 v[10:13], v[32:33], off offset:2048
	s_nop 0
	global_load_dwordx4 v[20:23], v[34:35], off offset:2048
	global_load_dwordx4 v[26:29], v[16:17], off
	v_lshl_add_u64 v[16:17], v[18:19], 0, v[30:31]
	s_waitcnt vmcnt(2)
	v_pk_mul_f32 v[6:7], v[10:11], v[6:7]
	v_pk_mul_f32 v[8:9], v[12:13], v[8:9]
	s_waitcnt vmcnt(0)
	v_pk_add_f32 v[10:11], v[26:27], 1.0 op_sel_hi:[1,0]
	s_nop 0
	v_pk_fma_f32 v[6:7], v[10:11], v[6:7], v[20:21]
	v_pk_add_f32 v[10:11], v[28:29], 1.0 op_sel_hi:[1,0]
	v_cvt_pk_bf16_f32 v6, v6, v7
	v_pk_fma_f32 v[8:9], v[10:11], v[8:9], v[22:23]
	s_nop 0
	v_cvt_pk_bf16_f32 v7, v8, v9
	global_store_dwordx2 v[14:15], v[6:7], off offset:1024
	global_load_dwordx4 v[6:9], v[32:33], off offset:3072
	s_nop 0
	global_load_dwordx4 v[10:13], v[34:35], off offset:3072
	s_waitcnt vmcnt(1)
	v_pk_mul_f32 v[2:3], v[6:7], v[2:3]
	global_load_dwordx4 v[16:19], v[16:17], off
	v_pk_mul_f32 v[4:5], v[8:9], v[4:5]
	s_waitcnt vmcnt(0)
	v_pk_add_f32 v[6:7], v[16:17], 1.0 op_sel_hi:[1,0]
	s_nop 0
	v_pk_fma_f32 v[2:3], v[2:3], v[6:7], v[10:11]
	v_pk_add_f32 v[6:7], v[18:19], 1.0 op_sel_hi:[1,0]
	v_cvt_pk_bf16_f32 v2, v2, v3
	v_pk_fma_f32 v[4:5], v[4:5], v[6:7], v[12:13]
	s_nop 0
	v_cvt_pk_bf16_f32 v3, v4, v5
	global_store_dwordx2 v[14:15], v[2:3], off offset:1536

.LBB0_1169:
	s_or_b64 exec, exec, s[28:29]
	s_waitcnt lgkmcnt(0)
	s_barrier
	ds_read_b128 v[18:21], v11 offset:24832
	ds_read_b128 v[22:25], v11 offset:24848
	ds_read_b128 v[26:29], v11 offset:24864
	ds_read_b128 v[30:33], v11 offset:24880
	ds_read2st64_b32 v[34:35], v1 offset1:1
	ds_read2st64_b32 v[36:37], v1 offset0:2 offset1:3
	ds_read2st64_b32 v[38:39], v1 offset0:4 offset1:5
	ds_read2st64_b32 v[40:41], v1 offset0:6 offset1:7
	ds_read_b32 v43, v1 offset:8192
	s_waitcnt lgkmcnt(4)
	v_fma_f32 v5, v18, v34, v6
	v_fmac_f32_e32 v5, v19, v35
	s_waitcnt lgkmcnt(3)
	v_fmac_f32_e32 v5, v20, v36
	v_fmac_f32_e32 v5, v21, v37
	ds_read2st64_b32 v[18:19], v1 offset0:8 offset1:9
	s_waitcnt lgkmcnt(3)
	v_fmac_f32_e32 v5, v22, v38
	v_fmac_f32_e32 v5, v23, v39
	s_waitcnt lgkmcnt(2)
	v_fmac_f32_e32 v5, v24, v40
	v_fmac_f32_e32 v5, v25, v41
	ds_read2st64_b32 v[20:21], v1 offset0:10 offset1:11
	ds_read2st64_b32 v[22:23], v1 offset0:12 offset1:13
	ds_read2st64_b32 v[24:25], v1 offset0:14 offset1:15
	s_waitcnt lgkmcnt(3)
	v_fmac_f32_e32 v5, v26, v18
	v_fmac_f32_e32 v5, v27, v19
	s_waitcnt lgkmcnt(2)
	v_fmac_f32_e32 v5, v28, v20
	v_fmac_f32_e32 v5, v29, v21
	s_waitcnt lgkmcnt(1)
	v_fmac_f32_e32 v5, v30, v22
	ds_read_b128 v[18:21], v11 offset:24896
	v_fmac_f32_e32 v5, v31, v23
	ds_read2st64_b32 v[22:23], v1 offset0:16 offset1:17
	s_waitcnt lgkmcnt(2)
	v_fmac_f32_e32 v5, v32, v24
	v_fmac_f32_e32 v5, v33, v25
	ds_read2st64_b32 v[26:27], v1 offset0:18 offset1:19
	ds_read2st64_b32 v[28:29], v1 offset0:20 offset1:21
	ds_read2st64_b32 v[30:31], v1 offset0:22 offset1:23
	v_add_u32_e32 v32, 0x617c, v11
	s_waitcnt lgkmcnt(3)
	v_fmac_f32_e32 v5, v18, v22
	v_fmac_f32_e32 v5, v19, v23
	ds_read_b96 v[22:24], v11 offset:24912
	s_waitcnt lgkmcnt(3)
	v_fmac_f32_e32 v5, v20, v26
	v_fmac_f32_e32 v5, v21, v27
	v_add_u32_e32 v18, 0x615c, v11
	ds_read2st64_b32 v[20:21], v1 offset0:24 offset1:25
	ds_read2_b32 v[18:19], v18 offset1:1
	s_waitcnt lgkmcnt(2)
	v_fmac_f32_e32 v5, v22, v28
	v_fmac_f32_e32 v5, v23, v29
	s_waitcnt lgkmcnt(1)
	v_fmac_f32_e32 v5, v24, v30
	s_waitcnt lgkmcnt(0)
	v_mul_f32_e32 v18, v18, v31
	v_mul_f32_e32 v19, v19, v20
	ds_read2st64_b32 v[24:25], v1 offset0:26 offset1:27
	ds_read2st64_b32 v[26:27], v1 offset0:28 offset1:29
	ds_read2st64_b32 v[28:29], v1 offset0:30 offset1:31
	v_add_f32_e32 v5, v5, v18
	v_add_u32_e32 v18, 0x6164, v11
	v_add_f32_e32 v5, v5, v19
	ds_read2_b32 v[18:19], v18 offset1:1
	v_mov_b32_e32 v20, v21
	s_waitcnt lgkmcnt(3)
	v_mov_b32_e32 v21, v24
	v_add_u32_e32 v22, 0x616c, v11
	v_add_u32_e32 v24, 0x6174, v11
	ds_read2_b32 v[22:23], v22 offset1:1
	ds_read2_b32 v[30:31], v24 offset1:1
	ds_read2_b32 v[32:33], v32 offset1:1
	s_waitcnt lgkmcnt(3)
	v_pk_mul_f32 v[18:19], v[18:19], v[20:21]
	v_mov_b32_e32 v42, v29
	v_add_f32_e32 v5, v5, v18
	v_add_f32_e32 v5, v5, v19
	s_waitcnt lgkmcnt(2)
	v_mul_f32_e32 v18, v22, v25
	v_mul_f32_e32 v19, v23, v26
	s_brev_b32 s0, 18
	v_add_f32_e32 v5, v5, v18
	v_add_f32_e32 v5, v5, v19
	s_waitcnt lgkmcnt(1)
	v_mul_f32_e32 v18, v30, v27
	v_mul_f32_e32 v19, v31, v28
	s_nop 0
	v_add_f32_e32 v5, v5, v18
	v_add_f32_e32 v5, v5, v19
	s_waitcnt lgkmcnt(0)
	v_pk_mul_f32 v[18:19], v[32:33], v[42:43]
	s_nop 0
	v_add_f32_e32 v5, v5, v18
	v_add_f32_e32 v5, v5, v19
	v_mul_f32_e32 v5, v7, v5
	v_and_b32_e32 v18, 0x7fffffff, v5
	v_cmp_nlt_f32_e64 s[0:1], |v5|, s0
	s_and_saveexec_b64 s[28:29], s[0:1]
	s_xor_b64 s[28:29], exec, s[28:29]
	s_cbranch_execz .LBB0_1171
	v_lshrrev_b32_e32 v19, 23, v18
	v_add_u32_e32 v19, 0xffffff88, v19
	v_cmp_lt_u32_e32 vcc, 63, v19
	s_mov_b32 s4, 0xfe5163ab
	v_mov_b32_e32 v23, v0
	v_cndmask_b32_e32 v20, 0, v198, vcc
	v_add_u32_e32 v19, v20, v19
	v_cmp_lt_u32_e64 s[0:1], 31, v19
	v_mov_b32_e32 v25, v0
	v_mov_b32_e32 v27, v0
	v_cndmask_b32_e64 v20, 0, v199, s[0:1]
	v_add_u32_e32 v19, v20, v19
	v_cmp_lt_u32_e64 s[42:43], 31, v19
	v_mov_b32_e32 v29, v0
	v_mov_b32_e32 v31, v0
	v_cndmask_b32_e64 v20, 0, v199, s[42:43]
	v_add_u32_e32 v19, v20, v19
	v_and_b32_e32 v20, 0x7fffff, v18
	v_or_b32_e32 v34, 0x800000, v20
	v_mad_u64_u32 v[20:21], s[34:35], v34, s4, 0
	v_mov_b32_e32 v22, v21
	s_mov_b32 s4, 0x3c439041
	v_mad_u64_u32 v[22:23], s[34:35], v34, s4, v[22:23]
	v_mov_b32_e32 v24, v23
	s_mov_b32 s4, 0xdb629599
	v_mad_u64_u32 v[24:25], s[34:35], v34, s4, v[24:25]
	v_mov_b32_e32 v26, v25
	s_mov_b32 s4, 0xf534ddc0
	v_mad_u64_u32 v[26:27], s[34:35], v34, s4, v[26:27]
	v_mov_b32_e32 v28, v27
	s_mov_b32 s4, 0xfc2757d1
	v_mad_u64_u32 v[28:29], s[34:35], v34, s4, v[28:29]
	v_mov_b32_e32 v30, v29
	s_mov_b32 s4, 0x4e441529
	v_mad_u64_u32 v[30:31], s[34:35], v34, s4, v[30:31]
	v_mov_b32_e32 v32, v31
	v_mov_b32_e32 v33, v0
	s_mov_b32 s4, 0xa2f9836e
	v_mad_u64_u32 v[32:33], s[34:35], v34, s4, v[32:33]
	v_cndmask_b32_e32 v21, v30, v26, vcc
	v_cndmask_b32_e32 v23, v32, v28, vcc
	v_cndmask_b32_e32 v27, v33, v30, vcc
	v_cndmask_b32_e64 v25, v23, v21, s[0:1]
	v_cndmask_b32_e64 v23, v27, v23, s[0:1]
	v_cndmask_b32_e32 v27, v28, v24, vcc
	v_cndmask_b32_e64 v21, v21, v27, s[0:1]
	v_cndmask_b32_e64 v23, v23, v25, s[42:43]
	v_cndmask_b32_e64 v25, v25, v21, s[42:43]
	v_sub_u32_e32 v28, 32, v19
	v_alignbit_b32 v29, v23, v25, v28
	v_cmp_eq_u32_e64 s[44:45], 0, v19
	v_cndmask_b32_e32 v22, v26, v22, vcc
	v_cndmask_b32_e32 v20, v24, v20, vcc
	v_cndmask_b32_e64 v19, v29, v23, s[44:45]
	v_cndmask_b32_e64 v23, v27, v22, s[0:1]
	v_cndmask_b32_e64 v21, v21, v23, s[42:43]
	v_alignbit_b32 v26, v25, v21, v28
	v_cndmask_b32_e64 v25, v26, v25, s[44:45]
	v_bfe_u32 v29, v19, 29, 1
	v_cndmask_b32_e64 v20, v22, v20, s[0:1]
	v_alignbit_b32 v26, v19, v25, 30
	v_sub_u32_e32 v30, 0, v29
	v_cndmask_b32_e64 v20, v23, v20, s[42:43]
	v_xor_b32_e32 v26, v26, v30
	v_alignbit_b32 v22, v21, v20, v28
	v_cndmask_b32_e64 v21, v22, v21, s[44:45]
	v_ffbh_u32_e32 v23, v26
	v_alignbit_b32 v22, v25, v21, 30
	v_min_u32_e32 v23, 32, v23
	v_alignbit_b32 v20, v21, v20, 30
	v_xor_b32_e32 v22, v22, v30
	v_sub_u32_e32 v24, 31, v23
	v_xor_b32_e32 v20, v20, v30
	v_alignbit_b32 v25, v26, v22, v24
	v_alignbit_b32 v20, v22, v20, v24
	v_alignbit_b32 v21, v25, v20, 9
	v_ffbh_u32_e32 v22, v21
	v_min_u32_e32 v22, 32, v22
	v_lshrrev_b32_e32 v27, 29, v19
	v_not_b32_e32 v24, v22
	v_alignbit_b32 v20, v21, v20, v24
	v_lshlrev_b32_e32 v21, 31, v27
	v_or_b32_e32 v24, 0x33000000, v21
	v_add_lshl_u32 v22, v22, v23, 23
	v_lshrrev_b32_e32 v20, 9, v20
	v_sub_u32_e32 v22, v24, v22
	v_or_b32_e32 v21, 0.5, v21
	v_lshlrev_b32_e32 v23, 23, v23
	v_or_b32_e32 v20, v22, v20
	v_lshrrev_b32_e32 v22, 9, v25
	v_sub_u32_e32 v21, v21, v23
	v_or_b32_e32 v21, v22, v21
	v_mul_f32_e32 v22, 0x3fc90fda, v21
	s_mov_b32 s0, 0x3fc90fda
	v_fma_f32 v23, v21, s0, -v22
	v_fmac_f32_e32 v23, 0x33a22168, v21
	v_fmac_f32_e32 v23, 0x3fc90fda, v20
	v_lshrrev_b32_e32 v19, 30, v19
	s_movk_i32 s43, 0x1fff
	v_add_f32_e32 v20, v22, v23
	v_add_u32_e32 v19, v29, v19
